# v34 plus write-through (sc1) stores in GEMM epilogues
# baseline (speedup 1.0000x reference)
; __device__ __forceinline__ float row_finish(float t) { t += shx(t, 16); t += shx(t, 32); return __builtin_amdgcn_rsqf(t * (1.0f / 1024.0f) + RMS_EPS); }
; __device__ __forceinline__ f32x4 silu4(f32x4 v) { return (f32x4){silu_f(v[0]), silu_f(v[1]), silu_f(v[2]), silu_f(v[3])}; }
; __device__ __forceinline__ float sq4(f32x4 v) { return (v[0] * v[0] + v[1] * v[1]) + (v[2] * v[2] + v[3] * v[3]); }
; __device__ __forceinline__ u32x4 pack8(f32x4 a, f32x4 b) { u32x4 w; w.x = cvt_pk_bf16(a[0], a[1]); w.y = cvt_pk_bf16(a[2], a[3]); w.z = cvt_pk_bf16(b[0], b[1]); w.w = cvt_pk_bf16(b[2], b[3]); return w; }
;     __device__ __forceinline__ void operator()(const f32x4 (&acc)[2][2][4][2], const Unit& u, int wr, int wc, int fr, int fq) const {
;     ...
;             for (int m = 0; m < 4; ++m) rs[ai][m] = row_finish(rs[ai][m]);
; #pragma unroll
;         for (int ai = 0; ai < 2; ++ai)
; #pragma unroll
;             for (int m = 0; m < 4; ++m) {
;                 const int row = u.pm * BM + ai * HALF + wr * 64 + m * 16 + fr;
;                 const float rstd = rs[ai][m];
;                 f32x4 v[2][2];
; #pragma unroll
;                 for (int bj = 0; bj < 2; ++bj)
; #pragma unroll
;                     for (int n = 0; n < 2; ++n) v[bj][n] = acc[ai][bj][m][n] * rstd;
;                 if (mode == 2) {
;                     float q = (sq4(v[0][0]) + sq4(v[0][1])) + (sq4(v[1][0]) + sq4(v[1][1]));
;                     q += shx(q, 16); q += shx(q, 32);
;                     const float r2 = __builtin_amdgcn_rsqf(q * (1.0f / 64.0f) + RMS_EPS);
; #pragma unroll
;                     for (int bj = 0; bj < 2; ++bj)
; #pragma unroll
;                         for (int n = 0; n < 2; ++n) v[bj][n] = v[bj][n] * r2 * wv[bj][n];
;                 } else if (mode == 1) {
; #pragma unroll
;                     for (int bj = 0; bj < 2; ++bj)
; #pragma unroll
;                         for (int n = 0; n < 2; ++n) v[bj][n] = silu4(v[bj][n]);
;                 } else {
; #pragma unroll
;                     for (int bj = 0; bj < 2; ++bj)
; #pragma unroll
;                         for (int n = 0; n < 2; ++n) v[bj][n] = v[bj][n] * sc;
;                 }
;                 bf16_t* rowp = U + (size_t)row * 2560 + lcol;
; #pragma unroll
;                 for (int bj = 0; bj < 2; ++bj) *(u32x4*)(rowp + 32 * bj) = pack8(v[bj][0], v[bj][1]);
.LBB0_130:
	v_add_f32_e32 v170, v212, v213
	v_fmamk_f32 v170, v170, 0x3a800000, v202
	v_rsq_f32_e32 v178, v170
	v_lshl_or_b32 v170, s36, 8, v197
	v_mov_b64_e32 v[180:181], s[14:15]
	v_ashrrev_i32_e32 v171, 31, v170
	v_mad_i64_i32 v[180:181], s[36:37], v176, s56, v[180:181]
	v_lshl_add_u64 v[180:181], v[170:171], 1, v[180:181]
	v_cvt_pk_bf16_f32 v112, v112, v113
	v_cvt_pk_bf16_f32 v113, v114, v115
	v_cvt_pk_bf16_f32 v114, v116, v117
	v_cvt_pk_bf16_f32 v115, v118, v119
	global_store_dwordx4 v[180:181], v[112:115], off sc1
	v_pk_mul_f32 v[116:117], v[102:103], v[178:179] op_sel_hi:[1,0]
	v_pk_mul_f32 v[118:119], v[100:101], v[178:179] op_sel_hi:[1,0]
	v_cvt_pk_bf16_f32 v112, v120, v121
	v_cvt_pk_bf16_f32 v113, v122, v123
	v_cvt_pk_bf16_f32 v114, v124, v125
	v_cvt_pk_bf16_f32 v115, v126, v127
	global_store_dwordx4 v[180:181], v[112:115], off offset:64 sc1
	v_pk_mul_f32 v[126:127], v[110:111], v[178:179] op_sel_hi:[1,0]
	v_pk_mul_f32 v[120:121], v[108:109], v[178:179] op_sel_hi:[1,0]
	v_pk_mul_f32 v[122:123], v[106:107], v[178:179] op_sel_hi:[1,0]
	v_pk_mul_f32 v[124:125], v[104:105], v[178:179] op_sel_hi:[1,0]
	v_pk_mul_f32 v[114:115], v[98:99], v[178:179] op_sel_hi:[1,0]
	v_pk_mul_f32 v[112:113], v[96:97], v[178:179] op_sel_hi:[1,0]
	s_mov_b64 s[36:37], -1
	s_and_b64 vcc, exec, s[34:35]
	s_cbranch_vccz .LBB0_132
	v_mov_b32_e32 v98, v121
	v_mov_b32_e32 v99, v119
	v_mov_b32_e32 v96, v120
	v_mov_b32_e32 v97, v118
	v_pk_mul_f32 v[98:99], v[98:99], v[98:99]
	v_mov_b32_e32 v100, v127
	v_mov_b32_e32 v101, v117
	v_pk_fma_f32 v[96:97], v[96:97], v[96:97], v[98:99]
	v_mov_b32_e32 v98, v126
	v_mov_b32_e32 v99, v116
	v_pk_mul_f32 v[100:101], v[100:101], v[100:101]
	v_mov_b32_e32 v102, v123
	v_pk_fma_f32 v[98:99], v[98:99], v[98:99], v[100:101]
	v_mov_b32_e32 v100, v125
	v_mov_b32_e32 v101, v113
	v_pk_add_f32 v[96:97], v[96:97], v[98:99]
	v_mov_b32_e32 v98, v124
	v_mov_b32_e32 v99, v112
	v_pk_mul_f32 v[100:101], v[100:101], v[100:101]
	v_mov_b32_e32 v103, v115
	v_pk_fma_f32 v[98:99], v[98:99], v[98:99], v[100:101]
	v_mov_b32_e32 v100, v122
	v_mov_b32_e32 v101, v114
	v_pk_mul_f32 v[102:103], v[102:103], v[102:103]
	s_mov_b64 s[36:37], 0
	v_pk_fma_f32 v[100:101], v[100:101], v[100:101], v[102:103]
	s_nop 0
	v_pk_add_f32 v[98:99], v[98:99], v[100:101]
	s_nop 0
	v_pk_add_f32 v[96:97], v[96:97], v[98:99]
	s_nop 0
	v_add_f32_e32 v96, v96, v97
	v_mov_b32_e32 v97, v201
	s_nop 0
	v_lshlrev_b32_e32 v97, 2, v97
	v_xor_b32_e32 v97, 64, v97
	v_mov_b32_e32 v97, v96
	s_nop 1
	v_permlane16_swap_b32_e32 v97, v96
	s_waitcnt lgkmcnt(0)
	v_add_f32_e32 v96, v96, v97
	v_mov_b32_e32 v97, v201
	s_nop 0
	v_lshlrev_b32_e32 v97, 2, v97
	v_xor_b32_e32 v97, 0x80, v97
	v_mov_b32_e32 v97, v96
	s_nop 1
	v_permlane32_swap_b32_e32 v97, v96
	s_waitcnt lgkmcnt(0)
	v_add_f32_e32 v96, v96, v97
	v_fmamk_f32 v96, v96, 0x3c800000, v202
	v_rsq_f32_e32 v108, v96
	s_nop 0
	v_pk_mul_f32 v[96:97], v[120:121], v[108:109] op_sel_hi:[1,0]
	v_pk_mul_f32 v[98:99], v[126:127], v[108:109] op_sel_hi:[1,0]
	v_pk_mul_f32 v[100:101], v[124:125], v[108:109] op_sel_hi:[1,0]
	v_pk_mul_f32 v[102:103], v[122:123], v[108:109] op_sel_hi:[1,0]
	v_pk_mul_f32 v[104:105], v[118:119], v[108:109] op_sel_hi:[1,0]
	v_pk_mul_f32 v[106:107], v[116:117], v[108:109] op_sel_hi:[1,0]
	v_pk_mul_f32 v[178:179], v[112:113], v[108:109] op_sel_hi:[1,0]
	v_pk_mul_f32 v[108:109], v[114:115], v[108:109] op_sel_hi:[1,0]
	v_pk_mul_f32 v[98:99], v[162:163], v[98:99]
	v_pk_mul_f32 v[96:97], v[164:165], v[96:97]
	v_pk_mul_f32 v[102:103], v[158:159], v[102:103]
	v_pk_mul_f32 v[100:101], v[160:161], v[100:101]
	v_pk_mul_f32 v[106:107], v[154:155], v[106:107]
	v_pk_mul_f32 v[104:105], v[156:157], v[104:105]
	v_pk_mul_f32 v[110:111], v[150:151], v[108:109]
	v_pk_mul_f32 v[108:109], v[152:153], v[178:179]

; __device__ __forceinline__ float row_finish(float t) { t += shx(t, 16); t += shx(t, 32); return __builtin_amdgcn_rsqf(t * (1.0f / 1024.0f) + RMS_EPS); }
; __device__ __forceinline__ f32x4 silu4(f32x4 v) { return (f32x4){silu_f(v[0]), silu_f(v[1]), silu_f(v[2]), silu_f(v[3])}; }
; __device__ __forceinline__ float sq4(f32x4 v) { return (v[0] * v[0] + v[1] * v[1]) + (v[2] * v[2] + v[3] * v[3]); }
; __device__ __forceinline__ u32x4 pack8(f32x4 a, f32x4 b) { u32x4 w; w.x = cvt_pk_bf16(a[0], a[1]); w.y = cvt_pk_bf16(a[2], a[3]); w.z = cvt_pk_bf16(b[0], b[1]); w.w = cvt_pk_bf16(b[2], b[3]); return w; }
;     __device__ __forceinline__ void operator()(const f32x4 (&acc)[2][2][4][2], const Unit& u, int wr, int wc, int fr, int fq) const {
;     ...
;             for (int m = 0; m < 4; ++m) rs[ai][m] = row_finish(rs[ai][m]);
; #pragma unroll
;         for (int ai = 0; ai < 2; ++ai)
; #pragma unroll
;             for (int m = 0; m < 4; ++m) {
;                 const int row = u.pm * BM + ai * HALF + wr * 64 + m * 16 + fr;
;                 const float rstd = rs[ai][m];
;                 f32x4 v[2][2];
; #pragma unroll
;                 for (int bj = 0; bj < 2; ++bj)
; #pragma unroll
;                     for (int n = 0; n < 2; ++n) v[bj][n] = acc[ai][bj][m][n] * rstd;
;                 if (mode == 2) {
;                     float q = (sq4(v[0][0]) + sq4(v[0][1])) + (sq4(v[1][0]) + sq4(v[1][1]));
;                     q += shx(q, 16); q += shx(q, 32);
;                     const float r2 = __builtin_amdgcn_rsqf(q * (1.0f / 64.0f) + RMS_EPS);
; #pragma unroll
;                     for (int bj = 0; bj < 2; ++bj)
; #pragma unroll
;                         for (int n = 0; n < 2; ++n) v[bj][n] = v[bj][n] * r2 * wv[bj][n];
;                 } else if (mode == 1) {
; #pragma unroll
;                     for (int bj = 0; bj < 2; ++bj)
; #pragma unroll
;                         for (int n = 0; n < 2; ++n) v[bj][n] = silu4(v[bj][n]);
;                 } else {
; #pragma unroll
;                     for (int bj = 0; bj < 2; ++bj)
; #pragma unroll
;                         for (int n = 0; n < 2; ++n) v[bj][n] = v[bj][n] * sc;
;                 }
;                 bf16_t* rowp = U + (size_t)row * 2560 + lcol;
; #pragma unroll
;                 for (int bj = 0; bj < 2; ++bj) *(u32x4*)(rowp + 32 * bj) = pack8(v[bj][0], v[bj][1]);
.LBB0_137:
	v_add_f32_e32 v112, v210, v211
	v_fmamk_f32 v112, v112, 0x3a800000, v202
	v_add_u32_e32 v113, s9, v194
	v_rsq_f32_e32 v112, v112
	v_mov_b64_e32 v[114:115], s[14:15]
	v_mad_i64_i32 v[114:115], s[36:37], v113, s56, v[114:115]
	v_lshl_add_u64 v[114:115], v[170:171], 1, v[114:115]
	v_cvt_pk_bf16_f32 v96, v96, v97
	v_cvt_pk_bf16_f32 v97, v98, v99
	v_cvt_pk_bf16_f32 v98, v100, v101
	v_cvt_pk_bf16_f32 v99, v102, v103
	global_store_dwordx4 v[114:115], v[96:99], off sc1
	v_pk_mul_f32 v[100:101], v[86:87], v[112:113] op_sel_hi:[1,0]
	v_pk_mul_f32 v[102:103], v[84:85], v[112:113] op_sel_hi:[1,0]
	v_cvt_pk_bf16_f32 v96, v104, v105
	v_cvt_pk_bf16_f32 v97, v106, v107
	v_cvt_pk_bf16_f32 v98, v108, v109
	v_cvt_pk_bf16_f32 v99, v110, v111
	global_store_dwordx4 v[114:115], v[96:99], off offset:64 sc1
	v_pk_mul_f32 v[110:111], v[94:95], v[112:113] op_sel_hi:[1,0]
	v_pk_mul_f32 v[104:105], v[92:93], v[112:113] op_sel_hi:[1,0]
	v_pk_mul_f32 v[106:107], v[90:91], v[112:113] op_sel_hi:[1,0]
	v_pk_mul_f32 v[108:109], v[88:89], v[112:113] op_sel_hi:[1,0]
	v_pk_mul_f32 v[98:99], v[82:83], v[112:113] op_sel_hi:[1,0]
	v_pk_mul_f32 v[96:97], v[80:81], v[112:113] op_sel_hi:[1,0]
	s_mov_b64 s[36:37], -1
	s_and_b64 vcc, exec, s[34:35]
	s_cbranch_vccz .LBB0_139
	v_mov_b32_e32 v82, v105
	v_mov_b32_e32 v83, v103
	v_mov_b32_e32 v80, v104
	v_mov_b32_e32 v81, v102
	v_pk_mul_f32 v[82:83], v[82:83], v[82:83]
	v_mov_b32_e32 v84, v111
	v_mov_b32_e32 v85, v101
	v_pk_fma_f32 v[80:81], v[80:81], v[80:81], v[82:83]
	v_mov_b32_e32 v82, v110
	v_mov_b32_e32 v83, v100
	v_pk_mul_f32 v[84:85], v[84:85], v[84:85]
	v_mov_b32_e32 v86, v107
	v_pk_fma_f32 v[82:83], v[82:83], v[82:83], v[84:85]
	v_mov_b32_e32 v84, v109
	v_mov_b32_e32 v85, v97
	v_pk_add_f32 v[80:81], v[80:81], v[82:83]
	v_mov_b32_e32 v82, v108
	v_mov_b32_e32 v83, v96
	v_pk_mul_f32 v[84:85], v[84:85], v[84:85]
	v_mov_b32_e32 v87, v99
	v_pk_fma_f32 v[82:83], v[82:83], v[82:83], v[84:85]
	v_mov_b32_e32 v84, v106
	v_mov_b32_e32 v85, v98
	v_pk_mul_f32 v[86:87], v[86:87], v[86:87]
	s_mov_b64 s[36:37], 0
	v_pk_fma_f32 v[84:85], v[84:85], v[84:85], v[86:87]
	s_nop 0
	v_pk_add_f32 v[82:83], v[82:83], v[84:85]
	s_nop 0
	v_pk_add_f32 v[80:81], v[80:81], v[82:83]
	s_nop 0
	v_add_f32_e32 v80, v80, v81
	v_mov_b32_e32 v81, v201
	s_nop 0
	v_lshlrev_b32_e32 v81, 2, v81
	v_xor_b32_e32 v81, 64, v81
	v_mov_b32_e32 v81, v80
	s_nop 1
	v_permlane16_swap_b32_e32 v81, v80
	s_waitcnt lgkmcnt(0)
	v_add_f32_e32 v80, v80, v81
	v_mov_b32_e32 v81, v201
	s_nop 0
	v_lshlrev_b32_e32 v81, 2, v81
	v_xor_b32_e32 v81, 0x80, v81
	v_mov_b32_e32 v81, v80
	s_nop 1
	v_permlane32_swap_b32_e32 v81, v80
	s_waitcnt lgkmcnt(0)
	v_add_f32_e32 v80, v80, v81
	v_fmamk_f32 v80, v80, 0x3c800000, v202
	v_rsq_f32_e32 v92, v80
	s_nop 0
	v_pk_mul_f32 v[80:81], v[104:105], v[92:93] op_sel_hi:[1,0]
	v_pk_mul_f32 v[82:83], v[110:111], v[92:93] op_sel_hi:[1,0]
	v_pk_mul_f32 v[84:85], v[108:109], v[92:93] op_sel_hi:[1,0]
	v_pk_mul_f32 v[86:87], v[106:107], v[92:93] op_sel_hi:[1,0]
	v_pk_mul_f32 v[88:89], v[102:103], v[92:93] op_sel_hi:[1,0]
	v_pk_mul_f32 v[90:91], v[100:101], v[92:93] op_sel_hi:[1,0]
	v_pk_mul_f32 v[112:113], v[96:97], v[92:93] op_sel_hi:[1,0]
	v_pk_mul_f32 v[92:93], v[98:99], v[92:93] op_sel_hi:[1,0]
	v_pk_mul_f32 v[82:83], v[162:163], v[82:83]
	v_pk_mul_f32 v[80:81], v[164:165], v[80:81]
	v_pk_mul_f32 v[86:87], v[158:159], v[86:87]
	v_pk_mul_f32 v[84:85], v[160:161], v[84:85]
	v_pk_mul_f32 v[90:91], v[154:155], v[90:91]
	v_pk_mul_f32 v[88:89], v[156:157], v[88:89]
	v_pk_mul_f32 v[94:95], v[150:151], v[92:93]
	v_pk_mul_f32 v[92:93], v[152:153], v[112:113]

; __device__ __forceinline__ float row_finish(float t) { t += shx(t, 16); t += shx(t, 32); return __builtin_amdgcn_rsqf(t * (1.0f / 1024.0f) + RMS_EPS); }
; __device__ __forceinline__ f32x4 silu4(f32x4 v) { return (f32x4){silu_f(v[0]), silu_f(v[1]), silu_f(v[2]), silu_f(v[3])}; }
; __device__ __forceinline__ float sq4(f32x4 v) { return (v[0] * v[0] + v[1] * v[1]) + (v[2] * v[2] + v[3] * v[3]); }
; __device__ __forceinline__ u32x4 pack8(f32x4 a, f32x4 b) { u32x4 w; w.x = cvt_pk_bf16(a[0], a[1]); w.y = cvt_pk_bf16(a[2], a[3]); w.z = cvt_pk_bf16(b[0], b[1]); w.w = cvt_pk_bf16(b[2], b[3]); return w; }
;     __device__ __forceinline__ void operator()(const f32x4 (&acc)[2][2][4][2], const Unit& u, int wr, int wc, int fr, int fq) const {
;     ...
;             for (int m = 0; m < 4; ++m) rs[ai][m] = row_finish(rs[ai][m]);
; #pragma unroll
;         for (int ai = 0; ai < 2; ++ai)
; #pragma unroll
;             for (int m = 0; m < 4; ++m) {
;                 const int row = u.pm * BM + ai * HALF + wr * 64 + m * 16 + fr;
;                 const float rstd = rs[ai][m];
;                 f32x4 v[2][2];
; #pragma unroll
;                 for (int bj = 0; bj < 2; ++bj)
; #pragma unroll
;                     for (int n = 0; n < 2; ++n) v[bj][n] = acc[ai][bj][m][n] * rstd;
;                 if (mode == 2) {
;                     float q = (sq4(v[0][0]) + sq4(v[0][1])) + (sq4(v[1][0]) + sq4(v[1][1]));
;                     q += shx(q, 16); q += shx(q, 32);
;                     const float r2 = __builtin_amdgcn_rsqf(q * (1.0f / 64.0f) + RMS_EPS);
; #pragma unroll
;                     for (int bj = 0; bj < 2; ++bj)
; #pragma unroll
;                         for (int n = 0; n < 2; ++n) v[bj][n] = v[bj][n] * r2 * wv[bj][n];
;                 } else if (mode == 1) {
; #pragma unroll
;                     for (int bj = 0; bj < 2; ++bj)
; #pragma unroll
;                         for (int n = 0; n < 2; ++n) v[bj][n] = silu4(v[bj][n]);
;                 } else {
; #pragma unroll
;                     for (int bj = 0; bj < 2; ++bj)
; #pragma unroll
;                         for (int n = 0; n < 2; ++n) v[bj][n] = v[bj][n] * sc;
;                 }
;                 bf16_t* rowp = U + (size_t)row * 2560 + lcol;
; #pragma unroll
;                 for (int bj = 0; bj < 2; ++bj) *(u32x4*)(rowp + 32 * bj) = pack8(v[bj][0], v[bj][1]);
.LBB0_144:
	v_add_f32_e32 v96, v208, v209
	v_fmamk_f32 v96, v96, 0x3a800000, v202
	v_add_u32_e32 v97, s9, v195
	v_rsq_f32_e32 v96, v96
	v_mov_b64_e32 v[98:99], s[14:15]
	v_mad_i64_i32 v[98:99], s[36:37], v97, s56, v[98:99]
	v_lshl_add_u64 v[98:99], v[170:171], 1, v[98:99]
	v_cvt_pk_bf16_f32 v80, v80, v81
	v_cvt_pk_bf16_f32 v81, v82, v83
	v_cvt_pk_bf16_f32 v82, v84, v85
	v_cvt_pk_bf16_f32 v83, v86, v87
	global_store_dwordx4 v[98:99], v[80:83], off sc1
	v_pk_mul_f32 v[84:85], v[70:71], v[96:97] op_sel_hi:[1,0]
	v_pk_mul_f32 v[86:87], v[68:69], v[96:97] op_sel_hi:[1,0]
	v_cvt_pk_bf16_f32 v80, v88, v89
	v_cvt_pk_bf16_f32 v81, v90, v91
	v_cvt_pk_bf16_f32 v82, v92, v93
	v_cvt_pk_bf16_f32 v83, v94, v95
	global_store_dwordx4 v[98:99], v[80:83], off offset:64 sc1
	v_pk_mul_f32 v[94:95], v[78:79], v[96:97] op_sel_hi:[1,0]
	v_pk_mul_f32 v[88:89], v[76:77], v[96:97] op_sel_hi:[1,0]
	v_pk_mul_f32 v[90:91], v[74:75], v[96:97] op_sel_hi:[1,0]
	v_pk_mul_f32 v[92:93], v[72:73], v[96:97] op_sel_hi:[1,0]
	v_pk_mul_f32 v[82:83], v[66:67], v[96:97] op_sel_hi:[1,0]
	v_pk_mul_f32 v[80:81], v[64:65], v[96:97] op_sel_hi:[1,0]
	s_mov_b64 s[36:37], -1
	s_and_b64 vcc, exec, s[34:35]
	s_cbranch_vccz .LBB0_146
	v_mov_b32_e32 v66, v89
	v_mov_b32_e32 v67, v87
	v_mov_b32_e32 v64, v88
	v_mov_b32_e32 v65, v86
	v_pk_mul_f32 v[66:67], v[66:67], v[66:67]
	v_mov_b32_e32 v68, v95
	v_mov_b32_e32 v69, v85
	v_pk_fma_f32 v[64:65], v[64:65], v[64:65], v[66:67]
	v_mov_b32_e32 v66, v94
	v_mov_b32_e32 v67, v84
	v_pk_mul_f32 v[68:69], v[68:69], v[68:69]
	v_mov_b32_e32 v70, v91
	v_pk_fma_f32 v[66:67], v[66:67], v[66:67], v[68:69]
	v_mov_b32_e32 v68, v93
	v_mov_b32_e32 v69, v81
	v_pk_add_f32 v[64:65], v[64:65], v[66:67]
	v_mov_b32_e32 v66, v92
	v_mov_b32_e32 v67, v80
	v_pk_mul_f32 v[68:69], v[68:69], v[68:69]
	v_mov_b32_e32 v71, v83
	v_pk_fma_f32 v[66:67], v[66:67], v[66:67], v[68:69]
	v_mov_b32_e32 v68, v90
	v_mov_b32_e32 v69, v82
	v_pk_mul_f32 v[70:71], v[70:71], v[70:71]
	s_mov_b64 s[36:37], 0
	v_pk_fma_f32 v[68:69], v[68:69], v[68:69], v[70:71]
	s_nop 0
	v_pk_add_f32 v[66:67], v[66:67], v[68:69]
	s_nop 0
	v_pk_add_f32 v[64:65], v[64:65], v[66:67]
	s_nop 0
	v_add_f32_e32 v64, v64, v65
	v_mov_b32_e32 v65, v201
	s_nop 0
	v_lshlrev_b32_e32 v65, 2, v65
	v_xor_b32_e32 v65, 64, v65
	v_mov_b32_e32 v65, v64
	s_nop 1
	v_permlane16_swap_b32_e32 v65, v64
	s_waitcnt lgkmcnt(0)
	v_add_f32_e32 v64, v64, v65
	v_mov_b32_e32 v65, v201
	s_nop 0
	v_lshlrev_b32_e32 v65, 2, v65
	v_xor_b32_e32 v65, 0x80, v65
	v_mov_b32_e32 v65, v64
	s_nop 1
	v_permlane32_swap_b32_e32 v65, v64
	s_waitcnt lgkmcnt(0)
	v_add_f32_e32 v64, v64, v65
	v_fmamk_f32 v64, v64, 0x3c800000, v202
	v_rsq_f32_e32 v76, v64
	s_nop 0
	v_pk_mul_f32 v[64:65], v[88:89], v[76:77] op_sel_hi:[1,0]
	v_pk_mul_f32 v[66:67], v[94:95], v[76:77] op_sel_hi:[1,0]
	v_pk_mul_f32 v[68:69], v[92:93], v[76:77] op_sel_hi:[1,0]
	v_pk_mul_f32 v[70:71], v[90:91], v[76:77] op_sel_hi:[1,0]
	v_pk_mul_f32 v[72:73], v[86:87], v[76:77] op_sel_hi:[1,0]
	v_pk_mul_f32 v[74:75], v[84:85], v[76:77] op_sel_hi:[1,0]
	v_pk_mul_f32 v[96:97], v[80:81], v[76:77] op_sel_hi:[1,0]
	v_pk_mul_f32 v[76:77], v[82:83], v[76:77] op_sel_hi:[1,0]
	v_pk_mul_f32 v[66:67], v[162:163], v[66:67]
	v_pk_mul_f32 v[64:65], v[164:165], v[64:65]
	v_pk_mul_f32 v[70:71], v[158:159], v[70:71]
	v_pk_mul_f32 v[68:69], v[160:161], v[68:69]
	v_pk_mul_f32 v[74:75], v[154:155], v[74:75]
	v_pk_mul_f32 v[72:73], v[156:157], v[72:73]
	v_pk_mul_f32 v[78:79], v[150:151], v[76:77]
	v_pk_mul_f32 v[76:77], v[152:153], v[96:97]

; __device__ __forceinline__ float row_finish(float t) { t += shx(t, 16); t += shx(t, 32); return __builtin_amdgcn_rsqf(t * (1.0f / 1024.0f) + RMS_EPS); }
; __device__ __forceinline__ f32x4 silu4(f32x4 v) { return (f32x4){silu_f(v[0]), silu_f(v[1]), silu_f(v[2]), silu_f(v[3])}; }
; __device__ __forceinline__ float sq4(f32x4 v) { return (v[0] * v[0] + v[1] * v[1]) + (v[2] * v[2] + v[3] * v[3]); }
; __device__ __forceinline__ u32x4 pack8(f32x4 a, f32x4 b) { u32x4 w; w.x = cvt_pk_bf16(a[0], a[1]); w.y = cvt_pk_bf16(a[2], a[3]); w.z = cvt_pk_bf16(b[0], b[1]); w.w = cvt_pk_bf16(b[2], b[3]); return w; }
;     __device__ __forceinline__ void operator()(const f32x4 (&acc)[2][2][4][2], const Unit& u, int wr, int wc, int fr, int fq) const {
;     ...
;             for (int m = 0; m < 4; ++m) rs[ai][m] = row_finish(rs[ai][m]);
; #pragma unroll
;         for (int ai = 0; ai < 2; ++ai)
; #pragma unroll
;             for (int m = 0; m < 4; ++m) {
;                 const int row = u.pm * BM + ai * HALF + wr * 64 + m * 16 + fr;
;                 const float rstd = rs[ai][m];
;                 f32x4 v[2][2];
; #pragma unroll
;                 for (int bj = 0; bj < 2; ++bj)
; #pragma unroll
;                     for (int n = 0; n < 2; ++n) v[bj][n] = acc[ai][bj][m][n] * rstd;
;                 if (mode == 2) {
;                     float q = (sq4(v[0][0]) + sq4(v[0][1])) + (sq4(v[1][0]) + sq4(v[1][1]));
;                     q += shx(q, 16); q += shx(q, 32);
;                     const float r2 = __builtin_amdgcn_rsqf(q * (1.0f / 64.0f) + RMS_EPS);
; #pragma unroll
;                     for (int bj = 0; bj < 2; ++bj)
; #pragma unroll
;                         for (int n = 0; n < 2; ++n) v[bj][n] = v[bj][n] * r2 * wv[bj][n];
;                 } else if (mode == 1) {
; #pragma unroll
;                     for (int bj = 0; bj < 2; ++bj)
; #pragma unroll
;                         for (int n = 0; n < 2; ++n) v[bj][n] = silu4(v[bj][n]);
;                 } else {
; #pragma unroll
;                     for (int bj = 0; bj < 2; ++bj)
; #pragma unroll
;                         for (int n = 0; n < 2; ++n) v[bj][n] = v[bj][n] * sc;
;                 }
;                 bf16_t* rowp = U + (size_t)row * 2560 + lcol;
; #pragma unroll
;                 for (int bj = 0; bj < 2; ++bj) *(u32x4*)(rowp + 32 * bj) = pack8(v[bj][0], v[bj][1]);
.LBB0_151:
	v_add_f32_e32 v80, v206, v207
	v_fmamk_f32 v80, v80, 0x3a800000, v202
	v_add_u32_e32 v81, s9, v196
	v_rsq_f32_e32 v80, v80
	v_mov_b64_e32 v[82:83], s[14:15]
	v_mad_i64_i32 v[82:83], s[36:37], v81, s56, v[82:83]
	v_lshl_add_u64 v[82:83], v[170:171], 1, v[82:83]
	v_cvt_pk_bf16_f32 v64, v64, v65
	v_cvt_pk_bf16_f32 v65, v66, v67
	v_cvt_pk_bf16_f32 v66, v68, v69
	v_cvt_pk_bf16_f32 v67, v70, v71
	global_store_dwordx4 v[82:83], v[64:67], off sc1
	v_pk_mul_f32 v[68:69], v[54:55], v[80:81] op_sel_hi:[1,0]
	v_pk_mul_f32 v[70:71], v[52:53], v[80:81] op_sel_hi:[1,0]
	v_cvt_pk_bf16_f32 v64, v72, v73
	v_cvt_pk_bf16_f32 v65, v74, v75
	v_cvt_pk_bf16_f32 v66, v76, v77
	v_cvt_pk_bf16_f32 v67, v78, v79
	global_store_dwordx4 v[82:83], v[64:67], off offset:64 sc1
	v_pk_mul_f32 v[78:79], v[62:63], v[80:81] op_sel_hi:[1,0]
	v_pk_mul_f32 v[72:73], v[60:61], v[80:81] op_sel_hi:[1,0]
	v_pk_mul_f32 v[74:75], v[58:59], v[80:81] op_sel_hi:[1,0]
	v_pk_mul_f32 v[76:77], v[56:57], v[80:81] op_sel_hi:[1,0]
	v_pk_mul_f32 v[66:67], v[50:51], v[80:81] op_sel_hi:[1,0]
	v_pk_mul_f32 v[64:65], v[48:49], v[80:81] op_sel_hi:[1,0]
	s_mov_b64 s[36:37], -1
	s_and_b64 vcc, exec, s[34:35]
	s_cbranch_vccz .LBB0_153
	v_mov_b32_e32 v50, v73
	v_mov_b32_e32 v51, v71
	v_mov_b32_e32 v48, v72
	v_mov_b32_e32 v49, v70
	v_pk_mul_f32 v[50:51], v[50:51], v[50:51]
	v_mov_b32_e32 v52, v79
	v_mov_b32_e32 v53, v69
	v_pk_fma_f32 v[48:49], v[48:49], v[48:49], v[50:51]
	v_mov_b32_e32 v50, v78
	v_mov_b32_e32 v51, v68
	v_pk_mul_f32 v[52:53], v[52:53], v[52:53]
	v_mov_b32_e32 v54, v75
	v_pk_fma_f32 v[50:51], v[50:51], v[50:51], v[52:53]
	v_mov_b32_e32 v52, v77
	v_mov_b32_e32 v53, v65
	v_pk_add_f32 v[48:49], v[48:49], v[50:51]
	v_mov_b32_e32 v50, v76
	v_mov_b32_e32 v51, v64
	v_pk_mul_f32 v[52:53], v[52:53], v[52:53]
	v_mov_b32_e32 v55, v67
	v_pk_fma_f32 v[50:51], v[50:51], v[50:51], v[52:53]
	v_mov_b32_e32 v52, v74
	v_mov_b32_e32 v53, v66
	v_pk_mul_f32 v[54:55], v[54:55], v[54:55]
	s_mov_b64 s[36:37], 0
	v_pk_fma_f32 v[52:53], v[52:53], v[52:53], v[54:55]
	s_nop 0
	v_pk_add_f32 v[50:51], v[50:51], v[52:53]
	s_nop 0
	v_pk_add_f32 v[48:49], v[48:49], v[50:51]
	s_nop 0
	v_add_f32_e32 v48, v48, v49
	v_mov_b32_e32 v49, v201
	s_nop 0
	v_lshlrev_b32_e32 v49, 2, v49
	v_xor_b32_e32 v49, 64, v49
	v_mov_b32_e32 v49, v48
	s_nop 1
	v_permlane16_swap_b32_e32 v49, v48
	s_waitcnt lgkmcnt(0)
	v_add_f32_e32 v48, v48, v49
	v_mov_b32_e32 v49, v201
	s_nop 0
	v_lshlrev_b32_e32 v49, 2, v49
	v_xor_b32_e32 v49, 0x80, v49
	v_mov_b32_e32 v49, v48
	s_nop 1
	v_permlane32_swap_b32_e32 v49, v48
	s_waitcnt lgkmcnt(0)
	v_add_f32_e32 v48, v48, v49
	v_fmamk_f32 v48, v48, 0x3c800000, v202
	v_rsq_f32_e32 v60, v48
	s_nop 0
	v_pk_mul_f32 v[48:49], v[72:73], v[60:61] op_sel_hi:[1,0]
	v_pk_mul_f32 v[50:51], v[78:79], v[60:61] op_sel_hi:[1,0]
	v_pk_mul_f32 v[52:53], v[76:77], v[60:61] op_sel_hi:[1,0]
	v_pk_mul_f32 v[54:55], v[74:75], v[60:61] op_sel_hi:[1,0]
	v_pk_mul_f32 v[56:57], v[70:71], v[60:61] op_sel_hi:[1,0]
	v_pk_mul_f32 v[58:59], v[68:69], v[60:61] op_sel_hi:[1,0]
	v_pk_mul_f32 v[80:81], v[64:65], v[60:61] op_sel_hi:[1,0]
	v_pk_mul_f32 v[60:61], v[66:67], v[60:61] op_sel_hi:[1,0]
	v_pk_mul_f32 v[50:51], v[162:163], v[50:51]
	v_pk_mul_f32 v[48:49], v[164:165], v[48:49]
	v_pk_mul_f32 v[54:55], v[158:159], v[54:55]
	v_pk_mul_f32 v[52:53], v[160:161], v[52:53]
	v_pk_mul_f32 v[58:59], v[154:155], v[58:59]
	v_pk_mul_f32 v[56:57], v[156:157], v[56:57]
	v_pk_mul_f32 v[62:63], v[150:151], v[60:61]
	v_pk_mul_f32 v[60:61], v[152:153], v[80:81]

; __device__ __forceinline__ float row_finish(float t) { t += shx(t, 16); t += shx(t, 32); return __builtin_amdgcn_rsqf(t * (1.0f / 1024.0f) + RMS_EPS); }
; __device__ __forceinline__ f32x4 silu4(f32x4 v) { return (f32x4){silu_f(v[0]), silu_f(v[1]), silu_f(v[2]), silu_f(v[3])}; }
; __device__ __forceinline__ float sq4(f32x4 v) { return (v[0] * v[0] + v[1] * v[1]) + (v[2] * v[2] + v[3] * v[3]); }
; __device__ __forceinline__ u32x4 pack8(f32x4 a, f32x4 b) { u32x4 w; w.x = cvt_pk_bf16(a[0], a[1]); w.y = cvt_pk_bf16(a[2], a[3]); w.z = cvt_pk_bf16(b[0], b[1]); w.w = cvt_pk_bf16(b[2], b[3]); return w; }
;     __device__ __forceinline__ void operator()(const f32x4 (&acc)[2][2][4][2], const Unit& u, int wr, int wc, int fr, int fq) const {
;     ...
;             for (int m = 0; m < 4; ++m) rs[ai][m] = row_finish(rs[ai][m]);
; #pragma unroll
;         for (int ai = 0; ai < 2; ++ai)
; #pragma unroll
;             for (int m = 0; m < 4; ++m) {
;                 const int row = u.pm * BM + ai * HALF + wr * 64 + m * 16 + fr;
;                 const float rstd = rs[ai][m];
;                 f32x4 v[2][2];
; #pragma unroll
;                 for (int bj = 0; bj < 2; ++bj)
; #pragma unroll
;                     for (int n = 0; n < 2; ++n) v[bj][n] = acc[ai][bj][m][n] * rstd;
;                 if (mode == 2) {
;                     float q = (sq4(v[0][0]) + sq4(v[0][1])) + (sq4(v[1][0]) + sq4(v[1][1]));
;                     q += shx(q, 16); q += shx(q, 32);
;                     const float r2 = __builtin_amdgcn_rsqf(q * (1.0f / 64.0f) + RMS_EPS);
; #pragma unroll
;                     for (int bj = 0; bj < 2; ++bj)
; #pragma unroll
;                         for (int n = 0; n < 2; ++n) v[bj][n] = v[bj][n] * r2 * wv[bj][n];
;                 } else if (mode == 1) {
; #pragma unroll
;                     for (int bj = 0; bj < 2; ++bj)
; #pragma unroll
;                         for (int n = 0; n < 2; ++n) v[bj][n] = silu4(v[bj][n]);
;                 } else {
; #pragma unroll
;                     for (int bj = 0; bj < 2; ++bj)
; #pragma unroll
;                         for (int n = 0; n < 2; ++n) v[bj][n] = v[bj][n] * sc;
;                 }
;                 bf16_t* rowp = U + (size_t)row * 2560 + lcol;
; #pragma unroll
;                 for (int bj = 0; bj < 2; ++bj) *(u32x4*)(rowp + 32 * bj) = pack8(v[bj][0], v[bj][1]);
.LBB0_158:
	v_add_f32_e32 v64, v177, v205
	v_fmamk_f32 v64, v64, 0x3a800000, v202
	v_rsq_f32_e32 v64, v64
	v_mov_b64_e32 v[66:67], s[14:15]
	v_mad_i64_i32 v[66:67], s[36:37], v174, s56, v[66:67]
	v_lshl_add_u64 v[66:67], v[170:171], 1, v[66:67]
	v_cvt_pk_bf16_f32 v48, v48, v49
	v_cvt_pk_bf16_f32 v49, v50, v51
	v_cvt_pk_bf16_f32 v50, v52, v53
	v_cvt_pk_bf16_f32 v51, v54, v55
	global_store_dwordx4 v[66:67], v[48:51], off sc1
	v_pk_mul_f32 v[52:53], v[38:39], v[64:65] op_sel_hi:[1,0]
	v_pk_mul_f32 v[54:55], v[36:37], v[64:65] op_sel_hi:[1,0]
	v_cvt_pk_bf16_f32 v48, v56, v57
	v_cvt_pk_bf16_f32 v49, v58, v59
	v_cvt_pk_bf16_f32 v50, v60, v61
	v_cvt_pk_bf16_f32 v51, v62, v63
	global_store_dwordx4 v[66:67], v[48:51], off offset:64 sc1
	v_pk_mul_f32 v[62:63], v[46:47], v[64:65] op_sel_hi:[1,0]
	v_pk_mul_f32 v[56:57], v[44:45], v[64:65] op_sel_hi:[1,0]
	v_pk_mul_f32 v[58:59], v[42:43], v[64:65] op_sel_hi:[1,0]
	v_pk_mul_f32 v[60:61], v[40:41], v[64:65] op_sel_hi:[1,0]
	v_pk_mul_f32 v[50:51], v[34:35], v[64:65] op_sel_hi:[1,0]
	v_pk_mul_f32 v[48:49], v[32:33], v[64:65] op_sel_hi:[1,0]
	s_mov_b64 s[36:37], -1
	s_and_b64 vcc, exec, s[34:35]
	s_cbranch_vccz .LBB0_160
	v_mov_b32_e32 v34, v57
	v_mov_b32_e32 v35, v55
	v_mov_b32_e32 v32, v56
	v_mov_b32_e32 v33, v54
	v_pk_mul_f32 v[34:35], v[34:35], v[34:35]
	v_mov_b32_e32 v36, v63
	v_mov_b32_e32 v37, v53
	v_pk_fma_f32 v[32:33], v[32:33], v[32:33], v[34:35]
	v_mov_b32_e32 v34, v62
	v_mov_b32_e32 v35, v52
	v_pk_mul_f32 v[36:37], v[36:37], v[36:37]
	v_mov_b32_e32 v38, v59
	v_pk_fma_f32 v[34:35], v[34:35], v[34:35], v[36:37]
	v_mov_b32_e32 v36, v61
	v_mov_b32_e32 v37, v49
	v_pk_add_f32 v[32:33], v[32:33], v[34:35]
	v_mov_b32_e32 v34, v60
	v_mov_b32_e32 v35, v48
	v_pk_mul_f32 v[36:37], v[36:37], v[36:37]
	v_mov_b32_e32 v39, v51
	v_pk_fma_f32 v[34:35], v[34:35], v[34:35], v[36:37]
	v_mov_b32_e32 v36, v58
	v_mov_b32_e32 v37, v50
	v_pk_mul_f32 v[38:39], v[38:39], v[38:39]
	s_mov_b64 s[36:37], 0
	v_pk_fma_f32 v[36:37], v[36:37], v[36:37], v[38:39]
	s_nop 0
	v_pk_add_f32 v[34:35], v[34:35], v[36:37]
	s_nop 0
	v_pk_add_f32 v[32:33], v[32:33], v[34:35]
	s_nop 0
	v_add_f32_e32 v32, v32, v33
	v_mov_b32_e32 v33, v201
	s_nop 0
	v_lshlrev_b32_e32 v33, 2, v33
	v_xor_b32_e32 v33, 64, v33
	v_mov_b32_e32 v33, v32
	s_nop 1
	v_permlane16_swap_b32_e32 v33, v32
	s_waitcnt lgkmcnt(0)
	v_add_f32_e32 v32, v32, v33
	v_mov_b32_e32 v33, v201
	s_nop 0
	v_lshlrev_b32_e32 v33, 2, v33
	v_xor_b32_e32 v33, 0x80, v33
	v_mov_b32_e32 v33, v32
	s_nop 1
	v_permlane32_swap_b32_e32 v33, v32
	s_waitcnt lgkmcnt(0)
	v_add_f32_e32 v32, v32, v33
	v_fmamk_f32 v32, v32, 0x3c800000, v202
	v_rsq_f32_e32 v44, v32
	s_nop 0
	v_pk_mul_f32 v[32:33], v[56:57], v[44:45] op_sel_hi:[1,0]
	v_pk_mul_f32 v[34:35], v[62:63], v[44:45] op_sel_hi:[1,0]
	v_pk_mul_f32 v[36:37], v[60:61], v[44:45] op_sel_hi:[1,0]
	v_pk_mul_f32 v[38:39], v[58:59], v[44:45] op_sel_hi:[1,0]
	v_pk_mul_f32 v[40:41], v[54:55], v[44:45] op_sel_hi:[1,0]
	v_pk_mul_f32 v[42:43], v[52:53], v[44:45] op_sel_hi:[1,0]
	v_pk_mul_f32 v[64:65], v[48:49], v[44:45] op_sel_hi:[1,0]
	v_pk_mul_f32 v[44:45], v[50:51], v[44:45] op_sel_hi:[1,0]
	v_pk_mul_f32 v[34:35], v[162:163], v[34:35]
	v_pk_mul_f32 v[32:33], v[164:165], v[32:33]
	v_pk_mul_f32 v[38:39], v[158:159], v[38:39]
	v_pk_mul_f32 v[36:37], v[160:161], v[36:37]
	v_pk_mul_f32 v[42:43], v[154:155], v[42:43]
	v_pk_mul_f32 v[40:41], v[156:157], v[40:41]
	v_pk_mul_f32 v[46:47], v[150:151], v[44:45]
	v_pk_mul_f32 v[44:45], v[152:153], v[64:65]

; __device__ __forceinline__ float row_finish(float t) { t += shx(t, 16); t += shx(t, 32); return __builtin_amdgcn_rsqf(t * (1.0f / 1024.0f) + RMS_EPS); }
; __device__ __forceinline__ f32x4 silu4(f32x4 v) { return (f32x4){silu_f(v[0]), silu_f(v[1]), silu_f(v[2]), silu_f(v[3])}; }
; __device__ __forceinline__ float sq4(f32x4 v) { return (v[0] * v[0] + v[1] * v[1]) + (v[2] * v[2] + v[3] * v[3]); }
; __device__ __forceinline__ u32x4 pack8(f32x4 a, f32x4 b) { u32x4 w; w.x = cvt_pk_bf16(a[0], a[1]); w.y = cvt_pk_bf16(a[2], a[3]); w.z = cvt_pk_bf16(b[0], b[1]); w.w = cvt_pk_bf16(b[2], b[3]); return w; }
;     __device__ __forceinline__ void operator()(const f32x4 (&acc)[2][2][4][2], const Unit& u, int wr, int wc, int fr, int fq) const {
;     ...
;             for (int m = 0; m < 4; ++m) rs[ai][m] = row_finish(rs[ai][m]);
; #pragma unroll
;         for (int ai = 0; ai < 2; ++ai)
; #pragma unroll
;             for (int m = 0; m < 4; ++m) {
;                 const int row = u.pm * BM + ai * HALF + wr * 64 + m * 16 + fr;
;                 const float rstd = rs[ai][m];
;                 f32x4 v[2][2];
; #pragma unroll
;                 for (int bj = 0; bj < 2; ++bj)
; #pragma unroll
;                     for (int n = 0; n < 2; ++n) v[bj][n] = acc[ai][bj][m][n] * rstd;
;                 if (mode == 2) {
;                     float q = (sq4(v[0][0]) + sq4(v[0][1])) + (sq4(v[1][0]) + sq4(v[1][1]));
;                     q += shx(q, 16); q += shx(q, 32);
;                     const float r2 = __builtin_amdgcn_rsqf(q * (1.0f / 64.0f) + RMS_EPS);
; #pragma unroll
;                     for (int bj = 0; bj < 2; ++bj)
; #pragma unroll
;                         for (int n = 0; n < 2; ++n) v[bj][n] = v[bj][n] * r2 * wv[bj][n];
;                 } else if (mode == 1) {
; #pragma unroll
;                     for (int bj = 0; bj < 2; ++bj)
; #pragma unroll
;                         for (int n = 0; n < 2; ++n) v[bj][n] = silu4(v[bj][n]);
;                 } else {
; #pragma unroll
;                     for (int bj = 0; bj < 2; ++bj)
; #pragma unroll
;                         for (int n = 0; n < 2; ++n) v[bj][n] = v[bj][n] * sc;
;                 }
;                 bf16_t* rowp = U + (size_t)row * 2560 + lcol;
; #pragma unroll
;                 for (int bj = 0; bj < 2; ++bj) *(u32x4*)(rowp + 32 * bj) = pack8(v[bj][0], v[bj][1]);
.LBB0_165:
	s_waitcnt lgkmcnt(0)
	v_add_f32_e32 v48, v173, v175
	v_fmamk_f32 v48, v48, 0x3a800000, v202
	v_rsq_f32_e32 v48, v48
	v_mov_b64_e32 v[50:51], s[14:15]
	v_mad_i64_i32 v[50:51], s[36:37], v172, s56, v[50:51]
	v_lshl_add_u64 v[50:51], v[170:171], 1, v[50:51]
	v_cvt_pk_bf16_f32 v32, v32, v33
	v_cvt_pk_bf16_f32 v33, v34, v35
	v_cvt_pk_bf16_f32 v34, v36, v37
	v_cvt_pk_bf16_f32 v35, v38, v39
	global_store_dwordx4 v[50:51], v[32:35], off sc1
	v_pk_mul_f32 v[36:37], v[22:23], v[48:49] op_sel_hi:[1,0]
	v_pk_mul_f32 v[38:39], v[20:21], v[48:49] op_sel_hi:[1,0]
	v_cvt_pk_bf16_f32 v32, v40, v41
	v_cvt_pk_bf16_f32 v33, v42, v43
	v_cvt_pk_bf16_f32 v34, v44, v45
	v_cvt_pk_bf16_f32 v35, v46, v47
	global_store_dwordx4 v[50:51], v[32:35], off offset:64 sc1
	v_pk_mul_f32 v[46:47], v[30:31], v[48:49] op_sel_hi:[1,0]
	v_pk_mul_f32 v[40:41], v[28:29], v[48:49] op_sel_hi:[1,0]
	v_pk_mul_f32 v[42:43], v[26:27], v[48:49] op_sel_hi:[1,0]
	v_pk_mul_f32 v[44:45], v[24:25], v[48:49] op_sel_hi:[1,0]
	v_pk_mul_f32 v[34:35], v[18:19], v[48:49] op_sel_hi:[1,0]
	v_pk_mul_f32 v[32:33], v[16:17], v[48:49] op_sel_hi:[1,0]
	s_mov_b64 s[36:37], -1
	s_and_b64 vcc, exec, s[34:35]
	s_cbranch_vccz .LBB0_167
	v_mov_b32_e32 v18, v41
	v_mov_b32_e32 v19, v39
	v_mov_b32_e32 v16, v40
	v_mov_b32_e32 v17, v38
	v_pk_mul_f32 v[18:19], v[18:19], v[18:19]
	v_mov_b32_e32 v20, v47
	v_mov_b32_e32 v21, v37
	v_pk_fma_f32 v[16:17], v[16:17], v[16:17], v[18:19]
	v_mov_b32_e32 v18, v46
	v_mov_b32_e32 v19, v36
	v_pk_mul_f32 v[20:21], v[20:21], v[20:21]
	v_mov_b32_e32 v22, v43
	v_pk_fma_f32 v[18:19], v[18:19], v[18:19], v[20:21]
	v_mov_b32_e32 v20, v45
	v_mov_b32_e32 v21, v33
	v_pk_add_f32 v[16:17], v[16:17], v[18:19]
	v_mov_b32_e32 v18, v44
	v_mov_b32_e32 v19, v32
	v_pk_mul_f32 v[20:21], v[20:21], v[20:21]
	v_mov_b32_e32 v23, v35
	v_pk_fma_f32 v[18:19], v[18:19], v[18:19], v[20:21]
	v_mov_b32_e32 v20, v42
	v_mov_b32_e32 v21, v34
	v_pk_mul_f32 v[22:23], v[22:23], v[22:23]
	s_mov_b64 s[36:37], 0
	v_pk_fma_f32 v[20:21], v[20:21], v[20:21], v[22:23]
	s_nop 0
	v_pk_add_f32 v[18:19], v[18:19], v[20:21]
	s_nop 0
	v_pk_add_f32 v[16:17], v[16:17], v[18:19]
	s_nop 0
	v_add_f32_e32 v16, v16, v17
	v_mov_b32_e32 v17, v201
	s_nop 0
	v_lshlrev_b32_e32 v17, 2, v17
	v_xor_b32_e32 v17, 64, v17
	v_mov_b32_e32 v17, v16
	s_nop 1
	v_permlane16_swap_b32_e32 v17, v16
	s_waitcnt lgkmcnt(0)
	v_add_f32_e32 v16, v16, v17
	v_mov_b32_e32 v17, v201
	s_nop 0
	v_lshlrev_b32_e32 v17, 2, v17
	v_xor_b32_e32 v17, 0x80, v17
	v_mov_b32_e32 v17, v16
	s_nop 1
	v_permlane32_swap_b32_e32 v17, v16
	s_waitcnt lgkmcnt(0)
	v_add_f32_e32 v16, v16, v17
	v_fmamk_f32 v16, v16, 0x3c800000, v202
	v_rsq_f32_e32 v28, v16
	s_nop 0
	v_pk_mul_f32 v[16:17], v[40:41], v[28:29] op_sel_hi:[1,0]
	v_pk_mul_f32 v[18:19], v[46:47], v[28:29] op_sel_hi:[1,0]
	v_pk_mul_f32 v[20:21], v[44:45], v[28:29] op_sel_hi:[1,0]
	v_pk_mul_f32 v[22:23], v[42:43], v[28:29] op_sel_hi:[1,0]
	v_pk_mul_f32 v[24:25], v[38:39], v[28:29] op_sel_hi:[1,0]
	v_pk_mul_f32 v[26:27], v[36:37], v[28:29] op_sel_hi:[1,0]
	v_pk_mul_f32 v[48:49], v[32:33], v[28:29] op_sel_hi:[1,0]
	v_pk_mul_f32 v[28:29], v[34:35], v[28:29] op_sel_hi:[1,0]
	v_pk_mul_f32 v[18:19], v[162:163], v[18:19]
	v_pk_mul_f32 v[16:17], v[164:165], v[16:17]
	v_pk_mul_f32 v[22:23], v[158:159], v[22:23]
	v_pk_mul_f32 v[20:21], v[160:161], v[20:21]
	v_pk_mul_f32 v[26:27], v[154:155], v[26:27]
	v_pk_mul_f32 v[24:25], v[156:157], v[24:25]
	v_pk_mul_f32 v[30:31], v[150:151], v[28:29]
	v_pk_mul_f32 v[28:29], v[152:153], v[48:49]

; __device__ __forceinline__ float row_finish(float t) { t += shx(t, 16); t += shx(t, 32); return __builtin_amdgcn_rsqf(t * (1.0f / 1024.0f) + RMS_EPS); }
; __device__ __forceinline__ f32x4 silu4(f32x4 v) { return (f32x4){silu_f(v[0]), silu_f(v[1]), silu_f(v[2]), silu_f(v[3])}; }
; __device__ __forceinline__ float sq4(f32x4 v) { return (v[0] * v[0] + v[1] * v[1]) + (v[2] * v[2] + v[3] * v[3]); }
; __device__ __forceinline__ u32x4 pack8(f32x4 a, f32x4 b) { u32x4 w; w.x = cvt_pk_bf16(a[0], a[1]); w.y = cvt_pk_bf16(a[2], a[3]); w.z = cvt_pk_bf16(b[0], b[1]); w.w = cvt_pk_bf16(b[2], b[3]); return w; }
;     __device__ __forceinline__ void operator()(const f32x4 (&acc)[2][2][4][2], const Unit& u, int wr, int wc, int fr, int fq) const {
;     ...
;             for (int m = 0; m < 4; ++m) rs[ai][m] = row_finish(rs[ai][m]);
; #pragma unroll
;         for (int ai = 0; ai < 2; ++ai)
; #pragma unroll
;             for (int m = 0; m < 4; ++m) {
;                 const int row = u.pm * BM + ai * HALF + wr * 64 + m * 16 + fr;
;                 const float rstd = rs[ai][m];
;                 f32x4 v[2][2];
; #pragma unroll
;                 for (int bj = 0; bj < 2; ++bj)
; #pragma unroll
;                     for (int n = 0; n < 2; ++n) v[bj][n] = acc[ai][bj][m][n] * rstd;
;                 if (mode == 2) {
;                     float q = (sq4(v[0][0]) + sq4(v[0][1])) + (sq4(v[1][0]) + sq4(v[1][1]));
;                     q += shx(q, 16); q += shx(q, 32);
;                     const float r2 = __builtin_amdgcn_rsqf(q * (1.0f / 64.0f) + RMS_EPS);
; #pragma unroll
;                     for (int bj = 0; bj < 2; ++bj)
; #pragma unroll
;                         for (int n = 0; n < 2; ++n) v[bj][n] = v[bj][n] * r2 * wv[bj][n];
;                 } else if (mode == 1) {
; #pragma unroll
;                     for (int bj = 0; bj < 2; ++bj)
; #pragma unroll
;                         for (int n = 0; n < 2; ++n) v[bj][n] = silu4(v[bj][n]);
;                 } else {
; #pragma unroll
;                     for (int bj = 0; bj < 2; ++bj)
; #pragma unroll
;                         for (int n = 0; n < 2; ++n) v[bj][n] = v[bj][n] * sc;
;                 }
;                 bf16_t* rowp = U + (size_t)row * 2560 + lcol;
; #pragma unroll
;                 for (int bj = 0; bj < 2; ++bj) *(u32x4*)(rowp + 32 * bj) = pack8(v[bj][0], v[bj][1]);
.LBB0_172:
	s_waitcnt lgkmcnt(0)
	v_add_f32_e32 v32, v149, v167
	v_fmamk_f32 v32, v32, 0x3a800000, v202
	v_rsq_f32_e32 v32, v32
	v_mov_b64_e32 v[34:35], s[14:15]
	v_mad_i64_i32 v[34:35], s[36:37], v166, s56, v[34:35]
	v_lshl_add_u64 v[34:35], v[170:171], 1, v[34:35]
	v_cvt_pk_bf16_f32 v16, v16, v17
	v_cvt_pk_bf16_f32 v17, v18, v19
	v_cvt_pk_bf16_f32 v18, v20, v21
	v_cvt_pk_bf16_f32 v19, v22, v23
	global_store_dwordx4 v[34:35], v[16:19], off sc1
	v_pk_mul_f32 v[20:21], v[6:7], v[32:33] op_sel_hi:[1,0]
	v_pk_mul_f32 v[22:23], v[4:5], v[32:33] op_sel_hi:[1,0]
	v_cvt_pk_bf16_f32 v16, v24, v25
	v_cvt_pk_bf16_f32 v17, v26, v27
	v_cvt_pk_bf16_f32 v18, v28, v29
	v_cvt_pk_bf16_f32 v19, v30, v31
	global_store_dwordx4 v[34:35], v[16:19], off offset:64 sc1
	v_pk_mul_f32 v[30:31], v[14:15], v[32:33] op_sel_hi:[1,0]
	v_pk_mul_f32 v[24:25], v[12:13], v[32:33] op_sel_hi:[1,0]
	v_pk_mul_f32 v[26:27], v[10:11], v[32:33] op_sel_hi:[1,0]
	v_pk_mul_f32 v[28:29], v[8:9], v[32:33] op_sel_hi:[1,0]
	v_pk_mul_f32 v[18:19], v[2:3], v[32:33] op_sel_hi:[1,0]
	v_pk_mul_f32 v[16:17], v[0:1], v[32:33] op_sel_hi:[1,0]
	s_mov_b64 s[36:37], -1
	s_and_b64 vcc, exec, s[34:35]
	s_cbranch_vccz .LBB0_174
	v_mov_b32_e32 v2, v25
	v_mov_b32_e32 v3, v23
	v_mov_b32_e32 v0, v24
	v_mov_b32_e32 v1, v22
	v_pk_mul_f32 v[2:3], v[2:3], v[2:3]
	v_mov_b32_e32 v4, v31
	v_mov_b32_e32 v5, v21
	v_pk_fma_f32 v[0:1], v[0:1], v[0:1], v[2:3]
	v_mov_b32_e32 v2, v30
	v_mov_b32_e32 v3, v20
	v_pk_mul_f32 v[4:5], v[4:5], v[4:5]
	v_mov_b32_e32 v6, v27
	v_pk_fma_f32 v[2:3], v[2:3], v[2:3], v[4:5]
	v_mov_b32_e32 v4, v29
	v_mov_b32_e32 v5, v17
	v_pk_add_f32 v[0:1], v[0:1], v[2:3]
	v_mov_b32_e32 v2, v28
	v_mov_b32_e32 v3, v16
	v_pk_mul_f32 v[4:5], v[4:5], v[4:5]
	v_mov_b32_e32 v7, v19
	v_pk_fma_f32 v[2:3], v[2:3], v[2:3], v[4:5]
	v_mov_b32_e32 v4, v26
	v_mov_b32_e32 v5, v18
	v_pk_mul_f32 v[6:7], v[6:7], v[6:7]
	s_mov_b64 s[36:37], 0
	v_pk_fma_f32 v[4:5], v[4:5], v[4:5], v[6:7]
	s_nop 0
	v_pk_add_f32 v[2:3], v[2:3], v[4:5]
	s_nop 0
	v_pk_add_f32 v[0:1], v[0:1], v[2:3]
	s_nop 0
	v_add_f32_e32 v0, v0, v1
	v_mov_b32_e32 v1, v201
	s_nop 0
	v_lshlrev_b32_e32 v1, 2, v1
	v_xor_b32_e32 v1, 64, v1
	v_mov_b32_e32 v1, v0
	s_nop 1
	v_permlane16_swap_b32_e32 v1, v0
	s_waitcnt lgkmcnt(0)
	v_add_f32_e32 v0, v0, v1
	v_mov_b32_e32 v1, v201
	s_nop 0
	v_lshlrev_b32_e32 v1, 2, v1
	v_xor_b32_e32 v1, 0x80, v1
	v_mov_b32_e32 v1, v0
	s_nop 1
	v_permlane32_swap_b32_e32 v1, v0
	s_waitcnt lgkmcnt(0)
	v_add_f32_e32 v0, v0, v1
	v_fmamk_f32 v0, v0, 0x3c800000, v202
	v_rsq_f32_e32 v12, v0
	s_nop 0
	v_pk_mul_f32 v[0:1], v[24:25], v[12:13] op_sel_hi:[1,0]
	v_pk_mul_f32 v[2:3], v[30:31], v[12:13] op_sel_hi:[1,0]
	v_pk_mul_f32 v[4:5], v[28:29], v[12:13] op_sel_hi:[1,0]
	v_pk_mul_f32 v[6:7], v[26:27], v[12:13] op_sel_hi:[1,0]
	v_pk_mul_f32 v[8:9], v[22:23], v[12:13] op_sel_hi:[1,0]
	v_pk_mul_f32 v[10:11], v[20:21], v[12:13] op_sel_hi:[1,0]
	v_pk_mul_f32 v[32:33], v[16:17], v[12:13] op_sel_hi:[1,0]
	v_pk_mul_f32 v[12:13], v[18:19], v[12:13] op_sel_hi:[1,0]
	v_pk_mul_f32 v[2:3], v[162:163], v[2:3]
	v_pk_mul_f32 v[0:1], v[164:165], v[0:1]
	v_pk_mul_f32 v[6:7], v[158:159], v[6:7]
	v_pk_mul_f32 v[4:5], v[160:161], v[4:5]
	v_pk_mul_f32 v[10:11], v[154:155], v[10:11]
	v_pk_mul_f32 v[8:9], v[156:157], v[8:9]
	v_pk_mul_f32 v[14:15], v[150:151], v[12:13]
	v_pk_mul_f32 v[12:13], v[152:153], v[32:33]

; __device__ __forceinline__ u32x4 pack8(f32x4 a, f32x4 b) { u32x4 w; w.x = cvt_pk_bf16(a[0], a[1]); w.y = cvt_pk_bf16(a[2], a[3]); w.z = cvt_pk_bf16(b[0], b[1]); w.w = cvt_pk_bf16(b[2], b[3]); return w; }
; #define PG8_BAR __builtin_amdgcn_s_barrier()
;     __device__ __forceinline__ void operator()(const f32x4 (&acc)[2][2][4][2], const Unit& u, int wr, int wc, int fr, int fq) const {
;     ...
;                 bf16_t* rowp = U + (size_t)row * 2560 + lcol;
; #pragma unroll
;                 for (int bj = 0; bj < 2; ++bj) *(u32x4*)(rowp + 32 * bj) = pack8(v[bj][0], v[bj][1]);
; template <class Epi, class Sched, bool ALIGN_EPI = false, bool SP2 = false>
; __device__ __forceinline__ void gemm_phase(PG8_LAS unsigned char* lds, const Gemm g, const Sched& S, const Epi& E, int tid_in) {
;     ...
;         if constexpr (!Epi::AFTER_DRAIN) { E(acc, cur, wr, wc, fr, fq); S.done(cur); }
;         if (!has_next) break;
; #pragma unroll
;         for (int a = 0; a < 2; ++a)
; #pragma unroll
;             for (int b = 0; b < 2; ++b)
; #pragma unroll
;                 for (int m = 0; m < 4; ++m)
; #pragma unroll
;                     for (int n = 0; n < 2; ++n) acc[a][b][m][n] = (f32x4){0.f, 0.f, 0.f, 0.f};
;         cur = nxt; cA = nA; cB = nB; ++ui;
;         if constexpr (ALIGN_EPI) { if (wr == 1) PG8_BAR; }
;     }
.LBB0_179:
	v_mov_b64_e32 v[16:17], s[14:15]
	v_mad_i64_i32 v[16:17], s[26:27], v148, s56, v[16:17]
	v_lshl_add_u64 v[16:17], v[170:171], 1, v[16:17]
	v_cvt_pk_bf16_f32 v0, v0, v1
	v_cvt_pk_bf16_f32 v1, v2, v3
	v_cvt_pk_bf16_f32 v2, v4, v5
	v_cvt_pk_bf16_f32 v3, v6, v7
	s_andn2_b64 vcc, exec, s[4:5]
	s_mov_b64 s[4:5], -1
	global_store_dwordx4 v[16:17], v[0:3], off sc1
	s_nop 1
	v_cvt_pk_bf16_f32 v0, v8, v9
	v_cvt_pk_bf16_f32 v1, v10, v11
	v_cvt_pk_bf16_f32 v2, v12, v13
	v_cvt_pk_bf16_f32 v3, v14, v15
	global_store_dwordx4 v[16:17], v[0:3], off offset:64 sc1
	s_cbranch_vccnz .LBB0_116
	s_andn2_b64 vcc, exec, s[12:13]
	s_cbranch_vccnz .LBB0_115
	s_barrier
	s_branch .LBB0_115

; __device__ __forceinline__ float sq4(f32x4 v) { return (v[0] * v[0] + v[1] * v[1]) + (v[2] * v[2] + v[3] * v[3]); }
; __device__ __forceinline__ u32x4 pack8(f32x4 a, f32x4 b) { u32x4 w; w.x = cvt_pk_bf16(a[0], a[1]); w.y = cvt_pk_bf16(a[2], a[3]); w.z = cvt_pk_bf16(b[0], b[1]); w.w = cvt_pk_bf16(b[2], b[3]); return w; }
;     __device__ __forceinline__ void operator()(const f32x4 (&acc)[2][2][4][2], const Unit& u, int wr, int wc, int fr, int fq) const {
;     ...
;         for (int ai = 0; ai < 2; ++ai) {
;             u32x4 bs[4][2];
; #pragma unroll
;             for (int m = 0; m < 4; ++m)
; #pragma unroll
;                 for (int bj = 0; bj < 2; ++bj) bs[m][bj] = *(const u32x4*)(xb + (size_t)(u.pm * BM + ai * HALF + wr * 64 + m * 16 + fr) * 1024 + col0 + 128 * bj);
; #pragma unroll
;             for (int m = 0; m < 4; ++m) {
;                 const int row = u.pm * BM + ai * HALF + wr * 64 + m * 16 + fr;
;                 float q = 0.f;
; #pragma unroll
;                 for (int bj = 0; bj < 2; ++bj) {
;                     const size_t off = (size_t)row * 1024 + col0 + 128 * bj; const u32x4 w = bs[m][bj];
;                     const f32x4 b0 = (f32x4){__builtin_bit_cast(float, w.x << 16), __builtin_bit_cast(float, w.x & 0xffff0000u), __builtin_bit_cast(float, w.y << 16), __builtin_bit_cast(float, w.y & 0xffff0000u)};
;                     const f32x4 b1 = (f32x4){__builtin_bit_cast(float, w.z << 16), __builtin_bit_cast(float, w.z & 0xffff0000u), __builtin_bit_cast(float, w.w << 16), __builtin_bit_cast(float, w.w & 0xffff0000u)};
;                     const f32x4 v0 = acc[ai][bj][m][0] + b0, v1 = acc[ai][bj][m][1] + b1;
;                     if (last) { __builtin_nontemporal_store(v0, (f32x4*)(out + off)); __builtin_nontemporal_store(v1, (f32x4*)(out + off + 4)); }
;                     else { q += sq4(v0) + sq4(v1); *(u32x4*)(xb + off) = pack8(v0, v1); }
;                 }
;                 if (!last) { q += shx(q, 16); q += shx(q, 32); if (fq == 0) ss[(size_t)row * 16 + u.pn * 4 + wc] = q; }
.LBB0_439:
	v_lshl_or_b32 v168, s14, 8, v188
	v_lshl_add_u32 v172, s42, 8, v186
	v_ashrrev_i32_e32 v169, 31, v168
	v_lshlrev_b64 v[202:203], 1, v[168:169]
	v_ashrrev_i32_e32 v173, 31, v172
	v_lshl_add_u64 v[170:171], s[18:19], 0, v[202:203]
	v_lshlrev_b64 v[204:205], 11, v[172:173]
	v_lshl_add_u64 v[128:129], v[170:171], 0, v[204:205]
	global_load_dwordx4 v[192:195], v[128:129], off
	global_load_dwordx4 v[196:199], v[128:129], off offset:256
	v_or_b32_e32 v182, 16, v172
	v_or_b32_e32 v178, 32, v172
	v_or_b32_e32 v174, 48, v172
	v_ashrrev_i32_e32 v183, 31, v182
	v_ashrrev_i32_e32 v179, 31, v178
	v_ashrrev_i32_e32 v175, 31, v174
	v_lshlrev_b64 v[184:185], 11, v[182:183]
	v_lshlrev_b64 v[180:181], 11, v[178:179]
	v_lshlrev_b64 v[176:177], 11, v[174:175]
	v_lshl_add_u64 v[128:129], v[170:171], 0, v[184:185]
	v_lshl_add_u64 v[130:131], v[170:171], 0, v[180:181]
	v_lshl_add_u64 v[206:207], v[170:171], 0, v[176:177]
	global_load_dwordx4 v[148:151], v[128:129], off
	global_load_dwordx4 v[144:147], v[128:129], off offset:256
	global_load_dwordx4 v[140:143], v[130:131], off
	global_load_dwordx4 v[136:139], v[130:131], off offset:256
	global_load_dwordx4 v[132:135], v[206:207], off
	s_nop 0
	global_load_dwordx4 v[128:131], v[206:207], off offset:256
	v_lshl_add_u64 v[204:205], s[18:19], 0, v[204:205]
	v_lshl_add_u64 v[202:203], v[204:205], 0, v[202:203]
	v_mov_b32_e32 v200, v201
	s_lshl_b32 s42, s14, 2
	s_ashr_i32 s43, s42, 31
	s_waitcnt vmcnt(0)
	v_lshlrev_b32_e32 v204, 16, v192
	v_and_b32_e32 v205, 0xffff0000, v192
	v_lshlrev_b32_e32 v192, 16, v193
	v_and_b32_e32 v193, 0xffff0000, v193
	v_lshlrev_b32_e32 v206, 16, v194
	v_and_b32_e32 v207, 0xffff0000, v194
	v_lshlrev_b32_e32 v194, 16, v195
	v_and_b32_e32 v195, 0xffff0000, v195
	v_lshlrev_b32_e32 v208, 16, v196
	v_and_b32_e32 v209, 0xffff0000, v196
	v_lshlrev_b32_e32 v196, 16, v197
	v_and_b32_e32 v197, 0xffff0000, v197
	v_lshlrev_b32_e32 v210, 16, v198
	v_and_b32_e32 v211, 0xffff0000, v198
	v_lshlrev_b32_e32 v198, 16, v199
	v_and_b32_e32 v199, 0xffff0000, v199
	v_pk_add_f32 v[126:127], v[126:127], v[192:193]
	v_pk_add_f32 v[124:125], v[124:125], v[204:205]
	v_pk_add_f32 v[122:123], v[122:123], v[194:195]
	v_pk_add_f32 v[120:121], v[120:121], v[206:207]
	v_pk_add_f32 v[118:119], v[118:119], v[196:197]
	v_pk_add_f32 v[116:117], v[116:117], v[208:209]
	v_pk_add_f32 v[192:193], v[114:115], v[198:199]
	v_pk_add_f32 v[194:195], v[112:113], v[210:211]
	v_mul_f32_e32 v196, v125, v125
	v_mul_f32_e32 v197, v127, v127
	v_mul_f32_e32 v198, v121, v121
	v_mul_f32_e32 v199, v123, v123
	v_cvt_pk_bf16_f32 v112, v124, v125
	v_cvt_pk_bf16_f32 v113, v126, v127
	v_cvt_pk_bf16_f32 v114, v120, v121
	v_cvt_pk_bf16_f32 v115, v122, v123
	v_mul_f32_e32 v121, v117, v117
	v_mul_f32_e32 v123, v119, v119
	v_mul_f32_e32 v125, v195, v195
	v_mul_f32_e32 v127, v193, v193
	v_fmac_f32_e32 v196, v124, v124
	v_fmac_f32_e32 v197, v126, v126
	v_fmac_f32_e32 v198, v120, v120
	v_fmac_f32_e32 v199, v122, v122
	v_fmac_f32_e32 v121, v116, v116
	v_fmac_f32_e32 v123, v118, v118
	v_fmac_f32_e32 v125, v194, v194
	v_fmac_f32_e32 v127, v192, v192
	global_store_dwordx4 v[202:203], v[112:115], off sc1
	s_nop 1
	v_cvt_pk_bf16_f32 v112, v116, v117
	v_cvt_pk_bf16_f32 v113, v118, v119
	v_cvt_pk_bf16_f32 v114, v194, v195
	v_add_f32_e32 v116, v196, v197
	v_add_f32_e32 v117, v198, v199
	v_add_f32_e32 v118, v121, v123
	v_add_f32_e32 v119, v125, v127
	v_cvt_pk_bf16_f32 v115, v192, v193
	global_store_dwordx4 v[202:203], v[112:115], off offset:256 sc1
	s_nop 1
	v_add_f32_e32 v112, v116, v117
	v_add_f32_e32 v113, v118, v119
	v_lshlrev_b32_e32 v114, 2, v200
	v_add_f32_e32 v112, v112, v113
	v_xor_b32_e32 v113, 64, v114
	v_mov_b32_e32 v113, v112
	s_nop 1
	v_permlane16_swap_b32_e32 v113, v112
	v_mov_b32_e32 v114, v201
	s_waitcnt lgkmcnt(0)
	v_add_f32_e32 v112, v112, v113
	v_lshlrev_b32_e32 v114, 2, v114
	v_xor_b32_e32 v113, 0x80, v114
	v_mov_b32_e32 v113, v112
	s_nop 1
	v_permlane32_swap_b32_e32 v113, v112
	s_and_saveexec_b64 s[44:45], s[10:11]
	s_cbranch_execz .LBB0_441
	s_waitcnt lgkmcnt(0)
	v_add_f32_e32 v114, v112, v113
	v_lshlrev_b64 v[112:113], 6, v[172:173]
	v_lshl_add_u64 v[112:113], s[22:23], 0, v[112:113]
	v_lshl_add_u64 v[112:113], s[42:43], 2, v[112:113]
	s_lshl_b32 s14, s52, 2
	v_lshl_add_u64 v[112:113], v[112:113], 0, s[14:15]
	global_store_dword v[112:113], v114, off sc1
; __device__ __forceinline__ float sq4(f32x4 v) { return (v[0] * v[0] + v[1] * v[1]) + (v[2] * v[2] + v[3] * v[3]); }
; __device__ __forceinline__ u32x4 pack8(f32x4 a, f32x4 b) { u32x4 w; w.x = cvt_pk_bf16(a[0], a[1]); w.y = cvt_pk_bf16(a[2], a[3]); w.z = cvt_pk_bf16(b[0], b[1]); w.w = cvt_pk_bf16(b[2], b[3]); return w; }
;     __device__ __forceinline__ void operator()(const f32x4 (&acc)[2][2][4][2], const Unit& u, int wr, int wc, int fr, int fq) const {
;     ...
;             for (int m = 0; m < 4; ++m) {
;                 const int row = u.pm * BM + ai * HALF + wr * 64 + m * 16 + fr;
;                 float q = 0.f;
; #pragma unroll
;                 for (int bj = 0; bj < 2; ++bj) {
;                     const size_t off = (size_t)row * 1024 + col0 + 128 * bj; const u32x4 w = bs[m][bj];
;                     const f32x4 b0 = (f32x4){__builtin_bit_cast(float, w.x << 16), __builtin_bit_cast(float, w.x & 0xffff0000u), __builtin_bit_cast(float, w.y << 16), __builtin_bit_cast(float, w.y & 0xffff0000u)};
;                     const f32x4 b1 = (f32x4){__builtin_bit_cast(float, w.z << 16), __builtin_bit_cast(float, w.z & 0xffff0000u), __builtin_bit_cast(float, w.w << 16), __builtin_bit_cast(float, w.w & 0xffff0000u)};
;                     const f32x4 v0 = acc[ai][bj][m][0] + b0, v1 = acc[ai][bj][m][1] + b1;
;                     if (last) { __builtin_nontemporal_store(v0, (f32x4*)(out + off)); __builtin_nontemporal_store(v1, (f32x4*)(out + off + 4)); }
;                     else { q += sq4(v0) + sq4(v1); *(u32x4*)(xb + off) = pack8(v0, v1); }
;                 }
;                 if (!last) { q += shx(q, 16); q += shx(q, 32); if (fq == 0) ss[(size_t)row * 16 + u.pn * 4 + wc] = q; }
.LBB0_441:
	s_or_b64 exec, exec, s[44:45]
	v_lshlrev_b32_e32 v112, 16, v148
	s_waitcnt lgkmcnt(0)
	v_and_b32_e32 v113, 0xffff0000, v148
	v_lshlrev_b32_e32 v114, 16, v149
	v_and_b32_e32 v115, 0xffff0000, v149
	v_lshlrev_b32_e32 v116, 16, v150
	v_and_b32_e32 v117, 0xffff0000, v150
	v_lshlrev_b32_e32 v118, 16, v151
	v_and_b32_e32 v119, 0xffff0000, v151
	v_pk_add_f32 v[110:111], v[110:111], v[114:115]
	v_pk_add_f32 v[108:109], v[108:109], v[112:113]
	v_pk_add_f32 v[112:113], v[106:107], v[118:119]
	v_pk_add_f32 v[106:107], v[104:105], v[116:117]
	v_mul_f32_e32 v104, v109, v109
	v_mul_f32_e32 v105, v111, v111
	v_fmac_f32_e32 v104, v108, v108
	v_fmac_f32_e32 v105, v110, v110
	v_add_f32_e32 v104, v104, v105
	v_mul_f32_e32 v105, v107, v107
	v_mul_f32_e32 v114, v113, v113
	v_fmac_f32_e32 v105, v106, v106
	v_fmac_f32_e32 v114, v112, v112
	v_add_f32_e32 v105, v105, v114
	v_add_f32_e32 v114, v104, v105
	v_cvt_pk_bf16_f32 v104, v108, v109
	v_lshl_add_u64 v[108:109], s[18:19], 0, v[184:185]
	v_cvt_pk_bf16_f32 v105, v110, v111
	v_cvt_pk_bf16_f32 v106, v106, v107
	v_cvt_pk_bf16_f32 v107, v112, v113
	v_lshl_add_u64 v[108:109], v[168:169], 1, v[108:109]
	global_store_dwordx4 v[108:109], v[104:107], off sc1
	v_lshlrev_b32_e32 v110, 16, v146
	v_and_b32_e32 v111, 0xffff0000, v146
	v_lshlrev_b32_e32 v104, 16, v144
	v_and_b32_e32 v105, 0xffff0000, v144
	v_lshlrev_b32_e32 v106, 16, v145
	v_and_b32_e32 v107, 0xffff0000, v145
	v_lshlrev_b32_e32 v112, 16, v147
	v_and_b32_e32 v113, 0xffff0000, v147
	v_pk_add_f32 v[102:103], v[102:103], v[106:107]
	v_pk_add_f32 v[100:101], v[100:101], v[104:105]
	v_pk_add_f32 v[104:105], v[98:99], v[112:113]
	v_pk_add_f32 v[98:99], v[96:97], v[110:111]
	v_mul_f32_e32 v96, v101, v101
	v_mul_f32_e32 v97, v103, v103
	v_fmac_f32_e32 v96, v100, v100
	v_fmac_f32_e32 v97, v102, v102
	v_add_f32_e32 v96, v96, v97
	v_mul_f32_e32 v97, v99, v99
	v_mul_f32_e32 v106, v105, v105
	v_fmac_f32_e32 v97, v98, v98
	v_fmac_f32_e32 v106, v104, v104
	v_add_f32_e32 v97, v97, v106
	v_add_f32_e32 v96, v96, v97
	v_add_f32_e32 v106, v114, v96
	v_cvt_pk_bf16_f32 v96, v100, v101
	v_cvt_pk_bf16_f32 v97, v102, v103
	v_cvt_pk_bf16_f32 v98, v98, v99
	v_cvt_pk_bf16_f32 v99, v104, v105
	global_store_dwordx4 v[108:109], v[96:99], off offset:256 sc1
	s_nop 1
	v_mov_b32_e32 v96, v201
	v_mov_b32_e32 v97, v201
	v_lshlrev_b32_e32 v96, 2, v96
	v_xor_b32_e32 v96, 64, v96
	v_mov_b32_e32 v96, v106
	s_nop 1
	v_permlane16_swap_b32_e32 v96, v106
	s_waitcnt lgkmcnt(0)
	v_add_f32_e32 v96, v106, v96
	v_lshlrev_b32_e32 v97, 2, v97
	v_xor_b32_e32 v97, 0x80, v97
	v_mov_b32_e32 v97, v96
	s_nop 1
	v_permlane32_swap_b32_e32 v97, v96
	s_and_saveexec_b64 s[44:45], s[10:11]
	s_cbranch_execz .LBB0_443
	s_waitcnt lgkmcnt(0)
	v_add_f32_e32 v98, v96, v97
	v_lshlrev_b64 v[96:97], 6, v[182:183]
	v_lshl_add_u64 v[96:97], s[22:23], 0, v[96:97]
	v_lshl_add_u64 v[96:97], s[42:43], 2, v[96:97]
	s_lshl_b32 s14, s52, 2
	v_lshl_add_u64 v[96:97], v[96:97], 0, s[14:15]
	global_store_dword v[96:97], v98, off sc1
.LBB0_443:
	s_or_b64 exec, exec, s[44:45]
	v_lshlrev_b32_e32 v96, 16, v140
	s_waitcnt lgkmcnt(0)
	v_and_b32_e32 v97, 0xffff0000, v140
	v_lshlrev_b32_e32 v98, 16, v141
	v_and_b32_e32 v99, 0xffff0000, v141
	v_lshlrev_b32_e32 v100, 16, v142
	v_and_b32_e32 v101, 0xffff0000, v142
	v_lshlrev_b32_e32 v102, 16, v143
	v_and_b32_e32 v103, 0xffff0000, v143
	v_pk_add_f32 v[94:95], v[94:95], v[98:99]
	v_pk_add_f32 v[92:93], v[92:93], v[96:97]
	v_pk_add_f32 v[96:97], v[90:91], v[102:103]
	v_pk_add_f32 v[90:91], v[88:89], v[100:101]
	v_mul_f32_e32 v88, v93, v93
	v_mul_f32_e32 v89, v95, v95
	v_fmac_f32_e32 v88, v92, v92
	v_fmac_f32_e32 v89, v94, v94
	v_add_f32_e32 v88, v88, v89
	v_mul_f32_e32 v89, v91, v91
	v_mul_f32_e32 v98, v97, v97
	v_fmac_f32_e32 v89, v90, v90
	v_fmac_f32_e32 v98, v96, v96
	v_add_f32_e32 v89, v89, v98
	v_add_f32_e32 v98, v88, v89
	v_cvt_pk_bf16_f32 v88, v92, v93
	v_lshl_add_u64 v[92:93], s[18:19], 0, v[180:181]
	v_cvt_pk_bf16_f32 v89, v94, v95
	v_cvt_pk_bf16_f32 v90, v90, v91
	v_cvt_pk_bf16_f32 v91, v96, v97
	v_lshl_add_u64 v[92:93], v[168:169], 1, v[92:93]
	global_store_dwordx4 v[92:93], v[88:91], off sc1
	v_lshlrev_b32_e32 v94, 16, v138
	v_and_b32_e32 v95, 0xffff0000, v138
	v_lshlrev_b32_e32 v88, 16, v136
	v_and_b32_e32 v89, 0xffff0000, v136
	v_lshlrev_b32_e32 v90, 16, v137
	v_and_b32_e32 v91, 0xffff0000, v137
	v_lshlrev_b32_e32 v96, 16, v139
	v_and_b32_e32 v97, 0xffff0000, v139
	v_pk_add_f32 v[86:87], v[86:87], v[90:91]
	v_pk_add_f32 v[84:85], v[84:85], v[88:89]
	v_pk_add_f32 v[88:89], v[82:83], v[96:97]
	v_pk_add_f32 v[82:83], v[80:81], v[94:95]
	v_mul_f32_e32 v80, v85, v85
	v_mul_f32_e32 v81, v87, v87
	v_fmac_f32_e32 v80, v84, v84
	v_fmac_f32_e32 v81, v86, v86
	v_add_f32_e32 v80, v80, v81
	v_mul_f32_e32 v81, v83, v83
	v_mul_f32_e32 v90, v89, v89
	v_fmac_f32_e32 v81, v82, v82
	v_fmac_f32_e32 v90, v88, v88
	v_add_f32_e32 v81, v81, v90
	v_add_f32_e32 v80, v80, v81
	v_add_f32_e32 v90, v98, v80
	v_cvt_pk_bf16_f32 v80, v84, v85
	v_cvt_pk_bf16_f32 v81, v86, v87
	v_cvt_pk_bf16_f32 v82, v82, v83
	v_cvt_pk_bf16_f32 v83, v88, v89
	global_store_dwordx4 v[92:93], v[80:83], off offset:256 sc1
	s_nop 1
	v_mov_b32_e32 v80, v201
	v_mov_b32_e32 v81, v201
	v_lshlrev_b32_e32 v80, 2, v80
	v_xor_b32_e32 v80, 64, v80
	v_mov_b32_e32 v80, v90
	s_nop 1
	v_permlane16_swap_b32_e32 v80, v90
	s_waitcnt lgkmcnt(0)
	v_add_f32_e32 v80, v90, v80
	v_lshlrev_b32_e32 v81, 2, v81
	v_xor_b32_e32 v81, 0x80, v81
	v_mov_b32_e32 v81, v80
	s_nop 1
	v_permlane32_swap_b32_e32 v81, v80
	s_and_saveexec_b64 s[44:45], s[10:11]
	s_cbranch_execz .LBB0_445
	s_waitcnt lgkmcnt(0)
	v_add_f32_e32 v82, v80, v81
	v_lshlrev_b64 v[80:81], 6, v[178:179]
	v_lshl_add_u64 v[80:81], s[22:23], 0, v[80:81]
	v_lshl_add_u64 v[80:81], s[42:43], 2, v[80:81]
	s_lshl_b32 s14, s52, 2
	v_lshl_add_u64 v[80:81], v[80:81], 0, s[14:15]
	global_store_dword v[80:81], v82, off sc1
; __device__ __forceinline__ float sq4(f32x4 v) { return (v[0] * v[0] + v[1] * v[1]) + (v[2] * v[2] + v[3] * v[3]); }
; __device__ __forceinline__ u32x4 pack8(f32x4 a, f32x4 b) { u32x4 w; w.x = cvt_pk_bf16(a[0], a[1]); w.y = cvt_pk_bf16(a[2], a[3]); w.z = cvt_pk_bf16(b[0], b[1]); w.w = cvt_pk_bf16(b[2], b[3]); return w; }
;     __device__ __forceinline__ void operator()(const f32x4 (&acc)[2][2][4][2], const Unit& u, int wr, int wc, int fr, int fq) const {
;     ...
;         for (int ai = 0; ai < 2; ++ai) {
;             u32x4 bs[4][2];
; #pragma unroll
;             for (int m = 0; m < 4; ++m)
; #pragma unroll
;                 for (int bj = 0; bj < 2; ++bj) bs[m][bj] = *(const u32x4*)(xb + (size_t)(u.pm * BM + ai * HALF + wr * 64 + m * 16 + fr) * 1024 + col0 + 128 * bj);
; #pragma unroll
;             for (int m = 0; m < 4; ++m) {
;                 const int row = u.pm * BM + ai * HALF + wr * 64 + m * 16 + fr;
;                 float q = 0.f;
; #pragma unroll
;                 for (int bj = 0; bj < 2; ++bj) {
;                     const size_t off = (size_t)row * 1024 + col0 + 128 * bj; const u32x4 w = bs[m][bj];
;                     const f32x4 b0 = (f32x4){__builtin_bit_cast(float, w.x << 16), __builtin_bit_cast(float, w.x & 0xffff0000u), __builtin_bit_cast(float, w.y << 16), __builtin_bit_cast(float, w.y & 0xffff0000u)};
;                     const f32x4 b1 = (f32x4){__builtin_bit_cast(float, w.z << 16), __builtin_bit_cast(float, w.z & 0xffff0000u), __builtin_bit_cast(float, w.w << 16), __builtin_bit_cast(float, w.w & 0xffff0000u)};
;                     const f32x4 v0 = acc[ai][bj][m][0] + b0, v1 = acc[ai][bj][m][1] + b1;
;                     if (last) { __builtin_nontemporal_store(v0, (f32x4*)(out + off)); __builtin_nontemporal_store(v1, (f32x4*)(out + off + 4)); }
;                     else { q += sq4(v0) + sq4(v1); *(u32x4*)(xb + off) = pack8(v0, v1); }
;                 }
;                 if (!last) { q += shx(q, 16); q += shx(q, 32); if (fq == 0) ss[(size_t)row * 16 + u.pn * 4 + wc] = q; }
.LBB0_445:
	s_or_b64 exec, exec, s[44:45]
	v_lshlrev_b32_e32 v80, 16, v132
	s_waitcnt lgkmcnt(0)
	v_and_b32_e32 v81, 0xffff0000, v132
	v_lshlrev_b32_e32 v82, 16, v133
	v_and_b32_e32 v83, 0xffff0000, v133
	v_lshlrev_b32_e32 v84, 16, v134
	v_and_b32_e32 v85, 0xffff0000, v134
	v_lshlrev_b32_e32 v86, 16, v135
	v_and_b32_e32 v87, 0xffff0000, v135
	v_pk_add_f32 v[78:79], v[78:79], v[82:83]
	v_pk_add_f32 v[76:77], v[76:77], v[80:81]
	v_pk_add_f32 v[80:81], v[74:75], v[86:87]
	v_pk_add_f32 v[74:75], v[72:73], v[84:85]
	v_mul_f32_e32 v72, v77, v77
	v_mul_f32_e32 v73, v79, v79
	v_fmac_f32_e32 v72, v76, v76
	v_fmac_f32_e32 v73, v78, v78
	v_add_f32_e32 v72, v72, v73
	v_mul_f32_e32 v73, v75, v75
	v_mul_f32_e32 v82, v81, v81
	v_fmac_f32_e32 v73, v74, v74
	v_fmac_f32_e32 v82, v80, v80
	v_add_f32_e32 v73, v73, v82
	v_add_f32_e32 v82, v72, v73
	v_cvt_pk_bf16_f32 v72, v76, v77
	v_lshl_add_u64 v[76:77], s[18:19], 0, v[176:177]
	v_cvt_pk_bf16_f32 v73, v78, v79
	v_cvt_pk_bf16_f32 v74, v74, v75
	v_cvt_pk_bf16_f32 v75, v80, v81
	v_lshl_add_u64 v[76:77], v[168:169], 1, v[76:77]
	global_store_dwordx4 v[76:77], v[72:75], off sc1
	v_lshlrev_b32_e32 v78, 16, v130
	v_and_b32_e32 v79, 0xffff0000, v130
	v_lshlrev_b32_e32 v72, 16, v128
	v_and_b32_e32 v73, 0xffff0000, v128
	v_lshlrev_b32_e32 v74, 16, v129
	v_and_b32_e32 v75, 0xffff0000, v129
	v_lshlrev_b32_e32 v80, 16, v131
	v_and_b32_e32 v81, 0xffff0000, v131
	v_pk_add_f32 v[70:71], v[70:71], v[74:75]
	v_pk_add_f32 v[68:69], v[68:69], v[72:73]
	v_pk_add_f32 v[72:73], v[66:67], v[80:81]
	v_pk_add_f32 v[66:67], v[64:65], v[78:79]
	v_mul_f32_e32 v64, v69, v69
	v_mul_f32_e32 v65, v71, v71
	v_fmac_f32_e32 v64, v68, v68
	v_fmac_f32_e32 v65, v70, v70
	v_add_f32_e32 v64, v64, v65
	v_mul_f32_e32 v65, v67, v67
	v_mul_f32_e32 v74, v73, v73
	v_fmac_f32_e32 v65, v66, v66
	v_fmac_f32_e32 v74, v72, v72
	v_add_f32_e32 v65, v65, v74
	v_add_f32_e32 v64, v64, v65
	v_add_f32_e32 v74, v82, v64
	v_cvt_pk_bf16_f32 v64, v68, v69
	v_cvt_pk_bf16_f32 v65, v70, v71
	v_cvt_pk_bf16_f32 v66, v66, v67
	v_cvt_pk_bf16_f32 v67, v72, v73
	global_store_dwordx4 v[76:77], v[64:67], off offset:256 sc1
	s_nop 1
	v_mov_b32_e32 v64, v201
	v_mov_b32_e32 v65, v201
	v_lshlrev_b32_e32 v64, 2, v64
	v_xor_b32_e32 v64, 64, v64
	v_mov_b32_e32 v64, v74
	s_nop 1
	v_permlane16_swap_b32_e32 v64, v74
	s_waitcnt lgkmcnt(0)
	v_add_f32_e32 v64, v74, v64
	v_lshlrev_b32_e32 v65, 2, v65
	v_xor_b32_e32 v65, 0x80, v65
	v_mov_b32_e32 v65, v64
	s_nop 1
	v_permlane32_swap_b32_e32 v65, v64
	s_and_saveexec_b64 s[44:45], s[10:11]
	s_cbranch_execz .LBB0_447
	s_waitcnt lgkmcnt(0)
	v_add_f32_e32 v66, v64, v65
	v_lshlrev_b64 v[64:65], 6, v[174:175]
	v_lshl_add_u64 v[64:65], s[22:23], 0, v[64:65]
	v_lshl_add_u64 v[64:65], s[42:43], 2, v[64:65]
	s_lshl_b32 s14, s52, 2
	v_lshl_add_u64 v[64:65], v[64:65], 0, s[14:15]
	global_store_dword v[64:65], v66, off sc1
.LBB0_447:
	s_or_b64 exec, exec, s[44:45]
	v_add_u32_e32 v100, 0x80, v172
	v_ashrrev_i32_e32 v101, 31, v100
	v_lshlrev_b64 v[110:111], 11, v[100:101]
	s_waitcnt lgkmcnt(0)
	v_lshl_add_u64 v[64:65], v[170:171], 0, v[110:111]
	global_load_dwordx4 v[102:105], v[64:65], off
	global_load_dwordx4 v[106:109], v[64:65], off offset:256
	v_add_u32_e32 v96, 0x90, v172
	v_add_u32_e32 v92, 0xa0, v172
	v_add_u32_e32 v88, 0xb0, v172
	v_ashrrev_i32_e32 v97, 31, v96
	v_ashrrev_i32_e32 v93, 31, v92
	v_ashrrev_i32_e32 v89, 31, v88
	v_lshlrev_b64 v[98:99], 11, v[96:97]
	v_lshlrev_b64 v[94:95], 11, v[92:93]
	v_lshlrev_b64 v[90:91], 11, v[88:89]
	v_lshl_add_u64 v[64:65], v[170:171], 0, v[98:99]
	v_lshl_add_u64 v[66:67], v[170:171], 0, v[94:95]
	v_lshl_add_u64 v[112:113], v[170:171], 0, v[90:91]
	global_load_dwordx4 v[84:87], v[64:65], off
	global_load_dwordx4 v[80:83], v[64:65], off offset:256
	global_load_dwordx4 v[76:79], v[66:67], off
	global_load_dwordx4 v[72:75], v[66:67], off offset:256
	global_load_dwordx4 v[68:71], v[112:113], off
	s_nop 0
	global_load_dwordx4 v[64:67], v[112:113], off offset:256
	v_lshl_add_u64 v[110:111], s[18:19], 0, v[110:111]
	v_lshl_add_u64 v[110:111], v[168:169], 1, v[110:111]
	v_mov_b32_e32 v120, v201
	s_waitcnt vmcnt(7)
	v_lshlrev_b32_e32 v112, 16, v102
	v_and_b32_e32 v113, 0xffff0000, v102
	v_lshlrev_b32_e32 v102, 16, v103
	v_and_b32_e32 v103, 0xffff0000, v103
	v_lshlrev_b32_e32 v114, 16, v104
	v_and_b32_e32 v115, 0xffff0000, v104
	v_lshlrev_b32_e32 v104, 16, v105
	v_and_b32_e32 v105, 0xffff0000, v105
	s_waitcnt vmcnt(6)
	v_lshlrev_b32_e32 v116, 16, v106
	v_and_b32_e32 v117, 0xffff0000, v106
	v_lshlrev_b32_e32 v106, 16, v107
	v_and_b32_e32 v107, 0xffff0000, v107
	v_lshlrev_b32_e32 v118, 16, v108
	v_and_b32_e32 v119, 0xffff0000, v108
	v_lshlrev_b32_e32 v108, 16, v109
	v_and_b32_e32 v109, 0xffff0000, v109
	v_pk_add_f32 v[62:63], v[62:63], v[102:103]
	v_pk_add_f32 v[60:61], v[60:61], v[112:113]
	v_pk_add_f32 v[58:59], v[58:59], v[104:105]
	v_pk_add_f32 v[56:57], v[56:57], v[114:115]
	v_pk_add_f32 v[54:55], v[54:55], v[106:107]
	v_pk_add_f32 v[52:53], v[52:53], v[116:117]
	v_pk_add_f32 v[102:103], v[50:51], v[108:109]
	v_pk_add_f32 v[104:105], v[48:49], v[118:119]
	v_mul_f32_e32 v106, v61, v61
	v_mul_f32_e32 v107, v63, v63
	v_mul_f32_e32 v108, v57, v57
	v_mul_f32_e32 v109, v59, v59
	v_cvt_pk_bf16_f32 v48, v60, v61
	v_cvt_pk_bf16_f32 v49, v62, v63
	v_cvt_pk_bf16_f32 v50, v56, v57
	v_cvt_pk_bf16_f32 v51, v58, v59
	v_mul_f32_e32 v57, v53, v53
	v_mul_f32_e32 v59, v55, v55
	v_mul_f32_e32 v61, v105, v105
	v_mul_f32_e32 v63, v103, v103
	v_fmac_f32_e32 v106, v60, v60
	v_fmac_f32_e32 v107, v62, v62
	v_fmac_f32_e32 v108, v56, v56
	v_fmac_f32_e32 v109, v58, v58
	v_fmac_f32_e32 v57, v52, v52
	v_fmac_f32_e32 v59, v54, v54
	v_fmac_f32_e32 v61, v104, v104
	v_fmac_f32_e32 v63, v102, v102
	global_store_dwordx4 v[110:111], v[48:51], off sc1
	s_nop 1
	v_cvt_pk_bf16_f32 v48, v52, v53
	v_cvt_pk_bf16_f32 v49, v54, v55
	v_cvt_pk_bf16_f32 v50, v104, v105
	v_add_f32_e32 v52, v106, v107
	v_add_f32_e32 v53, v108, v109
	v_add_f32_e32 v54, v57, v59
	v_add_f32_e32 v55, v61, v63
	v_cvt_pk_bf16_f32 v51, v102, v103
	global_store_dwordx4 v[110:111], v[48:51], off offset:256 sc1
	s_nop 1
	v_add_f32_e32 v48, v52, v53
	v_add_f32_e32 v49, v54, v55
	v_lshlrev_b32_e32 v50, 2, v120
	v_add_f32_e32 v48, v48, v49
	v_xor_b32_e32 v49, 64, v50
	v_mov_b32_e32 v49, v48
	s_nop 1
	v_permlane16_swap_b32_e32 v49, v48
	v_mov_b32_e32 v50, v201
	s_waitcnt lgkmcnt(0)
	v_add_f32_e32 v48, v48, v49
	v_lshlrev_b32_e32 v50, 2, v50
	v_xor_b32_e32 v49, 0x80, v50
	v_mov_b32_e32 v49, v48
	s_nop 1
	v_permlane32_swap_b32_e32 v49, v48
	s_and_saveexec_b64 s[44:45], s[10:11]
	s_cbranch_execz .LBB0_449
	s_waitcnt lgkmcnt(0)
	v_add_f32_e32 v50, v48, v49
	v_lshlrev_b64 v[48:49], 6, v[100:101]
	v_lshl_add_u64 v[48:49], s[22:23], 0, v[48:49]
	v_lshl_add_u64 v[48:49], s[42:43], 2, v[48:49]
	s_lshl_b32 s14, s52, 2
	v_lshl_add_u64 v[48:49], v[48:49], 0, s[14:15]
	global_store_dword v[48:49], v50, off sc1
; __device__ __forceinline__ float sq4(f32x4 v) { return (v[0] * v[0] + v[1] * v[1]) + (v[2] * v[2] + v[3] * v[3]); }
; __device__ __forceinline__ u32x4 pack8(f32x4 a, f32x4 b) { u32x4 w; w.x = cvt_pk_bf16(a[0], a[1]); w.y = cvt_pk_bf16(a[2], a[3]); w.z = cvt_pk_bf16(b[0], b[1]); w.w = cvt_pk_bf16(b[2], b[3]); return w; }
;     __device__ __forceinline__ void operator()(const f32x4 (&acc)[2][2][4][2], const Unit& u, int wr, int wc, int fr, int fq) const {
;     ...
;             for (int m = 0; m < 4; ++m) {
;                 const int row = u.pm * BM + ai * HALF + wr * 64 + m * 16 + fr;
;                 float q = 0.f;
; #pragma unroll
;                 for (int bj = 0; bj < 2; ++bj) {
;                     const size_t off = (size_t)row * 1024 + col0 + 128 * bj; const u32x4 w = bs[m][bj];
;                     const f32x4 b0 = (f32x4){__builtin_bit_cast(float, w.x << 16), __builtin_bit_cast(float, w.x & 0xffff0000u), __builtin_bit_cast(float, w.y << 16), __builtin_bit_cast(float, w.y & 0xffff0000u)};
;                     const f32x4 b1 = (f32x4){__builtin_bit_cast(float, w.z << 16), __builtin_bit_cast(float, w.z & 0xffff0000u), __builtin_bit_cast(float, w.w << 16), __builtin_bit_cast(float, w.w & 0xffff0000u)};
;                     const f32x4 v0 = acc[ai][bj][m][0] + b0, v1 = acc[ai][bj][m][1] + b1;
;                     if (last) { __builtin_nontemporal_store(v0, (f32x4*)(out + off)); __builtin_nontemporal_store(v1, (f32x4*)(out + off + 4)); }
;                     else { q += sq4(v0) + sq4(v1); *(u32x4*)(xb + off) = pack8(v0, v1); }
;                 }
;                 if (!last) { q += shx(q, 16); q += shx(q, 32); if (fq == 0) ss[(size_t)row * 16 + u.pn * 4 + wc] = q; }
.LBB0_449:
	s_or_b64 exec, exec, s[44:45]
	s_waitcnt vmcnt(7)
	v_lshlrev_b32_e32 v48, 16, v84
	s_waitcnt lgkmcnt(0)
	v_and_b32_e32 v49, 0xffff0000, v84
	v_lshlrev_b32_e32 v50, 16, v85
	v_and_b32_e32 v51, 0xffff0000, v85
	v_lshlrev_b32_e32 v52, 16, v86
	v_and_b32_e32 v53, 0xffff0000, v86
	v_lshlrev_b32_e32 v54, 16, v87
	v_and_b32_e32 v55, 0xffff0000, v87
	v_pk_add_f32 v[46:47], v[46:47], v[50:51]
	v_pk_add_f32 v[44:45], v[44:45], v[48:49]
	v_pk_add_f32 v[48:49], v[42:43], v[54:55]
	v_pk_add_f32 v[42:43], v[40:41], v[52:53]
	v_mul_f32_e32 v40, v45, v45
	v_mul_f32_e32 v41, v47, v47
	v_fmac_f32_e32 v40, v44, v44
	v_fmac_f32_e32 v41, v46, v46
	v_add_f32_e32 v40, v40, v41
	v_mul_f32_e32 v41, v43, v43
	v_mul_f32_e32 v50, v49, v49
	v_fmac_f32_e32 v41, v42, v42
	v_fmac_f32_e32 v50, v48, v48
	v_add_f32_e32 v41, v41, v50
	v_add_f32_e32 v50, v40, v41
	v_cvt_pk_bf16_f32 v40, v44, v45
	v_lshl_add_u64 v[44:45], s[18:19], 0, v[98:99]
	v_cvt_pk_bf16_f32 v41, v46, v47
	v_cvt_pk_bf16_f32 v42, v42, v43
	v_cvt_pk_bf16_f32 v43, v48, v49
	v_lshl_add_u64 v[44:45], v[168:169], 1, v[44:45]
	global_store_dwordx4 v[44:45], v[40:43], off sc1
	s_waitcnt vmcnt(7)
	v_lshlrev_b32_e32 v46, 16, v82
	v_and_b32_e32 v47, 0xffff0000, v82
	v_lshlrev_b32_e32 v40, 16, v80
	v_and_b32_e32 v41, 0xffff0000, v80
	v_lshlrev_b32_e32 v42, 16, v81
	v_and_b32_e32 v43, 0xffff0000, v81
	v_lshlrev_b32_e32 v48, 16, v83
	v_and_b32_e32 v49, 0xffff0000, v83
	v_pk_add_f32 v[38:39], v[38:39], v[42:43]
	v_pk_add_f32 v[36:37], v[36:37], v[40:41]
	v_pk_add_f32 v[40:41], v[34:35], v[48:49]
	v_pk_add_f32 v[34:35], v[32:33], v[46:47]
	v_mul_f32_e32 v32, v37, v37
	v_mul_f32_e32 v33, v39, v39
	v_fmac_f32_e32 v32, v36, v36
	v_fmac_f32_e32 v33, v38, v38
	v_add_f32_e32 v32, v32, v33
	v_mul_f32_e32 v33, v35, v35
	v_mul_f32_e32 v42, v41, v41
	v_fmac_f32_e32 v33, v34, v34
	v_fmac_f32_e32 v42, v40, v40
	v_add_f32_e32 v33, v33, v42
	v_add_f32_e32 v32, v32, v33
	v_add_f32_e32 v42, v50, v32
	v_cvt_pk_bf16_f32 v32, v36, v37
	v_cvt_pk_bf16_f32 v33, v38, v39
	v_cvt_pk_bf16_f32 v34, v34, v35
	v_cvt_pk_bf16_f32 v35, v40, v41
	global_store_dwordx4 v[44:45], v[32:35], off offset:256 sc1
	s_nop 1
	v_mov_b32_e32 v32, v201
	v_mov_b32_e32 v33, v201
	v_lshlrev_b32_e32 v32, 2, v32
	v_xor_b32_e32 v32, 64, v32
	v_mov_b32_e32 v32, v42
	s_nop 1
	v_permlane16_swap_b32_e32 v32, v42
	s_waitcnt lgkmcnt(0)
	v_add_f32_e32 v32, v42, v32
	v_lshlrev_b32_e32 v33, 2, v33
	v_xor_b32_e32 v33, 0x80, v33
	v_mov_b32_e32 v33, v32
	s_nop 1
	v_permlane32_swap_b32_e32 v33, v32
	s_and_saveexec_b64 s[44:45], s[10:11]
	s_cbranch_execz .LBB0_451
	s_waitcnt lgkmcnt(0)
	v_add_f32_e32 v34, v32, v33
	v_lshlrev_b64 v[32:33], 6, v[96:97]
	v_lshl_add_u64 v[32:33], s[22:23], 0, v[32:33]
	v_lshl_add_u64 v[32:33], s[42:43], 2, v[32:33]
	s_lshl_b32 s14, s52, 2
	v_lshl_add_u64 v[32:33], v[32:33], 0, s[14:15]
	global_store_dword v[32:33], v34, off sc1
; __device__ __forceinline__ float sq4(f32x4 v) { return (v[0] * v[0] + v[1] * v[1]) + (v[2] * v[2] + v[3] * v[3]); }
; __device__ __forceinline__ u32x4 pack8(f32x4 a, f32x4 b) { u32x4 w; w.x = cvt_pk_bf16(a[0], a[1]); w.y = cvt_pk_bf16(a[2], a[3]); w.z = cvt_pk_bf16(b[0], b[1]); w.w = cvt_pk_bf16(b[2], b[3]); return w; }
;     __device__ __forceinline__ void operator()(const f32x4 (&acc)[2][2][4][2], const Unit& u, int wr, int wc, int fr, int fq) const {
;     ...
;             for (int m = 0; m < 4; ++m) {
;                 const int row = u.pm * BM + ai * HALF + wr * 64 + m * 16 + fr;
;                 float q = 0.f;
; #pragma unroll
;                 for (int bj = 0; bj < 2; ++bj) {
;                     const size_t off = (size_t)row * 1024 + col0 + 128 * bj; const u32x4 w = bs[m][bj];
;                     const f32x4 b0 = (f32x4){__builtin_bit_cast(float, w.x << 16), __builtin_bit_cast(float, w.x & 0xffff0000u), __builtin_bit_cast(float, w.y << 16), __builtin_bit_cast(float, w.y & 0xffff0000u)};
;                     const f32x4 b1 = (f32x4){__builtin_bit_cast(float, w.z << 16), __builtin_bit_cast(float, w.z & 0xffff0000u), __builtin_bit_cast(float, w.w << 16), __builtin_bit_cast(float, w.w & 0xffff0000u)};
;                     const f32x4 v0 = acc[ai][bj][m][0] + b0, v1 = acc[ai][bj][m][1] + b1;
;                     if (last) { __builtin_nontemporal_store(v0, (f32x4*)(out + off)); __builtin_nontemporal_store(v1, (f32x4*)(out + off + 4)); }
;                     else { q += sq4(v0) + sq4(v1); *(u32x4*)(xb + off) = pack8(v0, v1); }
;                 }
;                 if (!last) { q += shx(q, 16); q += shx(q, 32); if (fq == 0) ss[(size_t)row * 16 + u.pn * 4 + wc] = q; }
.LBB0_451:
	s_or_b64 exec, exec, s[44:45]
	s_waitcnt vmcnt(7)
	v_lshlrev_b32_e32 v32, 16, v76
	s_waitcnt lgkmcnt(0)
	v_and_b32_e32 v33, 0xffff0000, v76
	v_lshlrev_b32_e32 v34, 16, v77
	v_and_b32_e32 v35, 0xffff0000, v77
	v_lshlrev_b32_e32 v36, 16, v78
	v_and_b32_e32 v37, 0xffff0000, v78
	v_lshlrev_b32_e32 v38, 16, v79
	v_and_b32_e32 v39, 0xffff0000, v79
	v_pk_add_f32 v[30:31], v[30:31], v[34:35]
	v_pk_add_f32 v[28:29], v[28:29], v[32:33]
	v_pk_add_f32 v[32:33], v[26:27], v[38:39]
	v_pk_add_f32 v[26:27], v[24:25], v[36:37]
	v_mul_f32_e32 v24, v29, v29
	v_mul_f32_e32 v25, v31, v31
	v_fmac_f32_e32 v24, v28, v28
	v_fmac_f32_e32 v25, v30, v30
	v_add_f32_e32 v24, v24, v25
	v_mul_f32_e32 v25, v27, v27
	v_mul_f32_e32 v34, v33, v33
	v_fmac_f32_e32 v25, v26, v26
	v_fmac_f32_e32 v34, v32, v32
	v_add_f32_e32 v25, v25, v34
	v_add_f32_e32 v34, v24, v25
	v_cvt_pk_bf16_f32 v24, v28, v29
	v_lshl_add_u64 v[28:29], s[18:19], 0, v[94:95]
	v_cvt_pk_bf16_f32 v25, v30, v31
	v_cvt_pk_bf16_f32 v26, v26, v27
	v_cvt_pk_bf16_f32 v27, v32, v33
	v_lshl_add_u64 v[28:29], v[168:169], 1, v[28:29]
	global_store_dwordx4 v[28:29], v[24:27], off sc1
	s_waitcnt vmcnt(7)
	v_lshlrev_b32_e32 v30, 16, v74
	v_and_b32_e32 v31, 0xffff0000, v74
	v_lshlrev_b32_e32 v24, 16, v72
	v_and_b32_e32 v25, 0xffff0000, v72
	v_lshlrev_b32_e32 v26, 16, v73
	v_and_b32_e32 v27, 0xffff0000, v73
	v_lshlrev_b32_e32 v32, 16, v75
	v_and_b32_e32 v33, 0xffff0000, v75
	v_pk_add_f32 v[22:23], v[22:23], v[26:27]
	v_pk_add_f32 v[20:21], v[20:21], v[24:25]
	v_pk_add_f32 v[24:25], v[18:19], v[32:33]
	v_pk_add_f32 v[18:19], v[16:17], v[30:31]
	v_mul_f32_e32 v16, v21, v21
	v_mul_f32_e32 v17, v23, v23
	v_fmac_f32_e32 v16, v20, v20
	v_fmac_f32_e32 v17, v22, v22
	v_add_f32_e32 v16, v16, v17
	v_mul_f32_e32 v17, v19, v19
	v_mul_f32_e32 v26, v25, v25
	v_fmac_f32_e32 v17, v18, v18
	v_fmac_f32_e32 v26, v24, v24
	v_add_f32_e32 v17, v17, v26
	v_add_f32_e32 v16, v16, v17
	v_add_f32_e32 v26, v34, v16
	v_cvt_pk_bf16_f32 v16, v20, v21
	v_cvt_pk_bf16_f32 v17, v22, v23
	v_cvt_pk_bf16_f32 v18, v18, v19
	v_cvt_pk_bf16_f32 v19, v24, v25
	global_store_dwordx4 v[28:29], v[16:19], off offset:256 sc1
	s_nop 1
	v_mov_b32_e32 v16, v201
	v_mov_b32_e32 v17, v201
	v_lshlrev_b32_e32 v16, 2, v16
	v_xor_b32_e32 v16, 64, v16
	v_mov_b32_e32 v16, v26
	s_nop 1
	v_permlane16_swap_b32_e32 v16, v26
	s_waitcnt lgkmcnt(0)
	v_add_f32_e32 v16, v26, v16
	v_lshlrev_b32_e32 v17, 2, v17
	v_xor_b32_e32 v17, 0x80, v17
	v_mov_b32_e32 v17, v16
	s_nop 1
	v_permlane32_swap_b32_e32 v17, v16
	s_and_saveexec_b64 s[44:45], s[10:11]
	s_cbranch_execz .LBB0_453
	s_waitcnt lgkmcnt(0)
	v_add_f32_e32 v18, v16, v17
	v_lshlrev_b64 v[16:17], 6, v[92:93]
	v_lshl_add_u64 v[16:17], s[22:23], 0, v[16:17]
	v_lshl_add_u64 v[16:17], s[42:43], 2, v[16:17]
	s_lshl_b32 s14, s52, 2
	v_lshl_add_u64 v[16:17], v[16:17], 0, s[14:15]
	global_store_dword v[16:17], v18, off sc1
.LBB0_453:
	s_or_b64 exec, exec, s[44:45]
	s_waitcnt vmcnt(7)
	v_lshlrev_b32_e32 v16, 16, v68
	s_waitcnt lgkmcnt(0)
	v_and_b32_e32 v17, 0xffff0000, v68
	v_lshlrev_b32_e32 v18, 16, v69
	v_and_b32_e32 v19, 0xffff0000, v69
	v_lshlrev_b32_e32 v20, 16, v70
	v_and_b32_e32 v21, 0xffff0000, v70
	v_lshlrev_b32_e32 v22, 16, v71
	v_and_b32_e32 v23, 0xffff0000, v71
	v_pk_add_f32 v[14:15], v[14:15], v[18:19]
	v_pk_add_f32 v[12:13], v[12:13], v[16:17]
	v_pk_add_f32 v[16:17], v[10:11], v[22:23]
	v_pk_add_f32 v[10:11], v[8:9], v[20:21]
	v_mul_f32_e32 v8, v13, v13
	v_mul_f32_e32 v9, v15, v15
	v_fmac_f32_e32 v8, v12, v12
	v_fmac_f32_e32 v9, v14, v14
	v_add_f32_e32 v8, v8, v9
	v_mul_f32_e32 v9, v11, v11
	v_mul_f32_e32 v18, v17, v17
	v_fmac_f32_e32 v9, v10, v10
	v_fmac_f32_e32 v18, v16, v16
	v_add_f32_e32 v9, v9, v18
	v_add_f32_e32 v18, v8, v9
	v_cvt_pk_bf16_f32 v8, v12, v13
	v_lshl_add_u64 v[12:13], s[18:19], 0, v[90:91]
	v_cvt_pk_bf16_f32 v9, v14, v15
	v_cvt_pk_bf16_f32 v10, v10, v11
	v_cvt_pk_bf16_f32 v11, v16, v17
	v_lshl_add_u64 v[12:13], v[168:169], 1, v[12:13]
	global_store_dwordx4 v[12:13], v[8:11], off sc1
	s_waitcnt vmcnt(7)
	v_lshlrev_b32_e32 v14, 16, v66
	v_and_b32_e32 v15, 0xffff0000, v66
	v_lshlrev_b32_e32 v8, 16, v64
	v_and_b32_e32 v9, 0xffff0000, v64
	v_lshlrev_b32_e32 v10, 16, v65
	v_and_b32_e32 v11, 0xffff0000, v65
	v_lshlrev_b32_e32 v16, 16, v67
	v_and_b32_e32 v17, 0xffff0000, v67
	v_pk_add_f32 v[6:7], v[6:7], v[10:11]
	v_pk_add_f32 v[4:5], v[4:5], v[8:9]
	v_pk_add_f32 v[8:9], v[2:3], v[16:17]
	v_pk_add_f32 v[2:3], v[0:1], v[14:15]
	v_mul_f32_e32 v0, v5, v5
	v_mul_f32_e32 v1, v7, v7
	v_fmac_f32_e32 v0, v4, v4
	v_fmac_f32_e32 v1, v6, v6
	v_add_f32_e32 v0, v0, v1
	v_mul_f32_e32 v1, v3, v3
	v_mul_f32_e32 v10, v9, v9
	v_fmac_f32_e32 v1, v2, v2
	v_fmac_f32_e32 v10, v8, v8
	v_add_f32_e32 v1, v1, v10
	v_add_f32_e32 v0, v0, v1
	v_add_f32_e32 v10, v18, v0
	v_cvt_pk_bf16_f32 v0, v4, v5
	v_cvt_pk_bf16_f32 v1, v6, v7
	v_cvt_pk_bf16_f32 v2, v2, v3
	v_cvt_pk_bf16_f32 v3, v8, v9
	global_store_dwordx4 v[12:13], v[0:3], off offset:256 sc1
	s_nop 1
	v_mov_b32_e32 v0, v201
	v_mov_b32_e32 v1, v201
	v_lshlrev_b32_e32 v0, 2, v0
	v_xor_b32_e32 v0, 64, v0
	v_mov_b32_e32 v0, v10
	s_nop 1
	v_permlane16_swap_b32_e32 v0, v10
	s_waitcnt lgkmcnt(0)
	v_add_f32_e32 v0, v10, v0
	v_lshlrev_b32_e32 v1, 2, v1
	v_xor_b32_e32 v1, 0x80, v1
	v_mov_b32_e32 v1, v0
	s_nop 1
	v_permlane32_swap_b32_e32 v1, v0
	s_and_saveexec_b64 s[44:45], s[10:11]
	s_cbranch_execz .LBB0_455
	s_waitcnt lgkmcnt(0)
	v_add_f32_e32 v2, v0, v1
	v_lshlrev_b64 v[0:1], 6, v[88:89]
	v_lshl_add_u64 v[0:1], s[22:23], 0, v[0:1]
	v_lshl_add_u64 v[0:1], s[42:43], 2, v[0:1]
	s_lshl_b32 s14, s52, 2
	v_lshl_add_u64 v[0:1], v[0:1], 0, s[14:15]
	global_store_dword v[0:1], v2, off sc1

; __device__ __forceinline__ float row_part(const float* ss, int row, int fq) { const f32x4 a = ((const f32x4*)(ss + (size_t)row * 16))[fq]; return (a[0] + a[1]) + (a[2] + a[3]); }
; __device__ __forceinline__ float row_finish(float t) { t += shx(t, 16); t += shx(t, 32); return __builtin_amdgcn_rsqf(t * (1.0f / 1024.0f) + RMS_EPS); }
;     __device__ __forceinline__ void operator()(const f32x4 (&acc)[2][2][4][2], const Unit& u, int wr, int wc, int fr, int fq) const {
;     ...
;         float rs[2][4];
; #pragma unroll
;         for (int ai = 0; ai < 2; ++ai)
; #pragma unroll
;             for (int m = 0; m < 4; ++m) rs[ai][m] = row_part(ss, u.pm * BM + ai * HALF + wr * 64 + m * 16 + fr, fq);
; #pragma unroll
;         for (int ai = 0; ai < 2; ++ai)
; #pragma unroll
;             for (int m = 0; m < 4; ++m) rs[ai][m] = row_finish(rs[ai][m]);
.LBB0_523:
	v_lshl_add_u32 v170, s36, 8, v153
	v_ashrrev_i32_e32 v171, 31, v170
	v_or_b32_e32 v166, 16, v170
	v_lshlrev_b64 v[146:147], 6, v[170:171]
	v_ashrrev_i32_e32 v167, 31, v166
	v_lshl_add_u64 v[146:147], v[136:137], 0, v[146:147]
	v_lshlrev_b64 v[148:149], 6, v[166:167]
	v_lshl_add_u64 v[148:149], v[136:137], 0, v[148:149]
	ds_read_b128 v[176:179], v239
	ds_read_b128 v[180:183], v239 offset:1024
	v_or_b32_e32 v162, 32, v170
	v_ashrrev_i32_e32 v163, 31, v162
	v_or_b32_e32 v158, 48, v170
	v_lshlrev_b64 v[146:147], 6, v[162:163]
	v_ashrrev_i32_e32 v159, 31, v158
	v_lshl_add_u64 v[146:147], v[136:137], 0, v[146:147]
	v_lshlrev_b64 v[148:149], 6, v[158:159]
	v_lshl_add_u64 v[148:149], v[136:137], 0, v[148:149]
	ds_read_b128 v[184:187], v239 offset:2048
	ds_read_b128 v[188:191], v239 offset:3072
	v_add_u32_e32 v154, 0x80, v170
	v_ashrrev_i32_e32 v155, 31, v154
	v_add_u32_e32 v150, 0x90, v170
	v_lshlrev_b64 v[146:147], 6, v[154:155]
	v_ashrrev_i32_e32 v151, 31, v150
	v_lshl_add_u64 v[146:147], v[136:137], 0, v[146:147]
	v_lshlrev_b64 v[148:149], 6, v[150:151]
	v_lshl_add_u64 v[148:149], v[136:137], 0, v[148:149]
	ds_read_b128 v[192:195], v239 offset:8192
	ds_read_b128 v[196:199], v239 offset:9216
	v_add_u32_e32 v148, 0xa0, v170
	v_ashrrev_i32_e32 v149, 31, v148
	v_lshlrev_b64 v[146:147], 6, v[148:149]
	v_lshl_add_u64 v[146:147], v[136:137], 0, v[146:147]
	ds_read_b128 v[202:205], v239 offset:10240
	v_add_u32_e32 v146, 0xb0, v170
	v_ashrrev_i32_e32 v147, 31, v146
	v_lshlrev_b64 v[206:207], 6, v[146:147]
	v_lshl_add_u64 v[206:207], v[136:137], 0, v[206:207]
	ds_read_b128 v[206:209], v239 offset:11264
	v_mov_b32_e32 v147, v201
	v_mov_b32_e32 v149, v201
	v_lshlrev_b32_e32 v147, 2, v147
	v_mov_b32_e32 v151, v201
	v_xor_b32_e32 v147, 64, v147
	s_andn2_b64 vcc, exec, s[10:11]
	v_lshlrev_b32_e32 v151, 2, v151
	v_xor_b32_e32 v151, 64, v151
	v_lshlrev_b32_e32 v149, 2, v149
	v_xor_b32_e32 v149, 0x80, v149
	s_mov_b64 s[10:11], -1
	s_waitcnt lgkmcnt(0)
	v_mov_b32_e32 v210, v177
	v_mov_b32_e32 v211, v178
	v_mov_b32_e32 v177, v179
	v_pk_add_f32 v[176:177], v[210:211], v[176:177]
	v_mov_b32_e32 v178, v181
	v_add_f32_e32 v152, v176, v177
	v_mov_b32_e32 v179, v182
	v_mov_b32_e32 v181, v183
	v_mov_b32_e32 v147, v152
	s_nop 1
	v_permlane16_swap_b32_e32 v147, v152
	v_pk_add_f32 v[176:177], v[178:179], v[180:181]
	v_mov_b32_e32 v182, v185
	v_add_f32_e32 v155, v176, v177
	v_mov_b32_e32 v151, v155
	s_nop 1
	v_permlane16_swap_b32_e32 v151, v155
	s_waitcnt lgkmcnt(0)
	v_add_f32_e32 v147, v152, v147
	v_mov_b32_e32 v152, v201
	v_mov_b32_e32 v149, v147
	s_nop 1
	v_permlane32_swap_b32_e32 v149, v147
	s_waitcnt lgkmcnt(0)
	v_add_f32_e32 v151, v155, v151
	v_lshlrev_b32_e32 v152, 2, v152
	v_xor_b32_e32 v152, 0x80, v152
	v_mov_b32_e32 v152, v151
	s_nop 1
	v_permlane32_swap_b32_e32 v152, v151
	s_waitcnt lgkmcnt(0)
	v_add_f32_e32 v147, v147, v149
	v_mov_b32_e32 v149, v201
	v_mov_b32_e32 v183, v186
	v_mov_b32_e32 v185, v187
	v_pk_add_f32 v[178:179], v[182:183], v[184:185]
	v_fmamk_f32 v147, v147, 0x3a800000, v175
	v_lshlrev_b32_e32 v149, 2, v149
	v_add_f32_e32 v156, v178, v179
	v_rsq_f32_e32 v176, v147
	s_waitcnt lgkmcnt(0)
	v_add_f32_e32 v147, v151, v152
	v_xor_b32_e32 v149, 64, v149
	v_mov_b32_e32 v151, v201
	v_mov_b32_e32 v152, v201
	v_mov_b32_e32 v186, v189
	v_mov_b32_e32 v187, v190
	v_mov_b32_e32 v189, v191
	v_mov_b32_e32 v149, v156
	s_nop 1
	v_permlane16_swap_b32_e32 v149, v156
	v_pk_add_f32 v[180:181], v[186:187], v[188:189]
	v_lshlrev_b32_e32 v152, 2, v152
	v_add_f32_e32 v159, v180, v181
	v_xor_b32_e32 v152, 64, v152
	v_mov_b32_e32 v152, v159
	s_nop 1
	v_permlane16_swap_b32_e32 v152, v159
	s_waitcnt lgkmcnt(0)
	v_add_f32_e32 v149, v156, v149
	v_lshlrev_b32_e32 v151, 2, v151
	v_mov_b32_e32 v156, v201
	v_xor_b32_e32 v151, 0x80, v151
	v_mov_b32_e32 v151, v149
	s_nop 1
	v_permlane32_swap_b32_e32 v151, v149
	v_lshlrev_b32_e32 v156, 2, v156
	s_waitcnt lgkmcnt(0)
	v_add_f32_e32 v152, v159, v152
	v_xor_b32_e32 v156, 0x80, v156
	v_mov_b32_e32 v156, v152
	s_nop 1
	v_permlane32_swap_b32_e32 v156, v152
	v_fmamk_f32 v147, v147, 0x3a800000, v175
	v_rsq_f32_e32 v174, v147
	s_waitcnt lgkmcnt(0)
	v_add_f32_e32 v147, v149, v151
	v_mov_b32_e32 v149, v201
	v_mov_b32_e32 v190, v193
	v_mov_b32_e32 v191, v194
	v_mov_b32_e32 v193, v195
	v_fmamk_f32 v147, v147, 0x3a800000, v175
	v_pk_add_f32 v[182:183], v[190:191], v[192:193]
	v_rsq_f32_e32 v172, v147
	s_waitcnt lgkmcnt(0)
	v_add_f32_e32 v147, v152, v156
	v_lshlrev_b32_e32 v149, 2, v149
	v_mov_b32_e32 v151, v201
	v_mov_b32_e32 v152, v201
	v_mov_b32_e32 v194, v197
	v_mov_b32_e32 v195, v198
	v_mov_b32_e32 v197, v199
	v_add_f32_e32 v160, v182, v183
	v_xor_b32_e32 v149, 64, v149
	v_pk_add_f32 v[184:185], v[194:195], v[196:197]
	v_mov_b32_e32 v149, v160
	s_nop 1
	v_permlane16_swap_b32_e32 v149, v160
	v_lshlrev_b32_e32 v152, 2, v152
	v_add_f32_e32 v163, v184, v185
	v_xor_b32_e32 v152, 64, v152
	v_mov_b32_e32 v152, v163
	s_nop 1
	v_permlane16_swap_b32_e32 v152, v163
	v_lshlrev_b32_e32 v151, 2, v151
	v_mov_b32_e32 v156, v201
	s_waitcnt lgkmcnt(0)
	v_add_f32_e32 v149, v160, v149
	v_xor_b32_e32 v151, 0x80, v151
	v_mov_b32_e32 v151, v149
	s_nop 1
	v_permlane32_swap_b32_e32 v151, v149
	v_lshlrev_b32_e32 v156, 2, v156
	s_waitcnt lgkmcnt(0)
	v_add_f32_e32 v152, v163, v152
	v_xor_b32_e32 v156, 0x80, v156
	v_mov_b32_e32 v156, v152
	s_nop 1
	v_permlane32_swap_b32_e32 v156, v152
	v_fmamk_f32 v147, v147, 0x3a800000, v175
	v_rsq_f32_e32 v168, v147
	s_waitcnt lgkmcnt(0)
	v_add_f32_e32 v147, v149, v151
	v_fmamk_f32 v147, v147, 0x3a800000, v175
	v_rsq_f32_e32 v164, v147
	s_waitcnt lgkmcnt(0)
; __device__ __forceinline__ float row_finish(float t) { t += shx(t, 16); t += shx(t, 32); return __builtin_amdgcn_rsqf(t * (1.0f / 1024.0f) + RMS_EPS); }
; __device__ __forceinline__ f32x4 silu4(f32x4 v) { return (f32x4){silu_f(v[0]), silu_f(v[1]), silu_f(v[2]), silu_f(v[3])}; }
; __device__ __forceinline__ u32x4 pack8(f32x4 a, f32x4 b) { u32x4 w; w.x = cvt_pk_bf16(a[0], a[1]); w.y = cvt_pk_bf16(a[2], a[3]); w.z = cvt_pk_bf16(b[0], b[1]); w.w = cvt_pk_bf16(b[2], b[3]); return w; }
;     __device__ __forceinline__ void operator()(const f32x4 (&acc)[2][2][4][2], const Unit& u, int wr, int wc, int fr, int fq) const {
;     ...
;             for (int m = 0; m < 4; ++m) rs[ai][m] = row_finish(rs[ai][m]);
; #pragma unroll
;         for (int ai = 0; ai < 2; ++ai)
; #pragma unroll
;             for (int m = 0; m < 4; ++m) {
;                 const int row = u.pm * BM + ai * HALF + wr * 64 + m * 16 + fr;
;                 const float rstd = rs[ai][m];
;                 const f32x4 a0 = silu4(acc[ai][0][m][0] * rstd) * (acc[ai][1][m][0] * rstd);
;                 const f32x4 a1 = silu4(acc[ai][0][m][1] * rstd) * (acc[ai][1][m][1] * rstd);
;                 *(u32x4*)(ACT + (size_t)row * 2816 + col0) = pack8(a0, a1);
	v_add_f32_e32 v147, v152, v156
	v_mov_b32_e32 v149, v201
	v_mov_b32_e32 v151, v201
	v_mov_b32_e32 v152, v201
	v_mov_b32_e32 v198, v203
	v_mov_b32_e32 v199, v204
	v_mov_b32_e32 v203, v205
	v_mov_b32_e32 v204, v207
	v_mov_b32_e32 v205, v208
	v_mov_b32_e32 v207, v209
	v_pk_add_f32 v[188:189], v[204:205], v[206:207]
	v_lshlrev_b32_e32 v152, 2, v152
	v_pk_add_f32 v[186:187], v[198:199], v[202:203]
	v_add_f32_e32 v155, v188, v189
	v_lshlrev_b32_e32 v149, 2, v149
	v_xor_b32_e32 v152, 64, v152
	v_add_f32_e32 v167, v186, v187
	v_xor_b32_e32 v149, 64, v149
	v_mov_b32_e32 v152, v155
	s_nop 1
	v_permlane16_swap_b32_e32 v152, v155
	v_mov_b32_e32 v149, v167
	s_nop 1
	v_permlane16_swap_b32_e32 v149, v167
	v_lshlrev_b32_e32 v151, 2, v151
	v_xor_b32_e32 v151, 0x80, v151
	v_fmamk_f32 v147, v147, 0x3a800000, v175
	s_waitcnt lgkmcnt(0)
	v_add_f32_e32 v152, v155, v152
	v_mov_b32_e32 v155, v201
	s_waitcnt lgkmcnt(0)
	v_add_f32_e32 v149, v167, v149
	v_mov_b32_e32 v151, v149
	s_nop 1
	v_permlane32_swap_b32_e32 v151, v149
	v_lshlrev_b32_e32 v155, 2, v155
	v_xor_b32_e32 v155, 0x80, v155
	v_mov_b32_e32 v155, v152
	s_nop 1
	v_permlane32_swap_b32_e32 v155, v152
	v_rsq_f32_e32 v160, v147
	s_waitcnt lgkmcnt(0)
	v_add_f32_e32 v147, v149, v151
	v_fmamk_f32 v147, v147, 0x3a800000, v175
	v_rsq_f32_e32 v156, v147
	s_waitcnt lgkmcnt(0)
	v_add_f32_e32 v147, v152, v155
	v_fmamk_f32 v147, v147, 0x3a800000, v175
	v_pk_mul_f32 v[124:125], v[124:125], v[176:177] op_sel_hi:[1,0]
	v_rsq_f32_e32 v152, v147
	v_mul_f32_e32 v147, 0xbfb8aa3b, v124
	v_exp_f32_e32 v147, v147
	v_mul_f32_e32 v149, 0xbfb8aa3b, v125
	v_exp_f32_e32 v149, v149
	v_pk_mul_f32 v[126:127], v[126:127], v[176:177] op_sel_hi:[1,0]
	v_add_f32_e32 v147, 1.0, v147
	v_rcp_f32_e32 v178, v147
	v_add_f32_e32 v147, 1.0, v149
	v_mul_f32_e32 v149, 0xbfb8aa3b, v126
	v_exp_f32_e32 v149, v149
	v_mul_f32_e32 v151, 0xbfb8aa3b, v127
	v_exp_f32_e32 v151, v151
	v_rcp_f32_e32 v179, v147
	v_add_f32_e32 v147, 1.0, v149
	v_rcp_f32_e32 v180, v147
	v_add_f32_e32 v147, 1.0, v151
	v_pk_mul_f32 v[120:121], v[120:121], v[176:177] op_sel_hi:[1,0]
	v_rcp_f32_e32 v181, v147
	v_mul_f32_e32 v147, 0xbfb8aa3b, v120
	v_exp_f32_e32 v147, v147
	v_mul_f32_e32 v149, 0xbfb8aa3b, v121
	v_exp_f32_e32 v149, v149
	v_pk_mul_f32 v[122:123], v[122:123], v[176:177] op_sel_hi:[1,0]
	v_add_f32_e32 v147, 1.0, v147
	v_pk_mul_f32 v[124:125], v[124:125], v[178:179]
	v_rcp_f32_e32 v178, v147
	v_add_f32_e32 v147, 1.0, v149
	v_mul_f32_e32 v149, 0xbfb8aa3b, v122
	v_exp_f32_e32 v149, v149
	v_mul_f32_e32 v151, 0xbfb8aa3b, v123
	v_exp_f32_e32 v151, v151
	v_rcp_f32_e32 v179, v147
	v_add_f32_e32 v147, 1.0, v149
	v_pk_mul_f32 v[126:127], v[126:127], v[180:181]
	v_rcp_f32_e32 v180, v147
	v_add_f32_e32 v147, 1.0, v151
	v_rcp_f32_e32 v181, v147
	v_pk_mul_f32 v[116:117], v[116:117], v[176:177] op_sel_hi:[1,0]
	v_pk_mul_f32 v[118:119], v[118:119], v[176:177] op_sel_hi:[1,0]
	v_pk_mul_f32 v[120:121], v[120:121], v[178:179]
	v_pk_mul_f32 v[112:113], v[112:113], v[176:177] op_sel_hi:[1,0]
	v_lshl_or_b32 v182, s57, 7, v161
	v_pk_mul_f32 v[118:119], v[118:119], v[126:127]
	v_pk_mul_f32 v[116:117], v[116:117], v[124:125]
	v_pk_mul_f32 v[122:123], v[122:123], v[180:181]
	v_pk_mul_f32 v[114:115], v[114:115], v[176:177] op_sel_hi:[1,0]
	v_pk_mul_f32 v[112:113], v[112:113], v[120:121]
	v_ashrrev_i32_e32 v183, 31, v182
	v_pk_mul_f32 v[114:115], v[114:115], v[122:123]
	v_cvt_pk_bf16_f32 v116, v116, v117
	v_cvt_pk_bf16_f32 v117, v118, v119
	v_cvt_pk_bf16_f32 v118, v112, v113
	v_mov_b64_e32 v[112:113], s[14:15]
	v_cvt_pk_bf16_f32 v119, v114, v115
	v_mad_i64_i32 v[120:121], s[38:39], v170, s56, v[112:113]
	v_lshlrev_b64 v[114:115], 1, v[182:183]
	v_pk_mul_f32 v[108:109], v[108:109], v[174:175] op_sel_hi:[1,0]
	v_pk_mul_f32 v[110:111], v[110:111], v[174:175] op_sel_hi:[1,0]
	v_mul_f32_e32 v122, 0xbfb8aa3b, v108
	v_mul_f32_e32 v123, 0xbfb8aa3b, v109
	v_lshl_add_u64 v[120:121], v[120:121], 0, v[114:115]
	v_pk_mul_f32 v[104:105], v[104:105], v[174:175] op_sel_hi:[1,0]
	v_pk_mul_f32 v[106:107], v[106:107], v[174:175] op_sel_hi:[1,0]
	v_exp_f32_e32 v122, v122
	v_exp_f32_e32 v123, v123
	v_mul_f32_e32 v124, 0xbfb8aa3b, v110
	v_mul_f32_e32 v125, 0xbfb8aa3b, v111
	global_store_dwordx4 v[120:121], v[116:119], off sc1
	v_exp_f32_e32 v124, v124
	v_exp_f32_e32 v125, v125
	v_mul_f32_e32 v116, 0xbfb8aa3b, v104
	v_mul_f32_e32 v117, 0xbfb8aa3b, v105
	v_mul_f32_e32 v118, 0xbfb8aa3b, v106
	v_mul_f32_e32 v119, 0xbfb8aa3b, v107
	v_exp_f32_e32 v116, v116
	v_exp_f32_e32 v117, v117
	v_exp_f32_e32 v118, v118
	v_exp_f32_e32 v119, v119
	v_add_f32_e32 v122, 1.0, v122
	v_add_f32_e32 v123, 1.0, v123
	v_rcp_f32_e32 v122, v122
	v_rcp_f32_e32 v123, v123
	v_add_f32_e32 v124, 1.0, v124
	v_add_f32_e32 v125, 1.0, v125
	v_add_f32_e32 v116, 1.0, v116
	v_add_f32_e32 v117, 1.0, v117
	v_add_f32_e32 v118, 1.0, v118
	v_add_f32_e32 v119, 1.0, v119
	v_rcp_f32_e32 v124, v124
	v_rcp_f32_e32 v125, v125
	v_rcp_f32_e32 v116, v116
	v_rcp_f32_e32 v117, v117
	v_rcp_f32_e32 v118, v118
	v_rcp_f32_e32 v119, v119
	v_pk_mul_f32 v[108:109], v[108:109], v[122:123]
	v_pk_mul_f32 v[100:101], v[100:101], v[174:175] op_sel_hi:[1,0]
	v_pk_mul_f32 v[110:111], v[110:111], v[124:125]
	v_pk_mul_f32 v[102:103], v[102:103], v[174:175] op_sel_hi:[1,0]
	v_pk_mul_f32 v[100:101], v[100:101], v[108:109]
	v_pk_mul_f32 v[104:105], v[104:105], v[116:117]
	v_pk_mul_f32 v[106:107], v[106:107], v[118:119]
	v_pk_mul_f32 v[96:97], v[96:97], v[174:175] op_sel_hi:[1,0]
	v_pk_mul_f32 v[98:99], v[98:99], v[174:175] op_sel_hi:[1,0]
	v_pk_mul_f32 v[102:103], v[102:103], v[110:111]
	v_pk_mul_f32 v[106:107], v[98:99], v[106:107]
	v_pk_mul_f32 v[98:99], v[96:97], v[104:105]
; __device__ __forceinline__ f32x4 silu4(f32x4 v) { return (f32x4){silu_f(v[0]), silu_f(v[1]), silu_f(v[2]), silu_f(v[3])}; }
; __device__ __forceinline__ u32x4 pack8(f32x4 a, f32x4 b) { u32x4 w; w.x = cvt_pk_bf16(a[0], a[1]); w.y = cvt_pk_bf16(a[2], a[3]); w.z = cvt_pk_bf16(b[0], b[1]); w.w = cvt_pk_bf16(b[2], b[3]); return w; }
;     __device__ __forceinline__ void operator()(const f32x4 (&acc)[2][2][4][2], const Unit& u, int wr, int wc, int fr, int fq) const {
;     ...
;         for (int ai = 0; ai < 2; ++ai)
; #pragma unroll
;             for (int m = 0; m < 4; ++m) {
;                 const int row = u.pm * BM + ai * HALF + wr * 64 + m * 16 + fr;
;                 const float rstd = rs[ai][m];
;                 const f32x4 a0 = silu4(acc[ai][0][m][0] * rstd) * (acc[ai][1][m][0] * rstd);
;                 const f32x4 a1 = silu4(acc[ai][0][m][1] * rstd) * (acc[ai][1][m][1] * rstd);
;                 *(u32x4*)(ACT + (size_t)row * 2816 + col0) = pack8(a0, a1);
;             }
	v_cvt_pk_bf16_f32 v96, v100, v101
	v_mad_i64_i32 v[100:101], s[38:39], v166, s56, v[112:113]
	v_pk_mul_f32 v[92:93], v[92:93], v[172:173] op_sel_hi:[1,0]
	v_cvt_pk_bf16_f32 v97, v102, v103
	v_cvt_pk_bf16_f32 v98, v98, v99
	v_cvt_pk_bf16_f32 v99, v106, v107
	v_pk_mul_f32 v[94:95], v[94:95], v[172:173] op_sel_hi:[1,0]
	v_mul_f32_e32 v102, 0xbfb8aa3b, v92
	v_mul_f32_e32 v103, 0xbfb8aa3b, v93
	v_lshl_add_u64 v[100:101], v[100:101], 0, v[114:115]
	v_pk_mul_f32 v[88:89], v[88:89], v[172:173] op_sel_hi:[1,0]
	v_pk_mul_f32 v[90:91], v[90:91], v[172:173] op_sel_hi:[1,0]
	v_exp_f32_e32 v102, v102
	v_exp_f32_e32 v103, v103
	v_mul_f32_e32 v104, 0xbfb8aa3b, v94
	v_mul_f32_e32 v105, 0xbfb8aa3b, v95
	global_store_dwordx4 v[100:101], v[96:99], off sc1
	v_exp_f32_e32 v104, v104
	v_exp_f32_e32 v105, v105
	v_mul_f32_e32 v96, 0xbfb8aa3b, v88
	v_mul_f32_e32 v97, 0xbfb8aa3b, v89
	v_mul_f32_e32 v98, 0xbfb8aa3b, v90
	v_mul_f32_e32 v99, 0xbfb8aa3b, v91
	v_exp_f32_e32 v96, v96
	v_exp_f32_e32 v97, v97
	v_exp_f32_e32 v98, v98
	v_exp_f32_e32 v99, v99
	v_add_f32_e32 v102, 1.0, v102
	v_add_f32_e32 v103, 1.0, v103
	v_rcp_f32_e32 v102, v102
	v_rcp_f32_e32 v103, v103
	v_add_f32_e32 v104, 1.0, v104
	v_add_f32_e32 v105, 1.0, v105
	v_add_f32_e32 v96, 1.0, v96
	v_add_f32_e32 v97, 1.0, v97
	v_add_f32_e32 v98, 1.0, v98
	v_add_f32_e32 v99, 1.0, v99
	v_rcp_f32_e32 v104, v104
	v_rcp_f32_e32 v105, v105
	v_rcp_f32_e32 v96, v96
	v_rcp_f32_e32 v97, v97
	v_rcp_f32_e32 v98, v98
	v_rcp_f32_e32 v99, v99
	v_pk_mul_f32 v[92:93], v[92:93], v[102:103]
	v_pk_mul_f32 v[84:85], v[84:85], v[172:173] op_sel_hi:[1,0]
	v_pk_mul_f32 v[94:95], v[94:95], v[104:105]
	v_pk_mul_f32 v[86:87], v[86:87], v[172:173] op_sel_hi:[1,0]
	v_pk_mul_f32 v[84:85], v[84:85], v[92:93]
	v_pk_mul_f32 v[88:89], v[88:89], v[96:97]
	v_pk_mul_f32 v[90:91], v[90:91], v[98:99]
	v_pk_mul_f32 v[80:81], v[80:81], v[172:173] op_sel_hi:[1,0]
	v_pk_mul_f32 v[82:83], v[82:83], v[172:173] op_sel_hi:[1,0]
	v_pk_mul_f32 v[86:87], v[86:87], v[94:95]
	v_pk_mul_f32 v[90:91], v[82:83], v[90:91]
	v_pk_mul_f32 v[82:83], v[80:81], v[88:89]
	v_cvt_pk_bf16_f32 v80, v84, v85
	v_mad_i64_i32 v[84:85], s[38:39], v162, s56, v[112:113]
	v_pk_mul_f32 v[76:77], v[76:77], v[168:169] op_sel_hi:[1,0]
	v_cvt_pk_bf16_f32 v81, v86, v87
	v_cvt_pk_bf16_f32 v82, v82, v83
	v_cvt_pk_bf16_f32 v83, v90, v91
	v_pk_mul_f32 v[78:79], v[78:79], v[168:169] op_sel_hi:[1,0]
	v_mul_f32_e32 v86, 0xbfb8aa3b, v76
	v_mul_f32_e32 v87, 0xbfb8aa3b, v77
	v_lshl_add_u64 v[84:85], v[84:85], 0, v[114:115]
	v_pk_mul_f32 v[72:73], v[72:73], v[168:169] op_sel_hi:[1,0]
	v_pk_mul_f32 v[74:75], v[74:75], v[168:169] op_sel_hi:[1,0]
	v_exp_f32_e32 v86, v86
	v_exp_f32_e32 v87, v87
	v_mul_f32_e32 v88, 0xbfb8aa3b, v78
	v_mul_f32_e32 v89, 0xbfb8aa3b, v79
	global_store_dwordx4 v[84:85], v[80:83], off sc1
	v_exp_f32_e32 v88, v88
	v_exp_f32_e32 v89, v89
	v_mul_f32_e32 v80, 0xbfb8aa3b, v72
	v_mul_f32_e32 v81, 0xbfb8aa3b, v73
	v_mul_f32_e32 v82, 0xbfb8aa3b, v74
	v_mul_f32_e32 v83, 0xbfb8aa3b, v75
	v_exp_f32_e32 v80, v80
	v_exp_f32_e32 v81, v81
	v_exp_f32_e32 v82, v82
	v_exp_f32_e32 v83, v83
	v_add_f32_e32 v86, 1.0, v86
	v_add_f32_e32 v87, 1.0, v87
	v_rcp_f32_e32 v86, v86
	v_rcp_f32_e32 v87, v87
	v_add_f32_e32 v88, 1.0, v88
	v_add_f32_e32 v89, 1.0, v89
	v_add_f32_e32 v80, 1.0, v80
	v_add_f32_e32 v81, 1.0, v81
	v_add_f32_e32 v82, 1.0, v82
	v_add_f32_e32 v83, 1.0, v83
	v_rcp_f32_e32 v88, v88
	v_rcp_f32_e32 v89, v89
	v_rcp_f32_e32 v80, v80
	v_rcp_f32_e32 v81, v81
	v_rcp_f32_e32 v82, v82
	v_rcp_f32_e32 v83, v83
	v_pk_mul_f32 v[76:77], v[76:77], v[86:87]
	v_pk_mul_f32 v[68:69], v[68:69], v[168:169] op_sel_hi:[1,0]
	v_pk_mul_f32 v[78:79], v[78:79], v[88:89]
	v_pk_mul_f32 v[70:71], v[70:71], v[168:169] op_sel_hi:[1,0]
	v_pk_mul_f32 v[68:69], v[68:69], v[76:77]
	v_pk_mul_f32 v[72:73], v[72:73], v[80:81]
	v_pk_mul_f32 v[74:75], v[74:75], v[82:83]
	v_pk_mul_f32 v[64:65], v[64:65], v[168:169] op_sel_hi:[1,0]
	v_pk_mul_f32 v[66:67], v[66:67], v[168:169] op_sel_hi:[1,0]
	v_pk_mul_f32 v[70:71], v[70:71], v[78:79]
	v_pk_mul_f32 v[74:75], v[66:67], v[74:75]
	v_pk_mul_f32 v[66:67], v[64:65], v[72:73]
	v_cvt_pk_bf16_f32 v64, v68, v69
	v_mad_i64_i32 v[68:69], s[38:39], v158, s56, v[112:113]
	v_pk_mul_f32 v[60:61], v[60:61], v[164:165] op_sel_hi:[1,0]
	v_cvt_pk_bf16_f32 v65, v70, v71
	v_cvt_pk_bf16_f32 v66, v66, v67
	v_cvt_pk_bf16_f32 v67, v74, v75
	v_pk_mul_f32 v[62:63], v[62:63], v[164:165] op_sel_hi:[1,0]
	v_mul_f32_e32 v70, 0xbfb8aa3b, v60
	v_mul_f32_e32 v71, 0xbfb8aa3b, v61
	v_lshl_add_u64 v[68:69], v[68:69], 0, v[114:115]
	v_pk_mul_f32 v[56:57], v[56:57], v[164:165] op_sel_hi:[1,0]
	v_pk_mul_f32 v[58:59], v[58:59], v[164:165] op_sel_hi:[1,0]
	v_exp_f32_e32 v70, v70
	v_exp_f32_e32 v71, v71
	v_mul_f32_e32 v72, 0xbfb8aa3b, v62
	v_mul_f32_e32 v73, 0xbfb8aa3b, v63
	global_store_dwordx4 v[68:69], v[64:67], off sc1
	v_exp_f32_e32 v72, v72
	v_exp_f32_e32 v73, v73
	v_mul_f32_e32 v64, 0xbfb8aa3b, v56
	v_mul_f32_e32 v65, 0xbfb8aa3b, v57
	v_mul_f32_e32 v66, 0xbfb8aa3b, v58
	v_mul_f32_e32 v67, 0xbfb8aa3b, v59
	v_exp_f32_e32 v64, v64
	v_exp_f32_e32 v65, v65
	v_exp_f32_e32 v66, v66
	v_exp_f32_e32 v67, v67
	v_add_f32_e32 v70, 1.0, v70
	v_add_f32_e32 v71, 1.0, v71
	v_rcp_f32_e32 v70, v70
	v_rcp_f32_e32 v71, v71
	v_add_f32_e32 v72, 1.0, v72
	v_add_f32_e32 v73, 1.0, v73
	v_add_f32_e32 v64, 1.0, v64
	v_add_f32_e32 v65, 1.0, v65
	v_add_f32_e32 v66, 1.0, v66
	v_add_f32_e32 v67, 1.0, v67
	v_rcp_f32_e32 v72, v72
	v_rcp_f32_e32 v73, v73
	v_rcp_f32_e32 v64, v64
	v_rcp_f32_e32 v65, v65
	v_rcp_f32_e32 v66, v66
	v_rcp_f32_e32 v67, v67
	v_pk_mul_f32 v[60:61], v[60:61], v[70:71]
	v_pk_mul_f32 v[52:53], v[52:53], v[164:165] op_sel_hi:[1,0]
; __device__ __forceinline__ f32x4 silu4(f32x4 v) { return (f32x4){silu_f(v[0]), silu_f(v[1]), silu_f(v[2]), silu_f(v[3])}; }
; __device__ __forceinline__ u32x4 pack8(f32x4 a, f32x4 b) { u32x4 w; w.x = cvt_pk_bf16(a[0], a[1]); w.y = cvt_pk_bf16(a[2], a[3]); w.z = cvt_pk_bf16(b[0], b[1]); w.w = cvt_pk_bf16(b[2], b[3]); return w; }
; #define PG8_BAR __builtin_amdgcn_s_barrier()
;     __device__ __forceinline__ void operator()(const f32x4 (&acc)[2][2][4][2], const Unit& u, int wr, int wc, int fr, int fq) const {
;     ...
;         for (int ai = 0; ai < 2; ++ai)
; #pragma unroll
;             for (int m = 0; m < 4; ++m) {
;                 const int row = u.pm * BM + ai * HALF + wr * 64 + m * 16 + fr;
;                 const float rstd = rs[ai][m];
;                 const f32x4 a0 = silu4(acc[ai][0][m][0] * rstd) * (acc[ai][1][m][0] * rstd);
;                 const f32x4 a1 = silu4(acc[ai][0][m][1] * rstd) * (acc[ai][1][m][1] * rstd);
;                 *(u32x4*)(ACT + (size_t)row * 2816 + col0) = pack8(a0, a1);
;             }
; template <class Epi, class Sched, bool ALIGN_EPI = false, bool SP2 = false>
; __device__ __forceinline__ void gemm_phase(PG8_LAS unsigned char* lds, const Gemm g, const Sched& S, const Epi& E, int tid_in) {
;     ...
;         if constexpr (!Epi::AFTER_DRAIN) { E(acc, cur, wr, wc, fr, fq); S.done(cur); }
;         if (!has_next) break;
; #pragma unroll
;         for (int a = 0; a < 2; ++a)
; #pragma unroll
;             for (int b = 0; b < 2; ++b)
; #pragma unroll
;                 for (int m = 0; m < 4; ++m)
; #pragma unroll
;                     for (int n = 0; n < 2; ++n) acc[a][b][m][n] = (f32x4){0.f, 0.f, 0.f, 0.f};
;         cur = nxt; cA = nA; cB = nB; ++ui;
;         if constexpr (ALIGN_EPI) { if (wr == 1) PG8_BAR; }
;     }
	v_pk_mul_f32 v[62:63], v[62:63], v[72:73]
	v_pk_mul_f32 v[54:55], v[54:55], v[164:165] op_sel_hi:[1,0]
	v_pk_mul_f32 v[52:53], v[52:53], v[60:61]
	v_pk_mul_f32 v[56:57], v[56:57], v[64:65]
	v_pk_mul_f32 v[58:59], v[58:59], v[66:67]
	v_pk_mul_f32 v[48:49], v[48:49], v[164:165] op_sel_hi:[1,0]
	v_pk_mul_f32 v[50:51], v[50:51], v[164:165] op_sel_hi:[1,0]
	v_pk_mul_f32 v[54:55], v[54:55], v[62:63]
	v_pk_mul_f32 v[58:59], v[50:51], v[58:59]
	v_pk_mul_f32 v[50:51], v[48:49], v[56:57]
	v_cvt_pk_bf16_f32 v48, v52, v53
	v_mad_i64_i32 v[52:53], s[38:39], v154, s56, v[112:113]
	v_pk_mul_f32 v[44:45], v[44:45], v[160:161] op_sel_hi:[1,0]
	v_cvt_pk_bf16_f32 v49, v54, v55
	v_cvt_pk_bf16_f32 v50, v50, v51
	v_cvt_pk_bf16_f32 v51, v58, v59
	v_pk_mul_f32 v[46:47], v[46:47], v[160:161] op_sel_hi:[1,0]
	v_mul_f32_e32 v54, 0xbfb8aa3b, v44
	v_mul_f32_e32 v55, 0xbfb8aa3b, v45
	v_lshl_add_u64 v[52:53], v[52:53], 0, v[114:115]
	v_pk_mul_f32 v[40:41], v[40:41], v[160:161] op_sel_hi:[1,0]
	v_pk_mul_f32 v[42:43], v[42:43], v[160:161] op_sel_hi:[1,0]
	v_exp_f32_e32 v54, v54
	v_exp_f32_e32 v55, v55
	v_mul_f32_e32 v56, 0xbfb8aa3b, v46
	v_mul_f32_e32 v57, 0xbfb8aa3b, v47
	global_store_dwordx4 v[52:53], v[48:51], off sc1
	v_exp_f32_e32 v56, v56
	v_exp_f32_e32 v57, v57
	v_mul_f32_e32 v48, 0xbfb8aa3b, v40
	v_mul_f32_e32 v49, 0xbfb8aa3b, v41
	v_mul_f32_e32 v50, 0xbfb8aa3b, v42
	v_mul_f32_e32 v51, 0xbfb8aa3b, v43
	v_exp_f32_e32 v48, v48
	v_exp_f32_e32 v49, v49
	v_exp_f32_e32 v50, v50
	v_exp_f32_e32 v51, v51
	v_add_f32_e32 v54, 1.0, v54
	v_add_f32_e32 v55, 1.0, v55
	v_rcp_f32_e32 v54, v54
	v_rcp_f32_e32 v55, v55
	v_add_f32_e32 v56, 1.0, v56
	v_add_f32_e32 v57, 1.0, v57
	v_add_f32_e32 v48, 1.0, v48
	v_add_f32_e32 v49, 1.0, v49
	v_add_f32_e32 v50, 1.0, v50
	v_add_f32_e32 v51, 1.0, v51
	v_rcp_f32_e32 v56, v56
	v_rcp_f32_e32 v57, v57
	v_rcp_f32_e32 v48, v48
	v_rcp_f32_e32 v49, v49
	v_rcp_f32_e32 v50, v50
	v_rcp_f32_e32 v51, v51
	v_pk_mul_f32 v[44:45], v[44:45], v[54:55]
	v_pk_mul_f32 v[36:37], v[36:37], v[160:161] op_sel_hi:[1,0]
	v_pk_mul_f32 v[46:47], v[46:47], v[56:57]
	v_pk_mul_f32 v[38:39], v[38:39], v[160:161] op_sel_hi:[1,0]
	v_pk_mul_f32 v[36:37], v[36:37], v[44:45]
	v_pk_mul_f32 v[40:41], v[40:41], v[48:49]
	v_pk_mul_f32 v[42:43], v[42:43], v[50:51]
	v_pk_mul_f32 v[32:33], v[32:33], v[160:161] op_sel_hi:[1,0]
	v_pk_mul_f32 v[34:35], v[34:35], v[160:161] op_sel_hi:[1,0]
	v_pk_mul_f32 v[38:39], v[38:39], v[46:47]
	v_pk_mul_f32 v[42:43], v[34:35], v[42:43]
	v_pk_mul_f32 v[34:35], v[32:33], v[40:41]
	v_cvt_pk_bf16_f32 v32, v36, v37
	v_mad_i64_i32 v[36:37], s[38:39], v150, s56, v[112:113]
	v_pk_mul_f32 v[28:29], v[28:29], v[156:157] op_sel_hi:[1,0]
	v_cvt_pk_bf16_f32 v33, v38, v39
	v_cvt_pk_bf16_f32 v34, v34, v35
	v_cvt_pk_bf16_f32 v35, v42, v43
	v_pk_mul_f32 v[30:31], v[30:31], v[156:157] op_sel_hi:[1,0]
	v_mul_f32_e32 v38, 0xbfb8aa3b, v28
	v_mul_f32_e32 v39, 0xbfb8aa3b, v29
	v_lshl_add_u64 v[36:37], v[36:37], 0, v[114:115]
	v_pk_mul_f32 v[24:25], v[24:25], v[156:157] op_sel_hi:[1,0]
	v_pk_mul_f32 v[26:27], v[26:27], v[156:157] op_sel_hi:[1,0]
	v_exp_f32_e32 v38, v38
	v_exp_f32_e32 v39, v39
	v_mul_f32_e32 v40, 0xbfb8aa3b, v30
	v_mul_f32_e32 v41, 0xbfb8aa3b, v31
	global_store_dwordx4 v[36:37], v[32:35], off sc1
	v_exp_f32_e32 v40, v40
	v_exp_f32_e32 v41, v41
	v_mul_f32_e32 v32, 0xbfb8aa3b, v24
	v_mul_f32_e32 v33, 0xbfb8aa3b, v25
	v_mul_f32_e32 v34, 0xbfb8aa3b, v26
	v_mul_f32_e32 v35, 0xbfb8aa3b, v27
	v_exp_f32_e32 v32, v32
	v_exp_f32_e32 v33, v33
	v_exp_f32_e32 v34, v34
	v_exp_f32_e32 v35, v35
	v_add_f32_e32 v38, 1.0, v38
	v_add_f32_e32 v39, 1.0, v39
	v_rcp_f32_e32 v38, v38
	v_rcp_f32_e32 v39, v39
	v_add_f32_e32 v40, 1.0, v40
	v_add_f32_e32 v41, 1.0, v41
	v_add_f32_e32 v32, 1.0, v32
	v_add_f32_e32 v33, 1.0, v33
	v_add_f32_e32 v34, 1.0, v34
	v_add_f32_e32 v35, 1.0, v35
	v_rcp_f32_e32 v40, v40
	v_rcp_f32_e32 v41, v41
	v_rcp_f32_e32 v32, v32
	v_rcp_f32_e32 v33, v33
	v_rcp_f32_e32 v34, v34
	v_rcp_f32_e32 v35, v35
	v_pk_mul_f32 v[28:29], v[28:29], v[38:39]
	v_pk_mul_f32 v[20:21], v[20:21], v[156:157] op_sel_hi:[1,0]
	v_pk_mul_f32 v[30:31], v[30:31], v[40:41]
	v_pk_mul_f32 v[22:23], v[22:23], v[156:157] op_sel_hi:[1,0]
	v_pk_mul_f32 v[20:21], v[20:21], v[28:29]
	v_pk_mul_f32 v[24:25], v[24:25], v[32:33]
	v_pk_mul_f32 v[26:27], v[26:27], v[34:35]
	v_pk_mul_f32 v[16:17], v[16:17], v[156:157] op_sel_hi:[1,0]
	v_pk_mul_f32 v[18:19], v[18:19], v[156:157] op_sel_hi:[1,0]
	v_pk_mul_f32 v[22:23], v[22:23], v[30:31]
	v_pk_mul_f32 v[26:27], v[18:19], v[26:27]
	v_pk_mul_f32 v[18:19], v[16:17], v[24:25]
	v_cvt_pk_bf16_f32 v16, v20, v21
	v_mad_i64_i32 v[20:21], s[38:39], v148, s56, v[112:113]
	v_pk_mul_f32 v[12:13], v[12:13], v[152:153] op_sel_hi:[1,0]
	v_cvt_pk_bf16_f32 v17, v22, v23
	v_cvt_pk_bf16_f32 v18, v18, v19
	v_cvt_pk_bf16_f32 v19, v26, v27
	v_lshl_add_u64 v[20:21], v[20:21], 0, v[114:115]
	v_mul_f32_e32 v22, 0xbfb8aa3b, v12
	v_mul_f32_e32 v23, 0xbfb8aa3b, v13
	v_pk_mul_f32 v[8:9], v[8:9], v[152:153] op_sel_hi:[1,0]
	v_pk_mul_f32 v[10:11], v[10:11], v[152:153] op_sel_hi:[1,0]
	v_exp_f32_e32 v22, v22
	v_exp_f32_e32 v23, v23
	global_store_dwordx4 v[20:21], v[16:19], off sc1
	v_pk_mul_f32 v[14:15], v[14:15], v[152:153] op_sel_hi:[1,0]
	v_add_f32_e32 v22, 1.0, v22
	v_mul_f32_e32 v16, 0xbfb8aa3b, v8
	v_mul_f32_e32 v17, 0xbfb8aa3b, v9
	v_mul_f32_e32 v18, 0xbfb8aa3b, v10
	v_mul_f32_e32 v19, 0xbfb8aa3b, v11
	v_exp_f32_e32 v16, v16
	v_exp_f32_e32 v17, v17
	v_exp_f32_e32 v18, v18
	v_exp_f32_e32 v19, v19
	v_mul_f32_e32 v24, 0xbfb8aa3b, v14
	v_mul_f32_e32 v25, 0xbfb8aa3b, v15
	v_exp_f32_e32 v24, v24
	v_exp_f32_e32 v25, v25
	v_add_f32_e32 v23, 1.0, v23
	v_rcp_f32_e32 v22, v22
	v_rcp_f32_e32 v23, v23
	v_add_f32_e32 v16, 1.0, v16
	v_add_f32_e32 v17, 1.0, v17
	v_add_f32_e32 v18, 1.0, v18
	v_add_f32_e32 v19, 1.0, v19
	v_rcp_f32_e32 v16, v16
	v_rcp_f32_e32 v17, v17
	v_rcp_f32_e32 v18, v18
	v_rcp_f32_e32 v19, v19
	v_add_f32_e32 v24, 1.0, v24
	v_add_f32_e32 v25, 1.0, v25
	v_rcp_f32_e32 v24, v24
	v_rcp_f32_e32 v25, v25
	v_pk_mul_f32 v[12:13], v[12:13], v[22:23]
	v_pk_mul_f32 v[4:5], v[4:5], v[152:153] op_sel_hi:[1,0]
	v_pk_mul_f32 v[8:9], v[8:9], v[16:17]
	v_pk_mul_f32 v[4:5], v[4:5], v[12:13]
	v_pk_mul_f32 v[10:11], v[10:11], v[18:19]
	v_pk_mul_f32 v[0:1], v[0:1], v[152:153] op_sel_hi:[1,0]
	v_pk_mul_f32 v[2:3], v[2:3], v[152:153] op_sel_hi:[1,0]
	v_pk_mul_f32 v[14:15], v[14:15], v[24:25]
	v_pk_mul_f32 v[10:11], v[2:3], v[10:11]
	v_pk_mul_f32 v[2:3], v[0:1], v[8:9]
	v_cvt_pk_bf16_f32 v0, v4, v5
	v_mad_i64_i32 v[4:5], s[38:39], v146, s56, v[112:113]
	v_pk_mul_f32 v[6:7], v[6:7], v[152:153] op_sel_hi:[1,0]
	v_lshl_add_u64 v[4:5], v[4:5], 0, v[114:115]
	v_pk_mul_f32 v[6:7], v[6:7], v[14:15]
	s_nop 0
	v_cvt_pk_bf16_f32 v1, v6, v7
	v_cvt_pk_bf16_f32 v2, v2, v3
	v_cvt_pk_bf16_f32 v3, v10, v11
	global_store_dwordx4 v[4:5], v[0:3], off sc1
	s_cbranch_vccnz .LBB0_516
	s_andn2_b64 vcc, exec, s[12:13]
	s_cbranch_vccnz .LBB0_515
	s_barrier
	s_branch .LBB0_515

; __device__ __forceinline__ float sq4(f32x4 v) { return (v[0] * v[0] + v[1] * v[1]) + (v[2] * v[2] + v[3] * v[3]); }
; __device__ __forceinline__ u32x4 pack8(f32x4 a, f32x4 b) { u32x4 w; w.x = cvt_pk_bf16(a[0], a[1]); w.y = cvt_pk_bf16(a[2], a[3]); w.z = cvt_pk_bf16(b[0], b[1]); w.w = cvt_pk_bf16(b[2], b[3]); return w; }
;     __device__ __forceinline__ void operator()(const f32x4 (&acc)[2][2][4][2], const Unit& u, int wr, int wc, int fr, int fq) const {
;     ...
;         for (int ai = 0; ai < 2; ++ai) {
;             u32x4 bs[4][2];
; #pragma unroll
;             for (int m = 0; m < 4; ++m)
; #pragma unroll
;                 for (int bj = 0; bj < 2; ++bj) bs[m][bj] = *(const u32x4*)(xb + (size_t)(u.pm * BM + ai * HALF + wr * 64 + m * 16 + fr) * 1024 + col0 + 128 * bj);
; #pragma unroll
;             for (int m = 0; m < 4; ++m) {
;                 const int row = u.pm * BM + ai * HALF + wr * 64 + m * 16 + fr;
;                 float q = 0.f;
; #pragma unroll
;                 for (int bj = 0; bj < 2; ++bj) {
;                     const size_t off = (size_t)row * 1024 + col0 + 128 * bj; const u32x4 w = bs[m][bj];
;                     const f32x4 b0 = (f32x4){__builtin_bit_cast(float, w.x << 16), __builtin_bit_cast(float, w.x & 0xffff0000u), __builtin_bit_cast(float, w.y << 16), __builtin_bit_cast(float, w.y & 0xffff0000u)};
;                     const f32x4 b1 = (f32x4){__builtin_bit_cast(float, w.z << 16), __builtin_bit_cast(float, w.z & 0xffff0000u), __builtin_bit_cast(float, w.w << 16), __builtin_bit_cast(float, w.w & 0xffff0000u)};
;                     const f32x4 v0 = acc[ai][bj][m][0] + b0, v1 = acc[ai][bj][m][1] + b1;
;                     if (last) { __builtin_nontemporal_store(v0, (f32x4*)(out + off)); __builtin_nontemporal_store(v1, (f32x4*)(out + off + 4)); }
;                     else { q += sq4(v0) + sq4(v1); *(u32x4*)(xb + off) = pack8(v0, v1); }
;                 }
;                 if (!last) { q += shx(q, 16); q += shx(q, 32); if (fq == 0) ss[(size_t)row * 16 + u.pn * 4 + wc] = q; }
.LBB0_605:
	v_lshl_or_b32 v168, s16, 8, v188
	v_lshl_add_u32 v172, s61, 8, v186
	v_ashrrev_i32_e32 v169, 31, v168
	v_lshlrev_b64 v[202:203], 1, v[168:169]
	v_ashrrev_i32_e32 v173, 31, v172
	v_lshl_add_u64 v[170:171], s[22:23], 0, v[202:203]
	v_lshlrev_b64 v[204:205], 11, v[172:173]
	v_lshl_add_u64 v[128:129], v[170:171], 0, v[204:205]
	global_load_dwordx4 v[192:195], v[128:129], off
	global_load_dwordx4 v[196:199], v[128:129], off offset:256
	v_or_b32_e32 v182, 16, v172
	v_or_b32_e32 v178, 32, v172
	v_or_b32_e32 v174, 48, v172
	v_ashrrev_i32_e32 v183, 31, v182
	v_ashrrev_i32_e32 v179, 31, v178
	v_ashrrev_i32_e32 v175, 31, v174
	v_lshlrev_b64 v[184:185], 11, v[182:183]
	v_lshlrev_b64 v[180:181], 11, v[178:179]
	v_lshlrev_b64 v[176:177], 11, v[174:175]
	v_lshl_add_u64 v[128:129], v[170:171], 0, v[184:185]
	v_lshl_add_u64 v[130:131], v[170:171], 0, v[180:181]
	v_lshl_add_u64 v[206:207], v[170:171], 0, v[176:177]
	global_load_dwordx4 v[148:151], v[128:129], off
	global_load_dwordx4 v[144:147], v[128:129], off offset:256
	global_load_dwordx4 v[140:143], v[130:131], off
	global_load_dwordx4 v[136:139], v[130:131], off offset:256
	global_load_dwordx4 v[132:135], v[206:207], off
	s_nop 0
	global_load_dwordx4 v[128:131], v[206:207], off offset:256
	v_lshl_add_u64 v[204:205], s[22:23], 0, v[204:205]
	v_lshl_add_u64 v[202:203], v[204:205], 0, v[202:203]
	v_mov_b32_e32 v200, v201
	s_lshl_b32 s38, s16, 2
	s_ashr_i32 s39, s38, 31
	s_waitcnt vmcnt(0)
	v_lshlrev_b32_e32 v204, 16, v192
	v_and_b32_e32 v205, 0xffff0000, v192
	v_lshlrev_b32_e32 v192, 16, v193
	v_and_b32_e32 v193, 0xffff0000, v193
	v_lshlrev_b32_e32 v206, 16, v194
	v_and_b32_e32 v207, 0xffff0000, v194
	v_lshlrev_b32_e32 v194, 16, v195
	v_and_b32_e32 v195, 0xffff0000, v195
	v_lshlrev_b32_e32 v208, 16, v196
	v_and_b32_e32 v209, 0xffff0000, v196
	v_lshlrev_b32_e32 v196, 16, v197
	v_and_b32_e32 v197, 0xffff0000, v197
	v_lshlrev_b32_e32 v210, 16, v198
	v_and_b32_e32 v211, 0xffff0000, v198
	v_lshlrev_b32_e32 v198, 16, v199
	v_and_b32_e32 v199, 0xffff0000, v199
	v_pk_add_f32 v[126:127], v[126:127], v[192:193]
	v_pk_add_f32 v[124:125], v[124:125], v[204:205]
	v_pk_add_f32 v[122:123], v[122:123], v[194:195]
	v_pk_add_f32 v[120:121], v[120:121], v[206:207]
	v_pk_add_f32 v[118:119], v[118:119], v[196:197]
	v_pk_add_f32 v[116:117], v[116:117], v[208:209]
	v_pk_add_f32 v[192:193], v[114:115], v[198:199]
	v_pk_add_f32 v[194:195], v[112:113], v[210:211]
	v_mul_f32_e32 v196, v125, v125
	v_mul_f32_e32 v197, v127, v127
	v_mul_f32_e32 v198, v121, v121
	v_mul_f32_e32 v199, v123, v123
	v_cvt_pk_bf16_f32 v112, v124, v125
	v_cvt_pk_bf16_f32 v113, v126, v127
	v_cvt_pk_bf16_f32 v114, v120, v121
	v_cvt_pk_bf16_f32 v115, v122, v123
	v_mul_f32_e32 v121, v117, v117
	v_mul_f32_e32 v123, v119, v119
	v_mul_f32_e32 v125, v195, v195
	v_mul_f32_e32 v127, v193, v193
	v_fmac_f32_e32 v196, v124, v124
	v_fmac_f32_e32 v197, v126, v126
	v_fmac_f32_e32 v198, v120, v120
	v_fmac_f32_e32 v199, v122, v122
	v_fmac_f32_e32 v121, v116, v116
	v_fmac_f32_e32 v123, v118, v118
	v_fmac_f32_e32 v125, v194, v194
	v_fmac_f32_e32 v127, v192, v192
	global_store_dwordx4 v[202:203], v[112:115], off sc1
	s_nop 1
	v_cvt_pk_bf16_f32 v112, v116, v117
	v_cvt_pk_bf16_f32 v113, v118, v119
	v_cvt_pk_bf16_f32 v114, v194, v195
	v_add_f32_e32 v116, v196, v197
	v_add_f32_e32 v117, v198, v199
	v_add_f32_e32 v118, v121, v123
	v_add_f32_e32 v119, v125, v127
	v_cvt_pk_bf16_f32 v115, v192, v193
	global_store_dwordx4 v[202:203], v[112:115], off offset:256 sc1
	s_nop 1
	v_add_f32_e32 v112, v116, v117
	v_add_f32_e32 v113, v118, v119
	v_lshlrev_b32_e32 v114, 2, v200
	v_add_f32_e32 v112, v112, v113
	v_xor_b32_e32 v113, 64, v114
	v_mov_b32_e32 v113, v112
	s_nop 1
	v_permlane16_swap_b32_e32 v113, v112
	v_mov_b32_e32 v114, v201
	s_waitcnt lgkmcnt(0)
	v_add_f32_e32 v112, v112, v113
	v_lshlrev_b32_e32 v114, 2, v114
	v_xor_b32_e32 v113, 0x80, v114
	v_mov_b32_e32 v113, v112
	s_nop 1
	v_permlane32_swap_b32_e32 v113, v112
	s_and_saveexec_b64 s[40:41], s[10:11]
	s_cbranch_execz .LBB0_607
	s_waitcnt lgkmcnt(0)
	v_add_f32_e32 v114, v112, v113
	v_lshlrev_b64 v[112:113], 6, v[172:173]
	v_lshl_add_u64 v[112:113], s[24:25], 0, v[112:113]
	v_lshl_add_u64 v[112:113], s[38:39], 2, v[112:113]
	s_lshl_b32 s16, s50, 2
	v_lshl_add_u64 v[112:113], v[112:113], 0, s[16:17]
	global_store_dword v[112:113], v114, off sc1
; __device__ __forceinline__ float sq4(f32x4 v) { return (v[0] * v[0] + v[1] * v[1]) + (v[2] * v[2] + v[3] * v[3]); }
; __device__ __forceinline__ u32x4 pack8(f32x4 a, f32x4 b) { u32x4 w; w.x = cvt_pk_bf16(a[0], a[1]); w.y = cvt_pk_bf16(a[2], a[3]); w.z = cvt_pk_bf16(b[0], b[1]); w.w = cvt_pk_bf16(b[2], b[3]); return w; }
;     __device__ __forceinline__ void operator()(const f32x4 (&acc)[2][2][4][2], const Unit& u, int wr, int wc, int fr, int fq) const {
;     ...
;             for (int m = 0; m < 4; ++m) {
;                 const int row = u.pm * BM + ai * HALF + wr * 64 + m * 16 + fr;
;                 float q = 0.f;
; #pragma unroll
;                 for (int bj = 0; bj < 2; ++bj) {
;                     const size_t off = (size_t)row * 1024 + col0 + 128 * bj; const u32x4 w = bs[m][bj];
;                     const f32x4 b0 = (f32x4){__builtin_bit_cast(float, w.x << 16), __builtin_bit_cast(float, w.x & 0xffff0000u), __builtin_bit_cast(float, w.y << 16), __builtin_bit_cast(float, w.y & 0xffff0000u)};
;                     const f32x4 b1 = (f32x4){__builtin_bit_cast(float, w.z << 16), __builtin_bit_cast(float, w.z & 0xffff0000u), __builtin_bit_cast(float, w.w << 16), __builtin_bit_cast(float, w.w & 0xffff0000u)};
;                     const f32x4 v0 = acc[ai][bj][m][0] + b0, v1 = acc[ai][bj][m][1] + b1;
;                     if (last) { __builtin_nontemporal_store(v0, (f32x4*)(out + off)); __builtin_nontemporal_store(v1, (f32x4*)(out + off + 4)); }
;                     else { q += sq4(v0) + sq4(v1); *(u32x4*)(xb + off) = pack8(v0, v1); }
;                 }
;                 if (!last) { q += shx(q, 16); q += shx(q, 32); if (fq == 0) ss[(size_t)row * 16 + u.pn * 4 + wc] = q; }
.LBB0_607:
	s_or_b64 exec, exec, s[40:41]
	v_lshlrev_b32_e32 v112, 16, v148
	s_waitcnt lgkmcnt(0)
	v_and_b32_e32 v113, 0xffff0000, v148
	v_lshlrev_b32_e32 v114, 16, v149
	v_and_b32_e32 v115, 0xffff0000, v149
	v_lshlrev_b32_e32 v116, 16, v150
	v_and_b32_e32 v117, 0xffff0000, v150
	v_lshlrev_b32_e32 v118, 16, v151
	v_and_b32_e32 v119, 0xffff0000, v151
	v_pk_add_f32 v[110:111], v[110:111], v[114:115]
	v_pk_add_f32 v[108:109], v[108:109], v[112:113]
	v_pk_add_f32 v[112:113], v[106:107], v[118:119]
	v_pk_add_f32 v[106:107], v[104:105], v[116:117]
	v_mul_f32_e32 v104, v109, v109
	v_mul_f32_e32 v105, v111, v111
	v_fmac_f32_e32 v104, v108, v108
	v_fmac_f32_e32 v105, v110, v110
	v_add_f32_e32 v104, v104, v105
	v_mul_f32_e32 v105, v107, v107
	v_mul_f32_e32 v114, v113, v113
	v_fmac_f32_e32 v105, v106, v106
	v_fmac_f32_e32 v114, v112, v112
	v_add_f32_e32 v105, v105, v114
	v_add_f32_e32 v114, v104, v105
	v_cvt_pk_bf16_f32 v104, v108, v109
	v_lshl_add_u64 v[108:109], s[22:23], 0, v[184:185]
	v_cvt_pk_bf16_f32 v105, v110, v111
	v_cvt_pk_bf16_f32 v106, v106, v107
	v_cvt_pk_bf16_f32 v107, v112, v113
	v_lshl_add_u64 v[108:109], v[168:169], 1, v[108:109]
	global_store_dwordx4 v[108:109], v[104:107], off sc1
	v_lshlrev_b32_e32 v110, 16, v146
	v_and_b32_e32 v111, 0xffff0000, v146
	v_lshlrev_b32_e32 v104, 16, v144
	v_and_b32_e32 v105, 0xffff0000, v144
	v_lshlrev_b32_e32 v106, 16, v145
	v_and_b32_e32 v107, 0xffff0000, v145
	v_lshlrev_b32_e32 v112, 16, v147
	v_and_b32_e32 v113, 0xffff0000, v147
	v_pk_add_f32 v[102:103], v[102:103], v[106:107]
	v_pk_add_f32 v[100:101], v[100:101], v[104:105]
	v_pk_add_f32 v[104:105], v[98:99], v[112:113]
	v_pk_add_f32 v[98:99], v[96:97], v[110:111]
	v_mul_f32_e32 v96, v101, v101
	v_mul_f32_e32 v97, v103, v103
	v_fmac_f32_e32 v96, v100, v100
	v_fmac_f32_e32 v97, v102, v102
	v_add_f32_e32 v96, v96, v97
	v_mul_f32_e32 v97, v99, v99
	v_mul_f32_e32 v106, v105, v105
	v_fmac_f32_e32 v97, v98, v98
	v_fmac_f32_e32 v106, v104, v104
	v_add_f32_e32 v97, v97, v106
	v_add_f32_e32 v96, v96, v97
	v_add_f32_e32 v106, v114, v96
	v_cvt_pk_bf16_f32 v96, v100, v101
	v_cvt_pk_bf16_f32 v97, v102, v103
	v_cvt_pk_bf16_f32 v98, v98, v99
	v_cvt_pk_bf16_f32 v99, v104, v105
	global_store_dwordx4 v[108:109], v[96:99], off offset:256 sc1
	s_nop 1
	v_mov_b32_e32 v96, v201
	v_mov_b32_e32 v97, v201
	v_lshlrev_b32_e32 v96, 2, v96
	v_xor_b32_e32 v96, 64, v96
	v_mov_b32_e32 v96, v106
	s_nop 1
	v_permlane16_swap_b32_e32 v96, v106
	s_waitcnt lgkmcnt(0)
	v_add_f32_e32 v96, v106, v96
	v_lshlrev_b32_e32 v97, 2, v97
	v_xor_b32_e32 v97, 0x80, v97
	v_mov_b32_e32 v97, v96
	s_nop 1
	v_permlane32_swap_b32_e32 v97, v96
	s_and_saveexec_b64 s[40:41], s[10:11]
	s_cbranch_execz .LBB0_609
	s_waitcnt lgkmcnt(0)
	v_add_f32_e32 v98, v96, v97
	v_lshlrev_b64 v[96:97], 6, v[182:183]
	v_lshl_add_u64 v[96:97], s[24:25], 0, v[96:97]
	v_lshl_add_u64 v[96:97], s[38:39], 2, v[96:97]
	s_lshl_b32 s16, s50, 2
	v_lshl_add_u64 v[96:97], v[96:97], 0, s[16:17]
	global_store_dword v[96:97], v98, off sc1
.LBB0_609:
	s_or_b64 exec, exec, s[40:41]
	v_lshlrev_b32_e32 v96, 16, v140
	s_waitcnt lgkmcnt(0)
	v_and_b32_e32 v97, 0xffff0000, v140
	v_lshlrev_b32_e32 v98, 16, v141
	v_and_b32_e32 v99, 0xffff0000, v141
	v_lshlrev_b32_e32 v100, 16, v142
	v_and_b32_e32 v101, 0xffff0000, v142
	v_lshlrev_b32_e32 v102, 16, v143
	v_and_b32_e32 v103, 0xffff0000, v143
	v_pk_add_f32 v[94:95], v[94:95], v[98:99]
	v_pk_add_f32 v[92:93], v[92:93], v[96:97]
	v_pk_add_f32 v[96:97], v[90:91], v[102:103]
	v_pk_add_f32 v[90:91], v[88:89], v[100:101]
	v_mul_f32_e32 v88, v93, v93
	v_mul_f32_e32 v89, v95, v95
	v_fmac_f32_e32 v88, v92, v92
	v_fmac_f32_e32 v89, v94, v94
	v_add_f32_e32 v88, v88, v89
	v_mul_f32_e32 v89, v91, v91
	v_mul_f32_e32 v98, v97, v97
	v_fmac_f32_e32 v89, v90, v90
	v_fmac_f32_e32 v98, v96, v96
	v_add_f32_e32 v89, v89, v98
	v_add_f32_e32 v98, v88, v89
	v_cvt_pk_bf16_f32 v88, v92, v93
	v_lshl_add_u64 v[92:93], s[22:23], 0, v[180:181]
	v_cvt_pk_bf16_f32 v89, v94, v95
	v_cvt_pk_bf16_f32 v90, v90, v91
	v_cvt_pk_bf16_f32 v91, v96, v97
	v_lshl_add_u64 v[92:93], v[168:169], 1, v[92:93]
	global_store_dwordx4 v[92:93], v[88:91], off sc1
	v_lshlrev_b32_e32 v94, 16, v138
	v_and_b32_e32 v95, 0xffff0000, v138
	v_lshlrev_b32_e32 v88, 16, v136
	v_and_b32_e32 v89, 0xffff0000, v136
	v_lshlrev_b32_e32 v90, 16, v137
	v_and_b32_e32 v91, 0xffff0000, v137
	v_lshlrev_b32_e32 v96, 16, v139
	v_and_b32_e32 v97, 0xffff0000, v139
	v_pk_add_f32 v[86:87], v[86:87], v[90:91]
	v_pk_add_f32 v[84:85], v[84:85], v[88:89]
	v_pk_add_f32 v[88:89], v[82:83], v[96:97]
	v_pk_add_f32 v[82:83], v[80:81], v[94:95]
	v_mul_f32_e32 v80, v85, v85
	v_mul_f32_e32 v81, v87, v87
	v_fmac_f32_e32 v80, v84, v84
	v_fmac_f32_e32 v81, v86, v86
	v_add_f32_e32 v80, v80, v81
	v_mul_f32_e32 v81, v83, v83
	v_mul_f32_e32 v90, v89, v89
	v_fmac_f32_e32 v81, v82, v82
	v_fmac_f32_e32 v90, v88, v88
	v_add_f32_e32 v81, v81, v90
	v_add_f32_e32 v80, v80, v81
	v_add_f32_e32 v90, v98, v80
	v_cvt_pk_bf16_f32 v80, v84, v85
	v_cvt_pk_bf16_f32 v81, v86, v87
	v_cvt_pk_bf16_f32 v82, v82, v83
	v_cvt_pk_bf16_f32 v83, v88, v89
	global_store_dwordx4 v[92:93], v[80:83], off offset:256 sc1
	s_nop 1
	v_mov_b32_e32 v80, v201
	v_mov_b32_e32 v81, v201
	v_lshlrev_b32_e32 v80, 2, v80
	v_xor_b32_e32 v80, 64, v80
	v_mov_b32_e32 v80, v90
	s_nop 1
	v_permlane16_swap_b32_e32 v80, v90
	s_waitcnt lgkmcnt(0)
	v_add_f32_e32 v80, v90, v80
	v_lshlrev_b32_e32 v81, 2, v81
	v_xor_b32_e32 v81, 0x80, v81
	v_mov_b32_e32 v81, v80
	s_nop 1
	v_permlane32_swap_b32_e32 v81, v80
	s_and_saveexec_b64 s[40:41], s[10:11]
	s_cbranch_execz .LBB0_611
	s_waitcnt lgkmcnt(0)
	v_add_f32_e32 v82, v80, v81
	v_lshlrev_b64 v[80:81], 6, v[178:179]
	v_lshl_add_u64 v[80:81], s[24:25], 0, v[80:81]
	v_lshl_add_u64 v[80:81], s[38:39], 2, v[80:81]
	s_lshl_b32 s16, s50, 2
	v_lshl_add_u64 v[80:81], v[80:81], 0, s[16:17]
	global_store_dword v[80:81], v82, off sc1
; __device__ __forceinline__ float sq4(f32x4 v) { return (v[0] * v[0] + v[1] * v[1]) + (v[2] * v[2] + v[3] * v[3]); }
; __device__ __forceinline__ u32x4 pack8(f32x4 a, f32x4 b) { u32x4 w; w.x = cvt_pk_bf16(a[0], a[1]); w.y = cvt_pk_bf16(a[2], a[3]); w.z = cvt_pk_bf16(b[0], b[1]); w.w = cvt_pk_bf16(b[2], b[3]); return w; }
;     __device__ __forceinline__ void operator()(const f32x4 (&acc)[2][2][4][2], const Unit& u, int wr, int wc, int fr, int fq) const {
;     ...
;         for (int ai = 0; ai < 2; ++ai) {
;             u32x4 bs[4][2];
; #pragma unroll
;             for (int m = 0; m < 4; ++m)
; #pragma unroll
;                 for (int bj = 0; bj < 2; ++bj) bs[m][bj] = *(const u32x4*)(xb + (size_t)(u.pm * BM + ai * HALF + wr * 64 + m * 16 + fr) * 1024 + col0 + 128 * bj);
; #pragma unroll
;             for (int m = 0; m < 4; ++m) {
;                 const int row = u.pm * BM + ai * HALF + wr * 64 + m * 16 + fr;
;                 float q = 0.f;
; #pragma unroll
;                 for (int bj = 0; bj < 2; ++bj) {
;                     const size_t off = (size_t)row * 1024 + col0 + 128 * bj; const u32x4 w = bs[m][bj];
;                     const f32x4 b0 = (f32x4){__builtin_bit_cast(float, w.x << 16), __builtin_bit_cast(float, w.x & 0xffff0000u), __builtin_bit_cast(float, w.y << 16), __builtin_bit_cast(float, w.y & 0xffff0000u)};
;                     const f32x4 b1 = (f32x4){__builtin_bit_cast(float, w.z << 16), __builtin_bit_cast(float, w.z & 0xffff0000u), __builtin_bit_cast(float, w.w << 16), __builtin_bit_cast(float, w.w & 0xffff0000u)};
;                     const f32x4 v0 = acc[ai][bj][m][0] + b0, v1 = acc[ai][bj][m][1] + b1;
;                     if (last) { __builtin_nontemporal_store(v0, (f32x4*)(out + off)); __builtin_nontemporal_store(v1, (f32x4*)(out + off + 4)); }
;                     else { q += sq4(v0) + sq4(v1); *(u32x4*)(xb + off) = pack8(v0, v1); }
;                 }
;                 if (!last) { q += shx(q, 16); q += shx(q, 32); if (fq == 0) ss[(size_t)row * 16 + u.pn * 4 + wc] = q; }
.LBB0_611:
	s_or_b64 exec, exec, s[40:41]
	v_lshlrev_b32_e32 v80, 16, v132
	s_waitcnt lgkmcnt(0)
	v_and_b32_e32 v81, 0xffff0000, v132
	v_lshlrev_b32_e32 v82, 16, v133
	v_and_b32_e32 v83, 0xffff0000, v133
	v_lshlrev_b32_e32 v84, 16, v134
	v_and_b32_e32 v85, 0xffff0000, v134
	v_lshlrev_b32_e32 v86, 16, v135
	v_and_b32_e32 v87, 0xffff0000, v135
	v_pk_add_f32 v[78:79], v[78:79], v[82:83]
	v_pk_add_f32 v[76:77], v[76:77], v[80:81]
	v_pk_add_f32 v[80:81], v[74:75], v[86:87]
	v_pk_add_f32 v[74:75], v[72:73], v[84:85]
	v_mul_f32_e32 v72, v77, v77
	v_mul_f32_e32 v73, v79, v79
	v_fmac_f32_e32 v72, v76, v76
	v_fmac_f32_e32 v73, v78, v78
	v_add_f32_e32 v72, v72, v73
	v_mul_f32_e32 v73, v75, v75
	v_mul_f32_e32 v82, v81, v81
	v_fmac_f32_e32 v73, v74, v74
	v_fmac_f32_e32 v82, v80, v80
	v_add_f32_e32 v73, v73, v82
	v_add_f32_e32 v82, v72, v73
	v_cvt_pk_bf16_f32 v72, v76, v77
	v_lshl_add_u64 v[76:77], s[22:23], 0, v[176:177]
	v_cvt_pk_bf16_f32 v73, v78, v79
	v_cvt_pk_bf16_f32 v74, v74, v75
	v_cvt_pk_bf16_f32 v75, v80, v81
	v_lshl_add_u64 v[76:77], v[168:169], 1, v[76:77]
	global_store_dwordx4 v[76:77], v[72:75], off sc1
	v_lshlrev_b32_e32 v78, 16, v130
	v_and_b32_e32 v79, 0xffff0000, v130
	v_lshlrev_b32_e32 v72, 16, v128
	v_and_b32_e32 v73, 0xffff0000, v128
	v_lshlrev_b32_e32 v74, 16, v129
	v_and_b32_e32 v75, 0xffff0000, v129
	v_lshlrev_b32_e32 v80, 16, v131
	v_and_b32_e32 v81, 0xffff0000, v131
	v_pk_add_f32 v[70:71], v[70:71], v[74:75]
	v_pk_add_f32 v[68:69], v[68:69], v[72:73]
	v_pk_add_f32 v[72:73], v[66:67], v[80:81]
	v_pk_add_f32 v[66:67], v[64:65], v[78:79]
	v_mul_f32_e32 v64, v69, v69
	v_mul_f32_e32 v65, v71, v71
	v_fmac_f32_e32 v64, v68, v68
	v_fmac_f32_e32 v65, v70, v70
	v_add_f32_e32 v64, v64, v65
	v_mul_f32_e32 v65, v67, v67
	v_mul_f32_e32 v74, v73, v73
	v_fmac_f32_e32 v65, v66, v66
	v_fmac_f32_e32 v74, v72, v72
	v_add_f32_e32 v65, v65, v74
	v_add_f32_e32 v64, v64, v65
	v_add_f32_e32 v74, v82, v64
	v_cvt_pk_bf16_f32 v64, v68, v69
	v_cvt_pk_bf16_f32 v65, v70, v71
	v_cvt_pk_bf16_f32 v66, v66, v67
	v_cvt_pk_bf16_f32 v67, v72, v73
	global_store_dwordx4 v[76:77], v[64:67], off offset:256 sc1
	s_nop 1
	v_mov_b32_e32 v64, v201
	v_mov_b32_e32 v65, v201
	v_lshlrev_b32_e32 v64, 2, v64
	v_xor_b32_e32 v64, 64, v64
	v_mov_b32_e32 v64, v74
	s_nop 1
	v_permlane16_swap_b32_e32 v64, v74
	s_waitcnt lgkmcnt(0)
	v_add_f32_e32 v64, v74, v64
	v_lshlrev_b32_e32 v65, 2, v65
	v_xor_b32_e32 v65, 0x80, v65
	v_mov_b32_e32 v65, v64
	s_nop 1
	v_permlane32_swap_b32_e32 v65, v64
	s_and_saveexec_b64 s[40:41], s[10:11]
	s_cbranch_execz .LBB0_613
	s_waitcnt lgkmcnt(0)
	v_add_f32_e32 v66, v64, v65
	v_lshlrev_b64 v[64:65], 6, v[174:175]
	v_lshl_add_u64 v[64:65], s[24:25], 0, v[64:65]
	v_lshl_add_u64 v[64:65], s[38:39], 2, v[64:65]
	s_lshl_b32 s16, s50, 2
	v_lshl_add_u64 v[64:65], v[64:65], 0, s[16:17]
	global_store_dword v[64:65], v66, off sc1
.LBB0_613:
	s_or_b64 exec, exec, s[40:41]
	v_add_u32_e32 v100, 0x80, v172
	v_ashrrev_i32_e32 v101, 31, v100
	v_lshlrev_b64 v[110:111], 11, v[100:101]
	s_waitcnt lgkmcnt(0)
	v_lshl_add_u64 v[64:65], v[170:171], 0, v[110:111]
	global_load_dwordx4 v[102:105], v[64:65], off
	global_load_dwordx4 v[106:109], v[64:65], off offset:256
	v_add_u32_e32 v96, 0x90, v172
	v_add_u32_e32 v92, 0xa0, v172
	v_add_u32_e32 v88, 0xb0, v172
	v_ashrrev_i32_e32 v97, 31, v96
	v_ashrrev_i32_e32 v93, 31, v92
	v_ashrrev_i32_e32 v89, 31, v88
	v_lshlrev_b64 v[98:99], 11, v[96:97]
	v_lshlrev_b64 v[94:95], 11, v[92:93]
	v_lshlrev_b64 v[90:91], 11, v[88:89]
	v_lshl_add_u64 v[64:65], v[170:171], 0, v[98:99]
	v_lshl_add_u64 v[66:67], v[170:171], 0, v[94:95]
	v_lshl_add_u64 v[112:113], v[170:171], 0, v[90:91]
	global_load_dwordx4 v[84:87], v[64:65], off
	global_load_dwordx4 v[80:83], v[64:65], off offset:256
	global_load_dwordx4 v[76:79], v[66:67], off
	global_load_dwordx4 v[72:75], v[66:67], off offset:256
	global_load_dwordx4 v[68:71], v[112:113], off
	s_nop 0
	global_load_dwordx4 v[64:67], v[112:113], off offset:256
	v_lshl_add_u64 v[110:111], s[22:23], 0, v[110:111]
	v_lshl_add_u64 v[110:111], v[168:169], 1, v[110:111]
	v_mov_b32_e32 v120, v201
	s_waitcnt vmcnt(7)
	v_lshlrev_b32_e32 v112, 16, v102
	v_and_b32_e32 v113, 0xffff0000, v102
	v_lshlrev_b32_e32 v102, 16, v103
	v_and_b32_e32 v103, 0xffff0000, v103
	v_lshlrev_b32_e32 v114, 16, v104
	v_and_b32_e32 v115, 0xffff0000, v104
	v_lshlrev_b32_e32 v104, 16, v105
	v_and_b32_e32 v105, 0xffff0000, v105
	s_waitcnt vmcnt(6)
	v_lshlrev_b32_e32 v116, 16, v106
	v_and_b32_e32 v117, 0xffff0000, v106
	v_lshlrev_b32_e32 v106, 16, v107
	v_and_b32_e32 v107, 0xffff0000, v107
	v_lshlrev_b32_e32 v118, 16, v108
	v_and_b32_e32 v119, 0xffff0000, v108
	v_lshlrev_b32_e32 v108, 16, v109
	v_and_b32_e32 v109, 0xffff0000, v109
	v_pk_add_f32 v[62:63], v[62:63], v[102:103]
	v_pk_add_f32 v[60:61], v[60:61], v[112:113]
	v_pk_add_f32 v[58:59], v[58:59], v[104:105]
	v_pk_add_f32 v[56:57], v[56:57], v[114:115]
	v_pk_add_f32 v[54:55], v[54:55], v[106:107]
	v_pk_add_f32 v[52:53], v[52:53], v[116:117]
	v_pk_add_f32 v[102:103], v[50:51], v[108:109]
	v_pk_add_f32 v[104:105], v[48:49], v[118:119]
	v_mul_f32_e32 v106, v61, v61
	v_mul_f32_e32 v107, v63, v63
	v_mul_f32_e32 v108, v57, v57
	v_mul_f32_e32 v109, v59, v59
	v_cvt_pk_bf16_f32 v48, v60, v61
	v_cvt_pk_bf16_f32 v49, v62, v63
	v_cvt_pk_bf16_f32 v50, v56, v57
	v_cvt_pk_bf16_f32 v51, v58, v59
	v_mul_f32_e32 v57, v53, v53
	v_mul_f32_e32 v59, v55, v55
	v_mul_f32_e32 v61, v105, v105
	v_mul_f32_e32 v63, v103, v103
	v_fmac_f32_e32 v106, v60, v60
	v_fmac_f32_e32 v107, v62, v62
	v_fmac_f32_e32 v108, v56, v56
	v_fmac_f32_e32 v109, v58, v58
	v_fmac_f32_e32 v57, v52, v52
	v_fmac_f32_e32 v59, v54, v54
	v_fmac_f32_e32 v61, v104, v104
	v_fmac_f32_e32 v63, v102, v102
	global_store_dwordx4 v[110:111], v[48:51], off sc1
	s_nop 1
	v_cvt_pk_bf16_f32 v48, v52, v53
	v_cvt_pk_bf16_f32 v49, v54, v55
	v_cvt_pk_bf16_f32 v50, v104, v105
	v_add_f32_e32 v52, v106, v107
	v_add_f32_e32 v53, v108, v109
	v_add_f32_e32 v54, v57, v59
	v_add_f32_e32 v55, v61, v63
	v_cvt_pk_bf16_f32 v51, v102, v103
	global_store_dwordx4 v[110:111], v[48:51], off offset:256 sc1
	s_nop 1
	v_add_f32_e32 v48, v52, v53
	v_add_f32_e32 v49, v54, v55
	v_lshlrev_b32_e32 v50, 2, v120
	v_add_f32_e32 v48, v48, v49
	v_xor_b32_e32 v49, 64, v50
	v_mov_b32_e32 v49, v48
	s_nop 1
	v_permlane16_swap_b32_e32 v49, v48
	v_mov_b32_e32 v50, v201
	s_waitcnt lgkmcnt(0)
	v_add_f32_e32 v48, v48, v49
	v_lshlrev_b32_e32 v50, 2, v50
	v_xor_b32_e32 v49, 0x80, v50
	v_mov_b32_e32 v49, v48
	s_nop 1
	v_permlane32_swap_b32_e32 v49, v48
	s_and_saveexec_b64 s[40:41], s[10:11]
	s_cbranch_execz .LBB0_615
	s_waitcnt lgkmcnt(0)
	v_add_f32_e32 v50, v48, v49
	v_lshlrev_b64 v[48:49], 6, v[100:101]
	v_lshl_add_u64 v[48:49], s[24:25], 0, v[48:49]
	v_lshl_add_u64 v[48:49], s[38:39], 2, v[48:49]
	s_lshl_b32 s16, s50, 2
	v_lshl_add_u64 v[48:49], v[48:49], 0, s[16:17]
	global_store_dword v[48:49], v50, off sc1
; __device__ __forceinline__ float sq4(f32x4 v) { return (v[0] * v[0] + v[1] * v[1]) + (v[2] * v[2] + v[3] * v[3]); }
; __device__ __forceinline__ u32x4 pack8(f32x4 a, f32x4 b) { u32x4 w; w.x = cvt_pk_bf16(a[0], a[1]); w.y = cvt_pk_bf16(a[2], a[3]); w.z = cvt_pk_bf16(b[0], b[1]); w.w = cvt_pk_bf16(b[2], b[3]); return w; }
;     __device__ __forceinline__ void operator()(const f32x4 (&acc)[2][2][4][2], const Unit& u, int wr, int wc, int fr, int fq) const {
;     ...
;             for (int m = 0; m < 4; ++m) {
;                 const int row = u.pm * BM + ai * HALF + wr * 64 + m * 16 + fr;
;                 float q = 0.f;
; #pragma unroll
;                 for (int bj = 0; bj < 2; ++bj) {
;                     const size_t off = (size_t)row * 1024 + col0 + 128 * bj; const u32x4 w = bs[m][bj];
;                     const f32x4 b0 = (f32x4){__builtin_bit_cast(float, w.x << 16), __builtin_bit_cast(float, w.x & 0xffff0000u), __builtin_bit_cast(float, w.y << 16), __builtin_bit_cast(float, w.y & 0xffff0000u)};
;                     const f32x4 b1 = (f32x4){__builtin_bit_cast(float, w.z << 16), __builtin_bit_cast(float, w.z & 0xffff0000u), __builtin_bit_cast(float, w.w << 16), __builtin_bit_cast(float, w.w & 0xffff0000u)};
;                     const f32x4 v0 = acc[ai][bj][m][0] + b0, v1 = acc[ai][bj][m][1] + b1;
;                     if (last) { __builtin_nontemporal_store(v0, (f32x4*)(out + off)); __builtin_nontemporal_store(v1, (f32x4*)(out + off + 4)); }
;                     else { q += sq4(v0) + sq4(v1); *(u32x4*)(xb + off) = pack8(v0, v1); }
;                 }
;                 if (!last) { q += shx(q, 16); q += shx(q, 32); if (fq == 0) ss[(size_t)row * 16 + u.pn * 4 + wc] = q; }
.LBB0_615:
	s_or_b64 exec, exec, s[40:41]
	s_waitcnt vmcnt(7)
	v_lshlrev_b32_e32 v48, 16, v84
	s_waitcnt lgkmcnt(0)
	v_and_b32_e32 v49, 0xffff0000, v84
	v_lshlrev_b32_e32 v50, 16, v85
	v_and_b32_e32 v51, 0xffff0000, v85
	v_lshlrev_b32_e32 v52, 16, v86
	v_and_b32_e32 v53, 0xffff0000, v86
	v_lshlrev_b32_e32 v54, 16, v87
	v_and_b32_e32 v55, 0xffff0000, v87
	v_pk_add_f32 v[46:47], v[46:47], v[50:51]
	v_pk_add_f32 v[44:45], v[44:45], v[48:49]
	v_pk_add_f32 v[48:49], v[42:43], v[54:55]
	v_pk_add_f32 v[42:43], v[40:41], v[52:53]
	v_mul_f32_e32 v40, v45, v45
	v_mul_f32_e32 v41, v47, v47
	v_fmac_f32_e32 v40, v44, v44
	v_fmac_f32_e32 v41, v46, v46
	v_add_f32_e32 v40, v40, v41
	v_mul_f32_e32 v41, v43, v43
	v_mul_f32_e32 v50, v49, v49
	v_fmac_f32_e32 v41, v42, v42
	v_fmac_f32_e32 v50, v48, v48
	v_add_f32_e32 v41, v41, v50
	v_add_f32_e32 v50, v40, v41
	v_cvt_pk_bf16_f32 v40, v44, v45
	v_lshl_add_u64 v[44:45], s[22:23], 0, v[98:99]
	v_cvt_pk_bf16_f32 v41, v46, v47
	v_cvt_pk_bf16_f32 v42, v42, v43
	v_cvt_pk_bf16_f32 v43, v48, v49
	v_lshl_add_u64 v[44:45], v[168:169], 1, v[44:45]
	global_store_dwordx4 v[44:45], v[40:43], off sc1
	s_waitcnt vmcnt(7)
	v_lshlrev_b32_e32 v46, 16, v82
	v_and_b32_e32 v47, 0xffff0000, v82
	v_lshlrev_b32_e32 v40, 16, v80
	v_and_b32_e32 v41, 0xffff0000, v80
	v_lshlrev_b32_e32 v42, 16, v81
	v_and_b32_e32 v43, 0xffff0000, v81
	v_lshlrev_b32_e32 v48, 16, v83
	v_and_b32_e32 v49, 0xffff0000, v83
	v_pk_add_f32 v[38:39], v[38:39], v[42:43]
	v_pk_add_f32 v[36:37], v[36:37], v[40:41]
	v_pk_add_f32 v[40:41], v[34:35], v[48:49]
	v_pk_add_f32 v[34:35], v[32:33], v[46:47]
	v_mul_f32_e32 v32, v37, v37
	v_mul_f32_e32 v33, v39, v39
	v_fmac_f32_e32 v32, v36, v36
	v_fmac_f32_e32 v33, v38, v38
	v_add_f32_e32 v32, v32, v33
	v_mul_f32_e32 v33, v35, v35
	v_mul_f32_e32 v42, v41, v41
	v_fmac_f32_e32 v33, v34, v34
	v_fmac_f32_e32 v42, v40, v40
	v_add_f32_e32 v33, v33, v42
	v_add_f32_e32 v32, v32, v33
	v_add_f32_e32 v42, v50, v32
	v_cvt_pk_bf16_f32 v32, v36, v37
	v_cvt_pk_bf16_f32 v33, v38, v39
	v_cvt_pk_bf16_f32 v34, v34, v35
	v_cvt_pk_bf16_f32 v35, v40, v41
	global_store_dwordx4 v[44:45], v[32:35], off offset:256 sc1
	s_nop 1
	v_mov_b32_e32 v32, v201
	v_mov_b32_e32 v33, v201
	v_lshlrev_b32_e32 v32, 2, v32
	v_xor_b32_e32 v32, 64, v32
	v_mov_b32_e32 v32, v42
	s_nop 1
	v_permlane16_swap_b32_e32 v32, v42
	s_waitcnt lgkmcnt(0)
	v_add_f32_e32 v32, v42, v32
	v_lshlrev_b32_e32 v33, 2, v33
	v_xor_b32_e32 v33, 0x80, v33
	v_mov_b32_e32 v33, v32
	s_nop 1
	v_permlane32_swap_b32_e32 v33, v32
	s_and_saveexec_b64 s[40:41], s[10:11]
	s_cbranch_execz .LBB0_617
	s_waitcnt lgkmcnt(0)
	v_add_f32_e32 v34, v32, v33
	v_lshlrev_b64 v[32:33], 6, v[96:97]
	v_lshl_add_u64 v[32:33], s[24:25], 0, v[32:33]
	v_lshl_add_u64 v[32:33], s[38:39], 2, v[32:33]
	s_lshl_b32 s16, s50, 2
	v_lshl_add_u64 v[32:33], v[32:33], 0, s[16:17]
	global_store_dword v[32:33], v34, off sc1
; __device__ __forceinline__ float sq4(f32x4 v) { return (v[0] * v[0] + v[1] * v[1]) + (v[2] * v[2] + v[3] * v[3]); }
; __device__ __forceinline__ u32x4 pack8(f32x4 a, f32x4 b) { u32x4 w; w.x = cvt_pk_bf16(a[0], a[1]); w.y = cvt_pk_bf16(a[2], a[3]); w.z = cvt_pk_bf16(b[0], b[1]); w.w = cvt_pk_bf16(b[2], b[3]); return w; }
;     __device__ __forceinline__ void operator()(const f32x4 (&acc)[2][2][4][2], const Unit& u, int wr, int wc, int fr, int fq) const {
;     ...
;             for (int m = 0; m < 4; ++m) {
;                 const int row = u.pm * BM + ai * HALF + wr * 64 + m * 16 + fr;
;                 float q = 0.f;
; #pragma unroll
;                 for (int bj = 0; bj < 2; ++bj) {
;                     const size_t off = (size_t)row * 1024 + col0 + 128 * bj; const u32x4 w = bs[m][bj];
;                     const f32x4 b0 = (f32x4){__builtin_bit_cast(float, w.x << 16), __builtin_bit_cast(float, w.x & 0xffff0000u), __builtin_bit_cast(float, w.y << 16), __builtin_bit_cast(float, w.y & 0xffff0000u)};
;                     const f32x4 b1 = (f32x4){__builtin_bit_cast(float, w.z << 16), __builtin_bit_cast(float, w.z & 0xffff0000u), __builtin_bit_cast(float, w.w << 16), __builtin_bit_cast(float, w.w & 0xffff0000u)};
;                     const f32x4 v0 = acc[ai][bj][m][0] + b0, v1 = acc[ai][bj][m][1] + b1;
;                     if (last) { __builtin_nontemporal_store(v0, (f32x4*)(out + off)); __builtin_nontemporal_store(v1, (f32x4*)(out + off + 4)); }
;                     else { q += sq4(v0) + sq4(v1); *(u32x4*)(xb + off) = pack8(v0, v1); }
;                 }
;                 if (!last) { q += shx(q, 16); q += shx(q, 32); if (fq == 0) ss[(size_t)row * 16 + u.pn * 4 + wc] = q; }
.LBB0_617:
	s_or_b64 exec, exec, s[40:41]
	s_waitcnt vmcnt(7)
	v_lshlrev_b32_e32 v32, 16, v76
	s_waitcnt lgkmcnt(0)
	v_and_b32_e32 v33, 0xffff0000, v76
	v_lshlrev_b32_e32 v34, 16, v77
	v_and_b32_e32 v35, 0xffff0000, v77
	v_lshlrev_b32_e32 v36, 16, v78
	v_and_b32_e32 v37, 0xffff0000, v78
	v_lshlrev_b32_e32 v38, 16, v79
	v_and_b32_e32 v39, 0xffff0000, v79
	v_pk_add_f32 v[30:31], v[30:31], v[34:35]
	v_pk_add_f32 v[28:29], v[28:29], v[32:33]
	v_pk_add_f32 v[32:33], v[26:27], v[38:39]
	v_pk_add_f32 v[26:27], v[24:25], v[36:37]
	v_mul_f32_e32 v24, v29, v29
	v_mul_f32_e32 v25, v31, v31
	v_fmac_f32_e32 v24, v28, v28
	v_fmac_f32_e32 v25, v30, v30
	v_add_f32_e32 v24, v24, v25
	v_mul_f32_e32 v25, v27, v27
	v_mul_f32_e32 v34, v33, v33
	v_fmac_f32_e32 v25, v26, v26
	v_fmac_f32_e32 v34, v32, v32
	v_add_f32_e32 v25, v25, v34
	v_add_f32_e32 v34, v24, v25
	v_cvt_pk_bf16_f32 v24, v28, v29
	v_lshl_add_u64 v[28:29], s[22:23], 0, v[94:95]
	v_cvt_pk_bf16_f32 v25, v30, v31
	v_cvt_pk_bf16_f32 v26, v26, v27
	v_cvt_pk_bf16_f32 v27, v32, v33
	v_lshl_add_u64 v[28:29], v[168:169], 1, v[28:29]
	global_store_dwordx4 v[28:29], v[24:27], off sc1
	s_waitcnt vmcnt(7)
	v_lshlrev_b32_e32 v30, 16, v74
	v_and_b32_e32 v31, 0xffff0000, v74
	v_lshlrev_b32_e32 v24, 16, v72
	v_and_b32_e32 v25, 0xffff0000, v72
	v_lshlrev_b32_e32 v26, 16, v73
	v_and_b32_e32 v27, 0xffff0000, v73
	v_lshlrev_b32_e32 v32, 16, v75
	v_and_b32_e32 v33, 0xffff0000, v75
	v_pk_add_f32 v[22:23], v[22:23], v[26:27]
	v_pk_add_f32 v[20:21], v[20:21], v[24:25]
	v_pk_add_f32 v[24:25], v[18:19], v[32:33]
	v_pk_add_f32 v[18:19], v[16:17], v[30:31]
	v_mul_f32_e32 v16, v21, v21
	v_mul_f32_e32 v17, v23, v23
	v_fmac_f32_e32 v16, v20, v20
	v_fmac_f32_e32 v17, v22, v22
	v_add_f32_e32 v16, v16, v17
	v_mul_f32_e32 v17, v19, v19
	v_mul_f32_e32 v26, v25, v25
	v_fmac_f32_e32 v17, v18, v18
	v_fmac_f32_e32 v26, v24, v24
	v_add_f32_e32 v17, v17, v26
	v_add_f32_e32 v16, v16, v17
	v_add_f32_e32 v26, v34, v16
	v_cvt_pk_bf16_f32 v16, v20, v21
	v_cvt_pk_bf16_f32 v17, v22, v23
	v_cvt_pk_bf16_f32 v18, v18, v19
	v_cvt_pk_bf16_f32 v19, v24, v25
	global_store_dwordx4 v[28:29], v[16:19], off offset:256 sc1
	s_nop 1
	v_mov_b32_e32 v16, v201
	v_mov_b32_e32 v17, v201
	v_lshlrev_b32_e32 v16, 2, v16
	v_xor_b32_e32 v16, 64, v16
	v_mov_b32_e32 v16, v26
	s_nop 1
	v_permlane16_swap_b32_e32 v16, v26
	s_waitcnt lgkmcnt(0)
	v_add_f32_e32 v16, v26, v16
	v_lshlrev_b32_e32 v17, 2, v17
	v_xor_b32_e32 v17, 0x80, v17
	v_mov_b32_e32 v17, v16
	s_nop 1
	v_permlane32_swap_b32_e32 v17, v16
	s_and_saveexec_b64 s[40:41], s[10:11]
	s_cbranch_execz .LBB0_619
	s_waitcnt lgkmcnt(0)
	v_add_f32_e32 v18, v16, v17
	v_lshlrev_b64 v[16:17], 6, v[92:93]
	v_lshl_add_u64 v[16:17], s[24:25], 0, v[16:17]
	v_lshl_add_u64 v[16:17], s[38:39], 2, v[16:17]
	s_lshl_b32 s16, s50, 2
	v_lshl_add_u64 v[16:17], v[16:17], 0, s[16:17]
	global_store_dword v[16:17], v18, off sc1
.LBB0_619:
	s_or_b64 exec, exec, s[40:41]
	s_waitcnt vmcnt(7)
	v_lshlrev_b32_e32 v16, 16, v68
	s_waitcnt lgkmcnt(0)
	v_and_b32_e32 v17, 0xffff0000, v68
	v_lshlrev_b32_e32 v18, 16, v69
	v_and_b32_e32 v19, 0xffff0000, v69
	v_lshlrev_b32_e32 v20, 16, v70
	v_and_b32_e32 v21, 0xffff0000, v70
	v_lshlrev_b32_e32 v22, 16, v71
	v_and_b32_e32 v23, 0xffff0000, v71
	v_pk_add_f32 v[14:15], v[14:15], v[18:19]
	v_pk_add_f32 v[12:13], v[12:13], v[16:17]
	v_pk_add_f32 v[16:17], v[10:11], v[22:23]
	v_pk_add_f32 v[10:11], v[8:9], v[20:21]
	v_mul_f32_e32 v8, v13, v13
	v_mul_f32_e32 v9, v15, v15
	v_fmac_f32_e32 v8, v12, v12
	v_fmac_f32_e32 v9, v14, v14
	v_add_f32_e32 v8, v8, v9
	v_mul_f32_e32 v9, v11, v11
	v_mul_f32_e32 v18, v17, v17
	v_fmac_f32_e32 v9, v10, v10
	v_fmac_f32_e32 v18, v16, v16
	v_add_f32_e32 v9, v9, v18
	v_add_f32_e32 v18, v8, v9
	v_cvt_pk_bf16_f32 v8, v12, v13
	v_lshl_add_u64 v[12:13], s[22:23], 0, v[90:91]
	v_cvt_pk_bf16_f32 v9, v14, v15
	v_cvt_pk_bf16_f32 v10, v10, v11
	v_cvt_pk_bf16_f32 v11, v16, v17
	v_lshl_add_u64 v[12:13], v[168:169], 1, v[12:13]
	global_store_dwordx4 v[12:13], v[8:11], off sc1
	s_waitcnt vmcnt(7)
	v_lshlrev_b32_e32 v14, 16, v66
	v_and_b32_e32 v15, 0xffff0000, v66
	v_lshlrev_b32_e32 v8, 16, v64
	v_and_b32_e32 v9, 0xffff0000, v64
	v_lshlrev_b32_e32 v10, 16, v65
	v_and_b32_e32 v11, 0xffff0000, v65
	v_lshlrev_b32_e32 v16, 16, v67
	v_and_b32_e32 v17, 0xffff0000, v67
	v_pk_add_f32 v[6:7], v[6:7], v[10:11]
	v_pk_add_f32 v[4:5], v[4:5], v[8:9]
	v_pk_add_f32 v[8:9], v[2:3], v[16:17]
	v_pk_add_f32 v[2:3], v[0:1], v[14:15]
	v_mul_f32_e32 v0, v5, v5
	v_mul_f32_e32 v1, v7, v7
	v_fmac_f32_e32 v0, v4, v4
	v_fmac_f32_e32 v1, v6, v6
	v_add_f32_e32 v0, v0, v1
	v_mul_f32_e32 v1, v3, v3
	v_mul_f32_e32 v10, v9, v9
	v_fmac_f32_e32 v1, v2, v2
	v_fmac_f32_e32 v10, v8, v8
	v_add_f32_e32 v1, v1, v10
	v_add_f32_e32 v0, v0, v1
	v_add_f32_e32 v10, v18, v0
	v_cvt_pk_bf16_f32 v0, v4, v5
	v_cvt_pk_bf16_f32 v1, v6, v7
	v_cvt_pk_bf16_f32 v2, v2, v3
	v_cvt_pk_bf16_f32 v3, v8, v9
	global_store_dwordx4 v[12:13], v[0:3], off offset:256 sc1
	s_nop 1
	v_mov_b32_e32 v0, v201
	v_mov_b32_e32 v1, v201
	v_lshlrev_b32_e32 v0, 2, v0
	v_xor_b32_e32 v0, 64, v0
	v_mov_b32_e32 v0, v10
	s_nop 1
	v_permlane16_swap_b32_e32 v0, v10
	s_waitcnt lgkmcnt(0)
	v_add_f32_e32 v0, v10, v0
	v_lshlrev_b32_e32 v1, 2, v1
	v_xor_b32_e32 v1, 0x80, v1
	v_mov_b32_e32 v1, v0
	s_nop 1
	v_permlane32_swap_b32_e32 v1, v0
	s_and_saveexec_b64 s[40:41], s[10:11]
	s_cbranch_execz .LBB0_621
	s_waitcnt lgkmcnt(0)
	v_add_f32_e32 v2, v0, v1
	v_lshlrev_b64 v[0:1], 6, v[88:89]
	v_lshl_add_u64 v[0:1], s[24:25], 0, v[0:1]
	v_lshl_add_u64 v[0:1], s[38:39], 2, v[0:1]
	s_lshl_b32 s16, s50, 2
	v_lshl_add_u64 v[0:1], v[0:1], 0, s[16:17]
	global_store_dword v[0:1], v2, off sc1

; __device__ __forceinline__ float row_finish(float t) { t += shx(t, 16); t += shx(t, 32); return __builtin_amdgcn_rsqf(t * (1.0f / 1024.0f) + RMS_EPS); }
; __device__ __forceinline__ f32x4 silu4(f32x4 v) { return (f32x4){silu_f(v[0]), silu_f(v[1]), silu_f(v[2]), silu_f(v[3])}; }
; __device__ __forceinline__ float sq4(f32x4 v) { return (v[0] * v[0] + v[1] * v[1]) + (v[2] * v[2] + v[3] * v[3]); }
; __device__ __forceinline__ u32x4 pack8(f32x4 a, f32x4 b) { u32x4 w; w.x = cvt_pk_bf16(a[0], a[1]); w.y = cvt_pk_bf16(a[2], a[3]); w.z = cvt_pk_bf16(b[0], b[1]); w.w = cvt_pk_bf16(b[2], b[3]); return w; }
;     __device__ __forceinline__ void operator()(const f32x4 (&acc)[2][2][4][2], const Unit& u, int wr, int wc, int fr, int fq) const {
;     ...
;             for (int m = 0; m < 4; ++m) rs[ai][m] = row_finish(rs[ai][m]);
; #pragma unroll
;         for (int ai = 0; ai < 2; ++ai)
; #pragma unroll
;             for (int m = 0; m < 4; ++m) {
;                 const int row = u.pm * BM + ai * HALF + wr * 64 + m * 16 + fr;
;                 const float rstd = rs[ai][m];
;                 f32x4 v[2][2];
; #pragma unroll
;                 for (int bj = 0; bj < 2; ++bj)
; #pragma unroll
;                     for (int n = 0; n < 2; ++n) v[bj][n] = acc[ai][bj][m][n] * rstd;
;                 if (mode == 2) {
;                     float q = (sq4(v[0][0]) + sq4(v[0][1])) + (sq4(v[1][0]) + sq4(v[1][1]));
;                     q += shx(q, 16); q += shx(q, 32);
;                     const float r2 = __builtin_amdgcn_rsqf(q * (1.0f / 64.0f) + RMS_EPS);
; #pragma unroll
;                     for (int bj = 0; bj < 2; ++bj)
; #pragma unroll
;                         for (int n = 0; n < 2; ++n) v[bj][n] = v[bj][n] * r2 * wv[bj][n];
;                 } else if (mode == 1) {
; #pragma unroll
;                     for (int bj = 0; bj < 2; ++bj)
; #pragma unroll
;                         for (int n = 0; n < 2; ++n) v[bj][n] = silu4(v[bj][n]);
;                 } else {
; #pragma unroll
;                     for (int bj = 0; bj < 2; ++bj)
; #pragma unroll
;                         for (int n = 0; n < 2; ++n) v[bj][n] = v[bj][n] * sc;
;                 }
;                 bf16_t* rowp = U + (size_t)row * 2560 + lcol;
; #pragma unroll
;                 for (int bj = 0; bj < 2; ++bj) *(u32x4*)(rowp + 32 * bj) = pack8(v[bj][0], v[bj][1]);
.LBB0_717:
	v_add_f32_e32 v112, v193, v194
	v_fmamk_f32 v112, v112, 0x3a800000, v184
	v_rsq_f32_e32 v194, v112
	v_lshl_or_b32 v112, s44, 8, v179
	v_mov_b64_e32 v[196:197], s[22:23]
	v_ashrrev_i32_e32 v113, 31, v112
	v_mad_i64_i32 v[196:197], s[12:13], v170, s64, v[196:197]
	v_lshl_add_u64 v[196:197], v[112:113], 1, v[196:197]
	v_cvt_pk_bf16_f32 v124, v124, v125
	v_cvt_pk_bf16_f32 v125, v126, v127
	v_cvt_pk_bf16_f32 v126, v172, v173
	v_cvt_pk_bf16_f32 v127, v122, v123
	global_store_dwordx4 v[196:197], v[124:127], off sc1
	v_cvt_pk_bf16_f32 v116, v116, v117
	v_cvt_pk_bf16_f32 v117, v118, v119
	v_cvt_pk_bf16_f32 v118, v120, v121
	v_cvt_pk_bf16_f32 v119, v114, v115
	v_cndmask_b32_e64 v114, 0, 1, s[48:49]
	v_pk_mul_f32 v[110:111], v[110:111], v[194:195] op_sel_hi:[1,0]
	v_pk_mul_f32 v[108:109], v[108:109], v[194:195] op_sel_hi:[1,0]
	v_pk_mul_f32 v[106:107], v[106:107], v[194:195] op_sel_hi:[1,0]
	v_pk_mul_f32 v[104:105], v[104:105], v[194:195] op_sel_hi:[1,0]
	v_pk_mul_f32 v[102:103], v[102:103], v[194:195] op_sel_hi:[1,0]
	v_pk_mul_f32 v[100:101], v[100:101], v[194:195] op_sel_hi:[1,0]
	v_pk_mul_f32 v[98:99], v[98:99], v[194:195] op_sel_hi:[1,0]
	v_cmp_ne_u32_e64 s[12:13], 1, v114
	s_andn2_b64 vcc, exec, s[48:49]
	v_pk_mul_f32 v[96:97], v[96:97], v[194:195] op_sel_hi:[1,0]
	global_store_dwordx4 v[196:197], v[116:119], off offset:64 sc1
	s_cbranch_vccnz .LBB0_719
	s_nop 0
	v_mov_b32_e32 v116, v109
	v_mov_b32_e32 v117, v101
	v_mov_b32_e32 v114, v108
	v_mov_b32_e32 v115, v100
	v_pk_mul_f32 v[116:117], v[116:117], v[116:117]
	v_mov_b32_e32 v118, v111
	v_mov_b32_e32 v119, v103
	v_pk_fma_f32 v[114:115], v[114:115], v[114:115], v[116:117]
	v_mov_b32_e32 v116, v110
	v_mov_b32_e32 v117, v102
	v_pk_mul_f32 v[118:119], v[118:119], v[118:119]
	v_mov_b32_e32 v120, v107
	v_pk_fma_f32 v[116:117], v[116:117], v[116:117], v[118:119]
	v_mov_b32_e32 v118, v105
	v_mov_b32_e32 v119, v97
	v_pk_add_f32 v[114:115], v[114:115], v[116:117]
	v_mov_b32_e32 v116, v104
	v_mov_b32_e32 v117, v96
	v_pk_mul_f32 v[118:119], v[118:119], v[118:119]
	v_mov_b32_e32 v121, v99
	v_pk_fma_f32 v[116:117], v[116:117], v[116:117], v[118:119]
	v_mov_b32_e32 v118, v106
	v_mov_b32_e32 v119, v98
	v_pk_mul_f32 v[120:121], v[120:121], v[120:121]
	s_nop 0
	v_pk_fma_f32 v[118:119], v[118:119], v[118:119], v[120:121]
	s_nop 0
	v_pk_add_f32 v[116:117], v[116:117], v[118:119]
	s_nop 0
	v_pk_add_f32 v[114:115], v[114:115], v[116:117]
	s_nop 0
	v_add_f32_e32 v114, v114, v115
	v_mov_b32_e32 v115, v201
	s_nop 0
	v_lshlrev_b32_e32 v115, 2, v115
	v_xor_b32_e32 v115, 64, v115
	v_mov_b32_e32 v115, v114
	s_nop 1
	v_permlane16_swap_b32_e32 v115, v114
	s_waitcnt lgkmcnt(0)
	v_add_f32_e32 v114, v114, v115
	v_mov_b32_e32 v115, v201
	s_nop 0
	v_lshlrev_b32_e32 v115, 2, v115
	v_xor_b32_e32 v115, 0x80, v115
	v_mov_b32_e32 v115, v114
	s_nop 1
	v_permlane32_swap_b32_e32 v115, v114
	s_waitcnt lgkmcnt(0)
	v_add_f32_e32 v114, v114, v115
	v_fmamk_f32 v114, v114, 0x3c800000, v184
	v_rsq_f32_e32 v114, v114
	s_nop 0
	v_pk_mul_f32 v[108:109], v[108:109], v[114:115] op_sel_hi:[1,0]
	v_pk_mul_f32 v[110:111], v[110:111], v[114:115] op_sel_hi:[1,0]
	v_pk_mul_f32 v[104:105], v[104:105], v[114:115] op_sel_hi:[1,0]
	v_pk_mul_f32 v[106:107], v[106:107], v[114:115] op_sel_hi:[1,0]
	v_pk_mul_f32 v[100:101], v[100:101], v[114:115] op_sel_hi:[1,0]
	v_pk_mul_f32 v[102:103], v[102:103], v[114:115] op_sel_hi:[1,0]
	v_pk_mul_f32 v[96:97], v[96:97], v[114:115] op_sel_hi:[1,0]
	v_pk_mul_f32 v[98:99], v[98:99], v[114:115] op_sel_hi:[1,0]
	v_pk_mul_f32 v[110:111], v[160:161], v[110:111]
	v_pk_mul_f32 v[108:109], v[162:163], v[108:109]
	v_pk_mul_f32 v[106:107], v[156:157], v[106:107]
	v_pk_mul_f32 v[104:105], v[158:159], v[104:105]
	v_pk_mul_f32 v[102:103], v[152:153], v[102:103]
	v_pk_mul_f32 v[100:101], v[154:155], v[100:101]
	v_pk_mul_f32 v[98:99], v[148:149], v[98:99]
	v_pk_mul_f32 v[96:97], v[150:151], v[96:97]
.LBB0_719:
	v_add_f32_e32 v114, v191, v192
	v_fmamk_f32 v114, v114, 0x3a800000, v184
	v_rsq_f32_e32 v114, v114
	v_add_u32_e32 v115, s35, v176
	v_mov_b64_e32 v[116:117], s[22:23]
	v_mad_i64_i32 v[116:117], s[48:49], v115, s64, v[116:117]
	v_lshl_add_u64 v[116:117], v[112:113], 1, v[116:117]
	v_pk_mul_f32 v[94:95], v[94:95], v[114:115] op_sel_hi:[1,0]
	v_pk_mul_f32 v[92:93], v[92:93], v[114:115] op_sel_hi:[1,0]
	v_pk_mul_f32 v[90:91], v[90:91], v[114:115] op_sel_hi:[1,0]
	v_pk_mul_f32 v[88:89], v[88:89], v[114:115] op_sel_hi:[1,0]
	v_pk_mul_f32 v[86:87], v[86:87], v[114:115] op_sel_hi:[1,0]
	v_pk_mul_f32 v[84:85], v[84:85], v[114:115] op_sel_hi:[1,0]
	v_pk_mul_f32 v[82:83], v[82:83], v[114:115] op_sel_hi:[1,0]
	s_and_b64 vcc, exec, s[12:13]
	v_pk_mul_f32 v[80:81], v[80:81], v[114:115] op_sel_hi:[1,0]
	v_cvt_pk_bf16_f32 v108, v108, v109
	v_cvt_pk_bf16_f32 v109, v110, v111
	v_cvt_pk_bf16_f32 v110, v104, v105
	v_cvt_pk_bf16_f32 v111, v106, v107
	global_store_dwordx4 v[116:117], v[108:111], off sc1
	v_cvt_pk_bf16_f32 v100, v100, v101
	v_cvt_pk_bf16_f32 v101, v102, v103
	v_cvt_pk_bf16_f32 v102, v96, v97
	v_cvt_pk_bf16_f32 v103, v98, v99
	global_store_dwordx4 v[116:117], v[100:103], off offset:64 sc1
	s_cbranch_vccnz .LBB0_721
; __device__ __forceinline__ f32x4 silu4(f32x4 v) { return (f32x4){silu_f(v[0]), silu_f(v[1]), silu_f(v[2]), silu_f(v[3])}; }
; __device__ __forceinline__ float sq4(f32x4 v) { return (v[0] * v[0] + v[1] * v[1]) + (v[2] * v[2] + v[3] * v[3]); }
; __device__ __forceinline__ u32x4 pack8(f32x4 a, f32x4 b) { u32x4 w; w.x = cvt_pk_bf16(a[0], a[1]); w.y = cvt_pk_bf16(a[2], a[3]); w.z = cvt_pk_bf16(b[0], b[1]); w.w = cvt_pk_bf16(b[2], b[3]); return w; }
;     __device__ __forceinline__ void operator()(const f32x4 (&acc)[2][2][4][2], const Unit& u, int wr, int wc, int fr, int fq) const {
;     ...
;                 if (mode == 2) {
;                     float q = (sq4(v[0][0]) + sq4(v[0][1])) + (sq4(v[1][0]) + sq4(v[1][1]));
;                     q += shx(q, 16); q += shx(q, 32);
;                     const float r2 = __builtin_amdgcn_rsqf(q * (1.0f / 64.0f) + RMS_EPS);
; #pragma unroll
;                     for (int bj = 0; bj < 2; ++bj)
; #pragma unroll
;                         for (int n = 0; n < 2; ++n) v[bj][n] = v[bj][n] * r2 * wv[bj][n];
;                 } else if (mode == 1) {
; #pragma unroll
;                     for (int bj = 0; bj < 2; ++bj)
; #pragma unroll
;                         for (int n = 0; n < 2; ++n) v[bj][n] = silu4(v[bj][n]);
;                 } else {
; #pragma unroll
;                     for (int bj = 0; bj < 2; ++bj)
; #pragma unroll
;                         for (int n = 0; n < 2; ++n) v[bj][n] = v[bj][n] * sc;
;                 }
;                 bf16_t* rowp = U + (size_t)row * 2560 + lcol;
; #pragma unroll
;                 for (int bj = 0; bj < 2; ++bj) *(u32x4*)(rowp + 32 * bj) = pack8(v[bj][0], v[bj][1]);
	v_mov_b32_e32 v98, v93
	v_mov_b32_e32 v99, v85
	v_mov_b32_e32 v96, v92
	v_mov_b32_e32 v97, v84
	v_pk_mul_f32 v[98:99], v[98:99], v[98:99]
	v_mov_b32_e32 v100, v95
	v_mov_b32_e32 v101, v87
	v_pk_fma_f32 v[96:97], v[96:97], v[96:97], v[98:99]
	v_mov_b32_e32 v98, v94
	v_mov_b32_e32 v99, v86
	v_pk_mul_f32 v[100:101], v[100:101], v[100:101]
	v_mov_b32_e32 v102, v91
	v_pk_fma_f32 v[98:99], v[98:99], v[98:99], v[100:101]
	v_mov_b32_e32 v100, v89
	v_mov_b32_e32 v101, v81
	v_pk_add_f32 v[96:97], v[96:97], v[98:99]
	v_mov_b32_e32 v98, v88
	v_mov_b32_e32 v99, v80
	v_pk_mul_f32 v[100:101], v[100:101], v[100:101]
	v_mov_b32_e32 v103, v83
	v_pk_fma_f32 v[98:99], v[98:99], v[98:99], v[100:101]
	v_mov_b32_e32 v100, v90
	v_mov_b32_e32 v101, v82
	v_pk_mul_f32 v[102:103], v[102:103], v[102:103]
	s_nop 0
	v_pk_fma_f32 v[100:101], v[100:101], v[100:101], v[102:103]
	s_nop 0
	v_pk_add_f32 v[98:99], v[98:99], v[100:101]
	s_nop 0
	v_pk_add_f32 v[96:97], v[96:97], v[98:99]
	s_nop 0
	v_add_f32_e32 v96, v96, v97
	v_mov_b32_e32 v97, v201
	s_nop 0
	v_lshlrev_b32_e32 v97, 2, v97
	v_xor_b32_e32 v97, 64, v97
	v_mov_b32_e32 v97, v96
	s_nop 1
	v_permlane16_swap_b32_e32 v97, v96
	s_waitcnt lgkmcnt(0)
	v_add_f32_e32 v96, v96, v97
	v_mov_b32_e32 v97, v201
	s_nop 0
	v_lshlrev_b32_e32 v97, 2, v97
	v_xor_b32_e32 v97, 0x80, v97
	v_mov_b32_e32 v97, v96
	s_nop 1
	v_permlane32_swap_b32_e32 v97, v96
	s_waitcnt lgkmcnt(0)
	v_add_f32_e32 v96, v96, v97
	v_fmamk_f32 v96, v96, 0x3c800000, v184
	v_rsq_f32_e32 v96, v96
	s_nop 0
	v_pk_mul_f32 v[92:93], v[92:93], v[96:97] op_sel_hi:[1,0]
	v_pk_mul_f32 v[94:95], v[94:95], v[96:97] op_sel_hi:[1,0]
	v_pk_mul_f32 v[88:89], v[88:89], v[96:97] op_sel_hi:[1,0]
	v_pk_mul_f32 v[90:91], v[90:91], v[96:97] op_sel_hi:[1,0]
	v_pk_mul_f32 v[84:85], v[84:85], v[96:97] op_sel_hi:[1,0]
	v_pk_mul_f32 v[86:87], v[86:87], v[96:97] op_sel_hi:[1,0]
	v_pk_mul_f32 v[80:81], v[80:81], v[96:97] op_sel_hi:[1,0]
	v_pk_mul_f32 v[82:83], v[82:83], v[96:97] op_sel_hi:[1,0]
	v_pk_mul_f32 v[94:95], v[160:161], v[94:95]
	v_pk_mul_f32 v[92:93], v[162:163], v[92:93]
	v_pk_mul_f32 v[90:91], v[156:157], v[90:91]
	v_pk_mul_f32 v[88:89], v[158:159], v[88:89]
	v_pk_mul_f32 v[86:87], v[152:153], v[86:87]
	v_pk_mul_f32 v[84:85], v[154:155], v[84:85]
	v_pk_mul_f32 v[82:83], v[148:149], v[82:83]
	v_pk_mul_f32 v[80:81], v[150:151], v[80:81]
.LBB0_721:
	v_add_f32_e32 v96, v189, v190
	v_fmamk_f32 v96, v96, 0x3a800000, v184
	v_rsq_f32_e32 v96, v96
	v_add_u32_e32 v97, s35, v177
	v_mov_b64_e32 v[98:99], s[22:23]
	v_mad_i64_i32 v[98:99], s[48:49], v97, s64, v[98:99]
	v_lshl_add_u64 v[98:99], v[112:113], 1, v[98:99]
	v_pk_mul_f32 v[78:79], v[78:79], v[96:97] op_sel_hi:[1,0]
	v_pk_mul_f32 v[76:77], v[76:77], v[96:97] op_sel_hi:[1,0]
	v_pk_mul_f32 v[74:75], v[74:75], v[96:97] op_sel_hi:[1,0]
	v_pk_mul_f32 v[72:73], v[72:73], v[96:97] op_sel_hi:[1,0]
	v_pk_mul_f32 v[70:71], v[70:71], v[96:97] op_sel_hi:[1,0]
	v_pk_mul_f32 v[68:69], v[68:69], v[96:97] op_sel_hi:[1,0]
	v_pk_mul_f32 v[66:67], v[66:67], v[96:97] op_sel_hi:[1,0]
	s_and_b64 vcc, exec, s[12:13]
	v_pk_mul_f32 v[64:65], v[64:65], v[96:97] op_sel_hi:[1,0]
	v_cvt_pk_bf16_f32 v92, v92, v93
	v_cvt_pk_bf16_f32 v93, v94, v95
	v_cvt_pk_bf16_f32 v94, v88, v89
	v_cvt_pk_bf16_f32 v95, v90, v91
	global_store_dwordx4 v[98:99], v[92:95], off sc1
	v_cvt_pk_bf16_f32 v84, v84, v85
	v_cvt_pk_bf16_f32 v85, v86, v87
	v_cvt_pk_bf16_f32 v86, v80, v81
	v_cvt_pk_bf16_f32 v87, v82, v83
	global_store_dwordx4 v[98:99], v[84:87], off offset:64 sc1
	s_cbranch_vccnz .LBB0_723
	v_mov_b32_e32 v82, v77
	v_mov_b32_e32 v83, v69
	v_mov_b32_e32 v80, v76
	v_mov_b32_e32 v81, v68
	v_pk_mul_f32 v[82:83], v[82:83], v[82:83]
	v_mov_b32_e32 v84, v79
	v_mov_b32_e32 v85, v71
	v_pk_fma_f32 v[80:81], v[80:81], v[80:81], v[82:83]
	v_mov_b32_e32 v82, v78
	v_mov_b32_e32 v83, v70
	v_pk_mul_f32 v[84:85], v[84:85], v[84:85]
	v_mov_b32_e32 v86, v75
	v_pk_fma_f32 v[82:83], v[82:83], v[82:83], v[84:85]
	v_mov_b32_e32 v84, v73
	v_mov_b32_e32 v85, v65
	v_pk_add_f32 v[80:81], v[80:81], v[82:83]
	v_mov_b32_e32 v82, v72
	v_mov_b32_e32 v83, v64
	v_pk_mul_f32 v[84:85], v[84:85], v[84:85]
	v_mov_b32_e32 v87, v67
	v_pk_fma_f32 v[82:83], v[82:83], v[82:83], v[84:85]
	v_mov_b32_e32 v84, v74
	v_mov_b32_e32 v85, v66
	v_pk_mul_f32 v[86:87], v[86:87], v[86:87]
	s_nop 0
	v_pk_fma_f32 v[84:85], v[84:85], v[84:85], v[86:87]
	s_nop 0
	v_pk_add_f32 v[82:83], v[82:83], v[84:85]
	s_nop 0
	v_pk_add_f32 v[80:81], v[80:81], v[82:83]
	s_nop 0
	v_add_f32_e32 v80, v80, v81
	v_mov_b32_e32 v81, v201
	s_nop 0
	v_lshlrev_b32_e32 v81, 2, v81
	v_xor_b32_e32 v81, 64, v81
	v_mov_b32_e32 v81, v80
	s_nop 1
	v_permlane16_swap_b32_e32 v81, v80
	s_waitcnt lgkmcnt(0)
	v_add_f32_e32 v80, v80, v81
	v_mov_b32_e32 v81, v201
	s_nop 0
	v_lshlrev_b32_e32 v81, 2, v81
	v_xor_b32_e32 v81, 0x80, v81
	v_mov_b32_e32 v81, v80
	s_nop 1
	v_permlane32_swap_b32_e32 v81, v80
	s_waitcnt lgkmcnt(0)
	v_add_f32_e32 v80, v80, v81
	v_fmamk_f32 v80, v80, 0x3c800000, v184
	v_rsq_f32_e32 v80, v80
	s_nop 0
	v_pk_mul_f32 v[76:77], v[76:77], v[80:81] op_sel_hi:[1,0]
	v_pk_mul_f32 v[78:79], v[78:79], v[80:81] op_sel_hi:[1,0]
	v_pk_mul_f32 v[72:73], v[72:73], v[80:81] op_sel_hi:[1,0]
	v_pk_mul_f32 v[74:75], v[74:75], v[80:81] op_sel_hi:[1,0]
	v_pk_mul_f32 v[68:69], v[68:69], v[80:81] op_sel_hi:[1,0]
	v_pk_mul_f32 v[70:71], v[70:71], v[80:81] op_sel_hi:[1,0]
	v_pk_mul_f32 v[64:65], v[64:65], v[80:81] op_sel_hi:[1,0]
	v_pk_mul_f32 v[66:67], v[66:67], v[80:81] op_sel_hi:[1,0]
	v_pk_mul_f32 v[78:79], v[160:161], v[78:79]
	v_pk_mul_f32 v[76:77], v[162:163], v[76:77]
	v_pk_mul_f32 v[74:75], v[156:157], v[74:75]
	v_pk_mul_f32 v[72:73], v[158:159], v[72:73]
	v_pk_mul_f32 v[70:71], v[152:153], v[70:71]
	v_pk_mul_f32 v[68:69], v[154:155], v[68:69]
	v_pk_mul_f32 v[66:67], v[148:149], v[66:67]
	v_pk_mul_f32 v[64:65], v[150:151], v[64:65]
; __device__ __forceinline__ float row_finish(float t) { t += shx(t, 16); t += shx(t, 32); return __builtin_amdgcn_rsqf(t * (1.0f / 1024.0f) + RMS_EPS); }
; __device__ __forceinline__ f32x4 silu4(f32x4 v) { return (f32x4){silu_f(v[0]), silu_f(v[1]), silu_f(v[2]), silu_f(v[3])}; }
; __device__ __forceinline__ float sq4(f32x4 v) { return (v[0] * v[0] + v[1] * v[1]) + (v[2] * v[2] + v[3] * v[3]); }
; __device__ __forceinline__ u32x4 pack8(f32x4 a, f32x4 b) { u32x4 w; w.x = cvt_pk_bf16(a[0], a[1]); w.y = cvt_pk_bf16(a[2], a[3]); w.z = cvt_pk_bf16(b[0], b[1]); w.w = cvt_pk_bf16(b[2], b[3]); return w; }
;     __device__ __forceinline__ void operator()(const f32x4 (&acc)[2][2][4][2], const Unit& u, int wr, int wc, int fr, int fq) const {
;     ...
;             for (int m = 0; m < 4; ++m) rs[ai][m] = row_finish(rs[ai][m]);
; #pragma unroll
;         for (int ai = 0; ai < 2; ++ai)
; #pragma unroll
;             for (int m = 0; m < 4; ++m) {
;                 const int row = u.pm * BM + ai * HALF + wr * 64 + m * 16 + fr;
;                 const float rstd = rs[ai][m];
;                 f32x4 v[2][2];
; #pragma unroll
;                 for (int bj = 0; bj < 2; ++bj)
; #pragma unroll
;                     for (int n = 0; n < 2; ++n) v[bj][n] = acc[ai][bj][m][n] * rstd;
;                 if (mode == 2) {
;                     float q = (sq4(v[0][0]) + sq4(v[0][1])) + (sq4(v[1][0]) + sq4(v[1][1]));
;                     q += shx(q, 16); q += shx(q, 32);
;                     const float r2 = __builtin_amdgcn_rsqf(q * (1.0f / 64.0f) + RMS_EPS);
; #pragma unroll
;                     for (int bj = 0; bj < 2; ++bj)
; #pragma unroll
;                         for (int n = 0; n < 2; ++n) v[bj][n] = v[bj][n] * r2 * wv[bj][n];
;                 } else if (mode == 1) {
; #pragma unroll
;                     for (int bj = 0; bj < 2; ++bj)
; #pragma unroll
;                         for (int n = 0; n < 2; ++n) v[bj][n] = silu4(v[bj][n]);
;                 } else {
; #pragma unroll
;                     for (int bj = 0; bj < 2; ++bj)
; #pragma unroll
;                         for (int n = 0; n < 2; ++n) v[bj][n] = v[bj][n] * sc;
;                 }
;                 bf16_t* rowp = U + (size_t)row * 2560 + lcol;
; #pragma unroll
;                 for (int bj = 0; bj < 2; ++bj) *(u32x4*)(rowp + 32 * bj) = pack8(v[bj][0], v[bj][1]);
.LBB0_723:
	v_add_f32_e32 v80, v187, v188
	v_fmamk_f32 v80, v80, 0x3a800000, v184
	v_rsq_f32_e32 v80, v80
	v_add_u32_e32 v81, s35, v178
	v_mov_b64_e32 v[82:83], s[22:23]
	v_mad_i64_i32 v[82:83], s[48:49], v81, s64, v[82:83]
	v_lshl_add_u64 v[82:83], v[112:113], 1, v[82:83]
	v_pk_mul_f32 v[62:63], v[62:63], v[80:81] op_sel_hi:[1,0]
	v_pk_mul_f32 v[60:61], v[60:61], v[80:81] op_sel_hi:[1,0]
	v_pk_mul_f32 v[58:59], v[58:59], v[80:81] op_sel_hi:[1,0]
	v_pk_mul_f32 v[56:57], v[56:57], v[80:81] op_sel_hi:[1,0]
	v_pk_mul_f32 v[54:55], v[54:55], v[80:81] op_sel_hi:[1,0]
	v_pk_mul_f32 v[52:53], v[52:53], v[80:81] op_sel_hi:[1,0]
	v_pk_mul_f32 v[50:51], v[50:51], v[80:81] op_sel_hi:[1,0]
	s_and_b64 vcc, exec, s[12:13]
	v_pk_mul_f32 v[48:49], v[48:49], v[80:81] op_sel_hi:[1,0]
	v_cvt_pk_bf16_f32 v76, v76, v77
	v_cvt_pk_bf16_f32 v77, v78, v79
	v_cvt_pk_bf16_f32 v78, v72, v73
	v_cvt_pk_bf16_f32 v79, v74, v75
	global_store_dwordx4 v[82:83], v[76:79], off sc1
	v_cvt_pk_bf16_f32 v68, v68, v69
	v_cvt_pk_bf16_f32 v69, v70, v71
	v_cvt_pk_bf16_f32 v70, v64, v65
	v_cvt_pk_bf16_f32 v71, v66, v67
	global_store_dwordx4 v[82:83], v[68:71], off offset:64 sc1
	s_cbranch_vccnz .LBB0_725
	v_mov_b32_e32 v66, v61
	v_mov_b32_e32 v67, v53
	v_mov_b32_e32 v64, v60
	v_mov_b32_e32 v65, v52
	v_pk_mul_f32 v[66:67], v[66:67], v[66:67]
	v_mov_b32_e32 v68, v63
	v_mov_b32_e32 v69, v55
	v_pk_fma_f32 v[64:65], v[64:65], v[64:65], v[66:67]
	v_mov_b32_e32 v66, v62
	v_mov_b32_e32 v67, v54
	v_pk_mul_f32 v[68:69], v[68:69], v[68:69]
	v_mov_b32_e32 v70, v59
	v_pk_fma_f32 v[66:67], v[66:67], v[66:67], v[68:69]
	v_mov_b32_e32 v68, v57
	v_mov_b32_e32 v69, v49
	v_pk_add_f32 v[64:65], v[64:65], v[66:67]
	v_mov_b32_e32 v66, v56
	v_mov_b32_e32 v67, v48
	v_pk_mul_f32 v[68:69], v[68:69], v[68:69]
	v_mov_b32_e32 v71, v51
	v_pk_fma_f32 v[66:67], v[66:67], v[66:67], v[68:69]
	v_mov_b32_e32 v68, v58
	v_mov_b32_e32 v69, v50
	v_pk_mul_f32 v[70:71], v[70:71], v[70:71]
	s_nop 0
	v_pk_fma_f32 v[68:69], v[68:69], v[68:69], v[70:71]
	s_nop 0
	v_pk_add_f32 v[66:67], v[66:67], v[68:69]
	s_nop 0
	v_pk_add_f32 v[64:65], v[64:65], v[66:67]
	s_nop 0
	v_add_f32_e32 v64, v64, v65
	v_mov_b32_e32 v65, v201
	s_nop 0
	v_lshlrev_b32_e32 v65, 2, v65
	v_xor_b32_e32 v65, 64, v65
	v_mov_b32_e32 v65, v64
	s_nop 1
	v_permlane16_swap_b32_e32 v65, v64
	s_waitcnt lgkmcnt(0)
	v_add_f32_e32 v64, v64, v65
	v_mov_b32_e32 v65, v201
	s_nop 0
	v_lshlrev_b32_e32 v65, 2, v65
	v_xor_b32_e32 v65, 0x80, v65
	v_mov_b32_e32 v65, v64
	s_nop 1
	v_permlane32_swap_b32_e32 v65, v64
	s_waitcnt lgkmcnt(0)
	v_add_f32_e32 v64, v64, v65
	v_fmamk_f32 v64, v64, 0x3c800000, v184
	v_rsq_f32_e32 v64, v64
	s_nop 0
	v_pk_mul_f32 v[60:61], v[60:61], v[64:65] op_sel_hi:[1,0]
	v_pk_mul_f32 v[62:63], v[62:63], v[64:65] op_sel_hi:[1,0]
	v_pk_mul_f32 v[56:57], v[56:57], v[64:65] op_sel_hi:[1,0]
	v_pk_mul_f32 v[58:59], v[58:59], v[64:65] op_sel_hi:[1,0]
	v_pk_mul_f32 v[52:53], v[52:53], v[64:65] op_sel_hi:[1,0]
	v_pk_mul_f32 v[54:55], v[54:55], v[64:65] op_sel_hi:[1,0]
	v_pk_mul_f32 v[48:49], v[48:49], v[64:65] op_sel_hi:[1,0]
	v_pk_mul_f32 v[50:51], v[50:51], v[64:65] op_sel_hi:[1,0]
	v_pk_mul_f32 v[62:63], v[160:161], v[62:63]
	v_pk_mul_f32 v[60:61], v[162:163], v[60:61]
	v_pk_mul_f32 v[58:59], v[156:157], v[58:59]
	v_pk_mul_f32 v[56:57], v[158:159], v[56:57]
	v_pk_mul_f32 v[54:55], v[152:153], v[54:55]
	v_pk_mul_f32 v[52:53], v[154:155], v[52:53]
	v_pk_mul_f32 v[50:51], v[148:149], v[50:51]
	v_pk_mul_f32 v[48:49], v[150:151], v[48:49]
.LBB0_725:
	v_add_f32_e32 v64, v171, v186
	v_fmamk_f32 v64, v64, 0x3a800000, v184
	v_rsq_f32_e32 v64, v64
	v_mov_b64_e32 v[66:67], s[22:23]
	v_mad_i64_i32 v[66:67], s[48:49], v168, s64, v[66:67]
	v_lshl_add_u64 v[66:67], v[112:113], 1, v[66:67]
	v_pk_mul_f32 v[46:47], v[46:47], v[64:65] op_sel_hi:[1,0]
	v_pk_mul_f32 v[44:45], v[44:45], v[64:65] op_sel_hi:[1,0]
	v_pk_mul_f32 v[42:43], v[42:43], v[64:65] op_sel_hi:[1,0]
	v_pk_mul_f32 v[40:41], v[40:41], v[64:65] op_sel_hi:[1,0]
	v_pk_mul_f32 v[38:39], v[38:39], v[64:65] op_sel_hi:[1,0]
	v_pk_mul_f32 v[36:37], v[36:37], v[64:65] op_sel_hi:[1,0]
	v_pk_mul_f32 v[34:35], v[34:35], v[64:65] op_sel_hi:[1,0]
	s_and_b64 vcc, exec, s[12:13]
	v_pk_mul_f32 v[32:33], v[32:33], v[64:65] op_sel_hi:[1,0]
	v_cvt_pk_bf16_f32 v60, v60, v61
	v_cvt_pk_bf16_f32 v61, v62, v63
	v_cvt_pk_bf16_f32 v62, v56, v57
	v_cvt_pk_bf16_f32 v63, v58, v59
	global_store_dwordx4 v[66:67], v[60:63], off sc1
	v_cvt_pk_bf16_f32 v52, v52, v53
	v_cvt_pk_bf16_f32 v53, v54, v55
	v_cvt_pk_bf16_f32 v54, v48, v49
	v_cvt_pk_bf16_f32 v55, v50, v51
	global_store_dwordx4 v[66:67], v[52:55], off offset:64 sc1
	s_cbranch_vccnz .LBB0_727
	v_mov_b32_e32 v50, v45
	v_mov_b32_e32 v51, v37
	v_mov_b32_e32 v48, v44
	v_mov_b32_e32 v49, v36
	v_pk_mul_f32 v[50:51], v[50:51], v[50:51]
	v_mov_b32_e32 v52, v47
	v_mov_b32_e32 v53, v39
	v_pk_fma_f32 v[48:49], v[48:49], v[48:49], v[50:51]
	v_mov_b32_e32 v50, v46
	v_mov_b32_e32 v51, v38
	v_pk_mul_f32 v[52:53], v[52:53], v[52:53]
	v_mov_b32_e32 v54, v43
	v_pk_fma_f32 v[50:51], v[50:51], v[50:51], v[52:53]
	v_mov_b32_e32 v52, v41
	v_mov_b32_e32 v53, v33
	v_pk_add_f32 v[48:49], v[48:49], v[50:51]
	v_mov_b32_e32 v50, v40
	v_mov_b32_e32 v51, v32
	v_pk_mul_f32 v[52:53], v[52:53], v[52:53]
	v_mov_b32_e32 v55, v35
	v_pk_fma_f32 v[50:51], v[50:51], v[50:51], v[52:53]
	v_mov_b32_e32 v52, v42
	v_mov_b32_e32 v53, v34
	v_pk_mul_f32 v[54:55], v[54:55], v[54:55]
	s_nop 0
	v_pk_fma_f32 v[52:53], v[52:53], v[52:53], v[54:55]
	s_nop 0
	v_pk_add_f32 v[50:51], v[50:51], v[52:53]
	s_nop 0
	v_pk_add_f32 v[48:49], v[48:49], v[50:51]
	s_nop 0
	v_add_f32_e32 v48, v48, v49
	v_mov_b32_e32 v49, v201
	s_nop 0
	v_lshlrev_b32_e32 v49, 2, v49
	v_xor_b32_e32 v49, 64, v49
	v_mov_b32_e32 v49, v48
	s_nop 1
	v_permlane16_swap_b32_e32 v49, v48
	s_waitcnt lgkmcnt(0)
	v_add_f32_e32 v48, v48, v49
	v_mov_b32_e32 v49, v201
	s_nop 0
	v_lshlrev_b32_e32 v49, 2, v49
	v_xor_b32_e32 v49, 0x80, v49
	v_mov_b32_e32 v49, v48
	s_nop 1
	v_permlane32_swap_b32_e32 v49, v48
	s_waitcnt lgkmcnt(0)
	v_add_f32_e32 v48, v48, v49
	v_fmamk_f32 v48, v48, 0x3c800000, v184
	v_rsq_f32_e32 v48, v48
	s_nop 0
	v_pk_mul_f32 v[44:45], v[44:45], v[48:49] op_sel_hi:[1,0]
	v_pk_mul_f32 v[46:47], v[46:47], v[48:49] op_sel_hi:[1,0]
	v_pk_mul_f32 v[40:41], v[40:41], v[48:49] op_sel_hi:[1,0]
	v_pk_mul_f32 v[42:43], v[42:43], v[48:49] op_sel_hi:[1,0]
	v_pk_mul_f32 v[36:37], v[36:37], v[48:49] op_sel_hi:[1,0]
	v_pk_mul_f32 v[38:39], v[38:39], v[48:49] op_sel_hi:[1,0]
	v_pk_mul_f32 v[32:33], v[32:33], v[48:49] op_sel_hi:[1,0]
	v_pk_mul_f32 v[34:35], v[34:35], v[48:49] op_sel_hi:[1,0]
	v_pk_mul_f32 v[46:47], v[160:161], v[46:47]
	v_pk_mul_f32 v[44:45], v[162:163], v[44:45]
	v_pk_mul_f32 v[42:43], v[156:157], v[42:43]
	v_pk_mul_f32 v[40:41], v[158:159], v[40:41]
	v_pk_mul_f32 v[38:39], v[152:153], v[38:39]
	v_pk_mul_f32 v[36:37], v[154:155], v[36:37]
	v_pk_mul_f32 v[34:35], v[148:149], v[34:35]
	v_pk_mul_f32 v[32:33], v[150:151], v[32:33]
; __device__ __forceinline__ float row_finish(float t) { t += shx(t, 16); t += shx(t, 32); return __builtin_amdgcn_rsqf(t * (1.0f / 1024.0f) + RMS_EPS); }
; __device__ __forceinline__ f32x4 silu4(f32x4 v) { return (f32x4){silu_f(v[0]), silu_f(v[1]), silu_f(v[2]), silu_f(v[3])}; }
; __device__ __forceinline__ float sq4(f32x4 v) { return (v[0] * v[0] + v[1] * v[1]) + (v[2] * v[2] + v[3] * v[3]); }
; __device__ __forceinline__ u32x4 pack8(f32x4 a, f32x4 b) { u32x4 w; w.x = cvt_pk_bf16(a[0], a[1]); w.y = cvt_pk_bf16(a[2], a[3]); w.z = cvt_pk_bf16(b[0], b[1]); w.w = cvt_pk_bf16(b[2], b[3]); return w; }
;     __device__ __forceinline__ void operator()(const f32x4 (&acc)[2][2][4][2], const Unit& u, int wr, int wc, int fr, int fq) const {
;     ...
;             for (int m = 0; m < 4; ++m) rs[ai][m] = row_finish(rs[ai][m]);
; #pragma unroll
;         for (int ai = 0; ai < 2; ++ai)
; #pragma unroll
;             for (int m = 0; m < 4; ++m) {
;                 const int row = u.pm * BM + ai * HALF + wr * 64 + m * 16 + fr;
;                 const float rstd = rs[ai][m];
;                 f32x4 v[2][2];
; #pragma unroll
;                 for (int bj = 0; bj < 2; ++bj)
; #pragma unroll
;                     for (int n = 0; n < 2; ++n) v[bj][n] = acc[ai][bj][m][n] * rstd;
;                 if (mode == 2) {
;                     float q = (sq4(v[0][0]) + sq4(v[0][1])) + (sq4(v[1][0]) + sq4(v[1][1]));
;                     q += shx(q, 16); q += shx(q, 32);
;                     const float r2 = __builtin_amdgcn_rsqf(q * (1.0f / 64.0f) + RMS_EPS);
; #pragma unroll
;                     for (int bj = 0; bj < 2; ++bj)
; #pragma unroll
;                         for (int n = 0; n < 2; ++n) v[bj][n] = v[bj][n] * r2 * wv[bj][n];
;                 } else if (mode == 1) {
; #pragma unroll
;                     for (int bj = 0; bj < 2; ++bj)
; #pragma unroll
;                         for (int n = 0; n < 2; ++n) v[bj][n] = silu4(v[bj][n]);
;                 } else {
; #pragma unroll
;                     for (int bj = 0; bj < 2; ++bj)
; #pragma unroll
;                         for (int n = 0; n < 2; ++n) v[bj][n] = v[bj][n] * sc;
;                 }
;                 bf16_t* rowp = U + (size_t)row * 2560 + lcol;
; #pragma unroll
;                 for (int bj = 0; bj < 2; ++bj) *(u32x4*)(rowp + 32 * bj) = pack8(v[bj][0], v[bj][1]);
.LBB0_727:
	s_waitcnt lgkmcnt(0)
	v_add_f32_e32 v48, v167, v169
	v_fmamk_f32 v48, v48, 0x3a800000, v184
	v_rsq_f32_e32 v48, v48
	v_mov_b64_e32 v[50:51], s[22:23]
	v_mad_i64_i32 v[50:51], s[48:49], v166, s64, v[50:51]
	v_lshl_add_u64 v[50:51], v[112:113], 1, v[50:51]
	v_pk_mul_f32 v[30:31], v[30:31], v[48:49] op_sel_hi:[1,0]
	v_pk_mul_f32 v[28:29], v[28:29], v[48:49] op_sel_hi:[1,0]
	v_pk_mul_f32 v[26:27], v[26:27], v[48:49] op_sel_hi:[1,0]
	v_pk_mul_f32 v[24:25], v[24:25], v[48:49] op_sel_hi:[1,0]
	v_pk_mul_f32 v[22:23], v[22:23], v[48:49] op_sel_hi:[1,0]
	v_pk_mul_f32 v[20:21], v[20:21], v[48:49] op_sel_hi:[1,0]
	v_pk_mul_f32 v[18:19], v[18:19], v[48:49] op_sel_hi:[1,0]
	s_and_b64 vcc, exec, s[12:13]
	v_pk_mul_f32 v[16:17], v[16:17], v[48:49] op_sel_hi:[1,0]
	v_cvt_pk_bf16_f32 v44, v44, v45
	v_cvt_pk_bf16_f32 v45, v46, v47
	v_cvt_pk_bf16_f32 v46, v40, v41
	v_cvt_pk_bf16_f32 v47, v42, v43
	global_store_dwordx4 v[50:51], v[44:47], off sc1
	v_cvt_pk_bf16_f32 v36, v36, v37
	v_cvt_pk_bf16_f32 v37, v38, v39
	v_cvt_pk_bf16_f32 v38, v32, v33
	v_cvt_pk_bf16_f32 v39, v34, v35
	global_store_dwordx4 v[50:51], v[36:39], off offset:64 sc1
	s_cbranch_vccnz .LBB0_729
	v_mov_b32_e32 v34, v29
	v_mov_b32_e32 v35, v21
	v_mov_b32_e32 v32, v28
	v_mov_b32_e32 v33, v20
	v_pk_mul_f32 v[34:35], v[34:35], v[34:35]
	v_mov_b32_e32 v36, v31
	v_mov_b32_e32 v37, v23
	v_pk_fma_f32 v[32:33], v[32:33], v[32:33], v[34:35]
	v_mov_b32_e32 v34, v30
	v_mov_b32_e32 v35, v22
	v_pk_mul_f32 v[36:37], v[36:37], v[36:37]
	v_mov_b32_e32 v38, v27
	v_pk_fma_f32 v[34:35], v[34:35], v[34:35], v[36:37]
	v_mov_b32_e32 v36, v25
	v_mov_b32_e32 v37, v17
	v_pk_add_f32 v[32:33], v[32:33], v[34:35]
	v_mov_b32_e32 v34, v24
	v_mov_b32_e32 v35, v16
	v_pk_mul_f32 v[36:37], v[36:37], v[36:37]
	v_mov_b32_e32 v39, v19
	v_pk_fma_f32 v[34:35], v[34:35], v[34:35], v[36:37]
	v_mov_b32_e32 v36, v26
	v_mov_b32_e32 v37, v18
	v_pk_mul_f32 v[38:39], v[38:39], v[38:39]
	s_nop 0
	v_pk_fma_f32 v[36:37], v[36:37], v[36:37], v[38:39]
	s_nop 0
	v_pk_add_f32 v[34:35], v[34:35], v[36:37]
	s_nop 0
	v_pk_add_f32 v[32:33], v[32:33], v[34:35]
	s_nop 0
	v_add_f32_e32 v32, v32, v33
	v_mov_b32_e32 v33, v201
	s_nop 0
	v_lshlrev_b32_e32 v33, 2, v33
	v_xor_b32_e32 v33, 64, v33
	v_mov_b32_e32 v33, v32
	s_nop 1
	v_permlane16_swap_b32_e32 v33, v32
	s_waitcnt lgkmcnt(0)
	v_add_f32_e32 v32, v32, v33
	v_mov_b32_e32 v33, v201
	s_nop 0
	v_lshlrev_b32_e32 v33, 2, v33
	v_xor_b32_e32 v33, 0x80, v33
	v_mov_b32_e32 v33, v32
	s_nop 1
	v_permlane32_swap_b32_e32 v33, v32
	s_waitcnt lgkmcnt(0)
	v_add_f32_e32 v32, v32, v33
	v_fmamk_f32 v32, v32, 0x3c800000, v184
	v_rsq_f32_e32 v32, v32
	s_nop 0
	v_pk_mul_f32 v[28:29], v[28:29], v[32:33] op_sel_hi:[1,0]
	v_pk_mul_f32 v[30:31], v[30:31], v[32:33] op_sel_hi:[1,0]
	v_pk_mul_f32 v[24:25], v[24:25], v[32:33] op_sel_hi:[1,0]
	v_pk_mul_f32 v[26:27], v[26:27], v[32:33] op_sel_hi:[1,0]
	v_pk_mul_f32 v[20:21], v[20:21], v[32:33] op_sel_hi:[1,0]
	v_pk_mul_f32 v[22:23], v[22:23], v[32:33] op_sel_hi:[1,0]
	v_pk_mul_f32 v[16:17], v[16:17], v[32:33] op_sel_hi:[1,0]
	v_pk_mul_f32 v[18:19], v[18:19], v[32:33] op_sel_hi:[1,0]
	v_pk_mul_f32 v[30:31], v[160:161], v[30:31]
	v_pk_mul_f32 v[28:29], v[162:163], v[28:29]
	v_pk_mul_f32 v[26:27], v[156:157], v[26:27]
	v_pk_mul_f32 v[24:25], v[158:159], v[24:25]
	v_pk_mul_f32 v[22:23], v[152:153], v[22:23]
	v_pk_mul_f32 v[20:21], v[154:155], v[20:21]
	v_pk_mul_f32 v[18:19], v[148:149], v[18:19]
	v_pk_mul_f32 v[16:17], v[150:151], v[16:17]
; __device__ __forceinline__ float row_finish(float t) { t += shx(t, 16); t += shx(t, 32); return __builtin_amdgcn_rsqf(t * (1.0f / 1024.0f) + RMS_EPS); }
; __device__ __forceinline__ f32x4 silu4(f32x4 v) { return (f32x4){silu_f(v[0]), silu_f(v[1]), silu_f(v[2]), silu_f(v[3])}; }
; #define PG8_BAR __builtin_amdgcn_s_barrier()
;     __device__ __forceinline__ void operator()(const f32x4 (&acc)[2][2][4][2], const Unit& u, int wr, int wc, int fr, int fq) const {
;     ...
;             for (int m = 0; m < 4; ++m) rs[ai][m] = row_finish(rs[ai][m]);
; #pragma unroll
;         for (int ai = 0; ai < 2; ++ai)
; #pragma unroll
;             for (int m = 0; m < 4; ++m) {
;                 const int row = u.pm * BM + ai * HALF + wr * 64 + m * 16 + fr;
;                 const float rstd = rs[ai][m];
;                 f32x4 v[2][2];
; #pragma unroll
;                 for (int bj = 0; bj < 2; ++bj)
; #pragma unroll
;                     for (int n = 0; n < 2; ++n) v[bj][n] = acc[ai][bj][m][n] * rstd;
;                 if (mode == 2) {
;                     float q = (sq4(v[0][0]) + sq4(v[0][1])) + (sq4(v[1][0]) + sq4(v[1][1]));
;                     q += shx(q, 16); q += shx(q, 32);
;                     const float r2 = __builtin_amdgcn_rsqf(q * (1.0f / 64.0f) + RMS_EPS);
; #pragma unroll
;                     for (int bj = 0; bj < 2; ++bj)
; #pragma unroll
;                         for (int n = 0; n < 2; ++n) v[bj][n] = v[bj][n] * r2 * wv[bj][n];
;                 } else if (mode == 1) {
; #pragma unroll
;                     for (int bj = 0; bj < 2; ++bj)
; #pragma unroll
;                         for (int n = 0; n < 2; ++n) v[bj][n] = silu4(v[bj][n]);
;                 } else {
; #pragma unroll
;                     for (int bj = 0; bj < 2; ++bj)
; #pragma unroll
;                         for (int n = 0; n < 2; ++n) v[bj][n] = v[bj][n] * sc;
;                 }
;                 bf16_t* rowp = U + (size_t)row * 2560 + lcol;
; #pragma unroll
;                 for (int bj = 0; bj < 2; ++bj) *(u32x4*)(rowp + 32 * bj) = pack8(v[bj][0], v[bj][1]);
; template <class Epi, class Sched, bool ALIGN_EPI = false, bool SP2 = false>
; __device__ __forceinline__ void gemm_phase(PG8_LAS unsigned char* lds, const Gemm g, const Sched& S, const Epi& E, int tid_in) {
;     ...
;         cur = nxt; cA = nA; cB = nB; ++ui;
;         if constexpr (ALIGN_EPI) { if (wr == 1) PG8_BAR; }
.LBB0_729:
	s_waitcnt lgkmcnt(0)
	v_add_f32_e32 v32, v147, v165
	v_fmamk_f32 v32, v32, 0x3a800000, v184
	v_rsq_f32_e32 v32, v32
	v_mov_b64_e32 v[34:35], s[22:23]
	v_mad_i64_i32 v[34:35], s[48:49], v164, s64, v[34:35]
	v_lshl_add_u64 v[34:35], v[112:113], 1, v[34:35]
	v_pk_mul_f32 v[14:15], v[14:15], v[32:33] op_sel_hi:[1,0]
	v_pk_mul_f32 v[12:13], v[12:13], v[32:33] op_sel_hi:[1,0]
	v_pk_mul_f32 v[10:11], v[10:11], v[32:33] op_sel_hi:[1,0]
	v_pk_mul_f32 v[8:9], v[8:9], v[32:33] op_sel_hi:[1,0]
	v_pk_mul_f32 v[6:7], v[6:7], v[32:33] op_sel_hi:[1,0]
	v_pk_mul_f32 v[4:5], v[4:5], v[32:33] op_sel_hi:[1,0]
	v_pk_mul_f32 v[2:3], v[2:3], v[32:33] op_sel_hi:[1,0]
	s_and_b64 vcc, exec, s[12:13]
	v_pk_mul_f32 v[0:1], v[0:1], v[32:33] op_sel_hi:[1,0]
	v_cvt_pk_bf16_f32 v28, v28, v29
	v_cvt_pk_bf16_f32 v29, v30, v31
	v_cvt_pk_bf16_f32 v30, v24, v25
	v_cvt_pk_bf16_f32 v31, v26, v27
	global_store_dwordx4 v[34:35], v[28:31], off sc1
	v_cvt_pk_bf16_f32 v20, v20, v21
	v_cvt_pk_bf16_f32 v21, v22, v23
	v_cvt_pk_bf16_f32 v22, v16, v17
	v_cvt_pk_bf16_f32 v23, v18, v19
	global_store_dwordx4 v[34:35], v[20:23], off offset:64 sc1
	s_cbranch_vccnz .LBB0_731
	v_mov_b32_e32 v18, v13
	v_mov_b32_e32 v19, v5
	v_mov_b32_e32 v16, v12
	v_mov_b32_e32 v17, v4
	v_pk_mul_f32 v[18:19], v[18:19], v[18:19]
	v_mov_b32_e32 v20, v15
	v_mov_b32_e32 v21, v7
	v_pk_fma_f32 v[16:17], v[16:17], v[16:17], v[18:19]
	v_mov_b32_e32 v18, v14
	v_mov_b32_e32 v19, v6
	v_pk_mul_f32 v[20:21], v[20:21], v[20:21]
	v_mov_b32_e32 v22, v11
	v_pk_fma_f32 v[18:19], v[18:19], v[18:19], v[20:21]
	v_mov_b32_e32 v20, v9
	v_mov_b32_e32 v21, v1
	v_pk_add_f32 v[16:17], v[16:17], v[18:19]
	v_mov_b32_e32 v18, v8
	v_mov_b32_e32 v19, v0
	v_pk_mul_f32 v[20:21], v[20:21], v[20:21]
	v_mov_b32_e32 v23, v3
	v_pk_fma_f32 v[18:19], v[18:19], v[18:19], v[20:21]
	v_mov_b32_e32 v20, v10
	v_mov_b32_e32 v21, v2
	v_pk_mul_f32 v[22:23], v[22:23], v[22:23]
	s_nop 0
	v_pk_fma_f32 v[20:21], v[20:21], v[20:21], v[22:23]
	s_nop 0
	v_pk_add_f32 v[18:19], v[18:19], v[20:21]
	s_nop 0
	v_pk_add_f32 v[16:17], v[16:17], v[18:19]
	s_nop 0
	v_add_f32_e32 v16, v16, v17
	v_mov_b32_e32 v17, v201
	s_nop 0
	v_lshlrev_b32_e32 v17, 2, v17
	v_xor_b32_e32 v17, 64, v17
	v_mov_b32_e32 v17, v16
	s_nop 1
	v_permlane16_swap_b32_e32 v17, v16
	s_waitcnt lgkmcnt(0)
	v_add_f32_e32 v16, v16, v17
	v_mov_b32_e32 v17, v201
	s_nop 0
	v_lshlrev_b32_e32 v17, 2, v17
	v_xor_b32_e32 v17, 0x80, v17
	v_mov_b32_e32 v17, v16
	s_nop 1
	v_permlane32_swap_b32_e32 v17, v16
	s_waitcnt lgkmcnt(0)
	v_add_f32_e32 v16, v16, v17
	v_fmamk_f32 v16, v16, 0x3c800000, v184
	v_rsq_f32_e32 v16, v16
	s_nop 0
	v_pk_mul_f32 v[12:13], v[12:13], v[16:17] op_sel_hi:[1,0]
	v_pk_mul_f32 v[14:15], v[14:15], v[16:17] op_sel_hi:[1,0]
	v_pk_mul_f32 v[8:9], v[8:9], v[16:17] op_sel_hi:[1,0]
	v_pk_mul_f32 v[10:11], v[10:11], v[16:17] op_sel_hi:[1,0]
	v_pk_mul_f32 v[4:5], v[4:5], v[16:17] op_sel_hi:[1,0]
	v_pk_mul_f32 v[6:7], v[6:7], v[16:17] op_sel_hi:[1,0]
	v_pk_mul_f32 v[0:1], v[0:1], v[16:17] op_sel_hi:[1,0]
	v_pk_mul_f32 v[2:3], v[2:3], v[16:17] op_sel_hi:[1,0]
	v_pk_mul_f32 v[14:15], v[160:161], v[14:15]
	v_pk_mul_f32 v[12:13], v[162:163], v[12:13]
	v_pk_mul_f32 v[10:11], v[156:157], v[10:11]
	v_pk_mul_f32 v[8:9], v[158:159], v[8:9]
	v_pk_mul_f32 v[6:7], v[152:153], v[6:7]
	v_pk_mul_f32 v[4:5], v[154:155], v[4:5]
	v_pk_mul_f32 v[2:3], v[148:149], v[2:3]
	v_pk_mul_f32 v[0:1], v[150:151], v[0:1]
.LBB0_731:
	v_mov_b64_e32 v[16:17], s[22:23]
	v_mad_i64_i32 v[16:17], s[12:13], v146, s64, v[16:17]
	v_lshl_add_u64 v[16:17], v[112:113], 1, v[16:17]
	s_andn2_b64 vcc, exec, s[10:11]
	s_mov_b64 s[10:11], -1
	v_cvt_pk_bf16_f32 v12, v12, v13
	v_cvt_pk_bf16_f32 v13, v14, v15
	v_cvt_pk_bf16_f32 v14, v8, v9
	v_cvt_pk_bf16_f32 v15, v10, v11
	global_store_dwordx4 v[16:17], v[12:15], off sc1
	v_cvt_pk_bf16_f32 v4, v4, v5
	v_cvt_pk_bf16_f32 v5, v6, v7
	v_cvt_pk_bf16_f32 v6, v0, v1
	v_cvt_pk_bf16_f32 v7, v2, v3
	global_store_dwordx4 v[16:17], v[4:7], off offset:64 sc1
	s_cbranch_vccnz .LBB0_708
	s_andn2_b64 vcc, exec, s[20:21]
	s_cbranch_vccnz .LBB0_707
	s_barrier
	s_branch .LBB0_707

; __device__ __forceinline__ float sq4(f32x4 v) { return (v[0] * v[0] + v[1] * v[1]) + (v[2] * v[2] + v[3] * v[3]); }
; __device__ __forceinline__ u32x4 pack8(f32x4 a, f32x4 b) { u32x4 w; w.x = cvt_pk_bf16(a[0], a[1]); w.y = cvt_pk_bf16(a[2], a[3]); w.z = cvt_pk_bf16(b[0], b[1]); w.w = cvt_pk_bf16(b[2], b[3]); return w; }
;     __device__ __forceinline__ void operator()(const f32x4 (&acc)[2][2][4][2], const Unit& u, int wr, int wc, int fr, int fq) const {
;         const int col0 = u.pn * 256 + 32 * wc + 8 * fq;
; #pragma unroll
;         for (int ai = 0; ai < 2; ++ai) {
;             u32x4 bs[4][2];
; #pragma unroll
;             for (int m = 0; m < 4; ++m)
; #pragma unroll
;                 for (int bj = 0; bj < 2; ++bj) bs[m][bj] = *(const u32x4*)(xb + (size_t)(u.pm * BM + ai * HALF + wr * 64 + m * 16 + fr) * 1024 + col0 + 128 * bj);
; #pragma unroll
;             for (int m = 0; m < 4; ++m) {
;                 const int row = u.pm * BM + ai * HALF + wr * 64 + m * 16 + fr;
;                 float q = 0.f;
; #pragma unroll
;                 for (int bj = 0; bj < 2; ++bj) {
;                     const size_t off = (size_t)row * 1024 + col0 + 128 * bj; const u32x4 w = bs[m][bj];
;                     const f32x4 b0 = (f32x4){__builtin_bit_cast(float, w.x << 16), __builtin_bit_cast(float, w.x & 0xffff0000u), __builtin_bit_cast(float, w.y << 16), __builtin_bit_cast(float, w.y & 0xffff0000u)};
;                     const f32x4 b1 = (f32x4){__builtin_bit_cast(float, w.z << 16), __builtin_bit_cast(float, w.z & 0xffff0000u), __builtin_bit_cast(float, w.w << 16), __builtin_bit_cast(float, w.w & 0xffff0000u)};
;                     const f32x4 v0 = acc[ai][bj][m][0] + b0, v1 = acc[ai][bj][m][1] + b1;
;                     if (last) { __builtin_nontemporal_store(v0, (f32x4*)(out + off)); __builtin_nontemporal_store(v1, (f32x4*)(out + off + 4)); }
;                     else { q += sq4(v0) + sq4(v1); *(u32x4*)(xb + off) = pack8(v0, v1); }
;                 }
;                 if (!last) { q += shx(q, 16); q += shx(q, 32); if (fq == 0) ss[(size_t)row * 16 + u.pn * 4 + wc] = q; }
.LBB0_915:
	v_lshl_or_b32 v168, s18, 8, v188
	v_lshl_add_u32 v172, s54, 8, v186
	v_ashrrev_i32_e32 v169, 31, v168
	v_lshlrev_b64 v[202:203], 1, v[168:169]
	v_ashrrev_i32_e32 v173, 31, v172
	v_lshl_add_u64 v[170:171], s[22:23], 0, v[202:203]
	v_lshlrev_b64 v[204:205], 11, v[172:173]
	v_lshl_add_u64 v[120:121], v[170:171], 0, v[204:205]
	global_load_dwordx4 v[192:195], v[120:121], off
	global_load_dwordx4 v[196:199], v[120:121], off offset:256
	v_or_b32_e32 v182, 16, v172
	v_ashrrev_i32_e32 v183, 31, v182
	v_or_b32_e32 v178, 32, v172
	v_lshlrev_b64 v[184:185], 11, v[182:183]
	v_ashrrev_i32_e32 v179, 31, v178
	v_or_b32_e32 v174, 48, v172
	v_lshl_add_u64 v[120:121], v[170:171], 0, v[184:185]
	v_lshlrev_b64 v[180:181], 11, v[178:179]
	v_ashrrev_i32_e32 v175, 31, v174
	global_load_dwordx4 v[148:151], v[120:121], off
	global_load_dwordx4 v[144:147], v[120:121], off offset:256
	v_lshl_add_u64 v[120:121], v[170:171], 0, v[180:181]
	v_lshlrev_b64 v[176:177], 11, v[174:175]
	global_load_dwordx4 v[140:143], v[120:121], off
	global_load_dwordx4 v[136:139], v[120:121], off offset:256
	v_lshl_add_u64 v[120:121], v[170:171], 0, v[176:177]
	global_load_dwordx4 v[132:135], v[120:121], off
	s_nop 0
	global_load_dwordx4 v[120:123], v[120:121], off offset:256
	s_lshl_b32 s54, s18, 2
	s_ashr_i32 s55, s54, 31
	s_waitcnt vmcnt(0)
	v_lshlrev_b32_e32 v206, 16, v192
	v_and_b32_e32 v207, 0xffff0000, v192
	v_lshlrev_b32_e32 v192, 16, v193
	v_and_b32_e32 v193, 0xffff0000, v193
	v_lshlrev_b32_e32 v208, 16, v194
	v_and_b32_e32 v209, 0xffff0000, v194
	v_lshlrev_b32_e32 v194, 16, v195
	v_and_b32_e32 v195, 0xffff0000, v195
	v_pk_add_f32 v[130:131], v[130:131], v[192:193]
	v_pk_add_f32 v[128:129], v[128:129], v[206:207]
	v_pk_add_f32 v[192:193], v[126:127], v[194:195]
	v_pk_add_f32 v[126:127], v[124:125], v[208:209]
	v_mul_f32_e32 v124, v129, v129
	v_mul_f32_e32 v125, v131, v131
	v_fmac_f32_e32 v124, v128, v128
	v_fmac_f32_e32 v125, v130, v130
	v_add_f32_e32 v124, v124, v125
	v_mul_f32_e32 v125, v127, v127
	v_mul_f32_e32 v194, v193, v193
	v_fmac_f32_e32 v125, v126, v126
	v_fmac_f32_e32 v194, v192, v192
	v_add_f32_e32 v125, v125, v194
	v_add_f32_e32 v194, v124, v125
	v_cvt_pk_bf16_f32 v124, v128, v129
	v_lshl_add_u64 v[128:129], s[22:23], 0, v[204:205]
	v_cvt_pk_bf16_f32 v125, v130, v131
	v_cvt_pk_bf16_f32 v126, v126, v127
	v_cvt_pk_bf16_f32 v127, v192, v193
	v_lshl_add_u64 v[128:129], v[128:129], 0, v[202:203]
	global_store_dwordx4 v[128:129], v[124:127], off sc1
	v_lshlrev_b32_e32 v130, 16, v198
	v_and_b32_e32 v131, 0xffff0000, v198
	v_lshlrev_b32_e32 v124, 16, v196
	v_and_b32_e32 v125, 0xffff0000, v196
	v_lshlrev_b32_e32 v126, 16, v197
	v_and_b32_e32 v127, 0xffff0000, v197
	v_lshlrev_b32_e32 v192, 16, v199
	v_and_b32_e32 v193, 0xffff0000, v199
	v_pk_add_f32 v[118:119], v[118:119], v[126:127]
	v_pk_add_f32 v[116:117], v[116:117], v[124:125]
	v_pk_add_f32 v[124:125], v[114:115], v[192:193]
	v_pk_add_f32 v[114:115], v[112:113], v[130:131]
	v_mul_f32_e32 v112, v117, v117
	v_mul_f32_e32 v113, v119, v119
	v_fmac_f32_e32 v112, v116, v116
	v_fmac_f32_e32 v113, v118, v118
	v_add_f32_e32 v112, v112, v113
	v_mul_f32_e32 v113, v115, v115
	v_mul_f32_e32 v126, v125, v125
	v_fmac_f32_e32 v113, v114, v114
	v_fmac_f32_e32 v126, v124, v124
	v_add_f32_e32 v113, v113, v126
	v_add_f32_e32 v112, v112, v113
	v_add_f32_e32 v126, v194, v112
	v_cvt_pk_bf16_f32 v112, v116, v117
	v_cvt_pk_bf16_f32 v113, v118, v119
	v_cvt_pk_bf16_f32 v114, v114, v115
	v_cvt_pk_bf16_f32 v115, v124, v125
	global_store_dwordx4 v[128:129], v[112:115], off offset:256 sc1
	s_nop 1
	v_mov_b32_e32 v112, v201
	v_mov_b32_e32 v113, v201
	v_lshlrev_b32_e32 v112, 2, v112
	v_xor_b32_e32 v112, 64, v112
	v_mov_b32_e32 v112, v126
	s_nop 1
	v_permlane16_swap_b32_e32 v112, v126
	s_waitcnt lgkmcnt(0)
	v_add_f32_e32 v112, v126, v112
	v_lshlrev_b32_e32 v113, 2, v113
	v_xor_b32_e32 v113, 0x80, v113
	v_mov_b32_e32 v113, v112
	s_nop 1
	v_permlane32_swap_b32_e32 v113, v112
	s_and_saveexec_b64 s[56:57], s[12:13]
	s_cbranch_execz .LBB0_917
	s_waitcnt lgkmcnt(0)
	v_add_f32_e32 v114, v112, v113
	v_lshlrev_b64 v[112:113], 6, v[172:173]
	v_lshl_add_u64 v[112:113], s[24:25], 0, v[112:113]
	v_lshl_add_u64 v[112:113], s[54:55], 2, v[112:113]
	s_lshl_b32 s18, s67, 2
	v_lshl_add_u64 v[112:113], v[112:113], 0, s[18:19]
	global_store_dword v[112:113], v114, off sc1
; __device__ __forceinline__ float sq4(f32x4 v) { return (v[0] * v[0] + v[1] * v[1]) + (v[2] * v[2] + v[3] * v[3]); }
; __device__ __forceinline__ u32x4 pack8(f32x4 a, f32x4 b) { u32x4 w; w.x = cvt_pk_bf16(a[0], a[1]); w.y = cvt_pk_bf16(a[2], a[3]); w.z = cvt_pk_bf16(b[0], b[1]); w.w = cvt_pk_bf16(b[2], b[3]); return w; }
;     __device__ __forceinline__ void operator()(const f32x4 (&acc)[2][2][4][2], const Unit& u, int wr, int wc, int fr, int fq) const {
;     ...
;             for (int m = 0; m < 4; ++m) {
;                 const int row = u.pm * BM + ai * HALF + wr * 64 + m * 16 + fr;
;                 float q = 0.f;
; #pragma unroll
;                 for (int bj = 0; bj < 2; ++bj) {
;                     const size_t off = (size_t)row * 1024 + col0 + 128 * bj; const u32x4 w = bs[m][bj];
;                     const f32x4 b0 = (f32x4){__builtin_bit_cast(float, w.x << 16), __builtin_bit_cast(float, w.x & 0xffff0000u), __builtin_bit_cast(float, w.y << 16), __builtin_bit_cast(float, w.y & 0xffff0000u)};
;                     const f32x4 b1 = (f32x4){__builtin_bit_cast(float, w.z << 16), __builtin_bit_cast(float, w.z & 0xffff0000u), __builtin_bit_cast(float, w.w << 16), __builtin_bit_cast(float, w.w & 0xffff0000u)};
;                     const f32x4 v0 = acc[ai][bj][m][0] + b0, v1 = acc[ai][bj][m][1] + b1;
;                     if (last) { __builtin_nontemporal_store(v0, (f32x4*)(out + off)); __builtin_nontemporal_store(v1, (f32x4*)(out + off + 4)); }
;                     else { q += sq4(v0) + sq4(v1); *(u32x4*)(xb + off) = pack8(v0, v1); }
;                 }
;                 if (!last) { q += shx(q, 16); q += shx(q, 32); if (fq == 0) ss[(size_t)row * 16 + u.pn * 4 + wc] = q; }
.LBB0_917:
	s_or_b64 exec, exec, s[56:57]
	v_lshlrev_b32_e32 v112, 16, v148
	s_waitcnt lgkmcnt(0)
	v_and_b32_e32 v113, 0xffff0000, v148
	v_lshlrev_b32_e32 v114, 16, v149
	v_and_b32_e32 v115, 0xffff0000, v149
	v_lshlrev_b32_e32 v116, 16, v150
	v_and_b32_e32 v117, 0xffff0000, v150
	v_lshlrev_b32_e32 v118, 16, v151
	v_and_b32_e32 v119, 0xffff0000, v151
	v_pk_add_f32 v[110:111], v[110:111], v[114:115]
	v_pk_add_f32 v[108:109], v[108:109], v[112:113]
	v_pk_add_f32 v[112:113], v[106:107], v[118:119]
	v_pk_add_f32 v[106:107], v[104:105], v[116:117]
	v_mul_f32_e32 v104, v109, v109
	v_mul_f32_e32 v105, v111, v111
	v_fmac_f32_e32 v104, v108, v108
	v_fmac_f32_e32 v105, v110, v110
	v_add_f32_e32 v104, v104, v105
	v_mul_f32_e32 v105, v107, v107
	v_mul_f32_e32 v114, v113, v113
	v_fmac_f32_e32 v105, v106, v106
	v_fmac_f32_e32 v114, v112, v112
	v_add_f32_e32 v105, v105, v114
	v_add_f32_e32 v114, v104, v105
	v_cvt_pk_bf16_f32 v104, v108, v109
	v_lshl_add_u64 v[108:109], s[22:23], 0, v[184:185]
	v_cvt_pk_bf16_f32 v105, v110, v111
	v_cvt_pk_bf16_f32 v106, v106, v107
	v_cvt_pk_bf16_f32 v107, v112, v113
	v_lshl_add_u64 v[108:109], v[168:169], 1, v[108:109]
	global_store_dwordx4 v[108:109], v[104:107], off sc1
	v_lshlrev_b32_e32 v110, 16, v146
	v_and_b32_e32 v111, 0xffff0000, v146
	v_lshlrev_b32_e32 v104, 16, v144
	v_and_b32_e32 v105, 0xffff0000, v144
	v_lshlrev_b32_e32 v106, 16, v145
	v_and_b32_e32 v107, 0xffff0000, v145
	v_lshlrev_b32_e32 v112, 16, v147
	v_and_b32_e32 v113, 0xffff0000, v147
	v_pk_add_f32 v[102:103], v[102:103], v[106:107]
	v_pk_add_f32 v[100:101], v[100:101], v[104:105]
	v_pk_add_f32 v[104:105], v[98:99], v[112:113]
	v_pk_add_f32 v[98:99], v[96:97], v[110:111]
	v_mul_f32_e32 v96, v101, v101
	v_mul_f32_e32 v97, v103, v103
	v_fmac_f32_e32 v96, v100, v100
	v_fmac_f32_e32 v97, v102, v102
	v_add_f32_e32 v96, v96, v97
	v_mul_f32_e32 v97, v99, v99
	v_mul_f32_e32 v106, v105, v105
	v_fmac_f32_e32 v97, v98, v98
	v_fmac_f32_e32 v106, v104, v104
	v_add_f32_e32 v97, v97, v106
	v_add_f32_e32 v96, v96, v97
	v_add_f32_e32 v106, v114, v96
	v_cvt_pk_bf16_f32 v96, v100, v101
	v_cvt_pk_bf16_f32 v97, v102, v103
	v_cvt_pk_bf16_f32 v98, v98, v99
	v_cvt_pk_bf16_f32 v99, v104, v105
	global_store_dwordx4 v[108:109], v[96:99], off offset:256 sc1
	s_nop 1
	v_mov_b32_e32 v96, v201
	v_mov_b32_e32 v97, v201
	v_lshlrev_b32_e32 v96, 2, v96
	v_xor_b32_e32 v96, 64, v96
	v_mov_b32_e32 v96, v106
	s_nop 1
	v_permlane16_swap_b32_e32 v96, v106
	s_waitcnt lgkmcnt(0)
	v_add_f32_e32 v96, v106, v96
	v_lshlrev_b32_e32 v97, 2, v97
	v_xor_b32_e32 v97, 0x80, v97
	v_mov_b32_e32 v97, v96
	s_nop 1
	v_permlane32_swap_b32_e32 v97, v96
	s_and_saveexec_b64 s[56:57], s[12:13]
	s_cbranch_execz .LBB0_919
	s_waitcnt lgkmcnt(0)
	v_add_f32_e32 v98, v96, v97
	v_lshlrev_b64 v[96:97], 6, v[182:183]
	v_lshl_add_u64 v[96:97], s[24:25], 0, v[96:97]
	v_lshl_add_u64 v[96:97], s[54:55], 2, v[96:97]
	s_lshl_b32 s18, s67, 2
	v_lshl_add_u64 v[96:97], v[96:97], 0, s[18:19]
	global_store_dword v[96:97], v98, off sc1
.LBB0_919:
	s_or_b64 exec, exec, s[56:57]
	v_lshlrev_b32_e32 v96, 16, v140
	s_waitcnt lgkmcnt(0)
	v_and_b32_e32 v97, 0xffff0000, v140
	v_lshlrev_b32_e32 v98, 16, v141
	v_and_b32_e32 v99, 0xffff0000, v141
	v_lshlrev_b32_e32 v100, 16, v142
	v_and_b32_e32 v101, 0xffff0000, v142
	v_lshlrev_b32_e32 v102, 16, v143
	v_and_b32_e32 v103, 0xffff0000, v143
	v_pk_add_f32 v[94:95], v[94:95], v[98:99]
	v_pk_add_f32 v[92:93], v[92:93], v[96:97]
	v_pk_add_f32 v[96:97], v[90:91], v[102:103]
	v_pk_add_f32 v[90:91], v[88:89], v[100:101]
	v_mul_f32_e32 v88, v93, v93
	v_mul_f32_e32 v89, v95, v95
	v_fmac_f32_e32 v88, v92, v92
	v_fmac_f32_e32 v89, v94, v94
	v_add_f32_e32 v88, v88, v89
	v_mul_f32_e32 v89, v91, v91
	v_mul_f32_e32 v98, v97, v97
	v_fmac_f32_e32 v89, v90, v90
	v_fmac_f32_e32 v98, v96, v96
	v_add_f32_e32 v89, v89, v98
	v_add_f32_e32 v98, v88, v89
	v_cvt_pk_bf16_f32 v88, v92, v93
	v_lshl_add_u64 v[92:93], s[22:23], 0, v[180:181]
	v_cvt_pk_bf16_f32 v89, v94, v95
	v_cvt_pk_bf16_f32 v90, v90, v91
	v_cvt_pk_bf16_f32 v91, v96, v97
	v_lshl_add_u64 v[92:93], v[168:169], 1, v[92:93]
	global_store_dwordx4 v[92:93], v[88:91], off sc1
	v_lshlrev_b32_e32 v94, 16, v138
	v_and_b32_e32 v95, 0xffff0000, v138
	v_lshlrev_b32_e32 v88, 16, v136
	v_and_b32_e32 v89, 0xffff0000, v136
	v_lshlrev_b32_e32 v90, 16, v137
	v_and_b32_e32 v91, 0xffff0000, v137
	v_lshlrev_b32_e32 v96, 16, v139
	v_and_b32_e32 v97, 0xffff0000, v139
	v_pk_add_f32 v[86:87], v[86:87], v[90:91]
	v_pk_add_f32 v[84:85], v[84:85], v[88:89]
	v_pk_add_f32 v[88:89], v[82:83], v[96:97]
	v_pk_add_f32 v[82:83], v[80:81], v[94:95]
	v_mul_f32_e32 v80, v85, v85
	v_mul_f32_e32 v81, v87, v87
	v_fmac_f32_e32 v80, v84, v84
	v_fmac_f32_e32 v81, v86, v86
	v_add_f32_e32 v80, v80, v81
	v_mul_f32_e32 v81, v83, v83
	v_mul_f32_e32 v90, v89, v89
	v_fmac_f32_e32 v81, v82, v82
	v_fmac_f32_e32 v90, v88, v88
	v_add_f32_e32 v81, v81, v90
	v_add_f32_e32 v80, v80, v81
	v_add_f32_e32 v90, v98, v80
	v_cvt_pk_bf16_f32 v80, v84, v85
	v_cvt_pk_bf16_f32 v81, v86, v87
	v_cvt_pk_bf16_f32 v82, v82, v83
	v_cvt_pk_bf16_f32 v83, v88, v89
	global_store_dwordx4 v[92:93], v[80:83], off offset:256 sc1
	s_nop 1
	v_mov_b32_e32 v80, v201
	v_mov_b32_e32 v81, v201
	v_lshlrev_b32_e32 v80, 2, v80
	v_xor_b32_e32 v80, 64, v80
	v_mov_b32_e32 v80, v90
	s_nop 1
	v_permlane16_swap_b32_e32 v80, v90
	s_waitcnt lgkmcnt(0)
	v_add_f32_e32 v80, v90, v80
	v_lshlrev_b32_e32 v81, 2, v81
	v_xor_b32_e32 v81, 0x80, v81
	v_mov_b32_e32 v81, v80
	s_nop 1
	v_permlane32_swap_b32_e32 v81, v80
	s_and_saveexec_b64 s[56:57], s[12:13]
	s_cbranch_execz .LBB0_921
	s_waitcnt lgkmcnt(0)
	v_add_f32_e32 v82, v80, v81
	v_lshlrev_b64 v[80:81], 6, v[178:179]
	v_lshl_add_u64 v[80:81], s[24:25], 0, v[80:81]
	v_lshl_add_u64 v[80:81], s[54:55], 2, v[80:81]
	s_lshl_b32 s18, s67, 2
	v_lshl_add_u64 v[80:81], v[80:81], 0, s[18:19]
	global_store_dword v[80:81], v82, off sc1
; __device__ __forceinline__ float sq4(f32x4 v) { return (v[0] * v[0] + v[1] * v[1]) + (v[2] * v[2] + v[3] * v[3]); }
; __device__ __forceinline__ u32x4 pack8(f32x4 a, f32x4 b) { u32x4 w; w.x = cvt_pk_bf16(a[0], a[1]); w.y = cvt_pk_bf16(a[2], a[3]); w.z = cvt_pk_bf16(b[0], b[1]); w.w = cvt_pk_bf16(b[2], b[3]); return w; }
;     __device__ __forceinline__ void operator()(const f32x4 (&acc)[2][2][4][2], const Unit& u, int wr, int wc, int fr, int fq) const {
;     ...
;         for (int ai = 0; ai < 2; ++ai) {
;             u32x4 bs[4][2];
; #pragma unroll
;             for (int m = 0; m < 4; ++m)
; #pragma unroll
;                 for (int bj = 0; bj < 2; ++bj) bs[m][bj] = *(const u32x4*)(xb + (size_t)(u.pm * BM + ai * HALF + wr * 64 + m * 16 + fr) * 1024 + col0 + 128 * bj);
; #pragma unroll
;             for (int m = 0; m < 4; ++m) {
;                 const int row = u.pm * BM + ai * HALF + wr * 64 + m * 16 + fr;
;                 float q = 0.f;
; #pragma unroll
;                 for (int bj = 0; bj < 2; ++bj) {
;                     const size_t off = (size_t)row * 1024 + col0 + 128 * bj; const u32x4 w = bs[m][bj];
;                     const f32x4 b0 = (f32x4){__builtin_bit_cast(float, w.x << 16), __builtin_bit_cast(float, w.x & 0xffff0000u), __builtin_bit_cast(float, w.y << 16), __builtin_bit_cast(float, w.y & 0xffff0000u)};
;                     const f32x4 b1 = (f32x4){__builtin_bit_cast(float, w.z << 16), __builtin_bit_cast(float, w.z & 0xffff0000u), __builtin_bit_cast(float, w.w << 16), __builtin_bit_cast(float, w.w & 0xffff0000u)};
;                     const f32x4 v0 = acc[ai][bj][m][0] + b0, v1 = acc[ai][bj][m][1] + b1;
;                     if (last) { __builtin_nontemporal_store(v0, (f32x4*)(out + off)); __builtin_nontemporal_store(v1, (f32x4*)(out + off + 4)); }
;                     else { q += sq4(v0) + sq4(v1); *(u32x4*)(xb + off) = pack8(v0, v1); }
;                 }
;                 if (!last) { q += shx(q, 16); q += shx(q, 32); if (fq == 0) ss[(size_t)row * 16 + u.pn * 4 + wc] = q; }
.LBB0_921:
	s_or_b64 exec, exec, s[56:57]
	v_lshlrev_b32_e32 v80, 16, v132
	s_waitcnt lgkmcnt(0)
	v_and_b32_e32 v81, 0xffff0000, v132
	v_lshlrev_b32_e32 v82, 16, v133
	v_and_b32_e32 v83, 0xffff0000, v133
	v_lshlrev_b32_e32 v84, 16, v134
	v_and_b32_e32 v85, 0xffff0000, v134
	v_lshlrev_b32_e32 v86, 16, v135
	v_and_b32_e32 v87, 0xffff0000, v135
	v_pk_add_f32 v[78:79], v[78:79], v[82:83]
	v_pk_add_f32 v[76:77], v[76:77], v[80:81]
	v_pk_add_f32 v[80:81], v[74:75], v[86:87]
	v_pk_add_f32 v[74:75], v[72:73], v[84:85]
	v_mul_f32_e32 v72, v77, v77
	v_mul_f32_e32 v73, v79, v79
	v_fmac_f32_e32 v72, v76, v76
	v_fmac_f32_e32 v73, v78, v78
	v_add_f32_e32 v72, v72, v73
	v_mul_f32_e32 v73, v75, v75
	v_mul_f32_e32 v82, v81, v81
	v_fmac_f32_e32 v73, v74, v74
	v_fmac_f32_e32 v82, v80, v80
	v_add_f32_e32 v73, v73, v82
	v_add_f32_e32 v82, v72, v73
	v_cvt_pk_bf16_f32 v72, v76, v77
	v_lshl_add_u64 v[76:77], s[22:23], 0, v[176:177]
	v_cvt_pk_bf16_f32 v73, v78, v79
	v_cvt_pk_bf16_f32 v74, v74, v75
	v_cvt_pk_bf16_f32 v75, v80, v81
	v_lshl_add_u64 v[76:77], v[168:169], 1, v[76:77]
	global_store_dwordx4 v[76:77], v[72:75], off sc1
	v_lshlrev_b32_e32 v78, 16, v122
	v_and_b32_e32 v79, 0xffff0000, v122
	v_lshlrev_b32_e32 v72, 16, v120
	v_and_b32_e32 v73, 0xffff0000, v120
	v_lshlrev_b32_e32 v74, 16, v121
	v_and_b32_e32 v75, 0xffff0000, v121
	v_lshlrev_b32_e32 v80, 16, v123
	v_and_b32_e32 v81, 0xffff0000, v123
	v_pk_add_f32 v[70:71], v[70:71], v[74:75]
	v_pk_add_f32 v[68:69], v[68:69], v[72:73]
	v_pk_add_f32 v[72:73], v[66:67], v[80:81]
	v_pk_add_f32 v[66:67], v[64:65], v[78:79]
	v_mul_f32_e32 v64, v69, v69
	v_mul_f32_e32 v65, v71, v71
	v_fmac_f32_e32 v64, v68, v68
	v_fmac_f32_e32 v65, v70, v70
	v_add_f32_e32 v64, v64, v65
	v_mul_f32_e32 v65, v67, v67
	v_mul_f32_e32 v74, v73, v73
	v_fmac_f32_e32 v65, v66, v66
	v_fmac_f32_e32 v74, v72, v72
	v_add_f32_e32 v65, v65, v74
	v_add_f32_e32 v64, v64, v65
	v_add_f32_e32 v74, v82, v64
	v_cvt_pk_bf16_f32 v64, v68, v69
	v_cvt_pk_bf16_f32 v65, v70, v71
	v_cvt_pk_bf16_f32 v66, v66, v67
	v_cvt_pk_bf16_f32 v67, v72, v73
	global_store_dwordx4 v[76:77], v[64:67], off offset:256 sc1
	s_nop 1
	v_mov_b32_e32 v64, v201
	v_mov_b32_e32 v65, v201
	v_lshlrev_b32_e32 v64, 2, v64
	v_xor_b32_e32 v64, 64, v64
	v_mov_b32_e32 v64, v74
	s_nop 1
	v_permlane16_swap_b32_e32 v64, v74
	s_waitcnt lgkmcnt(0)
	v_add_f32_e32 v64, v74, v64
	v_lshlrev_b32_e32 v65, 2, v65
	v_xor_b32_e32 v65, 0x80, v65
	v_mov_b32_e32 v65, v64
	s_nop 1
	v_permlane32_swap_b32_e32 v65, v64
	s_and_saveexec_b64 s[56:57], s[12:13]
	s_cbranch_execz .LBB0_923
	s_waitcnt lgkmcnt(0)
	v_add_f32_e32 v66, v64, v65
	v_lshlrev_b64 v[64:65], 6, v[174:175]
	v_lshl_add_u64 v[64:65], s[24:25], 0, v[64:65]
	v_lshl_add_u64 v[64:65], s[54:55], 2, v[64:65]
	s_lshl_b32 s18, s67, 2
	v_lshl_add_u64 v[64:65], v[64:65], 0, s[18:19]
	global_store_dword v[64:65], v66, off sc1
.LBB0_923:
	s_or_b64 exec, exec, s[56:57]
	v_add_u32_e32 v100, 0x80, v172
	v_ashrrev_i32_e32 v101, 31, v100
	v_lshlrev_b64 v[110:111], 11, v[100:101]
	s_waitcnt lgkmcnt(0)
	v_lshl_add_u64 v[64:65], v[170:171], 0, v[110:111]
	global_load_dwordx4 v[102:105], v[64:65], off
	global_load_dwordx4 v[106:109], v[64:65], off offset:256
	v_add_u32_e32 v96, 0x90, v172
	v_ashrrev_i32_e32 v97, 31, v96
	v_add_u32_e32 v92, 0xa0, v172
	v_lshlrev_b64 v[98:99], 11, v[96:97]
	v_ashrrev_i32_e32 v93, 31, v92
	v_add_u32_e32 v88, 0xb0, v172
	v_lshl_add_u64 v[64:65], v[170:171], 0, v[98:99]
	v_lshlrev_b64 v[94:95], 11, v[92:93]
	v_ashrrev_i32_e32 v89, 31, v88
	global_load_dwordx4 v[84:87], v[64:65], off
	global_load_dwordx4 v[80:83], v[64:65], off offset:256
	v_lshl_add_u64 v[64:65], v[170:171], 0, v[94:95]
	v_lshlrev_b64 v[90:91], 11, v[88:89]
	global_load_dwordx4 v[76:79], v[64:65], off
	global_load_dwordx4 v[72:75], v[64:65], off offset:256
	v_lshl_add_u64 v[64:65], v[170:171], 0, v[90:91]
	global_load_dwordx4 v[68:71], v[64:65], off
	s_nop 0
	global_load_dwordx4 v[64:67], v[64:65], off offset:256
	s_waitcnt vmcnt(7)
	v_lshlrev_b32_e32 v112, 16, v102
	v_and_b32_e32 v113, 0xffff0000, v102
	v_lshlrev_b32_e32 v102, 16, v103
	v_and_b32_e32 v103, 0xffff0000, v103
	v_lshlrev_b32_e32 v114, 16, v104
	v_and_b32_e32 v115, 0xffff0000, v104
	v_lshlrev_b32_e32 v104, 16, v105
	v_and_b32_e32 v105, 0xffff0000, v105
	v_pk_add_f32 v[62:63], v[62:63], v[102:103]
	v_pk_add_f32 v[60:61], v[60:61], v[112:113]
	v_pk_add_f32 v[102:103], v[58:59], v[104:105]
	v_pk_add_f32 v[58:59], v[56:57], v[114:115]
	v_mul_f32_e32 v56, v61, v61
	v_mul_f32_e32 v57, v63, v63
	v_fmac_f32_e32 v56, v60, v60
	v_fmac_f32_e32 v57, v62, v62
	v_add_f32_e32 v56, v56, v57
	v_mul_f32_e32 v57, v59, v59
	v_mul_f32_e32 v104, v103, v103
	v_fmac_f32_e32 v57, v58, v58
	v_fmac_f32_e32 v104, v102, v102
	v_add_f32_e32 v57, v57, v104
	v_add_f32_e32 v104, v56, v57
	v_cvt_pk_bf16_f32 v56, v60, v61
	v_lshl_add_u64 v[60:61], s[22:23], 0, v[110:111]
	v_cvt_pk_bf16_f32 v57, v62, v63
	v_cvt_pk_bf16_f32 v58, v58, v59
	v_cvt_pk_bf16_f32 v59, v102, v103
	v_lshl_add_u64 v[60:61], v[168:169], 1, v[60:61]
	global_store_dwordx4 v[60:61], v[56:59], off sc1
	s_waitcnt vmcnt(7)
	v_lshlrev_b32_e32 v62, 16, v108
	v_and_b32_e32 v63, 0xffff0000, v108
	v_lshlrev_b32_e32 v56, 16, v106
	v_and_b32_e32 v57, 0xffff0000, v106
	v_lshlrev_b32_e32 v58, 16, v107
	v_and_b32_e32 v59, 0xffff0000, v107
	v_lshlrev_b32_e32 v102, 16, v109
	v_and_b32_e32 v103, 0xffff0000, v109
	v_pk_add_f32 v[54:55], v[54:55], v[58:59]
	v_pk_add_f32 v[52:53], v[52:53], v[56:57]
	v_pk_add_f32 v[56:57], v[50:51], v[102:103]
	v_pk_add_f32 v[50:51], v[48:49], v[62:63]
	v_mul_f32_e32 v48, v53, v53
	v_mul_f32_e32 v49, v55, v55
	v_fmac_f32_e32 v48, v52, v52
	v_fmac_f32_e32 v49, v54, v54
	v_add_f32_e32 v48, v48, v49
	v_mul_f32_e32 v49, v51, v51
	v_mul_f32_e32 v58, v57, v57
	v_fmac_f32_e32 v49, v50, v50
	v_fmac_f32_e32 v58, v56, v56
	v_add_f32_e32 v49, v49, v58
	v_add_f32_e32 v48, v48, v49
	v_add_f32_e32 v58, v104, v48
	v_cvt_pk_bf16_f32 v48, v52, v53
	v_cvt_pk_bf16_f32 v49, v54, v55
	v_cvt_pk_bf16_f32 v50, v50, v51
	v_cvt_pk_bf16_f32 v51, v56, v57
	global_store_dwordx4 v[60:61], v[48:51], off offset:256 sc1
	s_nop 1
	v_mov_b32_e32 v48, v201
	v_mov_b32_e32 v49, v201
	v_lshlrev_b32_e32 v48, 2, v48
	v_xor_b32_e32 v48, 64, v48
	v_mov_b32_e32 v48, v58
	s_nop 1
	v_permlane16_swap_b32_e32 v48, v58
	s_waitcnt lgkmcnt(0)
	v_add_f32_e32 v48, v58, v48
	v_lshlrev_b32_e32 v49, 2, v49
	v_xor_b32_e32 v49, 0x80, v49
	v_mov_b32_e32 v49, v48
	s_nop 1
	v_permlane32_swap_b32_e32 v49, v48
	s_and_saveexec_b64 s[56:57], s[12:13]
	s_cbranch_execz .LBB0_925
	s_waitcnt lgkmcnt(0)
	v_add_f32_e32 v50, v48, v49
	v_lshlrev_b64 v[48:49], 6, v[100:101]
	v_lshl_add_u64 v[48:49], s[24:25], 0, v[48:49]
	v_lshl_add_u64 v[48:49], s[54:55], 2, v[48:49]
	s_lshl_b32 s18, s67, 2
	v_lshl_add_u64 v[48:49], v[48:49], 0, s[18:19]
	global_store_dword v[48:49], v50, off sc1
; __device__ __forceinline__ float sq4(f32x4 v) { return (v[0] * v[0] + v[1] * v[1]) + (v[2] * v[2] + v[3] * v[3]); }
; __device__ __forceinline__ u32x4 pack8(f32x4 a, f32x4 b) { u32x4 w; w.x = cvt_pk_bf16(a[0], a[1]); w.y = cvt_pk_bf16(a[2], a[3]); w.z = cvt_pk_bf16(b[0], b[1]); w.w = cvt_pk_bf16(b[2], b[3]); return w; }
;     __device__ __forceinline__ void operator()(const f32x4 (&acc)[2][2][4][2], const Unit& u, int wr, int wc, int fr, int fq) const {
;     ...
;             for (int m = 0; m < 4; ++m) {
;                 const int row = u.pm * BM + ai * HALF + wr * 64 + m * 16 + fr;
;                 float q = 0.f;
; #pragma unroll
;                 for (int bj = 0; bj < 2; ++bj) {
;                     const size_t off = (size_t)row * 1024 + col0 + 128 * bj; const u32x4 w = bs[m][bj];
;                     const f32x4 b0 = (f32x4){__builtin_bit_cast(float, w.x << 16), __builtin_bit_cast(float, w.x & 0xffff0000u), __builtin_bit_cast(float, w.y << 16), __builtin_bit_cast(float, w.y & 0xffff0000u)};
;                     const f32x4 b1 = (f32x4){__builtin_bit_cast(float, w.z << 16), __builtin_bit_cast(float, w.z & 0xffff0000u), __builtin_bit_cast(float, w.w << 16), __builtin_bit_cast(float, w.w & 0xffff0000u)};
;                     const f32x4 v0 = acc[ai][bj][m][0] + b0, v1 = acc[ai][bj][m][1] + b1;
;                     if (last) { __builtin_nontemporal_store(v0, (f32x4*)(out + off)); __builtin_nontemporal_store(v1, (f32x4*)(out + off + 4)); }
;                     else { q += sq4(v0) + sq4(v1); *(u32x4*)(xb + off) = pack8(v0, v1); }
;                 }
;                 if (!last) { q += shx(q, 16); q += shx(q, 32); if (fq == 0) ss[(size_t)row * 16 + u.pn * 4 + wc] = q; }
.LBB0_925:
	s_or_b64 exec, exec, s[56:57]
	s_waitcnt vmcnt(7)
	v_lshlrev_b32_e32 v48, 16, v84
	s_waitcnt lgkmcnt(0)
	v_and_b32_e32 v49, 0xffff0000, v84
	v_lshlrev_b32_e32 v50, 16, v85
	v_and_b32_e32 v51, 0xffff0000, v85
	v_lshlrev_b32_e32 v52, 16, v86
	v_and_b32_e32 v53, 0xffff0000, v86
	v_lshlrev_b32_e32 v54, 16, v87
	v_and_b32_e32 v55, 0xffff0000, v87
	v_pk_add_f32 v[46:47], v[46:47], v[50:51]
	v_pk_add_f32 v[44:45], v[44:45], v[48:49]
	v_pk_add_f32 v[48:49], v[42:43], v[54:55]
	v_pk_add_f32 v[42:43], v[40:41], v[52:53]
	v_mul_f32_e32 v40, v45, v45
	v_mul_f32_e32 v41, v47, v47
	v_fmac_f32_e32 v40, v44, v44
	v_fmac_f32_e32 v41, v46, v46
	v_add_f32_e32 v40, v40, v41
	v_mul_f32_e32 v41, v43, v43
	v_mul_f32_e32 v50, v49, v49
	v_fmac_f32_e32 v41, v42, v42
	v_fmac_f32_e32 v50, v48, v48
	v_add_f32_e32 v41, v41, v50
	v_add_f32_e32 v50, v40, v41
	v_cvt_pk_bf16_f32 v40, v44, v45
	v_lshl_add_u64 v[44:45], s[22:23], 0, v[98:99]
	v_cvt_pk_bf16_f32 v41, v46, v47
	v_cvt_pk_bf16_f32 v42, v42, v43
	v_cvt_pk_bf16_f32 v43, v48, v49
	v_lshl_add_u64 v[44:45], v[168:169], 1, v[44:45]
	global_store_dwordx4 v[44:45], v[40:43], off sc1
	s_waitcnt vmcnt(7)
	v_lshlrev_b32_e32 v46, 16, v82
	v_and_b32_e32 v47, 0xffff0000, v82
	v_lshlrev_b32_e32 v40, 16, v80
	v_and_b32_e32 v41, 0xffff0000, v80
	v_lshlrev_b32_e32 v42, 16, v81
	v_and_b32_e32 v43, 0xffff0000, v81
	v_lshlrev_b32_e32 v48, 16, v83
	v_and_b32_e32 v49, 0xffff0000, v83
	v_pk_add_f32 v[38:39], v[38:39], v[42:43]
	v_pk_add_f32 v[36:37], v[36:37], v[40:41]
	v_pk_add_f32 v[40:41], v[34:35], v[48:49]
	v_pk_add_f32 v[34:35], v[32:33], v[46:47]
	v_mul_f32_e32 v32, v37, v37
	v_mul_f32_e32 v33, v39, v39
	v_fmac_f32_e32 v32, v36, v36
	v_fmac_f32_e32 v33, v38, v38
	v_add_f32_e32 v32, v32, v33
	v_mul_f32_e32 v33, v35, v35
	v_mul_f32_e32 v42, v41, v41
	v_fmac_f32_e32 v33, v34, v34
	v_fmac_f32_e32 v42, v40, v40
	v_add_f32_e32 v33, v33, v42
	v_add_f32_e32 v32, v32, v33
	v_add_f32_e32 v42, v50, v32
	v_cvt_pk_bf16_f32 v32, v36, v37
	v_cvt_pk_bf16_f32 v33, v38, v39
	v_cvt_pk_bf16_f32 v34, v34, v35
	v_cvt_pk_bf16_f32 v35, v40, v41
	global_store_dwordx4 v[44:45], v[32:35], off offset:256 sc1
	s_nop 1
	v_mov_b32_e32 v32, v201
	v_mov_b32_e32 v33, v201
	v_lshlrev_b32_e32 v32, 2, v32
	v_xor_b32_e32 v32, 64, v32
	v_mov_b32_e32 v32, v42
	s_nop 1
	v_permlane16_swap_b32_e32 v32, v42
	s_waitcnt lgkmcnt(0)
	v_add_f32_e32 v32, v42, v32
	v_lshlrev_b32_e32 v33, 2, v33
	v_xor_b32_e32 v33, 0x80, v33
	v_mov_b32_e32 v33, v32
	s_nop 1
	v_permlane32_swap_b32_e32 v33, v32
	s_and_saveexec_b64 s[56:57], s[12:13]
	s_cbranch_execz .LBB0_927
	s_waitcnt lgkmcnt(0)
	v_add_f32_e32 v34, v32, v33
	v_lshlrev_b64 v[32:33], 6, v[96:97]
	v_lshl_add_u64 v[32:33], s[24:25], 0, v[32:33]
	v_lshl_add_u64 v[32:33], s[54:55], 2, v[32:33]
	s_lshl_b32 s18, s67, 2
	v_lshl_add_u64 v[32:33], v[32:33], 0, s[18:19]
	global_store_dword v[32:33], v34, off sc1
; __device__ __forceinline__ float sq4(f32x4 v) { return (v[0] * v[0] + v[1] * v[1]) + (v[2] * v[2] + v[3] * v[3]); }
; __device__ __forceinline__ u32x4 pack8(f32x4 a, f32x4 b) { u32x4 w; w.x = cvt_pk_bf16(a[0], a[1]); w.y = cvt_pk_bf16(a[2], a[3]); w.z = cvt_pk_bf16(b[0], b[1]); w.w = cvt_pk_bf16(b[2], b[3]); return w; }
;     __device__ __forceinline__ void operator()(const f32x4 (&acc)[2][2][4][2], const Unit& u, int wr, int wc, int fr, int fq) const {
;     ...
;             for (int m = 0; m < 4; ++m) {
;                 const int row = u.pm * BM + ai * HALF + wr * 64 + m * 16 + fr;
;                 float q = 0.f;
; #pragma unroll
;                 for (int bj = 0; bj < 2; ++bj) {
;                     const size_t off = (size_t)row * 1024 + col0 + 128 * bj; const u32x4 w = bs[m][bj];
;                     const f32x4 b0 = (f32x4){__builtin_bit_cast(float, w.x << 16), __builtin_bit_cast(float, w.x & 0xffff0000u), __builtin_bit_cast(float, w.y << 16), __builtin_bit_cast(float, w.y & 0xffff0000u)};
;                     const f32x4 b1 = (f32x4){__builtin_bit_cast(float, w.z << 16), __builtin_bit_cast(float, w.z & 0xffff0000u), __builtin_bit_cast(float, w.w << 16), __builtin_bit_cast(float, w.w & 0xffff0000u)};
;                     const f32x4 v0 = acc[ai][bj][m][0] + b0, v1 = acc[ai][bj][m][1] + b1;
;                     if (last) { __builtin_nontemporal_store(v0, (f32x4*)(out + off)); __builtin_nontemporal_store(v1, (f32x4*)(out + off + 4)); }
;                     else { q += sq4(v0) + sq4(v1); *(u32x4*)(xb + off) = pack8(v0, v1); }
;                 }
;                 if (!last) { q += shx(q, 16); q += shx(q, 32); if (fq == 0) ss[(size_t)row * 16 + u.pn * 4 + wc] = q; }
.LBB0_927:
	s_or_b64 exec, exec, s[56:57]
	s_waitcnt vmcnt(7)
	v_lshlrev_b32_e32 v32, 16, v76
	s_waitcnt lgkmcnt(0)
	v_and_b32_e32 v33, 0xffff0000, v76
	v_lshlrev_b32_e32 v34, 16, v77
	v_and_b32_e32 v35, 0xffff0000, v77
	v_lshlrev_b32_e32 v36, 16, v78
	v_and_b32_e32 v37, 0xffff0000, v78
	v_lshlrev_b32_e32 v38, 16, v79
	v_and_b32_e32 v39, 0xffff0000, v79
	v_pk_add_f32 v[30:31], v[30:31], v[34:35]
	v_pk_add_f32 v[28:29], v[28:29], v[32:33]
	v_pk_add_f32 v[32:33], v[26:27], v[38:39]
	v_pk_add_f32 v[26:27], v[24:25], v[36:37]
	v_mul_f32_e32 v24, v29, v29
	v_mul_f32_e32 v25, v31, v31
	v_fmac_f32_e32 v24, v28, v28
	v_fmac_f32_e32 v25, v30, v30
	v_add_f32_e32 v24, v24, v25
	v_mul_f32_e32 v25, v27, v27
	v_mul_f32_e32 v34, v33, v33
	v_fmac_f32_e32 v25, v26, v26
	v_fmac_f32_e32 v34, v32, v32
	v_add_f32_e32 v25, v25, v34
	v_add_f32_e32 v34, v24, v25
	v_cvt_pk_bf16_f32 v24, v28, v29
	v_lshl_add_u64 v[28:29], s[22:23], 0, v[94:95]
	v_cvt_pk_bf16_f32 v25, v30, v31
	v_cvt_pk_bf16_f32 v26, v26, v27
	v_cvt_pk_bf16_f32 v27, v32, v33
	v_lshl_add_u64 v[28:29], v[168:169], 1, v[28:29]
	global_store_dwordx4 v[28:29], v[24:27], off sc1
	s_waitcnt vmcnt(7)
	v_lshlrev_b32_e32 v30, 16, v74
	v_and_b32_e32 v31, 0xffff0000, v74
	v_lshlrev_b32_e32 v24, 16, v72
	v_and_b32_e32 v25, 0xffff0000, v72
	v_lshlrev_b32_e32 v26, 16, v73
	v_and_b32_e32 v27, 0xffff0000, v73
	v_lshlrev_b32_e32 v32, 16, v75
	v_and_b32_e32 v33, 0xffff0000, v75
	v_pk_add_f32 v[22:23], v[22:23], v[26:27]
	v_pk_add_f32 v[20:21], v[20:21], v[24:25]
	v_pk_add_f32 v[24:25], v[18:19], v[32:33]
	v_pk_add_f32 v[18:19], v[16:17], v[30:31]
	v_mul_f32_e32 v16, v21, v21
	v_mul_f32_e32 v17, v23, v23
	v_fmac_f32_e32 v16, v20, v20
	v_fmac_f32_e32 v17, v22, v22
	v_add_f32_e32 v16, v16, v17
	v_mul_f32_e32 v17, v19, v19
	v_mul_f32_e32 v26, v25, v25
	v_fmac_f32_e32 v17, v18, v18
	v_fmac_f32_e32 v26, v24, v24
	v_add_f32_e32 v17, v17, v26
	v_add_f32_e32 v16, v16, v17
	v_add_f32_e32 v26, v34, v16
	v_cvt_pk_bf16_f32 v16, v20, v21
	v_cvt_pk_bf16_f32 v17, v22, v23
	v_cvt_pk_bf16_f32 v18, v18, v19
	v_cvt_pk_bf16_f32 v19, v24, v25
	global_store_dwordx4 v[28:29], v[16:19], off offset:256 sc1
	s_nop 1
	v_mov_b32_e32 v16, v201
	v_mov_b32_e32 v17, v201
	v_lshlrev_b32_e32 v16, 2, v16
	v_xor_b32_e32 v16, 64, v16
	v_mov_b32_e32 v16, v26
	s_nop 1
	v_permlane16_swap_b32_e32 v16, v26
	s_waitcnt lgkmcnt(0)
	v_add_f32_e32 v16, v26, v16
	v_lshlrev_b32_e32 v17, 2, v17
	v_xor_b32_e32 v17, 0x80, v17
	v_mov_b32_e32 v17, v16
	s_nop 1
	v_permlane32_swap_b32_e32 v17, v16
	s_and_saveexec_b64 s[56:57], s[12:13]
	s_cbranch_execz .LBB0_929
	s_waitcnt lgkmcnt(0)
	v_add_f32_e32 v18, v16, v17
	v_lshlrev_b64 v[16:17], 6, v[92:93]
	v_lshl_add_u64 v[16:17], s[24:25], 0, v[16:17]
	v_lshl_add_u64 v[16:17], s[54:55], 2, v[16:17]
	s_lshl_b32 s18, s67, 2
	v_lshl_add_u64 v[16:17], v[16:17], 0, s[18:19]
	global_store_dword v[16:17], v18, off sc1
.LBB0_929:
	s_or_b64 exec, exec, s[56:57]
	s_waitcnt vmcnt(7)
	v_lshlrev_b32_e32 v16, 16, v68
	s_waitcnt lgkmcnt(0)
	v_and_b32_e32 v17, 0xffff0000, v68
	v_lshlrev_b32_e32 v18, 16, v69
	v_and_b32_e32 v19, 0xffff0000, v69
	v_lshlrev_b32_e32 v20, 16, v70
	v_and_b32_e32 v21, 0xffff0000, v70
	v_lshlrev_b32_e32 v22, 16, v71
	v_and_b32_e32 v23, 0xffff0000, v71
	v_pk_add_f32 v[14:15], v[14:15], v[18:19]
	v_pk_add_f32 v[12:13], v[12:13], v[16:17]
	v_pk_add_f32 v[16:17], v[10:11], v[22:23]
	v_pk_add_f32 v[10:11], v[8:9], v[20:21]
	v_mul_f32_e32 v8, v13, v13
	v_mul_f32_e32 v9, v15, v15
	v_fmac_f32_e32 v8, v12, v12
	v_fmac_f32_e32 v9, v14, v14
	v_add_f32_e32 v8, v8, v9
	v_mul_f32_e32 v9, v11, v11
	v_mul_f32_e32 v18, v17, v17
	v_fmac_f32_e32 v9, v10, v10
	v_fmac_f32_e32 v18, v16, v16
	v_add_f32_e32 v9, v9, v18
	v_add_f32_e32 v18, v8, v9
	v_cvt_pk_bf16_f32 v8, v12, v13
	v_lshl_add_u64 v[12:13], s[22:23], 0, v[90:91]
	v_cvt_pk_bf16_f32 v9, v14, v15
	v_cvt_pk_bf16_f32 v10, v10, v11
	v_cvt_pk_bf16_f32 v11, v16, v17
	v_lshl_add_u64 v[12:13], v[168:169], 1, v[12:13]
	global_store_dwordx4 v[12:13], v[8:11], off sc1
	s_waitcnt vmcnt(7)
	v_lshlrev_b32_e32 v14, 16, v66
	v_and_b32_e32 v15, 0xffff0000, v66
	v_lshlrev_b32_e32 v8, 16, v64
	v_and_b32_e32 v9, 0xffff0000, v64
	v_lshlrev_b32_e32 v10, 16, v65
	v_and_b32_e32 v11, 0xffff0000, v65
	v_lshlrev_b32_e32 v16, 16, v67
	v_and_b32_e32 v17, 0xffff0000, v67
	v_pk_add_f32 v[6:7], v[6:7], v[10:11]
	v_pk_add_f32 v[4:5], v[4:5], v[8:9]
	v_pk_add_f32 v[8:9], v[2:3], v[16:17]
	v_pk_add_f32 v[2:3], v[0:1], v[14:15]
	v_mul_f32_e32 v0, v5, v5
	v_mul_f32_e32 v1, v7, v7
	v_fmac_f32_e32 v0, v4, v4
	v_fmac_f32_e32 v1, v6, v6
	v_add_f32_e32 v0, v0, v1
	v_mul_f32_e32 v1, v3, v3
	v_mul_f32_e32 v10, v9, v9
	v_fmac_f32_e32 v1, v2, v2
	v_fmac_f32_e32 v10, v8, v8
	v_add_f32_e32 v1, v1, v10
	v_add_f32_e32 v0, v0, v1
	v_add_f32_e32 v10, v18, v0
	v_cvt_pk_bf16_f32 v0, v4, v5
	v_cvt_pk_bf16_f32 v1, v6, v7
	v_cvt_pk_bf16_f32 v2, v2, v3
	v_cvt_pk_bf16_f32 v3, v8, v9
	global_store_dwordx4 v[12:13], v[0:3], off offset:256 sc1
	s_nop 1
	v_mov_b32_e32 v0, v201
	v_mov_b32_e32 v1, v201
	v_lshlrev_b32_e32 v0, 2, v0
	v_xor_b32_e32 v0, 64, v0
	v_mov_b32_e32 v0, v10
	s_nop 1
	v_permlane16_swap_b32_e32 v0, v10
	s_waitcnt lgkmcnt(0)
	v_add_f32_e32 v0, v10, v0
	v_lshlrev_b32_e32 v1, 2, v1
	v_xor_b32_e32 v1, 0x80, v1
	v_mov_b32_e32 v1, v0
	s_nop 1
	v_permlane32_swap_b32_e32 v1, v0
	s_and_saveexec_b64 s[56:57], s[12:13]
	s_cbranch_execz .LBB0_931
	s_waitcnt lgkmcnt(0)
	v_add_f32_e32 v2, v0, v1
	v_lshlrev_b64 v[0:1], 6, v[88:89]
	v_lshl_add_u64 v[0:1], s[24:25], 0, v[0:1]
	v_lshl_add_u64 v[0:1], s[54:55], 2, v[0:1]
	s_lshl_b32 s18, s67, 2
	v_lshl_add_u64 v[0:1], v[0:1], 0, s[18:19]
	global_store_dword v[0:1], v2, off sc1

; __device__ __forceinline__ float row_part(const float* ss, int row, int fq) { const f32x4 a = ((const f32x4*)(ss + (size_t)row * 16))[fq]; return (a[0] + a[1]) + (a[2] + a[3]); }
; __device__ __forceinline__ float row_finish(float t) { t += shx(t, 16); t += shx(t, 32); return __builtin_amdgcn_rsqf(t * (1.0f / 1024.0f) + RMS_EPS); }
;     __device__ __forceinline__ void operator()(const f32x4 (&acc)[2][2][4][2], const Unit& u, int wr, int wc, int fr, int fq) const {
;     ...
;         for (int ai = 0; ai < 2; ++ai)
; #pragma unroll
;             for (int m = 0; m < 4; ++m) rs[ai][m] = row_part(ss, u.pm * BM + ai * HALF + wr * 64 + m * 16 + fr, fq);
; #pragma unroll
;         for (int ai = 0; ai < 2; ++ai)
; #pragma unroll
;             for (int m = 0; m < 4; ++m) rs[ai][m] = row_finish(rs[ai][m]);
.LBB0_999:
	v_lshl_add_u32 v168, s48, 8, v155
	v_ashrrev_i32_e32 v169, 31, v168
	v_lshlrev_b64 v[146:147], 6, v[168:169]
	v_lshl_add_u64 v[146:147], v[136:137], 0, v[146:147]
	ds_read_b128 v[146:149], v239
	v_or_b32_e32 v164, 16, v168
	v_ashrrev_i32_e32 v165, 31, v164
	v_or_b32_e32 v160, 32, v168
	v_ashrrev_i32_e32 v161, 31, v160
	v_or_b32_e32 v156, 48, v168
	v_ashrrev_i32_e32 v157, 31, v156
	v_add_u32_e32 v152, 0x80, v168
	v_ashrrev_i32_e32 v153, 31, v152
	v_mov_b32_e32 v162, v201
	s_andn2_b64 vcc, exec, s[16:17]
	s_waitcnt lgkmcnt(0)
	v_mov_b32_e32 v150, v147
	v_mov_b32_e32 v151, v148
	v_mov_b32_e32 v147, v149
	v_pk_add_f32 v[146:147], v[150:151], v[146:147]
	s_nop 0
	v_add_f32_e32 v154, v146, v147
	v_lshlrev_b64 v[146:147], 6, v[164:165]
	v_lshl_add_u64 v[146:147], v[136:137], 0, v[146:147]
	ds_read_b128 v[146:149], v239 offset:1024
	s_waitcnt lgkmcnt(0)
	v_mov_b32_e32 v150, v147
	v_mov_b32_e32 v151, v148
	v_mov_b32_e32 v147, v149
	v_pk_add_f32 v[146:147], v[150:151], v[146:147]
	s_nop 0
	v_add_f32_e32 v158, v146, v147
	v_lshlrev_b64 v[146:147], 6, v[160:161]
	v_lshl_add_u64 v[146:147], v[136:137], 0, v[146:147]
	ds_read_b128 v[146:149], v239 offset:2048
	s_waitcnt lgkmcnt(0)
	v_mov_b32_e32 v150, v147
	v_mov_b32_e32 v151, v148
	v_mov_b32_e32 v147, v149
	v_pk_add_f32 v[146:147], v[150:151], v[146:147]
	s_nop 0
	v_add_f32_e32 v161, v146, v147
	v_lshlrev_b64 v[146:147], 6, v[156:157]
	v_lshl_add_u64 v[146:147], v[136:137], 0, v[146:147]
	ds_read_b128 v[146:149], v239 offset:3072
	s_waitcnt lgkmcnt(0)
	v_mov_b32_e32 v150, v147
	v_mov_b32_e32 v151, v148
	v_mov_b32_e32 v147, v149
	v_pk_add_f32 v[146:147], v[150:151], v[146:147]
	s_nop 0
	v_add_f32_e32 v157, v146, v147
	v_lshlrev_b64 v[146:147], 6, v[152:153]
	v_lshl_add_u64 v[146:147], v[136:137], 0, v[146:147]
	ds_read_b128 v[146:149], v239 offset:8192
	s_waitcnt lgkmcnt(0)
	v_mov_b32_e32 v150, v147
	v_mov_b32_e32 v151, v148
	v_mov_b32_e32 v147, v149
	v_pk_add_f32 v[146:147], v[150:151], v[146:147]
	v_add_u32_e32 v150, 0x90, v168
	v_ashrrev_i32_e32 v151, 31, v150
	v_add_f32_e32 v153, v146, v147
	v_lshlrev_b64 v[146:147], 6, v[150:151]
	v_lshl_add_u64 v[146:147], v[136:137], 0, v[146:147]
	ds_read_b128 v[146:149], v239 offset:9216
	s_waitcnt lgkmcnt(0)
	v_mov_b32_e32 v176, v147
	v_mov_b32_e32 v177, v148
	v_mov_b32_e32 v147, v149
	v_add_u32_e32 v148, 0xa0, v168
	v_pk_add_f32 v[146:147], v[176:177], v[146:147]
	v_ashrrev_i32_e32 v149, 31, v148
	v_add_f32_e32 v151, v146, v147
	v_lshlrev_b64 v[146:147], 6, v[148:149]
	v_lshl_add_u64 v[146:147], v[136:137], 0, v[146:147]
	ds_read_b128 v[176:179], v239 offset:10240
	s_waitcnt lgkmcnt(0)
	v_mov_b32_e32 v146, v177
	v_mov_b32_e32 v147, v178
	v_mov_b32_e32 v177, v179
	v_pk_add_f32 v[146:147], v[146:147], v[176:177]
	s_nop 0
	v_add_f32_e32 v149, v146, v147
	v_add_u32_e32 v146, 0xb0, v168
	v_ashrrev_i32_e32 v147, 31, v146
	v_lshlrev_b64 v[176:177], 6, v[146:147]
	v_lshl_add_u64 v[176:177], v[136:137], 0, v[176:177]
	ds_read_b128 v[176:179], v239 offset:11264
	s_waitcnt lgkmcnt(0)
	v_mov_b32_e32 v180, v177
	v_lshlrev_b32_e32 v162, 2, v162
	v_xor_b32_e32 v162, 64, v162
	v_mov_b32_e32 v162, v154
	s_nop 1
	v_permlane16_swap_b32_e32 v162, v154
	v_mov_b32_e32 v181, v178
	v_mov_b32_e32 v177, v179
	v_pk_add_f32 v[176:177], v[180:181], v[176:177]
	v_lshl_or_b32 v178, s49, 7, v163
	s_waitcnt lgkmcnt(0)
	v_add_f32_e32 v154, v154, v162
	v_mov_b32_e32 v162, v201
	v_add_f32_e32 v147, v176, v177
	v_lshlrev_b32_e32 v162, 2, v162
	v_xor_b32_e32 v162, 0x80, v162
	v_mov_b32_e32 v162, v154
	s_nop 1
	v_permlane32_swap_b32_e32 v162, v154
	v_ashrrev_i32_e32 v179, 31, v178
	s_mov_b64 s[48:49], -1
	s_waitcnt lgkmcnt(0)
	v_add_f32_e32 v154, v154, v162
	v_fmamk_f32 v154, v154, 0x3a800000, v175
	v_rsq_f32_e32 v174, v154
	v_mov_b32_e32 v154, v201
	v_pk_mul_f32 v[124:125], v[124:125], v[174:175] op_sel_hi:[1,0]
	v_lshlrev_b32_e32 v154, 2, v154
	v_xor_b32_e32 v154, 64, v154
	v_mov_b32_e32 v154, v158
	s_nop 1
	v_permlane16_swap_b32_e32 v154, v158
	v_pk_mul_f32 v[126:127], v[126:127], v[174:175] op_sel_hi:[1,0]
	v_pk_mul_f32 v[116:117], v[116:117], v[174:175] op_sel_hi:[1,0]
	v_pk_mul_f32 v[120:121], v[120:121], v[174:175] op_sel_hi:[1,0]
	v_pk_mul_f32 v[118:119], v[118:119], v[174:175] op_sel_hi:[1,0]
	s_waitcnt lgkmcnt(0)
	v_add_f32_e32 v154, v158, v154
	v_mov_b32_e32 v158, v201
	v_pk_mul_f32 v[122:123], v[122:123], v[174:175] op_sel_hi:[1,0]
	v_lshlrev_b32_e32 v158, 2, v158
	v_xor_b32_e32 v158, 0x80, v158
	v_mov_b32_e32 v158, v154
	s_nop 1
	v_permlane32_swap_b32_e32 v158, v154
	v_pk_mul_f32 v[112:113], v[112:113], v[174:175] op_sel_hi:[1,0]
	v_pk_mul_f32 v[114:115], v[114:115], v[174:175] op_sel_hi:[1,0]
	s_waitcnt lgkmcnt(0)
	v_add_f32_e32 v154, v154, v158
	v_fmamk_f32 v154, v154, 0x3a800000, v175
	v_rsq_f32_e32 v176, v154
	v_mov_b32_e32 v154, v201
	v_mov_b32_e32 v158, v201
	v_lshlrev_b32_e32 v154, 2, v154
	v_xor_b32_e32 v154, 64, v154
	v_mov_b32_e32 v154, v161
	s_nop 1
	v_permlane16_swap_b32_e32 v154, v161
	v_pk_mul_f32 v[110:111], v[110:111], v[176:177] op_sel_hi:[1,0]
	v_lshlrev_b32_e32 v158, 2, v158
	v_xor_b32_e32 v158, 0x80, v158
	s_waitcnt lgkmcnt(0)
	v_add_f32_e32 v154, v161, v154
	v_mov_b32_e32 v158, v154
	s_nop 1
	v_permlane32_swap_b32_e32 v158, v154
	v_pk_mul_f32 v[108:109], v[108:109], v[176:177] op_sel_hi:[1,0]
	v_pk_mul_f32 v[100:101], v[100:101], v[176:177] op_sel_hi:[1,0]
	v_pk_mul_f32 v[102:103], v[102:103], v[176:177] op_sel_hi:[1,0]
	v_pk_mul_f32 v[106:107], v[106:107], v[176:177] op_sel_hi:[1,0]
	s_waitcnt lgkmcnt(0)
; __device__ __forceinline__ f32x4 silu4(f32x4 v) { return (f32x4){silu_f(v[0]), silu_f(v[1]), silu_f(v[2]), silu_f(v[3])}; }
; __device__ __forceinline__ float row_finish(float t) { t += shx(t, 16); t += shx(t, 32); return __builtin_amdgcn_rsqf(t * (1.0f / 1024.0f) + RMS_EPS); }
;     __device__ __forceinline__ void operator()(const f32x4 (&acc)[2][2][4][2], const Unit& u, int wr, int wc, int fr, int fq) const {
;     ...
;         for (int ai = 0; ai < 2; ++ai)
; #pragma unroll
;             for (int m = 0; m < 4; ++m) rs[ai][m] = row_finish(rs[ai][m]);
; #pragma unroll
;         for (int ai = 0; ai < 2; ++ai)
; #pragma unroll
;             for (int m = 0; m < 4; ++m) {
;                 const int row = u.pm * BM + ai * HALF + wr * 64 + m * 16 + fr;
;                 const float rstd = rs[ai][m];
;                 const f32x4 a0 = silu4(acc[ai][0][m][0] * rstd) * (acc[ai][1][m][0] * rstd);
;                 const f32x4 a1 = silu4(acc[ai][0][m][1] * rstd) * (acc[ai][1][m][1] * rstd);
	v_add_f32_e32 v154, v154, v158
	v_fmamk_f32 v154, v154, 0x3a800000, v175
	v_rsq_f32_e32 v172, v154
	v_mov_b32_e32 v154, v201
	v_pk_mul_f32 v[104:105], v[104:105], v[176:177] op_sel_hi:[1,0]
	v_lshlrev_b32_e32 v154, 2, v154
	v_xor_b32_e32 v154, 64, v154
	v_mov_b32_e32 v154, v157
	s_nop 1
	v_permlane16_swap_b32_e32 v154, v157
	v_pk_mul_f32 v[96:97], v[96:97], v[176:177] op_sel_hi:[1,0]
	v_pk_mul_f32 v[98:99], v[98:99], v[176:177] op_sel_hi:[1,0]
	v_pk_mul_f32 v[94:95], v[94:95], v[172:173] op_sel_hi:[1,0]
	v_pk_mul_f32 v[92:93], v[92:93], v[172:173] op_sel_hi:[1,0]
	s_waitcnt lgkmcnt(0)
	v_add_f32_e32 v154, v157, v154
	v_mov_b32_e32 v157, v201
	v_pk_mul_f32 v[84:85], v[84:85], v[172:173] op_sel_hi:[1,0]
	v_lshlrev_b32_e32 v157, 2, v157
	v_xor_b32_e32 v157, 0x80, v157
	v_mov_b32_e32 v157, v154
	s_nop 1
	v_permlane32_swap_b32_e32 v157, v154
	v_pk_mul_f32 v[86:87], v[86:87], v[172:173] op_sel_hi:[1,0]
	v_pk_mul_f32 v[90:91], v[90:91], v[172:173] op_sel_hi:[1,0]
	v_pk_mul_f32 v[88:89], v[88:89], v[172:173] op_sel_hi:[1,0]
	v_pk_mul_f32 v[80:81], v[80:81], v[172:173] op_sel_hi:[1,0]
	s_waitcnt lgkmcnt(0)
	v_add_f32_e32 v154, v154, v157
	v_fmamk_f32 v154, v154, 0x3a800000, v175
	v_rsq_f32_e32 v170, v154
	v_mov_b32_e32 v154, v201
	v_pk_mul_f32 v[82:83], v[82:83], v[172:173] op_sel_hi:[1,0]
	v_lshlrev_b32_e32 v154, 2, v154
	v_xor_b32_e32 v154, 64, v154
	v_mov_b32_e32 v154, v153
	s_nop 1
	v_permlane16_swap_b32_e32 v154, v153
	v_pk_mul_f32 v[78:79], v[78:79], v[170:171] op_sel_hi:[1,0]
	v_pk_mul_f32 v[76:77], v[76:77], v[170:171] op_sel_hi:[1,0]
	v_pk_mul_f32 v[68:69], v[68:69], v[170:171] op_sel_hi:[1,0]
	v_pk_mul_f32 v[70:71], v[70:71], v[170:171] op_sel_hi:[1,0]
	s_waitcnt lgkmcnt(0)
	v_add_f32_e32 v153, v153, v154
	v_mov_b32_e32 v154, v201
	v_pk_mul_f32 v[74:75], v[74:75], v[170:171] op_sel_hi:[1,0]
	v_lshlrev_b32_e32 v154, 2, v154
	v_xor_b32_e32 v154, 0x80, v154
	v_mov_b32_e32 v154, v153
	s_nop 1
	v_permlane32_swap_b32_e32 v154, v153
	v_pk_mul_f32 v[72:73], v[72:73], v[170:171] op_sel_hi:[1,0]
	v_pk_mul_f32 v[64:65], v[64:65], v[170:171] op_sel_hi:[1,0]
	v_pk_mul_f32 v[66:67], v[66:67], v[170:171] op_sel_hi:[1,0]
	s_waitcnt lgkmcnt(0)
	v_add_f32_e32 v153, v153, v154
	v_fmamk_f32 v153, v153, 0x3a800000, v175
	v_rsq_f32_e32 v166, v153
	v_mov_b32_e32 v153, v201
	v_pk_mul_f32 v[62:63], v[62:63], v[166:167] op_sel_hi:[1,0]
	v_lshlrev_b32_e32 v153, 2, v153
	v_xor_b32_e32 v153, 64, v153
	v_mov_b32_e32 v153, v151
	s_nop 1
	v_permlane16_swap_b32_e32 v153, v151
	v_pk_mul_f32 v[60:61], v[60:61], v[166:167] op_sel_hi:[1,0]
	v_pk_mul_f32 v[52:53], v[52:53], v[166:167] op_sel_hi:[1,0]
	v_pk_mul_f32 v[54:55], v[54:55], v[166:167] op_sel_hi:[1,0]
	v_pk_mul_f32 v[58:59], v[58:59], v[166:167] op_sel_hi:[1,0]
	s_waitcnt lgkmcnt(0)
	v_add_f32_e32 v151, v151, v153
	v_mov_b32_e32 v153, v201
	v_pk_mul_f32 v[56:57], v[56:57], v[166:167] op_sel_hi:[1,0]
	v_lshlrev_b32_e32 v153, 2, v153
	v_xor_b32_e32 v153, 0x80, v153
	v_mov_b32_e32 v153, v151
	s_nop 1
	v_permlane32_swap_b32_e32 v153, v151
	v_pk_mul_f32 v[48:49], v[48:49], v[166:167] op_sel_hi:[1,0]
	v_pk_mul_f32 v[50:51], v[50:51], v[166:167] op_sel_hi:[1,0]
	s_waitcnt lgkmcnt(0)
	v_add_f32_e32 v151, v151, v153
	v_fmamk_f32 v151, v151, 0x3a800000, v175
	v_rsq_f32_e32 v162, v151
	v_mov_b32_e32 v151, v201
	v_pk_mul_f32 v[46:47], v[46:47], v[162:163] op_sel_hi:[1,0]
	v_lshlrev_b32_e32 v151, 2, v151
	v_xor_b32_e32 v151, 64, v151
	v_mov_b32_e32 v151, v149
	s_nop 1
	v_permlane16_swap_b32_e32 v151, v149
	v_pk_mul_f32 v[44:45], v[44:45], v[162:163] op_sel_hi:[1,0]
	v_pk_mul_f32 v[36:37], v[36:37], v[162:163] op_sel_hi:[1,0]
	v_pk_mul_f32 v[38:39], v[38:39], v[162:163] op_sel_hi:[1,0]
	v_pk_mul_f32 v[42:43], v[42:43], v[162:163] op_sel_hi:[1,0]
	s_waitcnt lgkmcnt(0)
	v_add_f32_e32 v149, v149, v151
	v_mov_b32_e32 v151, v201
	v_pk_mul_f32 v[40:41], v[40:41], v[162:163] op_sel_hi:[1,0]
	v_lshlrev_b32_e32 v151, 2, v151
	v_xor_b32_e32 v151, 0x80, v151
	v_mov_b32_e32 v151, v149
	s_nop 1
	v_permlane32_swap_b32_e32 v151, v149
	v_pk_mul_f32 v[32:33], v[32:33], v[162:163] op_sel_hi:[1,0]
	v_pk_mul_f32 v[34:35], v[34:35], v[162:163] op_sel_hi:[1,0]
	s_waitcnt lgkmcnt(0)
	v_add_f32_e32 v149, v149, v151
	v_fmamk_f32 v149, v149, 0x3a800000, v175
	v_rsq_f32_e32 v158, v149
	v_mov_b32_e32 v149, v201
	v_pk_mul_f32 v[30:31], v[30:31], v[158:159] op_sel_hi:[1,0]
	v_lshlrev_b32_e32 v149, 2, v149
	v_xor_b32_e32 v149, 64, v149
	v_mov_b32_e32 v149, v147
	s_nop 1
	v_permlane16_swap_b32_e32 v149, v147
	v_pk_mul_f32 v[28:29], v[28:29], v[158:159] op_sel_hi:[1,0]
	v_pk_mul_f32 v[20:21], v[20:21], v[158:159] op_sel_hi:[1,0]
	v_pk_mul_f32 v[22:23], v[22:23], v[158:159] op_sel_hi:[1,0]
	v_pk_mul_f32 v[26:27], v[26:27], v[158:159] op_sel_hi:[1,0]
	s_waitcnt lgkmcnt(0)
	v_add_f32_e32 v147, v147, v149
	v_mov_b32_e32 v149, v201
	v_pk_mul_f32 v[24:25], v[24:25], v[158:159] op_sel_hi:[1,0]
	v_lshlrev_b32_e32 v149, 2, v149
	v_xor_b32_e32 v149, 0x80, v149
	v_mov_b32_e32 v149, v147
	s_nop 1
	v_permlane32_swap_b32_e32 v149, v147
	v_pk_mul_f32 v[16:17], v[16:17], v[158:159] op_sel_hi:[1,0]
	v_pk_mul_f32 v[18:19], v[18:19], v[158:159] op_sel_hi:[1,0]
	s_waitcnt lgkmcnt(0)
; __device__ __forceinline__ u32x4 pack8(f32x4 a, f32x4 b) { u32x4 w; w.x = cvt_pk_bf16(a[0], a[1]); w.y = cvt_pk_bf16(a[2], a[3]); w.z = cvt_pk_bf16(b[0], b[1]); w.w = cvt_pk_bf16(b[2], b[3]); return w; }
; __device__ __forceinline__ float silu_f(float v) { return v * __builtin_amdgcn_rcpf(1.0f + __builtin_amdgcn_exp2f(v * -1.4426950408889634f)); }
; __device__ __forceinline__ f32x4 silu4(f32x4 v) { return (f32x4){silu_f(v[0]), silu_f(v[1]), silu_f(v[2]), silu_f(v[3])}; }
;     __device__ __forceinline__ void operator()(const f32x4 (&acc)[2][2][4][2], const Unit& u, int wr, int wc, int fr, int fq) const {
;     ...
;         for (int ai = 0; ai < 2; ++ai)
; #pragma unroll
;             for (int m = 0; m < 4; ++m) {
;                 const int row = u.pm * BM + ai * HALF + wr * 64 + m * 16 + fr;
;                 const float rstd = rs[ai][m];
;                 const f32x4 a0 = silu4(acc[ai][0][m][0] * rstd) * (acc[ai][1][m][0] * rstd);
;                 const f32x4 a1 = silu4(acc[ai][0][m][1] * rstd) * (acc[ai][1][m][1] * rstd);
;                 *(u32x4*)(ACT + (size_t)row * 2816 + col0) = pack8(a0, a1);
	v_add_f32_e32 v147, v147, v149
	v_fmamk_f32 v147, v147, 0x3a800000, v175
	v_rsq_f32_e32 v154, v147
	v_mul_f32_e32 v147, 0xbfb8aa3b, v124
	v_exp_f32_e32 v147, v147
	v_pk_mul_f32 v[14:15], v[14:15], v[154:155] op_sel_hi:[1,0]
	v_pk_mul_f32 v[12:13], v[12:13], v[154:155] op_sel_hi:[1,0]
	v_add_f32_e32 v147, 1.0, v147
	v_rcp_f32_e32 v180, v147
	v_mul_f32_e32 v147, 0xbfb8aa3b, v125
	v_exp_f32_e32 v147, v147
	v_pk_mul_f32 v[4:5], v[4:5], v[154:155] op_sel_hi:[1,0]
	v_pk_mul_f32 v[6:7], v[6:7], v[154:155] op_sel_hi:[1,0]
	v_pk_mul_f32 v[10:11], v[10:11], v[154:155] op_sel_hi:[1,0]
	v_add_f32_e32 v147, 1.0, v147
	v_rcp_f32_e32 v181, v147
	v_mul_f32_e32 v147, 0xbfb8aa3b, v126
	v_exp_f32_e32 v147, v147
	v_pk_mul_f32 v[8:9], v[8:9], v[154:155] op_sel_hi:[1,0]
	v_pk_mul_f32 v[124:125], v[124:125], v[180:181]
	v_pk_mul_f32 v[0:1], v[0:1], v[154:155] op_sel_hi:[1,0]
	v_add_f32_e32 v147, 1.0, v147
	v_rcp_f32_e32 v182, v147
	v_mul_f32_e32 v147, 0xbfb8aa3b, v127
	v_exp_f32_e32 v147, v147
	v_pk_mul_f32 v[116:117], v[116:117], v[124:125]
	v_mul_f32_e32 v124, 0xbfb8aa3b, v120
	v_mul_f32_e32 v125, 0xbfb8aa3b, v121
	v_add_f32_e32 v147, 1.0, v147
	v_rcp_f32_e32 v183, v147
	v_exp_f32_e32 v124, v124
	v_exp_f32_e32 v125, v125
	v_cvt_pk_bf16_f32 v116, v116, v117
	v_pk_mul_f32 v[126:127], v[126:127], v[182:183]
	v_add_f32_e32 v124, 1.0, v124
	v_pk_mul_f32 v[118:119], v[118:119], v[126:127]
	v_mul_f32_e32 v126, 0xbfb8aa3b, v122
	v_mul_f32_e32 v127, 0xbfb8aa3b, v123
	v_exp_f32_e32 v126, v126
	v_exp_f32_e32 v127, v127
	v_add_f32_e32 v125, 1.0, v125
	v_rcp_f32_e32 v124, v124
	v_rcp_f32_e32 v125, v125
	v_add_f32_e32 v126, 1.0, v126
	v_add_f32_e32 v127, 1.0, v127
	v_rcp_f32_e32 v126, v126
	v_rcp_f32_e32 v127, v127
	v_pk_mul_f32 v[120:121], v[120:121], v[124:125]
	v_cvt_pk_bf16_f32 v117, v118, v119
	v_pk_mul_f32 v[2:3], v[2:3], v[154:155] op_sel_hi:[1,0]
	v_pk_mul_f32 v[122:123], v[122:123], v[126:127]
	v_pk_mul_f32 v[112:113], v[112:113], v[120:121]
	v_pk_mul_f32 v[114:115], v[114:115], v[122:123]
	v_cvt_pk_bf16_f32 v118, v112, v113
	v_mov_b64_e32 v[112:113], s[20:21]
	v_cvt_pk_bf16_f32 v119, v114, v115
	v_mad_i64_i32 v[120:121], s[14:15], v168, s68, v[112:113]
	v_lshlrev_b64 v[114:115], 1, v[178:179]
	v_lshl_add_u64 v[120:121], v[120:121], 0, v[114:115]
	global_store_dwordx4 v[120:121], v[116:119], off sc1
	s_nop 1
	v_mul_f32_e32 v116, 0xbfb8aa3b, v108
	v_mul_f32_e32 v117, 0xbfb8aa3b, v109
	v_mul_f32_e32 v118, 0xbfb8aa3b, v110
	v_mul_f32_e32 v119, 0xbfb8aa3b, v111
	v_exp_f32_e32 v116, v116
	v_exp_f32_e32 v117, v117
	v_exp_f32_e32 v118, v118
	v_exp_f32_e32 v119, v119
	v_add_f32_e32 v116, 1.0, v116
	v_add_f32_e32 v117, 1.0, v117
	v_add_f32_e32 v118, 1.0, v118
	v_add_f32_e32 v119, 1.0, v119
	v_rcp_f32_e32 v116, v116
	v_rcp_f32_e32 v117, v117
	v_rcp_f32_e32 v118, v118
	v_rcp_f32_e32 v119, v119
	v_pk_mul_f32 v[108:109], v[108:109], v[116:117]
	s_nop 0
	v_pk_mul_f32 v[100:101], v[100:101], v[108:109]
	v_pk_mul_f32 v[110:111], v[110:111], v[118:119]
	v_mul_f32_e32 v108, 0xbfb8aa3b, v104
	v_pk_mul_f32 v[102:103], v[102:103], v[110:111]
	v_mul_f32_e32 v109, 0xbfb8aa3b, v105
	v_mul_f32_e32 v110, 0xbfb8aa3b, v106
	v_mul_f32_e32 v111, 0xbfb8aa3b, v107
	v_exp_f32_e32 v108, v108
	v_exp_f32_e32 v109, v109
	v_exp_f32_e32 v110, v110
	v_exp_f32_e32 v111, v111
	v_add_f32_e32 v108, 1.0, v108
	v_add_f32_e32 v109, 1.0, v109
	v_add_f32_e32 v110, 1.0, v110
	v_add_f32_e32 v111, 1.0, v111
	v_rcp_f32_e32 v108, v108
	v_rcp_f32_e32 v109, v109
	v_rcp_f32_e32 v110, v110
	v_rcp_f32_e32 v111, v111
	v_pk_mul_f32 v[104:105], v[104:105], v[108:109]
	v_pk_mul_f32 v[106:107], v[106:107], v[110:111]
	s_nop 0
	v_pk_mul_f32 v[106:107], v[98:99], v[106:107]
	v_pk_mul_f32 v[98:99], v[96:97], v[104:105]
	v_cvt_pk_bf16_f32 v96, v100, v101
	v_mad_i64_i32 v[100:101], s[14:15], v164, s68, v[112:113]
	v_cvt_pk_bf16_f32 v97, v102, v103
	v_cvt_pk_bf16_f32 v98, v98, v99
	v_cvt_pk_bf16_f32 v99, v106, v107
	v_lshl_add_u64 v[100:101], v[100:101], 0, v[114:115]
	global_store_dwordx4 v[100:101], v[96:99], off sc1
	s_nop 1
	v_mul_f32_e32 v96, 0xbfb8aa3b, v92
	v_mul_f32_e32 v97, 0xbfb8aa3b, v93
	v_mul_f32_e32 v98, 0xbfb8aa3b, v94
	v_mul_f32_e32 v99, 0xbfb8aa3b, v95
	v_exp_f32_e32 v96, v96
	v_exp_f32_e32 v97, v97
	v_exp_f32_e32 v98, v98
	v_exp_f32_e32 v99, v99
	v_add_f32_e32 v96, 1.0, v96
	v_add_f32_e32 v97, 1.0, v97
	v_add_f32_e32 v98, 1.0, v98
	v_add_f32_e32 v99, 1.0, v99
	v_rcp_f32_e32 v96, v96
	v_rcp_f32_e32 v97, v97
	v_rcp_f32_e32 v98, v98
	v_rcp_f32_e32 v99, v99
	v_pk_mul_f32 v[92:93], v[92:93], v[96:97]
	s_nop 0
	v_pk_mul_f32 v[84:85], v[84:85], v[92:93]
	v_pk_mul_f32 v[94:95], v[94:95], v[98:99]
	v_mul_f32_e32 v92, 0xbfb8aa3b, v88
	v_pk_mul_f32 v[86:87], v[86:87], v[94:95]
	v_mul_f32_e32 v93, 0xbfb8aa3b, v89
	v_mul_f32_e32 v94, 0xbfb8aa3b, v90
	v_mul_f32_e32 v95, 0xbfb8aa3b, v91
	v_exp_f32_e32 v92, v92
	v_exp_f32_e32 v93, v93
	v_exp_f32_e32 v94, v94
	v_exp_f32_e32 v95, v95
	v_add_f32_e32 v92, 1.0, v92
	v_add_f32_e32 v93, 1.0, v93
	v_add_f32_e32 v94, 1.0, v94
	v_add_f32_e32 v95, 1.0, v95
	v_rcp_f32_e32 v92, v92
	v_rcp_f32_e32 v93, v93
	v_rcp_f32_e32 v94, v94
	v_rcp_f32_e32 v95, v95
	v_pk_mul_f32 v[88:89], v[88:89], v[92:93]
	v_pk_mul_f32 v[90:91], v[90:91], v[94:95]
	s_nop 0
	v_pk_mul_f32 v[90:91], v[82:83], v[90:91]
	v_pk_mul_f32 v[82:83], v[80:81], v[88:89]
	v_cvt_pk_bf16_f32 v80, v84, v85
	v_mad_i64_i32 v[84:85], s[14:15], v160, s68, v[112:113]
	v_cvt_pk_bf16_f32 v81, v86, v87
	v_cvt_pk_bf16_f32 v82, v82, v83
	v_cvt_pk_bf16_f32 v83, v90, v91
	v_lshl_add_u64 v[84:85], v[84:85], 0, v[114:115]
	global_store_dwordx4 v[84:85], v[80:83], off sc1
	s_nop 1
	v_mul_f32_e32 v80, 0xbfb8aa3b, v76
	v_mul_f32_e32 v81, 0xbfb8aa3b, v77
; __device__ __forceinline__ u32x4 pack8(f32x4 a, f32x4 b) { u32x4 w; w.x = cvt_pk_bf16(a[0], a[1]); w.y = cvt_pk_bf16(a[2], a[3]); w.z = cvt_pk_bf16(b[0], b[1]); w.w = cvt_pk_bf16(b[2], b[3]); return w; }
; __device__ __forceinline__ float silu_f(float v) { return v * __builtin_amdgcn_rcpf(1.0f + __builtin_amdgcn_exp2f(v * -1.4426950408889634f)); }
; __device__ __forceinline__ f32x4 silu4(f32x4 v) { return (f32x4){silu_f(v[0]), silu_f(v[1]), silu_f(v[2]), silu_f(v[3])}; }
;     __device__ __forceinline__ void operator()(const f32x4 (&acc)[2][2][4][2], const Unit& u, int wr, int wc, int fr, int fq) const {
;     ...
;                 const f32x4 a0 = silu4(acc[ai][0][m][0] * rstd) * (acc[ai][1][m][0] * rstd);
;                 const f32x4 a1 = silu4(acc[ai][0][m][1] * rstd) * (acc[ai][1][m][1] * rstd);
;                 *(u32x4*)(ACT + (size_t)row * 2816 + col0) = pack8(a0, a1);
	v_mul_f32_e32 v82, 0xbfb8aa3b, v78
	v_mul_f32_e32 v83, 0xbfb8aa3b, v79
	v_exp_f32_e32 v80, v80
	v_exp_f32_e32 v81, v81
	v_exp_f32_e32 v82, v82
	v_exp_f32_e32 v83, v83
	v_add_f32_e32 v80, 1.0, v80
	v_add_f32_e32 v81, 1.0, v81
	v_add_f32_e32 v82, 1.0, v82
	v_add_f32_e32 v83, 1.0, v83
	v_rcp_f32_e32 v80, v80
	v_rcp_f32_e32 v81, v81
	v_rcp_f32_e32 v82, v82
	v_rcp_f32_e32 v83, v83
	v_pk_mul_f32 v[76:77], v[76:77], v[80:81]
	s_nop 0
	v_pk_mul_f32 v[68:69], v[68:69], v[76:77]
	v_pk_mul_f32 v[78:79], v[78:79], v[82:83]
	v_mul_f32_e32 v76, 0xbfb8aa3b, v72
	v_pk_mul_f32 v[70:71], v[70:71], v[78:79]
	v_mul_f32_e32 v77, 0xbfb8aa3b, v73
	v_mul_f32_e32 v78, 0xbfb8aa3b, v74
	v_mul_f32_e32 v79, 0xbfb8aa3b, v75
	v_exp_f32_e32 v76, v76
	v_exp_f32_e32 v77, v77
	v_exp_f32_e32 v78, v78
	v_exp_f32_e32 v79, v79
	v_add_f32_e32 v76, 1.0, v76
	v_add_f32_e32 v77, 1.0, v77
	v_add_f32_e32 v78, 1.0, v78
	v_add_f32_e32 v79, 1.0, v79
	v_rcp_f32_e32 v76, v76
	v_rcp_f32_e32 v77, v77
	v_rcp_f32_e32 v78, v78
	v_rcp_f32_e32 v79, v79
	v_pk_mul_f32 v[72:73], v[72:73], v[76:77]
	v_pk_mul_f32 v[74:75], v[74:75], v[78:79]
	s_nop 0
	v_pk_mul_f32 v[74:75], v[66:67], v[74:75]
	v_pk_mul_f32 v[66:67], v[64:65], v[72:73]
	v_cvt_pk_bf16_f32 v64, v68, v69
	v_mad_i64_i32 v[68:69], s[14:15], v156, s68, v[112:113]
	v_cvt_pk_bf16_f32 v65, v70, v71
	v_cvt_pk_bf16_f32 v66, v66, v67
	v_cvt_pk_bf16_f32 v67, v74, v75
	v_lshl_add_u64 v[68:69], v[68:69], 0, v[114:115]
	global_store_dwordx4 v[68:69], v[64:67], off sc1
	s_nop 1
	v_mul_f32_e32 v64, 0xbfb8aa3b, v60
	v_mul_f32_e32 v65, 0xbfb8aa3b, v61
	v_mul_f32_e32 v66, 0xbfb8aa3b, v62
	v_mul_f32_e32 v67, 0xbfb8aa3b, v63
	v_exp_f32_e32 v64, v64
	v_exp_f32_e32 v65, v65
	v_exp_f32_e32 v66, v66
	v_exp_f32_e32 v67, v67
	v_add_f32_e32 v64, 1.0, v64
	v_add_f32_e32 v65, 1.0, v65
	v_add_f32_e32 v66, 1.0, v66
	v_add_f32_e32 v67, 1.0, v67
	v_rcp_f32_e32 v64, v64
	v_rcp_f32_e32 v65, v65
	v_rcp_f32_e32 v66, v66
	v_rcp_f32_e32 v67, v67
	v_pk_mul_f32 v[60:61], v[60:61], v[64:65]
	s_nop 0
	v_pk_mul_f32 v[52:53], v[52:53], v[60:61]
	v_pk_mul_f32 v[62:63], v[62:63], v[66:67]
	v_mul_f32_e32 v60, 0xbfb8aa3b, v56
	v_pk_mul_f32 v[54:55], v[54:55], v[62:63]
	v_mul_f32_e32 v61, 0xbfb8aa3b, v57
	v_mul_f32_e32 v62, 0xbfb8aa3b, v58
	v_mul_f32_e32 v63, 0xbfb8aa3b, v59
	v_exp_f32_e32 v60, v60
	v_exp_f32_e32 v61, v61
	v_exp_f32_e32 v62, v62
	v_exp_f32_e32 v63, v63
	v_add_f32_e32 v60, 1.0, v60
	v_add_f32_e32 v61, 1.0, v61
	v_add_f32_e32 v62, 1.0, v62
	v_add_f32_e32 v63, 1.0, v63
	v_rcp_f32_e32 v60, v60
	v_rcp_f32_e32 v61, v61
	v_rcp_f32_e32 v62, v62
	v_rcp_f32_e32 v63, v63
	v_pk_mul_f32 v[56:57], v[56:57], v[60:61]
	v_pk_mul_f32 v[58:59], v[58:59], v[62:63]
	s_nop 0
	v_pk_mul_f32 v[58:59], v[50:51], v[58:59]
	v_pk_mul_f32 v[50:51], v[48:49], v[56:57]
	v_cvt_pk_bf16_f32 v48, v52, v53
	v_mad_i64_i32 v[52:53], s[14:15], v152, s68, v[112:113]
	v_cvt_pk_bf16_f32 v49, v54, v55
	v_cvt_pk_bf16_f32 v50, v50, v51
	v_cvt_pk_bf16_f32 v51, v58, v59
	v_lshl_add_u64 v[52:53], v[52:53], 0, v[114:115]
	global_store_dwordx4 v[52:53], v[48:51], off sc1
	s_nop 1
	v_mul_f32_e32 v48, 0xbfb8aa3b, v44
	v_mul_f32_e32 v49, 0xbfb8aa3b, v45
	v_mul_f32_e32 v50, 0xbfb8aa3b, v46
	v_mul_f32_e32 v51, 0xbfb8aa3b, v47
	v_exp_f32_e32 v48, v48
	v_exp_f32_e32 v49, v49
	v_exp_f32_e32 v50, v50
	v_exp_f32_e32 v51, v51
	v_add_f32_e32 v48, 1.0, v48
	v_add_f32_e32 v49, 1.0, v49
	v_add_f32_e32 v50, 1.0, v50
	v_add_f32_e32 v51, 1.0, v51
	v_rcp_f32_e32 v48, v48
	v_rcp_f32_e32 v49, v49
	v_rcp_f32_e32 v50, v50
	v_rcp_f32_e32 v51, v51
	v_pk_mul_f32 v[44:45], v[44:45], v[48:49]
	s_nop 0
	v_pk_mul_f32 v[36:37], v[36:37], v[44:45]
	v_pk_mul_f32 v[46:47], v[46:47], v[50:51]
	v_mul_f32_e32 v44, 0xbfb8aa3b, v40
	v_pk_mul_f32 v[38:39], v[38:39], v[46:47]
	v_mul_f32_e32 v45, 0xbfb8aa3b, v41
	v_mul_f32_e32 v46, 0xbfb8aa3b, v42
	v_mul_f32_e32 v47, 0xbfb8aa3b, v43
	v_exp_f32_e32 v44, v44
	v_exp_f32_e32 v45, v45
	v_exp_f32_e32 v46, v46
; __device__ __forceinline__ unsigned cvt_pk_bf16(float lo, float hi) { unsigned r; asm volatile("v_cvt_pk_bf16_f32 %0, %1, %2" : "=v"(r) : "v"(lo), "v"(hi)); return r; }
; __device__ __forceinline__ float silu_f(float v) { return v * __builtin_amdgcn_rcpf(1.0f + __builtin_amdgcn_exp2f(v * -1.4426950408889634f)); }
; __device__ __forceinline__ f32x4 silu4(f32x4 v) { return (f32x4){silu_f(v[0]), silu_f(v[1]), silu_f(v[2]), silu_f(v[3])}; }
; __device__ __forceinline__ float sq4(f32x4 v) { return (v[0] * v[0] + v[1] * v[1]) + (v[2] * v[2] + v[3] * v[3]); }
; __device__ __forceinline__ u32x4 pack8(f32x4 a, f32x4 b) { u32x4 w; w.x = cvt_pk_bf16(a[0], a[1]); w.y = cvt_pk_bf16(a[2], a[3]); w.z = cvt_pk_bf16(b[0], b[1]); w.w = cvt_pk_bf16(b[2], b[3]); return w; }
;     __device__ __forceinline__ void operator()(const f32x4 (&acc)[2][2][4][2], const Unit& u, int wr, int wc, int fr, int fq) const {
;     ...
;         for (int ai = 0; ai < 2; ++ai)
; #pragma unroll
;             for (int m = 0; m < 4; ++m) {
;                 const int row = u.pm * BM + ai * HALF + wr * 64 + m * 16 + fr;
;                 const float rstd = rs[ai][m];
;                 const f32x4 a0 = silu4(acc[ai][0][m][0] * rstd) * (acc[ai][1][m][0] * rstd);
;                 const f32x4 a1 = silu4(acc[ai][0][m][1] * rstd) * (acc[ai][1][m][1] * rstd);
;                 *(u32x4*)(ACT + (size_t)row * 2816 + col0) = pack8(a0, a1);
;             }
	v_exp_f32_e32 v47, v47
	v_add_f32_e32 v44, 1.0, v44
	v_add_f32_e32 v45, 1.0, v45
	v_add_f32_e32 v46, 1.0, v46
	v_add_f32_e32 v47, 1.0, v47
	v_rcp_f32_e32 v44, v44
	v_rcp_f32_e32 v45, v45
	v_rcp_f32_e32 v46, v46
	v_rcp_f32_e32 v47, v47
	v_pk_mul_f32 v[40:41], v[40:41], v[44:45]
	v_pk_mul_f32 v[42:43], v[42:43], v[46:47]
	s_nop 0
	v_pk_mul_f32 v[42:43], v[34:35], v[42:43]
	v_pk_mul_f32 v[34:35], v[32:33], v[40:41]
	v_cvt_pk_bf16_f32 v32, v36, v37
	v_mad_i64_i32 v[36:37], s[14:15], v150, s68, v[112:113]
	v_cvt_pk_bf16_f32 v33, v38, v39
	v_cvt_pk_bf16_f32 v34, v34, v35
	v_cvt_pk_bf16_f32 v35, v42, v43
	v_lshl_add_u64 v[36:37], v[36:37], 0, v[114:115]
	global_store_dwordx4 v[36:37], v[32:35], off sc1
	s_nop 1
	v_mul_f32_e32 v32, 0xbfb8aa3b, v28
	v_mul_f32_e32 v33, 0xbfb8aa3b, v29
	v_mul_f32_e32 v34, 0xbfb8aa3b, v30
	v_mul_f32_e32 v35, 0xbfb8aa3b, v31
	v_exp_f32_e32 v32, v32
	v_exp_f32_e32 v33, v33
	v_exp_f32_e32 v34, v34
	v_exp_f32_e32 v35, v35
	v_add_f32_e32 v32, 1.0, v32
	v_add_f32_e32 v33, 1.0, v33
	v_add_f32_e32 v34, 1.0, v34
	v_add_f32_e32 v35, 1.0, v35
	v_rcp_f32_e32 v32, v32
	v_rcp_f32_e32 v33, v33
	v_rcp_f32_e32 v34, v34
	v_rcp_f32_e32 v35, v35
	v_pk_mul_f32 v[28:29], v[28:29], v[32:33]
	s_nop 0
	v_pk_mul_f32 v[20:21], v[20:21], v[28:29]
	v_pk_mul_f32 v[30:31], v[30:31], v[34:35]
	v_mul_f32_e32 v28, 0xbfb8aa3b, v24
	v_pk_mul_f32 v[22:23], v[22:23], v[30:31]
	v_mul_f32_e32 v29, 0xbfb8aa3b, v25
	v_mul_f32_e32 v30, 0xbfb8aa3b, v26
	v_mul_f32_e32 v31, 0xbfb8aa3b, v27
	v_exp_f32_e32 v28, v28
	v_exp_f32_e32 v29, v29
	v_exp_f32_e32 v30, v30
	v_exp_f32_e32 v31, v31
	v_add_f32_e32 v28, 1.0, v28
	v_add_f32_e32 v29, 1.0, v29
	v_add_f32_e32 v30, 1.0, v30
	v_add_f32_e32 v31, 1.0, v31
	v_rcp_f32_e32 v28, v28
	v_rcp_f32_e32 v29, v29
	v_rcp_f32_e32 v30, v30
	v_rcp_f32_e32 v31, v31
	v_pk_mul_f32 v[24:25], v[24:25], v[28:29]
	v_pk_mul_f32 v[26:27], v[26:27], v[30:31]
	s_nop 0
	v_pk_mul_f32 v[26:27], v[18:19], v[26:27]
	v_pk_mul_f32 v[18:19], v[16:17], v[24:25]
	v_cvt_pk_bf16_f32 v16, v20, v21
	v_mad_i64_i32 v[20:21], s[14:15], v148, s68, v[112:113]
	v_cvt_pk_bf16_f32 v17, v22, v23
	v_cvt_pk_bf16_f32 v18, v18, v19
	v_cvt_pk_bf16_f32 v19, v26, v27
	v_lshl_add_u64 v[20:21], v[20:21], 0, v[114:115]
	global_store_dwordx4 v[20:21], v[16:19], off sc1
	s_nop 1
	v_mul_f32_e32 v16, 0xbfb8aa3b, v12
	v_mul_f32_e32 v17, 0xbfb8aa3b, v13
	v_mul_f32_e32 v18, 0xbfb8aa3b, v14
	v_mul_f32_e32 v19, 0xbfb8aa3b, v15
	v_exp_f32_e32 v16, v16
	v_exp_f32_e32 v17, v17
	v_exp_f32_e32 v18, v18
	v_exp_f32_e32 v19, v19
	v_add_f32_e32 v16, 1.0, v16
	v_add_f32_e32 v17, 1.0, v17
	v_add_f32_e32 v18, 1.0, v18
	v_add_f32_e32 v19, 1.0, v19
	v_rcp_f32_e32 v16, v16
	v_rcp_f32_e32 v17, v17
	v_rcp_f32_e32 v18, v18
	v_rcp_f32_e32 v19, v19
	v_pk_mul_f32 v[12:13], v[12:13], v[16:17]
	s_nop 0
	v_pk_mul_f32 v[4:5], v[4:5], v[12:13]
	v_pk_mul_f32 v[14:15], v[14:15], v[18:19]
	v_mul_f32_e32 v12, 0xbfb8aa3b, v8
	v_pk_mul_f32 v[6:7], v[6:7], v[14:15]
	v_mul_f32_e32 v13, 0xbfb8aa3b, v9
	v_mul_f32_e32 v14, 0xbfb8aa3b, v10
	v_mul_f32_e32 v15, 0xbfb8aa3b, v11
	v_exp_f32_e32 v12, v12
	v_exp_f32_e32 v13, v13
	v_exp_f32_e32 v14, v14
	v_exp_f32_e32 v15, v15
	v_add_f32_e32 v12, 1.0, v12
	v_add_f32_e32 v13, 1.0, v13
	v_add_f32_e32 v14, 1.0, v14
	v_add_f32_e32 v15, 1.0, v15
	v_rcp_f32_e32 v12, v12
	v_rcp_f32_e32 v13, v13
	v_rcp_f32_e32 v14, v14
	v_rcp_f32_e32 v15, v15
	v_pk_mul_f32 v[8:9], v[8:9], v[12:13]
	v_pk_mul_f32 v[10:11], v[10:11], v[14:15]
	s_nop 0
	v_pk_mul_f32 v[10:11], v[2:3], v[10:11]
	v_pk_mul_f32 v[2:3], v[0:1], v[8:9]
	v_cvt_pk_bf16_f32 v0, v4, v5
	v_mad_i64_i32 v[4:5], s[14:15], v146, s68, v[112:113]
	v_lshl_add_u64 v[4:5], v[4:5], 0, v[114:115]
	v_cvt_pk_bf16_f32 v1, v6, v7
	v_cvt_pk_bf16_f32 v2, v2, v3
	v_cvt_pk_bf16_f32 v3, v10, v11
	global_store_dwordx4 v[4:5], v[0:3], off sc1
	s_cbranch_vccnz .LBB0_992
	s_andn2_b64 vcc, exec, s[18:19]
	s_cbranch_vccnz .LBB0_991
	s_barrier
	s_branch .LBB0_991

; __device__ __forceinline__ float sq4(f32x4 v) { return (v[0] * v[0] + v[1] * v[1]) + (v[2] * v[2] + v[3] * v[3]); }
; __device__ __forceinline__ u32x4 pack8(f32x4 a, f32x4 b) { u32x4 w; w.x = cvt_pk_bf16(a[0], a[1]); w.y = cvt_pk_bf16(a[2], a[3]); w.z = cvt_pk_bf16(b[0], b[1]); w.w = cvt_pk_bf16(b[2], b[3]); return w; }
;     __device__ __forceinline__ void operator()(const f32x4 (&acc)[2][2][4][2], const Unit& u, int wr, int wc, int fr, int fq) const {
;         const int col0 = u.pn * 256 + 32 * wc + 8 * fq;
; #pragma unroll
;         for (int ai = 0; ai < 2; ++ai) {
;             u32x4 bs[4][2];
; #pragma unroll
;             for (int m = 0; m < 4; ++m)
; #pragma unroll
;                 for (int bj = 0; bj < 2; ++bj) bs[m][bj] = *(const u32x4*)(xb + (size_t)(u.pm * BM + ai * HALF + wr * 64 + m * 16 + fr) * 1024 + col0 + 128 * bj);
; #pragma unroll
;             for (int m = 0; m < 4; ++m) {
;                 const int row = u.pm * BM + ai * HALF + wr * 64 + m * 16 + fr;
;                 float q = 0.f;
; #pragma unroll
;                 for (int bj = 0; bj < 2; ++bj) {
;                     const size_t off = (size_t)row * 1024 + col0 + 128 * bj; const u32x4 w = bs[m][bj];
;                     const f32x4 b0 = (f32x4){__builtin_bit_cast(float, w.x << 16), __builtin_bit_cast(float, w.x & 0xffff0000u), __builtin_bit_cast(float, w.y << 16), __builtin_bit_cast(float, w.y & 0xffff0000u)};
;                     const f32x4 b1 = (f32x4){__builtin_bit_cast(float, w.z << 16), __builtin_bit_cast(float, w.z & 0xffff0000u), __builtin_bit_cast(float, w.w << 16), __builtin_bit_cast(float, w.w & 0xffff0000u)};
;                     const f32x4 v0 = acc[ai][bj][m][0] + b0, v1 = acc[ai][bj][m][1] + b1;
;                     if (last) { __builtin_nontemporal_store(v0, (f32x4*)(out + off)); __builtin_nontemporal_store(v1, (f32x4*)(out + off + 4)); }
;                     else { q += sq4(v0) + sq4(v1); *(u32x4*)(xb + off) = pack8(v0, v1); }
;                 }
;                 if (!last) { q += shx(q, 16); q += shx(q, 32); if (fq == 0) ss[(size_t)row * 16 + u.pn * 4 + wc] = q; }
.LBB0_1081:
	v_lshl_or_b32 v168, s22, 8, v188
	v_lshl_add_u32 v172, s72, 8, v186
	v_ashrrev_i32_e32 v169, 31, v168
	v_lshlrev_b64 v[202:203], 1, v[168:169]
	v_ashrrev_i32_e32 v173, 31, v172
	v_lshl_add_u64 v[170:171], s[26:27], 0, v[202:203]
	v_lshlrev_b64 v[204:205], 11, v[172:173]
	v_lshl_add_u64 v[120:121], v[170:171], 0, v[204:205]
	global_load_dwordx4 v[192:195], v[120:121], off
	global_load_dwordx4 v[196:199], v[120:121], off offset:256
	v_or_b32_e32 v182, 16, v172
	v_ashrrev_i32_e32 v183, 31, v182
	v_or_b32_e32 v178, 32, v172
	v_lshlrev_b64 v[184:185], 11, v[182:183]
	v_ashrrev_i32_e32 v179, 31, v178
	v_or_b32_e32 v174, 48, v172
	v_lshl_add_u64 v[120:121], v[170:171], 0, v[184:185]
	v_lshlrev_b64 v[180:181], 11, v[178:179]
	v_ashrrev_i32_e32 v175, 31, v174
	global_load_dwordx4 v[148:151], v[120:121], off
	global_load_dwordx4 v[144:147], v[120:121], off offset:256
	v_lshl_add_u64 v[120:121], v[170:171], 0, v[180:181]
	v_lshlrev_b64 v[176:177], 11, v[174:175]
	global_load_dwordx4 v[140:143], v[120:121], off
	global_load_dwordx4 v[136:139], v[120:121], off offset:256
	v_lshl_add_u64 v[120:121], v[170:171], 0, v[176:177]
	global_load_dwordx4 v[132:135], v[120:121], off
	s_nop 0
	global_load_dwordx4 v[120:123], v[120:121], off offset:256
	s_lshl_b32 s50, s22, 2
	s_ashr_i32 s51, s50, 31
	s_waitcnt vmcnt(0)
	v_lshlrev_b32_e32 v206, 16, v192
	v_and_b32_e32 v207, 0xffff0000, v192
	v_lshlrev_b32_e32 v192, 16, v193
	v_and_b32_e32 v193, 0xffff0000, v193
	v_lshlrev_b32_e32 v208, 16, v194
	v_and_b32_e32 v209, 0xffff0000, v194
	v_lshlrev_b32_e32 v194, 16, v195
	v_and_b32_e32 v195, 0xffff0000, v195
	v_pk_add_f32 v[130:131], v[130:131], v[192:193]
	v_pk_add_f32 v[128:129], v[128:129], v[206:207]
	v_pk_add_f32 v[192:193], v[126:127], v[194:195]
	v_pk_add_f32 v[126:127], v[124:125], v[208:209]
	v_mul_f32_e32 v124, v129, v129
	v_mul_f32_e32 v125, v131, v131
	v_fmac_f32_e32 v124, v128, v128
	v_fmac_f32_e32 v125, v130, v130
	v_add_f32_e32 v124, v124, v125
	v_mul_f32_e32 v125, v127, v127
	v_mul_f32_e32 v194, v193, v193
	v_fmac_f32_e32 v125, v126, v126
	v_fmac_f32_e32 v194, v192, v192
	v_add_f32_e32 v125, v125, v194
	v_add_f32_e32 v194, v124, v125
	v_cvt_pk_bf16_f32 v124, v128, v129
	v_lshl_add_u64 v[128:129], s[26:27], 0, v[204:205]
	v_cvt_pk_bf16_f32 v125, v130, v131
	v_cvt_pk_bf16_f32 v126, v126, v127
	v_cvt_pk_bf16_f32 v127, v192, v193
	v_lshl_add_u64 v[128:129], v[128:129], 0, v[202:203]
	global_store_dwordx4 v[128:129], v[124:127], off sc1
	v_lshlrev_b32_e32 v130, 16, v198
	v_and_b32_e32 v131, 0xffff0000, v198
	v_lshlrev_b32_e32 v124, 16, v196
	v_and_b32_e32 v125, 0xffff0000, v196
	v_lshlrev_b32_e32 v126, 16, v197
	v_and_b32_e32 v127, 0xffff0000, v197
	v_lshlrev_b32_e32 v192, 16, v199
	v_and_b32_e32 v193, 0xffff0000, v199
	v_pk_add_f32 v[118:119], v[118:119], v[126:127]
	v_pk_add_f32 v[116:117], v[116:117], v[124:125]
	v_pk_add_f32 v[124:125], v[114:115], v[192:193]
	v_pk_add_f32 v[114:115], v[112:113], v[130:131]
	v_mul_f32_e32 v112, v117, v117
	v_mul_f32_e32 v113, v119, v119
	v_fmac_f32_e32 v112, v116, v116
	v_fmac_f32_e32 v113, v118, v118
	v_add_f32_e32 v112, v112, v113
	v_mul_f32_e32 v113, v115, v115
	v_mul_f32_e32 v126, v125, v125
	v_fmac_f32_e32 v113, v114, v114
	v_fmac_f32_e32 v126, v124, v124
	v_add_f32_e32 v113, v113, v126
	v_add_f32_e32 v112, v112, v113
	v_add_f32_e32 v126, v194, v112
	v_cvt_pk_bf16_f32 v112, v116, v117
	v_cvt_pk_bf16_f32 v113, v118, v119
	v_cvt_pk_bf16_f32 v114, v114, v115
	v_cvt_pk_bf16_f32 v115, v124, v125
	global_store_dwordx4 v[128:129], v[112:115], off offset:256 sc1
	s_nop 1
	v_mov_b32_e32 v112, v201
	v_mov_b32_e32 v113, v201
	v_lshlrev_b32_e32 v112, 2, v112
	v_xor_b32_e32 v112, 64, v112
	v_mov_b32_e32 v112, v126
	s_nop 1
	v_permlane16_swap_b32_e32 v112, v126
	s_waitcnt lgkmcnt(0)
	v_add_f32_e32 v112, v126, v112
	v_lshlrev_b32_e32 v113, 2, v113
	v_xor_b32_e32 v113, 0x80, v113
	v_mov_b32_e32 v113, v112
	s_nop 1
	v_permlane32_swap_b32_e32 v113, v112
	s_and_saveexec_b64 s[52:53], s[16:17]
	s_cbranch_execz .LBB0_1083
	s_waitcnt lgkmcnt(0)
	v_add_f32_e32 v114, v112, v113
	v_lshlrev_b64 v[112:113], 6, v[172:173]
	v_lshl_add_u64 v[112:113], s[42:43], 0, v[112:113]
	v_lshl_add_u64 v[112:113], s[50:51], 2, v[112:113]
	s_lshl_b32 s22, s61, 2
	v_lshl_add_u64 v[112:113], v[112:113], 0, s[22:23]
	global_store_dword v[112:113], v114, off sc1
; __device__ __forceinline__ float sq4(f32x4 v) { return (v[0] * v[0] + v[1] * v[1]) + (v[2] * v[2] + v[3] * v[3]); }
; __device__ __forceinline__ u32x4 pack8(f32x4 a, f32x4 b) { u32x4 w; w.x = cvt_pk_bf16(a[0], a[1]); w.y = cvt_pk_bf16(a[2], a[3]); w.z = cvt_pk_bf16(b[0], b[1]); w.w = cvt_pk_bf16(b[2], b[3]); return w; }
;     __device__ __forceinline__ void operator()(const f32x4 (&acc)[2][2][4][2], const Unit& u, int wr, int wc, int fr, int fq) const {
;     ...
;             for (int m = 0; m < 4; ++m) {
;                 const int row = u.pm * BM + ai * HALF + wr * 64 + m * 16 + fr;
;                 float q = 0.f;
; #pragma unroll
;                 for (int bj = 0; bj < 2; ++bj) {
;                     const size_t off = (size_t)row * 1024 + col0 + 128 * bj; const u32x4 w = bs[m][bj];
;                     const f32x4 b0 = (f32x4){__builtin_bit_cast(float, w.x << 16), __builtin_bit_cast(float, w.x & 0xffff0000u), __builtin_bit_cast(float, w.y << 16), __builtin_bit_cast(float, w.y & 0xffff0000u)};
;                     const f32x4 b1 = (f32x4){__builtin_bit_cast(float, w.z << 16), __builtin_bit_cast(float, w.z & 0xffff0000u), __builtin_bit_cast(float, w.w << 16), __builtin_bit_cast(float, w.w & 0xffff0000u)};
;                     const f32x4 v0 = acc[ai][bj][m][0] + b0, v1 = acc[ai][bj][m][1] + b1;
;                     if (last) { __builtin_nontemporal_store(v0, (f32x4*)(out + off)); __builtin_nontemporal_store(v1, (f32x4*)(out + off + 4)); }
;                     else { q += sq4(v0) + sq4(v1); *(u32x4*)(xb + off) = pack8(v0, v1); }
;                 }
;                 if (!last) { q += shx(q, 16); q += shx(q, 32); if (fq == 0) ss[(size_t)row * 16 + u.pn * 4 + wc] = q; }
.LBB0_1083:
	s_or_b64 exec, exec, s[52:53]
	v_lshlrev_b32_e32 v112, 16, v148
	s_waitcnt lgkmcnt(0)
	v_and_b32_e32 v113, 0xffff0000, v148
	v_lshlrev_b32_e32 v114, 16, v149
	v_and_b32_e32 v115, 0xffff0000, v149
	v_lshlrev_b32_e32 v116, 16, v150
	v_and_b32_e32 v117, 0xffff0000, v150
	v_lshlrev_b32_e32 v118, 16, v151
	v_and_b32_e32 v119, 0xffff0000, v151
	v_pk_add_f32 v[110:111], v[110:111], v[114:115]
	v_pk_add_f32 v[108:109], v[108:109], v[112:113]
	v_pk_add_f32 v[112:113], v[106:107], v[118:119]
	v_pk_add_f32 v[106:107], v[104:105], v[116:117]
	v_mul_f32_e32 v104, v109, v109
	v_mul_f32_e32 v105, v111, v111
	v_fmac_f32_e32 v104, v108, v108
	v_fmac_f32_e32 v105, v110, v110
	v_add_f32_e32 v104, v104, v105
	v_mul_f32_e32 v105, v107, v107
	v_mul_f32_e32 v114, v113, v113
	v_fmac_f32_e32 v105, v106, v106
	v_fmac_f32_e32 v114, v112, v112
	v_add_f32_e32 v105, v105, v114
	v_add_f32_e32 v114, v104, v105
	v_cvt_pk_bf16_f32 v104, v108, v109
	v_lshl_add_u64 v[108:109], s[26:27], 0, v[184:185]
	v_cvt_pk_bf16_f32 v105, v110, v111
	v_cvt_pk_bf16_f32 v106, v106, v107
	v_cvt_pk_bf16_f32 v107, v112, v113
	v_lshl_add_u64 v[108:109], v[168:169], 1, v[108:109]
	global_store_dwordx4 v[108:109], v[104:107], off sc1
	v_lshlrev_b32_e32 v110, 16, v146
	v_and_b32_e32 v111, 0xffff0000, v146
	v_lshlrev_b32_e32 v104, 16, v144
	v_and_b32_e32 v105, 0xffff0000, v144
	v_lshlrev_b32_e32 v106, 16, v145
	v_and_b32_e32 v107, 0xffff0000, v145
	v_lshlrev_b32_e32 v112, 16, v147
	v_and_b32_e32 v113, 0xffff0000, v147
	v_pk_add_f32 v[102:103], v[102:103], v[106:107]
	v_pk_add_f32 v[100:101], v[100:101], v[104:105]
	v_pk_add_f32 v[104:105], v[98:99], v[112:113]
	v_pk_add_f32 v[98:99], v[96:97], v[110:111]
	v_mul_f32_e32 v96, v101, v101
	v_mul_f32_e32 v97, v103, v103
	v_fmac_f32_e32 v96, v100, v100
	v_fmac_f32_e32 v97, v102, v102
	v_add_f32_e32 v96, v96, v97
	v_mul_f32_e32 v97, v99, v99
	v_mul_f32_e32 v106, v105, v105
	v_fmac_f32_e32 v97, v98, v98
	v_fmac_f32_e32 v106, v104, v104
	v_add_f32_e32 v97, v97, v106
	v_add_f32_e32 v96, v96, v97
	v_add_f32_e32 v106, v114, v96
	v_cvt_pk_bf16_f32 v96, v100, v101
	v_cvt_pk_bf16_f32 v97, v102, v103
	v_cvt_pk_bf16_f32 v98, v98, v99
	v_cvt_pk_bf16_f32 v99, v104, v105
	global_store_dwordx4 v[108:109], v[96:99], off offset:256 sc1
	s_nop 1
	v_mov_b32_e32 v96, v201
	v_mov_b32_e32 v97, v201
	v_lshlrev_b32_e32 v96, 2, v96
	v_xor_b32_e32 v96, 64, v96
	v_mov_b32_e32 v96, v106
	s_nop 1
	v_permlane16_swap_b32_e32 v96, v106
	s_waitcnt lgkmcnt(0)
	v_add_f32_e32 v96, v106, v96
	v_lshlrev_b32_e32 v97, 2, v97
	v_xor_b32_e32 v97, 0x80, v97
	v_mov_b32_e32 v97, v96
	s_nop 1
	v_permlane32_swap_b32_e32 v97, v96
	s_and_saveexec_b64 s[52:53], s[16:17]
	s_cbranch_execz .LBB0_1085
	s_waitcnt lgkmcnt(0)
	v_add_f32_e32 v98, v96, v97
	v_lshlrev_b64 v[96:97], 6, v[182:183]
	v_lshl_add_u64 v[96:97], s[42:43], 0, v[96:97]
	v_lshl_add_u64 v[96:97], s[50:51], 2, v[96:97]
	s_lshl_b32 s22, s61, 2
	v_lshl_add_u64 v[96:97], v[96:97], 0, s[22:23]
	global_store_dword v[96:97], v98, off sc1
.LBB0_1085:
	s_or_b64 exec, exec, s[52:53]
	v_lshlrev_b32_e32 v96, 16, v140
	s_waitcnt lgkmcnt(0)
	v_and_b32_e32 v97, 0xffff0000, v140
	v_lshlrev_b32_e32 v98, 16, v141
	v_and_b32_e32 v99, 0xffff0000, v141
	v_lshlrev_b32_e32 v100, 16, v142
	v_and_b32_e32 v101, 0xffff0000, v142
	v_lshlrev_b32_e32 v102, 16, v143
	v_and_b32_e32 v103, 0xffff0000, v143
	v_pk_add_f32 v[94:95], v[94:95], v[98:99]
	v_pk_add_f32 v[92:93], v[92:93], v[96:97]
	v_pk_add_f32 v[96:97], v[90:91], v[102:103]
	v_pk_add_f32 v[90:91], v[88:89], v[100:101]
	v_mul_f32_e32 v88, v93, v93
	v_mul_f32_e32 v89, v95, v95
	v_fmac_f32_e32 v88, v92, v92
	v_fmac_f32_e32 v89, v94, v94
	v_add_f32_e32 v88, v88, v89
	v_mul_f32_e32 v89, v91, v91
	v_mul_f32_e32 v98, v97, v97
	v_fmac_f32_e32 v89, v90, v90
	v_fmac_f32_e32 v98, v96, v96
	v_add_f32_e32 v89, v89, v98
	v_add_f32_e32 v98, v88, v89
	v_cvt_pk_bf16_f32 v88, v92, v93
	v_lshl_add_u64 v[92:93], s[26:27], 0, v[180:181]
	v_cvt_pk_bf16_f32 v89, v94, v95
	v_cvt_pk_bf16_f32 v90, v90, v91
	v_cvt_pk_bf16_f32 v91, v96, v97
	v_lshl_add_u64 v[92:93], v[168:169], 1, v[92:93]
	global_store_dwordx4 v[92:93], v[88:91], off sc1
	v_lshlrev_b32_e32 v94, 16, v138
	v_and_b32_e32 v95, 0xffff0000, v138
	v_lshlrev_b32_e32 v88, 16, v136
	v_and_b32_e32 v89, 0xffff0000, v136
	v_lshlrev_b32_e32 v90, 16, v137
	v_and_b32_e32 v91, 0xffff0000, v137
	v_lshlrev_b32_e32 v96, 16, v139
	v_and_b32_e32 v97, 0xffff0000, v139
	v_pk_add_f32 v[86:87], v[86:87], v[90:91]
	v_pk_add_f32 v[84:85], v[84:85], v[88:89]
	v_pk_add_f32 v[88:89], v[82:83], v[96:97]
	v_pk_add_f32 v[82:83], v[80:81], v[94:95]
	v_mul_f32_e32 v80, v85, v85
	v_mul_f32_e32 v81, v87, v87
	v_fmac_f32_e32 v80, v84, v84
	v_fmac_f32_e32 v81, v86, v86
	v_add_f32_e32 v80, v80, v81
	v_mul_f32_e32 v81, v83, v83
	v_mul_f32_e32 v90, v89, v89
	v_fmac_f32_e32 v81, v82, v82
	v_fmac_f32_e32 v90, v88, v88
	v_add_f32_e32 v81, v81, v90
	v_add_f32_e32 v80, v80, v81
	v_add_f32_e32 v90, v98, v80
	v_cvt_pk_bf16_f32 v80, v84, v85
	v_cvt_pk_bf16_f32 v81, v86, v87
	v_cvt_pk_bf16_f32 v82, v82, v83
	v_cvt_pk_bf16_f32 v83, v88, v89
	global_store_dwordx4 v[92:93], v[80:83], off offset:256 sc1
	s_nop 1
	v_mov_b32_e32 v80, v201
	v_mov_b32_e32 v81, v201
	v_lshlrev_b32_e32 v80, 2, v80
	v_xor_b32_e32 v80, 64, v80
	v_mov_b32_e32 v80, v90
	s_nop 1
	v_permlane16_swap_b32_e32 v80, v90
	s_waitcnt lgkmcnt(0)
	v_add_f32_e32 v80, v90, v80
	v_lshlrev_b32_e32 v81, 2, v81
	v_xor_b32_e32 v81, 0x80, v81
	v_mov_b32_e32 v81, v80
	s_nop 1
	v_permlane32_swap_b32_e32 v81, v80
	s_and_saveexec_b64 s[52:53], s[16:17]
	s_cbranch_execz .LBB0_1087
	s_waitcnt lgkmcnt(0)
	v_add_f32_e32 v82, v80, v81
	v_lshlrev_b64 v[80:81], 6, v[178:179]
	v_lshl_add_u64 v[80:81], s[42:43], 0, v[80:81]
	v_lshl_add_u64 v[80:81], s[50:51], 2, v[80:81]
	s_lshl_b32 s22, s61, 2
	v_lshl_add_u64 v[80:81], v[80:81], 0, s[22:23]
	global_store_dword v[80:81], v82, off sc1
; __device__ __forceinline__ float sq4(f32x4 v) { return (v[0] * v[0] + v[1] * v[1]) + (v[2] * v[2] + v[3] * v[3]); }
; __device__ __forceinline__ u32x4 pack8(f32x4 a, f32x4 b) { u32x4 w; w.x = cvt_pk_bf16(a[0], a[1]); w.y = cvt_pk_bf16(a[2], a[3]); w.z = cvt_pk_bf16(b[0], b[1]); w.w = cvt_pk_bf16(b[2], b[3]); return w; }
;     __device__ __forceinline__ void operator()(const f32x4 (&acc)[2][2][4][2], const Unit& u, int wr, int wc, int fr, int fq) const {
;     ...
;         for (int ai = 0; ai < 2; ++ai) {
;             u32x4 bs[4][2];
; #pragma unroll
;             for (int m = 0; m < 4; ++m)
; #pragma unroll
;                 for (int bj = 0; bj < 2; ++bj) bs[m][bj] = *(const u32x4*)(xb + (size_t)(u.pm * BM + ai * HALF + wr * 64 + m * 16 + fr) * 1024 + col0 + 128 * bj);
; #pragma unroll
;             for (int m = 0; m < 4; ++m) {
;                 const int row = u.pm * BM + ai * HALF + wr * 64 + m * 16 + fr;
;                 float q = 0.f;
; #pragma unroll
;                 for (int bj = 0; bj < 2; ++bj) {
;                     const size_t off = (size_t)row * 1024 + col0 + 128 * bj; const u32x4 w = bs[m][bj];
;                     const f32x4 b0 = (f32x4){__builtin_bit_cast(float, w.x << 16), __builtin_bit_cast(float, w.x & 0xffff0000u), __builtin_bit_cast(float, w.y << 16), __builtin_bit_cast(float, w.y & 0xffff0000u)};
;                     const f32x4 b1 = (f32x4){__builtin_bit_cast(float, w.z << 16), __builtin_bit_cast(float, w.z & 0xffff0000u), __builtin_bit_cast(float, w.w << 16), __builtin_bit_cast(float, w.w & 0xffff0000u)};
;                     const f32x4 v0 = acc[ai][bj][m][0] + b0, v1 = acc[ai][bj][m][1] + b1;
;                     if (last) { __builtin_nontemporal_store(v0, (f32x4*)(out + off)); __builtin_nontemporal_store(v1, (f32x4*)(out + off + 4)); }
;                     else { q += sq4(v0) + sq4(v1); *(u32x4*)(xb + off) = pack8(v0, v1); }
;                 }
;                 if (!last) { q += shx(q, 16); q += shx(q, 32); if (fq == 0) ss[(size_t)row * 16 + u.pn * 4 + wc] = q; }
.LBB0_1087:
	s_or_b64 exec, exec, s[52:53]
	v_lshlrev_b32_e32 v80, 16, v132
	s_waitcnt lgkmcnt(0)
	v_and_b32_e32 v81, 0xffff0000, v132
	v_lshlrev_b32_e32 v82, 16, v133
	v_and_b32_e32 v83, 0xffff0000, v133
	v_lshlrev_b32_e32 v84, 16, v134
	v_and_b32_e32 v85, 0xffff0000, v134
	v_lshlrev_b32_e32 v86, 16, v135
	v_and_b32_e32 v87, 0xffff0000, v135
	v_pk_add_f32 v[78:79], v[78:79], v[82:83]
	v_pk_add_f32 v[76:77], v[76:77], v[80:81]
	v_pk_add_f32 v[80:81], v[74:75], v[86:87]
	v_pk_add_f32 v[74:75], v[72:73], v[84:85]
	v_mul_f32_e32 v72, v77, v77
	v_mul_f32_e32 v73, v79, v79
	v_fmac_f32_e32 v72, v76, v76
	v_fmac_f32_e32 v73, v78, v78
	v_add_f32_e32 v72, v72, v73
	v_mul_f32_e32 v73, v75, v75
	v_mul_f32_e32 v82, v81, v81
	v_fmac_f32_e32 v73, v74, v74
	v_fmac_f32_e32 v82, v80, v80
	v_add_f32_e32 v73, v73, v82
	v_add_f32_e32 v82, v72, v73
	v_cvt_pk_bf16_f32 v72, v76, v77
	v_lshl_add_u64 v[76:77], s[26:27], 0, v[176:177]
	v_cvt_pk_bf16_f32 v73, v78, v79
	v_cvt_pk_bf16_f32 v74, v74, v75
	v_cvt_pk_bf16_f32 v75, v80, v81
	v_lshl_add_u64 v[76:77], v[168:169], 1, v[76:77]
	global_store_dwordx4 v[76:77], v[72:75], off sc1
	v_lshlrev_b32_e32 v78, 16, v122
	v_and_b32_e32 v79, 0xffff0000, v122
	v_lshlrev_b32_e32 v72, 16, v120
	v_and_b32_e32 v73, 0xffff0000, v120
	v_lshlrev_b32_e32 v74, 16, v121
	v_and_b32_e32 v75, 0xffff0000, v121
	v_lshlrev_b32_e32 v80, 16, v123
	v_and_b32_e32 v81, 0xffff0000, v123
	v_pk_add_f32 v[70:71], v[70:71], v[74:75]
	v_pk_add_f32 v[68:69], v[68:69], v[72:73]
	v_pk_add_f32 v[72:73], v[66:67], v[80:81]
	v_pk_add_f32 v[66:67], v[64:65], v[78:79]
	v_mul_f32_e32 v64, v69, v69
	v_mul_f32_e32 v65, v71, v71
	v_fmac_f32_e32 v64, v68, v68
	v_fmac_f32_e32 v65, v70, v70
	v_add_f32_e32 v64, v64, v65
	v_mul_f32_e32 v65, v67, v67
	v_mul_f32_e32 v74, v73, v73
	v_fmac_f32_e32 v65, v66, v66
	v_fmac_f32_e32 v74, v72, v72
	v_add_f32_e32 v65, v65, v74
	v_add_f32_e32 v64, v64, v65
	v_add_f32_e32 v74, v82, v64
	v_cvt_pk_bf16_f32 v64, v68, v69
	v_cvt_pk_bf16_f32 v65, v70, v71
	v_cvt_pk_bf16_f32 v66, v66, v67
	v_cvt_pk_bf16_f32 v67, v72, v73
	global_store_dwordx4 v[76:77], v[64:67], off offset:256 sc1
	s_nop 1
	v_mov_b32_e32 v64, v201
	v_mov_b32_e32 v65, v201
	v_lshlrev_b32_e32 v64, 2, v64
	v_xor_b32_e32 v64, 64, v64
	v_mov_b32_e32 v64, v74
	s_nop 1
	v_permlane16_swap_b32_e32 v64, v74
	s_waitcnt lgkmcnt(0)
	v_add_f32_e32 v64, v74, v64
	v_lshlrev_b32_e32 v65, 2, v65
	v_xor_b32_e32 v65, 0x80, v65
	v_mov_b32_e32 v65, v64
	s_nop 1
	v_permlane32_swap_b32_e32 v65, v64
	s_and_saveexec_b64 s[52:53], s[16:17]
	s_cbranch_execz .LBB0_1089
	s_waitcnt lgkmcnt(0)
	v_add_f32_e32 v66, v64, v65
	v_lshlrev_b64 v[64:65], 6, v[174:175]
	v_lshl_add_u64 v[64:65], s[42:43], 0, v[64:65]
	v_lshl_add_u64 v[64:65], s[50:51], 2, v[64:65]
	s_lshl_b32 s22, s61, 2
	v_lshl_add_u64 v[64:65], v[64:65], 0, s[22:23]
	global_store_dword v[64:65], v66, off sc1
.LBB0_1089:
	s_or_b64 exec, exec, s[52:53]
	v_add_u32_e32 v100, 0x80, v172
	v_ashrrev_i32_e32 v101, 31, v100
	v_lshlrev_b64 v[110:111], 11, v[100:101]
	s_waitcnt lgkmcnt(0)
	v_lshl_add_u64 v[64:65], v[170:171], 0, v[110:111]
	global_load_dwordx4 v[102:105], v[64:65], off
	global_load_dwordx4 v[106:109], v[64:65], off offset:256
	v_add_u32_e32 v96, 0x90, v172
	v_ashrrev_i32_e32 v97, 31, v96
	v_add_u32_e32 v92, 0xa0, v172
	v_lshlrev_b64 v[98:99], 11, v[96:97]
	v_ashrrev_i32_e32 v93, 31, v92
	v_add_u32_e32 v88, 0xb0, v172
	v_lshl_add_u64 v[64:65], v[170:171], 0, v[98:99]
	v_lshlrev_b64 v[94:95], 11, v[92:93]
	v_ashrrev_i32_e32 v89, 31, v88
	global_load_dwordx4 v[84:87], v[64:65], off
	global_load_dwordx4 v[80:83], v[64:65], off offset:256
	v_lshl_add_u64 v[64:65], v[170:171], 0, v[94:95]
	v_lshlrev_b64 v[90:91], 11, v[88:89]
	global_load_dwordx4 v[76:79], v[64:65], off
	global_load_dwordx4 v[72:75], v[64:65], off offset:256
	v_lshl_add_u64 v[64:65], v[170:171], 0, v[90:91]
	global_load_dwordx4 v[68:71], v[64:65], off
	s_nop 0
	global_load_dwordx4 v[64:67], v[64:65], off offset:256
	s_waitcnt vmcnt(7)
	v_lshlrev_b32_e32 v112, 16, v102
	v_and_b32_e32 v113, 0xffff0000, v102
	v_lshlrev_b32_e32 v102, 16, v103
	v_and_b32_e32 v103, 0xffff0000, v103
	v_lshlrev_b32_e32 v114, 16, v104
	v_and_b32_e32 v115, 0xffff0000, v104
	v_lshlrev_b32_e32 v104, 16, v105
	v_and_b32_e32 v105, 0xffff0000, v105
	v_pk_add_f32 v[62:63], v[62:63], v[102:103]
	v_pk_add_f32 v[60:61], v[60:61], v[112:113]
	v_pk_add_f32 v[102:103], v[58:59], v[104:105]
	v_pk_add_f32 v[58:59], v[56:57], v[114:115]
	v_mul_f32_e32 v56, v61, v61
	v_mul_f32_e32 v57, v63, v63
	v_fmac_f32_e32 v56, v60, v60
	v_fmac_f32_e32 v57, v62, v62
	v_add_f32_e32 v56, v56, v57
	v_mul_f32_e32 v57, v59, v59
	v_mul_f32_e32 v104, v103, v103
	v_fmac_f32_e32 v57, v58, v58
	v_fmac_f32_e32 v104, v102, v102
	v_add_f32_e32 v57, v57, v104
	v_add_f32_e32 v104, v56, v57
	v_cvt_pk_bf16_f32 v56, v60, v61
	v_lshl_add_u64 v[60:61], s[26:27], 0, v[110:111]
	v_cvt_pk_bf16_f32 v57, v62, v63
	v_cvt_pk_bf16_f32 v58, v58, v59
	v_cvt_pk_bf16_f32 v59, v102, v103
	v_lshl_add_u64 v[60:61], v[168:169], 1, v[60:61]
	global_store_dwordx4 v[60:61], v[56:59], off sc1
	s_waitcnt vmcnt(7)
	v_lshlrev_b32_e32 v62, 16, v108
	v_and_b32_e32 v63, 0xffff0000, v108
	v_lshlrev_b32_e32 v56, 16, v106
	v_and_b32_e32 v57, 0xffff0000, v106
	v_lshlrev_b32_e32 v58, 16, v107
	v_and_b32_e32 v59, 0xffff0000, v107
	v_lshlrev_b32_e32 v102, 16, v109
	v_and_b32_e32 v103, 0xffff0000, v109
	v_pk_add_f32 v[54:55], v[54:55], v[58:59]
	v_pk_add_f32 v[52:53], v[52:53], v[56:57]
	v_pk_add_f32 v[56:57], v[50:51], v[102:103]
	v_pk_add_f32 v[50:51], v[48:49], v[62:63]
	v_mul_f32_e32 v48, v53, v53
	v_mul_f32_e32 v49, v55, v55
	v_fmac_f32_e32 v48, v52, v52
	v_fmac_f32_e32 v49, v54, v54
	v_add_f32_e32 v48, v48, v49
	v_mul_f32_e32 v49, v51, v51
	v_mul_f32_e32 v58, v57, v57
	v_fmac_f32_e32 v49, v50, v50
	v_fmac_f32_e32 v58, v56, v56
	v_add_f32_e32 v49, v49, v58
	v_add_f32_e32 v48, v48, v49
	v_add_f32_e32 v58, v104, v48
	v_cvt_pk_bf16_f32 v48, v52, v53
	v_cvt_pk_bf16_f32 v49, v54, v55
	v_cvt_pk_bf16_f32 v50, v50, v51
	v_cvt_pk_bf16_f32 v51, v56, v57
	global_store_dwordx4 v[60:61], v[48:51], off offset:256 sc1
	s_nop 1
	v_mov_b32_e32 v48, v201
	v_mov_b32_e32 v49, v201
	v_lshlrev_b32_e32 v48, 2, v48
	v_xor_b32_e32 v48, 64, v48
	v_mov_b32_e32 v48, v58
	s_nop 1
	v_permlane16_swap_b32_e32 v48, v58
	s_waitcnt lgkmcnt(0)
	v_add_f32_e32 v48, v58, v48
	v_lshlrev_b32_e32 v49, 2, v49
	v_xor_b32_e32 v49, 0x80, v49
	v_mov_b32_e32 v49, v48
	s_nop 1
	v_permlane32_swap_b32_e32 v49, v48
	s_and_saveexec_b64 s[52:53], s[16:17]
	s_cbranch_execz .LBB0_1091
	s_waitcnt lgkmcnt(0)
	v_add_f32_e32 v50, v48, v49
	v_lshlrev_b64 v[48:49], 6, v[100:101]
	v_lshl_add_u64 v[48:49], s[42:43], 0, v[48:49]
	v_lshl_add_u64 v[48:49], s[50:51], 2, v[48:49]
	s_lshl_b32 s22, s61, 2
	v_lshl_add_u64 v[48:49], v[48:49], 0, s[22:23]
	global_store_dword v[48:49], v50, off sc1
; __device__ __forceinline__ float sq4(f32x4 v) { return (v[0] * v[0] + v[1] * v[1]) + (v[2] * v[2] + v[3] * v[3]); }
; __device__ __forceinline__ u32x4 pack8(f32x4 a, f32x4 b) { u32x4 w; w.x = cvt_pk_bf16(a[0], a[1]); w.y = cvt_pk_bf16(a[2], a[3]); w.z = cvt_pk_bf16(b[0], b[1]); w.w = cvt_pk_bf16(b[2], b[3]); return w; }
;     __device__ __forceinline__ void operator()(const f32x4 (&acc)[2][2][4][2], const Unit& u, int wr, int wc, int fr, int fq) const {
;     ...
;             for (int m = 0; m < 4; ++m) {
;                 const int row = u.pm * BM + ai * HALF + wr * 64 + m * 16 + fr;
;                 float q = 0.f;
; #pragma unroll
;                 for (int bj = 0; bj < 2; ++bj) {
;                     const size_t off = (size_t)row * 1024 + col0 + 128 * bj; const u32x4 w = bs[m][bj];
;                     const f32x4 b0 = (f32x4){__builtin_bit_cast(float, w.x << 16), __builtin_bit_cast(float, w.x & 0xffff0000u), __builtin_bit_cast(float, w.y << 16), __builtin_bit_cast(float, w.y & 0xffff0000u)};
;                     const f32x4 b1 = (f32x4){__builtin_bit_cast(float, w.z << 16), __builtin_bit_cast(float, w.z & 0xffff0000u), __builtin_bit_cast(float, w.w << 16), __builtin_bit_cast(float, w.w & 0xffff0000u)};
;                     const f32x4 v0 = acc[ai][bj][m][0] + b0, v1 = acc[ai][bj][m][1] + b1;
;                     if (last) { __builtin_nontemporal_store(v0, (f32x4*)(out + off)); __builtin_nontemporal_store(v1, (f32x4*)(out + off + 4)); }
;                     else { q += sq4(v0) + sq4(v1); *(u32x4*)(xb + off) = pack8(v0, v1); }
;                 }
;                 if (!last) { q += shx(q, 16); q += shx(q, 32); if (fq == 0) ss[(size_t)row * 16 + u.pn * 4 + wc] = q; }
.LBB0_1091:
	s_or_b64 exec, exec, s[52:53]
	s_waitcnt vmcnt(7)
	v_lshlrev_b32_e32 v48, 16, v84
	s_waitcnt lgkmcnt(0)
	v_and_b32_e32 v49, 0xffff0000, v84
	v_lshlrev_b32_e32 v50, 16, v85
	v_and_b32_e32 v51, 0xffff0000, v85
	v_lshlrev_b32_e32 v52, 16, v86
	v_and_b32_e32 v53, 0xffff0000, v86
	v_lshlrev_b32_e32 v54, 16, v87
	v_and_b32_e32 v55, 0xffff0000, v87
	v_pk_add_f32 v[46:47], v[46:47], v[50:51]
	v_pk_add_f32 v[44:45], v[44:45], v[48:49]
	v_pk_add_f32 v[48:49], v[42:43], v[54:55]
	v_pk_add_f32 v[42:43], v[40:41], v[52:53]
	v_mul_f32_e32 v40, v45, v45
	v_mul_f32_e32 v41, v47, v47
	v_fmac_f32_e32 v40, v44, v44
	v_fmac_f32_e32 v41, v46, v46
	v_add_f32_e32 v40, v40, v41
	v_mul_f32_e32 v41, v43, v43
	v_mul_f32_e32 v50, v49, v49
	v_fmac_f32_e32 v41, v42, v42
	v_fmac_f32_e32 v50, v48, v48
	v_add_f32_e32 v41, v41, v50
	v_add_f32_e32 v50, v40, v41
	v_cvt_pk_bf16_f32 v40, v44, v45
	v_lshl_add_u64 v[44:45], s[26:27], 0, v[98:99]
	v_cvt_pk_bf16_f32 v41, v46, v47
	v_cvt_pk_bf16_f32 v42, v42, v43
	v_cvt_pk_bf16_f32 v43, v48, v49
	v_lshl_add_u64 v[44:45], v[168:169], 1, v[44:45]
	global_store_dwordx4 v[44:45], v[40:43], off sc1
	s_waitcnt vmcnt(7)
	v_lshlrev_b32_e32 v46, 16, v82
	v_and_b32_e32 v47, 0xffff0000, v82
	v_lshlrev_b32_e32 v40, 16, v80
	v_and_b32_e32 v41, 0xffff0000, v80
	v_lshlrev_b32_e32 v42, 16, v81
	v_and_b32_e32 v43, 0xffff0000, v81
	v_lshlrev_b32_e32 v48, 16, v83
	v_and_b32_e32 v49, 0xffff0000, v83
	v_pk_add_f32 v[38:39], v[38:39], v[42:43]
	v_pk_add_f32 v[36:37], v[36:37], v[40:41]
	v_pk_add_f32 v[40:41], v[34:35], v[48:49]
	v_pk_add_f32 v[34:35], v[32:33], v[46:47]
	v_mul_f32_e32 v32, v37, v37
	v_mul_f32_e32 v33, v39, v39
	v_fmac_f32_e32 v32, v36, v36
	v_fmac_f32_e32 v33, v38, v38
	v_add_f32_e32 v32, v32, v33
	v_mul_f32_e32 v33, v35, v35
	v_mul_f32_e32 v42, v41, v41
	v_fmac_f32_e32 v33, v34, v34
	v_fmac_f32_e32 v42, v40, v40
	v_add_f32_e32 v33, v33, v42
	v_add_f32_e32 v32, v32, v33
	v_add_f32_e32 v42, v50, v32
	v_cvt_pk_bf16_f32 v32, v36, v37
	v_cvt_pk_bf16_f32 v33, v38, v39
	v_cvt_pk_bf16_f32 v34, v34, v35
	v_cvt_pk_bf16_f32 v35, v40, v41
	global_store_dwordx4 v[44:45], v[32:35], off offset:256 sc1
	s_nop 1
	v_mov_b32_e32 v32, v201
	v_mov_b32_e32 v33, v201
	v_lshlrev_b32_e32 v32, 2, v32
	v_xor_b32_e32 v32, 64, v32
	v_mov_b32_e32 v32, v42
	s_nop 1
	v_permlane16_swap_b32_e32 v32, v42
	s_waitcnt lgkmcnt(0)
	v_add_f32_e32 v32, v42, v32
	v_lshlrev_b32_e32 v33, 2, v33
	v_xor_b32_e32 v33, 0x80, v33
	v_mov_b32_e32 v33, v32
	s_nop 1
	v_permlane32_swap_b32_e32 v33, v32
	s_and_saveexec_b64 s[52:53], s[16:17]
	s_cbranch_execz .LBB0_1093
	s_waitcnt lgkmcnt(0)
	v_add_f32_e32 v34, v32, v33
	v_lshlrev_b64 v[32:33], 6, v[96:97]
	v_lshl_add_u64 v[32:33], s[42:43], 0, v[32:33]
	v_lshl_add_u64 v[32:33], s[50:51], 2, v[32:33]
	s_lshl_b32 s22, s61, 2
	v_lshl_add_u64 v[32:33], v[32:33], 0, s[22:23]
	global_store_dword v[32:33], v34, off sc1
; __device__ __forceinline__ float sq4(f32x4 v) { return (v[0] * v[0] + v[1] * v[1]) + (v[2] * v[2] + v[3] * v[3]); }
; __device__ __forceinline__ u32x4 pack8(f32x4 a, f32x4 b) { u32x4 w; w.x = cvt_pk_bf16(a[0], a[1]); w.y = cvt_pk_bf16(a[2], a[3]); w.z = cvt_pk_bf16(b[0], b[1]); w.w = cvt_pk_bf16(b[2], b[3]); return w; }
;     __device__ __forceinline__ void operator()(const f32x4 (&acc)[2][2][4][2], const Unit& u, int wr, int wc, int fr, int fq) const {
;     ...
;             for (int m = 0; m < 4; ++m) {
;                 const int row = u.pm * BM + ai * HALF + wr * 64 + m * 16 + fr;
;                 float q = 0.f;
; #pragma unroll
;                 for (int bj = 0; bj < 2; ++bj) {
;                     const size_t off = (size_t)row * 1024 + col0 + 128 * bj; const u32x4 w = bs[m][bj];
;                     const f32x4 b0 = (f32x4){__builtin_bit_cast(float, w.x << 16), __builtin_bit_cast(float, w.x & 0xffff0000u), __builtin_bit_cast(float, w.y << 16), __builtin_bit_cast(float, w.y & 0xffff0000u)};
;                     const f32x4 b1 = (f32x4){__builtin_bit_cast(float, w.z << 16), __builtin_bit_cast(float, w.z & 0xffff0000u), __builtin_bit_cast(float, w.w << 16), __builtin_bit_cast(float, w.w & 0xffff0000u)};
;                     const f32x4 v0 = acc[ai][bj][m][0] + b0, v1 = acc[ai][bj][m][1] + b1;
;                     if (last) { __builtin_nontemporal_store(v0, (f32x4*)(out + off)); __builtin_nontemporal_store(v1, (f32x4*)(out + off + 4)); }
;                     else { q += sq4(v0) + sq4(v1); *(u32x4*)(xb + off) = pack8(v0, v1); }
;                 }
;                 if (!last) { q += shx(q, 16); q += shx(q, 32); if (fq == 0) ss[(size_t)row * 16 + u.pn * 4 + wc] = q; }
.LBB0_1093:
	s_or_b64 exec, exec, s[52:53]
	s_waitcnt vmcnt(7)
	v_lshlrev_b32_e32 v32, 16, v76
	s_waitcnt lgkmcnt(0)
	v_and_b32_e32 v33, 0xffff0000, v76
	v_lshlrev_b32_e32 v34, 16, v77
	v_and_b32_e32 v35, 0xffff0000, v77
	v_lshlrev_b32_e32 v36, 16, v78
	v_and_b32_e32 v37, 0xffff0000, v78
	v_lshlrev_b32_e32 v38, 16, v79
	v_and_b32_e32 v39, 0xffff0000, v79
	v_pk_add_f32 v[30:31], v[30:31], v[34:35]
	v_pk_add_f32 v[28:29], v[28:29], v[32:33]
	v_pk_add_f32 v[32:33], v[26:27], v[38:39]
	v_pk_add_f32 v[26:27], v[24:25], v[36:37]
	v_mul_f32_e32 v24, v29, v29
	v_mul_f32_e32 v25, v31, v31
	v_fmac_f32_e32 v24, v28, v28
	v_fmac_f32_e32 v25, v30, v30
	v_add_f32_e32 v24, v24, v25
	v_mul_f32_e32 v25, v27, v27
	v_mul_f32_e32 v34, v33, v33
	v_fmac_f32_e32 v25, v26, v26
	v_fmac_f32_e32 v34, v32, v32
	v_add_f32_e32 v25, v25, v34
	v_add_f32_e32 v34, v24, v25
	v_cvt_pk_bf16_f32 v24, v28, v29
	v_lshl_add_u64 v[28:29], s[26:27], 0, v[94:95]
	v_cvt_pk_bf16_f32 v25, v30, v31
	v_cvt_pk_bf16_f32 v26, v26, v27
	v_cvt_pk_bf16_f32 v27, v32, v33
	v_lshl_add_u64 v[28:29], v[168:169], 1, v[28:29]
	global_store_dwordx4 v[28:29], v[24:27], off sc1
	s_waitcnt vmcnt(7)
	v_lshlrev_b32_e32 v30, 16, v74
	v_and_b32_e32 v31, 0xffff0000, v74
	v_lshlrev_b32_e32 v24, 16, v72
	v_and_b32_e32 v25, 0xffff0000, v72
	v_lshlrev_b32_e32 v26, 16, v73
	v_and_b32_e32 v27, 0xffff0000, v73
	v_lshlrev_b32_e32 v32, 16, v75
	v_and_b32_e32 v33, 0xffff0000, v75
	v_pk_add_f32 v[22:23], v[22:23], v[26:27]
	v_pk_add_f32 v[20:21], v[20:21], v[24:25]
	v_pk_add_f32 v[24:25], v[18:19], v[32:33]
	v_pk_add_f32 v[18:19], v[16:17], v[30:31]
	v_mul_f32_e32 v16, v21, v21
	v_mul_f32_e32 v17, v23, v23
	v_fmac_f32_e32 v16, v20, v20
	v_fmac_f32_e32 v17, v22, v22
	v_add_f32_e32 v16, v16, v17
	v_mul_f32_e32 v17, v19, v19
	v_mul_f32_e32 v26, v25, v25
	v_fmac_f32_e32 v17, v18, v18
	v_fmac_f32_e32 v26, v24, v24
	v_add_f32_e32 v17, v17, v26
	v_add_f32_e32 v16, v16, v17
	v_add_f32_e32 v26, v34, v16
	v_cvt_pk_bf16_f32 v16, v20, v21
	v_cvt_pk_bf16_f32 v17, v22, v23
	v_cvt_pk_bf16_f32 v18, v18, v19
	v_cvt_pk_bf16_f32 v19, v24, v25
	global_store_dwordx4 v[28:29], v[16:19], off offset:256 sc1
	s_nop 1
	v_mov_b32_e32 v16, v201
	v_mov_b32_e32 v17, v201
	v_lshlrev_b32_e32 v16, 2, v16
	v_xor_b32_e32 v16, 64, v16
	v_mov_b32_e32 v16, v26
	s_nop 1
	v_permlane16_swap_b32_e32 v16, v26
	s_waitcnt lgkmcnt(0)
	v_add_f32_e32 v16, v26, v16
	v_lshlrev_b32_e32 v17, 2, v17
	v_xor_b32_e32 v17, 0x80, v17
	v_mov_b32_e32 v17, v16
	s_nop 1
	v_permlane32_swap_b32_e32 v17, v16
	s_and_saveexec_b64 s[52:53], s[16:17]
	s_cbranch_execz .LBB0_1095
	s_waitcnt lgkmcnt(0)
	v_add_f32_e32 v18, v16, v17
	v_lshlrev_b64 v[16:17], 6, v[92:93]
	v_lshl_add_u64 v[16:17], s[42:43], 0, v[16:17]
	v_lshl_add_u64 v[16:17], s[50:51], 2, v[16:17]
	s_lshl_b32 s22, s61, 2
	v_lshl_add_u64 v[16:17], v[16:17], 0, s[22:23]
	global_store_dword v[16:17], v18, off sc1
.LBB0_1095:
	s_or_b64 exec, exec, s[52:53]
	s_waitcnt vmcnt(7)
	v_lshlrev_b32_e32 v16, 16, v68
	s_waitcnt lgkmcnt(0)
	v_and_b32_e32 v17, 0xffff0000, v68
	v_lshlrev_b32_e32 v18, 16, v69
	v_and_b32_e32 v19, 0xffff0000, v69
	v_lshlrev_b32_e32 v20, 16, v70
	v_and_b32_e32 v21, 0xffff0000, v70
	v_lshlrev_b32_e32 v22, 16, v71
	v_and_b32_e32 v23, 0xffff0000, v71
	v_pk_add_f32 v[14:15], v[14:15], v[18:19]
	v_pk_add_f32 v[12:13], v[12:13], v[16:17]
	v_pk_add_f32 v[16:17], v[10:11], v[22:23]
	v_pk_add_f32 v[10:11], v[8:9], v[20:21]
	v_mul_f32_e32 v8, v13, v13
	v_mul_f32_e32 v9, v15, v15
	v_fmac_f32_e32 v8, v12, v12
	v_fmac_f32_e32 v9, v14, v14
	v_add_f32_e32 v8, v8, v9
	v_mul_f32_e32 v9, v11, v11
	v_mul_f32_e32 v18, v17, v17
	v_fmac_f32_e32 v9, v10, v10
	v_fmac_f32_e32 v18, v16, v16
	v_add_f32_e32 v9, v9, v18
	v_add_f32_e32 v18, v8, v9
	v_cvt_pk_bf16_f32 v8, v12, v13
	v_lshl_add_u64 v[12:13], s[26:27], 0, v[90:91]
	v_cvt_pk_bf16_f32 v9, v14, v15
	v_cvt_pk_bf16_f32 v10, v10, v11
	v_cvt_pk_bf16_f32 v11, v16, v17
	v_lshl_add_u64 v[12:13], v[168:169], 1, v[12:13]
	global_store_dwordx4 v[12:13], v[8:11], off sc1
	s_waitcnt vmcnt(7)
	v_lshlrev_b32_e32 v14, 16, v66
	v_and_b32_e32 v15, 0xffff0000, v66
	v_lshlrev_b32_e32 v8, 16, v64
	v_and_b32_e32 v9, 0xffff0000, v64
	v_lshlrev_b32_e32 v10, 16, v65
	v_and_b32_e32 v11, 0xffff0000, v65
	v_lshlrev_b32_e32 v16, 16, v67
	v_and_b32_e32 v17, 0xffff0000, v67
	v_pk_add_f32 v[6:7], v[6:7], v[10:11]
	v_pk_add_f32 v[4:5], v[4:5], v[8:9]
	v_pk_add_f32 v[8:9], v[2:3], v[16:17]
	v_pk_add_f32 v[2:3], v[0:1], v[14:15]
	v_mul_f32_e32 v0, v5, v5
	v_mul_f32_e32 v1, v7, v7
	v_fmac_f32_e32 v0, v4, v4
	v_fmac_f32_e32 v1, v6, v6
	v_add_f32_e32 v0, v0, v1
	v_mul_f32_e32 v1, v3, v3
	v_mul_f32_e32 v10, v9, v9
	v_fmac_f32_e32 v1, v2, v2
	v_fmac_f32_e32 v10, v8, v8
	v_add_f32_e32 v1, v1, v10
	v_add_f32_e32 v0, v0, v1
	v_add_f32_e32 v10, v18, v0
	v_cvt_pk_bf16_f32 v0, v4, v5
	v_cvt_pk_bf16_f32 v1, v6, v7
	v_cvt_pk_bf16_f32 v2, v2, v3
	v_cvt_pk_bf16_f32 v3, v8, v9
	global_store_dwordx4 v[12:13], v[0:3], off offset:256 sc1
	s_nop 1
	v_mov_b32_e32 v0, v201
	v_mov_b32_e32 v1, v201
	v_lshlrev_b32_e32 v0, 2, v0
	v_xor_b32_e32 v0, 64, v0
	v_mov_b32_e32 v0, v10
	s_nop 1
	v_permlane16_swap_b32_e32 v0, v10
	s_waitcnt lgkmcnt(0)
	v_add_f32_e32 v0, v10, v0
	v_lshlrev_b32_e32 v1, 2, v1
	v_xor_b32_e32 v1, 0x80, v1
	v_mov_b32_e32 v1, v0
	s_nop 1
	v_permlane32_swap_b32_e32 v1, v0
	s_and_saveexec_b64 s[52:53], s[16:17]
	s_cbranch_execz .LBB0_1097
	s_waitcnt lgkmcnt(0)
	v_add_f32_e32 v2, v0, v1
	v_lshlrev_b64 v[0:1], 6, v[88:89]
	v_lshl_add_u64 v[0:1], s[42:43], 0, v[0:1]
	v_lshl_add_u64 v[0:1], s[50:51], 2, v[0:1]
	s_lshl_b32 s22, s61, 2
	v_lshl_add_u64 v[0:1], v[0:1], 0, s[22:23]
	global_store_dword v[0:1], v2, off sc1

; __device__ __forceinline__ float row_finish(float t) { t += shx(t, 16); t += shx(t, 32); return __builtin_amdgcn_rsqf(t * (1.0f / 1024.0f) + RMS_EPS); }
; __device__ __forceinline__ f32x4 silu4(f32x4 v) { return (f32x4){silu_f(v[0]), silu_f(v[1]), silu_f(v[2]), silu_f(v[3])}; }
; __device__ __forceinline__ float sq4(f32x4 v) { return (v[0] * v[0] + v[1] * v[1]) + (v[2] * v[2] + v[3] * v[3]); }
; __device__ __forceinline__ u32x4 pack8(f32x4 a, f32x4 b) { u32x4 w; w.x = cvt_pk_bf16(a[0], a[1]); w.y = cvt_pk_bf16(a[2], a[3]); w.z = cvt_pk_bf16(b[0], b[1]); w.w = cvt_pk_bf16(b[2], b[3]); return w; }
;     __device__ __forceinline__ void operator()(const f32x4 (&acc)[2][2][4][2], const Unit& u, int wr, int wc, int fr, int fq) const {
;     ...
;             for (int m = 0; m < 4; ++m) rs[ai][m] = row_finish(rs[ai][m]);
; #pragma unroll
;         for (int ai = 0; ai < 2; ++ai)
; #pragma unroll
;             for (int m = 0; m < 4; ++m) {
;                 const int row = u.pm * BM + ai * HALF + wr * 64 + m * 16 + fr;
;                 const float rstd = rs[ai][m];
;                 f32x4 v[2][2];
; #pragma unroll
;                 for (int bj = 0; bj < 2; ++bj)
; #pragma unroll
;                     for (int n = 0; n < 2; ++n) v[bj][n] = acc[ai][bj][m][n] * rstd;
;                 if (mode == 2) {
;                     float q = (sq4(v[0][0]) + sq4(v[0][1])) + (sq4(v[1][0]) + sq4(v[1][1]));
;                     q += shx(q, 16); q += shx(q, 32);
;                     const float r2 = __builtin_amdgcn_rsqf(q * (1.0f / 64.0f) + RMS_EPS);
; #pragma unroll
;                     for (int bj = 0; bj < 2; ++bj)
; #pragma unroll
;                         for (int n = 0; n < 2; ++n) v[bj][n] = v[bj][n] * r2 * wv[bj][n];
;                 } else if (mode == 1) {
; #pragma unroll
;                     for (int bj = 0; bj < 2; ++bj)
; #pragma unroll
;                         for (int n = 0; n < 2; ++n) v[bj][n] = silu4(v[bj][n]);
;                 } else {
; #pragma unroll
;                     for (int bj = 0; bj < 2; ++bj)
; #pragma unroll
;                         for (int n = 0; n < 2; ++n) v[bj][n] = v[bj][n] * sc;
;                 }
;                 bf16_t* rowp = U + (size_t)row * 2560 + lcol;
; #pragma unroll
;                 for (int bj = 0; bj < 2; ++bj) *(u32x4*)(rowp + 32 * bj) = pack8(v[bj][0], v[bj][1]);
.LBB0_1198:
	v_add_f32_e32 v170, v212, v213
	v_fmamk_f32 v170, v170, 0x3a800000, v202
	v_rsq_f32_e32 v178, v170
	v_lshl_or_b32 v170, s50, 8, v197
	v_mov_b64_e32 v[180:181], s[18:19]
	v_ashrrev_i32_e32 v171, 31, v170
	v_mad_i64_i32 v[180:181], s[50:51], v176, s12, v[180:181]
	v_lshl_add_u64 v[180:181], v[170:171], 1, v[180:181]
	v_cvt_pk_bf16_f32 v112, v112, v113
	v_cvt_pk_bf16_f32 v113, v114, v115
	v_cvt_pk_bf16_f32 v114, v116, v117
	v_cvt_pk_bf16_f32 v115, v118, v119
	global_store_dwordx4 v[180:181], v[112:115], off sc1
	v_pk_mul_f32 v[116:117], v[102:103], v[178:179] op_sel_hi:[1,0]
	v_pk_mul_f32 v[118:119], v[100:101], v[178:179] op_sel_hi:[1,0]
	v_cvt_pk_bf16_f32 v112, v120, v121
	v_cvt_pk_bf16_f32 v113, v122, v123
	v_cvt_pk_bf16_f32 v114, v124, v125
	v_cvt_pk_bf16_f32 v115, v126, v127
	global_store_dwordx4 v[180:181], v[112:115], off offset:64 sc1
	v_pk_mul_f32 v[124:125], v[110:111], v[178:179] op_sel_hi:[1,0]
	v_pk_mul_f32 v[126:127], v[108:109], v[178:179] op_sel_hi:[1,0]
	v_pk_mul_f32 v[120:121], v[106:107], v[178:179] op_sel_hi:[1,0]
	v_pk_mul_f32 v[122:123], v[104:105], v[178:179] op_sel_hi:[1,0]
	v_pk_mul_f32 v[114:115], v[98:99], v[178:179] op_sel_hi:[1,0]
	v_pk_mul_f32 v[112:113], v[96:97], v[178:179] op_sel_hi:[1,0]
	s_mov_b64 s[50:51], -1
	s_and_b64 vcc, exec, s[48:49]
	s_cbranch_vccz .LBB0_1200
	v_mov_b32_e32 v98, v127
	v_mov_b32_e32 v99, v119
	v_mov_b32_e32 v96, v126
	v_mov_b32_e32 v97, v118
	v_pk_mul_f32 v[98:99], v[98:99], v[98:99]
	v_mov_b32_e32 v100, v125
	v_mov_b32_e32 v101, v117
	v_pk_fma_f32 v[96:97], v[96:97], v[96:97], v[98:99]
	v_mov_b32_e32 v98, v124
	v_mov_b32_e32 v99, v116
	v_pk_mul_f32 v[100:101], v[100:101], v[100:101]
	v_mov_b32_e32 v102, v121
	v_pk_fma_f32 v[98:99], v[98:99], v[98:99], v[100:101]
	v_mov_b32_e32 v100, v123
	v_mov_b32_e32 v101, v113
	v_pk_add_f32 v[96:97], v[96:97], v[98:99]
	v_mov_b32_e32 v98, v122
	v_mov_b32_e32 v99, v112
	v_pk_mul_f32 v[100:101], v[100:101], v[100:101]
	v_mov_b32_e32 v103, v115
	v_pk_fma_f32 v[98:99], v[98:99], v[98:99], v[100:101]
	v_mov_b32_e32 v100, v120
	v_mov_b32_e32 v101, v114
	v_pk_mul_f32 v[102:103], v[102:103], v[102:103]
	s_mov_b64 s[50:51], 0
	v_pk_fma_f32 v[100:101], v[100:101], v[100:101], v[102:103]
	s_nop 0
	v_pk_add_f32 v[98:99], v[98:99], v[100:101]
	s_nop 0
	v_pk_add_f32 v[96:97], v[96:97], v[98:99]
	s_nop 0
	v_add_f32_e32 v96, v96, v97
	v_mov_b32_e32 v97, v201
	s_nop 0
	v_lshlrev_b32_e32 v97, 2, v97
	v_xor_b32_e32 v97, 64, v97
	v_mov_b32_e32 v97, v96
	s_nop 1
	v_permlane16_swap_b32_e32 v97, v96
	s_waitcnt lgkmcnt(0)
	v_add_f32_e32 v96, v96, v97
	v_mov_b32_e32 v97, v201
	s_nop 0
	v_lshlrev_b32_e32 v97, 2, v97
	v_xor_b32_e32 v97, 0x80, v97
	v_mov_b32_e32 v97, v96
	s_nop 1
	v_permlane32_swap_b32_e32 v97, v96
	s_waitcnt lgkmcnt(0)
	v_add_f32_e32 v96, v96, v97
	v_fmamk_f32 v96, v96, 0x3c800000, v202
	v_rsq_f32_e32 v108, v96
	s_nop 0
	v_pk_mul_f32 v[96:97], v[126:127], v[108:109] op_sel_hi:[1,0]
	v_pk_mul_f32 v[98:99], v[124:125], v[108:109] op_sel_hi:[1,0]
	v_pk_mul_f32 v[100:101], v[122:123], v[108:109] op_sel_hi:[1,0]
	v_pk_mul_f32 v[102:103], v[120:121], v[108:109] op_sel_hi:[1,0]
	v_pk_mul_f32 v[104:105], v[118:119], v[108:109] op_sel_hi:[1,0]
	v_pk_mul_f32 v[106:107], v[116:117], v[108:109] op_sel_hi:[1,0]
	v_pk_mul_f32 v[178:179], v[112:113], v[108:109] op_sel_hi:[1,0]
	v_pk_mul_f32 v[108:109], v[114:115], v[108:109] op_sel_hi:[1,0]
	v_pk_mul_f32 v[98:99], v[156:157], v[98:99]
	v_pk_mul_f32 v[96:97], v[160:161], v[96:97]
	v_pk_mul_f32 v[102:103], v[150:151], v[102:103]
	v_pk_mul_f32 v[100:101], v[152:153], v[100:101]
	v_pk_mul_f32 v[106:107], v[162:163], v[106:107]
	v_pk_mul_f32 v[104:105], v[164:165], v[104:105]
	v_pk_mul_f32 v[110:111], v[154:155], v[108:109]
	v_pk_mul_f32 v[108:109], v[158:159], v[178:179]

; __device__ __forceinline__ f32x4 silu4(f32x4 v) { return (f32x4){silu_f(v[0]), silu_f(v[1]), silu_f(v[2]), silu_f(v[3])}; }
; __device__ __forceinline__ float sq4(f32x4 v) { return (v[0] * v[0] + v[1] * v[1]) + (v[2] * v[2] + v[3] * v[3]); }
; __device__ __forceinline__ u32x4 pack8(f32x4 a, f32x4 b) { u32x4 w; w.x = cvt_pk_bf16(a[0], a[1]); w.y = cvt_pk_bf16(a[2], a[3]); w.z = cvt_pk_bf16(b[0], b[1]); w.w = cvt_pk_bf16(b[2], b[3]); return w; }
;     __device__ __forceinline__ void operator()(const f32x4 (&acc)[2][2][4][2], const Unit& u, int wr, int wc, int fr, int fq) const {
;     ...
;                 const int row = u.pm * BM + ai * HALF + wr * 64 + m * 16 + fr;
;                 const float rstd = rs[ai][m];
;                 f32x4 v[2][2];
; #pragma unroll
;                 for (int bj = 0; bj < 2; ++bj)
; #pragma unroll
;                     for (int n = 0; n < 2; ++n) v[bj][n] = acc[ai][bj][m][n] * rstd;
;                 if (mode == 2) {
;                     float q = (sq4(v[0][0]) + sq4(v[0][1])) + (sq4(v[1][0]) + sq4(v[1][1]));
;                     q += shx(q, 16); q += shx(q, 32);
;                     const float r2 = __builtin_amdgcn_rsqf(q * (1.0f / 64.0f) + RMS_EPS);
; #pragma unroll
;                     for (int bj = 0; bj < 2; ++bj)
; #pragma unroll
;                         for (int n = 0; n < 2; ++n) v[bj][n] = v[bj][n] * r2 * wv[bj][n];
;                 } else if (mode == 1) {
; #pragma unroll
;                     for (int bj = 0; bj < 2; ++bj)
; #pragma unroll
;                         for (int n = 0; n < 2; ++n) v[bj][n] = silu4(v[bj][n]);
;                 } else {
; #pragma unroll
;                     for (int bj = 0; bj < 2; ++bj)
; #pragma unroll
;                         for (int n = 0; n < 2; ++n) v[bj][n] = v[bj][n] * sc;
;                 }
;                 bf16_t* rowp = U + (size_t)row * 2560 + lcol;
; #pragma unroll
;                 for (int bj = 0; bj < 2; ++bj) *(u32x4*)(rowp + 32 * bj) = pack8(v[bj][0], v[bj][1]);
.LBB0_1205:
	v_add_f32_e32 v112, v210, v211
	v_fmamk_f32 v112, v112, 0x3a800000, v202
	v_add_u32_e32 v113, s0, v194
	v_rsq_f32_e32 v112, v112
	v_mov_b64_e32 v[114:115], s[18:19]
	v_mad_i64_i32 v[114:115], s[50:51], v113, s12, v[114:115]
	v_lshl_add_u64 v[114:115], v[170:171], 1, v[114:115]
	v_cvt_pk_bf16_f32 v96, v96, v97
	v_cvt_pk_bf16_f32 v97, v98, v99
	v_cvt_pk_bf16_f32 v98, v100, v101
	v_cvt_pk_bf16_f32 v99, v102, v103
	global_store_dwordx4 v[114:115], v[96:99], off sc1
	v_pk_mul_f32 v[100:101], v[86:87], v[112:113] op_sel_hi:[1,0]
	v_pk_mul_f32 v[102:103], v[84:85], v[112:113] op_sel_hi:[1,0]
	v_cvt_pk_bf16_f32 v96, v104, v105
	v_cvt_pk_bf16_f32 v97, v106, v107
	v_cvt_pk_bf16_f32 v98, v108, v109
	v_cvt_pk_bf16_f32 v99, v110, v111
	global_store_dwordx4 v[114:115], v[96:99], off offset:64 sc1
	v_pk_mul_f32 v[108:109], v[94:95], v[112:113] op_sel_hi:[1,0]
	v_pk_mul_f32 v[110:111], v[92:93], v[112:113] op_sel_hi:[1,0]
	v_pk_mul_f32 v[104:105], v[90:91], v[112:113] op_sel_hi:[1,0]
	v_pk_mul_f32 v[106:107], v[88:89], v[112:113] op_sel_hi:[1,0]
	v_pk_mul_f32 v[98:99], v[82:83], v[112:113] op_sel_hi:[1,0]
	v_pk_mul_f32 v[96:97], v[80:81], v[112:113] op_sel_hi:[1,0]
	s_mov_b64 s[50:51], -1
	s_and_b64 vcc, exec, s[48:49]
	s_cbranch_vccz .LBB0_1207
	v_mov_b32_e32 v82, v111
	v_mov_b32_e32 v83, v103
	v_mov_b32_e32 v80, v110
	v_mov_b32_e32 v81, v102
	v_pk_mul_f32 v[82:83], v[82:83], v[82:83]
	v_mov_b32_e32 v84, v109
	v_mov_b32_e32 v85, v101
	v_pk_fma_f32 v[80:81], v[80:81], v[80:81], v[82:83]
	v_mov_b32_e32 v82, v108
	v_mov_b32_e32 v83, v100
	v_pk_mul_f32 v[84:85], v[84:85], v[84:85]
	v_mov_b32_e32 v86, v105
	v_pk_fma_f32 v[82:83], v[82:83], v[82:83], v[84:85]
	v_mov_b32_e32 v84, v107
	v_mov_b32_e32 v85, v97
	v_pk_add_f32 v[80:81], v[80:81], v[82:83]
	v_mov_b32_e32 v82, v106
	v_mov_b32_e32 v83, v96
	v_pk_mul_f32 v[84:85], v[84:85], v[84:85]
	v_mov_b32_e32 v87, v99
	v_pk_fma_f32 v[82:83], v[82:83], v[82:83], v[84:85]
	v_mov_b32_e32 v84, v104
	v_mov_b32_e32 v85, v98
	v_pk_mul_f32 v[86:87], v[86:87], v[86:87]
	s_mov_b64 s[50:51], 0
	v_pk_fma_f32 v[84:85], v[84:85], v[84:85], v[86:87]
	s_nop 0
	v_pk_add_f32 v[82:83], v[82:83], v[84:85]
	s_nop 0
	v_pk_add_f32 v[80:81], v[80:81], v[82:83]
	s_nop 0
	v_add_f32_e32 v80, v80, v81
	v_mov_b32_e32 v81, v201
	s_nop 0
	v_lshlrev_b32_e32 v81, 2, v81
	v_xor_b32_e32 v81, 64, v81
	v_mov_b32_e32 v81, v80
	s_nop 1
	v_permlane16_swap_b32_e32 v81, v80
	s_waitcnt lgkmcnt(0)
	v_add_f32_e32 v80, v80, v81
	v_mov_b32_e32 v81, v201
	s_nop 0
	v_lshlrev_b32_e32 v81, 2, v81
	v_xor_b32_e32 v81, 0x80, v81
	v_mov_b32_e32 v81, v80
	s_nop 1
	v_permlane32_swap_b32_e32 v81, v80
	s_waitcnt lgkmcnt(0)
	v_add_f32_e32 v80, v80, v81
	v_fmamk_f32 v80, v80, 0x3c800000, v202
	v_rsq_f32_e32 v92, v80
	s_nop 0
	v_pk_mul_f32 v[80:81], v[110:111], v[92:93] op_sel_hi:[1,0]
	v_pk_mul_f32 v[82:83], v[108:109], v[92:93] op_sel_hi:[1,0]
	v_pk_mul_f32 v[84:85], v[106:107], v[92:93] op_sel_hi:[1,0]
	v_pk_mul_f32 v[86:87], v[104:105], v[92:93] op_sel_hi:[1,0]
	v_pk_mul_f32 v[88:89], v[102:103], v[92:93] op_sel_hi:[1,0]
	v_pk_mul_f32 v[90:91], v[100:101], v[92:93] op_sel_hi:[1,0]
	v_pk_mul_f32 v[112:113], v[96:97], v[92:93] op_sel_hi:[1,0]
	v_pk_mul_f32 v[92:93], v[98:99], v[92:93] op_sel_hi:[1,0]
	v_pk_mul_f32 v[82:83], v[156:157], v[82:83]
	v_pk_mul_f32 v[80:81], v[160:161], v[80:81]
	v_pk_mul_f32 v[86:87], v[150:151], v[86:87]
	v_pk_mul_f32 v[84:85], v[152:153], v[84:85]
	v_pk_mul_f32 v[90:91], v[162:163], v[90:91]
	v_pk_mul_f32 v[88:89], v[164:165], v[88:89]
	v_pk_mul_f32 v[94:95], v[154:155], v[92:93]
	v_pk_mul_f32 v[92:93], v[158:159], v[112:113]

; __device__ __forceinline__ f32x4 silu4(f32x4 v) { return (f32x4){silu_f(v[0]), silu_f(v[1]), silu_f(v[2]), silu_f(v[3])}; }
; __device__ __forceinline__ float sq4(f32x4 v) { return (v[0] * v[0] + v[1] * v[1]) + (v[2] * v[2] + v[3] * v[3]); }
; __device__ __forceinline__ u32x4 pack8(f32x4 a, f32x4 b) { u32x4 w; w.x = cvt_pk_bf16(a[0], a[1]); w.y = cvt_pk_bf16(a[2], a[3]); w.z = cvt_pk_bf16(b[0], b[1]); w.w = cvt_pk_bf16(b[2], b[3]); return w; }
;     __device__ __forceinline__ void operator()(const f32x4 (&acc)[2][2][4][2], const Unit& u, int wr, int wc, int fr, int fq) const {
;     ...
;                 const int row = u.pm * BM + ai * HALF + wr * 64 + m * 16 + fr;
;                 const float rstd = rs[ai][m];
;                 f32x4 v[2][2];
; #pragma unroll
;                 for (int bj = 0; bj < 2; ++bj)
; #pragma unroll
;                     for (int n = 0; n < 2; ++n) v[bj][n] = acc[ai][bj][m][n] * rstd;
;                 if (mode == 2) {
;                     float q = (sq4(v[0][0]) + sq4(v[0][1])) + (sq4(v[1][0]) + sq4(v[1][1]));
;                     q += shx(q, 16); q += shx(q, 32);
;                     const float r2 = __builtin_amdgcn_rsqf(q * (1.0f / 64.0f) + RMS_EPS);
; #pragma unroll
;                     for (int bj = 0; bj < 2; ++bj)
; #pragma unroll
;                         for (int n = 0; n < 2; ++n) v[bj][n] = v[bj][n] * r2 * wv[bj][n];
;                 } else if (mode == 1) {
; #pragma unroll
;                     for (int bj = 0; bj < 2; ++bj)
; #pragma unroll
;                         for (int n = 0; n < 2; ++n) v[bj][n] = silu4(v[bj][n]);
;                 } else {
; #pragma unroll
;                     for (int bj = 0; bj < 2; ++bj)
; #pragma unroll
;                         for (int n = 0; n < 2; ++n) v[bj][n] = v[bj][n] * sc;
;                 }
;                 bf16_t* rowp = U + (size_t)row * 2560 + lcol;
; #pragma unroll
;                 for (int bj = 0; bj < 2; ++bj) *(u32x4*)(rowp + 32 * bj) = pack8(v[bj][0], v[bj][1]);
.LBB0_1212:
	v_add_f32_e32 v96, v208, v209
	v_fmamk_f32 v96, v96, 0x3a800000, v202
	v_add_u32_e32 v97, s0, v195
	v_rsq_f32_e32 v96, v96
	v_mov_b64_e32 v[98:99], s[18:19]
	v_mad_i64_i32 v[98:99], s[50:51], v97, s12, v[98:99]
	v_lshl_add_u64 v[98:99], v[170:171], 1, v[98:99]
	v_cvt_pk_bf16_f32 v80, v80, v81
	v_cvt_pk_bf16_f32 v81, v82, v83
	v_cvt_pk_bf16_f32 v82, v84, v85
	v_cvt_pk_bf16_f32 v83, v86, v87
	global_store_dwordx4 v[98:99], v[80:83], off sc1
	v_pk_mul_f32 v[84:85], v[70:71], v[96:97] op_sel_hi:[1,0]
	v_pk_mul_f32 v[86:87], v[68:69], v[96:97] op_sel_hi:[1,0]
	v_cvt_pk_bf16_f32 v80, v88, v89
	v_cvt_pk_bf16_f32 v81, v90, v91
	v_cvt_pk_bf16_f32 v82, v92, v93
	v_cvt_pk_bf16_f32 v83, v94, v95
	global_store_dwordx4 v[98:99], v[80:83], off offset:64 sc1
	v_pk_mul_f32 v[92:93], v[78:79], v[96:97] op_sel_hi:[1,0]
	v_pk_mul_f32 v[94:95], v[76:77], v[96:97] op_sel_hi:[1,0]
	v_pk_mul_f32 v[88:89], v[74:75], v[96:97] op_sel_hi:[1,0]
	v_pk_mul_f32 v[90:91], v[72:73], v[96:97] op_sel_hi:[1,0]
	v_pk_mul_f32 v[82:83], v[66:67], v[96:97] op_sel_hi:[1,0]
	v_pk_mul_f32 v[80:81], v[64:65], v[96:97] op_sel_hi:[1,0]
	s_mov_b64 s[50:51], -1
	s_and_b64 vcc, exec, s[48:49]
	s_cbranch_vccz .LBB0_1214
	v_mov_b32_e32 v66, v95
	v_mov_b32_e32 v67, v87
	v_mov_b32_e32 v64, v94
	v_mov_b32_e32 v65, v86
	v_pk_mul_f32 v[66:67], v[66:67], v[66:67]
	v_mov_b32_e32 v68, v93
	v_mov_b32_e32 v69, v85
	v_pk_fma_f32 v[64:65], v[64:65], v[64:65], v[66:67]
	v_mov_b32_e32 v66, v92
	v_mov_b32_e32 v67, v84
	v_pk_mul_f32 v[68:69], v[68:69], v[68:69]
	v_mov_b32_e32 v70, v89
	v_pk_fma_f32 v[66:67], v[66:67], v[66:67], v[68:69]
	v_mov_b32_e32 v68, v91
	v_mov_b32_e32 v69, v81
	v_pk_add_f32 v[64:65], v[64:65], v[66:67]
	v_mov_b32_e32 v66, v90
	v_mov_b32_e32 v67, v80
	v_pk_mul_f32 v[68:69], v[68:69], v[68:69]
	v_mov_b32_e32 v71, v83
	v_pk_fma_f32 v[66:67], v[66:67], v[66:67], v[68:69]
	v_mov_b32_e32 v68, v88
	v_mov_b32_e32 v69, v82
	v_pk_mul_f32 v[70:71], v[70:71], v[70:71]
	s_mov_b64 s[50:51], 0
	v_pk_fma_f32 v[68:69], v[68:69], v[68:69], v[70:71]
	s_nop 0
	v_pk_add_f32 v[66:67], v[66:67], v[68:69]
	s_nop 0
	v_pk_add_f32 v[64:65], v[64:65], v[66:67]
	s_nop 0
	v_add_f32_e32 v64, v64, v65
	v_mov_b32_e32 v65, v201
	s_nop 0
	v_lshlrev_b32_e32 v65, 2, v65
	v_xor_b32_e32 v65, 64, v65
	v_mov_b32_e32 v65, v64
	s_nop 1
	v_permlane16_swap_b32_e32 v65, v64
	s_waitcnt lgkmcnt(0)
	v_add_f32_e32 v64, v64, v65
	v_mov_b32_e32 v65, v201
	s_nop 0
	v_lshlrev_b32_e32 v65, 2, v65
	v_xor_b32_e32 v65, 0x80, v65
	v_mov_b32_e32 v65, v64
	s_nop 1
	v_permlane32_swap_b32_e32 v65, v64
	s_waitcnt lgkmcnt(0)
	v_add_f32_e32 v64, v64, v65
	v_fmamk_f32 v64, v64, 0x3c800000, v202
	v_rsq_f32_e32 v76, v64
	s_nop 0
	v_pk_mul_f32 v[64:65], v[94:95], v[76:77] op_sel_hi:[1,0]
	v_pk_mul_f32 v[66:67], v[92:93], v[76:77] op_sel_hi:[1,0]
	v_pk_mul_f32 v[68:69], v[90:91], v[76:77] op_sel_hi:[1,0]
	v_pk_mul_f32 v[70:71], v[88:89], v[76:77] op_sel_hi:[1,0]
	v_pk_mul_f32 v[72:73], v[86:87], v[76:77] op_sel_hi:[1,0]
	v_pk_mul_f32 v[74:75], v[84:85], v[76:77] op_sel_hi:[1,0]
	v_pk_mul_f32 v[96:97], v[80:81], v[76:77] op_sel_hi:[1,0]
	v_pk_mul_f32 v[76:77], v[82:83], v[76:77] op_sel_hi:[1,0]
	v_pk_mul_f32 v[66:67], v[156:157], v[66:67]
	v_pk_mul_f32 v[64:65], v[160:161], v[64:65]
	v_pk_mul_f32 v[70:71], v[150:151], v[70:71]
	v_pk_mul_f32 v[68:69], v[152:153], v[68:69]
	v_pk_mul_f32 v[74:75], v[162:163], v[74:75]
	v_pk_mul_f32 v[72:73], v[164:165], v[72:73]
	v_pk_mul_f32 v[78:79], v[154:155], v[76:77]
	v_pk_mul_f32 v[76:77], v[158:159], v[96:97]

; __device__ __forceinline__ f32x4 silu4(f32x4 v) { return (f32x4){silu_f(v[0]), silu_f(v[1]), silu_f(v[2]), silu_f(v[3])}; }
; __device__ __forceinline__ float sq4(f32x4 v) { return (v[0] * v[0] + v[1] * v[1]) + (v[2] * v[2] + v[3] * v[3]); }
; __device__ __forceinline__ u32x4 pack8(f32x4 a, f32x4 b) { u32x4 w; w.x = cvt_pk_bf16(a[0], a[1]); w.y = cvt_pk_bf16(a[2], a[3]); w.z = cvt_pk_bf16(b[0], b[1]); w.w = cvt_pk_bf16(b[2], b[3]); return w; }
;     __device__ __forceinline__ void operator()(const f32x4 (&acc)[2][2][4][2], const Unit& u, int wr, int wc, int fr, int fq) const {
;     ...
;                 const int row = u.pm * BM + ai * HALF + wr * 64 + m * 16 + fr;
;                 const float rstd = rs[ai][m];
;                 f32x4 v[2][2];
; #pragma unroll
;                 for (int bj = 0; bj < 2; ++bj)
; #pragma unroll
;                     for (int n = 0; n < 2; ++n) v[bj][n] = acc[ai][bj][m][n] * rstd;
;                 if (mode == 2) {
;                     float q = (sq4(v[0][0]) + sq4(v[0][1])) + (sq4(v[1][0]) + sq4(v[1][1]));
;                     q += shx(q, 16); q += shx(q, 32);
;                     const float r2 = __builtin_amdgcn_rsqf(q * (1.0f / 64.0f) + RMS_EPS);
; #pragma unroll
;                     for (int bj = 0; bj < 2; ++bj)
; #pragma unroll
;                         for (int n = 0; n < 2; ++n) v[bj][n] = v[bj][n] * r2 * wv[bj][n];
;                 } else if (mode == 1) {
; #pragma unroll
;                     for (int bj = 0; bj < 2; ++bj)
; #pragma unroll
;                         for (int n = 0; n < 2; ++n) v[bj][n] = silu4(v[bj][n]);
;                 } else {
; #pragma unroll
;                     for (int bj = 0; bj < 2; ++bj)
; #pragma unroll
;                         for (int n = 0; n < 2; ++n) v[bj][n] = v[bj][n] * sc;
;                 }
;                 bf16_t* rowp = U + (size_t)row * 2560 + lcol;
; #pragma unroll
;                 for (int bj = 0; bj < 2; ++bj) *(u32x4*)(rowp + 32 * bj) = pack8(v[bj][0], v[bj][1]);
.LBB0_1219:
	v_add_f32_e32 v80, v206, v207
	v_fmamk_f32 v80, v80, 0x3a800000, v202
	v_add_u32_e32 v81, s0, v196
	v_rsq_f32_e32 v80, v80
	v_mov_b64_e32 v[82:83], s[18:19]
	v_mad_i64_i32 v[82:83], s[50:51], v81, s12, v[82:83]
	v_lshl_add_u64 v[82:83], v[170:171], 1, v[82:83]
	v_cvt_pk_bf16_f32 v64, v64, v65
	v_cvt_pk_bf16_f32 v65, v66, v67
	v_cvt_pk_bf16_f32 v66, v68, v69
	v_cvt_pk_bf16_f32 v67, v70, v71
	global_store_dwordx4 v[82:83], v[64:67], off sc1
	v_pk_mul_f32 v[68:69], v[54:55], v[80:81] op_sel_hi:[1,0]
	v_pk_mul_f32 v[70:71], v[52:53], v[80:81] op_sel_hi:[1,0]
	v_cvt_pk_bf16_f32 v64, v72, v73
	v_cvt_pk_bf16_f32 v65, v74, v75
	v_cvt_pk_bf16_f32 v66, v76, v77
	v_cvt_pk_bf16_f32 v67, v78, v79
	global_store_dwordx4 v[82:83], v[64:67], off offset:64 sc1
	v_pk_mul_f32 v[76:77], v[62:63], v[80:81] op_sel_hi:[1,0]
	v_pk_mul_f32 v[78:79], v[60:61], v[80:81] op_sel_hi:[1,0]
	v_pk_mul_f32 v[72:73], v[58:59], v[80:81] op_sel_hi:[1,0]
	v_pk_mul_f32 v[74:75], v[56:57], v[80:81] op_sel_hi:[1,0]
	v_pk_mul_f32 v[66:67], v[50:51], v[80:81] op_sel_hi:[1,0]
	v_pk_mul_f32 v[64:65], v[48:49], v[80:81] op_sel_hi:[1,0]
	s_mov_b64 s[50:51], -1
	s_and_b64 vcc, exec, s[48:49]
	s_cbranch_vccz .LBB0_1221
	v_mov_b32_e32 v50, v79
	v_mov_b32_e32 v51, v71
	v_mov_b32_e32 v48, v78
	v_mov_b32_e32 v49, v70
	v_pk_mul_f32 v[50:51], v[50:51], v[50:51]
	v_mov_b32_e32 v52, v77
	v_mov_b32_e32 v53, v69
	v_pk_fma_f32 v[48:49], v[48:49], v[48:49], v[50:51]
	v_mov_b32_e32 v50, v76
	v_mov_b32_e32 v51, v68
	v_pk_mul_f32 v[52:53], v[52:53], v[52:53]
	v_mov_b32_e32 v54, v73
	v_pk_fma_f32 v[50:51], v[50:51], v[50:51], v[52:53]
	v_mov_b32_e32 v52, v75
	v_mov_b32_e32 v53, v65
	v_pk_add_f32 v[48:49], v[48:49], v[50:51]
	v_mov_b32_e32 v50, v74
	v_mov_b32_e32 v51, v64
	v_pk_mul_f32 v[52:53], v[52:53], v[52:53]
	v_mov_b32_e32 v55, v67
	v_pk_fma_f32 v[50:51], v[50:51], v[50:51], v[52:53]
	v_mov_b32_e32 v52, v72
	v_mov_b32_e32 v53, v66
	v_pk_mul_f32 v[54:55], v[54:55], v[54:55]
	s_mov_b64 s[50:51], 0
	v_pk_fma_f32 v[52:53], v[52:53], v[52:53], v[54:55]
	s_nop 0
	v_pk_add_f32 v[50:51], v[50:51], v[52:53]
	s_nop 0
	v_pk_add_f32 v[48:49], v[48:49], v[50:51]
	s_nop 0
	v_add_f32_e32 v48, v48, v49
	v_mov_b32_e32 v49, v201
	s_nop 0
	v_lshlrev_b32_e32 v49, 2, v49
	v_xor_b32_e32 v49, 64, v49
	v_mov_b32_e32 v49, v48
	s_nop 1
	v_permlane16_swap_b32_e32 v49, v48
	s_waitcnt lgkmcnt(0)
	v_add_f32_e32 v48, v48, v49
	v_mov_b32_e32 v49, v201
	s_nop 0
	v_lshlrev_b32_e32 v49, 2, v49
	v_xor_b32_e32 v49, 0x80, v49
	v_mov_b32_e32 v49, v48
	s_nop 1
	v_permlane32_swap_b32_e32 v49, v48
	s_waitcnt lgkmcnt(0)
	v_add_f32_e32 v48, v48, v49
	v_fmamk_f32 v48, v48, 0x3c800000, v202
	v_rsq_f32_e32 v60, v48
	s_nop 0
	v_pk_mul_f32 v[48:49], v[78:79], v[60:61] op_sel_hi:[1,0]
	v_pk_mul_f32 v[50:51], v[76:77], v[60:61] op_sel_hi:[1,0]
	v_pk_mul_f32 v[52:53], v[74:75], v[60:61] op_sel_hi:[1,0]
	v_pk_mul_f32 v[54:55], v[72:73], v[60:61] op_sel_hi:[1,0]
	v_pk_mul_f32 v[56:57], v[70:71], v[60:61] op_sel_hi:[1,0]
	v_pk_mul_f32 v[58:59], v[68:69], v[60:61] op_sel_hi:[1,0]
	v_pk_mul_f32 v[80:81], v[64:65], v[60:61] op_sel_hi:[1,0]
	v_pk_mul_f32 v[60:61], v[66:67], v[60:61] op_sel_hi:[1,0]
	v_pk_mul_f32 v[50:51], v[156:157], v[50:51]
	v_pk_mul_f32 v[48:49], v[160:161], v[48:49]
	v_pk_mul_f32 v[54:55], v[150:151], v[54:55]
	v_pk_mul_f32 v[52:53], v[152:153], v[52:53]
	v_pk_mul_f32 v[58:59], v[162:163], v[58:59]
	v_pk_mul_f32 v[56:57], v[164:165], v[56:57]
	v_pk_mul_f32 v[62:63], v[154:155], v[60:61]
	v_pk_mul_f32 v[60:61], v[158:159], v[80:81]

; __device__ __forceinline__ f32x4 silu4(f32x4 v) { return (f32x4){silu_f(v[0]), silu_f(v[1]), silu_f(v[2]), silu_f(v[3])}; }
; __device__ __forceinline__ float sq4(f32x4 v) { return (v[0] * v[0] + v[1] * v[1]) + (v[2] * v[2] + v[3] * v[3]); }
; __device__ __forceinline__ u32x4 pack8(f32x4 a, f32x4 b) { u32x4 w; w.x = cvt_pk_bf16(a[0], a[1]); w.y = cvt_pk_bf16(a[2], a[3]); w.z = cvt_pk_bf16(b[0], b[1]); w.w = cvt_pk_bf16(b[2], b[3]); return w; }
;     __device__ __forceinline__ void operator()(const f32x4 (&acc)[2][2][4][2], const Unit& u, int wr, int wc, int fr, int fq) const {
;     ...
;                 const int row = u.pm * BM + ai * HALF + wr * 64 + m * 16 + fr;
;                 const float rstd = rs[ai][m];
;                 f32x4 v[2][2];
; #pragma unroll
;                 for (int bj = 0; bj < 2; ++bj)
; #pragma unroll
;                     for (int n = 0; n < 2; ++n) v[bj][n] = acc[ai][bj][m][n] * rstd;
;                 if (mode == 2) {
;                     float q = (sq4(v[0][0]) + sq4(v[0][1])) + (sq4(v[1][0]) + sq4(v[1][1]));
;                     q += shx(q, 16); q += shx(q, 32);
;                     const float r2 = __builtin_amdgcn_rsqf(q * (1.0f / 64.0f) + RMS_EPS);
; #pragma unroll
;                     for (int bj = 0; bj < 2; ++bj)
; #pragma unroll
;                         for (int n = 0; n < 2; ++n) v[bj][n] = v[bj][n] * r2 * wv[bj][n];
;                 } else if (mode == 1) {
; #pragma unroll
;                     for (int bj = 0; bj < 2; ++bj)
; #pragma unroll
;                         for (int n = 0; n < 2; ++n) v[bj][n] = silu4(v[bj][n]);
;                 } else {
; #pragma unroll
;                     for (int bj = 0; bj < 2; ++bj)
; #pragma unroll
;                         for (int n = 0; n < 2; ++n) v[bj][n] = v[bj][n] * sc;
;                 }
;                 bf16_t* rowp = U + (size_t)row * 2560 + lcol;
; #pragma unroll
;                 for (int bj = 0; bj < 2; ++bj) *(u32x4*)(rowp + 32 * bj) = pack8(v[bj][0], v[bj][1]);
.LBB0_1226:
	v_add_f32_e32 v64, v177, v205
	v_fmamk_f32 v64, v64, 0x3a800000, v202
	v_rsq_f32_e32 v64, v64
	v_mov_b64_e32 v[66:67], s[18:19]
	v_mad_i64_i32 v[66:67], s[50:51], v174, s12, v[66:67]
	v_lshl_add_u64 v[66:67], v[170:171], 1, v[66:67]
	v_cvt_pk_bf16_f32 v48, v48, v49
	v_cvt_pk_bf16_f32 v49, v50, v51
	v_cvt_pk_bf16_f32 v50, v52, v53
	v_cvt_pk_bf16_f32 v51, v54, v55
	global_store_dwordx4 v[66:67], v[48:51], off sc1
	v_pk_mul_f32 v[52:53], v[38:39], v[64:65] op_sel_hi:[1,0]
	v_pk_mul_f32 v[54:55], v[36:37], v[64:65] op_sel_hi:[1,0]
	v_cvt_pk_bf16_f32 v48, v56, v57
	v_cvt_pk_bf16_f32 v49, v58, v59
	v_cvt_pk_bf16_f32 v50, v60, v61
	v_cvt_pk_bf16_f32 v51, v62, v63
	global_store_dwordx4 v[66:67], v[48:51], off offset:64 sc1
	v_pk_mul_f32 v[60:61], v[46:47], v[64:65] op_sel_hi:[1,0]
	v_pk_mul_f32 v[62:63], v[44:45], v[64:65] op_sel_hi:[1,0]
	v_pk_mul_f32 v[56:57], v[42:43], v[64:65] op_sel_hi:[1,0]
	v_pk_mul_f32 v[58:59], v[40:41], v[64:65] op_sel_hi:[1,0]
	v_pk_mul_f32 v[50:51], v[34:35], v[64:65] op_sel_hi:[1,0]
	v_pk_mul_f32 v[48:49], v[32:33], v[64:65] op_sel_hi:[1,0]
	s_mov_b64 s[50:51], -1
	s_and_b64 vcc, exec, s[48:49]
	s_cbranch_vccz .LBB0_1228
	v_mov_b32_e32 v34, v63
	v_mov_b32_e32 v35, v55
	v_mov_b32_e32 v32, v62
	v_mov_b32_e32 v33, v54
	v_pk_mul_f32 v[34:35], v[34:35], v[34:35]
	v_mov_b32_e32 v36, v61
	v_mov_b32_e32 v37, v53
	v_pk_fma_f32 v[32:33], v[32:33], v[32:33], v[34:35]
	v_mov_b32_e32 v34, v60
	v_mov_b32_e32 v35, v52
	v_pk_mul_f32 v[36:37], v[36:37], v[36:37]
	v_mov_b32_e32 v38, v57
	v_pk_fma_f32 v[34:35], v[34:35], v[34:35], v[36:37]
	v_mov_b32_e32 v36, v59
	v_mov_b32_e32 v37, v49
	v_pk_add_f32 v[32:33], v[32:33], v[34:35]
	v_mov_b32_e32 v34, v58
	v_mov_b32_e32 v35, v48
	v_pk_mul_f32 v[36:37], v[36:37], v[36:37]
	v_mov_b32_e32 v39, v51
	v_pk_fma_f32 v[34:35], v[34:35], v[34:35], v[36:37]
	v_mov_b32_e32 v36, v56
	v_mov_b32_e32 v37, v50
	v_pk_mul_f32 v[38:39], v[38:39], v[38:39]
	s_mov_b64 s[50:51], 0
	v_pk_fma_f32 v[36:37], v[36:37], v[36:37], v[38:39]
	s_nop 0
	v_pk_add_f32 v[34:35], v[34:35], v[36:37]
	s_nop 0
	v_pk_add_f32 v[32:33], v[32:33], v[34:35]
	s_nop 0
	v_add_f32_e32 v32, v32, v33
	v_mov_b32_e32 v33, v201
	s_nop 0
	v_lshlrev_b32_e32 v33, 2, v33
	v_xor_b32_e32 v33, 64, v33
	v_mov_b32_e32 v33, v32
	s_nop 1
	v_permlane16_swap_b32_e32 v33, v32
	s_waitcnt lgkmcnt(0)
	v_add_f32_e32 v32, v32, v33
	v_mov_b32_e32 v33, v201
	s_nop 0
	v_lshlrev_b32_e32 v33, 2, v33
	v_xor_b32_e32 v33, 0x80, v33
	v_mov_b32_e32 v33, v32
	s_nop 1
	v_permlane32_swap_b32_e32 v33, v32
	s_waitcnt lgkmcnt(0)
	v_add_f32_e32 v32, v32, v33
	v_fmamk_f32 v32, v32, 0x3c800000, v202
	v_rsq_f32_e32 v44, v32
	s_nop 0
	v_pk_mul_f32 v[32:33], v[62:63], v[44:45] op_sel_hi:[1,0]
	v_pk_mul_f32 v[34:35], v[60:61], v[44:45] op_sel_hi:[1,0]
	v_pk_mul_f32 v[36:37], v[58:59], v[44:45] op_sel_hi:[1,0]
	v_pk_mul_f32 v[38:39], v[56:57], v[44:45] op_sel_hi:[1,0]
	v_pk_mul_f32 v[40:41], v[54:55], v[44:45] op_sel_hi:[1,0]
	v_pk_mul_f32 v[42:43], v[52:53], v[44:45] op_sel_hi:[1,0]
	v_pk_mul_f32 v[64:65], v[48:49], v[44:45] op_sel_hi:[1,0]
	v_pk_mul_f32 v[44:45], v[50:51], v[44:45] op_sel_hi:[1,0]
	v_pk_mul_f32 v[34:35], v[156:157], v[34:35]
	v_pk_mul_f32 v[32:33], v[160:161], v[32:33]
	v_pk_mul_f32 v[38:39], v[150:151], v[38:39]
	v_pk_mul_f32 v[36:37], v[152:153], v[36:37]
	v_pk_mul_f32 v[42:43], v[162:163], v[42:43]
	v_pk_mul_f32 v[40:41], v[164:165], v[40:41]
	v_pk_mul_f32 v[46:47], v[154:155], v[44:45]
	v_pk_mul_f32 v[44:45], v[158:159], v[64:65]

; __device__ __forceinline__ f32x4 silu4(f32x4 v) { return (f32x4){silu_f(v[0]), silu_f(v[1]), silu_f(v[2]), silu_f(v[3])}; }
; __device__ __forceinline__ float sq4(f32x4 v) { return (v[0] * v[0] + v[1] * v[1]) + (v[2] * v[2] + v[3] * v[3]); }
; __device__ __forceinline__ u32x4 pack8(f32x4 a, f32x4 b) { u32x4 w; w.x = cvt_pk_bf16(a[0], a[1]); w.y = cvt_pk_bf16(a[2], a[3]); w.z = cvt_pk_bf16(b[0], b[1]); w.w = cvt_pk_bf16(b[2], b[3]); return w; }
;     __device__ __forceinline__ void operator()(const f32x4 (&acc)[2][2][4][2], const Unit& u, int wr, int wc, int fr, int fq) const {
;     ...
;                 const int row = u.pm * BM + ai * HALF + wr * 64 + m * 16 + fr;
;                 const float rstd = rs[ai][m];
;                 f32x4 v[2][2];
; #pragma unroll
;                 for (int bj = 0; bj < 2; ++bj)
; #pragma unroll
;                     for (int n = 0; n < 2; ++n) v[bj][n] = acc[ai][bj][m][n] * rstd;
;                 if (mode == 2) {
;                     float q = (sq4(v[0][0]) + sq4(v[0][1])) + (sq4(v[1][0]) + sq4(v[1][1]));
;                     q += shx(q, 16); q += shx(q, 32);
;                     const float r2 = __builtin_amdgcn_rsqf(q * (1.0f / 64.0f) + RMS_EPS);
; #pragma unroll
;                     for (int bj = 0; bj < 2; ++bj)
; #pragma unroll
;                         for (int n = 0; n < 2; ++n) v[bj][n] = v[bj][n] * r2 * wv[bj][n];
;                 } else if (mode == 1) {
; #pragma unroll
;                     for (int bj = 0; bj < 2; ++bj)
; #pragma unroll
;                         for (int n = 0; n < 2; ++n) v[bj][n] = silu4(v[bj][n]);
;                 } else {
; #pragma unroll
;                     for (int bj = 0; bj < 2; ++bj)
; #pragma unroll
;                         for (int n = 0; n < 2; ++n) v[bj][n] = v[bj][n] * sc;
;                 }
;                 bf16_t* rowp = U + (size_t)row * 2560 + lcol;
; #pragma unroll
;                 for (int bj = 0; bj < 2; ++bj) *(u32x4*)(rowp + 32 * bj) = pack8(v[bj][0], v[bj][1]);
.LBB0_1233:
	v_add_f32_e32 v48, v173, v175
	v_fmamk_f32 v48, v48, 0x3a800000, v202
	v_rsq_f32_e32 v48, v48
	v_mov_b64_e32 v[50:51], s[18:19]
	v_mad_i64_i32 v[50:51], s[50:51], v172, s12, v[50:51]
	v_lshl_add_u64 v[50:51], v[170:171], 1, v[50:51]
	v_cvt_pk_bf16_f32 v32, v32, v33
	v_cvt_pk_bf16_f32 v33, v34, v35
	v_cvt_pk_bf16_f32 v34, v36, v37
	v_cvt_pk_bf16_f32 v35, v38, v39
	global_store_dwordx4 v[50:51], v[32:35], off sc1
	v_pk_mul_f32 v[36:37], v[22:23], v[48:49] op_sel_hi:[1,0]
	v_pk_mul_f32 v[38:39], v[20:21], v[48:49] op_sel_hi:[1,0]
	v_cvt_pk_bf16_f32 v32, v40, v41
	v_cvt_pk_bf16_f32 v33, v42, v43
	v_cvt_pk_bf16_f32 v34, v44, v45
	v_cvt_pk_bf16_f32 v35, v46, v47
	global_store_dwordx4 v[50:51], v[32:35], off offset:64 sc1
	v_pk_mul_f32 v[44:45], v[30:31], v[48:49] op_sel_hi:[1,0]
	v_pk_mul_f32 v[46:47], v[28:29], v[48:49] op_sel_hi:[1,0]
	v_pk_mul_f32 v[40:41], v[26:27], v[48:49] op_sel_hi:[1,0]
	v_pk_mul_f32 v[42:43], v[24:25], v[48:49] op_sel_hi:[1,0]
	v_pk_mul_f32 v[34:35], v[18:19], v[48:49] op_sel_hi:[1,0]
	v_pk_mul_f32 v[32:33], v[16:17], v[48:49] op_sel_hi:[1,0]
	s_mov_b64 s[50:51], -1
	s_and_b64 vcc, exec, s[48:49]
	s_cbranch_vccz .LBB0_1235
	v_mov_b32_e32 v18, v47
	v_mov_b32_e32 v19, v39
	v_mov_b32_e32 v16, v46
	v_mov_b32_e32 v17, v38
	v_pk_mul_f32 v[18:19], v[18:19], v[18:19]
	v_mov_b32_e32 v20, v45
	v_mov_b32_e32 v21, v37
	v_pk_fma_f32 v[16:17], v[16:17], v[16:17], v[18:19]
	v_mov_b32_e32 v18, v44
	v_mov_b32_e32 v19, v36
	v_pk_mul_f32 v[20:21], v[20:21], v[20:21]
	v_mov_b32_e32 v22, v41
	v_pk_fma_f32 v[18:19], v[18:19], v[18:19], v[20:21]
	v_mov_b32_e32 v20, v43
	v_mov_b32_e32 v21, v33
	v_pk_add_f32 v[16:17], v[16:17], v[18:19]
	v_mov_b32_e32 v18, v42
	v_mov_b32_e32 v19, v32
	v_pk_mul_f32 v[20:21], v[20:21], v[20:21]
	v_mov_b32_e32 v23, v35
	v_pk_fma_f32 v[18:19], v[18:19], v[18:19], v[20:21]
	v_mov_b32_e32 v20, v40
	v_mov_b32_e32 v21, v34
	v_pk_mul_f32 v[22:23], v[22:23], v[22:23]
	s_mov_b64 s[50:51], 0
	v_pk_fma_f32 v[20:21], v[20:21], v[20:21], v[22:23]
	s_nop 0
	v_pk_add_f32 v[18:19], v[18:19], v[20:21]
	s_nop 0
	v_pk_add_f32 v[16:17], v[16:17], v[18:19]
	s_nop 0
	v_add_f32_e32 v16, v16, v17
	v_mov_b32_e32 v17, v201
	s_nop 0
	v_lshlrev_b32_e32 v17, 2, v17
	v_xor_b32_e32 v17, 64, v17
	v_mov_b32_e32 v17, v16
	s_nop 1
	v_permlane16_swap_b32_e32 v17, v16
	s_waitcnt lgkmcnt(0)
	v_add_f32_e32 v16, v16, v17
	v_mov_b32_e32 v17, v201
	s_nop 0
	v_lshlrev_b32_e32 v17, 2, v17
	v_xor_b32_e32 v17, 0x80, v17
	v_mov_b32_e32 v17, v16
	s_nop 1
	v_permlane32_swap_b32_e32 v17, v16
	s_waitcnt lgkmcnt(0)
	v_add_f32_e32 v16, v16, v17
	v_fmamk_f32 v16, v16, 0x3c800000, v202
	v_rsq_f32_e32 v28, v16
	s_nop 0
	v_pk_mul_f32 v[16:17], v[46:47], v[28:29] op_sel_hi:[1,0]
	v_pk_mul_f32 v[18:19], v[44:45], v[28:29] op_sel_hi:[1,0]
	v_pk_mul_f32 v[20:21], v[42:43], v[28:29] op_sel_hi:[1,0]
	v_pk_mul_f32 v[22:23], v[40:41], v[28:29] op_sel_hi:[1,0]
	v_pk_mul_f32 v[24:25], v[38:39], v[28:29] op_sel_hi:[1,0]
	v_pk_mul_f32 v[26:27], v[36:37], v[28:29] op_sel_hi:[1,0]
	v_pk_mul_f32 v[48:49], v[32:33], v[28:29] op_sel_hi:[1,0]
	v_pk_mul_f32 v[28:29], v[34:35], v[28:29] op_sel_hi:[1,0]
	v_pk_mul_f32 v[18:19], v[156:157], v[18:19]
	v_pk_mul_f32 v[16:17], v[160:161], v[16:17]
	v_pk_mul_f32 v[22:23], v[150:151], v[22:23]
	v_pk_mul_f32 v[20:21], v[152:153], v[20:21]
	v_pk_mul_f32 v[26:27], v[162:163], v[26:27]
	v_pk_mul_f32 v[24:25], v[164:165], v[24:25]
	v_pk_mul_f32 v[30:31], v[154:155], v[28:29]
	v_pk_mul_f32 v[28:29], v[158:159], v[48:49]

; __device__ __forceinline__ f32x4 silu4(f32x4 v) { return (f32x4){silu_f(v[0]), silu_f(v[1]), silu_f(v[2]), silu_f(v[3])}; }
; __device__ __forceinline__ float sq4(f32x4 v) { return (v[0] * v[0] + v[1] * v[1]) + (v[2] * v[2] + v[3] * v[3]); }
; __device__ __forceinline__ u32x4 pack8(f32x4 a, f32x4 b) { u32x4 w; w.x = cvt_pk_bf16(a[0], a[1]); w.y = cvt_pk_bf16(a[2], a[3]); w.z = cvt_pk_bf16(b[0], b[1]); w.w = cvt_pk_bf16(b[2], b[3]); return w; }
;     __device__ __forceinline__ void operator()(const f32x4 (&acc)[2][2][4][2], const Unit& u, int wr, int wc, int fr, int fq) const {
;     ...
;                 const int row = u.pm * BM + ai * HALF + wr * 64 + m * 16 + fr;
;                 const float rstd = rs[ai][m];
;                 f32x4 v[2][2];
; #pragma unroll
;                 for (int bj = 0; bj < 2; ++bj)
; #pragma unroll
;                     for (int n = 0; n < 2; ++n) v[bj][n] = acc[ai][bj][m][n] * rstd;
;                 if (mode == 2) {
;                     float q = (sq4(v[0][0]) + sq4(v[0][1])) + (sq4(v[1][0]) + sq4(v[1][1]));
;                     q += shx(q, 16); q += shx(q, 32);
;                     const float r2 = __builtin_amdgcn_rsqf(q * (1.0f / 64.0f) + RMS_EPS);
; #pragma unroll
;                     for (int bj = 0; bj < 2; ++bj)
; #pragma unroll
;                         for (int n = 0; n < 2; ++n) v[bj][n] = v[bj][n] * r2 * wv[bj][n];
;                 } else if (mode == 1) {
; #pragma unroll
;                     for (int bj = 0; bj < 2; ++bj)
; #pragma unroll
;                         for (int n = 0; n < 2; ++n) v[bj][n] = silu4(v[bj][n]);
;                 } else {
; #pragma unroll
;                     for (int bj = 0; bj < 2; ++bj)
; #pragma unroll
;                         for (int n = 0; n < 2; ++n) v[bj][n] = v[bj][n] * sc;
;                 }
;                 bf16_t* rowp = U + (size_t)row * 2560 + lcol;
; #pragma unroll
;                 for (int bj = 0; bj < 2; ++bj) *(u32x4*)(rowp + 32 * bj) = pack8(v[bj][0], v[bj][1]);
.LBB0_1240:
	s_waitcnt lgkmcnt(0)
	v_add_f32_e32 v32, v149, v167
	v_fmamk_f32 v32, v32, 0x3a800000, v202
	v_rsq_f32_e32 v32, v32
	v_mov_b64_e32 v[34:35], s[18:19]
	v_mad_i64_i32 v[34:35], s[50:51], v166, s12, v[34:35]
	v_lshl_add_u64 v[34:35], v[170:171], 1, v[34:35]
	v_cvt_pk_bf16_f32 v16, v16, v17
	v_cvt_pk_bf16_f32 v17, v18, v19
	v_cvt_pk_bf16_f32 v18, v20, v21
	v_cvt_pk_bf16_f32 v19, v22, v23
	global_store_dwordx4 v[34:35], v[16:19], off sc1
	v_pk_mul_f32 v[20:21], v[6:7], v[32:33] op_sel_hi:[1,0]
	v_pk_mul_f32 v[22:23], v[4:5], v[32:33] op_sel_hi:[1,0]
	v_cvt_pk_bf16_f32 v16, v24, v25
	v_cvt_pk_bf16_f32 v17, v26, v27
	v_cvt_pk_bf16_f32 v18, v28, v29
	v_cvt_pk_bf16_f32 v19, v30, v31
	global_store_dwordx4 v[34:35], v[16:19], off offset:64 sc1
	v_pk_mul_f32 v[28:29], v[14:15], v[32:33] op_sel_hi:[1,0]
	v_pk_mul_f32 v[30:31], v[12:13], v[32:33] op_sel_hi:[1,0]
	v_pk_mul_f32 v[24:25], v[10:11], v[32:33] op_sel_hi:[1,0]
	v_pk_mul_f32 v[26:27], v[8:9], v[32:33] op_sel_hi:[1,0]
	v_pk_mul_f32 v[18:19], v[2:3], v[32:33] op_sel_hi:[1,0]
	v_pk_mul_f32 v[16:17], v[0:1], v[32:33] op_sel_hi:[1,0]
	s_mov_b64 s[50:51], -1
	s_and_b64 vcc, exec, s[48:49]
	s_cbranch_vccz .LBB0_1242
	v_mov_b32_e32 v2, v31
	v_mov_b32_e32 v3, v23
	v_mov_b32_e32 v0, v30
	v_mov_b32_e32 v1, v22
	v_pk_mul_f32 v[2:3], v[2:3], v[2:3]
	v_mov_b32_e32 v4, v29
	v_mov_b32_e32 v5, v21
	v_pk_fma_f32 v[0:1], v[0:1], v[0:1], v[2:3]
	v_mov_b32_e32 v2, v28
	v_mov_b32_e32 v3, v20
	v_pk_mul_f32 v[4:5], v[4:5], v[4:5]
	v_mov_b32_e32 v6, v25
	v_pk_fma_f32 v[2:3], v[2:3], v[2:3], v[4:5]
	v_mov_b32_e32 v4, v27
	v_mov_b32_e32 v5, v17
	v_pk_add_f32 v[0:1], v[0:1], v[2:3]
	v_mov_b32_e32 v2, v26
	v_mov_b32_e32 v3, v16
	v_pk_mul_f32 v[4:5], v[4:5], v[4:5]
	v_mov_b32_e32 v7, v19
	v_pk_fma_f32 v[2:3], v[2:3], v[2:3], v[4:5]
	v_mov_b32_e32 v4, v24
	v_mov_b32_e32 v5, v18
	v_pk_mul_f32 v[6:7], v[6:7], v[6:7]
	s_mov_b64 s[50:51], 0
	v_pk_fma_f32 v[4:5], v[4:5], v[4:5], v[6:7]
	s_nop 0
	v_pk_add_f32 v[2:3], v[2:3], v[4:5]
	s_nop 0
	v_pk_add_f32 v[0:1], v[0:1], v[2:3]
	s_nop 0
	v_add_f32_e32 v0, v0, v1
	v_mov_b32_e32 v1, v201
	s_nop 0
	v_lshlrev_b32_e32 v1, 2, v1
	v_xor_b32_e32 v1, 64, v1
	v_mov_b32_e32 v1, v0
	s_nop 1
	v_permlane16_swap_b32_e32 v1, v0
	s_waitcnt lgkmcnt(0)
	v_add_f32_e32 v0, v0, v1
	v_mov_b32_e32 v1, v201
	s_nop 0
	v_lshlrev_b32_e32 v1, 2, v1
	v_xor_b32_e32 v1, 0x80, v1
	v_mov_b32_e32 v1, v0
	s_nop 1
	v_permlane32_swap_b32_e32 v1, v0
	s_waitcnt lgkmcnt(0)
	v_add_f32_e32 v0, v0, v1
	v_fmamk_f32 v0, v0, 0x3c800000, v202
	v_rsq_f32_e32 v12, v0
	s_nop 0
	v_pk_mul_f32 v[0:1], v[30:31], v[12:13] op_sel_hi:[1,0]
	v_pk_mul_f32 v[2:3], v[28:29], v[12:13] op_sel_hi:[1,0]
	v_pk_mul_f32 v[4:5], v[26:27], v[12:13] op_sel_hi:[1,0]
	v_pk_mul_f32 v[6:7], v[24:25], v[12:13] op_sel_hi:[1,0]
	v_pk_mul_f32 v[8:9], v[22:23], v[12:13] op_sel_hi:[1,0]
	v_pk_mul_f32 v[10:11], v[20:21], v[12:13] op_sel_hi:[1,0]
	v_pk_mul_f32 v[32:33], v[16:17], v[12:13] op_sel_hi:[1,0]
	v_pk_mul_f32 v[12:13], v[18:19], v[12:13] op_sel_hi:[1,0]
	v_pk_mul_f32 v[2:3], v[156:157], v[2:3]
	v_pk_mul_f32 v[0:1], v[160:161], v[0:1]
	v_pk_mul_f32 v[6:7], v[150:151], v[6:7]
	v_pk_mul_f32 v[4:5], v[152:153], v[4:5]
	v_pk_mul_f32 v[10:11], v[162:163], v[10:11]
	v_pk_mul_f32 v[8:9], v[164:165], v[8:9]
	v_pk_mul_f32 v[14:15], v[154:155], v[12:13]
	v_pk_mul_f32 v[12:13], v[158:159], v[32:33]

; __device__ __forceinline__ u32x4 pack8(f32x4 a, f32x4 b) { u32x4 w; w.x = cvt_pk_bf16(a[0], a[1]); w.y = cvt_pk_bf16(a[2], a[3]); w.z = cvt_pk_bf16(b[0], b[1]); w.w = cvt_pk_bf16(b[2], b[3]); return w; }
; #define PG8_BAR __builtin_amdgcn_s_barrier()
;     __device__ __forceinline__ void operator()(const f32x4 (&acc)[2][2][4][2], const Unit& u, int wr, int wc, int fr, int fq) const {
;     ...
;                 bf16_t* rowp = U + (size_t)row * 2560 + lcol;
; #pragma unroll
;                 for (int bj = 0; bj < 2; ++bj) *(u32x4*)(rowp + 32 * bj) = pack8(v[bj][0], v[bj][1]);
; template <class Epi, class Sched, bool ALIGN_EPI = false, bool SP2 = false>
; __device__ __forceinline__ void gemm_phase(PG8_LAS unsigned char* lds, const Gemm g, const Sched& S, const Epi& E, int tid_in) {
;     ...
;         if (!has_next) break;
; #pragma unroll
;         for (int a = 0; a < 2; ++a)
; #pragma unroll
;             for (int b = 0; b < 2; ++b)
; #pragma unroll
;                 for (int m = 0; m < 4; ++m)
; #pragma unroll
;                     for (int n = 0; n < 2; ++n) acc[a][b][m][n] = (f32x4){0.f, 0.f, 0.f, 0.f};
;         cur = nxt; cA = nA; cB = nB; ++ui;
;         if constexpr (ALIGN_EPI) { if (wr == 1) PG8_BAR; }
.LBB0_1247:
	v_mov_b64_e32 v[16:17], s[18:19]
	v_mad_i64_i32 v[16:17], s[46:47], v148, s12, v[16:17]
	v_lshl_add_u64 v[16:17], v[170:171], 1, v[16:17]
	v_cvt_pk_bf16_f32 v0, v0, v1
	v_cvt_pk_bf16_f32 v1, v2, v3
	v_cvt_pk_bf16_f32 v2, v4, v5
	v_cvt_pk_bf16_f32 v3, v6, v7
	s_andn2_b64 vcc, exec, s[14:15]
	s_mov_b64 s[14:15], -1
	global_store_dwordx4 v[16:17], v[0:3], off sc1
	s_nop 1
	v_cvt_pk_bf16_f32 v0, v8, v9
	v_cvt_pk_bf16_f32 v1, v10, v11
	v_cvt_pk_bf16_f32 v2, v12, v13
	v_cvt_pk_bf16_f32 v3, v14, v15
	global_store_dwordx4 v[16:17], v[0:3], off offset:64 sc1
	s_cbranch_vccnz .LBB0_1184
	s_andn2_b64 vcc, exec, s[16:17]
	s_cbranch_vccnz .LBB0_1183
	s_barrier
	s_branch .LBB0_1183

; __device__ __forceinline__ float sq4(f32x4 v) { return (v[0] * v[0] + v[1] * v[1]) + (v[2] * v[2] + v[3] * v[3]); }
; __device__ __forceinline__ u32x4 pack8(f32x4 a, f32x4 b) { u32x4 w; w.x = cvt_pk_bf16(a[0], a[1]); w.y = cvt_pk_bf16(a[2], a[3]); w.z = cvt_pk_bf16(b[0], b[1]); w.w = cvt_pk_bf16(b[2], b[3]); return w; }
;     __device__ __forceinline__ void operator()(const f32x4 (&acc)[2][2][4][2], const Unit& u, int wr, int wc, int fr, int fq) const {
;         const int col0 = u.pn * 256 + 32 * wc + 8 * fq;
; #pragma unroll
;         for (int ai = 0; ai < 2; ++ai) {
;             u32x4 bs[4][2];
; #pragma unroll
;             for (int m = 0; m < 4; ++m)
; #pragma unroll
;                 for (int bj = 0; bj < 2; ++bj) bs[m][bj] = *(const u32x4*)(xb + (size_t)(u.pm * BM + ai * HALF + wr * 64 + m * 16 + fr) * 1024 + col0 + 128 * bj);
; #pragma unroll
;             for (int m = 0; m < 4; ++m) {
;                 const int row = u.pm * BM + ai * HALF + wr * 64 + m * 16 + fr;
;                 float q = 0.f;
; #pragma unroll
;                 for (int bj = 0; bj < 2; ++bj) {
;                     const size_t off = (size_t)row * 1024 + col0 + 128 * bj; const u32x4 w = bs[m][bj];
;                     const f32x4 b0 = (f32x4){__builtin_bit_cast(float, w.x << 16), __builtin_bit_cast(float, w.x & 0xffff0000u), __builtin_bit_cast(float, w.y << 16), __builtin_bit_cast(float, w.y & 0xffff0000u)};
;                     const f32x4 b1 = (f32x4){__builtin_bit_cast(float, w.z << 16), __builtin_bit_cast(float, w.z & 0xffff0000u), __builtin_bit_cast(float, w.w << 16), __builtin_bit_cast(float, w.w & 0xffff0000u)};
;                     const f32x4 v0 = acc[ai][bj][m][0] + b0, v1 = acc[ai][bj][m][1] + b1;
;                     if (last) { __builtin_nontemporal_store(v0, (f32x4*)(out + off)); __builtin_nontemporal_store(v1, (f32x4*)(out + off + 4)); }
;                     else { q += sq4(v0) + sq4(v1); *(u32x4*)(xb + off) = pack8(v0, v1); }
;                 }
;                 if (!last) { q += shx(q, 16); q += shx(q, 32); if (fq == 0) ss[(size_t)row * 16 + u.pn * 4 + wc] = q; }
.LBB0_1507:
	v_lshl_or_b32 v168, s16, 8, v188
	v_lshl_add_u32 v172, s50, 8, v186
	v_ashrrev_i32_e32 v169, 31, v168
	v_lshlrev_b64 v[202:203], 1, v[168:169]
	v_ashrrev_i32_e32 v173, 31, v172
	v_lshl_add_u64 v[170:171], s[20:21], 0, v[202:203]
	v_lshlrev_b64 v[204:205], 11, v[172:173]
	v_lshl_add_u64 v[120:121], v[170:171], 0, v[204:205]
	global_load_dwordx4 v[192:195], v[120:121], off
	global_load_dwordx4 v[196:199], v[120:121], off offset:256
	v_or_b32_e32 v182, 16, v172
	v_ashrrev_i32_e32 v183, 31, v182
	v_or_b32_e32 v178, 32, v172
	v_lshlrev_b64 v[184:185], 11, v[182:183]
	v_ashrrev_i32_e32 v179, 31, v178
	v_or_b32_e32 v174, 48, v172
	v_lshl_add_u64 v[120:121], v[170:171], 0, v[184:185]
	v_lshlrev_b64 v[180:181], 11, v[178:179]
	v_ashrrev_i32_e32 v175, 31, v174
	global_load_dwordx4 v[148:151], v[120:121], off
	global_load_dwordx4 v[144:147], v[120:121], off offset:256
	v_lshl_add_u64 v[120:121], v[170:171], 0, v[180:181]
	v_lshlrev_b64 v[176:177], 11, v[174:175]
	global_load_dwordx4 v[140:143], v[120:121], off
	global_load_dwordx4 v[136:139], v[120:121], off offset:256
	v_lshl_add_u64 v[120:121], v[170:171], 0, v[176:177]
	global_load_dwordx4 v[132:135], v[120:121], off
	s_nop 0
	global_load_dwordx4 v[120:123], v[120:121], off offset:256
	s_lshl_b32 s50, s16, 2
	s_ashr_i32 s51, s50, 31
	s_waitcnt vmcnt(0)
	v_lshlrev_b32_e32 v206, 16, v192
	v_and_b32_e32 v207, 0xffff0000, v192
	v_lshlrev_b32_e32 v192, 16, v193
	v_and_b32_e32 v193, 0xffff0000, v193
	v_lshlrev_b32_e32 v208, 16, v194
	v_and_b32_e32 v209, 0xffff0000, v194
	v_lshlrev_b32_e32 v194, 16, v195
	v_and_b32_e32 v195, 0xffff0000, v195
	v_pk_add_f32 v[130:131], v[130:131], v[192:193]
	v_pk_add_f32 v[128:129], v[128:129], v[206:207]
	v_pk_add_f32 v[192:193], v[126:127], v[194:195]
	v_pk_add_f32 v[126:127], v[124:125], v[208:209]
	v_mul_f32_e32 v124, v129, v129
	v_mul_f32_e32 v125, v131, v131
	v_fmac_f32_e32 v124, v128, v128
	v_fmac_f32_e32 v125, v130, v130
	v_add_f32_e32 v124, v124, v125
	v_mul_f32_e32 v125, v127, v127
	v_mul_f32_e32 v194, v193, v193
	v_fmac_f32_e32 v125, v126, v126
	v_fmac_f32_e32 v194, v192, v192
	v_add_f32_e32 v125, v125, v194
	v_add_f32_e32 v194, v124, v125
	v_cvt_pk_bf16_f32 v124, v128, v129
	v_lshl_add_u64 v[128:129], s[20:21], 0, v[204:205]
	v_cvt_pk_bf16_f32 v125, v130, v131
	v_cvt_pk_bf16_f32 v126, v126, v127
	v_cvt_pk_bf16_f32 v127, v192, v193
	v_lshl_add_u64 v[128:129], v[128:129], 0, v[202:203]
	global_store_dwordx4 v[128:129], v[124:127], off sc1
	v_lshlrev_b32_e32 v130, 16, v198
	v_and_b32_e32 v131, 0xffff0000, v198
	v_lshlrev_b32_e32 v124, 16, v196
	v_and_b32_e32 v125, 0xffff0000, v196
	v_lshlrev_b32_e32 v126, 16, v197
	v_and_b32_e32 v127, 0xffff0000, v197
	v_lshlrev_b32_e32 v192, 16, v199
	v_and_b32_e32 v193, 0xffff0000, v199
	v_pk_add_f32 v[118:119], v[118:119], v[126:127]
	v_pk_add_f32 v[116:117], v[116:117], v[124:125]
	v_pk_add_f32 v[124:125], v[114:115], v[192:193]
	v_pk_add_f32 v[114:115], v[112:113], v[130:131]
	v_mul_f32_e32 v112, v117, v117
	v_mul_f32_e32 v113, v119, v119
	v_fmac_f32_e32 v112, v116, v116
	v_fmac_f32_e32 v113, v118, v118
	v_add_f32_e32 v112, v112, v113
	v_mul_f32_e32 v113, v115, v115
	v_mul_f32_e32 v126, v125, v125
	v_fmac_f32_e32 v113, v114, v114
	v_fmac_f32_e32 v126, v124, v124
	v_add_f32_e32 v113, v113, v126
	v_add_f32_e32 v112, v112, v113
	v_add_f32_e32 v126, v194, v112
	v_cvt_pk_bf16_f32 v112, v116, v117
	v_cvt_pk_bf16_f32 v113, v118, v119
	v_cvt_pk_bf16_f32 v114, v114, v115
	v_cvt_pk_bf16_f32 v115, v124, v125
	global_store_dwordx4 v[128:129], v[112:115], off offset:256 sc1
	s_nop 1
	v_mov_b32_e32 v112, v201
	v_mov_b32_e32 v113, v201
	v_lshlrev_b32_e32 v112, 2, v112
	v_xor_b32_e32 v112, 64, v112
	v_mov_b32_e32 v112, v126
	s_nop 1
	v_permlane16_swap_b32_e32 v112, v126
	s_waitcnt lgkmcnt(0)
	v_add_f32_e32 v112, v126, v112
	v_lshlrev_b32_e32 v113, 2, v113
	v_xor_b32_e32 v113, 0x80, v113
	v_mov_b32_e32 v113, v112
	s_nop 1
	v_permlane32_swap_b32_e32 v113, v112
	s_and_saveexec_b64 s[52:53], s[8:9]
	s_cbranch_execz .LBB0_1509
	s_waitcnt lgkmcnt(0)
	v_add_f32_e32 v114, v112, v113
	v_lshlrev_b64 v[112:113], 6, v[172:173]
	v_lshl_add_u64 v[112:113], s[22:23], 0, v[112:113]
	v_lshl_add_u64 v[112:113], s[50:51], 2, v[112:113]
	s_lshl_b32 s16, s58, 2
	v_lshl_add_u64 v[112:113], v[112:113], 0, s[16:17]
	global_store_dword v[112:113], v114, off sc1
; __device__ __forceinline__ float sq4(f32x4 v) { return (v[0] * v[0] + v[1] * v[1]) + (v[2] * v[2] + v[3] * v[3]); }
; __device__ __forceinline__ u32x4 pack8(f32x4 a, f32x4 b) { u32x4 w; w.x = cvt_pk_bf16(a[0], a[1]); w.y = cvt_pk_bf16(a[2], a[3]); w.z = cvt_pk_bf16(b[0], b[1]); w.w = cvt_pk_bf16(b[2], b[3]); return w; }
;     __device__ __forceinline__ void operator()(const f32x4 (&acc)[2][2][4][2], const Unit& u, int wr, int wc, int fr, int fq) const {
;     ...
;             for (int m = 0; m < 4; ++m) {
;                 const int row = u.pm * BM + ai * HALF + wr * 64 + m * 16 + fr;
;                 float q = 0.f;
; #pragma unroll
;                 for (int bj = 0; bj < 2; ++bj) {
;                     const size_t off = (size_t)row * 1024 + col0 + 128 * bj; const u32x4 w = bs[m][bj];
;                     const f32x4 b0 = (f32x4){__builtin_bit_cast(float, w.x << 16), __builtin_bit_cast(float, w.x & 0xffff0000u), __builtin_bit_cast(float, w.y << 16), __builtin_bit_cast(float, w.y & 0xffff0000u)};
;                     const f32x4 b1 = (f32x4){__builtin_bit_cast(float, w.z << 16), __builtin_bit_cast(float, w.z & 0xffff0000u), __builtin_bit_cast(float, w.w << 16), __builtin_bit_cast(float, w.w & 0xffff0000u)};
;                     const f32x4 v0 = acc[ai][bj][m][0] + b0, v1 = acc[ai][bj][m][1] + b1;
;                     if (last) { __builtin_nontemporal_store(v0, (f32x4*)(out + off)); __builtin_nontemporal_store(v1, (f32x4*)(out + off + 4)); }
;                     else { q += sq4(v0) + sq4(v1); *(u32x4*)(xb + off) = pack8(v0, v1); }
;                 }
;                 if (!last) { q += shx(q, 16); q += shx(q, 32); if (fq == 0) ss[(size_t)row * 16 + u.pn * 4 + wc] = q; }
.LBB0_1509:
	s_or_b64 exec, exec, s[52:53]
	v_lshlrev_b32_e32 v112, 16, v148
	s_waitcnt lgkmcnt(0)
	v_and_b32_e32 v113, 0xffff0000, v148
	v_lshlrev_b32_e32 v114, 16, v149
	v_and_b32_e32 v115, 0xffff0000, v149
	v_lshlrev_b32_e32 v116, 16, v150
	v_and_b32_e32 v117, 0xffff0000, v150
	v_lshlrev_b32_e32 v118, 16, v151
	v_and_b32_e32 v119, 0xffff0000, v151
	v_pk_add_f32 v[110:111], v[110:111], v[114:115]
	v_pk_add_f32 v[108:109], v[108:109], v[112:113]
	v_pk_add_f32 v[112:113], v[106:107], v[118:119]
	v_pk_add_f32 v[106:107], v[104:105], v[116:117]
	v_mul_f32_e32 v104, v109, v109
	v_mul_f32_e32 v105, v111, v111
	v_fmac_f32_e32 v104, v108, v108
	v_fmac_f32_e32 v105, v110, v110
	v_add_f32_e32 v104, v104, v105
	v_mul_f32_e32 v105, v107, v107
	v_mul_f32_e32 v114, v113, v113
	v_fmac_f32_e32 v105, v106, v106
	v_fmac_f32_e32 v114, v112, v112
	v_add_f32_e32 v105, v105, v114
	v_add_f32_e32 v114, v104, v105
	v_cvt_pk_bf16_f32 v104, v108, v109
	v_lshl_add_u64 v[108:109], s[20:21], 0, v[184:185]
	v_cvt_pk_bf16_f32 v105, v110, v111
	v_cvt_pk_bf16_f32 v106, v106, v107
	v_cvt_pk_bf16_f32 v107, v112, v113
	v_lshl_add_u64 v[108:109], v[168:169], 1, v[108:109]
	global_store_dwordx4 v[108:109], v[104:107], off sc1
	v_lshlrev_b32_e32 v110, 16, v146
	v_and_b32_e32 v111, 0xffff0000, v146
	v_lshlrev_b32_e32 v104, 16, v144
	v_and_b32_e32 v105, 0xffff0000, v144
	v_lshlrev_b32_e32 v106, 16, v145
	v_and_b32_e32 v107, 0xffff0000, v145
	v_lshlrev_b32_e32 v112, 16, v147
	v_and_b32_e32 v113, 0xffff0000, v147
	v_pk_add_f32 v[102:103], v[102:103], v[106:107]
	v_pk_add_f32 v[100:101], v[100:101], v[104:105]
	v_pk_add_f32 v[104:105], v[98:99], v[112:113]
	v_pk_add_f32 v[98:99], v[96:97], v[110:111]
	v_mul_f32_e32 v96, v101, v101
	v_mul_f32_e32 v97, v103, v103
	v_fmac_f32_e32 v96, v100, v100
	v_fmac_f32_e32 v97, v102, v102
	v_add_f32_e32 v96, v96, v97
	v_mul_f32_e32 v97, v99, v99
	v_mul_f32_e32 v106, v105, v105
	v_fmac_f32_e32 v97, v98, v98
	v_fmac_f32_e32 v106, v104, v104
	v_add_f32_e32 v97, v97, v106
	v_add_f32_e32 v96, v96, v97
	v_add_f32_e32 v106, v114, v96
	v_cvt_pk_bf16_f32 v96, v100, v101
	v_cvt_pk_bf16_f32 v97, v102, v103
	v_cvt_pk_bf16_f32 v98, v98, v99
	v_cvt_pk_bf16_f32 v99, v104, v105
	global_store_dwordx4 v[108:109], v[96:99], off offset:256 sc1
	s_nop 1
	v_mov_b32_e32 v96, v201
	v_mov_b32_e32 v97, v201
	v_lshlrev_b32_e32 v96, 2, v96
	v_xor_b32_e32 v96, 64, v96
	v_mov_b32_e32 v96, v106
	s_nop 1
	v_permlane16_swap_b32_e32 v96, v106
	s_waitcnt lgkmcnt(0)
	v_add_f32_e32 v96, v106, v96
	v_lshlrev_b32_e32 v97, 2, v97
	v_xor_b32_e32 v97, 0x80, v97
	v_mov_b32_e32 v97, v96
	s_nop 1
	v_permlane32_swap_b32_e32 v97, v96
	s_and_saveexec_b64 s[52:53], s[8:9]
	s_cbranch_execz .LBB0_1511
	s_waitcnt lgkmcnt(0)
	v_add_f32_e32 v98, v96, v97
	v_lshlrev_b64 v[96:97], 6, v[182:183]
	v_lshl_add_u64 v[96:97], s[22:23], 0, v[96:97]
	v_lshl_add_u64 v[96:97], s[50:51], 2, v[96:97]
	s_lshl_b32 s16, s58, 2
	v_lshl_add_u64 v[96:97], v[96:97], 0, s[16:17]
	global_store_dword v[96:97], v98, off sc1
.LBB0_1511:
	s_or_b64 exec, exec, s[52:53]
	v_lshlrev_b32_e32 v96, 16, v140
	s_waitcnt lgkmcnt(0)
	v_and_b32_e32 v97, 0xffff0000, v140
	v_lshlrev_b32_e32 v98, 16, v141
	v_and_b32_e32 v99, 0xffff0000, v141
	v_lshlrev_b32_e32 v100, 16, v142
	v_and_b32_e32 v101, 0xffff0000, v142
	v_lshlrev_b32_e32 v102, 16, v143
	v_and_b32_e32 v103, 0xffff0000, v143
	v_pk_add_f32 v[94:95], v[94:95], v[98:99]
	v_pk_add_f32 v[92:93], v[92:93], v[96:97]
	v_pk_add_f32 v[96:97], v[90:91], v[102:103]
	v_pk_add_f32 v[90:91], v[88:89], v[100:101]
	v_mul_f32_e32 v88, v93, v93
	v_mul_f32_e32 v89, v95, v95
	v_fmac_f32_e32 v88, v92, v92
	v_fmac_f32_e32 v89, v94, v94
	v_add_f32_e32 v88, v88, v89
	v_mul_f32_e32 v89, v91, v91
	v_mul_f32_e32 v98, v97, v97
	v_fmac_f32_e32 v89, v90, v90
	v_fmac_f32_e32 v98, v96, v96
	v_add_f32_e32 v89, v89, v98
	v_add_f32_e32 v98, v88, v89
	v_cvt_pk_bf16_f32 v88, v92, v93
	v_lshl_add_u64 v[92:93], s[20:21], 0, v[180:181]
	v_cvt_pk_bf16_f32 v89, v94, v95
	v_cvt_pk_bf16_f32 v90, v90, v91
	v_cvt_pk_bf16_f32 v91, v96, v97
	v_lshl_add_u64 v[92:93], v[168:169], 1, v[92:93]
	global_store_dwordx4 v[92:93], v[88:91], off sc1
	v_lshlrev_b32_e32 v94, 16, v138
	v_and_b32_e32 v95, 0xffff0000, v138
	v_lshlrev_b32_e32 v88, 16, v136
	v_and_b32_e32 v89, 0xffff0000, v136
	v_lshlrev_b32_e32 v90, 16, v137
	v_and_b32_e32 v91, 0xffff0000, v137
	v_lshlrev_b32_e32 v96, 16, v139
	v_and_b32_e32 v97, 0xffff0000, v139
	v_pk_add_f32 v[86:87], v[86:87], v[90:91]
	v_pk_add_f32 v[84:85], v[84:85], v[88:89]
	v_pk_add_f32 v[88:89], v[82:83], v[96:97]
	v_pk_add_f32 v[82:83], v[80:81], v[94:95]
	v_mul_f32_e32 v80, v85, v85
	v_mul_f32_e32 v81, v87, v87
	v_fmac_f32_e32 v80, v84, v84
	v_fmac_f32_e32 v81, v86, v86
	v_add_f32_e32 v80, v80, v81
	v_mul_f32_e32 v81, v83, v83
	v_mul_f32_e32 v90, v89, v89
	v_fmac_f32_e32 v81, v82, v82
	v_fmac_f32_e32 v90, v88, v88
	v_add_f32_e32 v81, v81, v90
	v_add_f32_e32 v80, v80, v81
	v_add_f32_e32 v90, v98, v80
	v_cvt_pk_bf16_f32 v80, v84, v85
	v_cvt_pk_bf16_f32 v81, v86, v87
	v_cvt_pk_bf16_f32 v82, v82, v83
	v_cvt_pk_bf16_f32 v83, v88, v89
	global_store_dwordx4 v[92:93], v[80:83], off offset:256 sc1
	s_nop 1
	v_mov_b32_e32 v80, v201
	v_mov_b32_e32 v81, v201
	v_lshlrev_b32_e32 v80, 2, v80
	v_xor_b32_e32 v80, 64, v80
	v_mov_b32_e32 v80, v90
	s_nop 1
	v_permlane16_swap_b32_e32 v80, v90
	s_waitcnt lgkmcnt(0)
	v_add_f32_e32 v80, v90, v80
	v_lshlrev_b32_e32 v81, 2, v81
	v_xor_b32_e32 v81, 0x80, v81
	v_mov_b32_e32 v81, v80
	s_nop 1
	v_permlane32_swap_b32_e32 v81, v80
	s_and_saveexec_b64 s[52:53], s[8:9]
	s_cbranch_execz .LBB0_1513
	s_waitcnt lgkmcnt(0)
	v_add_f32_e32 v82, v80, v81
	v_lshlrev_b64 v[80:81], 6, v[178:179]
	v_lshl_add_u64 v[80:81], s[22:23], 0, v[80:81]
	v_lshl_add_u64 v[80:81], s[50:51], 2, v[80:81]
	s_lshl_b32 s16, s58, 2
	v_lshl_add_u64 v[80:81], v[80:81], 0, s[16:17]
	global_store_dword v[80:81], v82, off sc1
; __device__ __forceinline__ float sq4(f32x4 v) { return (v[0] * v[0] + v[1] * v[1]) + (v[2] * v[2] + v[3] * v[3]); }
; __device__ __forceinline__ u32x4 pack8(f32x4 a, f32x4 b) { u32x4 w; w.x = cvt_pk_bf16(a[0], a[1]); w.y = cvt_pk_bf16(a[2], a[3]); w.z = cvt_pk_bf16(b[0], b[1]); w.w = cvt_pk_bf16(b[2], b[3]); return w; }
;     __device__ __forceinline__ void operator()(const f32x4 (&acc)[2][2][4][2], const Unit& u, int wr, int wc, int fr, int fq) const {
;     ...
;         for (int ai = 0; ai < 2; ++ai) {
;             u32x4 bs[4][2];
; #pragma unroll
;             for (int m = 0; m < 4; ++m)
; #pragma unroll
;                 for (int bj = 0; bj < 2; ++bj) bs[m][bj] = *(const u32x4*)(xb + (size_t)(u.pm * BM + ai * HALF + wr * 64 + m * 16 + fr) * 1024 + col0 + 128 * bj);
; #pragma unroll
;             for (int m = 0; m < 4; ++m) {
;                 const int row = u.pm * BM + ai * HALF + wr * 64 + m * 16 + fr;
;                 float q = 0.f;
; #pragma unroll
;                 for (int bj = 0; bj < 2; ++bj) {
;                     const size_t off = (size_t)row * 1024 + col0 + 128 * bj; const u32x4 w = bs[m][bj];
;                     const f32x4 b0 = (f32x4){__builtin_bit_cast(float, w.x << 16), __builtin_bit_cast(float, w.x & 0xffff0000u), __builtin_bit_cast(float, w.y << 16), __builtin_bit_cast(float, w.y & 0xffff0000u)};
;                     const f32x4 b1 = (f32x4){__builtin_bit_cast(float, w.z << 16), __builtin_bit_cast(float, w.z & 0xffff0000u), __builtin_bit_cast(float, w.w << 16), __builtin_bit_cast(float, w.w & 0xffff0000u)};
;                     const f32x4 v0 = acc[ai][bj][m][0] + b0, v1 = acc[ai][bj][m][1] + b1;
;                     if (last) { __builtin_nontemporal_store(v0, (f32x4*)(out + off)); __builtin_nontemporal_store(v1, (f32x4*)(out + off + 4)); }
;                     else { q += sq4(v0) + sq4(v1); *(u32x4*)(xb + off) = pack8(v0, v1); }
;                 }
;                 if (!last) { q += shx(q, 16); q += shx(q, 32); if (fq == 0) ss[(size_t)row * 16 + u.pn * 4 + wc] = q; }
.LBB0_1513:
	s_or_b64 exec, exec, s[52:53]
	v_lshlrev_b32_e32 v80, 16, v132
	s_waitcnt lgkmcnt(0)
	v_and_b32_e32 v81, 0xffff0000, v132
	v_lshlrev_b32_e32 v82, 16, v133
	v_and_b32_e32 v83, 0xffff0000, v133
	v_lshlrev_b32_e32 v84, 16, v134
	v_and_b32_e32 v85, 0xffff0000, v134
	v_lshlrev_b32_e32 v86, 16, v135
	v_and_b32_e32 v87, 0xffff0000, v135
	v_pk_add_f32 v[78:79], v[78:79], v[82:83]
	v_pk_add_f32 v[76:77], v[76:77], v[80:81]
	v_pk_add_f32 v[80:81], v[74:75], v[86:87]
	v_pk_add_f32 v[74:75], v[72:73], v[84:85]
	v_mul_f32_e32 v72, v77, v77
	v_mul_f32_e32 v73, v79, v79
	v_fmac_f32_e32 v72, v76, v76
	v_fmac_f32_e32 v73, v78, v78
	v_add_f32_e32 v72, v72, v73
	v_mul_f32_e32 v73, v75, v75
	v_mul_f32_e32 v82, v81, v81
	v_fmac_f32_e32 v73, v74, v74
	v_fmac_f32_e32 v82, v80, v80
	v_add_f32_e32 v73, v73, v82
	v_add_f32_e32 v82, v72, v73
	v_cvt_pk_bf16_f32 v72, v76, v77
	v_lshl_add_u64 v[76:77], s[20:21], 0, v[176:177]
	v_cvt_pk_bf16_f32 v73, v78, v79
	v_cvt_pk_bf16_f32 v74, v74, v75
	v_cvt_pk_bf16_f32 v75, v80, v81
	v_lshl_add_u64 v[76:77], v[168:169], 1, v[76:77]
	global_store_dwordx4 v[76:77], v[72:75], off sc1
	v_lshlrev_b32_e32 v78, 16, v122
	v_and_b32_e32 v79, 0xffff0000, v122
	v_lshlrev_b32_e32 v72, 16, v120
	v_and_b32_e32 v73, 0xffff0000, v120
	v_lshlrev_b32_e32 v74, 16, v121
	v_and_b32_e32 v75, 0xffff0000, v121
	v_lshlrev_b32_e32 v80, 16, v123
	v_and_b32_e32 v81, 0xffff0000, v123
	v_pk_add_f32 v[70:71], v[70:71], v[74:75]
	v_pk_add_f32 v[68:69], v[68:69], v[72:73]
	v_pk_add_f32 v[72:73], v[66:67], v[80:81]
	v_pk_add_f32 v[66:67], v[64:65], v[78:79]
	v_mul_f32_e32 v64, v69, v69
	v_mul_f32_e32 v65, v71, v71
	v_fmac_f32_e32 v64, v68, v68
	v_fmac_f32_e32 v65, v70, v70
	v_add_f32_e32 v64, v64, v65
	v_mul_f32_e32 v65, v67, v67
	v_mul_f32_e32 v74, v73, v73
	v_fmac_f32_e32 v65, v66, v66
	v_fmac_f32_e32 v74, v72, v72
	v_add_f32_e32 v65, v65, v74
	v_add_f32_e32 v64, v64, v65
	v_add_f32_e32 v74, v82, v64
	v_cvt_pk_bf16_f32 v64, v68, v69
	v_cvt_pk_bf16_f32 v65, v70, v71
	v_cvt_pk_bf16_f32 v66, v66, v67
	v_cvt_pk_bf16_f32 v67, v72, v73
	global_store_dwordx4 v[76:77], v[64:67], off offset:256 sc1
	s_nop 1
	v_mov_b32_e32 v64, v201
	v_mov_b32_e32 v65, v201
	v_lshlrev_b32_e32 v64, 2, v64
	v_xor_b32_e32 v64, 64, v64
	v_mov_b32_e32 v64, v74
	s_nop 1
	v_permlane16_swap_b32_e32 v64, v74
	s_waitcnt lgkmcnt(0)
	v_add_f32_e32 v64, v74, v64
	v_lshlrev_b32_e32 v65, 2, v65
	v_xor_b32_e32 v65, 0x80, v65
	v_mov_b32_e32 v65, v64
	s_nop 1
	v_permlane32_swap_b32_e32 v65, v64
	s_and_saveexec_b64 s[52:53], s[8:9]
	s_cbranch_execz .LBB0_1515
	s_waitcnt lgkmcnt(0)
	v_add_f32_e32 v66, v64, v65
	v_lshlrev_b64 v[64:65], 6, v[174:175]
	v_lshl_add_u64 v[64:65], s[22:23], 0, v[64:65]
	v_lshl_add_u64 v[64:65], s[50:51], 2, v[64:65]
	s_lshl_b32 s16, s58, 2
	v_lshl_add_u64 v[64:65], v[64:65], 0, s[16:17]
	global_store_dword v[64:65], v66, off sc1
.LBB0_1515:
	s_or_b64 exec, exec, s[52:53]
	v_add_u32_e32 v100, 0x80, v172
	v_ashrrev_i32_e32 v101, 31, v100
	v_lshlrev_b64 v[110:111], 11, v[100:101]
	s_waitcnt lgkmcnt(0)
	v_lshl_add_u64 v[64:65], v[170:171], 0, v[110:111]
	global_load_dwordx4 v[102:105], v[64:65], off
	global_load_dwordx4 v[106:109], v[64:65], off offset:256
	v_add_u32_e32 v96, 0x90, v172
	v_ashrrev_i32_e32 v97, 31, v96
	v_add_u32_e32 v92, 0xa0, v172
	v_lshlrev_b64 v[98:99], 11, v[96:97]
	v_ashrrev_i32_e32 v93, 31, v92
	v_add_u32_e32 v88, 0xb0, v172
	v_lshl_add_u64 v[64:65], v[170:171], 0, v[98:99]
	v_lshlrev_b64 v[94:95], 11, v[92:93]
	v_ashrrev_i32_e32 v89, 31, v88
	global_load_dwordx4 v[84:87], v[64:65], off
	global_load_dwordx4 v[80:83], v[64:65], off offset:256
	v_lshl_add_u64 v[64:65], v[170:171], 0, v[94:95]
	v_lshlrev_b64 v[90:91], 11, v[88:89]
	global_load_dwordx4 v[76:79], v[64:65], off
	global_load_dwordx4 v[72:75], v[64:65], off offset:256
	v_lshl_add_u64 v[64:65], v[170:171], 0, v[90:91]
	global_load_dwordx4 v[68:71], v[64:65], off
	s_nop 0
	global_load_dwordx4 v[64:67], v[64:65], off offset:256
	s_waitcnt vmcnt(7)
	v_lshlrev_b32_e32 v112, 16, v102
	v_and_b32_e32 v113, 0xffff0000, v102
	v_lshlrev_b32_e32 v102, 16, v103
	v_and_b32_e32 v103, 0xffff0000, v103
	v_lshlrev_b32_e32 v114, 16, v104
	v_and_b32_e32 v115, 0xffff0000, v104
	v_lshlrev_b32_e32 v104, 16, v105
	v_and_b32_e32 v105, 0xffff0000, v105
	v_pk_add_f32 v[62:63], v[62:63], v[102:103]
	v_pk_add_f32 v[60:61], v[60:61], v[112:113]
	v_pk_add_f32 v[102:103], v[58:59], v[104:105]
	v_pk_add_f32 v[58:59], v[56:57], v[114:115]
	v_mul_f32_e32 v56, v61, v61
	v_mul_f32_e32 v57, v63, v63
	v_fmac_f32_e32 v56, v60, v60
	v_fmac_f32_e32 v57, v62, v62
	v_add_f32_e32 v56, v56, v57
	v_mul_f32_e32 v57, v59, v59
	v_mul_f32_e32 v104, v103, v103
	v_fmac_f32_e32 v57, v58, v58
	v_fmac_f32_e32 v104, v102, v102
	v_add_f32_e32 v57, v57, v104
	v_add_f32_e32 v104, v56, v57
	v_cvt_pk_bf16_f32 v56, v60, v61
	v_lshl_add_u64 v[60:61], s[20:21], 0, v[110:111]
	v_cvt_pk_bf16_f32 v57, v62, v63
	v_cvt_pk_bf16_f32 v58, v58, v59
	v_cvt_pk_bf16_f32 v59, v102, v103
	v_lshl_add_u64 v[60:61], v[168:169], 1, v[60:61]
	global_store_dwordx4 v[60:61], v[56:59], off sc1
	s_waitcnt vmcnt(7)
	v_lshlrev_b32_e32 v62, 16, v108
	v_and_b32_e32 v63, 0xffff0000, v108
	v_lshlrev_b32_e32 v56, 16, v106
	v_and_b32_e32 v57, 0xffff0000, v106
	v_lshlrev_b32_e32 v58, 16, v107
	v_and_b32_e32 v59, 0xffff0000, v107
	v_lshlrev_b32_e32 v102, 16, v109
	v_and_b32_e32 v103, 0xffff0000, v109
	v_pk_add_f32 v[54:55], v[54:55], v[58:59]
	v_pk_add_f32 v[52:53], v[52:53], v[56:57]
	v_pk_add_f32 v[56:57], v[50:51], v[102:103]
	v_pk_add_f32 v[50:51], v[48:49], v[62:63]
	v_mul_f32_e32 v48, v53, v53
	v_mul_f32_e32 v49, v55, v55
	v_fmac_f32_e32 v48, v52, v52
	v_fmac_f32_e32 v49, v54, v54
	v_add_f32_e32 v48, v48, v49
	v_mul_f32_e32 v49, v51, v51
	v_mul_f32_e32 v58, v57, v57
	v_fmac_f32_e32 v49, v50, v50
	v_fmac_f32_e32 v58, v56, v56
	v_add_f32_e32 v49, v49, v58
	v_add_f32_e32 v48, v48, v49
	v_add_f32_e32 v58, v104, v48
	v_cvt_pk_bf16_f32 v48, v52, v53
	v_cvt_pk_bf16_f32 v49, v54, v55
	v_cvt_pk_bf16_f32 v50, v50, v51
	v_cvt_pk_bf16_f32 v51, v56, v57
	global_store_dwordx4 v[60:61], v[48:51], off offset:256 sc1
	s_nop 1
	v_mov_b32_e32 v48, v201
	v_mov_b32_e32 v49, v201
	v_lshlrev_b32_e32 v48, 2, v48
	v_xor_b32_e32 v48, 64, v48
	v_mov_b32_e32 v48, v58
	s_nop 1
	v_permlane16_swap_b32_e32 v48, v58
	s_waitcnt lgkmcnt(0)
	v_add_f32_e32 v48, v58, v48
	v_lshlrev_b32_e32 v49, 2, v49
	v_xor_b32_e32 v49, 0x80, v49
	v_mov_b32_e32 v49, v48
	s_nop 1
	v_permlane32_swap_b32_e32 v49, v48
	s_and_saveexec_b64 s[52:53], s[8:9]
	s_cbranch_execz .LBB0_1517
	s_waitcnt lgkmcnt(0)
	v_add_f32_e32 v50, v48, v49
	v_lshlrev_b64 v[48:49], 6, v[100:101]
	v_lshl_add_u64 v[48:49], s[22:23], 0, v[48:49]
	v_lshl_add_u64 v[48:49], s[50:51], 2, v[48:49]
	s_lshl_b32 s16, s58, 2
	v_lshl_add_u64 v[48:49], v[48:49], 0, s[16:17]
	global_store_dword v[48:49], v50, off sc1
; __device__ __forceinline__ float sq4(f32x4 v) { return (v[0] * v[0] + v[1] * v[1]) + (v[2] * v[2] + v[3] * v[3]); }
; __device__ __forceinline__ u32x4 pack8(f32x4 a, f32x4 b) { u32x4 w; w.x = cvt_pk_bf16(a[0], a[1]); w.y = cvt_pk_bf16(a[2], a[3]); w.z = cvt_pk_bf16(b[0], b[1]); w.w = cvt_pk_bf16(b[2], b[3]); return w; }
;     __device__ __forceinline__ void operator()(const f32x4 (&acc)[2][2][4][2], const Unit& u, int wr, int wc, int fr, int fq) const {
;     ...
;             for (int m = 0; m < 4; ++m) {
;                 const int row = u.pm * BM + ai * HALF + wr * 64 + m * 16 + fr;
;                 float q = 0.f;
; #pragma unroll
;                 for (int bj = 0; bj < 2; ++bj) {
;                     const size_t off = (size_t)row * 1024 + col0 + 128 * bj; const u32x4 w = bs[m][bj];
;                     const f32x4 b0 = (f32x4){__builtin_bit_cast(float, w.x << 16), __builtin_bit_cast(float, w.x & 0xffff0000u), __builtin_bit_cast(float, w.y << 16), __builtin_bit_cast(float, w.y & 0xffff0000u)};
;                     const f32x4 b1 = (f32x4){__builtin_bit_cast(float, w.z << 16), __builtin_bit_cast(float, w.z & 0xffff0000u), __builtin_bit_cast(float, w.w << 16), __builtin_bit_cast(float, w.w & 0xffff0000u)};
;                     const f32x4 v0 = acc[ai][bj][m][0] + b0, v1 = acc[ai][bj][m][1] + b1;
;                     if (last) { __builtin_nontemporal_store(v0, (f32x4*)(out + off)); __builtin_nontemporal_store(v1, (f32x4*)(out + off + 4)); }
;                     else { q += sq4(v0) + sq4(v1); *(u32x4*)(xb + off) = pack8(v0, v1); }
;                 }
;                 if (!last) { q += shx(q, 16); q += shx(q, 32); if (fq == 0) ss[(size_t)row * 16 + u.pn * 4 + wc] = q; }
.LBB0_1517:
	s_or_b64 exec, exec, s[52:53]
	s_waitcnt vmcnt(7)
	v_lshlrev_b32_e32 v48, 16, v84
	s_waitcnt lgkmcnt(0)
	v_and_b32_e32 v49, 0xffff0000, v84
	v_lshlrev_b32_e32 v50, 16, v85
	v_and_b32_e32 v51, 0xffff0000, v85
	v_lshlrev_b32_e32 v52, 16, v86
	v_and_b32_e32 v53, 0xffff0000, v86
	v_lshlrev_b32_e32 v54, 16, v87
	v_and_b32_e32 v55, 0xffff0000, v87
	v_pk_add_f32 v[46:47], v[46:47], v[50:51]
	v_pk_add_f32 v[44:45], v[44:45], v[48:49]
	v_pk_add_f32 v[48:49], v[42:43], v[54:55]
	v_pk_add_f32 v[42:43], v[40:41], v[52:53]
	v_mul_f32_e32 v40, v45, v45
	v_mul_f32_e32 v41, v47, v47
	v_fmac_f32_e32 v40, v44, v44
	v_fmac_f32_e32 v41, v46, v46
	v_add_f32_e32 v40, v40, v41
	v_mul_f32_e32 v41, v43, v43
	v_mul_f32_e32 v50, v49, v49
	v_fmac_f32_e32 v41, v42, v42
	v_fmac_f32_e32 v50, v48, v48
	v_add_f32_e32 v41, v41, v50
	v_add_f32_e32 v50, v40, v41
	v_cvt_pk_bf16_f32 v40, v44, v45
	v_lshl_add_u64 v[44:45], s[20:21], 0, v[98:99]
	v_cvt_pk_bf16_f32 v41, v46, v47
	v_cvt_pk_bf16_f32 v42, v42, v43
	v_cvt_pk_bf16_f32 v43, v48, v49
	v_lshl_add_u64 v[44:45], v[168:169], 1, v[44:45]
	global_store_dwordx4 v[44:45], v[40:43], off sc1
	s_waitcnt vmcnt(7)
	v_lshlrev_b32_e32 v46, 16, v82
	v_and_b32_e32 v47, 0xffff0000, v82
	v_lshlrev_b32_e32 v40, 16, v80
	v_and_b32_e32 v41, 0xffff0000, v80
	v_lshlrev_b32_e32 v42, 16, v81
	v_and_b32_e32 v43, 0xffff0000, v81
	v_lshlrev_b32_e32 v48, 16, v83
	v_and_b32_e32 v49, 0xffff0000, v83
	v_pk_add_f32 v[38:39], v[38:39], v[42:43]
	v_pk_add_f32 v[36:37], v[36:37], v[40:41]
	v_pk_add_f32 v[40:41], v[34:35], v[48:49]
	v_pk_add_f32 v[34:35], v[32:33], v[46:47]
	v_mul_f32_e32 v32, v37, v37
	v_mul_f32_e32 v33, v39, v39
	v_fmac_f32_e32 v32, v36, v36
	v_fmac_f32_e32 v33, v38, v38
	v_add_f32_e32 v32, v32, v33
	v_mul_f32_e32 v33, v35, v35
	v_mul_f32_e32 v42, v41, v41
	v_fmac_f32_e32 v33, v34, v34
	v_fmac_f32_e32 v42, v40, v40
	v_add_f32_e32 v33, v33, v42
	v_add_f32_e32 v32, v32, v33
	v_add_f32_e32 v42, v50, v32
	v_cvt_pk_bf16_f32 v32, v36, v37
	v_cvt_pk_bf16_f32 v33, v38, v39
	v_cvt_pk_bf16_f32 v34, v34, v35
	v_cvt_pk_bf16_f32 v35, v40, v41
	global_store_dwordx4 v[44:45], v[32:35], off offset:256 sc1
	s_nop 1
	v_mov_b32_e32 v32, v201
	v_mov_b32_e32 v33, v201
	v_lshlrev_b32_e32 v32, 2, v32
	v_xor_b32_e32 v32, 64, v32
	v_mov_b32_e32 v32, v42
	s_nop 1
	v_permlane16_swap_b32_e32 v32, v42
	s_waitcnt lgkmcnt(0)
	v_add_f32_e32 v32, v42, v32
	v_lshlrev_b32_e32 v33, 2, v33
	v_xor_b32_e32 v33, 0x80, v33
	v_mov_b32_e32 v33, v32
	s_nop 1
	v_permlane32_swap_b32_e32 v33, v32
	s_and_saveexec_b64 s[52:53], s[8:9]
	s_cbranch_execz .LBB0_1519
	s_waitcnt lgkmcnt(0)
	v_add_f32_e32 v34, v32, v33
	v_lshlrev_b64 v[32:33], 6, v[96:97]
	v_lshl_add_u64 v[32:33], s[22:23], 0, v[32:33]
	v_lshl_add_u64 v[32:33], s[50:51], 2, v[32:33]
	s_lshl_b32 s16, s58, 2
	v_lshl_add_u64 v[32:33], v[32:33], 0, s[16:17]
	global_store_dword v[32:33], v34, off sc1
; __device__ __forceinline__ float sq4(f32x4 v) { return (v[0] * v[0] + v[1] * v[1]) + (v[2] * v[2] + v[3] * v[3]); }
; __device__ __forceinline__ u32x4 pack8(f32x4 a, f32x4 b) { u32x4 w; w.x = cvt_pk_bf16(a[0], a[1]); w.y = cvt_pk_bf16(a[2], a[3]); w.z = cvt_pk_bf16(b[0], b[1]); w.w = cvt_pk_bf16(b[2], b[3]); return w; }
;     __device__ __forceinline__ void operator()(const f32x4 (&acc)[2][2][4][2], const Unit& u, int wr, int wc, int fr, int fq) const {
;     ...
;             for (int m = 0; m < 4; ++m) {
;                 const int row = u.pm * BM + ai * HALF + wr * 64 + m * 16 + fr;
;                 float q = 0.f;
; #pragma unroll
;                 for (int bj = 0; bj < 2; ++bj) {
;                     const size_t off = (size_t)row * 1024 + col0 + 128 * bj; const u32x4 w = bs[m][bj];
;                     const f32x4 b0 = (f32x4){__builtin_bit_cast(float, w.x << 16), __builtin_bit_cast(float, w.x & 0xffff0000u), __builtin_bit_cast(float, w.y << 16), __builtin_bit_cast(float, w.y & 0xffff0000u)};
;                     const f32x4 b1 = (f32x4){__builtin_bit_cast(float, w.z << 16), __builtin_bit_cast(float, w.z & 0xffff0000u), __builtin_bit_cast(float, w.w << 16), __builtin_bit_cast(float, w.w & 0xffff0000u)};
;                     const f32x4 v0 = acc[ai][bj][m][0] + b0, v1 = acc[ai][bj][m][1] + b1;
;                     if (last) { __builtin_nontemporal_store(v0, (f32x4*)(out + off)); __builtin_nontemporal_store(v1, (f32x4*)(out + off + 4)); }
;                     else { q += sq4(v0) + sq4(v1); *(u32x4*)(xb + off) = pack8(v0, v1); }
;                 }
;                 if (!last) { q += shx(q, 16); q += shx(q, 32); if (fq == 0) ss[(size_t)row * 16 + u.pn * 4 + wc] = q; }
.LBB0_1519:
	s_or_b64 exec, exec, s[52:53]
	s_waitcnt vmcnt(7)
	v_lshlrev_b32_e32 v32, 16, v76
	s_waitcnt lgkmcnt(0)
	v_and_b32_e32 v33, 0xffff0000, v76
	v_lshlrev_b32_e32 v34, 16, v77
	v_and_b32_e32 v35, 0xffff0000, v77
	v_lshlrev_b32_e32 v36, 16, v78
	v_and_b32_e32 v37, 0xffff0000, v78
	v_lshlrev_b32_e32 v38, 16, v79
	v_and_b32_e32 v39, 0xffff0000, v79
	v_pk_add_f32 v[30:31], v[30:31], v[34:35]
	v_pk_add_f32 v[28:29], v[28:29], v[32:33]
	v_pk_add_f32 v[32:33], v[26:27], v[38:39]
	v_pk_add_f32 v[26:27], v[24:25], v[36:37]
	v_mul_f32_e32 v24, v29, v29
	v_mul_f32_e32 v25, v31, v31
	v_fmac_f32_e32 v24, v28, v28
	v_fmac_f32_e32 v25, v30, v30
	v_add_f32_e32 v24, v24, v25
	v_mul_f32_e32 v25, v27, v27
	v_mul_f32_e32 v34, v33, v33
	v_fmac_f32_e32 v25, v26, v26
	v_fmac_f32_e32 v34, v32, v32
	v_add_f32_e32 v25, v25, v34
	v_add_f32_e32 v34, v24, v25
	v_cvt_pk_bf16_f32 v24, v28, v29
	v_lshl_add_u64 v[28:29], s[20:21], 0, v[94:95]
	v_cvt_pk_bf16_f32 v25, v30, v31
	v_cvt_pk_bf16_f32 v26, v26, v27
	v_cvt_pk_bf16_f32 v27, v32, v33
	v_lshl_add_u64 v[28:29], v[168:169], 1, v[28:29]
	global_store_dwordx4 v[28:29], v[24:27], off sc1
	s_waitcnt vmcnt(7)
	v_lshlrev_b32_e32 v30, 16, v74
	v_and_b32_e32 v31, 0xffff0000, v74
	v_lshlrev_b32_e32 v24, 16, v72
	v_and_b32_e32 v25, 0xffff0000, v72
	v_lshlrev_b32_e32 v26, 16, v73
	v_and_b32_e32 v27, 0xffff0000, v73
	v_lshlrev_b32_e32 v32, 16, v75
	v_and_b32_e32 v33, 0xffff0000, v75
	v_pk_add_f32 v[22:23], v[22:23], v[26:27]
	v_pk_add_f32 v[20:21], v[20:21], v[24:25]
	v_pk_add_f32 v[24:25], v[18:19], v[32:33]
	v_pk_add_f32 v[18:19], v[16:17], v[30:31]
	v_mul_f32_e32 v16, v21, v21
	v_mul_f32_e32 v17, v23, v23
	v_fmac_f32_e32 v16, v20, v20
	v_fmac_f32_e32 v17, v22, v22
	v_add_f32_e32 v16, v16, v17
	v_mul_f32_e32 v17, v19, v19
	v_mul_f32_e32 v26, v25, v25
	v_fmac_f32_e32 v17, v18, v18
	v_fmac_f32_e32 v26, v24, v24
	v_add_f32_e32 v17, v17, v26
	v_add_f32_e32 v16, v16, v17
	v_add_f32_e32 v26, v34, v16
	v_cvt_pk_bf16_f32 v16, v20, v21
	v_cvt_pk_bf16_f32 v17, v22, v23
	v_cvt_pk_bf16_f32 v18, v18, v19
	v_cvt_pk_bf16_f32 v19, v24, v25
	global_store_dwordx4 v[28:29], v[16:19], off offset:256 sc1
	s_nop 1
	v_mov_b32_e32 v16, v201
	v_mov_b32_e32 v17, v201
	v_lshlrev_b32_e32 v16, 2, v16
	v_xor_b32_e32 v16, 64, v16
	v_mov_b32_e32 v16, v26
	s_nop 1
	v_permlane16_swap_b32_e32 v16, v26
	s_waitcnt lgkmcnt(0)
	v_add_f32_e32 v16, v26, v16
	v_lshlrev_b32_e32 v17, 2, v17
	v_xor_b32_e32 v17, 0x80, v17
	v_mov_b32_e32 v17, v16
	s_nop 1
	v_permlane32_swap_b32_e32 v17, v16
	s_and_saveexec_b64 s[52:53], s[8:9]
	s_cbranch_execz .LBB0_1521
	s_waitcnt lgkmcnt(0)
	v_add_f32_e32 v18, v16, v17
	v_lshlrev_b64 v[16:17], 6, v[92:93]
	v_lshl_add_u64 v[16:17], s[22:23], 0, v[16:17]
	v_lshl_add_u64 v[16:17], s[50:51], 2, v[16:17]
	s_lshl_b32 s16, s58, 2
	v_lshl_add_u64 v[16:17], v[16:17], 0, s[16:17]
	global_store_dword v[16:17], v18, off sc1
.LBB0_1521:
	s_or_b64 exec, exec, s[52:53]
	s_waitcnt vmcnt(7)
	v_lshlrev_b32_e32 v16, 16, v68
	s_waitcnt lgkmcnt(0)
	v_and_b32_e32 v17, 0xffff0000, v68
	v_lshlrev_b32_e32 v18, 16, v69
	v_and_b32_e32 v19, 0xffff0000, v69
	v_lshlrev_b32_e32 v20, 16, v70
	v_and_b32_e32 v21, 0xffff0000, v70
	v_lshlrev_b32_e32 v22, 16, v71
	v_and_b32_e32 v23, 0xffff0000, v71
	v_pk_add_f32 v[14:15], v[14:15], v[18:19]
	v_pk_add_f32 v[12:13], v[12:13], v[16:17]
	v_pk_add_f32 v[16:17], v[10:11], v[22:23]
	v_pk_add_f32 v[10:11], v[8:9], v[20:21]
	v_mul_f32_e32 v8, v13, v13
	v_mul_f32_e32 v9, v15, v15
	v_fmac_f32_e32 v8, v12, v12
	v_fmac_f32_e32 v9, v14, v14
	v_add_f32_e32 v8, v8, v9
	v_mul_f32_e32 v9, v11, v11
	v_mul_f32_e32 v18, v17, v17
	v_fmac_f32_e32 v9, v10, v10
	v_fmac_f32_e32 v18, v16, v16
	v_add_f32_e32 v9, v9, v18
	v_add_f32_e32 v18, v8, v9
	v_cvt_pk_bf16_f32 v8, v12, v13
	v_lshl_add_u64 v[12:13], s[20:21], 0, v[90:91]
	v_cvt_pk_bf16_f32 v9, v14, v15
	v_cvt_pk_bf16_f32 v10, v10, v11
	v_cvt_pk_bf16_f32 v11, v16, v17
	v_lshl_add_u64 v[12:13], v[168:169], 1, v[12:13]
	global_store_dwordx4 v[12:13], v[8:11], off sc1
	s_waitcnt vmcnt(7)
	v_lshlrev_b32_e32 v14, 16, v66
	v_and_b32_e32 v15, 0xffff0000, v66
	v_lshlrev_b32_e32 v8, 16, v64
	v_and_b32_e32 v9, 0xffff0000, v64
	v_lshlrev_b32_e32 v10, 16, v65
	v_and_b32_e32 v11, 0xffff0000, v65
	v_lshlrev_b32_e32 v16, 16, v67
	v_and_b32_e32 v17, 0xffff0000, v67
	v_pk_add_f32 v[6:7], v[6:7], v[10:11]
	v_pk_add_f32 v[4:5], v[4:5], v[8:9]
	v_pk_add_f32 v[8:9], v[2:3], v[16:17]
	v_pk_add_f32 v[2:3], v[0:1], v[14:15]
	v_mul_f32_e32 v0, v5, v5
	v_mul_f32_e32 v1, v7, v7
	v_fmac_f32_e32 v0, v4, v4
	v_fmac_f32_e32 v1, v6, v6
	v_add_f32_e32 v0, v0, v1
	v_mul_f32_e32 v1, v3, v3
	v_mul_f32_e32 v10, v9, v9
	v_fmac_f32_e32 v1, v2, v2
	v_fmac_f32_e32 v10, v8, v8
	v_add_f32_e32 v1, v1, v10
	v_add_f32_e32 v0, v0, v1
	v_add_f32_e32 v10, v18, v0
	v_cvt_pk_bf16_f32 v0, v4, v5
	v_cvt_pk_bf16_f32 v1, v6, v7
	v_cvt_pk_bf16_f32 v2, v2, v3
	v_cvt_pk_bf16_f32 v3, v8, v9
	global_store_dwordx4 v[12:13], v[0:3], off offset:256 sc1
	s_nop 1
	v_mov_b32_e32 v0, v201
	v_mov_b32_e32 v1, v201
	v_lshlrev_b32_e32 v0, 2, v0
	v_xor_b32_e32 v0, 64, v0
	v_mov_b32_e32 v0, v10
	s_nop 1
	v_permlane16_swap_b32_e32 v0, v10
	s_waitcnt lgkmcnt(0)
	v_add_f32_e32 v0, v10, v0
	v_lshlrev_b32_e32 v1, 2, v1
	v_xor_b32_e32 v1, 0x80, v1
	v_mov_b32_e32 v1, v0
	s_nop 1
	v_permlane32_swap_b32_e32 v1, v0
	s_and_saveexec_b64 s[52:53], s[8:9]
	s_cbranch_execz .LBB0_1523
	s_waitcnt lgkmcnt(0)
	v_add_f32_e32 v2, v0, v1
	v_lshlrev_b64 v[0:1], 6, v[88:89]
	v_lshl_add_u64 v[0:1], s[22:23], 0, v[0:1]
	v_lshl_add_u64 v[0:1], s[50:51], 2, v[0:1]
	s_lshl_b32 s16, s58, 2
	v_lshl_add_u64 v[0:1], v[0:1], 0, s[16:17]
	global_store_dword v[0:1], v2, off sc1

; __device__ __forceinline__ float row_part(const float* ss, int row, int fq) { const f32x4 a = ((const f32x4*)(ss + (size_t)row * 16))[fq]; return (a[0] + a[1]) + (a[2] + a[3]); }
; __device__ __forceinline__ float row_finish(float t) { t += shx(t, 16); t += shx(t, 32); return __builtin_amdgcn_rsqf(t * (1.0f / 1024.0f) + RMS_EPS); }
;     __device__ __forceinline__ void operator()(const f32x4 (&acc)[2][2][4][2], const Unit& u, int wr, int wc, int fr, int fq) const {
;         const int col0 = u.pn * 128 + 32 * wc + 8 * fq;
;         float rs[2][4];
; #pragma unroll
;         for (int ai = 0; ai < 2; ++ai)
; #pragma unroll
;             for (int m = 0; m < 4; ++m) rs[ai][m] = row_part(ss, u.pm * BM + ai * HALF + wr * 64 + m * 16 + fr, fq);
; #pragma unroll
;         for (int ai = 0; ai < 2; ++ai)
; #pragma unroll
;             for (int m = 0; m < 4; ++m) rs[ai][m] = row_finish(rs[ai][m]);
.LBB0_1591:
	v_lshl_add_u32 v170, s44, 8, v153
	v_ashrrev_i32_e32 v171, 31, v170
	v_or_b32_e32 v166, 16, v170
	v_lshlrev_b64 v[146:147], 6, v[170:171]
	v_ashrrev_i32_e32 v167, 31, v166
	v_lshl_add_u64 v[146:147], v[136:137], 0, v[146:147]
	v_lshlrev_b64 v[148:149], 6, v[166:167]
	v_lshl_add_u64 v[148:149], v[136:137], 0, v[148:149]
	ds_read_b128 v[176:179], v239
	ds_read_b128 v[180:183], v239 offset:1024
	v_or_b32_e32 v162, 32, v170
	v_ashrrev_i32_e32 v163, 31, v162
	v_or_b32_e32 v158, 48, v170
	v_lshlrev_b64 v[146:147], 6, v[162:163]
	v_ashrrev_i32_e32 v159, 31, v158
	v_lshl_add_u64 v[146:147], v[136:137], 0, v[146:147]
	v_lshlrev_b64 v[148:149], 6, v[158:159]
	v_lshl_add_u64 v[148:149], v[136:137], 0, v[148:149]
	ds_read_b128 v[184:187], v239 offset:2048
	ds_read_b128 v[188:191], v239 offset:3072
	v_add_u32_e32 v154, 0x80, v170
	v_ashrrev_i32_e32 v155, 31, v154
	v_add_u32_e32 v150, 0x90, v170
	v_lshlrev_b64 v[146:147], 6, v[154:155]
	v_ashrrev_i32_e32 v151, 31, v150
	v_lshl_add_u64 v[146:147], v[136:137], 0, v[146:147]
	v_lshlrev_b64 v[148:149], 6, v[150:151]
	v_lshl_add_u64 v[148:149], v[136:137], 0, v[148:149]
	ds_read_b128 v[192:195], v239 offset:8192
	ds_read_b128 v[196:199], v239 offset:9216
	v_add_u32_e32 v148, 0xa0, v170
	v_ashrrev_i32_e32 v149, 31, v148
	v_lshlrev_b64 v[146:147], 6, v[148:149]
	v_lshl_add_u64 v[146:147], v[136:137], 0, v[146:147]
	ds_read_b128 v[202:205], v239 offset:10240
	v_add_u32_e32 v146, 0xb0, v170
	v_ashrrev_i32_e32 v147, 31, v146
	v_lshlrev_b64 v[206:207], 6, v[146:147]
	v_lshl_add_u64 v[206:207], v[136:137], 0, v[206:207]
	ds_read_b128 v[206:209], v239 offset:11264
	v_mov_b32_e32 v147, v201
	v_mov_b32_e32 v149, v201
	v_lshlrev_b32_e32 v147, 2, v147
	v_mov_b32_e32 v151, v201
	v_xor_b32_e32 v147, 64, v147
	s_andn2_b64 vcc, exec, s[8:9]
	v_lshlrev_b32_e32 v151, 2, v151
	v_xor_b32_e32 v151, 64, v151
	v_lshlrev_b32_e32 v149, 2, v149
	v_xor_b32_e32 v149, 0x80, v149
	s_mov_b64 s[8:9], -1
	s_waitcnt lgkmcnt(0)
	v_mov_b32_e32 v210, v177
	v_mov_b32_e32 v211, v178
	v_mov_b32_e32 v177, v179
	v_pk_add_f32 v[176:177], v[210:211], v[176:177]
	v_mov_b32_e32 v178, v181
	v_add_f32_e32 v152, v176, v177
	v_mov_b32_e32 v179, v182
	v_mov_b32_e32 v181, v183
	v_mov_b32_e32 v147, v152
	s_nop 1
	v_permlane16_swap_b32_e32 v147, v152
	v_pk_add_f32 v[176:177], v[178:179], v[180:181]
	v_mov_b32_e32 v182, v185
	v_add_f32_e32 v155, v176, v177
	v_mov_b32_e32 v151, v155
	s_nop 1
	v_permlane16_swap_b32_e32 v151, v155
	s_waitcnt lgkmcnt(0)
	v_add_f32_e32 v147, v152, v147
	v_mov_b32_e32 v152, v201
	v_mov_b32_e32 v149, v147
	s_nop 1
	v_permlane32_swap_b32_e32 v149, v147
	s_waitcnt lgkmcnt(0)
	v_add_f32_e32 v151, v155, v151
	v_lshlrev_b32_e32 v152, 2, v152
	v_xor_b32_e32 v152, 0x80, v152
	v_mov_b32_e32 v152, v151
	s_nop 1
	v_permlane32_swap_b32_e32 v152, v151
	s_waitcnt lgkmcnt(0)
	v_add_f32_e32 v147, v147, v149
	v_mov_b32_e32 v149, v201
	v_mov_b32_e32 v183, v186
	v_mov_b32_e32 v185, v187
	v_pk_add_f32 v[178:179], v[182:183], v[184:185]
	v_fmamk_f32 v147, v147, 0x3a800000, v175
	v_lshlrev_b32_e32 v149, 2, v149
	v_add_f32_e32 v156, v178, v179
	v_rsq_f32_e32 v176, v147
	s_waitcnt lgkmcnt(0)
	v_add_f32_e32 v147, v151, v152
	v_xor_b32_e32 v149, 64, v149
	v_mov_b32_e32 v151, v201
	v_mov_b32_e32 v152, v201
	v_mov_b32_e32 v186, v189
	v_mov_b32_e32 v187, v190
	v_mov_b32_e32 v189, v191
	v_mov_b32_e32 v149, v156
	s_nop 1
	v_permlane16_swap_b32_e32 v149, v156
	v_pk_add_f32 v[180:181], v[186:187], v[188:189]
	v_lshlrev_b32_e32 v152, 2, v152
	v_add_f32_e32 v159, v180, v181
	v_xor_b32_e32 v152, 64, v152
	v_mov_b32_e32 v152, v159
	s_nop 1
	v_permlane16_swap_b32_e32 v152, v159
	s_waitcnt lgkmcnt(0)
	v_add_f32_e32 v149, v156, v149
	v_lshlrev_b32_e32 v151, 2, v151
	v_mov_b32_e32 v156, v201
	v_xor_b32_e32 v151, 0x80, v151
	v_mov_b32_e32 v151, v149
	s_nop 1
	v_permlane32_swap_b32_e32 v151, v149
	v_lshlrev_b32_e32 v156, 2, v156
	s_waitcnt lgkmcnt(0)
	v_add_f32_e32 v152, v159, v152
	v_xor_b32_e32 v156, 0x80, v156
	v_mov_b32_e32 v156, v152
	s_nop 1
	v_permlane32_swap_b32_e32 v156, v152
	v_fmamk_f32 v147, v147, 0x3a800000, v175
	v_rsq_f32_e32 v174, v147
	s_waitcnt lgkmcnt(0)
	v_add_f32_e32 v147, v149, v151
	v_mov_b32_e32 v149, v201
	v_mov_b32_e32 v190, v193
	v_mov_b32_e32 v191, v194
	v_mov_b32_e32 v193, v195
	v_fmamk_f32 v147, v147, 0x3a800000, v175
	v_pk_add_f32 v[182:183], v[190:191], v[192:193]
	v_rsq_f32_e32 v172, v147
	s_waitcnt lgkmcnt(0)
	v_add_f32_e32 v147, v152, v156
	v_lshlrev_b32_e32 v149, 2, v149
	v_mov_b32_e32 v151, v201
	v_mov_b32_e32 v152, v201
	v_mov_b32_e32 v194, v197
	v_mov_b32_e32 v195, v198
	v_mov_b32_e32 v197, v199
	v_add_f32_e32 v160, v182, v183
	v_xor_b32_e32 v149, 64, v149
	v_pk_add_f32 v[184:185], v[194:195], v[196:197]
	v_mov_b32_e32 v149, v160
	s_nop 1
	v_permlane16_swap_b32_e32 v149, v160
	v_lshlrev_b32_e32 v152, 2, v152
	v_add_f32_e32 v163, v184, v185
	v_xor_b32_e32 v152, 64, v152
	v_mov_b32_e32 v152, v163
	s_nop 1
	v_permlane16_swap_b32_e32 v152, v163
	v_lshlrev_b32_e32 v151, 2, v151
	v_mov_b32_e32 v156, v201
	s_waitcnt lgkmcnt(0)
	v_add_f32_e32 v149, v160, v149
	v_xor_b32_e32 v151, 0x80, v151
	v_mov_b32_e32 v151, v149
	s_nop 1
	v_permlane32_swap_b32_e32 v151, v149
	v_lshlrev_b32_e32 v156, 2, v156
	s_waitcnt lgkmcnt(0)
	v_add_f32_e32 v152, v163, v152
	v_xor_b32_e32 v156, 0x80, v156
	v_mov_b32_e32 v156, v152
	s_nop 1
	v_permlane32_swap_b32_e32 v156, v152
	v_fmamk_f32 v147, v147, 0x3a800000, v175
	v_rsq_f32_e32 v168, v147
	s_waitcnt lgkmcnt(0)
	v_add_f32_e32 v147, v149, v151
	v_fmamk_f32 v147, v147, 0x3a800000, v175
	v_rsq_f32_e32 v164, v147
	s_waitcnt lgkmcnt(0)
; __device__ __forceinline__ float row_finish(float t) { t += shx(t, 16); t += shx(t, 32); return __builtin_amdgcn_rsqf(t * (1.0f / 1024.0f) + RMS_EPS); }
; __device__ __forceinline__ f32x4 silu4(f32x4 v) { return (f32x4){silu_f(v[0]), silu_f(v[1]), silu_f(v[2]), silu_f(v[3])}; }
; __device__ __forceinline__ u32x4 pack8(f32x4 a, f32x4 b) { u32x4 w; w.x = cvt_pk_bf16(a[0], a[1]); w.y = cvt_pk_bf16(a[2], a[3]); w.z = cvt_pk_bf16(b[0], b[1]); w.w = cvt_pk_bf16(b[2], b[3]); return w; }
;     __device__ __forceinline__ void operator()(const f32x4 (&acc)[2][2][4][2], const Unit& u, int wr, int wc, int fr, int fq) const {
;     ...
;             for (int m = 0; m < 4; ++m) rs[ai][m] = row_finish(rs[ai][m]);
; #pragma unroll
;         for (int ai = 0; ai < 2; ++ai)
; #pragma unroll
;             for (int m = 0; m < 4; ++m) {
;                 const int row = u.pm * BM + ai * HALF + wr * 64 + m * 16 + fr;
;                 const float rstd = rs[ai][m];
;                 const f32x4 a0 = silu4(acc[ai][0][m][0] * rstd) * (acc[ai][1][m][0] * rstd);
;                 const f32x4 a1 = silu4(acc[ai][0][m][1] * rstd) * (acc[ai][1][m][1] * rstd);
;                 *(u32x4*)(ACT + (size_t)row * 2816 + col0) = pack8(a0, a1);
	v_add_f32_e32 v147, v152, v156
	v_mov_b32_e32 v149, v201
	v_mov_b32_e32 v151, v201
	v_mov_b32_e32 v152, v201
	v_mov_b32_e32 v198, v203
	v_mov_b32_e32 v199, v204
	v_mov_b32_e32 v203, v205
	v_mov_b32_e32 v204, v207
	v_mov_b32_e32 v205, v208
	v_mov_b32_e32 v207, v209
	v_pk_add_f32 v[188:189], v[204:205], v[206:207]
	v_lshlrev_b32_e32 v152, 2, v152
	v_pk_add_f32 v[186:187], v[198:199], v[202:203]
	v_add_f32_e32 v155, v188, v189
	v_lshlrev_b32_e32 v149, 2, v149
	v_xor_b32_e32 v152, 64, v152
	v_add_f32_e32 v167, v186, v187
	v_xor_b32_e32 v149, 64, v149
	v_mov_b32_e32 v152, v155
	s_nop 1
	v_permlane16_swap_b32_e32 v152, v155
	v_mov_b32_e32 v149, v167
	s_nop 1
	v_permlane16_swap_b32_e32 v149, v167
	v_lshlrev_b32_e32 v151, 2, v151
	v_xor_b32_e32 v151, 0x80, v151
	v_fmamk_f32 v147, v147, 0x3a800000, v175
	s_waitcnt lgkmcnt(0)
	v_add_f32_e32 v152, v155, v152
	v_mov_b32_e32 v155, v201
	s_waitcnt lgkmcnt(0)
	v_add_f32_e32 v149, v167, v149
	v_mov_b32_e32 v151, v149
	s_nop 1
	v_permlane32_swap_b32_e32 v151, v149
	v_lshlrev_b32_e32 v155, 2, v155
	v_xor_b32_e32 v155, 0x80, v155
	v_mov_b32_e32 v155, v152
	s_nop 1
	v_permlane32_swap_b32_e32 v155, v152
	v_rsq_f32_e32 v160, v147
	s_waitcnt lgkmcnt(0)
	v_add_f32_e32 v147, v149, v151
	v_fmamk_f32 v147, v147, 0x3a800000, v175
	v_rsq_f32_e32 v156, v147
	s_waitcnt lgkmcnt(0)
	v_add_f32_e32 v147, v152, v155
	v_fmamk_f32 v147, v147, 0x3a800000, v175
	v_pk_mul_f32 v[124:125], v[124:125], v[176:177] op_sel_hi:[1,0]
	v_rsq_f32_e32 v152, v147
	v_mul_f32_e32 v147, 0xbfb8aa3b, v124
	v_exp_f32_e32 v147, v147
	v_mul_f32_e32 v149, 0xbfb8aa3b, v125
	v_exp_f32_e32 v149, v149
	v_pk_mul_f32 v[126:127], v[126:127], v[176:177] op_sel_hi:[1,0]
	v_add_f32_e32 v147, 1.0, v147
	v_rcp_f32_e32 v178, v147
	v_add_f32_e32 v147, 1.0, v149
	v_mul_f32_e32 v149, 0xbfb8aa3b, v126
	v_exp_f32_e32 v149, v149
	v_mul_f32_e32 v151, 0xbfb8aa3b, v127
	v_exp_f32_e32 v151, v151
	v_rcp_f32_e32 v179, v147
	v_add_f32_e32 v147, 1.0, v149
	v_rcp_f32_e32 v180, v147
	v_add_f32_e32 v147, 1.0, v151
	v_pk_mul_f32 v[120:121], v[120:121], v[176:177] op_sel_hi:[1,0]
	v_rcp_f32_e32 v181, v147
	v_mul_f32_e32 v147, 0xbfb8aa3b, v120
	v_exp_f32_e32 v147, v147
	v_mul_f32_e32 v149, 0xbfb8aa3b, v121
	v_exp_f32_e32 v149, v149
	v_pk_mul_f32 v[122:123], v[122:123], v[176:177] op_sel_hi:[1,0]
	v_add_f32_e32 v147, 1.0, v147
	v_pk_mul_f32 v[124:125], v[124:125], v[178:179]
	v_rcp_f32_e32 v178, v147
	v_add_f32_e32 v147, 1.0, v149
	v_mul_f32_e32 v149, 0xbfb8aa3b, v122
	v_exp_f32_e32 v149, v149
	v_mul_f32_e32 v151, 0xbfb8aa3b, v123
	v_exp_f32_e32 v151, v151
	v_rcp_f32_e32 v179, v147
	v_add_f32_e32 v147, 1.0, v149
	v_pk_mul_f32 v[126:127], v[126:127], v[180:181]
	v_rcp_f32_e32 v180, v147
	v_add_f32_e32 v147, 1.0, v151
	v_rcp_f32_e32 v181, v147
	v_pk_mul_f32 v[116:117], v[116:117], v[176:177] op_sel_hi:[1,0]
	v_pk_mul_f32 v[118:119], v[118:119], v[176:177] op_sel_hi:[1,0]
	v_pk_mul_f32 v[120:121], v[120:121], v[178:179]
	v_pk_mul_f32 v[112:113], v[112:113], v[176:177] op_sel_hi:[1,0]
	v_lshl_or_b32 v182, s61, 7, v161
	v_pk_mul_f32 v[118:119], v[118:119], v[126:127]
	v_pk_mul_f32 v[116:117], v[116:117], v[124:125]
	v_pk_mul_f32 v[122:123], v[122:123], v[180:181]
	v_pk_mul_f32 v[114:115], v[114:115], v[176:177] op_sel_hi:[1,0]
	v_pk_mul_f32 v[112:113], v[112:113], v[120:121]
	v_ashrrev_i32_e32 v183, 31, v182
	v_pk_mul_f32 v[114:115], v[114:115], v[122:123]
	v_cvt_pk_bf16_f32 v116, v116, v117
	v_cvt_pk_bf16_f32 v117, v118, v119
	v_cvt_pk_bf16_f32 v118, v112, v113
	v_mov_b64_e32 v[112:113], s[16:17]
	v_cvt_pk_bf16_f32 v119, v114, v115
	v_mad_i64_i32 v[120:121], s[46:47], v170, s60, v[112:113]
	v_lshlrev_b64 v[114:115], 1, v[182:183]
	v_pk_mul_f32 v[108:109], v[108:109], v[174:175] op_sel_hi:[1,0]
	v_pk_mul_f32 v[110:111], v[110:111], v[174:175] op_sel_hi:[1,0]
	v_mul_f32_e32 v122, 0xbfb8aa3b, v108
	v_mul_f32_e32 v123, 0xbfb8aa3b, v109
	v_lshl_add_u64 v[120:121], v[120:121], 0, v[114:115]
	v_pk_mul_f32 v[104:105], v[104:105], v[174:175] op_sel_hi:[1,0]
	v_pk_mul_f32 v[106:107], v[106:107], v[174:175] op_sel_hi:[1,0]
	v_exp_f32_e32 v122, v122
	v_exp_f32_e32 v123, v123
	v_mul_f32_e32 v124, 0xbfb8aa3b, v110
	v_mul_f32_e32 v125, 0xbfb8aa3b, v111
	global_store_dwordx4 v[120:121], v[116:119], off sc1
	v_exp_f32_e32 v124, v124
	v_exp_f32_e32 v125, v125
	v_mul_f32_e32 v116, 0xbfb8aa3b, v104
	v_mul_f32_e32 v117, 0xbfb8aa3b, v105
	v_mul_f32_e32 v118, 0xbfb8aa3b, v106
	v_mul_f32_e32 v119, 0xbfb8aa3b, v107
	v_exp_f32_e32 v116, v116
	v_exp_f32_e32 v117, v117
	v_exp_f32_e32 v118, v118
	v_exp_f32_e32 v119, v119
	v_add_f32_e32 v122, 1.0, v122
	v_add_f32_e32 v123, 1.0, v123
	v_rcp_f32_e32 v122, v122
	v_rcp_f32_e32 v123, v123
	v_add_f32_e32 v124, 1.0, v124
	v_add_f32_e32 v125, 1.0, v125
	v_add_f32_e32 v116, 1.0, v116
	v_add_f32_e32 v117, 1.0, v117
	v_add_f32_e32 v118, 1.0, v118
	v_add_f32_e32 v119, 1.0, v119
	v_rcp_f32_e32 v124, v124
	v_rcp_f32_e32 v125, v125
	v_rcp_f32_e32 v116, v116
	v_rcp_f32_e32 v117, v117
	v_rcp_f32_e32 v118, v118
	v_rcp_f32_e32 v119, v119
	v_pk_mul_f32 v[108:109], v[108:109], v[122:123]
	v_pk_mul_f32 v[100:101], v[100:101], v[174:175] op_sel_hi:[1,0]
	v_pk_mul_f32 v[110:111], v[110:111], v[124:125]
	v_pk_mul_f32 v[102:103], v[102:103], v[174:175] op_sel_hi:[1,0]
	v_pk_mul_f32 v[100:101], v[100:101], v[108:109]
	v_pk_mul_f32 v[104:105], v[104:105], v[116:117]
	v_pk_mul_f32 v[106:107], v[106:107], v[118:119]
	v_pk_mul_f32 v[96:97], v[96:97], v[174:175] op_sel_hi:[1,0]
	v_pk_mul_f32 v[98:99], v[98:99], v[174:175] op_sel_hi:[1,0]
	v_pk_mul_f32 v[102:103], v[102:103], v[110:111]
	v_pk_mul_f32 v[106:107], v[98:99], v[106:107]
	v_pk_mul_f32 v[98:99], v[96:97], v[104:105]
; __device__ __forceinline__ f32x4 silu4(f32x4 v) { return (f32x4){silu_f(v[0]), silu_f(v[1]), silu_f(v[2]), silu_f(v[3])}; }
; __device__ __forceinline__ u32x4 pack8(f32x4 a, f32x4 b) { u32x4 w; w.x = cvt_pk_bf16(a[0], a[1]); w.y = cvt_pk_bf16(a[2], a[3]); w.z = cvt_pk_bf16(b[0], b[1]); w.w = cvt_pk_bf16(b[2], b[3]); return w; }
;     __device__ __forceinline__ void operator()(const f32x4 (&acc)[2][2][4][2], const Unit& u, int wr, int wc, int fr, int fq) const {
;     ...
;         for (int ai = 0; ai < 2; ++ai)
; #pragma unroll
;             for (int m = 0; m < 4; ++m) {
;                 const int row = u.pm * BM + ai * HALF + wr * 64 + m * 16 + fr;
;                 const float rstd = rs[ai][m];
;                 const f32x4 a0 = silu4(acc[ai][0][m][0] * rstd) * (acc[ai][1][m][0] * rstd);
;                 const f32x4 a1 = silu4(acc[ai][0][m][1] * rstd) * (acc[ai][1][m][1] * rstd);
;                 *(u32x4*)(ACT + (size_t)row * 2816 + col0) = pack8(a0, a1);
	v_cvt_pk_bf16_f32 v96, v100, v101
	v_mad_i64_i32 v[100:101], s[46:47], v166, s60, v[112:113]
	v_pk_mul_f32 v[92:93], v[92:93], v[172:173] op_sel_hi:[1,0]
	v_cvt_pk_bf16_f32 v97, v102, v103
	v_cvt_pk_bf16_f32 v98, v98, v99
	v_cvt_pk_bf16_f32 v99, v106, v107
	v_pk_mul_f32 v[94:95], v[94:95], v[172:173] op_sel_hi:[1,0]
	v_mul_f32_e32 v102, 0xbfb8aa3b, v92
	v_mul_f32_e32 v103, 0xbfb8aa3b, v93
	v_lshl_add_u64 v[100:101], v[100:101], 0, v[114:115]
	v_pk_mul_f32 v[88:89], v[88:89], v[172:173] op_sel_hi:[1,0]
	v_pk_mul_f32 v[90:91], v[90:91], v[172:173] op_sel_hi:[1,0]
	v_exp_f32_e32 v102, v102
	v_exp_f32_e32 v103, v103
	v_mul_f32_e32 v104, 0xbfb8aa3b, v94
	v_mul_f32_e32 v105, 0xbfb8aa3b, v95
	global_store_dwordx4 v[100:101], v[96:99], off sc1
	v_exp_f32_e32 v104, v104
	v_exp_f32_e32 v105, v105
	v_mul_f32_e32 v96, 0xbfb8aa3b, v88
	v_mul_f32_e32 v97, 0xbfb8aa3b, v89
	v_mul_f32_e32 v98, 0xbfb8aa3b, v90
	v_mul_f32_e32 v99, 0xbfb8aa3b, v91
	v_exp_f32_e32 v96, v96
	v_exp_f32_e32 v97, v97
	v_exp_f32_e32 v98, v98
	v_exp_f32_e32 v99, v99
	v_add_f32_e32 v102, 1.0, v102
	v_add_f32_e32 v103, 1.0, v103
	v_rcp_f32_e32 v102, v102
	v_rcp_f32_e32 v103, v103
	v_add_f32_e32 v104, 1.0, v104
	v_add_f32_e32 v105, 1.0, v105
	v_add_f32_e32 v96, 1.0, v96
	v_add_f32_e32 v97, 1.0, v97
	v_add_f32_e32 v98, 1.0, v98
	v_add_f32_e32 v99, 1.0, v99
	v_rcp_f32_e32 v104, v104
	v_rcp_f32_e32 v105, v105
	v_rcp_f32_e32 v96, v96
	v_rcp_f32_e32 v97, v97
	v_rcp_f32_e32 v98, v98
	v_rcp_f32_e32 v99, v99
	v_pk_mul_f32 v[92:93], v[92:93], v[102:103]
	v_pk_mul_f32 v[84:85], v[84:85], v[172:173] op_sel_hi:[1,0]
	v_pk_mul_f32 v[94:95], v[94:95], v[104:105]
	v_pk_mul_f32 v[86:87], v[86:87], v[172:173] op_sel_hi:[1,0]
	v_pk_mul_f32 v[84:85], v[84:85], v[92:93]
	v_pk_mul_f32 v[88:89], v[88:89], v[96:97]
	v_pk_mul_f32 v[90:91], v[90:91], v[98:99]
	v_pk_mul_f32 v[80:81], v[80:81], v[172:173] op_sel_hi:[1,0]
	v_pk_mul_f32 v[82:83], v[82:83], v[172:173] op_sel_hi:[1,0]
	v_pk_mul_f32 v[86:87], v[86:87], v[94:95]
	v_pk_mul_f32 v[90:91], v[82:83], v[90:91]
	v_pk_mul_f32 v[82:83], v[80:81], v[88:89]
	v_cvt_pk_bf16_f32 v80, v84, v85
	v_mad_i64_i32 v[84:85], s[46:47], v162, s60, v[112:113]
	v_pk_mul_f32 v[76:77], v[76:77], v[168:169] op_sel_hi:[1,0]
	v_cvt_pk_bf16_f32 v81, v86, v87
	v_cvt_pk_bf16_f32 v82, v82, v83
	v_cvt_pk_bf16_f32 v83, v90, v91
	v_pk_mul_f32 v[78:79], v[78:79], v[168:169] op_sel_hi:[1,0]
	v_mul_f32_e32 v86, 0xbfb8aa3b, v76
	v_mul_f32_e32 v87, 0xbfb8aa3b, v77
	v_lshl_add_u64 v[84:85], v[84:85], 0, v[114:115]
	v_pk_mul_f32 v[72:73], v[72:73], v[168:169] op_sel_hi:[1,0]
	v_pk_mul_f32 v[74:75], v[74:75], v[168:169] op_sel_hi:[1,0]
	v_exp_f32_e32 v86, v86
	v_exp_f32_e32 v87, v87
	v_mul_f32_e32 v88, 0xbfb8aa3b, v78
	v_mul_f32_e32 v89, 0xbfb8aa3b, v79
	global_store_dwordx4 v[84:85], v[80:83], off sc1
	v_exp_f32_e32 v88, v88
	v_exp_f32_e32 v89, v89
	v_mul_f32_e32 v80, 0xbfb8aa3b, v72
	v_mul_f32_e32 v81, 0xbfb8aa3b, v73
	v_mul_f32_e32 v82, 0xbfb8aa3b, v74
	v_mul_f32_e32 v83, 0xbfb8aa3b, v75
	v_exp_f32_e32 v80, v80
	v_exp_f32_e32 v81, v81
	v_exp_f32_e32 v82, v82
	v_exp_f32_e32 v83, v83
	v_add_f32_e32 v86, 1.0, v86
	v_add_f32_e32 v87, 1.0, v87
	v_rcp_f32_e32 v86, v86
	v_rcp_f32_e32 v87, v87
	v_add_f32_e32 v88, 1.0, v88
	v_add_f32_e32 v89, 1.0, v89
	v_add_f32_e32 v80, 1.0, v80
	v_add_f32_e32 v81, 1.0, v81
	v_add_f32_e32 v82, 1.0, v82
	v_add_f32_e32 v83, 1.0, v83
	v_rcp_f32_e32 v88, v88
	v_rcp_f32_e32 v89, v89
	v_rcp_f32_e32 v80, v80
	v_rcp_f32_e32 v81, v81
	v_rcp_f32_e32 v82, v82
	v_rcp_f32_e32 v83, v83
	v_pk_mul_f32 v[76:77], v[76:77], v[86:87]
	v_pk_mul_f32 v[68:69], v[68:69], v[168:169] op_sel_hi:[1,0]
	v_pk_mul_f32 v[78:79], v[78:79], v[88:89]
	v_pk_mul_f32 v[70:71], v[70:71], v[168:169] op_sel_hi:[1,0]
	v_pk_mul_f32 v[68:69], v[68:69], v[76:77]
	v_pk_mul_f32 v[72:73], v[72:73], v[80:81]
	v_pk_mul_f32 v[74:75], v[74:75], v[82:83]
	v_pk_mul_f32 v[64:65], v[64:65], v[168:169] op_sel_hi:[1,0]
	v_pk_mul_f32 v[66:67], v[66:67], v[168:169] op_sel_hi:[1,0]
	v_pk_mul_f32 v[70:71], v[70:71], v[78:79]
	v_pk_mul_f32 v[74:75], v[66:67], v[74:75]
	v_pk_mul_f32 v[66:67], v[64:65], v[72:73]
	v_cvt_pk_bf16_f32 v64, v68, v69
	v_mad_i64_i32 v[68:69], s[46:47], v158, s60, v[112:113]
	v_pk_mul_f32 v[60:61], v[60:61], v[164:165] op_sel_hi:[1,0]
	v_cvt_pk_bf16_f32 v65, v70, v71
	v_cvt_pk_bf16_f32 v66, v66, v67
	v_cvt_pk_bf16_f32 v67, v74, v75
	v_pk_mul_f32 v[62:63], v[62:63], v[164:165] op_sel_hi:[1,0]
	v_mul_f32_e32 v70, 0xbfb8aa3b, v60
	v_mul_f32_e32 v71, 0xbfb8aa3b, v61
	v_lshl_add_u64 v[68:69], v[68:69], 0, v[114:115]
	v_pk_mul_f32 v[56:57], v[56:57], v[164:165] op_sel_hi:[1,0]
	v_pk_mul_f32 v[58:59], v[58:59], v[164:165] op_sel_hi:[1,0]
	v_exp_f32_e32 v70, v70
	v_exp_f32_e32 v71, v71
	v_mul_f32_e32 v72, 0xbfb8aa3b, v62
	v_mul_f32_e32 v73, 0xbfb8aa3b, v63
	global_store_dwordx4 v[68:69], v[64:67], off sc1
	v_exp_f32_e32 v72, v72
	v_exp_f32_e32 v73, v73
	v_mul_f32_e32 v64, 0xbfb8aa3b, v56
	v_mul_f32_e32 v65, 0xbfb8aa3b, v57
	v_mul_f32_e32 v66, 0xbfb8aa3b, v58
	v_mul_f32_e32 v67, 0xbfb8aa3b, v59
	v_exp_f32_e32 v64, v64
	v_exp_f32_e32 v65, v65
	v_exp_f32_e32 v66, v66
	v_exp_f32_e32 v67, v67
	v_add_f32_e32 v70, 1.0, v70
	v_add_f32_e32 v71, 1.0, v71
	v_rcp_f32_e32 v70, v70
	v_rcp_f32_e32 v71, v71
	v_add_f32_e32 v72, 1.0, v72
	v_add_f32_e32 v73, 1.0, v73
	v_add_f32_e32 v64, 1.0, v64
	v_add_f32_e32 v65, 1.0, v65
	v_add_f32_e32 v66, 1.0, v66
	v_add_f32_e32 v67, 1.0, v67
	v_rcp_f32_e32 v72, v72
	v_rcp_f32_e32 v73, v73
	v_rcp_f32_e32 v64, v64
	v_rcp_f32_e32 v65, v65
	v_rcp_f32_e32 v66, v66
	v_rcp_f32_e32 v67, v67
	v_pk_mul_f32 v[60:61], v[60:61], v[70:71]
	v_pk_mul_f32 v[52:53], v[52:53], v[164:165] op_sel_hi:[1,0]
; __device__ __forceinline__ f32x4 silu4(f32x4 v) { return (f32x4){silu_f(v[0]), silu_f(v[1]), silu_f(v[2]), silu_f(v[3])}; }
; __device__ __forceinline__ u32x4 pack8(f32x4 a, f32x4 b) { u32x4 w; w.x = cvt_pk_bf16(a[0], a[1]); w.y = cvt_pk_bf16(a[2], a[3]); w.z = cvt_pk_bf16(b[0], b[1]); w.w = cvt_pk_bf16(b[2], b[3]); return w; }
; #define PG8_BAR __builtin_amdgcn_s_barrier()
;     __device__ __forceinline__ void operator()(const f32x4 (&acc)[2][2][4][2], const Unit& u, int wr, int wc, int fr, int fq) const {
;     ...
;         for (int ai = 0; ai < 2; ++ai)
; #pragma unroll
;             for (int m = 0; m < 4; ++m) {
;                 const int row = u.pm * BM + ai * HALF + wr * 64 + m * 16 + fr;
;                 const float rstd = rs[ai][m];
;                 const f32x4 a0 = silu4(acc[ai][0][m][0] * rstd) * (acc[ai][1][m][0] * rstd);
;                 const f32x4 a1 = silu4(acc[ai][0][m][1] * rstd) * (acc[ai][1][m][1] * rstd);
;                 *(u32x4*)(ACT + (size_t)row * 2816 + col0) = pack8(a0, a1);
;             }
; template <class Epi, class Sched, bool ALIGN_EPI = false, bool SP2 = false>
; __device__ __forceinline__ void gemm_phase(PG8_LAS unsigned char* lds, const Gemm g, const Sched& S, const Epi& E, int tid_in) {
;     ...
;         if (!has_next) break;
; #pragma unroll
;         for (int a = 0; a < 2; ++a)
; #pragma unroll
;             for (int b = 0; b < 2; ++b)
; #pragma unroll
;                 for (int m = 0; m < 4; ++m)
; #pragma unroll
;                     for (int n = 0; n < 2; ++n) acc[a][b][m][n] = (f32x4){0.f, 0.f, 0.f, 0.f};
;         cur = nxt; cA = nA; cB = nB; ++ui;
;         if constexpr (ALIGN_EPI) { if (wr == 1) PG8_BAR; }
	v_pk_mul_f32 v[62:63], v[62:63], v[72:73]
	v_pk_mul_f32 v[54:55], v[54:55], v[164:165] op_sel_hi:[1,0]
	v_pk_mul_f32 v[52:53], v[52:53], v[60:61]
	v_pk_mul_f32 v[56:57], v[56:57], v[64:65]
	v_pk_mul_f32 v[58:59], v[58:59], v[66:67]
	v_pk_mul_f32 v[48:49], v[48:49], v[164:165] op_sel_hi:[1,0]
	v_pk_mul_f32 v[50:51], v[50:51], v[164:165] op_sel_hi:[1,0]
	v_pk_mul_f32 v[54:55], v[54:55], v[62:63]
	v_pk_mul_f32 v[58:59], v[50:51], v[58:59]
	v_pk_mul_f32 v[50:51], v[48:49], v[56:57]
	v_cvt_pk_bf16_f32 v48, v52, v53
	v_mad_i64_i32 v[52:53], s[46:47], v154, s60, v[112:113]
	v_pk_mul_f32 v[44:45], v[44:45], v[160:161] op_sel_hi:[1,0]
	v_cvt_pk_bf16_f32 v49, v54, v55
	v_cvt_pk_bf16_f32 v50, v50, v51
	v_cvt_pk_bf16_f32 v51, v58, v59
	v_pk_mul_f32 v[46:47], v[46:47], v[160:161] op_sel_hi:[1,0]
	v_mul_f32_e32 v54, 0xbfb8aa3b, v44
	v_mul_f32_e32 v55, 0xbfb8aa3b, v45
	v_lshl_add_u64 v[52:53], v[52:53], 0, v[114:115]
	v_pk_mul_f32 v[40:41], v[40:41], v[160:161] op_sel_hi:[1,0]
	v_pk_mul_f32 v[42:43], v[42:43], v[160:161] op_sel_hi:[1,0]
	v_exp_f32_e32 v54, v54
	v_exp_f32_e32 v55, v55
	v_mul_f32_e32 v56, 0xbfb8aa3b, v46
	v_mul_f32_e32 v57, 0xbfb8aa3b, v47
	global_store_dwordx4 v[52:53], v[48:51], off sc1
	v_exp_f32_e32 v56, v56
	v_exp_f32_e32 v57, v57
	v_mul_f32_e32 v48, 0xbfb8aa3b, v40
	v_mul_f32_e32 v49, 0xbfb8aa3b, v41
	v_mul_f32_e32 v50, 0xbfb8aa3b, v42
	v_mul_f32_e32 v51, 0xbfb8aa3b, v43
	v_exp_f32_e32 v48, v48
	v_exp_f32_e32 v49, v49
	v_exp_f32_e32 v50, v50
	v_exp_f32_e32 v51, v51
	v_add_f32_e32 v54, 1.0, v54
	v_add_f32_e32 v55, 1.0, v55
	v_rcp_f32_e32 v54, v54
	v_rcp_f32_e32 v55, v55
	v_add_f32_e32 v56, 1.0, v56
	v_add_f32_e32 v57, 1.0, v57
	v_add_f32_e32 v48, 1.0, v48
	v_add_f32_e32 v49, 1.0, v49
	v_add_f32_e32 v50, 1.0, v50
	v_add_f32_e32 v51, 1.0, v51
	v_rcp_f32_e32 v56, v56
	v_rcp_f32_e32 v57, v57
	v_rcp_f32_e32 v48, v48
	v_rcp_f32_e32 v49, v49
	v_rcp_f32_e32 v50, v50
	v_rcp_f32_e32 v51, v51
	v_pk_mul_f32 v[44:45], v[44:45], v[54:55]
	v_pk_mul_f32 v[36:37], v[36:37], v[160:161] op_sel_hi:[1,0]
	v_pk_mul_f32 v[46:47], v[46:47], v[56:57]
	v_pk_mul_f32 v[38:39], v[38:39], v[160:161] op_sel_hi:[1,0]
	v_pk_mul_f32 v[36:37], v[36:37], v[44:45]
	v_pk_mul_f32 v[40:41], v[40:41], v[48:49]
	v_pk_mul_f32 v[42:43], v[42:43], v[50:51]
	v_pk_mul_f32 v[32:33], v[32:33], v[160:161] op_sel_hi:[1,0]
	v_pk_mul_f32 v[34:35], v[34:35], v[160:161] op_sel_hi:[1,0]
	v_pk_mul_f32 v[38:39], v[38:39], v[46:47]
	v_pk_mul_f32 v[42:43], v[34:35], v[42:43]
	v_pk_mul_f32 v[34:35], v[32:33], v[40:41]
	v_cvt_pk_bf16_f32 v32, v36, v37
	v_mad_i64_i32 v[36:37], s[46:47], v150, s60, v[112:113]
	v_pk_mul_f32 v[28:29], v[28:29], v[156:157] op_sel_hi:[1,0]
	v_cvt_pk_bf16_f32 v33, v38, v39
	v_cvt_pk_bf16_f32 v34, v34, v35
	v_cvt_pk_bf16_f32 v35, v42, v43
	v_pk_mul_f32 v[30:31], v[30:31], v[156:157] op_sel_hi:[1,0]
	v_mul_f32_e32 v38, 0xbfb8aa3b, v28
	v_mul_f32_e32 v39, 0xbfb8aa3b, v29
	v_lshl_add_u64 v[36:37], v[36:37], 0, v[114:115]
	v_pk_mul_f32 v[24:25], v[24:25], v[156:157] op_sel_hi:[1,0]
	v_pk_mul_f32 v[26:27], v[26:27], v[156:157] op_sel_hi:[1,0]
	v_exp_f32_e32 v38, v38
	v_exp_f32_e32 v39, v39
	v_mul_f32_e32 v40, 0xbfb8aa3b, v30
	v_mul_f32_e32 v41, 0xbfb8aa3b, v31
	global_store_dwordx4 v[36:37], v[32:35], off sc1
	v_exp_f32_e32 v40, v40
	v_exp_f32_e32 v41, v41
	v_mul_f32_e32 v32, 0xbfb8aa3b, v24
	v_mul_f32_e32 v33, 0xbfb8aa3b, v25
	v_mul_f32_e32 v34, 0xbfb8aa3b, v26
	v_mul_f32_e32 v35, 0xbfb8aa3b, v27
	v_exp_f32_e32 v32, v32
	v_exp_f32_e32 v33, v33
	v_exp_f32_e32 v34, v34
	v_exp_f32_e32 v35, v35
	v_add_f32_e32 v38, 1.0, v38
	v_add_f32_e32 v39, 1.0, v39
	v_rcp_f32_e32 v38, v38
	v_rcp_f32_e32 v39, v39
	v_add_f32_e32 v40, 1.0, v40
	v_add_f32_e32 v41, 1.0, v41
	v_add_f32_e32 v32, 1.0, v32
	v_add_f32_e32 v33, 1.0, v33
	v_add_f32_e32 v34, 1.0, v34
	v_add_f32_e32 v35, 1.0, v35
	v_rcp_f32_e32 v40, v40
	v_rcp_f32_e32 v41, v41
	v_rcp_f32_e32 v32, v32
	v_rcp_f32_e32 v33, v33
	v_rcp_f32_e32 v34, v34
	v_rcp_f32_e32 v35, v35
	v_pk_mul_f32 v[28:29], v[28:29], v[38:39]
	v_pk_mul_f32 v[20:21], v[20:21], v[156:157] op_sel_hi:[1,0]
	v_pk_mul_f32 v[30:31], v[30:31], v[40:41]
	v_pk_mul_f32 v[22:23], v[22:23], v[156:157] op_sel_hi:[1,0]
	v_pk_mul_f32 v[20:21], v[20:21], v[28:29]
	v_pk_mul_f32 v[24:25], v[24:25], v[32:33]
	v_pk_mul_f32 v[26:27], v[26:27], v[34:35]
	v_pk_mul_f32 v[16:17], v[16:17], v[156:157] op_sel_hi:[1,0]
	v_pk_mul_f32 v[18:19], v[18:19], v[156:157] op_sel_hi:[1,0]
	v_pk_mul_f32 v[22:23], v[22:23], v[30:31]
	v_pk_mul_f32 v[26:27], v[18:19], v[26:27]
	v_pk_mul_f32 v[18:19], v[16:17], v[24:25]
	v_cvt_pk_bf16_f32 v16, v20, v21
	v_mad_i64_i32 v[20:21], s[46:47], v148, s60, v[112:113]
	v_pk_mul_f32 v[12:13], v[12:13], v[152:153] op_sel_hi:[1,0]
	v_cvt_pk_bf16_f32 v17, v22, v23
	v_cvt_pk_bf16_f32 v18, v18, v19
	v_cvt_pk_bf16_f32 v19, v26, v27
	v_lshl_add_u64 v[20:21], v[20:21], 0, v[114:115]
	v_mul_f32_e32 v22, 0xbfb8aa3b, v12
	v_mul_f32_e32 v23, 0xbfb8aa3b, v13
	v_pk_mul_f32 v[8:9], v[8:9], v[152:153] op_sel_hi:[1,0]
	v_pk_mul_f32 v[10:11], v[10:11], v[152:153] op_sel_hi:[1,0]
	v_exp_f32_e32 v22, v22
	v_exp_f32_e32 v23, v23
	global_store_dwordx4 v[20:21], v[16:19], off sc1
	v_pk_mul_f32 v[14:15], v[14:15], v[152:153] op_sel_hi:[1,0]
	v_add_f32_e32 v22, 1.0, v22
	v_mul_f32_e32 v16, 0xbfb8aa3b, v8
	v_mul_f32_e32 v17, 0xbfb8aa3b, v9
	v_mul_f32_e32 v18, 0xbfb8aa3b, v10
	v_mul_f32_e32 v19, 0xbfb8aa3b, v11
	v_exp_f32_e32 v16, v16
	v_exp_f32_e32 v17, v17
	v_exp_f32_e32 v18, v18
	v_exp_f32_e32 v19, v19
	v_mul_f32_e32 v24, 0xbfb8aa3b, v14
	v_mul_f32_e32 v25, 0xbfb8aa3b, v15
	v_exp_f32_e32 v24, v24
	v_exp_f32_e32 v25, v25
	v_add_f32_e32 v23, 1.0, v23
	v_rcp_f32_e32 v22, v22
	v_rcp_f32_e32 v23, v23
	v_add_f32_e32 v16, 1.0, v16
	v_add_f32_e32 v17, 1.0, v17
	v_add_f32_e32 v18, 1.0, v18
	v_add_f32_e32 v19, 1.0, v19
	v_rcp_f32_e32 v16, v16
	v_rcp_f32_e32 v17, v17
	v_rcp_f32_e32 v18, v18
	v_rcp_f32_e32 v19, v19
	v_add_f32_e32 v24, 1.0, v24
	v_add_f32_e32 v25, 1.0, v25
	v_rcp_f32_e32 v24, v24
	v_rcp_f32_e32 v25, v25
	v_pk_mul_f32 v[12:13], v[12:13], v[22:23]
	v_pk_mul_f32 v[4:5], v[4:5], v[152:153] op_sel_hi:[1,0]
	v_pk_mul_f32 v[8:9], v[8:9], v[16:17]
	v_pk_mul_f32 v[4:5], v[4:5], v[12:13]
	v_pk_mul_f32 v[10:11], v[10:11], v[18:19]
	v_pk_mul_f32 v[0:1], v[0:1], v[152:153] op_sel_hi:[1,0]
	v_pk_mul_f32 v[2:3], v[2:3], v[152:153] op_sel_hi:[1,0]
	v_pk_mul_f32 v[14:15], v[14:15], v[24:25]
	v_pk_mul_f32 v[10:11], v[2:3], v[10:11]
	v_pk_mul_f32 v[2:3], v[0:1], v[8:9]
	v_cvt_pk_bf16_f32 v0, v4, v5
	v_mad_i64_i32 v[4:5], s[46:47], v146, s60, v[112:113]
	v_pk_mul_f32 v[6:7], v[6:7], v[152:153] op_sel_hi:[1,0]
	v_lshl_add_u64 v[4:5], v[4:5], 0, v[114:115]
	v_pk_mul_f32 v[6:7], v[6:7], v[14:15]
	s_nop 0
	v_cvt_pk_bf16_f32 v1, v6, v7
	v_cvt_pk_bf16_f32 v2, v2, v3
	v_cvt_pk_bf16_f32 v3, v10, v11
	global_store_dwordx4 v[4:5], v[0:3], off sc1
	s_cbranch_vccnz .LBB0_1584
	s_andn2_b64 vcc, exec, s[14:15]
	s_cbranch_vccnz .LBB0_1583
	s_barrier
	s_branch .LBB0_1583

; __device__ __forceinline__ float sq4(f32x4 v) { return (v[0] * v[0] + v[1] * v[1]) + (v[2] * v[2] + v[3] * v[3]); }
; __device__ __forceinline__ u32x4 pack8(f32x4 a, f32x4 b) { u32x4 w; w.x = cvt_pk_bf16(a[0], a[1]); w.y = cvt_pk_bf16(a[2], a[3]); w.z = cvt_pk_bf16(b[0], b[1]); w.w = cvt_pk_bf16(b[2], b[3]); return w; }
;     __device__ __forceinline__ void operator()(const f32x4 (&acc)[2][2][4][2], const Unit& u, int wr, int wc, int fr, int fq) const {
;         const int col0 = u.pn * 256 + 32 * wc + 8 * fq;
; #pragma unroll
;         for (int ai = 0; ai < 2; ++ai) {
;             u32x4 bs[4][2];
; #pragma unroll
;             for (int m = 0; m < 4; ++m)
; #pragma unroll
;                 for (int bj = 0; bj < 2; ++bj) bs[m][bj] = *(const u32x4*)(xb + (size_t)(u.pm * BM + ai * HALF + wr * 64 + m * 16 + fr) * 1024 + col0 + 128 * bj);
; #pragma unroll
;             for (int m = 0; m < 4; ++m) {
;                 const int row = u.pm * BM + ai * HALF + wr * 64 + m * 16 + fr;
;                 float q = 0.f;
; #pragma unroll
;                 for (int bj = 0; bj < 2; ++bj) {
;                     const size_t off = (size_t)row * 1024 + col0 + 128 * bj; const u32x4 w = bs[m][bj];
;                     const f32x4 b0 = (f32x4){__builtin_bit_cast(float, w.x << 16), __builtin_bit_cast(float, w.x & 0xffff0000u), __builtin_bit_cast(float, w.y << 16), __builtin_bit_cast(float, w.y & 0xffff0000u)};
;                     const f32x4 b1 = (f32x4){__builtin_bit_cast(float, w.z << 16), __builtin_bit_cast(float, w.z & 0xffff0000u), __builtin_bit_cast(float, w.w << 16), __builtin_bit_cast(float, w.w & 0xffff0000u)};
;                     const f32x4 v0 = acc[ai][bj][m][0] + b0, v1 = acc[ai][bj][m][1] + b1;
;                     if (last) { __builtin_nontemporal_store(v0, (f32x4*)(out + off)); __builtin_nontemporal_store(v1, (f32x4*)(out + off + 4)); }
;                     else { q += sq4(v0) + sq4(v1); *(u32x4*)(xb + off) = pack8(v0, v1); }
;                 }
;                 if (!last) { q += shx(q, 16); q += shx(q, 32); if (fq == 0) ss[(size_t)row * 16 + u.pn * 4 + wc] = q; }
.LBB0_1673:
	v_lshl_or_b32 v168, s18, 8, v188
	v_lshl_add_u32 v172, s65, 8, v186
	v_ashrrev_i32_e32 v169, 31, v168
	v_lshlrev_b64 v[202:203], 1, v[168:169]
	v_ashrrev_i32_e32 v173, 31, v172
	v_lshl_add_u64 v[170:171], s[22:23], 0, v[202:203]
	v_lshlrev_b64 v[204:205], 11, v[172:173]
	v_lshl_add_u64 v[120:121], v[170:171], 0, v[204:205]
	global_load_dwordx4 v[192:195], v[120:121], off
	global_load_dwordx4 v[196:199], v[120:121], off offset:256
	v_or_b32_e32 v182, 16, v172
	v_ashrrev_i32_e32 v183, 31, v182
	v_or_b32_e32 v178, 32, v172
	v_lshlrev_b64 v[184:185], 11, v[182:183]
	v_ashrrev_i32_e32 v179, 31, v178
	v_or_b32_e32 v174, 48, v172
	v_lshl_add_u64 v[120:121], v[170:171], 0, v[184:185]
	v_lshlrev_b64 v[180:181], 11, v[178:179]
	v_ashrrev_i32_e32 v175, 31, v174
	global_load_dwordx4 v[148:151], v[120:121], off
	global_load_dwordx4 v[144:147], v[120:121], off offset:256
	v_lshl_add_u64 v[120:121], v[170:171], 0, v[180:181]
	v_lshlrev_b64 v[176:177], 11, v[174:175]
	global_load_dwordx4 v[140:143], v[120:121], off
	global_load_dwordx4 v[136:139], v[120:121], off offset:256
	v_lshl_add_u64 v[120:121], v[170:171], 0, v[176:177]
	global_load_dwordx4 v[132:135], v[120:121], off
	s_nop 0
	global_load_dwordx4 v[120:123], v[120:121], off offset:256
	s_lshl_b32 s46, s18, 2
	s_ashr_i32 s47, s46, 31
	s_waitcnt vmcnt(0)
	v_lshlrev_b32_e32 v206, 16, v192
	v_and_b32_e32 v207, 0xffff0000, v192
	v_lshlrev_b32_e32 v192, 16, v193
	v_and_b32_e32 v193, 0xffff0000, v193
	v_lshlrev_b32_e32 v208, 16, v194
	v_and_b32_e32 v209, 0xffff0000, v194
	v_lshlrev_b32_e32 v194, 16, v195
	v_and_b32_e32 v195, 0xffff0000, v195
	v_pk_add_f32 v[130:131], v[130:131], v[192:193]
	v_pk_add_f32 v[128:129], v[128:129], v[206:207]
	v_pk_add_f32 v[192:193], v[126:127], v[194:195]
	v_pk_add_f32 v[126:127], v[124:125], v[208:209]
	v_mul_f32_e32 v124, v129, v129
	v_mul_f32_e32 v125, v131, v131
	v_fmac_f32_e32 v124, v128, v128
	v_fmac_f32_e32 v125, v130, v130
	v_add_f32_e32 v124, v124, v125
	v_mul_f32_e32 v125, v127, v127
	v_mul_f32_e32 v194, v193, v193
	v_fmac_f32_e32 v125, v126, v126
	v_fmac_f32_e32 v194, v192, v192
	v_add_f32_e32 v125, v125, v194
	v_add_f32_e32 v194, v124, v125
	v_cvt_pk_bf16_f32 v124, v128, v129
	v_lshl_add_u64 v[128:129], s[22:23], 0, v[204:205]
	v_cvt_pk_bf16_f32 v125, v130, v131
	v_cvt_pk_bf16_f32 v126, v126, v127
	v_cvt_pk_bf16_f32 v127, v192, v193
	v_lshl_add_u64 v[128:129], v[128:129], 0, v[202:203]
	global_store_dwordx4 v[128:129], v[124:127], off sc1
	v_lshlrev_b32_e32 v130, 16, v198
	v_and_b32_e32 v131, 0xffff0000, v198
	v_lshlrev_b32_e32 v124, 16, v196
	v_and_b32_e32 v125, 0xffff0000, v196
	v_lshlrev_b32_e32 v126, 16, v197
	v_and_b32_e32 v127, 0xffff0000, v197
	v_lshlrev_b32_e32 v192, 16, v199
	v_and_b32_e32 v193, 0xffff0000, v199
	v_pk_add_f32 v[118:119], v[118:119], v[126:127]
	v_pk_add_f32 v[116:117], v[116:117], v[124:125]
	v_pk_add_f32 v[124:125], v[114:115], v[192:193]
	v_pk_add_f32 v[114:115], v[112:113], v[130:131]
	v_mul_f32_e32 v112, v117, v117
	v_mul_f32_e32 v113, v119, v119
	v_fmac_f32_e32 v112, v116, v116
	v_fmac_f32_e32 v113, v118, v118
	v_add_f32_e32 v112, v112, v113
	v_mul_f32_e32 v113, v115, v115
	v_mul_f32_e32 v126, v125, v125
	v_fmac_f32_e32 v113, v114, v114
	v_fmac_f32_e32 v126, v124, v124
	v_add_f32_e32 v113, v113, v126
	v_add_f32_e32 v112, v112, v113
	v_add_f32_e32 v126, v194, v112
	v_cvt_pk_bf16_f32 v112, v116, v117
	v_cvt_pk_bf16_f32 v113, v118, v119
	v_cvt_pk_bf16_f32 v114, v114, v115
	v_cvt_pk_bf16_f32 v115, v124, v125
	global_store_dwordx4 v[128:129], v[112:115], off offset:256 sc1
	s_nop 1
	v_mov_b32_e32 v112, v201
	v_mov_b32_e32 v113, v201
	v_lshlrev_b32_e32 v112, 2, v112
	v_xor_b32_e32 v112, 64, v112
	v_mov_b32_e32 v112, v126
	s_nop 1
	v_permlane16_swap_b32_e32 v112, v126
	s_waitcnt lgkmcnt(0)
	v_add_f32_e32 v112, v126, v112
	v_lshlrev_b32_e32 v113, 2, v113
	v_xor_b32_e32 v113, 0x80, v113
	v_mov_b32_e32 v113, v112
	s_nop 1
	v_permlane32_swap_b32_e32 v113, v112
	s_and_saveexec_b64 s[48:49], s[8:9]
	s_cbranch_execz .LBB0_1675
	s_waitcnt lgkmcnt(0)
	v_add_f32_e32 v114, v112, v113
	v_lshlrev_b64 v[112:113], 6, v[172:173]
	v_lshl_add_u64 v[112:113], s[24:25], 0, v[112:113]
	v_lshl_add_u64 v[112:113], s[46:47], 2, v[112:113]
	s_lshl_b32 s18, s54, 2
	v_lshl_add_u64 v[112:113], v[112:113], 0, s[18:19]
	global_store_dword v[112:113], v114, off sc1
; __device__ __forceinline__ float sq4(f32x4 v) { return (v[0] * v[0] + v[1] * v[1]) + (v[2] * v[2] + v[3] * v[3]); }
; __device__ __forceinline__ u32x4 pack8(f32x4 a, f32x4 b) { u32x4 w; w.x = cvt_pk_bf16(a[0], a[1]); w.y = cvt_pk_bf16(a[2], a[3]); w.z = cvt_pk_bf16(b[0], b[1]); w.w = cvt_pk_bf16(b[2], b[3]); return w; }
;     __device__ __forceinline__ void operator()(const f32x4 (&acc)[2][2][4][2], const Unit& u, int wr, int wc, int fr, int fq) const {
;     ...
;             for (int m = 0; m < 4; ++m) {
;                 const int row = u.pm * BM + ai * HALF + wr * 64 + m * 16 + fr;
;                 float q = 0.f;
; #pragma unroll
;                 for (int bj = 0; bj < 2; ++bj) {
;                     const size_t off = (size_t)row * 1024 + col0 + 128 * bj; const u32x4 w = bs[m][bj];
;                     const f32x4 b0 = (f32x4){__builtin_bit_cast(float, w.x << 16), __builtin_bit_cast(float, w.x & 0xffff0000u), __builtin_bit_cast(float, w.y << 16), __builtin_bit_cast(float, w.y & 0xffff0000u)};
;                     const f32x4 b1 = (f32x4){__builtin_bit_cast(float, w.z << 16), __builtin_bit_cast(float, w.z & 0xffff0000u), __builtin_bit_cast(float, w.w << 16), __builtin_bit_cast(float, w.w & 0xffff0000u)};
;                     const f32x4 v0 = acc[ai][bj][m][0] + b0, v1 = acc[ai][bj][m][1] + b1;
;                     if (last) { __builtin_nontemporal_store(v0, (f32x4*)(out + off)); __builtin_nontemporal_store(v1, (f32x4*)(out + off + 4)); }
;                     else { q += sq4(v0) + sq4(v1); *(u32x4*)(xb + off) = pack8(v0, v1); }
;                 }
;                 if (!last) { q += shx(q, 16); q += shx(q, 32); if (fq == 0) ss[(size_t)row * 16 + u.pn * 4 + wc] = q; }
.LBB0_1675:
	s_or_b64 exec, exec, s[48:49]
	v_lshlrev_b32_e32 v112, 16, v148
	s_waitcnt lgkmcnt(0)
	v_and_b32_e32 v113, 0xffff0000, v148
	v_lshlrev_b32_e32 v114, 16, v149
	v_and_b32_e32 v115, 0xffff0000, v149
	v_lshlrev_b32_e32 v116, 16, v150
	v_and_b32_e32 v117, 0xffff0000, v150
	v_lshlrev_b32_e32 v118, 16, v151
	v_and_b32_e32 v119, 0xffff0000, v151
	v_pk_add_f32 v[110:111], v[110:111], v[114:115]
	v_pk_add_f32 v[108:109], v[108:109], v[112:113]
	v_pk_add_f32 v[112:113], v[106:107], v[118:119]
	v_pk_add_f32 v[106:107], v[104:105], v[116:117]
	v_mul_f32_e32 v104, v109, v109
	v_mul_f32_e32 v105, v111, v111
	v_fmac_f32_e32 v104, v108, v108
	v_fmac_f32_e32 v105, v110, v110
	v_add_f32_e32 v104, v104, v105
	v_mul_f32_e32 v105, v107, v107
	v_mul_f32_e32 v114, v113, v113
	v_fmac_f32_e32 v105, v106, v106
	v_fmac_f32_e32 v114, v112, v112
	v_add_f32_e32 v105, v105, v114
	v_add_f32_e32 v114, v104, v105
	v_cvt_pk_bf16_f32 v104, v108, v109
	v_lshl_add_u64 v[108:109], s[22:23], 0, v[184:185]
	v_cvt_pk_bf16_f32 v105, v110, v111
	v_cvt_pk_bf16_f32 v106, v106, v107
	v_cvt_pk_bf16_f32 v107, v112, v113
	v_lshl_add_u64 v[108:109], v[168:169], 1, v[108:109]
	global_store_dwordx4 v[108:109], v[104:107], off sc1
	v_lshlrev_b32_e32 v110, 16, v146
	v_and_b32_e32 v111, 0xffff0000, v146
	v_lshlrev_b32_e32 v104, 16, v144
	v_and_b32_e32 v105, 0xffff0000, v144
	v_lshlrev_b32_e32 v106, 16, v145
	v_and_b32_e32 v107, 0xffff0000, v145
	v_lshlrev_b32_e32 v112, 16, v147
	v_and_b32_e32 v113, 0xffff0000, v147
	v_pk_add_f32 v[102:103], v[102:103], v[106:107]
	v_pk_add_f32 v[100:101], v[100:101], v[104:105]
	v_pk_add_f32 v[104:105], v[98:99], v[112:113]
	v_pk_add_f32 v[98:99], v[96:97], v[110:111]
	v_mul_f32_e32 v96, v101, v101
	v_mul_f32_e32 v97, v103, v103
	v_fmac_f32_e32 v96, v100, v100
	v_fmac_f32_e32 v97, v102, v102
	v_add_f32_e32 v96, v96, v97
	v_mul_f32_e32 v97, v99, v99
	v_mul_f32_e32 v106, v105, v105
	v_fmac_f32_e32 v97, v98, v98
	v_fmac_f32_e32 v106, v104, v104
	v_add_f32_e32 v97, v97, v106
	v_add_f32_e32 v96, v96, v97
	v_add_f32_e32 v106, v114, v96
	v_cvt_pk_bf16_f32 v96, v100, v101
	v_cvt_pk_bf16_f32 v97, v102, v103
	v_cvt_pk_bf16_f32 v98, v98, v99
	v_cvt_pk_bf16_f32 v99, v104, v105
	global_store_dwordx4 v[108:109], v[96:99], off offset:256 sc1
	s_nop 1
	v_mov_b32_e32 v96, v201
	v_mov_b32_e32 v97, v201
	v_lshlrev_b32_e32 v96, 2, v96
	v_xor_b32_e32 v96, 64, v96
	v_mov_b32_e32 v96, v106
	s_nop 1
	v_permlane16_swap_b32_e32 v96, v106
	s_waitcnt lgkmcnt(0)
	v_add_f32_e32 v96, v106, v96
	v_lshlrev_b32_e32 v97, 2, v97
	v_xor_b32_e32 v97, 0x80, v97
	v_mov_b32_e32 v97, v96
	s_nop 1
	v_permlane32_swap_b32_e32 v97, v96
	s_and_saveexec_b64 s[48:49], s[8:9]
	s_cbranch_execz .LBB0_1677
	s_waitcnt lgkmcnt(0)
	v_add_f32_e32 v98, v96, v97
	v_lshlrev_b64 v[96:97], 6, v[182:183]
	v_lshl_add_u64 v[96:97], s[24:25], 0, v[96:97]
	v_lshl_add_u64 v[96:97], s[46:47], 2, v[96:97]
	s_lshl_b32 s18, s54, 2
	v_lshl_add_u64 v[96:97], v[96:97], 0, s[18:19]
	global_store_dword v[96:97], v98, off sc1
.LBB0_1677:
	s_or_b64 exec, exec, s[48:49]
	v_lshlrev_b32_e32 v96, 16, v140
	s_waitcnt lgkmcnt(0)
	v_and_b32_e32 v97, 0xffff0000, v140
	v_lshlrev_b32_e32 v98, 16, v141
	v_and_b32_e32 v99, 0xffff0000, v141
	v_lshlrev_b32_e32 v100, 16, v142
	v_and_b32_e32 v101, 0xffff0000, v142
	v_lshlrev_b32_e32 v102, 16, v143
	v_and_b32_e32 v103, 0xffff0000, v143
	v_pk_add_f32 v[94:95], v[94:95], v[98:99]
	v_pk_add_f32 v[92:93], v[92:93], v[96:97]
	v_pk_add_f32 v[96:97], v[90:91], v[102:103]
	v_pk_add_f32 v[90:91], v[88:89], v[100:101]
	v_mul_f32_e32 v88, v93, v93
	v_mul_f32_e32 v89, v95, v95
	v_fmac_f32_e32 v88, v92, v92
	v_fmac_f32_e32 v89, v94, v94
	v_add_f32_e32 v88, v88, v89
	v_mul_f32_e32 v89, v91, v91
	v_mul_f32_e32 v98, v97, v97
	v_fmac_f32_e32 v89, v90, v90
	v_fmac_f32_e32 v98, v96, v96
	v_add_f32_e32 v89, v89, v98
	v_add_f32_e32 v98, v88, v89
	v_cvt_pk_bf16_f32 v88, v92, v93
	v_lshl_add_u64 v[92:93], s[22:23], 0, v[180:181]
	v_cvt_pk_bf16_f32 v89, v94, v95
	v_cvt_pk_bf16_f32 v90, v90, v91
	v_cvt_pk_bf16_f32 v91, v96, v97
	v_lshl_add_u64 v[92:93], v[168:169], 1, v[92:93]
	global_store_dwordx4 v[92:93], v[88:91], off sc1
	v_lshlrev_b32_e32 v94, 16, v138
	v_and_b32_e32 v95, 0xffff0000, v138
	v_lshlrev_b32_e32 v88, 16, v136
	v_and_b32_e32 v89, 0xffff0000, v136
	v_lshlrev_b32_e32 v90, 16, v137
	v_and_b32_e32 v91, 0xffff0000, v137
	v_lshlrev_b32_e32 v96, 16, v139
	v_and_b32_e32 v97, 0xffff0000, v139
	v_pk_add_f32 v[86:87], v[86:87], v[90:91]
	v_pk_add_f32 v[84:85], v[84:85], v[88:89]
	v_pk_add_f32 v[88:89], v[82:83], v[96:97]
	v_pk_add_f32 v[82:83], v[80:81], v[94:95]
	v_mul_f32_e32 v80, v85, v85
	v_mul_f32_e32 v81, v87, v87
	v_fmac_f32_e32 v80, v84, v84
	v_fmac_f32_e32 v81, v86, v86
	v_add_f32_e32 v80, v80, v81
	v_mul_f32_e32 v81, v83, v83
	v_mul_f32_e32 v90, v89, v89
	v_fmac_f32_e32 v81, v82, v82
	v_fmac_f32_e32 v90, v88, v88
	v_add_f32_e32 v81, v81, v90
	v_add_f32_e32 v80, v80, v81
	v_add_f32_e32 v90, v98, v80
	v_cvt_pk_bf16_f32 v80, v84, v85
	v_cvt_pk_bf16_f32 v81, v86, v87
	v_cvt_pk_bf16_f32 v82, v82, v83
	v_cvt_pk_bf16_f32 v83, v88, v89
	global_store_dwordx4 v[92:93], v[80:83], off offset:256 sc1
	s_nop 1
	v_mov_b32_e32 v80, v201
	v_mov_b32_e32 v81, v201
	v_lshlrev_b32_e32 v80, 2, v80
	v_xor_b32_e32 v80, 64, v80
	v_mov_b32_e32 v80, v90
	s_nop 1
	v_permlane16_swap_b32_e32 v80, v90
	s_waitcnt lgkmcnt(0)
	v_add_f32_e32 v80, v90, v80
	v_lshlrev_b32_e32 v81, 2, v81
	v_xor_b32_e32 v81, 0x80, v81
	v_mov_b32_e32 v81, v80
	s_nop 1
	v_permlane32_swap_b32_e32 v81, v80
	s_and_saveexec_b64 s[48:49], s[8:9]
	s_cbranch_execz .LBB0_1679
	s_waitcnt lgkmcnt(0)
	v_add_f32_e32 v82, v80, v81
	v_lshlrev_b64 v[80:81], 6, v[178:179]
	v_lshl_add_u64 v[80:81], s[24:25], 0, v[80:81]
	v_lshl_add_u64 v[80:81], s[46:47], 2, v[80:81]
	s_lshl_b32 s18, s54, 2
	v_lshl_add_u64 v[80:81], v[80:81], 0, s[18:19]
	global_store_dword v[80:81], v82, off sc1
; __device__ __forceinline__ float sq4(f32x4 v) { return (v[0] * v[0] + v[1] * v[1]) + (v[2] * v[2] + v[3] * v[3]); }
; __device__ __forceinline__ u32x4 pack8(f32x4 a, f32x4 b) { u32x4 w; w.x = cvt_pk_bf16(a[0], a[1]); w.y = cvt_pk_bf16(a[2], a[3]); w.z = cvt_pk_bf16(b[0], b[1]); w.w = cvt_pk_bf16(b[2], b[3]); return w; }
;     __device__ __forceinline__ void operator()(const f32x4 (&acc)[2][2][4][2], const Unit& u, int wr, int wc, int fr, int fq) const {
;     ...
;         for (int ai = 0; ai < 2; ++ai) {
;             u32x4 bs[4][2];
; #pragma unroll
;             for (int m = 0; m < 4; ++m)
; #pragma unroll
;                 for (int bj = 0; bj < 2; ++bj) bs[m][bj] = *(const u32x4*)(xb + (size_t)(u.pm * BM + ai * HALF + wr * 64 + m * 16 + fr) * 1024 + col0 + 128 * bj);
; #pragma unroll
;             for (int m = 0; m < 4; ++m) {
;                 const int row = u.pm * BM + ai * HALF + wr * 64 + m * 16 + fr;
;                 float q = 0.f;
; #pragma unroll
;                 for (int bj = 0; bj < 2; ++bj) {
;                     const size_t off = (size_t)row * 1024 + col0 + 128 * bj; const u32x4 w = bs[m][bj];
;                     const f32x4 b0 = (f32x4){__builtin_bit_cast(float, w.x << 16), __builtin_bit_cast(float, w.x & 0xffff0000u), __builtin_bit_cast(float, w.y << 16), __builtin_bit_cast(float, w.y & 0xffff0000u)};
;                     const f32x4 b1 = (f32x4){__builtin_bit_cast(float, w.z << 16), __builtin_bit_cast(float, w.z & 0xffff0000u), __builtin_bit_cast(float, w.w << 16), __builtin_bit_cast(float, w.w & 0xffff0000u)};
;                     const f32x4 v0 = acc[ai][bj][m][0] + b0, v1 = acc[ai][bj][m][1] + b1;
;                     if (last) { __builtin_nontemporal_store(v0, (f32x4*)(out + off)); __builtin_nontemporal_store(v1, (f32x4*)(out + off + 4)); }
;                     else { q += sq4(v0) + sq4(v1); *(u32x4*)(xb + off) = pack8(v0, v1); }
;                 }
;                 if (!last) { q += shx(q, 16); q += shx(q, 32); if (fq == 0) ss[(size_t)row * 16 + u.pn * 4 + wc] = q; }
.LBB0_1679:
	s_or_b64 exec, exec, s[48:49]
	v_lshlrev_b32_e32 v80, 16, v132
	s_waitcnt lgkmcnt(0)
	v_and_b32_e32 v81, 0xffff0000, v132
	v_lshlrev_b32_e32 v82, 16, v133
	v_and_b32_e32 v83, 0xffff0000, v133
	v_lshlrev_b32_e32 v84, 16, v134
	v_and_b32_e32 v85, 0xffff0000, v134
	v_lshlrev_b32_e32 v86, 16, v135
	v_and_b32_e32 v87, 0xffff0000, v135
	v_pk_add_f32 v[78:79], v[78:79], v[82:83]
	v_pk_add_f32 v[76:77], v[76:77], v[80:81]
	v_pk_add_f32 v[80:81], v[74:75], v[86:87]
	v_pk_add_f32 v[74:75], v[72:73], v[84:85]
	v_mul_f32_e32 v72, v77, v77
	v_mul_f32_e32 v73, v79, v79
	v_fmac_f32_e32 v72, v76, v76
	v_fmac_f32_e32 v73, v78, v78
	v_add_f32_e32 v72, v72, v73
	v_mul_f32_e32 v73, v75, v75
	v_mul_f32_e32 v82, v81, v81
	v_fmac_f32_e32 v73, v74, v74
	v_fmac_f32_e32 v82, v80, v80
	v_add_f32_e32 v73, v73, v82
	v_add_f32_e32 v82, v72, v73
	v_cvt_pk_bf16_f32 v72, v76, v77
	v_lshl_add_u64 v[76:77], s[22:23], 0, v[176:177]
	v_cvt_pk_bf16_f32 v73, v78, v79
	v_cvt_pk_bf16_f32 v74, v74, v75
	v_cvt_pk_bf16_f32 v75, v80, v81
	v_lshl_add_u64 v[76:77], v[168:169], 1, v[76:77]
	global_store_dwordx4 v[76:77], v[72:75], off sc1
	v_lshlrev_b32_e32 v78, 16, v122
	v_and_b32_e32 v79, 0xffff0000, v122
	v_lshlrev_b32_e32 v72, 16, v120
	v_and_b32_e32 v73, 0xffff0000, v120
	v_lshlrev_b32_e32 v74, 16, v121
	v_and_b32_e32 v75, 0xffff0000, v121
	v_lshlrev_b32_e32 v80, 16, v123
	v_and_b32_e32 v81, 0xffff0000, v123
	v_pk_add_f32 v[70:71], v[70:71], v[74:75]
	v_pk_add_f32 v[68:69], v[68:69], v[72:73]
	v_pk_add_f32 v[72:73], v[66:67], v[80:81]
	v_pk_add_f32 v[66:67], v[64:65], v[78:79]
	v_mul_f32_e32 v64, v69, v69
	v_mul_f32_e32 v65, v71, v71
	v_fmac_f32_e32 v64, v68, v68
	v_fmac_f32_e32 v65, v70, v70
	v_add_f32_e32 v64, v64, v65
	v_mul_f32_e32 v65, v67, v67
	v_mul_f32_e32 v74, v73, v73
	v_fmac_f32_e32 v65, v66, v66
	v_fmac_f32_e32 v74, v72, v72
	v_add_f32_e32 v65, v65, v74
	v_add_f32_e32 v64, v64, v65
	v_add_f32_e32 v74, v82, v64
	v_cvt_pk_bf16_f32 v64, v68, v69
	v_cvt_pk_bf16_f32 v65, v70, v71
	v_cvt_pk_bf16_f32 v66, v66, v67
	v_cvt_pk_bf16_f32 v67, v72, v73
	global_store_dwordx4 v[76:77], v[64:67], off offset:256 sc1
	s_nop 1
	v_mov_b32_e32 v64, v201
	v_mov_b32_e32 v65, v201
	v_lshlrev_b32_e32 v64, 2, v64
	v_xor_b32_e32 v64, 64, v64
	v_mov_b32_e32 v64, v74
	s_nop 1
	v_permlane16_swap_b32_e32 v64, v74
	s_waitcnt lgkmcnt(0)
	v_add_f32_e32 v64, v74, v64
	v_lshlrev_b32_e32 v65, 2, v65
	v_xor_b32_e32 v65, 0x80, v65
	v_mov_b32_e32 v65, v64
	s_nop 1
	v_permlane32_swap_b32_e32 v65, v64
	s_and_saveexec_b64 s[48:49], s[8:9]
	s_cbranch_execz .LBB0_1681
	s_waitcnt lgkmcnt(0)
	v_add_f32_e32 v66, v64, v65
	v_lshlrev_b64 v[64:65], 6, v[174:175]
	v_lshl_add_u64 v[64:65], s[24:25], 0, v[64:65]
	v_lshl_add_u64 v[64:65], s[46:47], 2, v[64:65]
	s_lshl_b32 s18, s54, 2
	v_lshl_add_u64 v[64:65], v[64:65], 0, s[18:19]
	global_store_dword v[64:65], v66, off sc1
.LBB0_1681:
	s_or_b64 exec, exec, s[48:49]
	v_add_u32_e32 v100, 0x80, v172
	v_ashrrev_i32_e32 v101, 31, v100
	v_lshlrev_b64 v[110:111], 11, v[100:101]
	s_waitcnt lgkmcnt(0)
	v_lshl_add_u64 v[64:65], v[170:171], 0, v[110:111]
	global_load_dwordx4 v[102:105], v[64:65], off
	global_load_dwordx4 v[106:109], v[64:65], off offset:256
	v_add_u32_e32 v96, 0x90, v172
	v_ashrrev_i32_e32 v97, 31, v96
	v_add_u32_e32 v92, 0xa0, v172
	v_lshlrev_b64 v[98:99], 11, v[96:97]
	v_ashrrev_i32_e32 v93, 31, v92
	v_add_u32_e32 v88, 0xb0, v172
	v_lshl_add_u64 v[64:65], v[170:171], 0, v[98:99]
	v_lshlrev_b64 v[94:95], 11, v[92:93]
	v_ashrrev_i32_e32 v89, 31, v88
	global_load_dwordx4 v[84:87], v[64:65], off
	global_load_dwordx4 v[80:83], v[64:65], off offset:256
	v_lshl_add_u64 v[64:65], v[170:171], 0, v[94:95]
	v_lshlrev_b64 v[90:91], 11, v[88:89]
	global_load_dwordx4 v[76:79], v[64:65], off
	global_load_dwordx4 v[72:75], v[64:65], off offset:256
	v_lshl_add_u64 v[64:65], v[170:171], 0, v[90:91]
	global_load_dwordx4 v[68:71], v[64:65], off
	s_nop 0
	global_load_dwordx4 v[64:67], v[64:65], off offset:256
	s_waitcnt vmcnt(7)
	v_lshlrev_b32_e32 v112, 16, v102
	v_and_b32_e32 v113, 0xffff0000, v102
	v_lshlrev_b32_e32 v102, 16, v103
	v_and_b32_e32 v103, 0xffff0000, v103
	v_lshlrev_b32_e32 v114, 16, v104
	v_and_b32_e32 v115, 0xffff0000, v104
	v_lshlrev_b32_e32 v104, 16, v105
	v_and_b32_e32 v105, 0xffff0000, v105
	v_pk_add_f32 v[62:63], v[62:63], v[102:103]
	v_pk_add_f32 v[60:61], v[60:61], v[112:113]
	v_pk_add_f32 v[102:103], v[58:59], v[104:105]
	v_pk_add_f32 v[58:59], v[56:57], v[114:115]
	v_mul_f32_e32 v56, v61, v61
	v_mul_f32_e32 v57, v63, v63
	v_fmac_f32_e32 v56, v60, v60
	v_fmac_f32_e32 v57, v62, v62
	v_add_f32_e32 v56, v56, v57
	v_mul_f32_e32 v57, v59, v59
	v_mul_f32_e32 v104, v103, v103
	v_fmac_f32_e32 v57, v58, v58
	v_fmac_f32_e32 v104, v102, v102
	v_add_f32_e32 v57, v57, v104
	v_add_f32_e32 v104, v56, v57
	v_cvt_pk_bf16_f32 v56, v60, v61
	v_lshl_add_u64 v[60:61], s[22:23], 0, v[110:111]
	v_cvt_pk_bf16_f32 v57, v62, v63
	v_cvt_pk_bf16_f32 v58, v58, v59
	v_cvt_pk_bf16_f32 v59, v102, v103
	v_lshl_add_u64 v[60:61], v[168:169], 1, v[60:61]
	global_store_dwordx4 v[60:61], v[56:59], off sc1
	s_waitcnt vmcnt(7)
	v_lshlrev_b32_e32 v62, 16, v108
	v_and_b32_e32 v63, 0xffff0000, v108
	v_lshlrev_b32_e32 v56, 16, v106
	v_and_b32_e32 v57, 0xffff0000, v106
	v_lshlrev_b32_e32 v58, 16, v107
	v_and_b32_e32 v59, 0xffff0000, v107
	v_lshlrev_b32_e32 v102, 16, v109
	v_and_b32_e32 v103, 0xffff0000, v109
	v_pk_add_f32 v[54:55], v[54:55], v[58:59]
	v_pk_add_f32 v[52:53], v[52:53], v[56:57]
	v_pk_add_f32 v[56:57], v[50:51], v[102:103]
	v_pk_add_f32 v[50:51], v[48:49], v[62:63]
	v_mul_f32_e32 v48, v53, v53
	v_mul_f32_e32 v49, v55, v55
	v_fmac_f32_e32 v48, v52, v52
	v_fmac_f32_e32 v49, v54, v54
	v_add_f32_e32 v48, v48, v49
	v_mul_f32_e32 v49, v51, v51
	v_mul_f32_e32 v58, v57, v57
	v_fmac_f32_e32 v49, v50, v50
	v_fmac_f32_e32 v58, v56, v56
	v_add_f32_e32 v49, v49, v58
	v_add_f32_e32 v48, v48, v49
	v_add_f32_e32 v58, v104, v48
	v_cvt_pk_bf16_f32 v48, v52, v53
	v_cvt_pk_bf16_f32 v49, v54, v55
	v_cvt_pk_bf16_f32 v50, v50, v51
	v_cvt_pk_bf16_f32 v51, v56, v57
	global_store_dwordx4 v[60:61], v[48:51], off offset:256 sc1
	s_nop 1
	v_mov_b32_e32 v48, v201
	v_mov_b32_e32 v49, v201
	v_lshlrev_b32_e32 v48, 2, v48
	v_xor_b32_e32 v48, 64, v48
	v_mov_b32_e32 v48, v58
	s_nop 1
	v_permlane16_swap_b32_e32 v48, v58
	s_waitcnt lgkmcnt(0)
	v_add_f32_e32 v48, v58, v48
	v_lshlrev_b32_e32 v49, 2, v49
	v_xor_b32_e32 v49, 0x80, v49
	v_mov_b32_e32 v49, v48
	s_nop 1
	v_permlane32_swap_b32_e32 v49, v48
	s_and_saveexec_b64 s[48:49], s[8:9]
	s_cbranch_execz .LBB0_1683
	s_waitcnt lgkmcnt(0)
	v_add_f32_e32 v50, v48, v49
	v_lshlrev_b64 v[48:49], 6, v[100:101]
	v_lshl_add_u64 v[48:49], s[24:25], 0, v[48:49]
	v_lshl_add_u64 v[48:49], s[46:47], 2, v[48:49]
	s_lshl_b32 s18, s54, 2
	v_lshl_add_u64 v[48:49], v[48:49], 0, s[18:19]
	global_store_dword v[48:49], v50, off sc1
; __device__ __forceinline__ float sq4(f32x4 v) { return (v[0] * v[0] + v[1] * v[1]) + (v[2] * v[2] + v[3] * v[3]); }
; __device__ __forceinline__ u32x4 pack8(f32x4 a, f32x4 b) { u32x4 w; w.x = cvt_pk_bf16(a[0], a[1]); w.y = cvt_pk_bf16(a[2], a[3]); w.z = cvt_pk_bf16(b[0], b[1]); w.w = cvt_pk_bf16(b[2], b[3]); return w; }
;     __device__ __forceinline__ void operator()(const f32x4 (&acc)[2][2][4][2], const Unit& u, int wr, int wc, int fr, int fq) const {
;     ...
;             for (int m = 0; m < 4; ++m) {
;                 const int row = u.pm * BM + ai * HALF + wr * 64 + m * 16 + fr;
;                 float q = 0.f;
; #pragma unroll
;                 for (int bj = 0; bj < 2; ++bj) {
;                     const size_t off = (size_t)row * 1024 + col0 + 128 * bj; const u32x4 w = bs[m][bj];
;                     const f32x4 b0 = (f32x4){__builtin_bit_cast(float, w.x << 16), __builtin_bit_cast(float, w.x & 0xffff0000u), __builtin_bit_cast(float, w.y << 16), __builtin_bit_cast(float, w.y & 0xffff0000u)};
;                     const f32x4 b1 = (f32x4){__builtin_bit_cast(float, w.z << 16), __builtin_bit_cast(float, w.z & 0xffff0000u), __builtin_bit_cast(float, w.w << 16), __builtin_bit_cast(float, w.w & 0xffff0000u)};
;                     const f32x4 v0 = acc[ai][bj][m][0] + b0, v1 = acc[ai][bj][m][1] + b1;
;                     if (last) { __builtin_nontemporal_store(v0, (f32x4*)(out + off)); __builtin_nontemporal_store(v1, (f32x4*)(out + off + 4)); }
;                     else { q += sq4(v0) + sq4(v1); *(u32x4*)(xb + off) = pack8(v0, v1); }
;                 }
;                 if (!last) { q += shx(q, 16); q += shx(q, 32); if (fq == 0) ss[(size_t)row * 16 + u.pn * 4 + wc] = q; }
.LBB0_1683:
	s_or_b64 exec, exec, s[48:49]
	s_waitcnt vmcnt(7)
	v_lshlrev_b32_e32 v48, 16, v84
	s_waitcnt lgkmcnt(0)
	v_and_b32_e32 v49, 0xffff0000, v84
	v_lshlrev_b32_e32 v50, 16, v85
	v_and_b32_e32 v51, 0xffff0000, v85
	v_lshlrev_b32_e32 v52, 16, v86
	v_and_b32_e32 v53, 0xffff0000, v86
	v_lshlrev_b32_e32 v54, 16, v87
	v_and_b32_e32 v55, 0xffff0000, v87
	v_pk_add_f32 v[46:47], v[46:47], v[50:51]
	v_pk_add_f32 v[44:45], v[44:45], v[48:49]
	v_pk_add_f32 v[48:49], v[42:43], v[54:55]
	v_pk_add_f32 v[42:43], v[40:41], v[52:53]
	v_mul_f32_e32 v40, v45, v45
	v_mul_f32_e32 v41, v47, v47
	v_fmac_f32_e32 v40, v44, v44
	v_fmac_f32_e32 v41, v46, v46
	v_add_f32_e32 v40, v40, v41
	v_mul_f32_e32 v41, v43, v43
	v_mul_f32_e32 v50, v49, v49
	v_fmac_f32_e32 v41, v42, v42
	v_fmac_f32_e32 v50, v48, v48
	v_add_f32_e32 v41, v41, v50
	v_add_f32_e32 v50, v40, v41
	v_cvt_pk_bf16_f32 v40, v44, v45
	v_lshl_add_u64 v[44:45], s[22:23], 0, v[98:99]
	v_cvt_pk_bf16_f32 v41, v46, v47
	v_cvt_pk_bf16_f32 v42, v42, v43
	v_cvt_pk_bf16_f32 v43, v48, v49
	v_lshl_add_u64 v[44:45], v[168:169], 1, v[44:45]
	global_store_dwordx4 v[44:45], v[40:43], off sc1
	s_waitcnt vmcnt(7)
	v_lshlrev_b32_e32 v46, 16, v82
	v_and_b32_e32 v47, 0xffff0000, v82
	v_lshlrev_b32_e32 v40, 16, v80
	v_and_b32_e32 v41, 0xffff0000, v80
	v_lshlrev_b32_e32 v42, 16, v81
	v_and_b32_e32 v43, 0xffff0000, v81
	v_lshlrev_b32_e32 v48, 16, v83
	v_and_b32_e32 v49, 0xffff0000, v83
	v_pk_add_f32 v[38:39], v[38:39], v[42:43]
	v_pk_add_f32 v[36:37], v[36:37], v[40:41]
	v_pk_add_f32 v[40:41], v[34:35], v[48:49]
	v_pk_add_f32 v[34:35], v[32:33], v[46:47]
	v_mul_f32_e32 v32, v37, v37
	v_mul_f32_e32 v33, v39, v39
	v_fmac_f32_e32 v32, v36, v36
	v_fmac_f32_e32 v33, v38, v38
	v_add_f32_e32 v32, v32, v33
	v_mul_f32_e32 v33, v35, v35
	v_mul_f32_e32 v42, v41, v41
	v_fmac_f32_e32 v33, v34, v34
	v_fmac_f32_e32 v42, v40, v40
	v_add_f32_e32 v33, v33, v42
	v_add_f32_e32 v32, v32, v33
	v_add_f32_e32 v42, v50, v32
	v_cvt_pk_bf16_f32 v32, v36, v37
	v_cvt_pk_bf16_f32 v33, v38, v39
	v_cvt_pk_bf16_f32 v34, v34, v35
	v_cvt_pk_bf16_f32 v35, v40, v41
	global_store_dwordx4 v[44:45], v[32:35], off offset:256 sc1
	s_nop 1
	v_mov_b32_e32 v32, v201
	v_mov_b32_e32 v33, v201
	v_lshlrev_b32_e32 v32, 2, v32
	v_xor_b32_e32 v32, 64, v32
	v_mov_b32_e32 v32, v42
	s_nop 1
	v_permlane16_swap_b32_e32 v32, v42
	s_waitcnt lgkmcnt(0)
	v_add_f32_e32 v32, v42, v32
	v_lshlrev_b32_e32 v33, 2, v33
	v_xor_b32_e32 v33, 0x80, v33
	v_mov_b32_e32 v33, v32
	s_nop 1
	v_permlane32_swap_b32_e32 v33, v32
	s_and_saveexec_b64 s[48:49], s[8:9]
	s_cbranch_execz .LBB0_1685
	s_waitcnt lgkmcnt(0)
	v_add_f32_e32 v34, v32, v33
	v_lshlrev_b64 v[32:33], 6, v[96:97]
	v_lshl_add_u64 v[32:33], s[24:25], 0, v[32:33]
	v_lshl_add_u64 v[32:33], s[46:47], 2, v[32:33]
	s_lshl_b32 s18, s54, 2
	v_lshl_add_u64 v[32:33], v[32:33], 0, s[18:19]
	global_store_dword v[32:33], v34, off sc1
; __device__ __forceinline__ float sq4(f32x4 v) { return (v[0] * v[0] + v[1] * v[1]) + (v[2] * v[2] + v[3] * v[3]); }
; __device__ __forceinline__ u32x4 pack8(f32x4 a, f32x4 b) { u32x4 w; w.x = cvt_pk_bf16(a[0], a[1]); w.y = cvt_pk_bf16(a[2], a[3]); w.z = cvt_pk_bf16(b[0], b[1]); w.w = cvt_pk_bf16(b[2], b[3]); return w; }
;     __device__ __forceinline__ void operator()(const f32x4 (&acc)[2][2][4][2], const Unit& u, int wr, int wc, int fr, int fq) const {
;     ...
;             for (int m = 0; m < 4; ++m) {
;                 const int row = u.pm * BM + ai * HALF + wr * 64 + m * 16 + fr;
;                 float q = 0.f;
; #pragma unroll
;                 for (int bj = 0; bj < 2; ++bj) {
;                     const size_t off = (size_t)row * 1024 + col0 + 128 * bj; const u32x4 w = bs[m][bj];
;                     const f32x4 b0 = (f32x4){__builtin_bit_cast(float, w.x << 16), __builtin_bit_cast(float, w.x & 0xffff0000u), __builtin_bit_cast(float, w.y << 16), __builtin_bit_cast(float, w.y & 0xffff0000u)};
;                     const f32x4 b1 = (f32x4){__builtin_bit_cast(float, w.z << 16), __builtin_bit_cast(float, w.z & 0xffff0000u), __builtin_bit_cast(float, w.w << 16), __builtin_bit_cast(float, w.w & 0xffff0000u)};
;                     const f32x4 v0 = acc[ai][bj][m][0] + b0, v1 = acc[ai][bj][m][1] + b1;
;                     if (last) { __builtin_nontemporal_store(v0, (f32x4*)(out + off)); __builtin_nontemporal_store(v1, (f32x4*)(out + off + 4)); }
;                     else { q += sq4(v0) + sq4(v1); *(u32x4*)(xb + off) = pack8(v0, v1); }
;                 }
;                 if (!last) { q += shx(q, 16); q += shx(q, 32); if (fq == 0) ss[(size_t)row * 16 + u.pn * 4 + wc] = q; }
.LBB0_1685:
	s_or_b64 exec, exec, s[48:49]
	s_waitcnt vmcnt(7)
	v_lshlrev_b32_e32 v32, 16, v76
	s_waitcnt lgkmcnt(0)
	v_and_b32_e32 v33, 0xffff0000, v76
	v_lshlrev_b32_e32 v34, 16, v77
	v_and_b32_e32 v35, 0xffff0000, v77
	v_lshlrev_b32_e32 v36, 16, v78
	v_and_b32_e32 v37, 0xffff0000, v78
	v_lshlrev_b32_e32 v38, 16, v79
	v_and_b32_e32 v39, 0xffff0000, v79
	v_pk_add_f32 v[30:31], v[30:31], v[34:35]
	v_pk_add_f32 v[28:29], v[28:29], v[32:33]
	v_pk_add_f32 v[32:33], v[26:27], v[38:39]
	v_pk_add_f32 v[26:27], v[24:25], v[36:37]
	v_mul_f32_e32 v24, v29, v29
	v_mul_f32_e32 v25, v31, v31
	v_fmac_f32_e32 v24, v28, v28
	v_fmac_f32_e32 v25, v30, v30
	v_add_f32_e32 v24, v24, v25
	v_mul_f32_e32 v25, v27, v27
	v_mul_f32_e32 v34, v33, v33
	v_fmac_f32_e32 v25, v26, v26
	v_fmac_f32_e32 v34, v32, v32
	v_add_f32_e32 v25, v25, v34
	v_add_f32_e32 v34, v24, v25
	v_cvt_pk_bf16_f32 v24, v28, v29
	v_lshl_add_u64 v[28:29], s[22:23], 0, v[94:95]
	v_cvt_pk_bf16_f32 v25, v30, v31
	v_cvt_pk_bf16_f32 v26, v26, v27
	v_cvt_pk_bf16_f32 v27, v32, v33
	v_lshl_add_u64 v[28:29], v[168:169], 1, v[28:29]
	global_store_dwordx4 v[28:29], v[24:27], off sc1
	s_waitcnt vmcnt(7)
	v_lshlrev_b32_e32 v30, 16, v74
	v_and_b32_e32 v31, 0xffff0000, v74
	v_lshlrev_b32_e32 v24, 16, v72
	v_and_b32_e32 v25, 0xffff0000, v72
	v_lshlrev_b32_e32 v26, 16, v73
	v_and_b32_e32 v27, 0xffff0000, v73
	v_lshlrev_b32_e32 v32, 16, v75
	v_and_b32_e32 v33, 0xffff0000, v75
	v_pk_add_f32 v[22:23], v[22:23], v[26:27]
	v_pk_add_f32 v[20:21], v[20:21], v[24:25]
	v_pk_add_f32 v[24:25], v[18:19], v[32:33]
	v_pk_add_f32 v[18:19], v[16:17], v[30:31]
	v_mul_f32_e32 v16, v21, v21
	v_mul_f32_e32 v17, v23, v23
	v_fmac_f32_e32 v16, v20, v20
	v_fmac_f32_e32 v17, v22, v22
	v_add_f32_e32 v16, v16, v17
	v_mul_f32_e32 v17, v19, v19
	v_mul_f32_e32 v26, v25, v25
	v_fmac_f32_e32 v17, v18, v18
	v_fmac_f32_e32 v26, v24, v24
	v_add_f32_e32 v17, v17, v26
	v_add_f32_e32 v16, v16, v17
	v_add_f32_e32 v26, v34, v16
	v_cvt_pk_bf16_f32 v16, v20, v21
	v_cvt_pk_bf16_f32 v17, v22, v23
	v_cvt_pk_bf16_f32 v18, v18, v19
	v_cvt_pk_bf16_f32 v19, v24, v25
	global_store_dwordx4 v[28:29], v[16:19], off offset:256 sc1
	s_nop 1
	v_mov_b32_e32 v16, v201
	v_mov_b32_e32 v17, v201
	v_lshlrev_b32_e32 v16, 2, v16
	v_xor_b32_e32 v16, 64, v16
	v_mov_b32_e32 v16, v26
	s_nop 1
	v_permlane16_swap_b32_e32 v16, v26
	s_waitcnt lgkmcnt(0)
	v_add_f32_e32 v16, v26, v16
	v_lshlrev_b32_e32 v17, 2, v17
	v_xor_b32_e32 v17, 0x80, v17
	v_mov_b32_e32 v17, v16
	s_nop 1
	v_permlane32_swap_b32_e32 v17, v16
	s_and_saveexec_b64 s[48:49], s[8:9]
	s_cbranch_execz .LBB0_1687
	s_waitcnt lgkmcnt(0)
	v_add_f32_e32 v18, v16, v17
	v_lshlrev_b64 v[16:17], 6, v[92:93]
	v_lshl_add_u64 v[16:17], s[24:25], 0, v[16:17]
	v_lshl_add_u64 v[16:17], s[46:47], 2, v[16:17]
	s_lshl_b32 s18, s54, 2
	v_lshl_add_u64 v[16:17], v[16:17], 0, s[18:19]
	global_store_dword v[16:17], v18, off sc1
.LBB0_1687:
	s_or_b64 exec, exec, s[48:49]
	s_waitcnt vmcnt(7)
	v_lshlrev_b32_e32 v16, 16, v68
	s_waitcnt lgkmcnt(0)
	v_and_b32_e32 v17, 0xffff0000, v68
	v_lshlrev_b32_e32 v18, 16, v69
	v_and_b32_e32 v19, 0xffff0000, v69
	v_lshlrev_b32_e32 v20, 16, v70
	v_and_b32_e32 v21, 0xffff0000, v70
	v_lshlrev_b32_e32 v22, 16, v71
	v_and_b32_e32 v23, 0xffff0000, v71
	v_pk_add_f32 v[14:15], v[14:15], v[18:19]
	v_pk_add_f32 v[12:13], v[12:13], v[16:17]
	v_pk_add_f32 v[16:17], v[10:11], v[22:23]
	v_pk_add_f32 v[10:11], v[8:9], v[20:21]
	v_mul_f32_e32 v8, v13, v13
	v_mul_f32_e32 v9, v15, v15
	v_fmac_f32_e32 v8, v12, v12
	v_fmac_f32_e32 v9, v14, v14
	v_add_f32_e32 v8, v8, v9
	v_mul_f32_e32 v9, v11, v11
	v_mul_f32_e32 v18, v17, v17
	v_fmac_f32_e32 v9, v10, v10
	v_fmac_f32_e32 v18, v16, v16
	v_add_f32_e32 v9, v9, v18
	v_add_f32_e32 v18, v8, v9
	v_cvt_pk_bf16_f32 v8, v12, v13
	v_lshl_add_u64 v[12:13], s[22:23], 0, v[90:91]
	v_cvt_pk_bf16_f32 v9, v14, v15
	v_cvt_pk_bf16_f32 v10, v10, v11
	v_cvt_pk_bf16_f32 v11, v16, v17
	v_lshl_add_u64 v[12:13], v[168:169], 1, v[12:13]
	global_store_dwordx4 v[12:13], v[8:11], off sc1
	s_waitcnt vmcnt(7)
	v_lshlrev_b32_e32 v14, 16, v66
	v_and_b32_e32 v15, 0xffff0000, v66
	v_lshlrev_b32_e32 v8, 16, v64
	v_and_b32_e32 v9, 0xffff0000, v64
	v_lshlrev_b32_e32 v10, 16, v65
	v_and_b32_e32 v11, 0xffff0000, v65
	v_lshlrev_b32_e32 v16, 16, v67
	v_and_b32_e32 v17, 0xffff0000, v67
	v_pk_add_f32 v[6:7], v[6:7], v[10:11]
	v_pk_add_f32 v[4:5], v[4:5], v[8:9]
	v_pk_add_f32 v[8:9], v[2:3], v[16:17]
	v_pk_add_f32 v[2:3], v[0:1], v[14:15]
	v_mul_f32_e32 v0, v5, v5
	v_mul_f32_e32 v1, v7, v7
	v_fmac_f32_e32 v0, v4, v4
	v_fmac_f32_e32 v1, v6, v6
	v_add_f32_e32 v0, v0, v1
	v_mul_f32_e32 v1, v3, v3
	v_mul_f32_e32 v10, v9, v9
	v_fmac_f32_e32 v1, v2, v2
	v_fmac_f32_e32 v10, v8, v8
	v_add_f32_e32 v1, v1, v10
	v_add_f32_e32 v0, v0, v1
	v_add_f32_e32 v10, v18, v0
	v_cvt_pk_bf16_f32 v0, v4, v5
	v_cvt_pk_bf16_f32 v1, v6, v7
	v_cvt_pk_bf16_f32 v2, v2, v3
	v_cvt_pk_bf16_f32 v3, v8, v9
	global_store_dwordx4 v[12:13], v[0:3], off offset:256 sc1
	s_nop 1
	v_mov_b32_e32 v0, v201
	v_mov_b32_e32 v1, v201
	v_lshlrev_b32_e32 v0, 2, v0
	v_xor_b32_e32 v0, 64, v0
	v_mov_b32_e32 v0, v10
	s_nop 1
	v_permlane16_swap_b32_e32 v0, v10
	s_waitcnt lgkmcnt(0)
	v_add_f32_e32 v0, v10, v0
	v_lshlrev_b32_e32 v1, 2, v1
	v_xor_b32_e32 v1, 0x80, v1
	v_mov_b32_e32 v1, v0
	s_nop 1
	v_permlane32_swap_b32_e32 v1, v0
	s_and_saveexec_b64 s[48:49], s[8:9]
	s_cbranch_execz .LBB0_1689
	s_waitcnt lgkmcnt(0)
	v_add_f32_e32 v2, v0, v1
	v_lshlrev_b64 v[0:1], 6, v[88:89]
	v_lshl_add_u64 v[0:1], s[24:25], 0, v[0:1]
	v_lshl_add_u64 v[0:1], s[46:47], 2, v[0:1]
	s_lshl_b32 s18, s54, 2
	v_lshl_add_u64 v[0:1], v[0:1], 0, s[18:19]
	global_store_dword v[0:1], v2, off sc1

; __device__ __forceinline__ f32x4 silu4(f32x4 v) { return (f32x4){silu_f(v[0]), silu_f(v[1]), silu_f(v[2]), silu_f(v[3])}; }
; __device__ __forceinline__ float sq4(f32x4 v) { return (v[0] * v[0] + v[1] * v[1]) + (v[2] * v[2] + v[3] * v[3]); }
; __device__ __forceinline__ u32x4 pack8(f32x4 a, f32x4 b) { u32x4 w; w.x = cvt_pk_bf16(a[0], a[1]); w.y = cvt_pk_bf16(a[2], a[3]); w.z = cvt_pk_bf16(b[0], b[1]); w.w = cvt_pk_bf16(b[2], b[3]); return w; }
;     __device__ __forceinline__ void operator()(const f32x4 (&acc)[2][2][4][2], const Unit& u, int wr, int wc, int fr, int fq) const {
;     ...
;                 const int row = u.pm * BM + ai * HALF + wr * 64 + m * 16 + fr;
;                 const float rstd = rs[ai][m];
;                 f32x4 v[2][2];
; #pragma unroll
;                 for (int bj = 0; bj < 2; ++bj)
; #pragma unroll
;                     for (int n = 0; n < 2; ++n) v[bj][n] = acc[ai][bj][m][n] * rstd;
;                 if (mode == 2) {
;                     float q = (sq4(v[0][0]) + sq4(v[0][1])) + (sq4(v[1][0]) + sq4(v[1][1]));
;                     q += shx(q, 16); q += shx(q, 32);
;                     const float r2 = __builtin_amdgcn_rsqf(q * (1.0f / 64.0f) + RMS_EPS);
; #pragma unroll
;                     for (int bj = 0; bj < 2; ++bj)
; #pragma unroll
;                         for (int n = 0; n < 2; ++n) v[bj][n] = v[bj][n] * r2 * wv[bj][n];
;                 } else if (mode == 1) {
; #pragma unroll
;                     for (int bj = 0; bj < 2; ++bj)
; #pragma unroll
;                         for (int n = 0; n < 2; ++n) v[bj][n] = silu4(v[bj][n]);
;                 } else {
; #pragma unroll
;                     for (int bj = 0; bj < 2; ++bj)
; #pragma unroll
;                         for (int n = 0; n < 2; ++n) v[bj][n] = v[bj][n] * sc;
;                 }
;                 bf16_t* rowp = U + (size_t)row * 2560 + lcol;
; #pragma unroll
;                 for (int bj = 0; bj < 2; ++bj) *(u32x4*)(rowp + 32 * bj) = pack8(v[bj][0], v[bj][1]);
.LBB0_1761:
	v_add_f32_e32 v112, v193, v194
	v_fmamk_f32 v112, v112, 0x3a800000, v184
	v_rsq_f32_e32 v194, v112
	v_lshl_or_b32 v112, s8, 8, v179
	v_mov_b64_e32 v[196:197], s[20:21]
	v_ashrrev_i32_e32 v113, 31, v112
	v_mad_i64_i32 v[196:197], s[8:9], v170, s68, v[196:197]
	v_lshl_add_u64 v[196:197], v[112:113], 1, v[196:197]
	v_cvt_pk_bf16_f32 v124, v124, v125
	v_cvt_pk_bf16_f32 v125, v126, v127
	v_cvt_pk_bf16_f32 v126, v172, v173
	v_cvt_pk_bf16_f32 v127, v122, v123
	global_store_dwordx4 v[196:197], v[124:127], off sc1
	v_cvt_pk_bf16_f32 v116, v116, v117
	v_cvt_pk_bf16_f32 v117, v118, v119
	v_cvt_pk_bf16_f32 v118, v120, v121
	v_cvt_pk_bf16_f32 v119, v114, v115
	v_cndmask_b32_e64 v114, 0, 1, s[46:47]
	v_pk_mul_f32 v[110:111], v[110:111], v[194:195] op_sel_hi:[1,0]
	v_pk_mul_f32 v[108:109], v[108:109], v[194:195] op_sel_hi:[1,0]
	v_pk_mul_f32 v[106:107], v[106:107], v[194:195] op_sel_hi:[1,0]
	v_pk_mul_f32 v[104:105], v[104:105], v[194:195] op_sel_hi:[1,0]
	v_pk_mul_f32 v[102:103], v[102:103], v[194:195] op_sel_hi:[1,0]
	v_pk_mul_f32 v[100:101], v[100:101], v[194:195] op_sel_hi:[1,0]
	v_pk_mul_f32 v[98:99], v[98:99], v[194:195] op_sel_hi:[1,0]
	v_cmp_ne_u32_e64 s[8:9], 1, v114
	s_andn2_b64 vcc, exec, s[46:47]
	v_pk_mul_f32 v[96:97], v[96:97], v[194:195] op_sel_hi:[1,0]
	global_store_dwordx4 v[196:197], v[116:119], off offset:64 sc1
	s_cbranch_vccnz .LBB0_1763
	s_nop 0
	v_mov_b32_e32 v116, v109
	v_mov_b32_e32 v117, v101
	v_mov_b32_e32 v114, v108
	v_mov_b32_e32 v115, v100
	v_pk_mul_f32 v[116:117], v[116:117], v[116:117]
	v_mov_b32_e32 v118, v111
	v_mov_b32_e32 v119, v103
	v_pk_fma_f32 v[114:115], v[114:115], v[114:115], v[116:117]
	v_mov_b32_e32 v116, v110
	v_mov_b32_e32 v117, v102
	v_pk_mul_f32 v[118:119], v[118:119], v[118:119]
	v_mov_b32_e32 v120, v107
	v_pk_fma_f32 v[116:117], v[116:117], v[116:117], v[118:119]
	v_mov_b32_e32 v118, v105
	v_mov_b32_e32 v119, v97
	v_pk_add_f32 v[114:115], v[114:115], v[116:117]
	v_mov_b32_e32 v116, v104
	v_mov_b32_e32 v117, v96
	v_pk_mul_f32 v[118:119], v[118:119], v[118:119]
	v_mov_b32_e32 v121, v99
	v_pk_fma_f32 v[116:117], v[116:117], v[116:117], v[118:119]
	v_mov_b32_e32 v118, v106
	v_mov_b32_e32 v119, v98
	v_pk_mul_f32 v[120:121], v[120:121], v[120:121]
	s_nop 0
	v_pk_fma_f32 v[118:119], v[118:119], v[118:119], v[120:121]
	s_nop 0
	v_pk_add_f32 v[116:117], v[116:117], v[118:119]
	s_nop 0
	v_pk_add_f32 v[114:115], v[114:115], v[116:117]
	s_nop 0
	v_add_f32_e32 v114, v114, v115
	v_mov_b32_e32 v115, v201
	s_nop 0
	v_lshlrev_b32_e32 v115, 2, v115
	v_xor_b32_e32 v115, 64, v115
	v_mov_b32_e32 v115, v114
	s_nop 1
	v_permlane16_swap_b32_e32 v115, v114
	s_waitcnt lgkmcnt(0)
	v_add_f32_e32 v114, v114, v115
	v_mov_b32_e32 v115, v201
	s_nop 0
	v_lshlrev_b32_e32 v115, 2, v115
	v_xor_b32_e32 v115, 0x80, v115
	v_mov_b32_e32 v115, v114
	s_nop 1
	v_permlane32_swap_b32_e32 v115, v114
	s_waitcnt lgkmcnt(0)
	v_add_f32_e32 v114, v114, v115
	v_fmamk_f32 v114, v114, 0x3c800000, v184
	v_rsq_f32_e32 v114, v114
	s_nop 0
	v_pk_mul_f32 v[108:109], v[108:109], v[114:115] op_sel_hi:[1,0]
	v_pk_mul_f32 v[110:111], v[110:111], v[114:115] op_sel_hi:[1,0]
	v_pk_mul_f32 v[104:105], v[104:105], v[114:115] op_sel_hi:[1,0]
	v_pk_mul_f32 v[106:107], v[106:107], v[114:115] op_sel_hi:[1,0]
	v_pk_mul_f32 v[100:101], v[100:101], v[114:115] op_sel_hi:[1,0]
	v_pk_mul_f32 v[102:103], v[102:103], v[114:115] op_sel_hi:[1,0]
	v_pk_mul_f32 v[96:97], v[96:97], v[114:115] op_sel_hi:[1,0]
	v_pk_mul_f32 v[98:99], v[98:99], v[114:115] op_sel_hi:[1,0]
	v_pk_mul_f32 v[110:111], v[152:153], v[110:111]
	v_pk_mul_f32 v[108:109], v[156:157], v[108:109]
	v_pk_mul_f32 v[106:107], v[146:147], v[106:107]
	v_pk_mul_f32 v[104:105], v[148:149], v[104:105]
	v_pk_mul_f32 v[102:103], v[158:159], v[102:103]
	v_pk_mul_f32 v[100:101], v[160:161], v[100:101]
	v_pk_mul_f32 v[98:99], v[150:151], v[98:99]
	v_pk_mul_f32 v[96:97], v[154:155], v[96:97]
.LBB0_1763:
	v_add_f32_e32 v114, v191, v192
	v_fmamk_f32 v114, v114, 0x3a800000, v184
	v_rsq_f32_e32 v114, v114
	v_add_u32_e32 v115, s23, v176
	v_mov_b64_e32 v[116:117], s[20:21]
	v_mad_i64_i32 v[116:117], s[46:47], v115, s68, v[116:117]
	v_lshl_add_u64 v[116:117], v[112:113], 1, v[116:117]
	v_pk_mul_f32 v[94:95], v[94:95], v[114:115] op_sel_hi:[1,0]
	v_pk_mul_f32 v[92:93], v[92:93], v[114:115] op_sel_hi:[1,0]
	v_pk_mul_f32 v[90:91], v[90:91], v[114:115] op_sel_hi:[1,0]
	v_pk_mul_f32 v[88:89], v[88:89], v[114:115] op_sel_hi:[1,0]
	v_pk_mul_f32 v[86:87], v[86:87], v[114:115] op_sel_hi:[1,0]
	v_pk_mul_f32 v[84:85], v[84:85], v[114:115] op_sel_hi:[1,0]
	v_pk_mul_f32 v[82:83], v[82:83], v[114:115] op_sel_hi:[1,0]
	s_and_b64 vcc, exec, s[8:9]
	v_pk_mul_f32 v[80:81], v[80:81], v[114:115] op_sel_hi:[1,0]
	v_cvt_pk_bf16_f32 v108, v108, v109
	v_cvt_pk_bf16_f32 v109, v110, v111
	v_cvt_pk_bf16_f32 v110, v104, v105
	v_cvt_pk_bf16_f32 v111, v106, v107
	global_store_dwordx4 v[116:117], v[108:111], off sc1
	v_cvt_pk_bf16_f32 v100, v100, v101
	v_cvt_pk_bf16_f32 v101, v102, v103
	v_cvt_pk_bf16_f32 v102, v96, v97
	v_cvt_pk_bf16_f32 v103, v98, v99
	global_store_dwordx4 v[116:117], v[100:103], off offset:64 sc1
	s_cbranch_vccnz .LBB0_1765
; __device__ __forceinline__ f32x4 silu4(f32x4 v) { return (f32x4){silu_f(v[0]), silu_f(v[1]), silu_f(v[2]), silu_f(v[3])}; }
; __device__ __forceinline__ float sq4(f32x4 v) { return (v[0] * v[0] + v[1] * v[1]) + (v[2] * v[2] + v[3] * v[3]); }
; __device__ __forceinline__ u32x4 pack8(f32x4 a, f32x4 b) { u32x4 w; w.x = cvt_pk_bf16(a[0], a[1]); w.y = cvt_pk_bf16(a[2], a[3]); w.z = cvt_pk_bf16(b[0], b[1]); w.w = cvt_pk_bf16(b[2], b[3]); return w; }
;     __device__ __forceinline__ void operator()(const f32x4 (&acc)[2][2][4][2], const Unit& u, int wr, int wc, int fr, int fq) const {
;     ...
;                 const int row = u.pm * BM + ai * HALF + wr * 64 + m * 16 + fr;
;                 const float rstd = rs[ai][m];
;                 f32x4 v[2][2];
; #pragma unroll
;                 for (int bj = 0; bj < 2; ++bj)
; #pragma unroll
;                     for (int n = 0; n < 2; ++n) v[bj][n] = acc[ai][bj][m][n] * rstd;
;                 if (mode == 2) {
;                     float q = (sq4(v[0][0]) + sq4(v[0][1])) + (sq4(v[1][0]) + sq4(v[1][1]));
;                     q += shx(q, 16); q += shx(q, 32);
;                     const float r2 = __builtin_amdgcn_rsqf(q * (1.0f / 64.0f) + RMS_EPS);
; #pragma unroll
;                     for (int bj = 0; bj < 2; ++bj)
; #pragma unroll
;                         for (int n = 0; n < 2; ++n) v[bj][n] = v[bj][n] * r2 * wv[bj][n];
;                 } else if (mode == 1) {
; #pragma unroll
;                     for (int bj = 0; bj < 2; ++bj)
; #pragma unroll
;                         for (int n = 0; n < 2; ++n) v[bj][n] = silu4(v[bj][n]);
;                 } else {
; #pragma unroll
;                     for (int bj = 0; bj < 2; ++bj)
; #pragma unroll
;                         for (int n = 0; n < 2; ++n) v[bj][n] = v[bj][n] * sc;
;                 }
;                 bf16_t* rowp = U + (size_t)row * 2560 + lcol;
; #pragma unroll
;                 for (int bj = 0; bj < 2; ++bj) *(u32x4*)(rowp + 32 * bj) = pack8(v[bj][0], v[bj][1]);
	v_mov_b32_e32 v98, v93
	v_mov_b32_e32 v99, v85
	v_mov_b32_e32 v96, v92
	v_mov_b32_e32 v97, v84
	v_pk_mul_f32 v[98:99], v[98:99], v[98:99]
	v_mov_b32_e32 v100, v95
	v_mov_b32_e32 v101, v87
	v_pk_fma_f32 v[96:97], v[96:97], v[96:97], v[98:99]
	v_mov_b32_e32 v98, v94
	v_mov_b32_e32 v99, v86
	v_pk_mul_f32 v[100:101], v[100:101], v[100:101]
	v_mov_b32_e32 v102, v91
	v_pk_fma_f32 v[98:99], v[98:99], v[98:99], v[100:101]
	v_mov_b32_e32 v100, v89
	v_mov_b32_e32 v101, v81
	v_pk_add_f32 v[96:97], v[96:97], v[98:99]
	v_mov_b32_e32 v98, v88
	v_mov_b32_e32 v99, v80
	v_pk_mul_f32 v[100:101], v[100:101], v[100:101]
	v_mov_b32_e32 v103, v83
	v_pk_fma_f32 v[98:99], v[98:99], v[98:99], v[100:101]
	v_mov_b32_e32 v100, v90
	v_mov_b32_e32 v101, v82
	v_pk_mul_f32 v[102:103], v[102:103], v[102:103]
	s_nop 0
	v_pk_fma_f32 v[100:101], v[100:101], v[100:101], v[102:103]
	s_nop 0
	v_pk_add_f32 v[98:99], v[98:99], v[100:101]
	s_nop 0
	v_pk_add_f32 v[96:97], v[96:97], v[98:99]
	s_nop 0
	v_add_f32_e32 v96, v96, v97
	v_mov_b32_e32 v97, v201
	s_nop 0
	v_lshlrev_b32_e32 v97, 2, v97
	v_xor_b32_e32 v97, 64, v97
	v_mov_b32_e32 v97, v96
	s_nop 1
	v_permlane16_swap_b32_e32 v97, v96
	s_waitcnt lgkmcnt(0)
	v_add_f32_e32 v96, v96, v97
	v_mov_b32_e32 v97, v201
	s_nop 0
	v_lshlrev_b32_e32 v97, 2, v97
	v_xor_b32_e32 v97, 0x80, v97
	v_mov_b32_e32 v97, v96
	s_nop 1
	v_permlane32_swap_b32_e32 v97, v96
	s_waitcnt lgkmcnt(0)
	v_add_f32_e32 v96, v96, v97
	v_fmamk_f32 v96, v96, 0x3c800000, v184
	v_rsq_f32_e32 v96, v96
	s_nop 0
	v_pk_mul_f32 v[92:93], v[92:93], v[96:97] op_sel_hi:[1,0]
	v_pk_mul_f32 v[94:95], v[94:95], v[96:97] op_sel_hi:[1,0]
	v_pk_mul_f32 v[88:89], v[88:89], v[96:97] op_sel_hi:[1,0]
	v_pk_mul_f32 v[90:91], v[90:91], v[96:97] op_sel_hi:[1,0]
	v_pk_mul_f32 v[84:85], v[84:85], v[96:97] op_sel_hi:[1,0]
	v_pk_mul_f32 v[86:87], v[86:87], v[96:97] op_sel_hi:[1,0]
	v_pk_mul_f32 v[80:81], v[80:81], v[96:97] op_sel_hi:[1,0]
	v_pk_mul_f32 v[82:83], v[82:83], v[96:97] op_sel_hi:[1,0]
	v_pk_mul_f32 v[94:95], v[152:153], v[94:95]
	v_pk_mul_f32 v[92:93], v[156:157], v[92:93]
	v_pk_mul_f32 v[90:91], v[146:147], v[90:91]
	v_pk_mul_f32 v[88:89], v[148:149], v[88:89]
	v_pk_mul_f32 v[86:87], v[158:159], v[86:87]
	v_pk_mul_f32 v[84:85], v[160:161], v[84:85]
	v_pk_mul_f32 v[82:83], v[150:151], v[82:83]
	v_pk_mul_f32 v[80:81], v[154:155], v[80:81]
.LBB0_1765:
	v_add_f32_e32 v96, v189, v190
	v_fmamk_f32 v96, v96, 0x3a800000, v184
	v_rsq_f32_e32 v96, v96
	v_add_u32_e32 v97, s23, v177
	v_mov_b64_e32 v[98:99], s[20:21]
	v_mad_i64_i32 v[98:99], s[46:47], v97, s68, v[98:99]
	v_lshl_add_u64 v[98:99], v[112:113], 1, v[98:99]
	v_pk_mul_f32 v[78:79], v[78:79], v[96:97] op_sel_hi:[1,0]
	v_pk_mul_f32 v[76:77], v[76:77], v[96:97] op_sel_hi:[1,0]
	v_pk_mul_f32 v[74:75], v[74:75], v[96:97] op_sel_hi:[1,0]
	v_pk_mul_f32 v[72:73], v[72:73], v[96:97] op_sel_hi:[1,0]
	v_pk_mul_f32 v[70:71], v[70:71], v[96:97] op_sel_hi:[1,0]
	v_pk_mul_f32 v[68:69], v[68:69], v[96:97] op_sel_hi:[1,0]
	v_pk_mul_f32 v[66:67], v[66:67], v[96:97] op_sel_hi:[1,0]
	s_and_b64 vcc, exec, s[8:9]
	v_pk_mul_f32 v[64:65], v[64:65], v[96:97] op_sel_hi:[1,0]
	v_cvt_pk_bf16_f32 v92, v92, v93
	v_cvt_pk_bf16_f32 v93, v94, v95
	v_cvt_pk_bf16_f32 v94, v88, v89
	v_cvt_pk_bf16_f32 v95, v90, v91
	global_store_dwordx4 v[98:99], v[92:95], off sc1
	v_cvt_pk_bf16_f32 v84, v84, v85
	v_cvt_pk_bf16_f32 v85, v86, v87
	v_cvt_pk_bf16_f32 v86, v80, v81
	v_cvt_pk_bf16_f32 v87, v82, v83
	global_store_dwordx4 v[98:99], v[84:87], off offset:64 sc1
	s_cbranch_vccnz .LBB0_1767
	v_mov_b32_e32 v82, v77
	v_mov_b32_e32 v83, v69
	v_mov_b32_e32 v80, v76
	v_mov_b32_e32 v81, v68
	v_pk_mul_f32 v[82:83], v[82:83], v[82:83]
	v_mov_b32_e32 v84, v79
	v_mov_b32_e32 v85, v71
	v_pk_fma_f32 v[80:81], v[80:81], v[80:81], v[82:83]
	v_mov_b32_e32 v82, v78
	v_mov_b32_e32 v83, v70
	v_pk_mul_f32 v[84:85], v[84:85], v[84:85]
	v_mov_b32_e32 v86, v75
	v_pk_fma_f32 v[82:83], v[82:83], v[82:83], v[84:85]
	v_mov_b32_e32 v84, v73
	v_mov_b32_e32 v85, v65
	v_pk_add_f32 v[80:81], v[80:81], v[82:83]
	v_mov_b32_e32 v82, v72
	v_mov_b32_e32 v83, v64
	v_pk_mul_f32 v[84:85], v[84:85], v[84:85]
	v_mov_b32_e32 v87, v67
	v_pk_fma_f32 v[82:83], v[82:83], v[82:83], v[84:85]
	v_mov_b32_e32 v84, v74
	v_mov_b32_e32 v85, v66
	v_pk_mul_f32 v[86:87], v[86:87], v[86:87]
	s_nop 0
	v_pk_fma_f32 v[84:85], v[84:85], v[84:85], v[86:87]
	s_nop 0
	v_pk_add_f32 v[82:83], v[82:83], v[84:85]
	s_nop 0
	v_pk_add_f32 v[80:81], v[80:81], v[82:83]
	s_nop 0
	v_add_f32_e32 v80, v80, v81
	v_mov_b32_e32 v81, v201
	s_nop 0
	v_lshlrev_b32_e32 v81, 2, v81
	v_xor_b32_e32 v81, 64, v81
	v_mov_b32_e32 v81, v80
	s_nop 1
	v_permlane16_swap_b32_e32 v81, v80
	s_waitcnt lgkmcnt(0)
	v_add_f32_e32 v80, v80, v81
	v_mov_b32_e32 v81, v201
	s_nop 0
	v_lshlrev_b32_e32 v81, 2, v81
	v_xor_b32_e32 v81, 0x80, v81
	v_mov_b32_e32 v81, v80
	s_nop 1
	v_permlane32_swap_b32_e32 v81, v80
	s_waitcnt lgkmcnt(0)
	v_add_f32_e32 v80, v80, v81
	v_fmamk_f32 v80, v80, 0x3c800000, v184
	v_rsq_f32_e32 v80, v80
	s_nop 0
	v_pk_mul_f32 v[76:77], v[76:77], v[80:81] op_sel_hi:[1,0]
	v_pk_mul_f32 v[78:79], v[78:79], v[80:81] op_sel_hi:[1,0]
	v_pk_mul_f32 v[72:73], v[72:73], v[80:81] op_sel_hi:[1,0]
	v_pk_mul_f32 v[74:75], v[74:75], v[80:81] op_sel_hi:[1,0]
	v_pk_mul_f32 v[68:69], v[68:69], v[80:81] op_sel_hi:[1,0]
	v_pk_mul_f32 v[70:71], v[70:71], v[80:81] op_sel_hi:[1,0]
	v_pk_mul_f32 v[64:65], v[64:65], v[80:81] op_sel_hi:[1,0]
	v_pk_mul_f32 v[66:67], v[66:67], v[80:81] op_sel_hi:[1,0]
	v_pk_mul_f32 v[78:79], v[152:153], v[78:79]
	v_pk_mul_f32 v[76:77], v[156:157], v[76:77]
	v_pk_mul_f32 v[74:75], v[146:147], v[74:75]
	v_pk_mul_f32 v[72:73], v[148:149], v[72:73]
	v_pk_mul_f32 v[70:71], v[158:159], v[70:71]
	v_pk_mul_f32 v[68:69], v[160:161], v[68:69]
	v_pk_mul_f32 v[66:67], v[150:151], v[66:67]
	v_pk_mul_f32 v[64:65], v[154:155], v[64:65]
; __device__ __forceinline__ f32x4 silu4(f32x4 v) { return (f32x4){silu_f(v[0]), silu_f(v[1]), silu_f(v[2]), silu_f(v[3])}; }
; __device__ __forceinline__ float sq4(f32x4 v) { return (v[0] * v[0] + v[1] * v[1]) + (v[2] * v[2] + v[3] * v[3]); }
; __device__ __forceinline__ u32x4 pack8(f32x4 a, f32x4 b) { u32x4 w; w.x = cvt_pk_bf16(a[0], a[1]); w.y = cvt_pk_bf16(a[2], a[3]); w.z = cvt_pk_bf16(b[0], b[1]); w.w = cvt_pk_bf16(b[2], b[3]); return w; }
;     __device__ __forceinline__ void operator()(const f32x4 (&acc)[2][2][4][2], const Unit& u, int wr, int wc, int fr, int fq) const {
;     ...
;                 const int row = u.pm * BM + ai * HALF + wr * 64 + m * 16 + fr;
;                 const float rstd = rs[ai][m];
;                 f32x4 v[2][2];
; #pragma unroll
;                 for (int bj = 0; bj < 2; ++bj)
; #pragma unroll
;                     for (int n = 0; n < 2; ++n) v[bj][n] = acc[ai][bj][m][n] * rstd;
;                 if (mode == 2) {
;                     float q = (sq4(v[0][0]) + sq4(v[0][1])) + (sq4(v[1][0]) + sq4(v[1][1]));
;                     q += shx(q, 16); q += shx(q, 32);
;                     const float r2 = __builtin_amdgcn_rsqf(q * (1.0f / 64.0f) + RMS_EPS);
; #pragma unroll
;                     for (int bj = 0; bj < 2; ++bj)
; #pragma unroll
;                         for (int n = 0; n < 2; ++n) v[bj][n] = v[bj][n] * r2 * wv[bj][n];
;                 } else if (mode == 1) {
; #pragma unroll
;                     for (int bj = 0; bj < 2; ++bj)
; #pragma unroll
;                         for (int n = 0; n < 2; ++n) v[bj][n] = silu4(v[bj][n]);
;                 } else {
; #pragma unroll
;                     for (int bj = 0; bj < 2; ++bj)
; #pragma unroll
;                         for (int n = 0; n < 2; ++n) v[bj][n] = v[bj][n] * sc;
;                 }
;                 bf16_t* rowp = U + (size_t)row * 2560 + lcol;
; #pragma unroll
;                 for (int bj = 0; bj < 2; ++bj) *(u32x4*)(rowp + 32 * bj) = pack8(v[bj][0], v[bj][1]);
.LBB0_1767:
	v_add_f32_e32 v80, v187, v188
	v_fmamk_f32 v80, v80, 0x3a800000, v184
	v_rsq_f32_e32 v80, v80
	v_add_u32_e32 v81, s23, v178
	v_mov_b64_e32 v[82:83], s[20:21]
	v_mad_i64_i32 v[82:83], s[46:47], v81, s68, v[82:83]
	v_lshl_add_u64 v[82:83], v[112:113], 1, v[82:83]
	v_pk_mul_f32 v[62:63], v[62:63], v[80:81] op_sel_hi:[1,0]
	v_pk_mul_f32 v[60:61], v[60:61], v[80:81] op_sel_hi:[1,0]
	v_pk_mul_f32 v[58:59], v[58:59], v[80:81] op_sel_hi:[1,0]
	v_pk_mul_f32 v[56:57], v[56:57], v[80:81] op_sel_hi:[1,0]
	v_pk_mul_f32 v[54:55], v[54:55], v[80:81] op_sel_hi:[1,0]
	v_pk_mul_f32 v[52:53], v[52:53], v[80:81] op_sel_hi:[1,0]
	v_pk_mul_f32 v[50:51], v[50:51], v[80:81] op_sel_hi:[1,0]
	s_and_b64 vcc, exec, s[8:9]
	v_pk_mul_f32 v[48:49], v[48:49], v[80:81] op_sel_hi:[1,0]
	v_cvt_pk_bf16_f32 v76, v76, v77
	v_cvt_pk_bf16_f32 v77, v78, v79
	v_cvt_pk_bf16_f32 v78, v72, v73
	v_cvt_pk_bf16_f32 v79, v74, v75
	global_store_dwordx4 v[82:83], v[76:79], off sc1
	v_cvt_pk_bf16_f32 v68, v68, v69
	v_cvt_pk_bf16_f32 v69, v70, v71
	v_cvt_pk_bf16_f32 v70, v64, v65
	v_cvt_pk_bf16_f32 v71, v66, v67
	global_store_dwordx4 v[82:83], v[68:71], off offset:64 sc1
	s_cbranch_vccnz .LBB0_1769
	v_mov_b32_e32 v66, v61
	v_mov_b32_e32 v67, v53
	v_mov_b32_e32 v64, v60
	v_mov_b32_e32 v65, v52
	v_pk_mul_f32 v[66:67], v[66:67], v[66:67]
	v_mov_b32_e32 v68, v63
	v_mov_b32_e32 v69, v55
	v_pk_fma_f32 v[64:65], v[64:65], v[64:65], v[66:67]
	v_mov_b32_e32 v66, v62
	v_mov_b32_e32 v67, v54
	v_pk_mul_f32 v[68:69], v[68:69], v[68:69]
	v_mov_b32_e32 v70, v59
	v_pk_fma_f32 v[66:67], v[66:67], v[66:67], v[68:69]
	v_mov_b32_e32 v68, v57
	v_mov_b32_e32 v69, v49
	v_pk_add_f32 v[64:65], v[64:65], v[66:67]
	v_mov_b32_e32 v66, v56
	v_mov_b32_e32 v67, v48
	v_pk_mul_f32 v[68:69], v[68:69], v[68:69]
	v_mov_b32_e32 v71, v51
	v_pk_fma_f32 v[66:67], v[66:67], v[66:67], v[68:69]
	v_mov_b32_e32 v68, v58
	v_mov_b32_e32 v69, v50
	v_pk_mul_f32 v[70:71], v[70:71], v[70:71]
	s_nop 0
	v_pk_fma_f32 v[68:69], v[68:69], v[68:69], v[70:71]
	s_nop 0
	v_pk_add_f32 v[66:67], v[66:67], v[68:69]
	s_nop 0
	v_pk_add_f32 v[64:65], v[64:65], v[66:67]
	s_nop 0
	v_add_f32_e32 v64, v64, v65
	v_mov_b32_e32 v65, v201
	s_nop 0
	v_lshlrev_b32_e32 v65, 2, v65
	v_xor_b32_e32 v65, 64, v65
	v_mov_b32_e32 v65, v64
	s_nop 1
	v_permlane16_swap_b32_e32 v65, v64
	s_waitcnt lgkmcnt(0)
	v_add_f32_e32 v64, v64, v65
	v_mov_b32_e32 v65, v201
	s_nop 0
	v_lshlrev_b32_e32 v65, 2, v65
	v_xor_b32_e32 v65, 0x80, v65
	v_mov_b32_e32 v65, v64
	s_nop 1
	v_permlane32_swap_b32_e32 v65, v64
	s_waitcnt lgkmcnt(0)
	v_add_f32_e32 v64, v64, v65
	v_fmamk_f32 v64, v64, 0x3c800000, v184
	v_rsq_f32_e32 v64, v64
	s_nop 0
	v_pk_mul_f32 v[60:61], v[60:61], v[64:65] op_sel_hi:[1,0]
	v_pk_mul_f32 v[62:63], v[62:63], v[64:65] op_sel_hi:[1,0]
	v_pk_mul_f32 v[56:57], v[56:57], v[64:65] op_sel_hi:[1,0]
	v_pk_mul_f32 v[58:59], v[58:59], v[64:65] op_sel_hi:[1,0]
	v_pk_mul_f32 v[52:53], v[52:53], v[64:65] op_sel_hi:[1,0]
	v_pk_mul_f32 v[54:55], v[54:55], v[64:65] op_sel_hi:[1,0]
	v_pk_mul_f32 v[48:49], v[48:49], v[64:65] op_sel_hi:[1,0]
	v_pk_mul_f32 v[50:51], v[50:51], v[64:65] op_sel_hi:[1,0]
	v_pk_mul_f32 v[62:63], v[152:153], v[62:63]
	v_pk_mul_f32 v[60:61], v[156:157], v[60:61]
	v_pk_mul_f32 v[58:59], v[146:147], v[58:59]
	v_pk_mul_f32 v[56:57], v[148:149], v[56:57]
	v_pk_mul_f32 v[54:55], v[158:159], v[54:55]
	v_pk_mul_f32 v[52:53], v[160:161], v[52:53]
	v_pk_mul_f32 v[50:51], v[150:151], v[50:51]
	v_pk_mul_f32 v[48:49], v[154:155], v[48:49]
.LBB0_1769:
	v_add_f32_e32 v64, v171, v186
	v_fmamk_f32 v64, v64, 0x3a800000, v184
	v_rsq_f32_e32 v64, v64
	v_mov_b64_e32 v[66:67], s[20:21]
	v_mad_i64_i32 v[66:67], s[46:47], v168, s68, v[66:67]
	v_lshl_add_u64 v[66:67], v[112:113], 1, v[66:67]
	v_pk_mul_f32 v[46:47], v[46:47], v[64:65] op_sel_hi:[1,0]
	v_pk_mul_f32 v[44:45], v[44:45], v[64:65] op_sel_hi:[1,0]
	v_pk_mul_f32 v[42:43], v[42:43], v[64:65] op_sel_hi:[1,0]
	v_pk_mul_f32 v[40:41], v[40:41], v[64:65] op_sel_hi:[1,0]
	v_pk_mul_f32 v[38:39], v[38:39], v[64:65] op_sel_hi:[1,0]
	v_pk_mul_f32 v[36:37], v[36:37], v[64:65] op_sel_hi:[1,0]
	v_pk_mul_f32 v[34:35], v[34:35], v[64:65] op_sel_hi:[1,0]
	s_and_b64 vcc, exec, s[8:9]
	v_pk_mul_f32 v[32:33], v[32:33], v[64:65] op_sel_hi:[1,0]
	v_cvt_pk_bf16_f32 v60, v60, v61
	v_cvt_pk_bf16_f32 v61, v62, v63
	v_cvt_pk_bf16_f32 v62, v56, v57
	v_cvt_pk_bf16_f32 v63, v58, v59
	global_store_dwordx4 v[66:67], v[60:63], off sc1
	v_cvt_pk_bf16_f32 v52, v52, v53
	v_cvt_pk_bf16_f32 v53, v54, v55
	v_cvt_pk_bf16_f32 v54, v48, v49
	v_cvt_pk_bf16_f32 v55, v50, v51
	global_store_dwordx4 v[66:67], v[52:55], off offset:64 sc1
	s_cbranch_vccnz .LBB0_1771
	v_mov_b32_e32 v50, v45
	v_mov_b32_e32 v51, v37
	v_mov_b32_e32 v48, v44
	v_mov_b32_e32 v49, v36
	v_pk_mul_f32 v[50:51], v[50:51], v[50:51]
	v_mov_b32_e32 v52, v47
	v_mov_b32_e32 v53, v39
	v_pk_fma_f32 v[48:49], v[48:49], v[48:49], v[50:51]
	v_mov_b32_e32 v50, v46
	v_mov_b32_e32 v51, v38
	v_pk_mul_f32 v[52:53], v[52:53], v[52:53]
	v_mov_b32_e32 v54, v43
	v_pk_fma_f32 v[50:51], v[50:51], v[50:51], v[52:53]
	v_mov_b32_e32 v52, v41
	v_mov_b32_e32 v53, v33
	v_pk_add_f32 v[48:49], v[48:49], v[50:51]
	v_mov_b32_e32 v50, v40
	v_mov_b32_e32 v51, v32
	v_pk_mul_f32 v[52:53], v[52:53], v[52:53]
	v_mov_b32_e32 v55, v35
	v_pk_fma_f32 v[50:51], v[50:51], v[50:51], v[52:53]
	v_mov_b32_e32 v52, v42
	v_mov_b32_e32 v53, v34
	v_pk_mul_f32 v[54:55], v[54:55], v[54:55]
	s_nop 0
	v_pk_fma_f32 v[52:53], v[52:53], v[52:53], v[54:55]
	s_nop 0
	v_pk_add_f32 v[50:51], v[50:51], v[52:53]
	s_nop 0
	v_pk_add_f32 v[48:49], v[48:49], v[50:51]
	s_nop 0
	v_add_f32_e32 v48, v48, v49
	v_mov_b32_e32 v49, v201
	s_nop 0
	v_lshlrev_b32_e32 v49, 2, v49
	v_xor_b32_e32 v49, 64, v49
	v_mov_b32_e32 v49, v48
	s_nop 1
	v_permlane16_swap_b32_e32 v49, v48
	s_waitcnt lgkmcnt(0)
	v_add_f32_e32 v48, v48, v49
	v_mov_b32_e32 v49, v201
	s_nop 0
	v_lshlrev_b32_e32 v49, 2, v49
	v_xor_b32_e32 v49, 0x80, v49
	v_mov_b32_e32 v49, v48
	s_nop 1
	v_permlane32_swap_b32_e32 v49, v48
	s_waitcnt lgkmcnt(0)
	v_add_f32_e32 v48, v48, v49
	v_fmamk_f32 v48, v48, 0x3c800000, v184
	v_rsq_f32_e32 v48, v48
	s_nop 0
	v_pk_mul_f32 v[44:45], v[44:45], v[48:49] op_sel_hi:[1,0]
	v_pk_mul_f32 v[46:47], v[46:47], v[48:49] op_sel_hi:[1,0]
	v_pk_mul_f32 v[40:41], v[40:41], v[48:49] op_sel_hi:[1,0]
	v_pk_mul_f32 v[42:43], v[42:43], v[48:49] op_sel_hi:[1,0]
	v_pk_mul_f32 v[36:37], v[36:37], v[48:49] op_sel_hi:[1,0]
	v_pk_mul_f32 v[38:39], v[38:39], v[48:49] op_sel_hi:[1,0]
	v_pk_mul_f32 v[32:33], v[32:33], v[48:49] op_sel_hi:[1,0]
	v_pk_mul_f32 v[34:35], v[34:35], v[48:49] op_sel_hi:[1,0]
	v_pk_mul_f32 v[46:47], v[152:153], v[46:47]
	v_pk_mul_f32 v[44:45], v[156:157], v[44:45]
	v_pk_mul_f32 v[42:43], v[146:147], v[42:43]
	v_pk_mul_f32 v[40:41], v[148:149], v[40:41]
	v_pk_mul_f32 v[38:39], v[158:159], v[38:39]
	v_pk_mul_f32 v[36:37], v[160:161], v[36:37]
	v_pk_mul_f32 v[34:35], v[150:151], v[34:35]
	v_pk_mul_f32 v[32:33], v[154:155], v[32:33]
; __device__ __forceinline__ f32x4 silu4(f32x4 v) { return (f32x4){silu_f(v[0]), silu_f(v[1]), silu_f(v[2]), silu_f(v[3])}; }
; __device__ __forceinline__ float sq4(f32x4 v) { return (v[0] * v[0] + v[1] * v[1]) + (v[2] * v[2] + v[3] * v[3]); }
; __device__ __forceinline__ u32x4 pack8(f32x4 a, f32x4 b) { u32x4 w; w.x = cvt_pk_bf16(a[0], a[1]); w.y = cvt_pk_bf16(a[2], a[3]); w.z = cvt_pk_bf16(b[0], b[1]); w.w = cvt_pk_bf16(b[2], b[3]); return w; }
;     __device__ __forceinline__ void operator()(const f32x4 (&acc)[2][2][4][2], const Unit& u, int wr, int wc, int fr, int fq) const {
;     ...
;                 const int row = u.pm * BM + ai * HALF + wr * 64 + m * 16 + fr;
;                 const float rstd = rs[ai][m];
;                 f32x4 v[2][2];
; #pragma unroll
;                 for (int bj = 0; bj < 2; ++bj)
; #pragma unroll
;                     for (int n = 0; n < 2; ++n) v[bj][n] = acc[ai][bj][m][n] * rstd;
;                 if (mode == 2) {
;                     float q = (sq4(v[0][0]) + sq4(v[0][1])) + (sq4(v[1][0]) + sq4(v[1][1]));
;                     q += shx(q, 16); q += shx(q, 32);
;                     const float r2 = __builtin_amdgcn_rsqf(q * (1.0f / 64.0f) + RMS_EPS);
; #pragma unroll
;                     for (int bj = 0; bj < 2; ++bj)
; #pragma unroll
;                         for (int n = 0; n < 2; ++n) v[bj][n] = v[bj][n] * r2 * wv[bj][n];
;                 } else if (mode == 1) {
; #pragma unroll
;                     for (int bj = 0; bj < 2; ++bj)
; #pragma unroll
;                         for (int n = 0; n < 2; ++n) v[bj][n] = silu4(v[bj][n]);
;                 } else {
; #pragma unroll
;                     for (int bj = 0; bj < 2; ++bj)
; #pragma unroll
;                         for (int n = 0; n < 2; ++n) v[bj][n] = v[bj][n] * sc;
;                 }
;                 bf16_t* rowp = U + (size_t)row * 2560 + lcol;
; #pragma unroll
;                 for (int bj = 0; bj < 2; ++bj) *(u32x4*)(rowp + 32 * bj) = pack8(v[bj][0], v[bj][1]);
.LBB0_1771:
	v_add_f32_e32 v48, v167, v169
	v_fmamk_f32 v48, v48, 0x3a800000, v184
	v_rsq_f32_e32 v48, v48
	v_mov_b64_e32 v[50:51], s[20:21]
	v_mad_i64_i32 v[50:51], s[46:47], v166, s68, v[50:51]
	v_lshl_add_u64 v[50:51], v[112:113], 1, v[50:51]
	v_pk_mul_f32 v[30:31], v[30:31], v[48:49] op_sel_hi:[1,0]
	v_pk_mul_f32 v[28:29], v[28:29], v[48:49] op_sel_hi:[1,0]
	v_pk_mul_f32 v[26:27], v[26:27], v[48:49] op_sel_hi:[1,0]
	v_pk_mul_f32 v[24:25], v[24:25], v[48:49] op_sel_hi:[1,0]
	v_pk_mul_f32 v[22:23], v[22:23], v[48:49] op_sel_hi:[1,0]
	v_pk_mul_f32 v[20:21], v[20:21], v[48:49] op_sel_hi:[1,0]
	v_pk_mul_f32 v[18:19], v[18:19], v[48:49] op_sel_hi:[1,0]
	s_and_b64 vcc, exec, s[8:9]
	v_pk_mul_f32 v[16:17], v[16:17], v[48:49] op_sel_hi:[1,0]
	v_cvt_pk_bf16_f32 v44, v44, v45
	v_cvt_pk_bf16_f32 v45, v46, v47
	v_cvt_pk_bf16_f32 v46, v40, v41
	v_cvt_pk_bf16_f32 v47, v42, v43
	global_store_dwordx4 v[50:51], v[44:47], off sc1
	v_cvt_pk_bf16_f32 v36, v36, v37
	v_cvt_pk_bf16_f32 v37, v38, v39
	v_cvt_pk_bf16_f32 v38, v32, v33
	v_cvt_pk_bf16_f32 v39, v34, v35
	global_store_dwordx4 v[50:51], v[36:39], off offset:64 sc1
	s_cbranch_vccnz .LBB0_1773
	v_mov_b32_e32 v34, v29
	v_mov_b32_e32 v35, v21
	v_mov_b32_e32 v32, v28
	v_mov_b32_e32 v33, v20
	v_pk_mul_f32 v[34:35], v[34:35], v[34:35]
	v_mov_b32_e32 v36, v31
	v_mov_b32_e32 v37, v23
	v_pk_fma_f32 v[32:33], v[32:33], v[32:33], v[34:35]
	v_mov_b32_e32 v34, v30
	v_mov_b32_e32 v35, v22
	v_pk_mul_f32 v[36:37], v[36:37], v[36:37]
	v_mov_b32_e32 v38, v27
	v_pk_fma_f32 v[34:35], v[34:35], v[34:35], v[36:37]
	v_mov_b32_e32 v36, v25
	v_mov_b32_e32 v37, v17
	v_pk_add_f32 v[32:33], v[32:33], v[34:35]
	v_mov_b32_e32 v34, v24
	v_mov_b32_e32 v35, v16
	v_pk_mul_f32 v[36:37], v[36:37], v[36:37]
	v_mov_b32_e32 v39, v19
	v_pk_fma_f32 v[34:35], v[34:35], v[34:35], v[36:37]
	v_mov_b32_e32 v36, v26
	v_mov_b32_e32 v37, v18
	v_pk_mul_f32 v[38:39], v[38:39], v[38:39]
	s_nop 0
	v_pk_fma_f32 v[36:37], v[36:37], v[36:37], v[38:39]
	s_nop 0
	v_pk_add_f32 v[34:35], v[34:35], v[36:37]
	s_nop 0
	v_pk_add_f32 v[32:33], v[32:33], v[34:35]
	s_nop 0
	v_add_f32_e32 v32, v32, v33
	v_mov_b32_e32 v33, v201
	s_nop 0
	v_lshlrev_b32_e32 v33, 2, v33
	v_xor_b32_e32 v33, 64, v33
	v_mov_b32_e32 v33, v32
	s_nop 1
	v_permlane16_swap_b32_e32 v33, v32
	s_waitcnt lgkmcnt(0)
	v_add_f32_e32 v32, v32, v33
	v_mov_b32_e32 v33, v201
	s_nop 0
	v_lshlrev_b32_e32 v33, 2, v33
	v_xor_b32_e32 v33, 0x80, v33
	v_mov_b32_e32 v33, v32
	s_nop 1
	v_permlane32_swap_b32_e32 v33, v32
	s_waitcnt lgkmcnt(0)
	v_add_f32_e32 v32, v32, v33
	v_fmamk_f32 v32, v32, 0x3c800000, v184
	v_rsq_f32_e32 v32, v32
	s_nop 0
	v_pk_mul_f32 v[28:29], v[28:29], v[32:33] op_sel_hi:[1,0]
	v_pk_mul_f32 v[30:31], v[30:31], v[32:33] op_sel_hi:[1,0]
	v_pk_mul_f32 v[24:25], v[24:25], v[32:33] op_sel_hi:[1,0]
	v_pk_mul_f32 v[26:27], v[26:27], v[32:33] op_sel_hi:[1,0]
	v_pk_mul_f32 v[20:21], v[20:21], v[32:33] op_sel_hi:[1,0]
	v_pk_mul_f32 v[22:23], v[22:23], v[32:33] op_sel_hi:[1,0]
	v_pk_mul_f32 v[16:17], v[16:17], v[32:33] op_sel_hi:[1,0]
	v_pk_mul_f32 v[18:19], v[18:19], v[32:33] op_sel_hi:[1,0]
	v_pk_mul_f32 v[30:31], v[152:153], v[30:31]
	v_pk_mul_f32 v[28:29], v[156:157], v[28:29]
	v_pk_mul_f32 v[26:27], v[146:147], v[26:27]
	v_pk_mul_f32 v[24:25], v[148:149], v[24:25]
	v_pk_mul_f32 v[22:23], v[158:159], v[22:23]
	v_pk_mul_f32 v[20:21], v[160:161], v[20:21]
	v_pk_mul_f32 v[18:19], v[150:151], v[18:19]
	v_pk_mul_f32 v[16:17], v[154:155], v[16:17]
; __device__ __forceinline__ f32x4 silu4(f32x4 v) { return (f32x4){silu_f(v[0]), silu_f(v[1]), silu_f(v[2]), silu_f(v[3])}; }
; #define PG8_BAR __builtin_amdgcn_s_barrier()
;     __device__ __forceinline__ void operator()(const f32x4 (&acc)[2][2][4][2], const Unit& u, int wr, int wc, int fr, int fq) const {
;     ...
;                 const int row = u.pm * BM + ai * HALF + wr * 64 + m * 16 + fr;
;                 const float rstd = rs[ai][m];
;                 f32x4 v[2][2];
; #pragma unroll
;                 for (int bj = 0; bj < 2; ++bj)
; #pragma unroll
;                     for (int n = 0; n < 2; ++n) v[bj][n] = acc[ai][bj][m][n] * rstd;
;                 if (mode == 2) {
;                     float q = (sq4(v[0][0]) + sq4(v[0][1])) + (sq4(v[1][0]) + sq4(v[1][1]));
;                     q += shx(q, 16); q += shx(q, 32);
;                     const float r2 = __builtin_amdgcn_rsqf(q * (1.0f / 64.0f) + RMS_EPS);
; #pragma unroll
;                     for (int bj = 0; bj < 2; ++bj)
; #pragma unroll
;                         for (int n = 0; n < 2; ++n) v[bj][n] = v[bj][n] * r2 * wv[bj][n];
;                 } else if (mode == 1) {
; #pragma unroll
;                     for (int bj = 0; bj < 2; ++bj)
; #pragma unroll
;                         for (int n = 0; n < 2; ++n) v[bj][n] = silu4(v[bj][n]);
;                 } else {
; #pragma unroll
;                     for (int bj = 0; bj < 2; ++bj)
; #pragma unroll
;                         for (int n = 0; n < 2; ++n) v[bj][n] = v[bj][n] * sc;
;                 }
;                 bf16_t* rowp = U + (size_t)row * 2560 + lcol;
; #pragma unroll
;                 for (int bj = 0; bj < 2; ++bj) *(u32x4*)(rowp + 32 * bj) = pack8(v[bj][0], v[bj][1]);
; template <class Epi, class Sched, bool ALIGN_EPI = false, bool SP2 = false>
; __device__ __forceinline__ void gemm_phase(PG8_LAS unsigned char* lds, const Gemm g, const Sched& S, const Epi& E, int tid_in) {
;     ...
;         if (!has_next) break;
; #pragma unroll
;         for (int a = 0; a < 2; ++a)
; #pragma unroll
;             for (int b = 0; b < 2; ++b)
; #pragma unroll
;                 for (int m = 0; m < 4; ++m)
; #pragma unroll
;                     for (int n = 0; n < 2; ++n) acc[a][b][m][n] = (f32x4){0.f, 0.f, 0.f, 0.f};
;         cur = nxt; cA = nA; cB = nB; ++ui;
;         if constexpr (ALIGN_EPI) { if (wr == 1) PG8_BAR; }
.LBB0_1773:
	s_waitcnt lgkmcnt(0)
	v_add_f32_e32 v32, v163, v165
	v_fmamk_f32 v32, v32, 0x3a800000, v184
	v_rsq_f32_e32 v32, v32
	v_mov_b64_e32 v[34:35], s[20:21]
	v_mad_i64_i32 v[34:35], s[46:47], v164, s68, v[34:35]
	v_lshl_add_u64 v[34:35], v[112:113], 1, v[34:35]
	v_pk_mul_f32 v[14:15], v[14:15], v[32:33] op_sel_hi:[1,0]
	v_pk_mul_f32 v[12:13], v[12:13], v[32:33] op_sel_hi:[1,0]
	v_pk_mul_f32 v[10:11], v[10:11], v[32:33] op_sel_hi:[1,0]
	v_pk_mul_f32 v[8:9], v[8:9], v[32:33] op_sel_hi:[1,0]
	v_pk_mul_f32 v[6:7], v[6:7], v[32:33] op_sel_hi:[1,0]
	v_pk_mul_f32 v[4:5], v[4:5], v[32:33] op_sel_hi:[1,0]
	v_pk_mul_f32 v[2:3], v[2:3], v[32:33] op_sel_hi:[1,0]
	s_and_b64 vcc, exec, s[8:9]
	v_pk_mul_f32 v[0:1], v[0:1], v[32:33] op_sel_hi:[1,0]
	v_cvt_pk_bf16_f32 v28, v28, v29
	v_cvt_pk_bf16_f32 v29, v30, v31
	v_cvt_pk_bf16_f32 v30, v24, v25
	v_cvt_pk_bf16_f32 v31, v26, v27
	global_store_dwordx4 v[34:35], v[28:31], off sc1
	v_cvt_pk_bf16_f32 v20, v20, v21
	v_cvt_pk_bf16_f32 v21, v22, v23
	v_cvt_pk_bf16_f32 v22, v16, v17
	v_cvt_pk_bf16_f32 v23, v18, v19
	global_store_dwordx4 v[34:35], v[20:23], off offset:64 sc1
	s_cbranch_vccnz .LBB0_1775
	v_mov_b32_e32 v18, v13
	v_mov_b32_e32 v19, v5
	v_mov_b32_e32 v16, v12
	v_mov_b32_e32 v17, v4
	v_pk_mul_f32 v[18:19], v[18:19], v[18:19]
	v_mov_b32_e32 v20, v15
	v_mov_b32_e32 v21, v7
	v_pk_fma_f32 v[16:17], v[16:17], v[16:17], v[18:19]
	v_mov_b32_e32 v18, v14
	v_mov_b32_e32 v19, v6
	v_pk_mul_f32 v[20:21], v[20:21], v[20:21]
	v_mov_b32_e32 v22, v11
	v_pk_fma_f32 v[18:19], v[18:19], v[18:19], v[20:21]
	v_mov_b32_e32 v20, v9
	v_mov_b32_e32 v21, v1
	v_pk_add_f32 v[16:17], v[16:17], v[18:19]
	v_mov_b32_e32 v18, v8
	v_mov_b32_e32 v19, v0
	v_pk_mul_f32 v[20:21], v[20:21], v[20:21]
	v_mov_b32_e32 v23, v3
	v_pk_fma_f32 v[18:19], v[18:19], v[18:19], v[20:21]
	v_mov_b32_e32 v20, v10
	v_mov_b32_e32 v21, v2
	v_pk_mul_f32 v[22:23], v[22:23], v[22:23]
	s_nop 0
	v_pk_fma_f32 v[20:21], v[20:21], v[20:21], v[22:23]
	s_nop 0
	v_pk_add_f32 v[18:19], v[18:19], v[20:21]
	s_nop 0
	v_pk_add_f32 v[16:17], v[16:17], v[18:19]
	s_nop 0
	v_add_f32_e32 v16, v16, v17
	v_mov_b32_e32 v17, v201
	s_nop 0
	v_lshlrev_b32_e32 v17, 2, v17
	v_xor_b32_e32 v17, 64, v17
	v_mov_b32_e32 v17, v16
	s_nop 1
	v_permlane16_swap_b32_e32 v17, v16
	s_waitcnt lgkmcnt(0)
	v_add_f32_e32 v16, v16, v17
	v_mov_b32_e32 v17, v201
	s_nop 0
	v_lshlrev_b32_e32 v17, 2, v17
	v_xor_b32_e32 v17, 0x80, v17
	v_mov_b32_e32 v17, v16
	s_nop 1
	v_permlane32_swap_b32_e32 v17, v16
	s_waitcnt lgkmcnt(0)
	v_add_f32_e32 v16, v16, v17
	v_fmamk_f32 v16, v16, 0x3c800000, v184
	v_rsq_f32_e32 v16, v16
	s_nop 0
	v_pk_mul_f32 v[12:13], v[12:13], v[16:17] op_sel_hi:[1,0]
	v_pk_mul_f32 v[14:15], v[14:15], v[16:17] op_sel_hi:[1,0]
	v_pk_mul_f32 v[8:9], v[8:9], v[16:17] op_sel_hi:[1,0]
	v_pk_mul_f32 v[10:11], v[10:11], v[16:17] op_sel_hi:[1,0]
	v_pk_mul_f32 v[4:5], v[4:5], v[16:17] op_sel_hi:[1,0]
	v_pk_mul_f32 v[6:7], v[6:7], v[16:17] op_sel_hi:[1,0]
	v_pk_mul_f32 v[0:1], v[0:1], v[16:17] op_sel_hi:[1,0]
	v_pk_mul_f32 v[2:3], v[2:3], v[16:17] op_sel_hi:[1,0]
	v_pk_mul_f32 v[14:15], v[152:153], v[14:15]
	v_pk_mul_f32 v[12:13], v[156:157], v[12:13]
	v_pk_mul_f32 v[10:11], v[146:147], v[10:11]
	v_pk_mul_f32 v[8:9], v[148:149], v[8:9]
	v_pk_mul_f32 v[6:7], v[158:159], v[6:7]
	v_pk_mul_f32 v[4:5], v[160:161], v[4:5]
	v_pk_mul_f32 v[2:3], v[150:151], v[2:3]
	v_pk_mul_f32 v[0:1], v[154:155], v[0:1]
.LBB0_1775:
	v_mov_b64_e32 v[16:17], s[20:21]
	v_mad_i64_i32 v[16:17], s[8:9], v162, s68, v[16:17]
	v_lshl_add_u64 v[16:17], v[112:113], 1, v[16:17]
	s_andn2_b64 vcc, exec, s[6:7]
	s_mov_b64 s[6:7], -1
	v_cvt_pk_bf16_f32 v12, v12, v13
	v_cvt_pk_bf16_f32 v13, v14, v15
	v_cvt_pk_bf16_f32 v14, v8, v9
	v_cvt_pk_bf16_f32 v15, v10, v11
	global_store_dwordx4 v[16:17], v[12:15], off sc1
	v_cvt_pk_bf16_f32 v4, v4, v5
	v_cvt_pk_bf16_f32 v5, v6, v7
	v_cvt_pk_bf16_f32 v6, v0, v1
	v_cvt_pk_bf16_f32 v7, v2, v3
	global_store_dwordx4 v[16:17], v[4:7], off offset:64 sc1
	s_cbranch_vccnz .LBB0_1752
	s_andn2_b64 vcc, exec, s[14:15]
	s_cbranch_vccnz .LBB0_1751
	s_barrier
	s_branch .LBB0_1751

; __device__ __forceinline__ float sq4(f32x4 v) { return (v[0] * v[0] + v[1] * v[1]) + (v[2] * v[2] + v[3] * v[3]); }
; __device__ __forceinline__ u32x4 pack8(f32x4 a, f32x4 b) { u32x4 w; w.x = cvt_pk_bf16(a[0], a[1]); w.y = cvt_pk_bf16(a[2], a[3]); w.z = cvt_pk_bf16(b[0], b[1]); w.w = cvt_pk_bf16(b[2], b[3]); return w; }
;     __device__ __forceinline__ void operator()(const f32x4 (&acc)[2][2][4][2], const Unit& u, int wr, int wc, int fr, int fq) const {
;         const int col0 = u.pn * 256 + 32 * wc + 8 * fq;
; #pragma unroll
;         for (int ai = 0; ai < 2; ++ai) {
;             u32x4 bs[4][2];
; #pragma unroll
;             for (int m = 0; m < 4; ++m)
; #pragma unroll
;                 for (int bj = 0; bj < 2; ++bj) bs[m][bj] = *(const u32x4*)(xb + (size_t)(u.pm * BM + ai * HALF + wr * 64 + m * 16 + fr) * 1024 + col0 + 128 * bj);
; #pragma unroll
;             for (int m = 0; m < 4; ++m) {
;                 const int row = u.pm * BM + ai * HALF + wr * 64 + m * 16 + fr;
;                 float q = 0.f;
; #pragma unroll
;                 for (int bj = 0; bj < 2; ++bj) {
;                     const size_t off = (size_t)row * 1024 + col0 + 128 * bj; const u32x4 w = bs[m][bj];
;                     const f32x4 b0 = (f32x4){__builtin_bit_cast(float, w.x << 16), __builtin_bit_cast(float, w.x & 0xffff0000u), __builtin_bit_cast(float, w.y << 16), __builtin_bit_cast(float, w.y & 0xffff0000u)};
;                     const f32x4 b1 = (f32x4){__builtin_bit_cast(float, w.z << 16), __builtin_bit_cast(float, w.z & 0xffff0000u), __builtin_bit_cast(float, w.w << 16), __builtin_bit_cast(float, w.w & 0xffff0000u)};
;                     const f32x4 v0 = acc[ai][bj][m][0] + b0, v1 = acc[ai][bj][m][1] + b1;
;                     if (last) { __builtin_nontemporal_store(v0, (f32x4*)(out + off)); __builtin_nontemporal_store(v1, (f32x4*)(out + off + 4)); }
;                     else { q += sq4(v0) + sq4(v1); *(u32x4*)(xb + off) = pack8(v0, v1); }
;                 }
;                 if (!last) { q += shx(q, 16); q += shx(q, 32); if (fq == 0) ss[(size_t)row * 16 + u.pn * 4 + wc] = q; }
.LBB0_1959:
	v_lshl_or_b32 v168, s10, 8, v188
	v_lshl_add_u32 v172, s38, 8, v186
	v_ashrrev_i32_e32 v169, 31, v168
	v_lshlrev_b64 v[202:203], 1, v[168:169]
	v_ashrrev_i32_e32 v173, 31, v172
	v_lshl_add_u64 v[170:171], s[16:17], 0, v[202:203]
	v_lshlrev_b64 v[204:205], 11, v[172:173]
	v_lshl_add_u64 v[128:129], v[170:171], 0, v[204:205]
	global_load_dwordx4 v[192:195], v[128:129], off
	global_load_dwordx4 v[196:199], v[128:129], off offset:256
	v_or_b32_e32 v182, 16, v172
	v_or_b32_e32 v178, 32, v172
	v_or_b32_e32 v174, 48, v172
	v_ashrrev_i32_e32 v183, 31, v182
	v_ashrrev_i32_e32 v179, 31, v178
	v_ashrrev_i32_e32 v175, 31, v174
	v_lshlrev_b64 v[184:185], 11, v[182:183]
	v_lshlrev_b64 v[180:181], 11, v[178:179]
	v_lshlrev_b64 v[176:177], 11, v[174:175]
	v_lshl_add_u64 v[128:129], v[170:171], 0, v[184:185]
	v_lshl_add_u64 v[130:131], v[170:171], 0, v[180:181]
	v_lshl_add_u64 v[206:207], v[170:171], 0, v[176:177]
	global_load_dwordx4 v[148:151], v[128:129], off
	global_load_dwordx4 v[144:147], v[128:129], off offset:256
	global_load_dwordx4 v[140:143], v[130:131], off
	global_load_dwordx4 v[136:139], v[130:131], off offset:256
	global_load_dwordx4 v[132:135], v[206:207], off
	s_nop 0
	global_load_dwordx4 v[128:131], v[206:207], off offset:256
	v_lshl_add_u64 v[204:205], s[16:17], 0, v[204:205]
	v_lshl_add_u64 v[202:203], v[204:205], 0, v[202:203]
	v_mov_b32_e32 v200, v201
	s_lshl_b32 s38, s10, 2
	s_ashr_i32 s39, s38, 31
	s_waitcnt vmcnt(0)
	v_lshlrev_b32_e32 v204, 16, v192
	v_and_b32_e32 v205, 0xffff0000, v192
	v_lshlrev_b32_e32 v192, 16, v193
	v_and_b32_e32 v193, 0xffff0000, v193
	v_lshlrev_b32_e32 v206, 16, v194
	v_and_b32_e32 v207, 0xffff0000, v194
	v_lshlrev_b32_e32 v194, 16, v195
	v_and_b32_e32 v195, 0xffff0000, v195
	v_lshlrev_b32_e32 v208, 16, v196
	v_and_b32_e32 v209, 0xffff0000, v196
	v_lshlrev_b32_e32 v196, 16, v197
	v_and_b32_e32 v197, 0xffff0000, v197
	v_lshlrev_b32_e32 v210, 16, v198
	v_and_b32_e32 v211, 0xffff0000, v198
	v_lshlrev_b32_e32 v198, 16, v199
	v_and_b32_e32 v199, 0xffff0000, v199
	v_pk_add_f32 v[126:127], v[126:127], v[192:193]
	v_pk_add_f32 v[124:125], v[124:125], v[204:205]
	v_pk_add_f32 v[122:123], v[122:123], v[194:195]
	v_pk_add_f32 v[120:121], v[120:121], v[206:207]
	v_pk_add_f32 v[118:119], v[118:119], v[196:197]
	v_pk_add_f32 v[116:117], v[116:117], v[208:209]
	v_pk_add_f32 v[192:193], v[114:115], v[198:199]
	v_pk_add_f32 v[194:195], v[112:113], v[210:211]
	v_mul_f32_e32 v196, v125, v125
	v_mul_f32_e32 v197, v127, v127
	v_mul_f32_e32 v198, v121, v121
	v_mul_f32_e32 v199, v123, v123
	v_cvt_pk_bf16_f32 v112, v124, v125
	v_cvt_pk_bf16_f32 v113, v126, v127
	v_cvt_pk_bf16_f32 v114, v120, v121
	v_cvt_pk_bf16_f32 v115, v122, v123
	v_mul_f32_e32 v121, v117, v117
	v_mul_f32_e32 v123, v119, v119
	v_mul_f32_e32 v125, v195, v195
	v_mul_f32_e32 v127, v193, v193
	v_fmac_f32_e32 v196, v124, v124
	v_fmac_f32_e32 v197, v126, v126
	v_fmac_f32_e32 v198, v120, v120
	v_fmac_f32_e32 v199, v122, v122
	v_fmac_f32_e32 v121, v116, v116
	v_fmac_f32_e32 v123, v118, v118
	v_fmac_f32_e32 v125, v194, v194
	v_fmac_f32_e32 v127, v192, v192
	global_store_dwordx4 v[202:203], v[112:115], off sc1
	s_nop 1
	v_cvt_pk_bf16_f32 v112, v116, v117
	v_cvt_pk_bf16_f32 v113, v118, v119
	v_cvt_pk_bf16_f32 v114, v194, v195
	v_add_f32_e32 v116, v196, v197
	v_add_f32_e32 v117, v198, v199
	v_add_f32_e32 v118, v121, v123
	v_add_f32_e32 v119, v125, v127
	v_cvt_pk_bf16_f32 v115, v192, v193
	global_store_dwordx4 v[202:203], v[112:115], off offset:256 sc1
	s_nop 1
	v_add_f32_e32 v112, v116, v117
	v_add_f32_e32 v113, v118, v119
	v_lshlrev_b32_e32 v114, 2, v200
	v_add_f32_e32 v112, v112, v113
	v_xor_b32_e32 v113, 64, v114
	v_mov_b32_e32 v113, v112
	s_nop 1
	v_permlane16_swap_b32_e32 v113, v112
	v_mov_b32_e32 v114, v201
	s_waitcnt lgkmcnt(0)
	v_add_f32_e32 v112, v112, v113
	v_lshlrev_b32_e32 v114, 2, v114
	v_xor_b32_e32 v113, 0x80, v114
	v_mov_b32_e32 v113, v112
	s_nop 1
	v_permlane32_swap_b32_e32 v113, v112
	s_and_saveexec_b64 s[40:41], s[6:7]
	s_cbranch_execz .LBB0_1961
	s_waitcnt lgkmcnt(0)
	v_add_f32_e32 v114, v112, v113
	v_lshlrev_b64 v[112:113], 6, v[172:173]
	v_lshl_add_u64 v[112:113], s[18:19], 0, v[112:113]
	v_lshl_add_u64 v[112:113], s[38:39], 2, v[112:113]
	s_lshl_b32 s10, s33, 2
	v_lshl_add_u64 v[112:113], v[112:113], 0, s[10:11]
	global_store_dword v[112:113], v114, off sc1
; __device__ __forceinline__ float sq4(f32x4 v) { return (v[0] * v[0] + v[1] * v[1]) + (v[2] * v[2] + v[3] * v[3]); }
; __device__ __forceinline__ u32x4 pack8(f32x4 a, f32x4 b) { u32x4 w; w.x = cvt_pk_bf16(a[0], a[1]); w.y = cvt_pk_bf16(a[2], a[3]); w.z = cvt_pk_bf16(b[0], b[1]); w.w = cvt_pk_bf16(b[2], b[3]); return w; }
;     __device__ __forceinline__ void operator()(const f32x4 (&acc)[2][2][4][2], const Unit& u, int wr, int wc, int fr, int fq) const {
;     ...
;             for (int m = 0; m < 4; ++m) {
;                 const int row = u.pm * BM + ai * HALF + wr * 64 + m * 16 + fr;
;                 float q = 0.f;
; #pragma unroll
;                 for (int bj = 0; bj < 2; ++bj) {
;                     const size_t off = (size_t)row * 1024 + col0 + 128 * bj; const u32x4 w = bs[m][bj];
;                     const f32x4 b0 = (f32x4){__builtin_bit_cast(float, w.x << 16), __builtin_bit_cast(float, w.x & 0xffff0000u), __builtin_bit_cast(float, w.y << 16), __builtin_bit_cast(float, w.y & 0xffff0000u)};
;                     const f32x4 b1 = (f32x4){__builtin_bit_cast(float, w.z << 16), __builtin_bit_cast(float, w.z & 0xffff0000u), __builtin_bit_cast(float, w.w << 16), __builtin_bit_cast(float, w.w & 0xffff0000u)};
;                     const f32x4 v0 = acc[ai][bj][m][0] + b0, v1 = acc[ai][bj][m][1] + b1;
;                     if (last) { __builtin_nontemporal_store(v0, (f32x4*)(out + off)); __builtin_nontemporal_store(v1, (f32x4*)(out + off + 4)); }
;                     else { q += sq4(v0) + sq4(v1); *(u32x4*)(xb + off) = pack8(v0, v1); }
;                 }
;                 if (!last) { q += shx(q, 16); q += shx(q, 32); if (fq == 0) ss[(size_t)row * 16 + u.pn * 4 + wc] = q; }
.LBB0_1961:
	s_or_b64 exec, exec, s[40:41]
	v_lshlrev_b32_e32 v112, 16, v148
	s_waitcnt lgkmcnt(0)
	v_and_b32_e32 v113, 0xffff0000, v148
	v_lshlrev_b32_e32 v114, 16, v149
	v_and_b32_e32 v115, 0xffff0000, v149
	v_lshlrev_b32_e32 v116, 16, v150
	v_and_b32_e32 v117, 0xffff0000, v150
	v_lshlrev_b32_e32 v118, 16, v151
	v_and_b32_e32 v119, 0xffff0000, v151
	v_pk_add_f32 v[110:111], v[110:111], v[114:115]
	v_pk_add_f32 v[108:109], v[108:109], v[112:113]
	v_pk_add_f32 v[112:113], v[106:107], v[118:119]
	v_pk_add_f32 v[106:107], v[104:105], v[116:117]
	v_mul_f32_e32 v104, v109, v109
	v_mul_f32_e32 v105, v111, v111
	v_fmac_f32_e32 v104, v108, v108
	v_fmac_f32_e32 v105, v110, v110
	v_add_f32_e32 v104, v104, v105
	v_mul_f32_e32 v105, v107, v107
	v_mul_f32_e32 v114, v113, v113
	v_fmac_f32_e32 v105, v106, v106
	v_fmac_f32_e32 v114, v112, v112
	v_add_f32_e32 v105, v105, v114
	v_add_f32_e32 v114, v104, v105
	v_cvt_pk_bf16_f32 v104, v108, v109
	v_lshl_add_u64 v[108:109], s[16:17], 0, v[184:185]
	v_cvt_pk_bf16_f32 v105, v110, v111
	v_cvt_pk_bf16_f32 v106, v106, v107
	v_cvt_pk_bf16_f32 v107, v112, v113
	v_lshl_add_u64 v[108:109], v[168:169], 1, v[108:109]
	global_store_dwordx4 v[108:109], v[104:107], off sc1
	v_lshlrev_b32_e32 v110, 16, v146
	v_and_b32_e32 v111, 0xffff0000, v146
	v_lshlrev_b32_e32 v104, 16, v144
	v_and_b32_e32 v105, 0xffff0000, v144
	v_lshlrev_b32_e32 v106, 16, v145
	v_and_b32_e32 v107, 0xffff0000, v145
	v_lshlrev_b32_e32 v112, 16, v147
	v_and_b32_e32 v113, 0xffff0000, v147
	v_pk_add_f32 v[102:103], v[102:103], v[106:107]
	v_pk_add_f32 v[100:101], v[100:101], v[104:105]
	v_pk_add_f32 v[104:105], v[98:99], v[112:113]
	v_pk_add_f32 v[98:99], v[96:97], v[110:111]
	v_mul_f32_e32 v96, v101, v101
	v_mul_f32_e32 v97, v103, v103
	v_fmac_f32_e32 v96, v100, v100
	v_fmac_f32_e32 v97, v102, v102
	v_add_f32_e32 v96, v96, v97
	v_mul_f32_e32 v97, v99, v99
	v_mul_f32_e32 v106, v105, v105
	v_fmac_f32_e32 v97, v98, v98
	v_fmac_f32_e32 v106, v104, v104
	v_add_f32_e32 v97, v97, v106
	v_add_f32_e32 v96, v96, v97
	v_add_f32_e32 v106, v114, v96
	v_cvt_pk_bf16_f32 v96, v100, v101
	v_cvt_pk_bf16_f32 v97, v102, v103
	v_cvt_pk_bf16_f32 v98, v98, v99
	v_cvt_pk_bf16_f32 v99, v104, v105
	global_store_dwordx4 v[108:109], v[96:99], off offset:256 sc1
	s_nop 1
	v_mov_b32_e32 v96, v201
	v_mov_b32_e32 v97, v201
	v_lshlrev_b32_e32 v96, 2, v96
	v_xor_b32_e32 v96, 64, v96
	v_mov_b32_e32 v96, v106
	s_nop 1
	v_permlane16_swap_b32_e32 v96, v106
	s_waitcnt lgkmcnt(0)
	v_add_f32_e32 v96, v106, v96
	v_lshlrev_b32_e32 v97, 2, v97
	v_xor_b32_e32 v97, 0x80, v97
	v_mov_b32_e32 v97, v96
	s_nop 1
	v_permlane32_swap_b32_e32 v97, v96
	s_and_saveexec_b64 s[40:41], s[6:7]
	s_cbranch_execz .LBB0_1963
	s_waitcnt lgkmcnt(0)
	v_add_f32_e32 v98, v96, v97
	v_lshlrev_b64 v[96:97], 6, v[182:183]
	v_lshl_add_u64 v[96:97], s[18:19], 0, v[96:97]
	v_lshl_add_u64 v[96:97], s[38:39], 2, v[96:97]
	s_lshl_b32 s10, s33, 2
	v_lshl_add_u64 v[96:97], v[96:97], 0, s[10:11]
	global_store_dword v[96:97], v98, off sc1
.LBB0_1963:
	s_or_b64 exec, exec, s[40:41]
	v_lshlrev_b32_e32 v96, 16, v140
	s_waitcnt lgkmcnt(0)
	v_and_b32_e32 v97, 0xffff0000, v140
	v_lshlrev_b32_e32 v98, 16, v141
	v_and_b32_e32 v99, 0xffff0000, v141
	v_lshlrev_b32_e32 v100, 16, v142
	v_and_b32_e32 v101, 0xffff0000, v142
	v_lshlrev_b32_e32 v102, 16, v143
	v_and_b32_e32 v103, 0xffff0000, v143
	v_pk_add_f32 v[94:95], v[94:95], v[98:99]
	v_pk_add_f32 v[92:93], v[92:93], v[96:97]
	v_pk_add_f32 v[96:97], v[90:91], v[102:103]
	v_pk_add_f32 v[90:91], v[88:89], v[100:101]
	v_mul_f32_e32 v88, v93, v93
	v_mul_f32_e32 v89, v95, v95
	v_fmac_f32_e32 v88, v92, v92
	v_fmac_f32_e32 v89, v94, v94
	v_add_f32_e32 v88, v88, v89
	v_mul_f32_e32 v89, v91, v91
	v_mul_f32_e32 v98, v97, v97
	v_fmac_f32_e32 v89, v90, v90
	v_fmac_f32_e32 v98, v96, v96
	v_add_f32_e32 v89, v89, v98
	v_add_f32_e32 v98, v88, v89
	v_cvt_pk_bf16_f32 v88, v92, v93
	v_lshl_add_u64 v[92:93], s[16:17], 0, v[180:181]
	v_cvt_pk_bf16_f32 v89, v94, v95
	v_cvt_pk_bf16_f32 v90, v90, v91
	v_cvt_pk_bf16_f32 v91, v96, v97
	v_lshl_add_u64 v[92:93], v[168:169], 1, v[92:93]
	global_store_dwordx4 v[92:93], v[88:91], off sc1
	v_lshlrev_b32_e32 v94, 16, v138
	v_and_b32_e32 v95, 0xffff0000, v138
	v_lshlrev_b32_e32 v88, 16, v136
	v_and_b32_e32 v89, 0xffff0000, v136
	v_lshlrev_b32_e32 v90, 16, v137
	v_and_b32_e32 v91, 0xffff0000, v137
	v_lshlrev_b32_e32 v96, 16, v139
	v_and_b32_e32 v97, 0xffff0000, v139
	v_pk_add_f32 v[86:87], v[86:87], v[90:91]
	v_pk_add_f32 v[84:85], v[84:85], v[88:89]
	v_pk_add_f32 v[88:89], v[82:83], v[96:97]
	v_pk_add_f32 v[82:83], v[80:81], v[94:95]
	v_mul_f32_e32 v80, v85, v85
	v_mul_f32_e32 v81, v87, v87
	v_fmac_f32_e32 v80, v84, v84
	v_fmac_f32_e32 v81, v86, v86
	v_add_f32_e32 v80, v80, v81
	v_mul_f32_e32 v81, v83, v83
	v_mul_f32_e32 v90, v89, v89
	v_fmac_f32_e32 v81, v82, v82
	v_fmac_f32_e32 v90, v88, v88
	v_add_f32_e32 v81, v81, v90
	v_add_f32_e32 v80, v80, v81
	v_add_f32_e32 v90, v98, v80
	v_cvt_pk_bf16_f32 v80, v84, v85
	v_cvt_pk_bf16_f32 v81, v86, v87
	v_cvt_pk_bf16_f32 v82, v82, v83
	v_cvt_pk_bf16_f32 v83, v88, v89
	global_store_dwordx4 v[92:93], v[80:83], off offset:256 sc1
	s_nop 1
	v_mov_b32_e32 v80, v201
	v_mov_b32_e32 v81, v201
	v_lshlrev_b32_e32 v80, 2, v80
	v_xor_b32_e32 v80, 64, v80
	v_mov_b32_e32 v80, v90
	s_nop 1
	v_permlane16_swap_b32_e32 v80, v90
	s_waitcnt lgkmcnt(0)
	v_add_f32_e32 v80, v90, v80
	v_lshlrev_b32_e32 v81, 2, v81
	v_xor_b32_e32 v81, 0x80, v81
	v_mov_b32_e32 v81, v80
	s_nop 1
	v_permlane32_swap_b32_e32 v81, v80
	s_and_saveexec_b64 s[40:41], s[6:7]
	s_cbranch_execz .LBB0_1965
	s_waitcnt lgkmcnt(0)
	v_add_f32_e32 v82, v80, v81
	v_lshlrev_b64 v[80:81], 6, v[178:179]
	v_lshl_add_u64 v[80:81], s[18:19], 0, v[80:81]
	v_lshl_add_u64 v[80:81], s[38:39], 2, v[80:81]
	s_lshl_b32 s10, s33, 2
	v_lshl_add_u64 v[80:81], v[80:81], 0, s[10:11]
	global_store_dword v[80:81], v82, off sc1
; __device__ __forceinline__ float sq4(f32x4 v) { return (v[0] * v[0] + v[1] * v[1]) + (v[2] * v[2] + v[3] * v[3]); }
; __device__ __forceinline__ u32x4 pack8(f32x4 a, f32x4 b) { u32x4 w; w.x = cvt_pk_bf16(a[0], a[1]); w.y = cvt_pk_bf16(a[2], a[3]); w.z = cvt_pk_bf16(b[0], b[1]); w.w = cvt_pk_bf16(b[2], b[3]); return w; }
;     __device__ __forceinline__ void operator()(const f32x4 (&acc)[2][2][4][2], const Unit& u, int wr, int wc, int fr, int fq) const {
;         const int col0 = u.pn * 256 + 32 * wc + 8 * fq;
; #pragma unroll
;         for (int ai = 0; ai < 2; ++ai) {
;             u32x4 bs[4][2];
; #pragma unroll
;             for (int m = 0; m < 4; ++m)
; #pragma unroll
;                 for (int bj = 0; bj < 2; ++bj) bs[m][bj] = *(const u32x4*)(xb + (size_t)(u.pm * BM + ai * HALF + wr * 64 + m * 16 + fr) * 1024 + col0 + 128 * bj);
; #pragma unroll
;             for (int m = 0; m < 4; ++m) {
;                 const int row = u.pm * BM + ai * HALF + wr * 64 + m * 16 + fr;
;                 float q = 0.f;
; #pragma unroll
;                 for (int bj = 0; bj < 2; ++bj) {
;                     const size_t off = (size_t)row * 1024 + col0 + 128 * bj; const u32x4 w = bs[m][bj];
;                     const f32x4 b0 = (f32x4){__builtin_bit_cast(float, w.x << 16), __builtin_bit_cast(float, w.x & 0xffff0000u), __builtin_bit_cast(float, w.y << 16), __builtin_bit_cast(float, w.y & 0xffff0000u)};
;                     const f32x4 b1 = (f32x4){__builtin_bit_cast(float, w.z << 16), __builtin_bit_cast(float, w.z & 0xffff0000u), __builtin_bit_cast(float, w.w << 16), __builtin_bit_cast(float, w.w & 0xffff0000u)};
;                     const f32x4 v0 = acc[ai][bj][m][0] + b0, v1 = acc[ai][bj][m][1] + b1;
;                     if (last) { __builtin_nontemporal_store(v0, (f32x4*)(out + off)); __builtin_nontemporal_store(v1, (f32x4*)(out + off + 4)); }
;                     else { q += sq4(v0) + sq4(v1); *(u32x4*)(xb + off) = pack8(v0, v1); }
;                 }
;                 if (!last) { q += shx(q, 16); q += shx(q, 32); if (fq == 0) ss[(size_t)row * 16 + u.pn * 4 + wc] = q; }
;             }
.LBB0_1965:
	s_or_b64 exec, exec, s[40:41]
	v_lshlrev_b32_e32 v80, 16, v132
	s_waitcnt lgkmcnt(0)
	v_and_b32_e32 v81, 0xffff0000, v132
	v_lshlrev_b32_e32 v82, 16, v133
	v_and_b32_e32 v83, 0xffff0000, v133
	v_lshlrev_b32_e32 v84, 16, v134
	v_and_b32_e32 v85, 0xffff0000, v134
	v_lshlrev_b32_e32 v86, 16, v135
	v_and_b32_e32 v87, 0xffff0000, v135
	v_pk_add_f32 v[78:79], v[78:79], v[82:83]
	v_pk_add_f32 v[76:77], v[76:77], v[80:81]
	v_pk_add_f32 v[80:81], v[74:75], v[86:87]
	v_pk_add_f32 v[74:75], v[72:73], v[84:85]
	v_mul_f32_e32 v72, v77, v77
	v_mul_f32_e32 v73, v79, v79
	v_fmac_f32_e32 v72, v76, v76
	v_fmac_f32_e32 v73, v78, v78
	v_add_f32_e32 v72, v72, v73
	v_mul_f32_e32 v73, v75, v75
	v_mul_f32_e32 v82, v81, v81
	v_fmac_f32_e32 v73, v74, v74
	v_fmac_f32_e32 v82, v80, v80
	v_add_f32_e32 v73, v73, v82
	v_add_f32_e32 v82, v72, v73
	v_cvt_pk_bf16_f32 v72, v76, v77
	v_lshl_add_u64 v[76:77], s[16:17], 0, v[176:177]
	v_cvt_pk_bf16_f32 v73, v78, v79
	v_cvt_pk_bf16_f32 v74, v74, v75
	v_cvt_pk_bf16_f32 v75, v80, v81
	v_lshl_add_u64 v[76:77], v[168:169], 1, v[76:77]
	global_store_dwordx4 v[76:77], v[72:75], off sc1
	v_lshlrev_b32_e32 v78, 16, v130
	v_and_b32_e32 v79, 0xffff0000, v130
	v_lshlrev_b32_e32 v72, 16, v128
	v_and_b32_e32 v73, 0xffff0000, v128
	v_lshlrev_b32_e32 v74, 16, v129
	v_and_b32_e32 v75, 0xffff0000, v129
	v_lshlrev_b32_e32 v80, 16, v131
	v_and_b32_e32 v81, 0xffff0000, v131
	v_pk_add_f32 v[70:71], v[70:71], v[74:75]
	v_pk_add_f32 v[68:69], v[68:69], v[72:73]
	v_pk_add_f32 v[72:73], v[66:67], v[80:81]
	v_pk_add_f32 v[66:67], v[64:65], v[78:79]
	v_mul_f32_e32 v64, v69, v69
	v_mul_f32_e32 v65, v71, v71
	v_fmac_f32_e32 v64, v68, v68
	v_fmac_f32_e32 v65, v70, v70
	v_add_f32_e32 v64, v64, v65
	v_mul_f32_e32 v65, v67, v67
	v_mul_f32_e32 v74, v73, v73
	v_fmac_f32_e32 v65, v66, v66
	v_fmac_f32_e32 v74, v72, v72
	v_add_f32_e32 v65, v65, v74
	v_add_f32_e32 v64, v64, v65
	v_add_f32_e32 v74, v82, v64
	v_cvt_pk_bf16_f32 v64, v68, v69
	v_cvt_pk_bf16_f32 v65, v70, v71
	v_cvt_pk_bf16_f32 v66, v66, v67
	v_cvt_pk_bf16_f32 v67, v72, v73
	global_store_dwordx4 v[76:77], v[64:67], off offset:256 sc1
	s_nop 1
	v_mov_b32_e32 v64, v201
	v_mov_b32_e32 v65, v201
	v_lshlrev_b32_e32 v64, 2, v64
	v_xor_b32_e32 v64, 64, v64
	v_mov_b32_e32 v64, v74
	s_nop 1
	v_permlane16_swap_b32_e32 v64, v74
	s_waitcnt lgkmcnt(0)
	v_add_f32_e32 v64, v74, v64
	v_lshlrev_b32_e32 v65, 2, v65
	v_xor_b32_e32 v65, 0x80, v65
	v_mov_b32_e32 v65, v64
	s_nop 1
	v_permlane32_swap_b32_e32 v65, v64
	s_and_saveexec_b64 s[40:41], s[6:7]
	s_cbranch_execz .LBB0_1967
	s_waitcnt lgkmcnt(0)
	v_add_f32_e32 v66, v64, v65
	v_lshlrev_b64 v[64:65], 6, v[174:175]
	v_lshl_add_u64 v[64:65], s[18:19], 0, v[64:65]
	v_lshl_add_u64 v[64:65], s[38:39], 2, v[64:65]
	s_lshl_b32 s10, s33, 2
	v_lshl_add_u64 v[64:65], v[64:65], 0, s[10:11]
	global_store_dword v[64:65], v66, off sc1
.LBB0_1967:
	s_or_b64 exec, exec, s[40:41]
	v_add_u32_e32 v100, 0x80, v172
	v_ashrrev_i32_e32 v101, 31, v100
	v_lshlrev_b64 v[110:111], 11, v[100:101]
	s_waitcnt lgkmcnt(0)
	v_lshl_add_u64 v[64:65], v[170:171], 0, v[110:111]
	global_load_dwordx4 v[102:105], v[64:65], off
	global_load_dwordx4 v[106:109], v[64:65], off offset:256
	v_add_u32_e32 v96, 0x90, v172
	v_add_u32_e32 v92, 0xa0, v172
	v_add_u32_e32 v88, 0xb0, v172
	v_ashrrev_i32_e32 v97, 31, v96
	v_ashrrev_i32_e32 v93, 31, v92
	v_ashrrev_i32_e32 v89, 31, v88
	v_lshlrev_b64 v[98:99], 11, v[96:97]
	v_lshlrev_b64 v[94:95], 11, v[92:93]
	v_lshlrev_b64 v[90:91], 11, v[88:89]
	v_lshl_add_u64 v[64:65], v[170:171], 0, v[98:99]
	v_lshl_add_u64 v[66:67], v[170:171], 0, v[94:95]
	v_lshl_add_u64 v[112:113], v[170:171], 0, v[90:91]
	global_load_dwordx4 v[84:87], v[64:65], off
	global_load_dwordx4 v[80:83], v[64:65], off offset:256
	global_load_dwordx4 v[76:79], v[66:67], off
	global_load_dwordx4 v[72:75], v[66:67], off offset:256
	global_load_dwordx4 v[68:71], v[112:113], off
	s_nop 0
	global_load_dwordx4 v[64:67], v[112:113], off offset:256
	v_lshl_add_u64 v[110:111], s[16:17], 0, v[110:111]
	v_lshl_add_u64 v[110:111], v[168:169], 1, v[110:111]
	v_mov_b32_e32 v120, v201
	s_waitcnt vmcnt(7)
	v_lshlrev_b32_e32 v112, 16, v102
	v_and_b32_e32 v113, 0xffff0000, v102
	v_lshlrev_b32_e32 v102, 16, v103
	v_and_b32_e32 v103, 0xffff0000, v103
	v_lshlrev_b32_e32 v114, 16, v104
	v_and_b32_e32 v115, 0xffff0000, v104
	v_lshlrev_b32_e32 v104, 16, v105
	v_and_b32_e32 v105, 0xffff0000, v105
	s_waitcnt vmcnt(6)
	v_lshlrev_b32_e32 v116, 16, v106
	v_and_b32_e32 v117, 0xffff0000, v106
	v_lshlrev_b32_e32 v106, 16, v107
	v_and_b32_e32 v107, 0xffff0000, v107
	v_lshlrev_b32_e32 v118, 16, v108
	v_and_b32_e32 v119, 0xffff0000, v108
	v_lshlrev_b32_e32 v108, 16, v109
	v_and_b32_e32 v109, 0xffff0000, v109
	v_pk_add_f32 v[62:63], v[62:63], v[102:103]
	v_pk_add_f32 v[60:61], v[60:61], v[112:113]
	v_pk_add_f32 v[58:59], v[58:59], v[104:105]
	v_pk_add_f32 v[56:57], v[56:57], v[114:115]
	v_pk_add_f32 v[54:55], v[54:55], v[106:107]
	v_pk_add_f32 v[52:53], v[52:53], v[116:117]
	v_pk_add_f32 v[102:103], v[50:51], v[108:109]
	v_pk_add_f32 v[104:105], v[48:49], v[118:119]
	v_mul_f32_e32 v106, v61, v61
	v_mul_f32_e32 v107, v63, v63
	v_mul_f32_e32 v108, v57, v57
	v_mul_f32_e32 v109, v59, v59
	v_cvt_pk_bf16_f32 v48, v60, v61
	v_cvt_pk_bf16_f32 v49, v62, v63
	v_cvt_pk_bf16_f32 v50, v56, v57
	v_cvt_pk_bf16_f32 v51, v58, v59
	v_mul_f32_e32 v57, v53, v53
	v_mul_f32_e32 v59, v55, v55
	v_mul_f32_e32 v61, v105, v105
	v_mul_f32_e32 v63, v103, v103
	v_fmac_f32_e32 v106, v60, v60
	v_fmac_f32_e32 v107, v62, v62
	v_fmac_f32_e32 v108, v56, v56
	v_fmac_f32_e32 v109, v58, v58
	v_fmac_f32_e32 v57, v52, v52
	v_fmac_f32_e32 v59, v54, v54
	v_fmac_f32_e32 v61, v104, v104
	v_fmac_f32_e32 v63, v102, v102
	global_store_dwordx4 v[110:111], v[48:51], off sc1
	s_nop 1
	v_cvt_pk_bf16_f32 v48, v52, v53
	v_cvt_pk_bf16_f32 v49, v54, v55
	v_cvt_pk_bf16_f32 v50, v104, v105
	v_add_f32_e32 v52, v106, v107
	v_add_f32_e32 v53, v108, v109
	v_add_f32_e32 v54, v57, v59
	v_add_f32_e32 v55, v61, v63
	v_cvt_pk_bf16_f32 v51, v102, v103
	global_store_dwordx4 v[110:111], v[48:51], off offset:256 sc1
	s_nop 1
	v_add_f32_e32 v48, v52, v53
	v_add_f32_e32 v49, v54, v55
	v_lshlrev_b32_e32 v50, 2, v120
	v_add_f32_e32 v48, v48, v49
	v_xor_b32_e32 v49, 64, v50
	v_mov_b32_e32 v49, v48
	s_nop 1
	v_permlane16_swap_b32_e32 v49, v48
	v_mov_b32_e32 v50, v201
	s_waitcnt lgkmcnt(0)
	v_add_f32_e32 v48, v48, v49
	v_lshlrev_b32_e32 v50, 2, v50
	v_xor_b32_e32 v49, 0x80, v50
	v_mov_b32_e32 v49, v48
	s_nop 1
	v_permlane32_swap_b32_e32 v49, v48
	s_and_saveexec_b64 s[40:41], s[6:7]
	s_cbranch_execz .LBB0_1969
	s_waitcnt lgkmcnt(0)
	v_add_f32_e32 v50, v48, v49
	v_lshlrev_b64 v[48:49], 6, v[100:101]
	v_lshl_add_u64 v[48:49], s[18:19], 0, v[48:49]
	v_lshl_add_u64 v[48:49], s[38:39], 2, v[48:49]
	s_lshl_b32 s10, s33, 2
	v_lshl_add_u64 v[48:49], v[48:49], 0, s[10:11]
	global_store_dword v[48:49], v50, off sc1
; __device__ __forceinline__ float sq4(f32x4 v) { return (v[0] * v[0] + v[1] * v[1]) + (v[2] * v[2] + v[3] * v[3]); }
; __device__ __forceinline__ u32x4 pack8(f32x4 a, f32x4 b) { u32x4 w; w.x = cvt_pk_bf16(a[0], a[1]); w.y = cvt_pk_bf16(a[2], a[3]); w.z = cvt_pk_bf16(b[0], b[1]); w.w = cvt_pk_bf16(b[2], b[3]); return w; }
;     __device__ __forceinline__ void operator()(const f32x4 (&acc)[2][2][4][2], const Unit& u, int wr, int wc, int fr, int fq) const {
;     ...
;             for (int m = 0; m < 4; ++m) {
;                 const int row = u.pm * BM + ai * HALF + wr * 64 + m * 16 + fr;
;                 float q = 0.f;
; #pragma unroll
;                 for (int bj = 0; bj < 2; ++bj) {
;                     const size_t off = (size_t)row * 1024 + col0 + 128 * bj; const u32x4 w = bs[m][bj];
;                     const f32x4 b0 = (f32x4){__builtin_bit_cast(float, w.x << 16), __builtin_bit_cast(float, w.x & 0xffff0000u), __builtin_bit_cast(float, w.y << 16), __builtin_bit_cast(float, w.y & 0xffff0000u)};
;                     const f32x4 b1 = (f32x4){__builtin_bit_cast(float, w.z << 16), __builtin_bit_cast(float, w.z & 0xffff0000u), __builtin_bit_cast(float, w.w << 16), __builtin_bit_cast(float, w.w & 0xffff0000u)};
;                     const f32x4 v0 = acc[ai][bj][m][0] + b0, v1 = acc[ai][bj][m][1] + b1;
;                     if (last) { __builtin_nontemporal_store(v0, (f32x4*)(out + off)); __builtin_nontemporal_store(v1, (f32x4*)(out + off + 4)); }
;                     else { q += sq4(v0) + sq4(v1); *(u32x4*)(xb + off) = pack8(v0, v1); }
;                 }
;                 if (!last) { q += shx(q, 16); q += shx(q, 32); if (fq == 0) ss[(size_t)row * 16 + u.pn * 4 + wc] = q; }
.LBB0_1969:
	s_or_b64 exec, exec, s[40:41]
	s_waitcnt vmcnt(7)
	v_lshlrev_b32_e32 v48, 16, v84
	s_waitcnt lgkmcnt(0)
	v_and_b32_e32 v49, 0xffff0000, v84
	v_lshlrev_b32_e32 v50, 16, v85
	v_and_b32_e32 v51, 0xffff0000, v85
	v_lshlrev_b32_e32 v52, 16, v86
	v_and_b32_e32 v53, 0xffff0000, v86
	v_lshlrev_b32_e32 v54, 16, v87
	v_and_b32_e32 v55, 0xffff0000, v87
	v_pk_add_f32 v[46:47], v[46:47], v[50:51]
	v_pk_add_f32 v[44:45], v[44:45], v[48:49]
	v_pk_add_f32 v[48:49], v[42:43], v[54:55]
	v_pk_add_f32 v[42:43], v[40:41], v[52:53]
	v_mul_f32_e32 v40, v45, v45
	v_mul_f32_e32 v41, v47, v47
	v_fmac_f32_e32 v40, v44, v44
	v_fmac_f32_e32 v41, v46, v46
	v_add_f32_e32 v40, v40, v41
	v_mul_f32_e32 v41, v43, v43
	v_mul_f32_e32 v50, v49, v49
	v_fmac_f32_e32 v41, v42, v42
	v_fmac_f32_e32 v50, v48, v48
	v_add_f32_e32 v41, v41, v50
	v_add_f32_e32 v50, v40, v41
	v_cvt_pk_bf16_f32 v40, v44, v45
	v_lshl_add_u64 v[44:45], s[16:17], 0, v[98:99]
	v_cvt_pk_bf16_f32 v41, v46, v47
	v_cvt_pk_bf16_f32 v42, v42, v43
	v_cvt_pk_bf16_f32 v43, v48, v49
	v_lshl_add_u64 v[44:45], v[168:169], 1, v[44:45]
	global_store_dwordx4 v[44:45], v[40:43], off sc1
	s_waitcnt vmcnt(7)
	v_lshlrev_b32_e32 v46, 16, v82
	v_and_b32_e32 v47, 0xffff0000, v82
	v_lshlrev_b32_e32 v40, 16, v80
	v_and_b32_e32 v41, 0xffff0000, v80
	v_lshlrev_b32_e32 v42, 16, v81
	v_and_b32_e32 v43, 0xffff0000, v81
	v_lshlrev_b32_e32 v48, 16, v83
	v_and_b32_e32 v49, 0xffff0000, v83
	v_pk_add_f32 v[38:39], v[38:39], v[42:43]
	v_pk_add_f32 v[36:37], v[36:37], v[40:41]
	v_pk_add_f32 v[40:41], v[34:35], v[48:49]
	v_pk_add_f32 v[34:35], v[32:33], v[46:47]
	v_mul_f32_e32 v32, v37, v37
	v_mul_f32_e32 v33, v39, v39
	v_fmac_f32_e32 v32, v36, v36
	v_fmac_f32_e32 v33, v38, v38
	v_add_f32_e32 v32, v32, v33
	v_mul_f32_e32 v33, v35, v35
	v_mul_f32_e32 v42, v41, v41
	v_fmac_f32_e32 v33, v34, v34
	v_fmac_f32_e32 v42, v40, v40
	v_add_f32_e32 v33, v33, v42
	v_add_f32_e32 v32, v32, v33
	v_add_f32_e32 v42, v50, v32
	v_cvt_pk_bf16_f32 v32, v36, v37
	v_cvt_pk_bf16_f32 v33, v38, v39
	v_cvt_pk_bf16_f32 v34, v34, v35
	v_cvt_pk_bf16_f32 v35, v40, v41
	global_store_dwordx4 v[44:45], v[32:35], off offset:256 sc1
	s_nop 1
	v_mov_b32_e32 v32, v201
	v_mov_b32_e32 v33, v201
	v_lshlrev_b32_e32 v32, 2, v32
	v_xor_b32_e32 v32, 64, v32
	v_mov_b32_e32 v32, v42
	s_nop 1
	v_permlane16_swap_b32_e32 v32, v42
	s_waitcnt lgkmcnt(0)
	v_add_f32_e32 v32, v42, v32
	v_lshlrev_b32_e32 v33, 2, v33
	v_xor_b32_e32 v33, 0x80, v33
	v_mov_b32_e32 v33, v32
	s_nop 1
	v_permlane32_swap_b32_e32 v33, v32
	s_and_saveexec_b64 s[40:41], s[6:7]
	s_cbranch_execz .LBB0_1971
	s_waitcnt lgkmcnt(0)
	v_add_f32_e32 v34, v32, v33
	v_lshlrev_b64 v[32:33], 6, v[96:97]
	v_lshl_add_u64 v[32:33], s[18:19], 0, v[32:33]
	v_lshl_add_u64 v[32:33], s[38:39], 2, v[32:33]
	s_lshl_b32 s10, s33, 2
	v_lshl_add_u64 v[32:33], v[32:33], 0, s[10:11]
	global_store_dword v[32:33], v34, off sc1
; __device__ __forceinline__ float sq4(f32x4 v) { return (v[0] * v[0] + v[1] * v[1]) + (v[2] * v[2] + v[3] * v[3]); }
; __device__ __forceinline__ u32x4 pack8(f32x4 a, f32x4 b) { u32x4 w; w.x = cvt_pk_bf16(a[0], a[1]); w.y = cvt_pk_bf16(a[2], a[3]); w.z = cvt_pk_bf16(b[0], b[1]); w.w = cvt_pk_bf16(b[2], b[3]); return w; }
;     __device__ __forceinline__ void operator()(const f32x4 (&acc)[2][2][4][2], const Unit& u, int wr, int wc, int fr, int fq) const {
;     ...
;             for (int m = 0; m < 4; ++m) {
;                 const int row = u.pm * BM + ai * HALF + wr * 64 + m * 16 + fr;
;                 float q = 0.f;
; #pragma unroll
;                 for (int bj = 0; bj < 2; ++bj) {
;                     const size_t off = (size_t)row * 1024 + col0 + 128 * bj; const u32x4 w = bs[m][bj];
;                     const f32x4 b0 = (f32x4){__builtin_bit_cast(float, w.x << 16), __builtin_bit_cast(float, w.x & 0xffff0000u), __builtin_bit_cast(float, w.y << 16), __builtin_bit_cast(float, w.y & 0xffff0000u)};
;                     const f32x4 b1 = (f32x4){__builtin_bit_cast(float, w.z << 16), __builtin_bit_cast(float, w.z & 0xffff0000u), __builtin_bit_cast(float, w.w << 16), __builtin_bit_cast(float, w.w & 0xffff0000u)};
;                     const f32x4 v0 = acc[ai][bj][m][0] + b0, v1 = acc[ai][bj][m][1] + b1;
;                     if (last) { __builtin_nontemporal_store(v0, (f32x4*)(out + off)); __builtin_nontemporal_store(v1, (f32x4*)(out + off + 4)); }
;                     else { q += sq4(v0) + sq4(v1); *(u32x4*)(xb + off) = pack8(v0, v1); }
;                 }
;                 if (!last) { q += shx(q, 16); q += shx(q, 32); if (fq == 0) ss[(size_t)row * 16 + u.pn * 4 + wc] = q; }
.LBB0_1971:
	s_or_b64 exec, exec, s[40:41]
	s_waitcnt vmcnt(7)
	v_lshlrev_b32_e32 v32, 16, v76
	s_waitcnt lgkmcnt(0)
	v_and_b32_e32 v33, 0xffff0000, v76
	v_lshlrev_b32_e32 v34, 16, v77
	v_and_b32_e32 v35, 0xffff0000, v77
	v_lshlrev_b32_e32 v36, 16, v78
	v_and_b32_e32 v37, 0xffff0000, v78
	v_lshlrev_b32_e32 v38, 16, v79
	v_and_b32_e32 v39, 0xffff0000, v79
	v_pk_add_f32 v[30:31], v[30:31], v[34:35]
	v_pk_add_f32 v[28:29], v[28:29], v[32:33]
	v_pk_add_f32 v[32:33], v[26:27], v[38:39]
	v_pk_add_f32 v[26:27], v[24:25], v[36:37]
	v_mul_f32_e32 v24, v29, v29
	v_mul_f32_e32 v25, v31, v31
	v_fmac_f32_e32 v24, v28, v28
	v_fmac_f32_e32 v25, v30, v30
	v_add_f32_e32 v24, v24, v25
	v_mul_f32_e32 v25, v27, v27
	v_mul_f32_e32 v34, v33, v33
	v_fmac_f32_e32 v25, v26, v26
	v_fmac_f32_e32 v34, v32, v32
	v_add_f32_e32 v25, v25, v34
	v_add_f32_e32 v34, v24, v25
	v_cvt_pk_bf16_f32 v24, v28, v29
	v_lshl_add_u64 v[28:29], s[16:17], 0, v[94:95]
	v_cvt_pk_bf16_f32 v25, v30, v31
	v_cvt_pk_bf16_f32 v26, v26, v27
	v_cvt_pk_bf16_f32 v27, v32, v33
	v_lshl_add_u64 v[28:29], v[168:169], 1, v[28:29]
	global_store_dwordx4 v[28:29], v[24:27], off sc1
	s_waitcnt vmcnt(7)
	v_lshlrev_b32_e32 v30, 16, v74
	v_and_b32_e32 v31, 0xffff0000, v74
	v_lshlrev_b32_e32 v24, 16, v72
	v_and_b32_e32 v25, 0xffff0000, v72
	v_lshlrev_b32_e32 v26, 16, v73
	v_and_b32_e32 v27, 0xffff0000, v73
	v_lshlrev_b32_e32 v32, 16, v75
	v_and_b32_e32 v33, 0xffff0000, v75
	v_pk_add_f32 v[22:23], v[22:23], v[26:27]
	v_pk_add_f32 v[20:21], v[20:21], v[24:25]
	v_pk_add_f32 v[24:25], v[18:19], v[32:33]
	v_pk_add_f32 v[18:19], v[16:17], v[30:31]
	v_mul_f32_e32 v16, v21, v21
	v_mul_f32_e32 v17, v23, v23
	v_fmac_f32_e32 v16, v20, v20
	v_fmac_f32_e32 v17, v22, v22
	v_add_f32_e32 v16, v16, v17
	v_mul_f32_e32 v17, v19, v19
	v_mul_f32_e32 v26, v25, v25
	v_fmac_f32_e32 v17, v18, v18
	v_fmac_f32_e32 v26, v24, v24
	v_add_f32_e32 v17, v17, v26
	v_add_f32_e32 v16, v16, v17
	v_add_f32_e32 v26, v34, v16
	v_cvt_pk_bf16_f32 v16, v20, v21
	v_cvt_pk_bf16_f32 v17, v22, v23
	v_cvt_pk_bf16_f32 v18, v18, v19
	v_cvt_pk_bf16_f32 v19, v24, v25
	global_store_dwordx4 v[28:29], v[16:19], off offset:256 sc1
	s_nop 1
	v_mov_b32_e32 v16, v201
	v_mov_b32_e32 v17, v201
	v_lshlrev_b32_e32 v16, 2, v16
	v_xor_b32_e32 v16, 64, v16
	v_mov_b32_e32 v16, v26
	s_nop 1
	v_permlane16_swap_b32_e32 v16, v26
	s_waitcnt lgkmcnt(0)
	v_add_f32_e32 v16, v26, v16
	v_lshlrev_b32_e32 v17, 2, v17
	v_xor_b32_e32 v17, 0x80, v17
	v_mov_b32_e32 v17, v16
	s_nop 1
	v_permlane32_swap_b32_e32 v17, v16
	s_and_saveexec_b64 s[40:41], s[6:7]
	s_cbranch_execz .LBB0_1973
	s_waitcnt lgkmcnt(0)
	v_add_f32_e32 v18, v16, v17
	v_lshlrev_b64 v[16:17], 6, v[92:93]
	v_lshl_add_u64 v[16:17], s[18:19], 0, v[16:17]
	v_lshl_add_u64 v[16:17], s[38:39], 2, v[16:17]
	s_lshl_b32 s10, s33, 2
	v_lshl_add_u64 v[16:17], v[16:17], 0, s[10:11]
	global_store_dword v[16:17], v18, off sc1
.LBB0_1973:
	s_or_b64 exec, exec, s[40:41]
	s_waitcnt vmcnt(7)
	v_lshlrev_b32_e32 v16, 16, v68
	s_waitcnt lgkmcnt(0)
	v_and_b32_e32 v17, 0xffff0000, v68
	v_lshlrev_b32_e32 v18, 16, v69
	v_and_b32_e32 v19, 0xffff0000, v69
	v_lshlrev_b32_e32 v20, 16, v70
	v_and_b32_e32 v21, 0xffff0000, v70
	v_lshlrev_b32_e32 v22, 16, v71
	v_and_b32_e32 v23, 0xffff0000, v71
	v_pk_add_f32 v[14:15], v[14:15], v[18:19]
	v_pk_add_f32 v[12:13], v[12:13], v[16:17]
	v_pk_add_f32 v[16:17], v[10:11], v[22:23]
	v_pk_add_f32 v[10:11], v[8:9], v[20:21]
	v_mul_f32_e32 v8, v13, v13
	v_mul_f32_e32 v9, v15, v15
	v_fmac_f32_e32 v8, v12, v12
	v_fmac_f32_e32 v9, v14, v14
	v_add_f32_e32 v8, v8, v9
	v_mul_f32_e32 v9, v11, v11
	v_mul_f32_e32 v18, v17, v17
	v_fmac_f32_e32 v9, v10, v10
	v_fmac_f32_e32 v18, v16, v16
	v_add_f32_e32 v9, v9, v18
	v_add_f32_e32 v18, v8, v9
	v_cvt_pk_bf16_f32 v8, v12, v13
	v_lshl_add_u64 v[12:13], s[16:17], 0, v[90:91]
	v_cvt_pk_bf16_f32 v9, v14, v15
	v_cvt_pk_bf16_f32 v10, v10, v11
	v_cvt_pk_bf16_f32 v11, v16, v17
	v_lshl_add_u64 v[12:13], v[168:169], 1, v[12:13]
	global_store_dwordx4 v[12:13], v[8:11], off sc1
	s_waitcnt vmcnt(7)
	v_lshlrev_b32_e32 v14, 16, v66
	v_and_b32_e32 v15, 0xffff0000, v66
	v_lshlrev_b32_e32 v8, 16, v64
	v_and_b32_e32 v9, 0xffff0000, v64
	v_lshlrev_b32_e32 v10, 16, v65
	v_and_b32_e32 v11, 0xffff0000, v65
	v_lshlrev_b32_e32 v16, 16, v67
	v_and_b32_e32 v17, 0xffff0000, v67
	v_pk_add_f32 v[6:7], v[6:7], v[10:11]
	v_pk_add_f32 v[4:5], v[4:5], v[8:9]
	v_pk_add_f32 v[8:9], v[2:3], v[16:17]
	v_pk_add_f32 v[2:3], v[0:1], v[14:15]
	v_mul_f32_e32 v0, v5, v5
	v_mul_f32_e32 v1, v7, v7
	v_fmac_f32_e32 v0, v4, v4
	v_fmac_f32_e32 v1, v6, v6
	v_add_f32_e32 v0, v0, v1
	v_mul_f32_e32 v1, v3, v3
	v_mul_f32_e32 v10, v9, v9
	v_fmac_f32_e32 v1, v2, v2
	v_fmac_f32_e32 v10, v8, v8
	v_add_f32_e32 v1, v1, v10
	v_add_f32_e32 v0, v0, v1
	v_add_f32_e32 v10, v18, v0
	v_cvt_pk_bf16_f32 v0, v4, v5
	v_cvt_pk_bf16_f32 v1, v6, v7
	v_cvt_pk_bf16_f32 v2, v2, v3
	v_cvt_pk_bf16_f32 v3, v8, v9
	global_store_dwordx4 v[12:13], v[0:3], off offset:256 sc1
	s_nop 1
	v_mov_b32_e32 v0, v201
	v_mov_b32_e32 v1, v201
	v_lshlrev_b32_e32 v0, 2, v0
	v_xor_b32_e32 v0, 64, v0
	v_mov_b32_e32 v0, v10
	s_nop 1
	v_permlane16_swap_b32_e32 v0, v10
	s_waitcnt lgkmcnt(0)
	v_add_f32_e32 v0, v10, v0
	v_lshlrev_b32_e32 v1, 2, v1
	v_xor_b32_e32 v1, 0x80, v1
	v_mov_b32_e32 v1, v0
	s_nop 1
	v_permlane32_swap_b32_e32 v1, v0
	s_and_saveexec_b64 s[40:41], s[6:7]
	s_cbranch_execz .LBB0_1975
	s_waitcnt lgkmcnt(0)
	v_add_f32_e32 v2, v0, v1
	v_lshlrev_b64 v[0:1], 6, v[88:89]
	v_lshl_add_u64 v[0:1], s[18:19], 0, v[0:1]
	v_lshl_add_u64 v[0:1], s[38:39], 2, v[0:1]
	s_lshl_b32 s10, s33, 2
	v_lshl_add_u64 v[0:1], v[0:1], 0, s[10:11]
	global_store_dword v[0:1], v2, off sc1

; __device__ __forceinline__ float row_part(const float* ss, int row, int fq) { const f32x4 a = ((const f32x4*)(ss + (size_t)row * 16))[fq]; return (a[0] + a[1]) + (a[2] + a[3]); }
; __device__ __forceinline__ float row_finish(float t) { t += shx(t, 16); t += shx(t, 32); return __builtin_amdgcn_rsqf(t * (1.0f / 1024.0f) + RMS_EPS); }
;     __device__ __forceinline__ void operator()(const f32x4 (&acc)[2][2][4][2], const Unit& u, int wr, int wc, int fr, int fq) const {
;         const int col0 = u.pn * 128 + 32 * wc + 8 * fq;
;         float rs[2][4];
; #pragma unroll
;         for (int ai = 0; ai < 2; ++ai)
; #pragma unroll
;             for (int m = 0; m < 4; ++m) rs[ai][m] = row_part(ss, u.pm * BM + ai * HALF + wr * 64 + m * 16 + fr, fq);
; #pragma unroll
;         for (int ai = 0; ai < 2; ++ai)
; #pragma unroll
;             for (int m = 0; m < 4; ++m) rs[ai][m] = row_finish(rs[ai][m]);
.LBB0_2043:
	v_lshl_add_u32 v170, s24, 8, v153
	v_ashrrev_i32_e32 v171, 31, v170
	v_or_b32_e32 v166, 16, v170
	v_lshlrev_b64 v[146:147], 6, v[170:171]
	v_ashrrev_i32_e32 v167, 31, v166
	v_lshl_add_u64 v[146:147], v[136:137], 0, v[146:147]
	v_lshlrev_b64 v[148:149], 6, v[166:167]
	v_lshl_add_u64 v[148:149], v[136:137], 0, v[148:149]
	ds_read_b128 v[176:179], v239
	ds_read_b128 v[180:183], v239 offset:1024
	v_or_b32_e32 v162, 32, v170
	v_ashrrev_i32_e32 v163, 31, v162
	v_or_b32_e32 v158, 48, v170
	v_lshlrev_b64 v[146:147], 6, v[162:163]
	v_ashrrev_i32_e32 v159, 31, v158
	v_lshl_add_u64 v[146:147], v[136:137], 0, v[146:147]
	v_lshlrev_b64 v[148:149], 6, v[158:159]
	v_lshl_add_u64 v[148:149], v[136:137], 0, v[148:149]
	ds_read_b128 v[184:187], v239 offset:2048
	ds_read_b128 v[188:191], v239 offset:3072
	v_add_u32_e32 v154, 0x80, v170
	v_ashrrev_i32_e32 v155, 31, v154
	v_add_u32_e32 v150, 0x90, v170
	v_lshlrev_b64 v[146:147], 6, v[154:155]
	v_ashrrev_i32_e32 v151, 31, v150
	v_lshl_add_u64 v[146:147], v[136:137], 0, v[146:147]
	v_lshlrev_b64 v[148:149], 6, v[150:151]
	v_lshl_add_u64 v[148:149], v[136:137], 0, v[148:149]
	ds_read_b128 v[192:195], v239 offset:8192
	ds_read_b128 v[196:199], v239 offset:9216
	v_add_u32_e32 v148, 0xa0, v170
	v_ashrrev_i32_e32 v149, 31, v148
	v_lshlrev_b64 v[146:147], 6, v[148:149]
	v_lshl_add_u64 v[146:147], v[136:137], 0, v[146:147]
	ds_read_b128 v[202:205], v239 offset:10240
	v_add_u32_e32 v146, 0xb0, v170
	v_ashrrev_i32_e32 v147, 31, v146
	v_lshlrev_b64 v[206:207], 6, v[146:147]
	v_lshl_add_u64 v[206:207], v[136:137], 0, v[206:207]
	ds_read_b128 v[206:209], v239 offset:11264
	v_mov_b32_e32 v147, v201
	v_mov_b32_e32 v149, v201
	v_lshlrev_b32_e32 v147, 2, v147
	v_mov_b32_e32 v151, v201
	v_xor_b32_e32 v147, 64, v147
	s_andn2_b64 vcc, exec, s[6:7]
	v_lshlrev_b32_e32 v151, 2, v151
	v_xor_b32_e32 v151, 64, v151
	v_lshlrev_b32_e32 v149, 2, v149
	v_xor_b32_e32 v149, 0x80, v149
	s_mov_b64 s[6:7], -1
	s_waitcnt lgkmcnt(0)
	v_mov_b32_e32 v210, v177
	v_mov_b32_e32 v211, v178
	v_mov_b32_e32 v177, v179
	v_pk_add_f32 v[176:177], v[210:211], v[176:177]
	v_mov_b32_e32 v178, v181
	v_add_f32_e32 v152, v176, v177
	v_mov_b32_e32 v179, v182
	v_mov_b32_e32 v181, v183
	v_mov_b32_e32 v147, v152
	s_nop 1
	v_permlane16_swap_b32_e32 v147, v152
	v_pk_add_f32 v[176:177], v[178:179], v[180:181]
	v_mov_b32_e32 v182, v185
	v_add_f32_e32 v155, v176, v177
	v_mov_b32_e32 v151, v155
	s_nop 1
	v_permlane16_swap_b32_e32 v151, v155
	s_waitcnt lgkmcnt(0)
	v_add_f32_e32 v147, v152, v147
	v_mov_b32_e32 v152, v201
	v_mov_b32_e32 v149, v147
	s_nop 1
	v_permlane32_swap_b32_e32 v149, v147
	s_waitcnt lgkmcnt(0)
	v_add_f32_e32 v151, v155, v151
	v_lshlrev_b32_e32 v152, 2, v152
	v_xor_b32_e32 v152, 0x80, v152
	v_mov_b32_e32 v152, v151
	s_nop 1
	v_permlane32_swap_b32_e32 v152, v151
	s_waitcnt lgkmcnt(0)
	v_add_f32_e32 v147, v147, v149
	v_mov_b32_e32 v149, v201
	v_mov_b32_e32 v183, v186
	v_mov_b32_e32 v185, v187
	v_pk_add_f32 v[178:179], v[182:183], v[184:185]
	v_fmamk_f32 v147, v147, 0x3a800000, v175
	v_lshlrev_b32_e32 v149, 2, v149
	v_add_f32_e32 v156, v178, v179
	v_rsq_f32_e32 v176, v147
	s_waitcnt lgkmcnt(0)
	v_add_f32_e32 v147, v151, v152
	v_xor_b32_e32 v149, 64, v149
	v_mov_b32_e32 v151, v201
	v_mov_b32_e32 v152, v201
	v_mov_b32_e32 v186, v189
	v_mov_b32_e32 v187, v190
	v_mov_b32_e32 v189, v191
	v_mov_b32_e32 v149, v156
	s_nop 1
	v_permlane16_swap_b32_e32 v149, v156
	v_pk_add_f32 v[180:181], v[186:187], v[188:189]
	v_lshlrev_b32_e32 v152, 2, v152
	v_add_f32_e32 v159, v180, v181
	v_xor_b32_e32 v152, 64, v152
	v_mov_b32_e32 v152, v159
	s_nop 1
	v_permlane16_swap_b32_e32 v152, v159
	s_waitcnt lgkmcnt(0)
	v_add_f32_e32 v149, v156, v149
	v_lshlrev_b32_e32 v151, 2, v151
	v_mov_b32_e32 v156, v201
	v_xor_b32_e32 v151, 0x80, v151
	v_mov_b32_e32 v151, v149
	s_nop 1
	v_permlane32_swap_b32_e32 v151, v149
	v_lshlrev_b32_e32 v156, 2, v156
	s_waitcnt lgkmcnt(0)
	v_add_f32_e32 v152, v159, v152
	v_xor_b32_e32 v156, 0x80, v156
	v_mov_b32_e32 v156, v152
	s_nop 1
	v_permlane32_swap_b32_e32 v156, v152
	v_fmamk_f32 v147, v147, 0x3a800000, v175
	v_rsq_f32_e32 v174, v147
	s_waitcnt lgkmcnt(0)
	v_add_f32_e32 v147, v149, v151
	v_mov_b32_e32 v149, v201
	v_mov_b32_e32 v190, v193
	v_mov_b32_e32 v191, v194
	v_mov_b32_e32 v193, v195
	v_fmamk_f32 v147, v147, 0x3a800000, v175
	v_pk_add_f32 v[182:183], v[190:191], v[192:193]
	v_rsq_f32_e32 v172, v147
	s_waitcnt lgkmcnt(0)
	v_add_f32_e32 v147, v152, v156
	v_lshlrev_b32_e32 v149, 2, v149
	v_mov_b32_e32 v151, v201
	v_mov_b32_e32 v152, v201
	v_mov_b32_e32 v194, v197
	v_mov_b32_e32 v195, v198
	v_mov_b32_e32 v197, v199
	v_add_f32_e32 v160, v182, v183
	v_xor_b32_e32 v149, 64, v149
	v_pk_add_f32 v[184:185], v[194:195], v[196:197]
	v_mov_b32_e32 v149, v160
	s_nop 1
	v_permlane16_swap_b32_e32 v149, v160
	v_lshlrev_b32_e32 v152, 2, v152
	v_add_f32_e32 v163, v184, v185
	v_xor_b32_e32 v152, 64, v152
	v_mov_b32_e32 v152, v163
	s_nop 1
	v_permlane16_swap_b32_e32 v152, v163
	v_lshlrev_b32_e32 v151, 2, v151
	v_mov_b32_e32 v156, v201
	s_waitcnt lgkmcnt(0)
	v_add_f32_e32 v149, v160, v149
	v_xor_b32_e32 v151, 0x80, v151
	v_mov_b32_e32 v151, v149
	s_nop 1
	v_permlane32_swap_b32_e32 v151, v149
	v_lshlrev_b32_e32 v156, 2, v156
	s_waitcnt lgkmcnt(0)
	v_add_f32_e32 v152, v163, v152
	v_xor_b32_e32 v156, 0x80, v156
	v_mov_b32_e32 v156, v152
	s_nop 1
	v_permlane32_swap_b32_e32 v156, v152
	v_fmamk_f32 v147, v147, 0x3a800000, v175
	v_rsq_f32_e32 v168, v147
	s_waitcnt lgkmcnt(0)
	v_add_f32_e32 v147, v149, v151
	v_fmamk_f32 v147, v147, 0x3a800000, v175
	v_rsq_f32_e32 v164, v147
	s_waitcnt lgkmcnt(0)
; __device__ __forceinline__ u32x4 pack8(f32x4 a, f32x4 b) { u32x4 w; w.x = cvt_pk_bf16(a[0], a[1]); w.y = cvt_pk_bf16(a[2], a[3]); w.z = cvt_pk_bf16(b[0], b[1]); w.w = cvt_pk_bf16(b[2], b[3]); return w; }
; __device__ __forceinline__ float silu_f(float v) { return v * __builtin_amdgcn_rcpf(1.0f + __builtin_amdgcn_exp2f(v * -1.4426950408889634f)); }
; __device__ __forceinline__ f32x4 silu4(f32x4 v) { return (f32x4){silu_f(v[0]), silu_f(v[1]), silu_f(v[2]), silu_f(v[3])}; }
;     __device__ __forceinline__ void operator()(const f32x4 (&acc)[2][2][4][2], const Unit& u, int wr, int wc, int fr, int fq) const {
;     ...
;         for (int ai = 0; ai < 2; ++ai)
; #pragma unroll
;             for (int m = 0; m < 4; ++m) {
;                 const int row = u.pm * BM + ai * HALF + wr * 64 + m * 16 + fr;
;                 const float rstd = rs[ai][m];
;                 const f32x4 a0 = silu4(acc[ai][0][m][0] * rstd) * (acc[ai][1][m][0] * rstd);
;                 const f32x4 a1 = silu4(acc[ai][0][m][1] * rstd) * (acc[ai][1][m][1] * rstd);
;                 *(u32x4*)(ACT + (size_t)row * 2816 + col0) = pack8(a0, a1);
;             }
	v_add_f32_e32 v147, v152, v156
	v_mov_b32_e32 v149, v201
	v_mov_b32_e32 v151, v201
	v_mov_b32_e32 v152, v201
	v_mov_b32_e32 v198, v203
	v_mov_b32_e32 v199, v204
	v_mov_b32_e32 v203, v205
	v_mov_b32_e32 v204, v207
	v_mov_b32_e32 v205, v208
	v_mov_b32_e32 v207, v209
	v_pk_add_f32 v[188:189], v[204:205], v[206:207]
	v_lshlrev_b32_e32 v152, 2, v152
	v_pk_add_f32 v[186:187], v[198:199], v[202:203]
	v_add_f32_e32 v155, v188, v189
	v_lshlrev_b32_e32 v149, 2, v149
	v_xor_b32_e32 v152, 64, v152
	v_add_f32_e32 v167, v186, v187
	v_xor_b32_e32 v149, 64, v149
	v_mov_b32_e32 v152, v155
	s_nop 1
	v_permlane16_swap_b32_e32 v152, v155
	v_mov_b32_e32 v149, v167
	s_nop 1
	v_permlane16_swap_b32_e32 v149, v167
	v_lshlrev_b32_e32 v151, 2, v151
	v_xor_b32_e32 v151, 0x80, v151
	v_fmamk_f32 v147, v147, 0x3a800000, v175
	s_waitcnt lgkmcnt(0)
	v_add_f32_e32 v152, v155, v152
	v_mov_b32_e32 v155, v201
	s_waitcnt lgkmcnt(0)
	v_add_f32_e32 v149, v167, v149
	v_mov_b32_e32 v151, v149
	s_nop 1
	v_permlane32_swap_b32_e32 v151, v149
	v_lshlrev_b32_e32 v155, 2, v155
	v_xor_b32_e32 v155, 0x80, v155
	v_mov_b32_e32 v155, v152
	s_nop 1
	v_permlane32_swap_b32_e32 v155, v152
	v_rsq_f32_e32 v160, v147
	s_waitcnt lgkmcnt(0)
	v_add_f32_e32 v147, v149, v151
	v_fmamk_f32 v147, v147, 0x3a800000, v175
	v_rsq_f32_e32 v156, v147
	s_waitcnt lgkmcnt(0)
	v_add_f32_e32 v147, v152, v155
	v_fmamk_f32 v147, v147, 0x3a800000, v175
	v_pk_mul_f32 v[124:125], v[124:125], v[176:177] op_sel_hi:[1,0]
	v_rsq_f32_e32 v152, v147
	v_mul_f32_e32 v147, 0xbfb8aa3b, v124
	v_exp_f32_e32 v147, v147
	v_mul_f32_e32 v149, 0xbfb8aa3b, v125
	v_exp_f32_e32 v149, v149
	v_pk_mul_f32 v[126:127], v[126:127], v[176:177] op_sel_hi:[1,0]
	v_add_f32_e32 v147, 1.0, v147
	v_rcp_f32_e32 v178, v147
	v_add_f32_e32 v147, 1.0, v149
	v_mul_f32_e32 v149, 0xbfb8aa3b, v126
	v_exp_f32_e32 v149, v149
	v_mul_f32_e32 v151, 0xbfb8aa3b, v127
	v_exp_f32_e32 v151, v151
	v_rcp_f32_e32 v179, v147
	v_add_f32_e32 v147, 1.0, v149
	v_rcp_f32_e32 v180, v147
	v_add_f32_e32 v147, 1.0, v151
	v_pk_mul_f32 v[120:121], v[120:121], v[176:177] op_sel_hi:[1,0]
	v_rcp_f32_e32 v181, v147
	v_mul_f32_e32 v147, 0xbfb8aa3b, v120
	v_exp_f32_e32 v147, v147
	v_mul_f32_e32 v149, 0xbfb8aa3b, v121
	v_exp_f32_e32 v149, v149
	v_pk_mul_f32 v[122:123], v[122:123], v[176:177] op_sel_hi:[1,0]
	v_add_f32_e32 v147, 1.0, v147
	v_pk_mul_f32 v[124:125], v[124:125], v[178:179]
	v_rcp_f32_e32 v178, v147
	v_add_f32_e32 v147, 1.0, v149
	v_mul_f32_e32 v149, 0xbfb8aa3b, v122
	v_exp_f32_e32 v149, v149
	v_mul_f32_e32 v151, 0xbfb8aa3b, v123
	v_exp_f32_e32 v151, v151
	v_rcp_f32_e32 v179, v147
	v_add_f32_e32 v147, 1.0, v149
	v_pk_mul_f32 v[126:127], v[126:127], v[180:181]
	v_rcp_f32_e32 v180, v147
	v_add_f32_e32 v147, 1.0, v151
	v_rcp_f32_e32 v181, v147
	v_pk_mul_f32 v[116:117], v[116:117], v[176:177] op_sel_hi:[1,0]
	v_pk_mul_f32 v[118:119], v[118:119], v[176:177] op_sel_hi:[1,0]
	v_pk_mul_f32 v[120:121], v[120:121], v[178:179]
	v_pk_mul_f32 v[112:113], v[112:113], v[176:177] op_sel_hi:[1,0]
	v_lshl_or_b32 v182, s48, 7, v161
	v_pk_mul_f32 v[118:119], v[118:119], v[126:127]
	v_pk_mul_f32 v[116:117], v[116:117], v[124:125]
	v_pk_mul_f32 v[122:123], v[122:123], v[180:181]
	v_pk_mul_f32 v[114:115], v[114:115], v[176:177] op_sel_hi:[1,0]
	v_pk_mul_f32 v[112:113], v[112:113], v[120:121]
	v_ashrrev_i32_e32 v183, 31, v182
	v_pk_mul_f32 v[114:115], v[114:115], v[122:123]
	v_cvt_pk_bf16_f32 v116, v116, v117
	v_cvt_pk_bf16_f32 v117, v118, v119
	v_cvt_pk_bf16_f32 v118, v112, v113
	v_mov_b64_e32 v[112:113], s[10:11]
	v_cvt_pk_bf16_f32 v119, v114, v115
	v_mad_i64_i32 v[120:121], s[26:27], v170, s47, v[112:113]
	v_lshlrev_b64 v[114:115], 1, v[182:183]
	v_pk_mul_f32 v[108:109], v[108:109], v[174:175] op_sel_hi:[1,0]
	v_pk_mul_f32 v[110:111], v[110:111], v[174:175] op_sel_hi:[1,0]
	v_mul_f32_e32 v122, 0xbfb8aa3b, v108
	v_mul_f32_e32 v123, 0xbfb8aa3b, v109
	v_lshl_add_u64 v[120:121], v[120:121], 0, v[114:115]
	v_pk_mul_f32 v[104:105], v[104:105], v[174:175] op_sel_hi:[1,0]
	v_pk_mul_f32 v[106:107], v[106:107], v[174:175] op_sel_hi:[1,0]
	v_exp_f32_e32 v122, v122
	v_exp_f32_e32 v123, v123
	v_mul_f32_e32 v124, 0xbfb8aa3b, v110
	v_mul_f32_e32 v125, 0xbfb8aa3b, v111
	global_store_dwordx4 v[120:121], v[116:119], off sc1
	v_exp_f32_e32 v124, v124
	v_exp_f32_e32 v125, v125
	v_mul_f32_e32 v116, 0xbfb8aa3b, v104
	v_mul_f32_e32 v117, 0xbfb8aa3b, v105
	v_mul_f32_e32 v118, 0xbfb8aa3b, v106
	v_mul_f32_e32 v119, 0xbfb8aa3b, v107
	v_exp_f32_e32 v116, v116
	v_exp_f32_e32 v117, v117
	v_exp_f32_e32 v118, v118
	v_exp_f32_e32 v119, v119
	v_add_f32_e32 v122, 1.0, v122
	v_add_f32_e32 v123, 1.0, v123
	v_rcp_f32_e32 v122, v122
	v_rcp_f32_e32 v123, v123
	v_add_f32_e32 v124, 1.0, v124
	v_add_f32_e32 v125, 1.0, v125
	v_add_f32_e32 v116, 1.0, v116
	v_add_f32_e32 v117, 1.0, v117
	v_add_f32_e32 v118, 1.0, v118
	v_add_f32_e32 v119, 1.0, v119
	v_rcp_f32_e32 v124, v124
	v_rcp_f32_e32 v125, v125
	v_rcp_f32_e32 v116, v116
	v_rcp_f32_e32 v117, v117
	v_rcp_f32_e32 v118, v118
	v_rcp_f32_e32 v119, v119
	v_pk_mul_f32 v[108:109], v[108:109], v[122:123]
	v_pk_mul_f32 v[100:101], v[100:101], v[174:175] op_sel_hi:[1,0]
	v_pk_mul_f32 v[110:111], v[110:111], v[124:125]
	v_pk_mul_f32 v[102:103], v[102:103], v[174:175] op_sel_hi:[1,0]
	v_pk_mul_f32 v[100:101], v[100:101], v[108:109]
	v_pk_mul_f32 v[104:105], v[104:105], v[116:117]
	v_pk_mul_f32 v[106:107], v[106:107], v[118:119]
	v_pk_mul_f32 v[96:97], v[96:97], v[174:175] op_sel_hi:[1,0]
	v_pk_mul_f32 v[98:99], v[98:99], v[174:175] op_sel_hi:[1,0]
	v_pk_mul_f32 v[102:103], v[102:103], v[110:111]
	v_pk_mul_f32 v[106:107], v[98:99], v[106:107]
	v_pk_mul_f32 v[98:99], v[96:97], v[104:105]
; __device__ __forceinline__ u32x4 pack8(f32x4 a, f32x4 b) { u32x4 w; w.x = cvt_pk_bf16(a[0], a[1]); w.y = cvt_pk_bf16(a[2], a[3]); w.z = cvt_pk_bf16(b[0], b[1]); w.w = cvt_pk_bf16(b[2], b[3]); return w; }
; __device__ __forceinline__ float silu_f(float v) { return v * __builtin_amdgcn_rcpf(1.0f + __builtin_amdgcn_exp2f(v * -1.4426950408889634f)); }
; __device__ __forceinline__ f32x4 silu4(f32x4 v) { return (f32x4){silu_f(v[0]), silu_f(v[1]), silu_f(v[2]), silu_f(v[3])}; }
;     __device__ __forceinline__ void operator()(const f32x4 (&acc)[2][2][4][2], const Unit& u, int wr, int wc, int fr, int fq) const {
;     ...
;         for (int ai = 0; ai < 2; ++ai)
; #pragma unroll
;             for (int m = 0; m < 4; ++m) {
;                 const int row = u.pm * BM + ai * HALF + wr * 64 + m * 16 + fr;
;                 const float rstd = rs[ai][m];
;                 const f32x4 a0 = silu4(acc[ai][0][m][0] * rstd) * (acc[ai][1][m][0] * rstd);
;                 const f32x4 a1 = silu4(acc[ai][0][m][1] * rstd) * (acc[ai][1][m][1] * rstd);
;                 *(u32x4*)(ACT + (size_t)row * 2816 + col0) = pack8(a0, a1);
;             }
	v_cvt_pk_bf16_f32 v96, v100, v101
	v_mad_i64_i32 v[100:101], s[26:27], v166, s47, v[112:113]
	v_pk_mul_f32 v[92:93], v[92:93], v[172:173] op_sel_hi:[1,0]
	v_cvt_pk_bf16_f32 v97, v102, v103
	v_cvt_pk_bf16_f32 v98, v98, v99
	v_cvt_pk_bf16_f32 v99, v106, v107
	v_pk_mul_f32 v[94:95], v[94:95], v[172:173] op_sel_hi:[1,0]
	v_mul_f32_e32 v102, 0xbfb8aa3b, v92
	v_mul_f32_e32 v103, 0xbfb8aa3b, v93
	v_lshl_add_u64 v[100:101], v[100:101], 0, v[114:115]
	v_pk_mul_f32 v[88:89], v[88:89], v[172:173] op_sel_hi:[1,0]
	v_pk_mul_f32 v[90:91], v[90:91], v[172:173] op_sel_hi:[1,0]
	v_exp_f32_e32 v102, v102
	v_exp_f32_e32 v103, v103
	v_mul_f32_e32 v104, 0xbfb8aa3b, v94
	v_mul_f32_e32 v105, 0xbfb8aa3b, v95
	global_store_dwordx4 v[100:101], v[96:99], off sc1
	v_exp_f32_e32 v104, v104
	v_exp_f32_e32 v105, v105
	v_mul_f32_e32 v96, 0xbfb8aa3b, v88
	v_mul_f32_e32 v97, 0xbfb8aa3b, v89
	v_mul_f32_e32 v98, 0xbfb8aa3b, v90
	v_mul_f32_e32 v99, 0xbfb8aa3b, v91
	v_exp_f32_e32 v96, v96
	v_exp_f32_e32 v97, v97
	v_exp_f32_e32 v98, v98
	v_exp_f32_e32 v99, v99
	v_add_f32_e32 v102, 1.0, v102
	v_add_f32_e32 v103, 1.0, v103
	v_rcp_f32_e32 v102, v102
	v_rcp_f32_e32 v103, v103
	v_add_f32_e32 v104, 1.0, v104
	v_add_f32_e32 v105, 1.0, v105
	v_add_f32_e32 v96, 1.0, v96
	v_add_f32_e32 v97, 1.0, v97
	v_add_f32_e32 v98, 1.0, v98
	v_add_f32_e32 v99, 1.0, v99
	v_rcp_f32_e32 v104, v104
	v_rcp_f32_e32 v105, v105
	v_rcp_f32_e32 v96, v96
	v_rcp_f32_e32 v97, v97
	v_rcp_f32_e32 v98, v98
	v_rcp_f32_e32 v99, v99
	v_pk_mul_f32 v[92:93], v[92:93], v[102:103]
	v_pk_mul_f32 v[84:85], v[84:85], v[172:173] op_sel_hi:[1,0]
	v_pk_mul_f32 v[94:95], v[94:95], v[104:105]
	v_pk_mul_f32 v[86:87], v[86:87], v[172:173] op_sel_hi:[1,0]
	v_pk_mul_f32 v[84:85], v[84:85], v[92:93]
	v_pk_mul_f32 v[88:89], v[88:89], v[96:97]
	v_pk_mul_f32 v[90:91], v[90:91], v[98:99]
	v_pk_mul_f32 v[80:81], v[80:81], v[172:173] op_sel_hi:[1,0]
	v_pk_mul_f32 v[82:83], v[82:83], v[172:173] op_sel_hi:[1,0]
	v_pk_mul_f32 v[86:87], v[86:87], v[94:95]
	v_pk_mul_f32 v[90:91], v[82:83], v[90:91]
	v_pk_mul_f32 v[82:83], v[80:81], v[88:89]
	v_cvt_pk_bf16_f32 v80, v84, v85
	v_mad_i64_i32 v[84:85], s[26:27], v162, s47, v[112:113]
	v_pk_mul_f32 v[76:77], v[76:77], v[168:169] op_sel_hi:[1,0]
	v_cvt_pk_bf16_f32 v81, v86, v87
	v_cvt_pk_bf16_f32 v82, v82, v83
	v_cvt_pk_bf16_f32 v83, v90, v91
	v_pk_mul_f32 v[78:79], v[78:79], v[168:169] op_sel_hi:[1,0]
	v_mul_f32_e32 v86, 0xbfb8aa3b, v76
	v_mul_f32_e32 v87, 0xbfb8aa3b, v77
	v_lshl_add_u64 v[84:85], v[84:85], 0, v[114:115]
	v_pk_mul_f32 v[72:73], v[72:73], v[168:169] op_sel_hi:[1,0]
	v_pk_mul_f32 v[74:75], v[74:75], v[168:169] op_sel_hi:[1,0]
	v_exp_f32_e32 v86, v86
	v_exp_f32_e32 v87, v87
	v_mul_f32_e32 v88, 0xbfb8aa3b, v78
	v_mul_f32_e32 v89, 0xbfb8aa3b, v79
	global_store_dwordx4 v[84:85], v[80:83], off sc1
	v_exp_f32_e32 v88, v88
	v_exp_f32_e32 v89, v89
	v_mul_f32_e32 v80, 0xbfb8aa3b, v72
	v_mul_f32_e32 v81, 0xbfb8aa3b, v73
	v_mul_f32_e32 v82, 0xbfb8aa3b, v74
	v_mul_f32_e32 v83, 0xbfb8aa3b, v75
	v_exp_f32_e32 v80, v80
	v_exp_f32_e32 v81, v81
	v_exp_f32_e32 v82, v82
	v_exp_f32_e32 v83, v83
	v_add_f32_e32 v86, 1.0, v86
	v_add_f32_e32 v87, 1.0, v87
	v_rcp_f32_e32 v86, v86
	v_rcp_f32_e32 v87, v87
	v_add_f32_e32 v88, 1.0, v88
	v_add_f32_e32 v89, 1.0, v89
	v_add_f32_e32 v80, 1.0, v80
	v_add_f32_e32 v81, 1.0, v81
	v_add_f32_e32 v82, 1.0, v82
	v_add_f32_e32 v83, 1.0, v83
	v_rcp_f32_e32 v88, v88
	v_rcp_f32_e32 v89, v89
	v_rcp_f32_e32 v80, v80
	v_rcp_f32_e32 v81, v81
	v_rcp_f32_e32 v82, v82
	v_rcp_f32_e32 v83, v83
	v_pk_mul_f32 v[76:77], v[76:77], v[86:87]
	v_pk_mul_f32 v[68:69], v[68:69], v[168:169] op_sel_hi:[1,0]
	v_pk_mul_f32 v[78:79], v[78:79], v[88:89]
	v_pk_mul_f32 v[70:71], v[70:71], v[168:169] op_sel_hi:[1,0]
	v_pk_mul_f32 v[68:69], v[68:69], v[76:77]
	v_pk_mul_f32 v[72:73], v[72:73], v[80:81]
	v_pk_mul_f32 v[74:75], v[74:75], v[82:83]
	v_pk_mul_f32 v[64:65], v[64:65], v[168:169] op_sel_hi:[1,0]
	v_pk_mul_f32 v[66:67], v[66:67], v[168:169] op_sel_hi:[1,0]
	v_pk_mul_f32 v[70:71], v[70:71], v[78:79]
	v_pk_mul_f32 v[74:75], v[66:67], v[74:75]
	v_pk_mul_f32 v[66:67], v[64:65], v[72:73]
	v_cvt_pk_bf16_f32 v64, v68, v69
	v_mad_i64_i32 v[68:69], s[26:27], v158, s47, v[112:113]
	v_pk_mul_f32 v[60:61], v[60:61], v[164:165] op_sel_hi:[1,0]
	v_cvt_pk_bf16_f32 v65, v70, v71
	v_cvt_pk_bf16_f32 v66, v66, v67
	v_cvt_pk_bf16_f32 v67, v74, v75
	v_pk_mul_f32 v[62:63], v[62:63], v[164:165] op_sel_hi:[1,0]
	v_mul_f32_e32 v70, 0xbfb8aa3b, v60
	v_mul_f32_e32 v71, 0xbfb8aa3b, v61
	v_lshl_add_u64 v[68:69], v[68:69], 0, v[114:115]
	v_pk_mul_f32 v[56:57], v[56:57], v[164:165] op_sel_hi:[1,0]
	v_pk_mul_f32 v[58:59], v[58:59], v[164:165] op_sel_hi:[1,0]
	v_exp_f32_e32 v70, v70
	v_exp_f32_e32 v71, v71
	v_mul_f32_e32 v72, 0xbfb8aa3b, v62
	v_mul_f32_e32 v73, 0xbfb8aa3b, v63
	global_store_dwordx4 v[68:69], v[64:67], off sc1
	v_exp_f32_e32 v72, v72
	v_exp_f32_e32 v73, v73
	v_mul_f32_e32 v64, 0xbfb8aa3b, v56
	v_mul_f32_e32 v65, 0xbfb8aa3b, v57
	v_mul_f32_e32 v66, 0xbfb8aa3b, v58
	v_mul_f32_e32 v67, 0xbfb8aa3b, v59
	v_exp_f32_e32 v64, v64
	v_exp_f32_e32 v65, v65
	v_exp_f32_e32 v66, v66
	v_exp_f32_e32 v67, v67
	v_add_f32_e32 v70, 1.0, v70
	v_add_f32_e32 v71, 1.0, v71
	v_rcp_f32_e32 v70, v70
	v_rcp_f32_e32 v71, v71
	v_add_f32_e32 v72, 1.0, v72
	v_add_f32_e32 v73, 1.0, v73
	v_add_f32_e32 v64, 1.0, v64
	v_add_f32_e32 v65, 1.0, v65
	v_add_f32_e32 v66, 1.0, v66
	v_add_f32_e32 v67, 1.0, v67
	v_rcp_f32_e32 v72, v72
	v_rcp_f32_e32 v73, v73
	v_rcp_f32_e32 v64, v64
	v_rcp_f32_e32 v65, v65
	v_rcp_f32_e32 v66, v66
	v_rcp_f32_e32 v67, v67
	v_pk_mul_f32 v[60:61], v[60:61], v[70:71]
	v_pk_mul_f32 v[52:53], v[52:53], v[164:165] op_sel_hi:[1,0]
; #define PG8_BAR __builtin_amdgcn_s_barrier()
; __device__ __forceinline__ float silu_f(float v) { return v * __builtin_amdgcn_rcpf(1.0f + __builtin_amdgcn_exp2f(v * -1.4426950408889634f)); }
; __device__ __forceinline__ f32x4 silu4(f32x4 v) { return (f32x4){silu_f(v[0]), silu_f(v[1]), silu_f(v[2]), silu_f(v[3])}; }
;     __device__ __forceinline__ void operator()(const f32x4 (&acc)[2][2][4][2], const Unit& u, int wr, int wc, int fr, int fq) const {
;     ...
;         for (int ai = 0; ai < 2; ++ai)
; #pragma unroll
;             for (int m = 0; m < 4; ++m) {
;                 const int row = u.pm * BM + ai * HALF + wr * 64 + m * 16 + fr;
;                 const float rstd = rs[ai][m];
;                 const f32x4 a0 = silu4(acc[ai][0][m][0] * rstd) * (acc[ai][1][m][0] * rstd);
;                 const f32x4 a1 = silu4(acc[ai][0][m][1] * rstd) * (acc[ai][1][m][1] * rstd);
;                 *(u32x4*)(ACT + (size_t)row * 2816 + col0) = pack8(a0, a1);
;             }
; template <class Epi, class Sched, bool ALIGN_EPI = false, bool SP2 = false>
; __device__ __forceinline__ void gemm_phase(PG8_LAS unsigned char* lds, const Gemm g, const Sched& S, const Epi& E, int tid_in) {
;     ...
;         for (int t = 0; t < nt; t += 2) {
;             const bool last = (t == nt - 2);
;             const char* a1 = cA + (size_t)(t + 1) * kstep;
;             const char* a2 = last ? nA : cA + (size_t)(t + 2) * kstep; const char* b2 = last ? nB : cB + (size_t)(t + 2) * kstep;
;             const char* a3 = a2 + kstep; const char* b3 = b2 + kstep;
;             if (last && has_next) S.a_ready(nxt);
;             if constexpr (SP2) {
;             PG8_LDB(B0, 0, 0); PG8_LDB(B1, 0, 1); PG8_SCHED; PG8_LDA(At, 0, 0); PG8_STAGE(PG8_SA(1, 1), a1 + hstep, voffA);
;             PG8_WAIT_V(8); PG8_WAIT_L(0); PG8_BAR; PG8_MMA(0, 0, At, B0); PG8_MMA(0, 1, At, B1); PG8_BAR; PG8_SCHED;
;             PG8_LDA(At, 0, 1); PG8_STAGE(PG8_SB(0, 0), b2, voffB); PG8_STAGE(PG8_SB(0, 1), b2 + hstep, voffB); PG8_STAGE(PG8_SA(0, 0), a2, voffA);
;             PG8_WAIT_V(8); PG8_WAIT_L(0); PG8_BAR; PG8_MMA(1, 0, At, B0); PG8_MMA(1, 1, At, B1); PG8_BAR; PG8_SCHED;
;             PG8_LDB(B0, 1, 0); PG8_LDB(B1, 1, 1); PG8_SCHED; PG8_LDA(At, 1, 0); PG8_STAGE(PG8_SA(0, 1), a2 + hstep, voffA);
;             PG8_WAIT_V(8); PG8_WAIT_L(0); PG8_BAR; PG8_MMA(0, 0, At, B0); PG8_MMA(0, 1, At, B1); PG8_BAR; PG8_SCHED;
	v_pk_mul_f32 v[62:63], v[62:63], v[72:73]
	v_pk_mul_f32 v[54:55], v[54:55], v[164:165] op_sel_hi:[1,0]
	v_pk_mul_f32 v[52:53], v[52:53], v[60:61]
	v_pk_mul_f32 v[56:57], v[56:57], v[64:65]
	v_pk_mul_f32 v[58:59], v[58:59], v[66:67]
	v_pk_mul_f32 v[48:49], v[48:49], v[164:165] op_sel_hi:[1,0]
	v_pk_mul_f32 v[50:51], v[50:51], v[164:165] op_sel_hi:[1,0]
	v_pk_mul_f32 v[54:55], v[54:55], v[62:63]
	v_pk_mul_f32 v[58:59], v[50:51], v[58:59]
	v_pk_mul_f32 v[50:51], v[48:49], v[56:57]
	v_cvt_pk_bf16_f32 v48, v52, v53
	v_mad_i64_i32 v[52:53], s[26:27], v154, s47, v[112:113]
	v_pk_mul_f32 v[44:45], v[44:45], v[160:161] op_sel_hi:[1,0]
	v_cvt_pk_bf16_f32 v49, v54, v55
	v_cvt_pk_bf16_f32 v50, v50, v51
	v_cvt_pk_bf16_f32 v51, v58, v59
	v_pk_mul_f32 v[46:47], v[46:47], v[160:161] op_sel_hi:[1,0]
	v_mul_f32_e32 v54, 0xbfb8aa3b, v44
	v_mul_f32_e32 v55, 0xbfb8aa3b, v45
	v_lshl_add_u64 v[52:53], v[52:53], 0, v[114:115]
	v_pk_mul_f32 v[40:41], v[40:41], v[160:161] op_sel_hi:[1,0]
	v_pk_mul_f32 v[42:43], v[42:43], v[160:161] op_sel_hi:[1,0]
	v_exp_f32_e32 v54, v54
	v_exp_f32_e32 v55, v55
	v_mul_f32_e32 v56, 0xbfb8aa3b, v46
	v_mul_f32_e32 v57, 0xbfb8aa3b, v47
	global_store_dwordx4 v[52:53], v[48:51], off sc1
	v_exp_f32_e32 v56, v56
	v_exp_f32_e32 v57, v57
	v_mul_f32_e32 v48, 0xbfb8aa3b, v40
	v_mul_f32_e32 v49, 0xbfb8aa3b, v41
	v_mul_f32_e32 v50, 0xbfb8aa3b, v42
	v_mul_f32_e32 v51, 0xbfb8aa3b, v43
	v_exp_f32_e32 v48, v48
	v_exp_f32_e32 v49, v49
	v_exp_f32_e32 v50, v50
	v_exp_f32_e32 v51, v51
	v_add_f32_e32 v54, 1.0, v54
	v_add_f32_e32 v55, 1.0, v55
	v_rcp_f32_e32 v54, v54
	v_rcp_f32_e32 v55, v55
	v_add_f32_e32 v56, 1.0, v56
	v_add_f32_e32 v57, 1.0, v57
	v_add_f32_e32 v48, 1.0, v48
	v_add_f32_e32 v49, 1.0, v49
	v_add_f32_e32 v50, 1.0, v50
	v_add_f32_e32 v51, 1.0, v51
	v_rcp_f32_e32 v56, v56
	v_rcp_f32_e32 v57, v57
	v_rcp_f32_e32 v48, v48
	v_rcp_f32_e32 v49, v49
	v_rcp_f32_e32 v50, v50
	v_rcp_f32_e32 v51, v51
	v_pk_mul_f32 v[44:45], v[44:45], v[54:55]
	v_pk_mul_f32 v[36:37], v[36:37], v[160:161] op_sel_hi:[1,0]
	v_pk_mul_f32 v[46:47], v[46:47], v[56:57]
	v_pk_mul_f32 v[38:39], v[38:39], v[160:161] op_sel_hi:[1,0]
	v_pk_mul_f32 v[36:37], v[36:37], v[44:45]
	v_pk_mul_f32 v[40:41], v[40:41], v[48:49]
	v_pk_mul_f32 v[42:43], v[42:43], v[50:51]
	v_pk_mul_f32 v[32:33], v[32:33], v[160:161] op_sel_hi:[1,0]
	v_pk_mul_f32 v[34:35], v[34:35], v[160:161] op_sel_hi:[1,0]
	v_pk_mul_f32 v[38:39], v[38:39], v[46:47]
	v_pk_mul_f32 v[42:43], v[34:35], v[42:43]
	v_pk_mul_f32 v[34:35], v[32:33], v[40:41]
	v_cvt_pk_bf16_f32 v32, v36, v37
	v_mad_i64_i32 v[36:37], s[26:27], v150, s47, v[112:113]
	v_pk_mul_f32 v[28:29], v[28:29], v[156:157] op_sel_hi:[1,0]
	v_cvt_pk_bf16_f32 v33, v38, v39
	v_cvt_pk_bf16_f32 v34, v34, v35
	v_cvt_pk_bf16_f32 v35, v42, v43
	v_pk_mul_f32 v[30:31], v[30:31], v[156:157] op_sel_hi:[1,0]
	v_mul_f32_e32 v38, 0xbfb8aa3b, v28
	v_mul_f32_e32 v39, 0xbfb8aa3b, v29
	v_lshl_add_u64 v[36:37], v[36:37], 0, v[114:115]
	v_pk_mul_f32 v[24:25], v[24:25], v[156:157] op_sel_hi:[1,0]
	v_pk_mul_f32 v[26:27], v[26:27], v[156:157] op_sel_hi:[1,0]
	v_exp_f32_e32 v38, v38
	v_exp_f32_e32 v39, v39
	v_mul_f32_e32 v40, 0xbfb8aa3b, v30
	v_mul_f32_e32 v41, 0xbfb8aa3b, v31
	global_store_dwordx4 v[36:37], v[32:35], off sc1
	v_exp_f32_e32 v40, v40
	v_exp_f32_e32 v41, v41
	v_mul_f32_e32 v32, 0xbfb8aa3b, v24
	v_mul_f32_e32 v33, 0xbfb8aa3b, v25
	v_mul_f32_e32 v34, 0xbfb8aa3b, v26
	v_mul_f32_e32 v35, 0xbfb8aa3b, v27
	v_exp_f32_e32 v32, v32
	v_exp_f32_e32 v33, v33
	v_exp_f32_e32 v34, v34
	v_exp_f32_e32 v35, v35
	v_add_f32_e32 v38, 1.0, v38
	v_add_f32_e32 v39, 1.0, v39
	v_rcp_f32_e32 v38, v38
	v_rcp_f32_e32 v39, v39
	v_add_f32_e32 v40, 1.0, v40
	v_add_f32_e32 v41, 1.0, v41
	v_add_f32_e32 v32, 1.0, v32
	v_add_f32_e32 v33, 1.0, v33
	v_add_f32_e32 v34, 1.0, v34
	v_add_f32_e32 v35, 1.0, v35
	v_rcp_f32_e32 v40, v40
	v_rcp_f32_e32 v41, v41
	v_rcp_f32_e32 v32, v32
	v_rcp_f32_e32 v33, v33
	v_rcp_f32_e32 v34, v34
	v_rcp_f32_e32 v35, v35
	v_pk_mul_f32 v[28:29], v[28:29], v[38:39]
	v_pk_mul_f32 v[20:21], v[20:21], v[156:157] op_sel_hi:[1,0]
	v_pk_mul_f32 v[30:31], v[30:31], v[40:41]
	v_pk_mul_f32 v[22:23], v[22:23], v[156:157] op_sel_hi:[1,0]
	v_pk_mul_f32 v[20:21], v[20:21], v[28:29]
	v_pk_mul_f32 v[24:25], v[24:25], v[32:33]
	v_pk_mul_f32 v[26:27], v[26:27], v[34:35]
	v_pk_mul_f32 v[16:17], v[16:17], v[156:157] op_sel_hi:[1,0]
	v_pk_mul_f32 v[18:19], v[18:19], v[156:157] op_sel_hi:[1,0]
	v_pk_mul_f32 v[22:23], v[22:23], v[30:31]
	v_pk_mul_f32 v[26:27], v[18:19], v[26:27]
	v_pk_mul_f32 v[18:19], v[16:17], v[24:25]
	v_cvt_pk_bf16_f32 v16, v20, v21
	v_mad_i64_i32 v[20:21], s[26:27], v148, s47, v[112:113]
	v_pk_mul_f32 v[12:13], v[12:13], v[152:153] op_sel_hi:[1,0]
	v_cvt_pk_bf16_f32 v17, v22, v23
	v_cvt_pk_bf16_f32 v18, v18, v19
	v_cvt_pk_bf16_f32 v19, v26, v27
	v_lshl_add_u64 v[20:21], v[20:21], 0, v[114:115]
	v_mul_f32_e32 v22, 0xbfb8aa3b, v12
	v_mul_f32_e32 v23, 0xbfb8aa3b, v13
	v_pk_mul_f32 v[8:9], v[8:9], v[152:153] op_sel_hi:[1,0]
	v_pk_mul_f32 v[10:11], v[10:11], v[152:153] op_sel_hi:[1,0]
	v_exp_f32_e32 v22, v22
	v_exp_f32_e32 v23, v23
	global_store_dwordx4 v[20:21], v[16:19], off sc1
	v_pk_mul_f32 v[14:15], v[14:15], v[152:153] op_sel_hi:[1,0]
	v_add_f32_e32 v22, 1.0, v22
	v_mul_f32_e32 v16, 0xbfb8aa3b, v8
	v_mul_f32_e32 v17, 0xbfb8aa3b, v9
	v_mul_f32_e32 v18, 0xbfb8aa3b, v10
	v_mul_f32_e32 v19, 0xbfb8aa3b, v11
	v_exp_f32_e32 v16, v16
	v_exp_f32_e32 v17, v17
	v_exp_f32_e32 v18, v18
	v_exp_f32_e32 v19, v19
	v_mul_f32_e32 v24, 0xbfb8aa3b, v14
	v_mul_f32_e32 v25, 0xbfb8aa3b, v15
	v_exp_f32_e32 v24, v24
	v_exp_f32_e32 v25, v25
	v_add_f32_e32 v23, 1.0, v23
	v_rcp_f32_e32 v22, v22
	v_rcp_f32_e32 v23, v23
	v_add_f32_e32 v16, 1.0, v16
	v_add_f32_e32 v17, 1.0, v17
	v_add_f32_e32 v18, 1.0, v18
	v_add_f32_e32 v19, 1.0, v19
	v_rcp_f32_e32 v16, v16
	v_rcp_f32_e32 v17, v17
	v_rcp_f32_e32 v18, v18
	v_rcp_f32_e32 v19, v19
	v_add_f32_e32 v24, 1.0, v24
	v_add_f32_e32 v25, 1.0, v25
	v_rcp_f32_e32 v24, v24
	v_rcp_f32_e32 v25, v25
	v_pk_mul_f32 v[12:13], v[12:13], v[22:23]
	v_pk_mul_f32 v[4:5], v[4:5], v[152:153] op_sel_hi:[1,0]
	v_pk_mul_f32 v[8:9], v[8:9], v[16:17]
	v_pk_mul_f32 v[4:5], v[4:5], v[12:13]
	v_pk_mul_f32 v[10:11], v[10:11], v[18:19]
	v_pk_mul_f32 v[0:1], v[0:1], v[152:153] op_sel_hi:[1,0]
	v_pk_mul_f32 v[2:3], v[2:3], v[152:153] op_sel_hi:[1,0]
	v_pk_mul_f32 v[14:15], v[14:15], v[24:25]
	v_pk_mul_f32 v[10:11], v[2:3], v[10:11]
	v_pk_mul_f32 v[2:3], v[0:1], v[8:9]
	v_cvt_pk_bf16_f32 v0, v4, v5
	v_mad_i64_i32 v[4:5], s[26:27], v146, s47, v[112:113]
	v_pk_mul_f32 v[6:7], v[6:7], v[152:153] op_sel_hi:[1,0]
	v_lshl_add_u64 v[4:5], v[4:5], 0, v[114:115]
	v_pk_mul_f32 v[6:7], v[6:7], v[14:15]
	s_nop 0
	v_cvt_pk_bf16_f32 v1, v6, v7
	v_cvt_pk_bf16_f32 v2, v2, v3
	v_cvt_pk_bf16_f32 v3, v10, v11
	global_store_dwordx4 v[4:5], v[0:3], off sc1
	s_cbranch_vccnz .LBB0_2036
	s_andn2_b64 vcc, exec, s[8:9]
	s_cbranch_vccnz .LBB0_2035
	s_barrier
	s_branch .LBB0_2035
